# GEMM loops: dropped the pre-barrier lgkmcnt(8) (the post-barrier lgkmcnt(0) still guards the fragments); on top of v12
# baseline (speedup 1.0000x reference)
; #define PG8_STAGE(bufoff, gbase, voff) do { _Pragma("unroll") for (int _i = 0; _i < 2; ++_i) \
;         __builtin_amdgcn_global_load_lds((const unsigned*)((const char*)(gbase) + (voff)[_i]), (LAS unsigned*)(lds + (bufoff) + ldsw + _i * 8192), 16, 0, 0); } while (0)
; #define PG8_LDA(dst, b, h) do { _Pragma("unroll") for (int m = 0; m < 4; ++m) _Pragma("unroll") for (int k = 0; k < 2; ++k) dst[m][k] = *(const LAS bf16x8*)(lds + PG8_SA(b, h) + aoff + m * 2048 + k * 1024); } while (0)
; #define PG8_LDB(dst, b, h) do { _Pragma("unroll") for (int n = 0; n < 2; ++n) _Pragma("unroll") for (int k = 0; k < 2; ++k) dst[n][k] = *(const LAS bf16x8*)(lds + PG8_SB(b, h) + boff + n * 2048 + k * 1024); } while (0)
; template <class Epi, class Sched>
; __device__ __forceinline__ void gemm_phase(LAS unsigned char* lds, const Gemm g, const Sched& S, const Epi& E) {
;     ...
;     f32x4 acc[2][2][4][2];
; #pragma unroll
;     for (int a = 0; a < 2; ++a)
; #pragma unroll
;         for (int b = 0; b < 2; ++b)
; #pragma unroll
;             for (int m = 0; m < 4; ++m)
; #pragma unroll
;                 for (int n = 0; n < 2; ++n) acc[a][b][m][n] = (f32x4){0.f, 0.f, 0.f, 0.f};
;     ...
;         const bool has_next = S.next(ui + 1, nxt);
;         const char* nA = has_next ? (const char*)g.A + (size_t)nxt.pm * tstep : cA; const char* nB = has_next ? (const char*)g.Bt + (size_t)nxt.pn * tstep : cB;
;         for (int t = 0; t < nt; t += 2) {
;             const bool last = (t == nt - 2);
;             const char* a1 = cA + (size_t)(t + 1) * kstep;
;             const char* a2 = last ? nA : cA + (size_t)(t + 2) * kstep; const char* b2 = last ? nB : cB + (size_t)(t + 2) * kstep;
;             const char* a3 = a2 + kstep; const char* b3 = b2 + kstep;
;             PG8_LDB(B0, 0, 0); PG8_SCHED; PG8_LDA(At, 0, 0); PG8_STAGE(PG8_SA(1, 1), a1 + hstep, voffA);
;             PG8_WAIT_L(8); PG8_BAR; PG8_WAIT_L(0); PG8_MMA(0, 0, At, B0); PG8_BAR; PG8_SCHED;
;             PG8_LDB(B1, 0, 1); PG8_STAGE(PG8_SB(0, 0), b2, voffB);
;             PG8_BAR; PG8_WAIT_L(0); PG8_MMA(0, 1, At, B1); PG8_BAR;
;             PG8_LDA(At, 0, 1); PG8_STAGE(PG8_SA(0, 0), a2, voffA);
;             PG8_BAR; PG8_WAIT_L(0); PG8_MMA(1, 0, At, B0); PG8_BAR; PG8_SCHED;
;             PG8_STAGE(PG8_SB(0, 1), b2 + hstep, voffB);
;             PG8_WAIT_V(6); PG8_BAR; PG8_MMA(1, 1, At, B1); PG8_BAR;
.LBB0_234:
	s_ashr_i32 s7, s6, 31
	v_cmp_lt_i64_e32 vcc, s[8:9], v[140:141]
	s_lshl_b64 s[8:9], s[6:7], 19
	s_add_u32 s8, s96, s8
	s_addc_u32 s9, s97, s9
	s_and_b64 s[10:11], vcc, exec
	s_cselect_b32 s7, s9, s15
	s_cselect_b32 s44, s8, s14
	s_ashr_i32 s5, s4, 31
	s_lshl_b64 s[10:11], s[4:5], 19
	s_add_u32 s10, s72, s10
	s_addc_u32 s11, s73, s11
	s_and_b64 s[16:17], vcc, exec
	s_cselect_b32 s5, s11, s19
	s_cselect_b32 s45, s10, s18
	s_add_u32 s14, s14, 0x40080
	s_addc_u32 s15, s15, 0
	s_add_u32 s46, s18, 0x100
	s_addc_u32 s47, s19, 0
	s_mov_b32 s48, -2
	ds_read_b128 v[150:153], v147
	ds_read_b128 v[154:157], v147 offset:1024
	ds_read_b128 v[158:161], v147 offset:2048
	ds_read_b128 v[162:165], v147 offset:3072
	s_add_u32 s16, s14, 0xfffc0080
	s_addc_u32 s17, s15, -1
	s_cmp_eq_u32 s48, 12
	s_cselect_b32 s23, s7, s17
	s_cselect_b32 s22, s44, s16
	s_cselect_b32 s19, s5, s47
	s_cselect_b32 s18, s45, s46
	s_add_i32 m0, s13, 0xc000
	ds_read_b128 v[166:169], v148
	ds_read_b128 v[170:173], v148 offset:1024
	ds_read_b128 v[174:177], v148 offset:2048
	ds_read_b128 v[178:181], v148 offset:3072
	ds_read_b128 v[182:185], v148 offset:4096
	ds_read_b128 v[186:189], v148 offset:5120
	ds_read_b128 v[190:193], v148 offset:6144
	ds_read_b128 v[194:197], v148 offset:7168
	global_load_lds_dwordx4 v136, s[14:15]
	s_add_i32 m0, s13, 0xe000
	s_nop 0
	global_load_lds_dwordx4 v138, s[14:15]
	s_waitcnt vmcnt(10)
	s_barrier
	s_waitcnt lgkmcnt(0)
	s_setprio 1
	s_waitcnt lgkmcnt(0)
	v_mfma_f32_16x16x32_bf16 v[124:127], v[150:153], v[166:169], 0
	v_mfma_f32_16x16x32_bf16 v[116:119], v[158:161], v[166:169], 0
	v_mfma_f32_16x16x32_bf16 v[108:111], v[150:153], v[174:177], 0
	v_mfma_f32_16x16x32_bf16 v[100:103], v[158:161], v[174:177], 0
	v_mfma_f32_16x16x32_bf16 v[92:95], v[150:153], v[182:185], 0
	v_mfma_f32_16x16x32_bf16 v[84:87], v[158:161], v[182:185], 0
	v_mfma_f32_16x16x32_bf16 v[76:79], v[150:153], v[190:193], 0
	v_mfma_f32_16x16x32_bf16 v[68:71], v[158:161], v[190:193], 0
	v_mfma_f32_16x16x32_bf16 v[124:127], v[154:157], v[170:173], v[124:127]
	v_mfma_f32_16x16x32_bf16 v[116:119], v[162:165], v[170:173], v[116:119]
	v_mfma_f32_16x16x32_bf16 v[108:111], v[154:157], v[178:181], v[108:111]
	v_mfma_f32_16x16x32_bf16 v[100:103], v[162:165], v[178:181], v[100:103]
	v_mfma_f32_16x16x32_bf16 v[92:95], v[154:157], v[186:189], v[92:95]
	v_mfma_f32_16x16x32_bf16 v[84:87], v[162:165], v[186:189], v[84:87]
	v_mfma_f32_16x16x32_bf16 v[76:79], v[154:157], v[194:197], v[76:79]
	v_mfma_f32_16x16x32_bf16 v[68:71], v[162:165], v[194:197], v[68:71]
	s_setprio 0
	s_barrier
	s_add_i32 s16, s40, s25
	s_mov_b32 m0, s16
	ds_read_b128 v[202:205], v149
	ds_read_b128 v[206:209], v149 offset:1024
	ds_read_b128 v[210:213], v149 offset:2048
	ds_read_b128 v[214:217], v149 offset:3072
	global_load_lds_dwordx4 v132, s[18:19]
	s_add_i32 m0, s16, 0x2000
	s_nop 0
	global_load_lds_dwordx4 v128, s[18:19]
	s_waitcnt vmcnt(10)
	s_barrier
	s_waitcnt lgkmcnt(0)
	s_setprio 1
	s_waitcnt lgkmcnt(0)
	v_mfma_f32_16x16x32_bf16 v[120:123], v[202:205], v[166:169], 0
	v_mfma_f32_16x16x32_bf16 v[112:115], v[210:213], v[166:169], 0
	v_mfma_f32_16x16x32_bf16 v[104:107], v[202:205], v[174:177], 0
	v_mfma_f32_16x16x32_bf16 v[96:99], v[210:213], v[174:177], 0
	v_mfma_f32_16x16x32_bf16 v[88:91], v[202:205], v[182:185], 0
	v_mfma_f32_16x16x32_bf16 v[80:83], v[210:213], v[182:185], 0
	v_mfma_f32_16x16x32_bf16 v[72:75], v[202:205], v[190:193], 0
	v_mfma_f32_16x16x32_bf16 v[64:67], v[210:213], v[190:193], 0
	v_mfma_f32_16x16x32_bf16 v[120:123], v[206:209], v[170:173], v[120:123]
	v_mfma_f32_16x16x32_bf16 v[112:115], v[214:217], v[170:173], v[112:115]
	v_mfma_f32_16x16x32_bf16 v[104:107], v[206:209], v[178:181], v[104:107]
	v_mfma_f32_16x16x32_bf16 v[96:99], v[214:217], v[178:181], v[96:99]
	v_mfma_f32_16x16x32_bf16 v[88:91], v[206:209], v[186:189], v[88:91]
	v_mfma_f32_16x16x32_bf16 v[80:83], v[214:217], v[186:189], v[80:83]
	v_mfma_f32_16x16x32_bf16 v[72:75], v[206:209], v[194:197], v[72:75]
	v_mfma_f32_16x16x32_bf16 v[64:67], v[214:217], v[194:197], v[64:67]
	s_setprio 0
	s_mov_b32 m0, s13
	s_barrier
	ds_read_b128 v[166:169], v148 offset:16384
	ds_read_b128 v[170:173], v148 offset:17408
	ds_read_b128 v[174:177], v148 offset:18432
	ds_read_b128 v[178:181], v148 offset:19456
	ds_read_b128 v[182:185], v148 offset:20480
	ds_read_b128 v[186:189], v148 offset:21504
	ds_read_b128 v[190:193], v148 offset:22528
	ds_read_b128 v[194:197], v148 offset:23552
	global_load_lds_dwordx4 v134, s[22:23]
	s_mov_b32 m0, s28
	s_nop 0
	global_load_lds_dwordx4 v130, s[22:23]
	s_barrier
	s_waitcnt lgkmcnt(0)
	s_setprio 1
	s_waitcnt lgkmcnt(0)
	v_mfma_f32_16x16x32_bf16 v[60:63], v[150:153], v[166:169], 0
	v_mfma_f32_16x16x32_bf16 v[56:59], v[158:161], v[166:169], 0
	v_mfma_f32_16x16x32_bf16 v[44:47], v[150:153], v[174:177], 0
	v_mfma_f32_16x16x32_bf16 v[40:43], v[158:161], v[174:177], 0
	v_mfma_f32_16x16x32_bf16 v[28:31], v[150:153], v[182:185], 0
	v_mfma_f32_16x16x32_bf16 v[24:27], v[158:161], v[182:185], 0
	v_mfma_f32_16x16x32_bf16 v[12:15], v[150:153], v[190:193], 0
	v_mfma_f32_16x16x32_bf16 v[8:11], v[158:161], v[190:193], 0
	v_mfma_f32_16x16x32_bf16 v[60:63], v[154:157], v[170:173], v[60:63]
	v_mfma_f32_16x16x32_bf16 v[56:59], v[162:165], v[170:173], v[56:59]
	v_mfma_f32_16x16x32_bf16 v[44:47], v[154:157], v[178:181], v[44:47]
	v_mfma_f32_16x16x32_bf16 v[40:43], v[162:165], v[178:181], v[40:43]
	v_mfma_f32_16x16x32_bf16 v[28:31], v[154:157], v[186:189], v[28:31]
	v_mfma_f32_16x16x32_bf16 v[24:27], v[162:165], v[186:189], v[24:27]
	v_mfma_f32_16x16x32_bf16 v[12:15], v[154:157], v[194:197], v[12:15]
	v_mfma_f32_16x16x32_bf16 v[8:11], v[162:165], v[194:197], v[8:11]
	s_setprio 0
	s_barrier
; #define PG8_STAGE(bufoff, gbase, voff) do { _Pragma("unroll") for (int _i = 0; _i < 2; ++_i) \
;         __builtin_amdgcn_global_load_lds((const unsigned*)((const char*)(gbase) + (voff)[_i]), (LAS unsigned*)(lds + (bufoff) + ldsw + _i * 8192), 16, 0, 0); } while (0)
; #define PG8_LDA(dst, b, h) do { _Pragma("unroll") for (int m = 0; m < 4; ++m) _Pragma("unroll") for (int k = 0; k < 2; ++k) dst[m][k] = *(const LAS bf16x8*)(lds + PG8_SA(b, h) + aoff + m * 2048 + k * 1024); } while (0)
; #define PG8_LDB(dst, b, h) do { _Pragma("unroll") for (int n = 0; n < 2; ++n) _Pragma("unroll") for (int k = 0; k < 2; ++k) dst[n][k] = *(const LAS bf16x8*)(lds + PG8_SB(b, h) + boff + n * 2048 + k * 1024); } while (0)
; #define PG8_MMA(ai, bj, At, Bt) do { __builtin_amdgcn_s_setprio(1); _Pragma("unroll") for (int m = 0; m < 4; ++m) _Pragma("unroll") for (int n = 0; n < 2; ++n) _Pragma("unroll") for (int k = 0; k < 2; ++k) \
;         acc[ai][bj][m][n] = __builtin_amdgcn_mfma_f32_16x16x32_bf16(Bt[n][k], At[m][k], acc[ai][bj][m][n], 0, 0, 0); __builtin_amdgcn_s_setprio(0); } while (0)
; #define PG8_WAIT_V(n) asm volatile("s_waitcnt vmcnt(" #n ")" ::: "memory")
; #define PG8_WAIT_L(n) asm volatile("s_waitcnt lgkmcnt(" #n ")" ::: "memory")
; #define PG8_BAR __builtin_amdgcn_s_barrier()
; #define PG8_SCHED __builtin_amdgcn_sched_barrier(0)
; template <class Epi, class Sched>
; __device__ __forceinline__ void gemm_phase(LAS unsigned char* lds, const Gemm g, const Sched& S, const Epi& E) {
;     ...
;             PG8_BAR; PG8_WAIT_L(0); PG8_MMA(1, 0, At, B0); PG8_BAR; PG8_SCHED;
;             PG8_STAGE(PG8_SB(0, 1), b2 + hstep, voffB);
;             PG8_WAIT_V(6); PG8_BAR; PG8_MMA(1, 1, At, B1); PG8_BAR;
;             PG8_LDB(B0, 1, 0); PG8_SCHED; PG8_LDA(At, 1, 0); PG8_STAGE(PG8_SA(0, 1), a2 + hstep, voffA);
;             PG8_WAIT_L(8); PG8_BAR; PG8_WAIT_L(0); PG8_MMA(0, 0, At, B0); PG8_BAR; PG8_SCHED;
;             PG8_LDB(B1, 1, 1); PG8_STAGE(PG8_SB(1, 0), b3, voffB);
;             PG8_BAR; PG8_WAIT_L(0); PG8_MMA(0, 1, At, B1); PG8_BAR;
;             PG8_LDA(At, 1, 1); PG8_STAGE(PG8_SA(1, 0), a3, voffA);
;             PG8_BAR; PG8_WAIT_L(0); PG8_MMA(1, 0, At, B0); PG8_BAR; PG8_SCHED;
	s_add_u32 s16, s18, 0x40000
	s_addc_u32 s17, s19, 0
	s_add_i32 s20, s41, s25
	s_mov_b32 m0, s20
	s_nop 0
	global_load_lds_dwordx4 v132, s[16:17]
	s_add_i32 m0, s20, 0x2000
	s_nop 0
	global_load_lds_dwordx4 v128, s[16:17]
	s_add_u32 s16, s22, 0x40000
	s_addc_u32 s17, s23, 0
	s_mov_b32 m0, s29
	s_nop 0
	global_load_lds_dwordx4 v134, s[16:17]
	s_mov_b32 m0, s33
	s_nop 0
	global_load_lds_dwordx4 v130, s[16:17]
	s_waitcnt vmcnt(12)
	s_barrier
	s_setprio 1
	v_mfma_f32_16x16x32_bf16 v[52:55], v[202:205], v[166:169], 0
	v_mfma_f32_16x16x32_bf16 v[48:51], v[210:213], v[166:169], 0
	v_mfma_f32_16x16x32_bf16 v[36:39], v[202:205], v[174:177], 0
	v_mfma_f32_16x16x32_bf16 v[32:35], v[210:213], v[174:177], 0
	v_mfma_f32_16x16x32_bf16 v[20:23], v[202:205], v[182:185], 0
	v_mfma_f32_16x16x32_bf16 v[16:19], v[210:213], v[182:185], 0
	v_mfma_f32_16x16x32_bf16 v[4:7], v[202:205], v[190:193], 0
	v_mfma_f32_16x16x32_bf16 v[0:3], v[210:213], v[190:193], 0
	v_mfma_f32_16x16x32_bf16 v[52:55], v[206:209], v[170:173], v[52:55]
	v_mfma_f32_16x16x32_bf16 v[48:51], v[214:217], v[170:173], v[48:51]
	v_mfma_f32_16x16x32_bf16 v[36:39], v[206:209], v[178:181], v[36:39]
	v_mfma_f32_16x16x32_bf16 v[32:35], v[214:217], v[178:181], v[32:35]
	v_mfma_f32_16x16x32_bf16 v[20:23], v[206:209], v[186:189], v[20:23]
	v_mfma_f32_16x16x32_bf16 v[16:19], v[214:217], v[186:189], v[16:19]
	v_mfma_f32_16x16x32_bf16 v[4:7], v[206:209], v[194:197], v[4:7]
	v_mfma_f32_16x16x32_bf16 v[0:3], v[214:217], v[194:197], v[0:3]
	s_setprio 0
	s_add_i32 s20, 0, 0x18000
	v_add_u32_e32 v162, s20, v146
	s_barrier
	ds_read_b128 v[150:153], v162
	ds_read_b128 v[154:157], v162 offset:1024
	ds_read_b128 v[158:161], v162 offset:2048
	ds_read_b128 v[162:165], v162 offset:3072
	ds_read_b128 v[166:169], v148 offset:32768
	ds_read_b128 v[170:173], v148 offset:33792
	ds_read_b128 v[174:177], v148 offset:34816
	ds_read_b128 v[178:181], v148 offset:35840
	ds_read_b128 v[182:185], v148 offset:36864
	ds_read_b128 v[186:189], v148 offset:37888
	ds_read_b128 v[190:193], v148 offset:38912
	ds_read_b128 v[194:197], v148 offset:39936
	s_waitcnt vmcnt(10)
	s_barrier
	s_waitcnt lgkmcnt(0)
	s_setprio 1
	s_waitcnt lgkmcnt(0)
	v_mfma_f32_16x16x32_bf16 v[124:127], v[150:153], v[166:169], v[124:127]
	v_mfma_f32_16x16x32_bf16 v[116:119], v[158:161], v[166:169], v[116:119]
	v_mfma_f32_16x16x32_bf16 v[108:111], v[150:153], v[174:177], v[108:111]
	v_mfma_f32_16x16x32_bf16 v[100:103], v[158:161], v[174:177], v[100:103]
	v_mfma_f32_16x16x32_bf16 v[92:95], v[150:153], v[182:185], v[92:95]
	v_mfma_f32_16x16x32_bf16 v[84:87], v[158:161], v[182:185], v[84:87]
	v_mfma_f32_16x16x32_bf16 v[76:79], v[150:153], v[190:193], v[76:79]
	v_mfma_f32_16x16x32_bf16 v[68:71], v[158:161], v[190:193], v[68:71]
	v_mfma_f32_16x16x32_bf16 v[124:127], v[154:157], v[170:173], v[124:127]
	v_mfma_f32_16x16x32_bf16 v[116:119], v[162:165], v[170:173], v[116:119]
	v_mfma_f32_16x16x32_bf16 v[108:111], v[154:157], v[178:181], v[108:111]
	v_mfma_f32_16x16x32_bf16 v[100:103], v[162:165], v[178:181], v[100:103]
	v_mfma_f32_16x16x32_bf16 v[92:95], v[154:157], v[186:189], v[92:95]
	v_mfma_f32_16x16x32_bf16 v[84:87], v[162:165], v[186:189], v[84:87]
	v_mfma_f32_16x16x32_bf16 v[76:79], v[154:157], v[194:197], v[76:79]
	v_mfma_f32_16x16x32_bf16 v[68:71], v[162:165], v[194:197], v[68:71]
	s_setprio 0
	s_barrier
	s_add_i32 s21, 0, 0x1c000
	s_add_i32 s16, s20, s25
	v_add_u32_e32 v214, s21, v146
	s_add_u32 s0, s18, 0x80
	s_addc_u32 s1, s19, 0
	s_mov_b32 m0, s16
	ds_read_b128 v[202:205], v214
	ds_read_b128 v[206:209], v214 offset:1024
	ds_read_b128 v[210:213], v214 offset:2048
	ds_read_b128 v[214:217], v214 offset:3072
	global_load_lds_dwordx4 v132, s[0:1]
	s_add_i32 m0, s16, 0x2000
	s_nop 0
	global_load_lds_dwordx4 v128, s[0:1]
	s_waitcnt vmcnt(10)
	s_barrier
	s_waitcnt lgkmcnt(0)
	s_setprio 1
	s_waitcnt lgkmcnt(0)
	v_mfma_f32_16x16x32_bf16 v[120:123], v[202:205], v[166:169], v[120:123]
	v_mfma_f32_16x16x32_bf16 v[112:115], v[210:213], v[166:169], v[112:115]
	v_mfma_f32_16x16x32_bf16 v[104:107], v[202:205], v[174:177], v[104:107]
	v_mfma_f32_16x16x32_bf16 v[96:99], v[210:213], v[174:177], v[96:99]
	v_mfma_f32_16x16x32_bf16 v[88:91], v[202:205], v[182:185], v[88:91]
	v_mfma_f32_16x16x32_bf16 v[80:83], v[210:213], v[182:185], v[80:83]
	v_mfma_f32_16x16x32_bf16 v[72:75], v[202:205], v[190:193], v[72:75]
	v_mfma_f32_16x16x32_bf16 v[64:67], v[210:213], v[190:193], v[64:67]
	v_mfma_f32_16x16x32_bf16 v[120:123], v[206:209], v[170:173], v[120:123]
	v_mfma_f32_16x16x32_bf16 v[112:115], v[214:217], v[170:173], v[112:115]
	v_mfma_f32_16x16x32_bf16 v[104:107], v[206:209], v[178:181], v[104:107]
	v_mfma_f32_16x16x32_bf16 v[96:99], v[214:217], v[178:181], v[96:99]
	v_mfma_f32_16x16x32_bf16 v[88:91], v[206:209], v[186:189], v[88:91]
	v_mfma_f32_16x16x32_bf16 v[80:83], v[214:217], v[186:189], v[80:83]
	v_mfma_f32_16x16x32_bf16 v[72:75], v[206:209], v[194:197], v[72:75]
	v_mfma_f32_16x16x32_bf16 v[64:67], v[214:217], v[194:197], v[64:67]
	s_setprio 0
	s_mov_b32 m0, s36
	s_add_u32 s0, s22, 0x80
	s_addc_u32 s1, s23, 0
	s_barrier
	ds_read_b128 v[166:169], v148 offset:49152
	ds_read_b128 v[170:173], v148 offset:50176
	ds_read_b128 v[174:177], v148 offset:51200
	ds_read_b128 v[178:181], v148 offset:52224
	ds_read_b128 v[182:185], v148 offset:53248
	ds_read_b128 v[186:189], v148 offset:54272
	ds_read_b128 v[190:193], v148 offset:55296
	ds_read_b128 v[194:197], v148 offset:56320
	global_load_lds_dwordx4 v134, s[0:1]
	s_mov_b32 m0, s37
	s_nop 0
	global_load_lds_dwordx4 v130, s[0:1]
	s_barrier
; #define PG8_STAGE(bufoff, gbase, voff) do { _Pragma("unroll") for (int _i = 0; _i < 2; ++_i) \
;         __builtin_amdgcn_global_load_lds((const unsigned*)((const char*)(gbase) + (voff)[_i]), (LAS unsigned*)(lds + (bufoff) + ldsw + _i * 8192), 16, 0, 0); } while (0)
; #define PG8_LDA(dst, b, h) do { _Pragma("unroll") for (int m = 0; m < 4; ++m) _Pragma("unroll") for (int k = 0; k < 2; ++k) dst[m][k] = *(const LAS bf16x8*)(lds + PG8_SA(b, h) + aoff + m * 2048 + k * 1024); } while (0)
; #define PG8_LDB(dst, b, h) do { _Pragma("unroll") for (int n = 0; n < 2; ++n) _Pragma("unroll") for (int k = 0; k < 2; ++k) dst[n][k] = *(const LAS bf16x8*)(lds + PG8_SB(b, h) + boff + n * 2048 + k * 1024); } while (0)
; #define PG8_MMA(ai, bj, At, Bt) do { __builtin_amdgcn_s_setprio(1); _Pragma("unroll") for (int m = 0; m < 4; ++m) _Pragma("unroll") for (int n = 0; n < 2; ++n) _Pragma("unroll") for (int k = 0; k < 2; ++k) \
;         acc[ai][bj][m][n] = __builtin_amdgcn_mfma_f32_16x16x32_bf16(Bt[n][k], At[m][k], acc[ai][bj][m][n], 0, 0, 0); __builtin_amdgcn_s_setprio(0); } while (0)
; #define PG8_WAIT_V(n) asm volatile("s_waitcnt vmcnt(" #n ")" ::: "memory")
; #define PG8_WAIT_L(n) asm volatile("s_waitcnt lgkmcnt(" #n ")" ::: "memory")
; #define PG8_BAR __builtin_amdgcn_s_barrier()
; #define PG8_SCHED __builtin_amdgcn_sched_barrier(0)
; template <class Epi, class Sched>
; __device__ __forceinline__ void gemm_phase(LAS unsigned char* lds, const Gemm g, const Sched& S, const Epi& E) {
;     ...
;             PG8_LDB(B0, 0, 0); PG8_SCHED; PG8_LDA(At, 0, 0); PG8_STAGE(PG8_SA(1, 1), a1 + hstep, voffA);
;             PG8_WAIT_L(8); PG8_BAR; PG8_WAIT_L(0); PG8_MMA(0, 0, At, B0); PG8_BAR; PG8_SCHED;
;             PG8_LDB(B1, 0, 1); PG8_STAGE(PG8_SB(0, 0), b2, voffB);
;             PG8_BAR; PG8_WAIT_L(0); PG8_MMA(0, 1, At, B1); PG8_BAR;
;             PG8_LDA(At, 0, 1); PG8_STAGE(PG8_SA(0, 0), a2, voffA);
;             PG8_BAR; PG8_WAIT_L(0); PG8_MMA(1, 0, At, B0); PG8_BAR; PG8_SCHED;
;     ...
;             PG8_BAR; PG8_WAIT_L(0); PG8_MMA(1, 0, At, B0); PG8_BAR; PG8_SCHED;
;             PG8_STAGE(PG8_SB(1, 1), b3 + hstep, voffB);
;             PG8_WAIT_V(6); PG8_BAR; PG8_MMA(1, 1, At, B1); PG8_BAR;
	s_waitcnt lgkmcnt(0)
	s_setprio 1
	s_waitcnt lgkmcnt(0)
	v_mfma_f32_16x16x32_bf16 v[60:63], v[150:153], v[166:169], v[60:63]
	v_mfma_f32_16x16x32_bf16 v[56:59], v[158:161], v[166:169], v[56:59]
	v_mfma_f32_16x16x32_bf16 v[44:47], v[150:153], v[174:177], v[44:47]
	v_mfma_f32_16x16x32_bf16 v[40:43], v[158:161], v[174:177], v[40:43]
	v_mfma_f32_16x16x32_bf16 v[28:31], v[150:153], v[182:185], v[28:31]
	v_mfma_f32_16x16x32_bf16 v[24:27], v[158:161], v[182:185], v[24:27]
	v_mfma_f32_16x16x32_bf16 v[12:15], v[150:153], v[190:193], v[12:15]
	v_mfma_f32_16x16x32_bf16 v[8:11], v[158:161], v[190:193], v[8:11]
	v_mfma_f32_16x16x32_bf16 v[60:63], v[154:157], v[170:173], v[60:63]
	v_mfma_f32_16x16x32_bf16 v[56:59], v[162:165], v[170:173], v[56:59]
	v_mfma_f32_16x16x32_bf16 v[44:47], v[154:157], v[178:181], v[44:47]
	v_mfma_f32_16x16x32_bf16 v[40:43], v[162:165], v[178:181], v[40:43]
	v_mfma_f32_16x16x32_bf16 v[28:31], v[154:157], v[186:189], v[28:31]
	v_mfma_f32_16x16x32_bf16 v[24:27], v[162:165], v[186:189], v[24:27]
	v_mfma_f32_16x16x32_bf16 v[12:15], v[154:157], v[194:197], v[12:15]
	v_mfma_f32_16x16x32_bf16 v[8:11], v[162:165], v[194:197], v[8:11]
	s_setprio 0
	s_barrier
	s_add_u32 s16, s18, 0x40080
	s_addc_u32 s17, s19, 0
	s_add_i32 s18, s21, s25
	s_mov_b32 m0, s18
	s_nop 0
	global_load_lds_dwordx4 v132, s[16:17]
	s_add_i32 m0, s18, 0x2000
	s_nop 0
	global_load_lds_dwordx4 v128, s[16:17]
	s_waitcnt vmcnt(10)
	s_barrier
	s_setprio 1
	v_mfma_f32_16x16x32_bf16 v[52:55], v[202:205], v[166:169], v[52:55]
	v_mfma_f32_16x16x32_bf16 v[48:51], v[210:213], v[166:169], v[48:51]
	v_mfma_f32_16x16x32_bf16 v[36:39], v[202:205], v[174:177], v[36:39]
	v_mfma_f32_16x16x32_bf16 v[32:35], v[210:213], v[174:177], v[32:35]
	v_mfma_f32_16x16x32_bf16 v[20:23], v[202:205], v[182:185], v[20:23]
	v_mfma_f32_16x16x32_bf16 v[16:19], v[210:213], v[182:185], v[16:19]
	v_mfma_f32_16x16x32_bf16 v[4:7], v[202:205], v[190:193], v[4:7]
	v_mfma_f32_16x16x32_bf16 v[0:3], v[210:213], v[190:193], v[0:3]
	v_mfma_f32_16x16x32_bf16 v[52:55], v[206:209], v[170:173], v[52:55]
	v_mfma_f32_16x16x32_bf16 v[48:51], v[214:217], v[170:173], v[48:51]
	v_mfma_f32_16x16x32_bf16 v[36:39], v[206:209], v[178:181], v[36:39]
	v_mfma_f32_16x16x32_bf16 v[32:35], v[214:217], v[178:181], v[32:35]
	v_mfma_f32_16x16x32_bf16 v[20:23], v[206:209], v[186:189], v[20:23]
	v_mfma_f32_16x16x32_bf16 v[16:19], v[214:217], v[186:189], v[16:19]
	v_mfma_f32_16x16x32_bf16 v[4:7], v[206:209], v[194:197], v[4:7]
	v_mfma_f32_16x16x32_bf16 v[0:3], v[214:217], v[194:197], v[0:3]
	s_setprio 0
	s_add_i32 s48, s48, 2
	s_add_u32 s14, s14, 0x100
	s_addc_u32 s15, s15, 0
	s_add_u32 s46, s46, 0x100
	s_addc_u32 s47, s47, 0
	s_cmp_gt_u32 s48, 13
	s_barrier
.LBB0_235:
	ds_read_b128 v[150:153], v147
	ds_read_b128 v[154:157], v147 offset:1024
	ds_read_b128 v[158:161], v147 offset:2048
	ds_read_b128 v[162:165], v147 offset:3072
	s_add_u32 s16, s14, 0xfffc0080
	s_addc_u32 s17, s15, -1
	s_cmp_eq_u32 s48, 12
	s_cselect_b32 s23, s7, s17
	s_cselect_b32 s22, s44, s16
	s_cselect_b32 s19, s5, s47
	s_cselect_b32 s18, s45, s46
	s_add_i32 m0, s13, 0xc000
	ds_read_b128 v[166:169], v148
	ds_read_b128 v[170:173], v148 offset:1024
	ds_read_b128 v[174:177], v148 offset:2048
	ds_read_b128 v[178:181], v148 offset:3072
	ds_read_b128 v[182:185], v148 offset:4096
	ds_read_b128 v[186:189], v148 offset:5120
	ds_read_b128 v[190:193], v148 offset:6144
	ds_read_b128 v[194:197], v148 offset:7168
	global_load_lds_dwordx4 v136, s[14:15]
	s_add_i32 m0, s13, 0xe000
	s_nop 0
	global_load_lds_dwordx4 v138, s[14:15]
	s_waitcnt vmcnt(10)
	s_barrier
	s_waitcnt lgkmcnt(0)
	s_setprio 1
	s_waitcnt lgkmcnt(0)
	v_mfma_f32_16x16x32_bf16 v[124:127], v[150:153], v[166:169], v[124:127]
	v_mfma_f32_16x16x32_bf16 v[116:119], v[158:161], v[166:169], v[116:119]
	v_mfma_f32_16x16x32_bf16 v[108:111], v[150:153], v[174:177], v[108:111]
	v_mfma_f32_16x16x32_bf16 v[100:103], v[158:161], v[174:177], v[100:103]
	v_mfma_f32_16x16x32_bf16 v[92:95], v[150:153], v[182:185], v[92:95]
	v_mfma_f32_16x16x32_bf16 v[84:87], v[158:161], v[182:185], v[84:87]
	v_mfma_f32_16x16x32_bf16 v[76:79], v[150:153], v[190:193], v[76:79]
	v_mfma_f32_16x16x32_bf16 v[68:71], v[158:161], v[190:193], v[68:71]
	v_mfma_f32_16x16x32_bf16 v[124:127], v[154:157], v[170:173], v[124:127]
	v_mfma_f32_16x16x32_bf16 v[116:119], v[162:165], v[170:173], v[116:119]
	v_mfma_f32_16x16x32_bf16 v[108:111], v[154:157], v[178:181], v[108:111]
	v_mfma_f32_16x16x32_bf16 v[100:103], v[162:165], v[178:181], v[100:103]
	v_mfma_f32_16x16x32_bf16 v[92:95], v[154:157], v[186:189], v[92:95]
	v_mfma_f32_16x16x32_bf16 v[84:87], v[162:165], v[186:189], v[84:87]
	v_mfma_f32_16x16x32_bf16 v[76:79], v[154:157], v[194:197], v[76:79]
	v_mfma_f32_16x16x32_bf16 v[68:71], v[162:165], v[194:197], v[68:71]
	s_setprio 0
	s_barrier
	s_add_i32 s16, s40, s25
	s_mov_b32 m0, s16
	ds_read_b128 v[202:205], v149
	ds_read_b128 v[206:209], v149 offset:1024
	ds_read_b128 v[210:213], v149 offset:2048
	ds_read_b128 v[214:217], v149 offset:3072
	global_load_lds_dwordx4 v132, s[18:19]
	s_add_i32 m0, s16, 0x2000
	s_nop 0
	global_load_lds_dwordx4 v128, s[18:19]
	s_waitcnt vmcnt(10)
	s_barrier
; #define PG8_STAGE(bufoff, gbase, voff) do { _Pragma("unroll") for (int _i = 0; _i < 2; ++_i) \
;         __builtin_amdgcn_global_load_lds((const unsigned*)((const char*)(gbase) + (voff)[_i]), (LAS unsigned*)(lds + (bufoff) + ldsw + _i * 8192), 16, 0, 0); } while (0)
; #define PG8_LDA(dst, b, h) do { _Pragma("unroll") for (int m = 0; m < 4; ++m) _Pragma("unroll") for (int k = 0; k < 2; ++k) dst[m][k] = *(const LAS bf16x8*)(lds + PG8_SA(b, h) + aoff + m * 2048 + k * 1024); } while (0)
; #define PG8_LDB(dst, b, h) do { _Pragma("unroll") for (int n = 0; n < 2; ++n) _Pragma("unroll") for (int k = 0; k < 2; ++k) dst[n][k] = *(const LAS bf16x8*)(lds + PG8_SB(b, h) + boff + n * 2048 + k * 1024); } while (0)
; #define PG8_MMA(ai, bj, At, Bt) do { __builtin_amdgcn_s_setprio(1); _Pragma("unroll") for (int m = 0; m < 4; ++m) _Pragma("unroll") for (int n = 0; n < 2; ++n) _Pragma("unroll") for (int k = 0; k < 2; ++k) \
;         acc[ai][bj][m][n] = __builtin_amdgcn_mfma_f32_16x16x32_bf16(Bt[n][k], At[m][k], acc[ai][bj][m][n], 0, 0, 0); __builtin_amdgcn_s_setprio(0); } while (0)
; #define PG8_WAIT_V(n) asm volatile("s_waitcnt vmcnt(" #n ")" ::: "memory")
; #define PG8_WAIT_L(n) asm volatile("s_waitcnt lgkmcnt(" #n ")" ::: "memory")
; #define PG8_BAR __builtin_amdgcn_s_barrier()
; #define PG8_SCHED __builtin_amdgcn_sched_barrier(0)
; template <class Epi, class Sched>
; __device__ __forceinline__ void gemm_phase(LAS unsigned char* lds, const Gemm g, const Sched& S, const Epi& E) {
;     ...
;             PG8_LDB(B1, 0, 1); PG8_STAGE(PG8_SB(0, 0), b2, voffB);
;             PG8_BAR; PG8_WAIT_L(0); PG8_MMA(0, 1, At, B1); PG8_BAR;
;             PG8_LDA(At, 0, 1); PG8_STAGE(PG8_SA(0, 0), a2, voffA);
;             PG8_BAR; PG8_WAIT_L(0); PG8_MMA(1, 0, At, B0); PG8_BAR; PG8_SCHED;
;             PG8_STAGE(PG8_SB(0, 1), b2 + hstep, voffB);
;             PG8_WAIT_V(6); PG8_BAR; PG8_MMA(1, 1, At, B1); PG8_BAR;
;             PG8_LDB(B0, 1, 0); PG8_SCHED; PG8_LDA(At, 1, 0); PG8_STAGE(PG8_SA(0, 1), a2 + hstep, voffA);
;             PG8_WAIT_L(8); PG8_BAR; PG8_WAIT_L(0); PG8_MMA(0, 0, At, B0); PG8_BAR; PG8_SCHED;
	s_waitcnt lgkmcnt(0)
	s_setprio 1
	s_waitcnt lgkmcnt(0)
	v_mfma_f32_16x16x32_bf16 v[120:123], v[202:205], v[166:169], v[120:123]
	v_mfma_f32_16x16x32_bf16 v[112:115], v[210:213], v[166:169], v[112:115]
	v_mfma_f32_16x16x32_bf16 v[104:107], v[202:205], v[174:177], v[104:107]
	v_mfma_f32_16x16x32_bf16 v[96:99], v[210:213], v[174:177], v[96:99]
	v_mfma_f32_16x16x32_bf16 v[88:91], v[202:205], v[182:185], v[88:91]
	v_mfma_f32_16x16x32_bf16 v[80:83], v[210:213], v[182:185], v[80:83]
	v_mfma_f32_16x16x32_bf16 v[72:75], v[202:205], v[190:193], v[72:75]
	v_mfma_f32_16x16x32_bf16 v[64:67], v[210:213], v[190:193], v[64:67]
	v_mfma_f32_16x16x32_bf16 v[120:123], v[206:209], v[170:173], v[120:123]
	v_mfma_f32_16x16x32_bf16 v[112:115], v[214:217], v[170:173], v[112:115]
	v_mfma_f32_16x16x32_bf16 v[104:107], v[206:209], v[178:181], v[104:107]
	v_mfma_f32_16x16x32_bf16 v[96:99], v[214:217], v[178:181], v[96:99]
	v_mfma_f32_16x16x32_bf16 v[88:91], v[206:209], v[186:189], v[88:91]
	v_mfma_f32_16x16x32_bf16 v[80:83], v[214:217], v[186:189], v[80:83]
	v_mfma_f32_16x16x32_bf16 v[72:75], v[206:209], v[194:197], v[72:75]
	v_mfma_f32_16x16x32_bf16 v[64:67], v[214:217], v[194:197], v[64:67]
	s_setprio 0
	s_mov_b32 m0, s13
	s_barrier
	ds_read_b128 v[166:169], v148 offset:16384
	ds_read_b128 v[170:173], v148 offset:17408
	ds_read_b128 v[174:177], v148 offset:18432
	ds_read_b128 v[178:181], v148 offset:19456
	ds_read_b128 v[182:185], v148 offset:20480
	ds_read_b128 v[186:189], v148 offset:21504
	ds_read_b128 v[190:193], v148 offset:22528
	ds_read_b128 v[194:197], v148 offset:23552
	global_load_lds_dwordx4 v134, s[22:23]
	s_mov_b32 m0, s28
	s_nop 0
	global_load_lds_dwordx4 v130, s[22:23]
	s_barrier
	s_waitcnt lgkmcnt(0)
	s_setprio 1
	s_waitcnt lgkmcnt(0)
	v_mfma_f32_16x16x32_bf16 v[60:63], v[150:153], v[166:169], v[60:63]
	v_mfma_f32_16x16x32_bf16 v[56:59], v[158:161], v[166:169], v[56:59]
	v_mfma_f32_16x16x32_bf16 v[44:47], v[150:153], v[174:177], v[44:47]
	v_mfma_f32_16x16x32_bf16 v[40:43], v[158:161], v[174:177], v[40:43]
	v_mfma_f32_16x16x32_bf16 v[28:31], v[150:153], v[182:185], v[28:31]
	v_mfma_f32_16x16x32_bf16 v[24:27], v[158:161], v[182:185], v[24:27]
	v_mfma_f32_16x16x32_bf16 v[12:15], v[150:153], v[190:193], v[12:15]
	v_mfma_f32_16x16x32_bf16 v[8:11], v[158:161], v[190:193], v[8:11]
	v_mfma_f32_16x16x32_bf16 v[60:63], v[154:157], v[170:173], v[60:63]
	v_mfma_f32_16x16x32_bf16 v[56:59], v[162:165], v[170:173], v[56:59]
	v_mfma_f32_16x16x32_bf16 v[44:47], v[154:157], v[178:181], v[44:47]
	v_mfma_f32_16x16x32_bf16 v[40:43], v[162:165], v[178:181], v[40:43]
	v_mfma_f32_16x16x32_bf16 v[28:31], v[154:157], v[186:189], v[28:31]
	v_mfma_f32_16x16x32_bf16 v[24:27], v[162:165], v[186:189], v[24:27]
	v_mfma_f32_16x16x32_bf16 v[12:15], v[154:157], v[194:197], v[12:15]
	v_mfma_f32_16x16x32_bf16 v[8:11], v[162:165], v[194:197], v[8:11]
	s_setprio 0
	s_barrier
	s_add_u32 s16, s18, 0x40000
	s_addc_u32 s17, s19, 0
	s_add_i32 s20, s41, s25
	s_mov_b32 m0, s20
	s_nop 0
	global_load_lds_dwordx4 v132, s[16:17]
	s_add_i32 m0, s20, 0x2000
	s_nop 0
	global_load_lds_dwordx4 v128, s[16:17]
	s_add_u32 s16, s22, 0x40000
	s_addc_u32 s17, s23, 0
	s_mov_b32 m0, s29
	s_nop 0
	global_load_lds_dwordx4 v134, s[16:17]
	s_mov_b32 m0, s33
	s_nop 0
	global_load_lds_dwordx4 v130, s[16:17]
	s_waitcnt vmcnt(12)
	s_barrier
	s_setprio 1
	v_mfma_f32_16x16x32_bf16 v[52:55], v[202:205], v[166:169], v[52:55]
	v_mfma_f32_16x16x32_bf16 v[48:51], v[210:213], v[166:169], v[48:51]
	v_mfma_f32_16x16x32_bf16 v[36:39], v[202:205], v[174:177], v[36:39]
	v_mfma_f32_16x16x32_bf16 v[32:35], v[210:213], v[174:177], v[32:35]
	v_mfma_f32_16x16x32_bf16 v[20:23], v[202:205], v[182:185], v[20:23]
	v_mfma_f32_16x16x32_bf16 v[16:19], v[210:213], v[182:185], v[16:19]
	v_mfma_f32_16x16x32_bf16 v[4:7], v[202:205], v[190:193], v[4:7]
	v_mfma_f32_16x16x32_bf16 v[0:3], v[210:213], v[190:193], v[0:3]
	v_mfma_f32_16x16x32_bf16 v[52:55], v[206:209], v[170:173], v[52:55]
	v_mfma_f32_16x16x32_bf16 v[48:51], v[214:217], v[170:173], v[48:51]
	v_mfma_f32_16x16x32_bf16 v[36:39], v[206:209], v[178:181], v[36:39]
	v_mfma_f32_16x16x32_bf16 v[32:35], v[214:217], v[178:181], v[32:35]
	v_mfma_f32_16x16x32_bf16 v[20:23], v[206:209], v[186:189], v[20:23]
	v_mfma_f32_16x16x32_bf16 v[16:19], v[214:217], v[186:189], v[16:19]
	v_mfma_f32_16x16x32_bf16 v[4:7], v[206:209], v[194:197], v[4:7]
	v_mfma_f32_16x16x32_bf16 v[0:3], v[214:217], v[194:197], v[0:3]
	s_setprio 0
	s_add_i32 s20, 0, 0x18000
	v_add_u32_e32 v162, s20, v146
	s_barrier
	ds_read_b128 v[150:153], v162
	ds_read_b128 v[154:157], v162 offset:1024
	ds_read_b128 v[158:161], v162 offset:2048
	ds_read_b128 v[162:165], v162 offset:3072
	ds_read_b128 v[166:169], v148 offset:32768
	ds_read_b128 v[170:173], v148 offset:33792
	ds_read_b128 v[174:177], v148 offset:34816
	ds_read_b128 v[178:181], v148 offset:35840
	ds_read_b128 v[182:185], v148 offset:36864
	ds_read_b128 v[186:189], v148 offset:37888
	ds_read_b128 v[190:193], v148 offset:38912
	ds_read_b128 v[194:197], v148 offset:39936
	s_waitcnt vmcnt(10)
	s_barrier
; #define PG8_STAGE(bufoff, gbase, voff) do { _Pragma("unroll") for (int _i = 0; _i < 2; ++_i) \
;         __builtin_amdgcn_global_load_lds((const unsigned*)((const char*)(gbase) + (voff)[_i]), (LAS unsigned*)(lds + (bufoff) + ldsw + _i * 8192), 16, 0, 0); } while (0)
; #define PG8_LDA(dst, b, h) do { _Pragma("unroll") for (int m = 0; m < 4; ++m) _Pragma("unroll") for (int k = 0; k < 2; ++k) dst[m][k] = *(const LAS bf16x8*)(lds + PG8_SA(b, h) + aoff + m * 2048 + k * 1024); } while (0)
; #define PG8_LDB(dst, b, h) do { _Pragma("unroll") for (int n = 0; n < 2; ++n) _Pragma("unroll") for (int k = 0; k < 2; ++k) dst[n][k] = *(const LAS bf16x8*)(lds + PG8_SB(b, h) + boff + n * 2048 + k * 1024); } while (0)
; #define PG8_MMA(ai, bj, At, Bt) do { __builtin_amdgcn_s_setprio(1); _Pragma("unroll") for (int m = 0; m < 4; ++m) _Pragma("unroll") for (int n = 0; n < 2; ++n) _Pragma("unroll") for (int k = 0; k < 2; ++k) \
;         acc[ai][bj][m][n] = __builtin_amdgcn_mfma_f32_16x16x32_bf16(Bt[n][k], At[m][k], acc[ai][bj][m][n], 0, 0, 0); __builtin_amdgcn_s_setprio(0); } while (0)
; #define PG8_WAIT_V(n) asm volatile("s_waitcnt vmcnt(" #n ")" ::: "memory")
; #define PG8_WAIT_L(n) asm volatile("s_waitcnt lgkmcnt(" #n ")" ::: "memory")
; #define PG8_BAR __builtin_amdgcn_s_barrier()
; #define PG8_SCHED __builtin_amdgcn_sched_barrier(0)
; template <class Epi, class Sched>
; __device__ __forceinline__ void gemm_phase(LAS unsigned char* lds, const Gemm g, const Sched& S, const Epi& E) {
;     ...
;             PG8_WAIT_L(8); PG8_BAR; PG8_WAIT_L(0); PG8_MMA(0, 0, At, B0); PG8_BAR; PG8_SCHED;
;             PG8_LDB(B1, 1, 1); PG8_STAGE(PG8_SB(1, 0), b3, voffB);
;             PG8_BAR; PG8_WAIT_L(0); PG8_MMA(0, 1, At, B1); PG8_BAR;
;             PG8_LDA(At, 1, 1); PG8_STAGE(PG8_SA(1, 0), a3, voffA);
;             PG8_BAR; PG8_WAIT_L(0); PG8_MMA(1, 0, At, B0); PG8_BAR; PG8_SCHED;
;             PG8_STAGE(PG8_SB(1, 1), b3 + hstep, voffB);
;             PG8_WAIT_V(6); PG8_BAR; PG8_MMA(1, 1, At, B1); PG8_BAR;
	s_waitcnt lgkmcnt(0)
	s_setprio 1
	s_waitcnt lgkmcnt(0)
	v_mfma_f32_16x16x32_bf16 v[124:127], v[150:153], v[166:169], v[124:127]
	v_mfma_f32_16x16x32_bf16 v[116:119], v[158:161], v[166:169], v[116:119]
	v_mfma_f32_16x16x32_bf16 v[108:111], v[150:153], v[174:177], v[108:111]
	v_mfma_f32_16x16x32_bf16 v[100:103], v[158:161], v[174:177], v[100:103]
	v_mfma_f32_16x16x32_bf16 v[92:95], v[150:153], v[182:185], v[92:95]
	v_mfma_f32_16x16x32_bf16 v[84:87], v[158:161], v[182:185], v[84:87]
	v_mfma_f32_16x16x32_bf16 v[76:79], v[150:153], v[190:193], v[76:79]
	v_mfma_f32_16x16x32_bf16 v[68:71], v[158:161], v[190:193], v[68:71]
	v_mfma_f32_16x16x32_bf16 v[124:127], v[154:157], v[170:173], v[124:127]
	v_mfma_f32_16x16x32_bf16 v[116:119], v[162:165], v[170:173], v[116:119]
	v_mfma_f32_16x16x32_bf16 v[108:111], v[154:157], v[178:181], v[108:111]
	v_mfma_f32_16x16x32_bf16 v[100:103], v[162:165], v[178:181], v[100:103]
	v_mfma_f32_16x16x32_bf16 v[92:95], v[154:157], v[186:189], v[92:95]
	v_mfma_f32_16x16x32_bf16 v[84:87], v[162:165], v[186:189], v[84:87]
	v_mfma_f32_16x16x32_bf16 v[76:79], v[154:157], v[194:197], v[76:79]
	v_mfma_f32_16x16x32_bf16 v[68:71], v[162:165], v[194:197], v[68:71]
	s_setprio 0
	s_barrier
	s_add_i32 s21, 0, 0x1c000
	s_add_i32 s16, s20, s25
	v_add_u32_e32 v214, s21, v146
	s_add_u32 s0, s18, 0x80
	s_addc_u32 s1, s19, 0
	s_mov_b32 m0, s16
	ds_read_b128 v[202:205], v214
	ds_read_b128 v[206:209], v214 offset:1024
	ds_read_b128 v[210:213], v214 offset:2048
	ds_read_b128 v[214:217], v214 offset:3072
	global_load_lds_dwordx4 v132, s[0:1]
	s_add_i32 m0, s16, 0x2000
	s_nop 0
	global_load_lds_dwordx4 v128, s[0:1]
	s_waitcnt vmcnt(10)
	s_barrier
	s_waitcnt lgkmcnt(0)
	s_setprio 1
	s_waitcnt lgkmcnt(0)
	v_mfma_f32_16x16x32_bf16 v[120:123], v[202:205], v[166:169], v[120:123]
	v_mfma_f32_16x16x32_bf16 v[112:115], v[210:213], v[166:169], v[112:115]
	v_mfma_f32_16x16x32_bf16 v[104:107], v[202:205], v[174:177], v[104:107]
	v_mfma_f32_16x16x32_bf16 v[96:99], v[210:213], v[174:177], v[96:99]
	v_mfma_f32_16x16x32_bf16 v[88:91], v[202:205], v[182:185], v[88:91]
	v_mfma_f32_16x16x32_bf16 v[80:83], v[210:213], v[182:185], v[80:83]
	v_mfma_f32_16x16x32_bf16 v[72:75], v[202:205], v[190:193], v[72:75]
	v_mfma_f32_16x16x32_bf16 v[64:67], v[210:213], v[190:193], v[64:67]
	v_mfma_f32_16x16x32_bf16 v[120:123], v[206:209], v[170:173], v[120:123]
	v_mfma_f32_16x16x32_bf16 v[112:115], v[214:217], v[170:173], v[112:115]
	v_mfma_f32_16x16x32_bf16 v[104:107], v[206:209], v[178:181], v[104:107]
	v_mfma_f32_16x16x32_bf16 v[96:99], v[214:217], v[178:181], v[96:99]
	v_mfma_f32_16x16x32_bf16 v[88:91], v[206:209], v[186:189], v[88:91]
	v_mfma_f32_16x16x32_bf16 v[80:83], v[214:217], v[186:189], v[80:83]
	v_mfma_f32_16x16x32_bf16 v[72:75], v[206:209], v[194:197], v[72:75]
	v_mfma_f32_16x16x32_bf16 v[64:67], v[214:217], v[194:197], v[64:67]
	s_setprio 0
	s_mov_b32 m0, s36
	s_add_u32 s0, s22, 0x80
	s_addc_u32 s1, s23, 0
	s_barrier
	ds_read_b128 v[166:169], v148 offset:49152
	ds_read_b128 v[170:173], v148 offset:50176
	ds_read_b128 v[174:177], v148 offset:51200
	ds_read_b128 v[178:181], v148 offset:52224
	ds_read_b128 v[182:185], v148 offset:53248
	ds_read_b128 v[186:189], v148 offset:54272
	ds_read_b128 v[190:193], v148 offset:55296
	ds_read_b128 v[194:197], v148 offset:56320
	global_load_lds_dwordx4 v134, s[0:1]
	s_mov_b32 m0, s37
	s_nop 0
	global_load_lds_dwordx4 v130, s[0:1]
	s_barrier
	s_waitcnt lgkmcnt(0)
	s_setprio 1
	s_waitcnt lgkmcnt(0)
	v_mfma_f32_16x16x32_bf16 v[60:63], v[150:153], v[166:169], v[60:63]
	v_mfma_f32_16x16x32_bf16 v[56:59], v[158:161], v[166:169], v[56:59]
	v_mfma_f32_16x16x32_bf16 v[44:47], v[150:153], v[174:177], v[44:47]
	v_mfma_f32_16x16x32_bf16 v[40:43], v[158:161], v[174:177], v[40:43]
	v_mfma_f32_16x16x32_bf16 v[28:31], v[150:153], v[182:185], v[28:31]
	v_mfma_f32_16x16x32_bf16 v[24:27], v[158:161], v[182:185], v[24:27]
	v_mfma_f32_16x16x32_bf16 v[12:15], v[150:153], v[190:193], v[12:15]
	v_mfma_f32_16x16x32_bf16 v[8:11], v[158:161], v[190:193], v[8:11]
	v_mfma_f32_16x16x32_bf16 v[60:63], v[154:157], v[170:173], v[60:63]
	v_mfma_f32_16x16x32_bf16 v[56:59], v[162:165], v[170:173], v[56:59]
	v_mfma_f32_16x16x32_bf16 v[44:47], v[154:157], v[178:181], v[44:47]
	v_mfma_f32_16x16x32_bf16 v[40:43], v[162:165], v[178:181], v[40:43]
	v_mfma_f32_16x16x32_bf16 v[28:31], v[154:157], v[186:189], v[28:31]
	v_mfma_f32_16x16x32_bf16 v[24:27], v[162:165], v[186:189], v[24:27]
	v_mfma_f32_16x16x32_bf16 v[12:15], v[154:157], v[194:197], v[12:15]
	v_mfma_f32_16x16x32_bf16 v[8:11], v[162:165], v[194:197], v[8:11]
	s_setprio 0
	s_barrier
	s_add_u32 s16, s18, 0x40080
	s_addc_u32 s17, s19, 0
	s_add_i32 s18, s21, s25
	s_mov_b32 m0, s18
	s_nop 0
	global_load_lds_dwordx4 v132, s[16:17]
	s_add_i32 m0, s18, 0x2000
	s_nop 0
	global_load_lds_dwordx4 v128, s[16:17]
	s_waitcnt vmcnt(10)
	s_barrier
	s_setprio 1
	v_mfma_f32_16x16x32_bf16 v[52:55], v[202:205], v[166:169], v[52:55]
	v_mfma_f32_16x16x32_bf16 v[48:51], v[210:213], v[166:169], v[48:51]
	v_mfma_f32_16x16x32_bf16 v[36:39], v[202:205], v[174:177], v[36:39]
	v_mfma_f32_16x16x32_bf16 v[32:35], v[210:213], v[174:177], v[32:35]
	v_mfma_f32_16x16x32_bf16 v[20:23], v[202:205], v[182:185], v[20:23]
	v_mfma_f32_16x16x32_bf16 v[16:19], v[210:213], v[182:185], v[16:19]
	v_mfma_f32_16x16x32_bf16 v[4:7], v[202:205], v[190:193], v[4:7]
	v_mfma_f32_16x16x32_bf16 v[0:3], v[210:213], v[190:193], v[0:3]
	v_mfma_f32_16x16x32_bf16 v[52:55], v[206:209], v[170:173], v[52:55]
	v_mfma_f32_16x16x32_bf16 v[48:51], v[214:217], v[170:173], v[48:51]
	v_mfma_f32_16x16x32_bf16 v[36:39], v[206:209], v[178:181], v[36:39]
	v_mfma_f32_16x16x32_bf16 v[32:35], v[214:217], v[178:181], v[32:35]
	v_mfma_f32_16x16x32_bf16 v[20:23], v[206:209], v[186:189], v[20:23]
	v_mfma_f32_16x16x32_bf16 v[16:19], v[214:217], v[186:189], v[16:19]
	v_mfma_f32_16x16x32_bf16 v[4:7], v[206:209], v[194:197], v[4:7]
	v_mfma_f32_16x16x32_bf16 v[0:3], v[214:217], v[194:197], v[0:3]
	s_setprio 0
	s_add_i32 s48, s48, 2
	s_add_u32 s14, s14, 0x100
	s_addc_u32 s15, s15, 0
	s_add_u32 s46, s46, 0x100
	s_addc_u32 s47, s47, 0
	s_cmp_gt_u32 s48, 13
	s_cbranch_scc1 .Lconc_last_g0
	s_barrier
	s_branch .LBB0_235

; #define PG8_STAGE(bufoff, gbase, voff) do { _Pragma("unroll") for (int _i = 0; _i < 2; ++_i) \
;         __builtin_amdgcn_global_load_lds((const unsigned*)((const char*)(gbase) + (voff)[_i]), (LAS unsigned*)(lds + (bufoff) + ldsw + _i * 8192), 16, 0, 0); } while (0)
; #define PG8_LDA(dst, b, h) do { _Pragma("unroll") for (int m = 0; m < 4; ++m) _Pragma("unroll") for (int k = 0; k < 2; ++k) dst[m][k] = *(const LAS bf16x8*)(lds + PG8_SA(b, h) + aoff + m * 2048 + k * 1024); } while (0)
; #define PG8_LDB(dst, b, h) do { _Pragma("unroll") for (int n = 0; n < 2; ++n) _Pragma("unroll") for (int k = 0; k < 2; ++k) dst[n][k] = *(const LAS bf16x8*)(lds + PG8_SB(b, h) + boff + n * 2048 + k * 1024); } while (0)
; #define PG8_WAIT_V(n) asm volatile("s_waitcnt vmcnt(" #n ")" ::: "memory")
; #define PG8_WAIT_L(n) asm volatile("s_waitcnt lgkmcnt(" #n ")" ::: "memory")
; #define PG8_BAR __builtin_amdgcn_s_barrier()
; #define PG8_SCHED __builtin_amdgcn_sched_barrier(0)
; template <class Epi, class Sched>
; __device__ __forceinline__ void gemm_phase(LAS unsigned char* lds, const Gemm g, const Sched& S, const Epi& E) {
;     ...
;         const bool has_next = S.next(ui + 1, nxt);
;         const char* nA = has_next ? (const char*)g.A + (size_t)nxt.pm * tstep : cA; const char* nB = has_next ? (const char*)g.Bt + (size_t)nxt.pn * tstep : cB;
;         for (int t = 0; t < nt; t += 2) {
;             const bool last = (t == nt - 2);
;             const char* a1 = cA + (size_t)(t + 1) * kstep;
;             const char* a2 = last ? nA : cA + (size_t)(t + 2) * kstep; const char* b2 = last ? nB : cB + (size_t)(t + 2) * kstep;
;             const char* a3 = a2 + kstep; const char* b3 = b2 + kstep;
;             PG8_LDB(B0, 0, 0); PG8_SCHED; PG8_LDA(At, 0, 0); PG8_STAGE(PG8_SA(1, 1), a1 + hstep, voffA);
;             PG8_WAIT_L(8); PG8_BAR; PG8_WAIT_L(0); PG8_MMA(0, 0, At, B0); PG8_BAR; PG8_SCHED;
;             PG8_LDB(B1, 0, 1); PG8_STAGE(PG8_SB(0, 0), b2, voffB);
;             PG8_BAR; PG8_WAIT_L(0); PG8_MMA(0, 1, At, B1); PG8_BAR;
;             PG8_LDA(At, 0, 1); PG8_STAGE(PG8_SA(0, 0), a2, voffA);
;             PG8_BAR; PG8_WAIT_L(0); PG8_MMA(1, 0, At, B0); PG8_BAR; PG8_SCHED;
;             PG8_STAGE(PG8_SB(0, 1), b2 + hstep, voffB);
;             PG8_WAIT_V(6); PG8_BAR; PG8_MMA(1, 1, At, B1); PG8_BAR;
.LBB0_304:
	s_add_u32 s0, s28, 0x100
	s_addc_u32 s67, s29, 0
	s_mov_b32 s68, -2
	ds_read_b128 v[144:147], v165
	ds_read_b128 v[148:151], v165 offset:1024
	ds_read_b128 v[152:155], v165 offset:2048
	ds_read_b128 v[156:159], v165 offset:3072
	s_add_u32 s28, s26, 0x100
	s_addc_u32 s29, s27, 0
	s_cmp_eq_u32 s68, 40
	s_cselect_b32 s37, s5, s29
	s_cselect_b32 s36, s4, s28
	s_cselect_b32 s35, s7, s67
	s_cselect_b32 s34, s6, s0
	v_lshl_add_u64 v[160:161], s[26:27], 0, v[136:137]
	s_add_i32 m0, s42, 0xc000
	ds_read_b128 v[168:171], v166
	ds_read_b128 v[172:175], v166 offset:1024
	ds_read_b128 v[176:179], v166 offset:2048
	ds_read_b128 v[180:183], v166 offset:3072
	ds_read_b128 v[184:187], v166 offset:4096
	ds_read_b128 v[188:191], v166 offset:5120
	ds_read_b128 v[192:195], v166 offset:6144
	ds_read_b128 v[196:199], v166 offset:7168
	global_load_lds_dwordx4 v[160:161], off
	v_lshl_add_u64 v[160:161], s[26:27], 0, v[138:139]
	s_add_i32 m0, s42, 0xe000
	s_nop 0
	global_load_lds_dwordx4 v[160:161], off
	s_waitcnt vmcnt(10)
	s_barrier
	s_waitcnt lgkmcnt(0)
	s_setprio 1
	s_waitcnt lgkmcnt(0)
	v_mfma_f32_16x16x32_bf16 v[124:127], v[144:147], v[168:171], 0
	v_mfma_f32_16x16x32_bf16 v[120:123], v[152:155], v[168:171], 0
	v_mfma_f32_16x16x32_bf16 v[116:119], v[144:147], v[176:179], 0
	v_mfma_f32_16x16x32_bf16 v[104:107], v[152:155], v[176:179], 0
	v_mfma_f32_16x16x32_bf16 v[96:99], v[144:147], v[184:187], 0
	v_mfma_f32_16x16x32_bf16 v[88:91], v[152:155], v[184:187], 0
	v_mfma_f32_16x16x32_bf16 v[80:83], v[144:147], v[192:195], 0
	v_mfma_f32_16x16x32_bf16 v[72:75], v[152:155], v[192:195], 0
	v_mfma_f32_16x16x32_bf16 v[124:127], v[148:151], v[172:175], v[124:127]
	v_mfma_f32_16x16x32_bf16 v[120:123], v[156:159], v[172:175], v[120:123]
	v_mfma_f32_16x16x32_bf16 v[116:119], v[148:151], v[180:183], v[116:119]
	v_mfma_f32_16x16x32_bf16 v[104:107], v[156:159], v[180:183], v[104:107]
	v_mfma_f32_16x16x32_bf16 v[96:99], v[148:151], v[188:191], v[96:99]
	v_mfma_f32_16x16x32_bf16 v[88:91], v[156:159], v[188:191], v[88:91]
	v_mfma_f32_16x16x32_bf16 v[80:83], v[148:151], v[196:199], v[80:83]
	v_mfma_f32_16x16x32_bf16 v[72:75], v[156:159], v[196:199], v[72:75]
	s_setprio 0
	s_barrier
	s_add_i32 s16, s58, s40
	s_mov_b32 m0, s16
	ds_read_b128 v[202:205], v167
	ds_read_b128 v[206:209], v167 offset:1024
	ds_read_b128 v[210:213], v167 offset:2048
	ds_read_b128 v[214:217], v167 offset:3072
	global_load_lds_dwordx4 v132, s[34:35]
	s_add_i32 m0, s16, 0x2000
	s_nop 0
	global_load_lds_dwordx4 v128, s[34:35]
	s_waitcnt vmcnt(10)
	s_barrier
	s_waitcnt lgkmcnt(0)
	s_setprio 1
	s_waitcnt lgkmcnt(0)
	v_mfma_f32_16x16x32_bf16 v[112:115], v[202:205], v[168:171], 0
	v_mfma_f32_16x16x32_bf16 v[108:111], v[210:213], v[168:171], 0
	v_mfma_f32_16x16x32_bf16 v[100:103], v[202:205], v[176:179], 0
	v_mfma_f32_16x16x32_bf16 v[92:95], v[210:213], v[176:179], 0
	v_mfma_f32_16x16x32_bf16 v[84:87], v[202:205], v[184:187], 0
	v_mfma_f32_16x16x32_bf16 v[76:79], v[210:213], v[184:187], 0
	v_mfma_f32_16x16x32_bf16 v[68:71], v[202:205], v[192:195], 0
	v_mfma_f32_16x16x32_bf16 v[64:67], v[210:213], v[192:195], 0
	v_mfma_f32_16x16x32_bf16 v[112:115], v[206:209], v[172:175], v[112:115]
	v_mfma_f32_16x16x32_bf16 v[108:111], v[214:217], v[172:175], v[108:111]
	v_mfma_f32_16x16x32_bf16 v[100:103], v[206:209], v[180:183], v[100:103]
	v_mfma_f32_16x16x32_bf16 v[92:95], v[214:217], v[180:183], v[92:95]
	v_mfma_f32_16x16x32_bf16 v[84:87], v[206:209], v[188:191], v[84:87]
	v_mfma_f32_16x16x32_bf16 v[76:79], v[214:217], v[188:191], v[76:79]
	v_mfma_f32_16x16x32_bf16 v[68:71], v[206:209], v[196:199], v[68:71]
	v_mfma_f32_16x16x32_bf16 v[64:67], v[214:217], v[196:199], v[64:67]
	s_setprio 0
	s_mov_b32 m0, s42
	s_barrier
	ds_read_b128 v[168:171], v166 offset:16384
	ds_read_b128 v[172:175], v166 offset:17408
	ds_read_b128 v[176:179], v166 offset:18432
	ds_read_b128 v[180:183], v166 offset:19456
	ds_read_b128 v[184:187], v166 offset:20480
	ds_read_b128 v[188:191], v166 offset:21504
	ds_read_b128 v[192:195], v166 offset:22528
	ds_read_b128 v[196:199], v166 offset:23552
	global_load_lds_dwordx4 v134, s[36:37]
	s_mov_b32 m0, s43
	s_nop 0
	global_load_lds_dwordx4 v130, s[36:37]
	s_barrier
	s_waitcnt lgkmcnt(0)
	s_setprio 1
	s_waitcnt lgkmcnt(0)
	v_mfma_f32_16x16x32_bf16 v[60:63], v[144:147], v[168:171], 0
	v_mfma_f32_16x16x32_bf16 v[56:59], v[152:155], v[168:171], 0
	v_mfma_f32_16x16x32_bf16 v[48:51], v[144:147], v[176:179], 0
	v_mfma_f32_16x16x32_bf16 v[40:43], v[152:155], v[176:179], 0
	v_mfma_f32_16x16x32_bf16 v[32:35], v[144:147], v[184:187], 0
	v_mfma_f32_16x16x32_bf16 v[24:27], v[152:155], v[184:187], 0
	v_mfma_f32_16x16x32_bf16 v[16:19], v[144:147], v[192:195], 0
	v_mfma_f32_16x16x32_bf16 v[8:11], v[152:155], v[192:195], 0
	v_mfma_f32_16x16x32_bf16 v[60:63], v[148:151], v[172:175], v[60:63]
	v_mfma_f32_16x16x32_bf16 v[56:59], v[156:159], v[172:175], v[56:59]
	v_mfma_f32_16x16x32_bf16 v[48:51], v[148:151], v[180:183], v[48:51]
	v_mfma_f32_16x16x32_bf16 v[40:43], v[156:159], v[180:183], v[40:43]
	v_mfma_f32_16x16x32_bf16 v[32:35], v[148:151], v[188:191], v[32:35]
	v_mfma_f32_16x16x32_bf16 v[24:27], v[156:159], v[188:191], v[24:27]
	v_mfma_f32_16x16x32_bf16 v[16:19], v[148:151], v[196:199], v[16:19]
	v_mfma_f32_16x16x32_bf16 v[8:11], v[156:159], v[196:199], v[8:11]
	s_setprio 0
	s_barrier
	s_add_u32 s16, s34, 0xb0000
	s_addc_u32 s17, s35, 0
	s_add_i32 s20, s59, s40
	s_mov_b32 m0, s20
	s_nop 0
	global_load_lds_dwordx4 v132, s[16:17]
	s_add_i32 m0, s20, 0x2000
	s_nop 0
	global_load_lds_dwordx4 v128, s[16:17]
	s_add_u32 s16, s36, 0xb0000
	s_addc_u32 s17, s37, 0
	s_mov_b32 m0, s44
	s_nop 0
	global_load_lds_dwordx4 v134, s[16:17]
	s_mov_b32 m0, s45
	s_nop 0
	global_load_lds_dwordx4 v130, s[16:17]
	s_waitcnt vmcnt(12)
	s_barrier
; #define PG8_STAGE(bufoff, gbase, voff) do { _Pragma("unroll") for (int _i = 0; _i < 2; ++_i) \
;         __builtin_amdgcn_global_load_lds((const unsigned*)((const char*)(gbase) + (voff)[_i]), (LAS unsigned*)(lds + (bufoff) + ldsw + _i * 8192), 16, 0, 0); } while (0)
; #define PG8_LDA(dst, b, h) do { _Pragma("unroll") for (int m = 0; m < 4; ++m) _Pragma("unroll") for (int k = 0; k < 2; ++k) dst[m][k] = *(const LAS bf16x8*)(lds + PG8_SA(b, h) + aoff + m * 2048 + k * 1024); } while (0)
; #define PG8_LDB(dst, b, h) do { _Pragma("unroll") for (int n = 0; n < 2; ++n) _Pragma("unroll") for (int k = 0; k < 2; ++k) dst[n][k] = *(const LAS bf16x8*)(lds + PG8_SB(b, h) + boff + n * 2048 + k * 1024); } while (0)
; #define PG8_MMA(ai, bj, At, Bt) do { __builtin_amdgcn_s_setprio(1); _Pragma("unroll") for (int m = 0; m < 4; ++m) _Pragma("unroll") for (int n = 0; n < 2; ++n) _Pragma("unroll") for (int k = 0; k < 2; ++k) \
;         acc[ai][bj][m][n] = __builtin_amdgcn_mfma_f32_16x16x32_bf16(Bt[n][k], At[m][k], acc[ai][bj][m][n], 0, 0, 0); __builtin_amdgcn_s_setprio(0); } while (0)
; #define PG8_WAIT_V(n) asm volatile("s_waitcnt vmcnt(" #n ")" ::: "memory")
; #define PG8_WAIT_L(n) asm volatile("s_waitcnt lgkmcnt(" #n ")" ::: "memory")
; #define PG8_BAR __builtin_amdgcn_s_barrier()
; #define PG8_SCHED __builtin_amdgcn_sched_barrier(0)
; template <class Epi, class Sched>
; __device__ __forceinline__ void gemm_phase(LAS unsigned char* lds, const Gemm g, const Sched& S, const Epi& E) {
;     ...
;             PG8_WAIT_V(6); PG8_BAR; PG8_MMA(1, 1, At, B1); PG8_BAR;
;             PG8_LDB(B0, 1, 0); PG8_SCHED; PG8_LDA(At, 1, 0); PG8_STAGE(PG8_SA(0, 1), a2 + hstep, voffA);
;             PG8_WAIT_L(8); PG8_BAR; PG8_WAIT_L(0); PG8_MMA(0, 0, At, B0); PG8_BAR; PG8_SCHED;
;             PG8_LDB(B1, 1, 1); PG8_STAGE(PG8_SB(1, 0), b3, voffB);
;             PG8_BAR; PG8_WAIT_L(0); PG8_MMA(0, 1, At, B1); PG8_BAR;
;             PG8_LDA(At, 1, 1); PG8_STAGE(PG8_SA(1, 0), a3, voffA);
;             PG8_BAR; PG8_WAIT_L(0); PG8_MMA(1, 0, At, B0); PG8_BAR; PG8_SCHED;
	s_setprio 1
	v_mfma_f32_16x16x32_bf16 v[52:55], v[202:205], v[168:171], 0
	v_mfma_f32_16x16x32_bf16 v[44:47], v[210:213], v[168:171], 0
	v_mfma_f32_16x16x32_bf16 v[36:39], v[202:205], v[176:179], 0
	v_mfma_f32_16x16x32_bf16 v[28:31], v[210:213], v[176:179], 0
	v_mfma_f32_16x16x32_bf16 v[20:23], v[202:205], v[184:187], 0
	v_mfma_f32_16x16x32_bf16 v[12:15], v[210:213], v[184:187], 0
	v_mfma_f32_16x16x32_bf16 v[4:7], v[202:205], v[192:195], 0
	v_mfma_f32_16x16x32_bf16 v[0:3], v[210:213], v[192:195], 0
	v_mfma_f32_16x16x32_bf16 v[52:55], v[206:209], v[172:175], v[52:55]
	v_mfma_f32_16x16x32_bf16 v[44:47], v[214:217], v[172:175], v[44:47]
	v_mfma_f32_16x16x32_bf16 v[36:39], v[206:209], v[180:183], v[36:39]
	v_mfma_f32_16x16x32_bf16 v[28:31], v[214:217], v[180:183], v[28:31]
	v_mfma_f32_16x16x32_bf16 v[20:23], v[206:209], v[188:191], v[20:23]
	v_mfma_f32_16x16x32_bf16 v[12:15], v[214:217], v[188:191], v[12:15]
	v_mfma_f32_16x16x32_bf16 v[4:7], v[206:209], v[196:199], v[4:7]
	v_mfma_f32_16x16x32_bf16 v[0:3], v[214:217], v[196:199], v[0:3]
	s_setprio 0
	s_add_i32 s20, 0, 0x18000
	v_add_u32_e32 v156, s20, v164
	s_barrier
	ds_read_b128 v[144:147], v156
	ds_read_b128 v[148:151], v156 offset:1024
	ds_read_b128 v[152:155], v156 offset:2048
	ds_read_b128 v[156:159], v156 offset:3072
	ds_read_b128 v[168:171], v166 offset:32768
	ds_read_b128 v[172:175], v166 offset:33792
	ds_read_b128 v[176:179], v166 offset:34816
	ds_read_b128 v[180:183], v166 offset:35840
	ds_read_b128 v[184:187], v166 offset:36864
	ds_read_b128 v[188:191], v166 offset:37888
	ds_read_b128 v[192:195], v166 offset:38912
	ds_read_b128 v[196:199], v166 offset:39936
	s_waitcnt vmcnt(10)
	s_barrier
	s_waitcnt lgkmcnt(0)
	s_setprio 1
	s_waitcnt lgkmcnt(0)
	v_mfma_f32_16x16x32_bf16 v[124:127], v[144:147], v[168:171], v[124:127]
	v_mfma_f32_16x16x32_bf16 v[120:123], v[152:155], v[168:171], v[120:123]
	v_mfma_f32_16x16x32_bf16 v[116:119], v[144:147], v[176:179], v[116:119]
	v_mfma_f32_16x16x32_bf16 v[104:107], v[152:155], v[176:179], v[104:107]
	v_mfma_f32_16x16x32_bf16 v[96:99], v[144:147], v[184:187], v[96:99]
	v_mfma_f32_16x16x32_bf16 v[88:91], v[152:155], v[184:187], v[88:91]
	v_mfma_f32_16x16x32_bf16 v[80:83], v[144:147], v[192:195], v[80:83]
	v_mfma_f32_16x16x32_bf16 v[72:75], v[152:155], v[192:195], v[72:75]
	v_mfma_f32_16x16x32_bf16 v[124:127], v[148:151], v[172:175], v[124:127]
	v_mfma_f32_16x16x32_bf16 v[120:123], v[156:159], v[172:175], v[120:123]
	v_mfma_f32_16x16x32_bf16 v[116:119], v[148:151], v[180:183], v[116:119]
	v_mfma_f32_16x16x32_bf16 v[104:107], v[156:159], v[180:183], v[104:107]
	v_mfma_f32_16x16x32_bf16 v[96:99], v[148:151], v[188:191], v[96:99]
	v_mfma_f32_16x16x32_bf16 v[88:91], v[156:159], v[188:191], v[88:91]
	v_mfma_f32_16x16x32_bf16 v[80:83], v[148:151], v[196:199], v[80:83]
	v_mfma_f32_16x16x32_bf16 v[72:75], v[156:159], v[196:199], v[72:75]
	s_setprio 0
	s_barrier
	s_add_i32 s21, 0, 0x1c000
	s_add_i32 s16, s20, s40
	v_add_u32_e32 v214, s21, v164
	s_add_u32 s8, s34, 0x80
	s_addc_u32 s9, s35, 0
	s_mov_b32 m0, s16
	ds_read_b128 v[202:205], v214
	ds_read_b128 v[206:209], v214 offset:1024
	ds_read_b128 v[210:213], v214 offset:2048
	ds_read_b128 v[214:217], v214 offset:3072
	global_load_lds_dwordx4 v132, s[8:9]
	s_add_i32 m0, s16, 0x2000
	s_nop 0
	global_load_lds_dwordx4 v128, s[8:9]
	s_waitcnt vmcnt(10)
	s_barrier
	s_waitcnt lgkmcnt(0)
	s_setprio 1
	s_waitcnt lgkmcnt(0)
	v_mfma_f32_16x16x32_bf16 v[112:115], v[202:205], v[168:171], v[112:115]
	v_mfma_f32_16x16x32_bf16 v[108:111], v[210:213], v[168:171], v[108:111]
	v_mfma_f32_16x16x32_bf16 v[100:103], v[202:205], v[176:179], v[100:103]
	v_mfma_f32_16x16x32_bf16 v[92:95], v[210:213], v[176:179], v[92:95]
	v_mfma_f32_16x16x32_bf16 v[84:87], v[202:205], v[184:187], v[84:87]
	v_mfma_f32_16x16x32_bf16 v[76:79], v[210:213], v[184:187], v[76:79]
	v_mfma_f32_16x16x32_bf16 v[68:71], v[202:205], v[192:195], v[68:71]
	v_mfma_f32_16x16x32_bf16 v[64:67], v[210:213], v[192:195], v[64:67]
	v_mfma_f32_16x16x32_bf16 v[112:115], v[206:209], v[172:175], v[112:115]
	v_mfma_f32_16x16x32_bf16 v[108:111], v[214:217], v[172:175], v[108:111]
	v_mfma_f32_16x16x32_bf16 v[100:103], v[206:209], v[180:183], v[100:103]
	v_mfma_f32_16x16x32_bf16 v[92:95], v[214:217], v[180:183], v[92:95]
	v_mfma_f32_16x16x32_bf16 v[84:87], v[206:209], v[188:191], v[84:87]
	v_mfma_f32_16x16x32_bf16 v[76:79], v[214:217], v[188:191], v[76:79]
	v_mfma_f32_16x16x32_bf16 v[68:71], v[206:209], v[196:199], v[68:71]
	v_mfma_f32_16x16x32_bf16 v[64:67], v[214:217], v[196:199], v[64:67]
	s_setprio 0
	s_mov_b32 m0, s52
	s_add_u32 s8, s36, 0x80
	s_addc_u32 s9, s37, 0
	s_barrier
	ds_read_b128 v[168:171], v166 offset:49152
	ds_read_b128 v[172:175], v166 offset:50176
	ds_read_b128 v[176:179], v166 offset:51200
	ds_read_b128 v[180:183], v166 offset:52224
	ds_read_b128 v[184:187], v166 offset:53248
	ds_read_b128 v[188:191], v166 offset:54272
	ds_read_b128 v[192:195], v166 offset:55296
	ds_read_b128 v[196:199], v166 offset:56320
	global_load_lds_dwordx4 v134, s[8:9]
	s_mov_b32 m0, s53
	s_nop 0
	global_load_lds_dwordx4 v130, s[8:9]
	s_barrier
; #define PG8_STAGE(bufoff, gbase, voff) do { _Pragma("unroll") for (int _i = 0; _i < 2; ++_i) \
;         __builtin_amdgcn_global_load_lds((const unsigned*)((const char*)(gbase) + (voff)[_i]), (LAS unsigned*)(lds + (bufoff) + ldsw + _i * 8192), 16, 0, 0); } while (0)
; #define PG8_LDA(dst, b, h) do { _Pragma("unroll") for (int m = 0; m < 4; ++m) _Pragma("unroll") for (int k = 0; k < 2; ++k) dst[m][k] = *(const LAS bf16x8*)(lds + PG8_SA(b, h) + aoff + m * 2048 + k * 1024); } while (0)
; #define PG8_LDB(dst, b, h) do { _Pragma("unroll") for (int n = 0; n < 2; ++n) _Pragma("unroll") for (int k = 0; k < 2; ++k) dst[n][k] = *(const LAS bf16x8*)(lds + PG8_SB(b, h) + boff + n * 2048 + k * 1024); } while (0)
; #define PG8_MMA(ai, bj, At, Bt) do { __builtin_amdgcn_s_setprio(1); _Pragma("unroll") for (int m = 0; m < 4; ++m) _Pragma("unroll") for (int n = 0; n < 2; ++n) _Pragma("unroll") for (int k = 0; k < 2; ++k) \
;         acc[ai][bj][m][n] = __builtin_amdgcn_mfma_f32_16x16x32_bf16(Bt[n][k], At[m][k], acc[ai][bj][m][n], 0, 0, 0); __builtin_amdgcn_s_setprio(0); } while (0)
; #define PG8_WAIT_V(n) asm volatile("s_waitcnt vmcnt(" #n ")" ::: "memory")
; #define PG8_WAIT_L(n) asm volatile("s_waitcnt lgkmcnt(" #n ")" ::: "memory")
; #define PG8_BAR __builtin_amdgcn_s_barrier()
; #define PG8_SCHED __builtin_amdgcn_sched_barrier(0)
; template <class Epi, class Sched>
; __device__ __forceinline__ void gemm_phase(LAS unsigned char* lds, const Gemm g, const Sched& S, const Epi& E) {
;     ...
;             PG8_LDB(B0, 0, 0); PG8_SCHED; PG8_LDA(At, 0, 0); PG8_STAGE(PG8_SA(1, 1), a1 + hstep, voffA);
;             PG8_WAIT_L(8); PG8_BAR; PG8_WAIT_L(0); PG8_MMA(0, 0, At, B0); PG8_BAR; PG8_SCHED;
;             PG8_LDB(B1, 0, 1); PG8_STAGE(PG8_SB(0, 0), b2, voffB);
;             PG8_BAR; PG8_WAIT_L(0); PG8_MMA(0, 1, At, B1); PG8_BAR;
;             PG8_LDA(At, 0, 1); PG8_STAGE(PG8_SA(0, 0), a2, voffA);
;             PG8_BAR; PG8_WAIT_L(0); PG8_MMA(1, 0, At, B0); PG8_BAR; PG8_SCHED;
;     ...
;             PG8_BAR; PG8_WAIT_L(0); PG8_MMA(1, 0, At, B0); PG8_BAR; PG8_SCHED;
;             PG8_STAGE(PG8_SB(1, 1), b3 + hstep, voffB);
;             PG8_WAIT_V(6); PG8_BAR; PG8_MMA(1, 1, At, B1); PG8_BAR;
	s_waitcnt lgkmcnt(0)
	s_setprio 1
	s_waitcnt lgkmcnt(0)
	v_mfma_f32_16x16x32_bf16 v[60:63], v[144:147], v[168:171], v[60:63]
	v_mfma_f32_16x16x32_bf16 v[56:59], v[152:155], v[168:171], v[56:59]
	v_mfma_f32_16x16x32_bf16 v[48:51], v[144:147], v[176:179], v[48:51]
	v_mfma_f32_16x16x32_bf16 v[40:43], v[152:155], v[176:179], v[40:43]
	v_mfma_f32_16x16x32_bf16 v[32:35], v[144:147], v[184:187], v[32:35]
	v_mfma_f32_16x16x32_bf16 v[24:27], v[152:155], v[184:187], v[24:27]
	v_mfma_f32_16x16x32_bf16 v[16:19], v[144:147], v[192:195], v[16:19]
	v_mfma_f32_16x16x32_bf16 v[8:11], v[152:155], v[192:195], v[8:11]
	v_mfma_f32_16x16x32_bf16 v[60:63], v[148:151], v[172:175], v[60:63]
	v_mfma_f32_16x16x32_bf16 v[56:59], v[156:159], v[172:175], v[56:59]
	v_mfma_f32_16x16x32_bf16 v[48:51], v[148:151], v[180:183], v[48:51]
	v_mfma_f32_16x16x32_bf16 v[40:43], v[156:159], v[180:183], v[40:43]
	v_mfma_f32_16x16x32_bf16 v[32:35], v[148:151], v[188:191], v[32:35]
	v_mfma_f32_16x16x32_bf16 v[24:27], v[156:159], v[188:191], v[24:27]
	v_mfma_f32_16x16x32_bf16 v[16:19], v[148:151], v[196:199], v[16:19]
	v_mfma_f32_16x16x32_bf16 v[8:11], v[156:159], v[196:199], v[8:11]
	s_setprio 0
	s_barrier
	s_add_u32 s16, s34, 0xb0080
	s_addc_u32 s17, s35, 0
	s_add_i32 s20, s21, s40
	s_mov_b32 m0, s20
	s_nop 0
	global_load_lds_dwordx4 v132, s[16:17]
	s_add_i32 m0, s20, 0x2000
	s_nop 0
	global_load_lds_dwordx4 v128, s[16:17]
	s_waitcnt vmcnt(10)
	s_barrier
	s_setprio 1
	v_mfma_f32_16x16x32_bf16 v[52:55], v[202:205], v[168:171], v[52:55]
	v_mfma_f32_16x16x32_bf16 v[44:47], v[210:213], v[168:171], v[44:47]
	v_mfma_f32_16x16x32_bf16 v[36:39], v[202:205], v[176:179], v[36:39]
	v_mfma_f32_16x16x32_bf16 v[28:31], v[210:213], v[176:179], v[28:31]
	v_mfma_f32_16x16x32_bf16 v[20:23], v[202:205], v[184:187], v[20:23]
	v_mfma_f32_16x16x32_bf16 v[12:15], v[210:213], v[184:187], v[12:15]
	v_mfma_f32_16x16x32_bf16 v[4:7], v[202:205], v[192:195], v[4:7]
	v_mfma_f32_16x16x32_bf16 v[0:3], v[210:213], v[192:195], v[0:3]
	v_mfma_f32_16x16x32_bf16 v[52:55], v[206:209], v[172:175], v[52:55]
	v_mfma_f32_16x16x32_bf16 v[44:47], v[214:217], v[172:175], v[44:47]
	v_mfma_f32_16x16x32_bf16 v[36:39], v[206:209], v[180:183], v[36:39]
	v_mfma_f32_16x16x32_bf16 v[28:31], v[214:217], v[180:183], v[28:31]
	v_mfma_f32_16x16x32_bf16 v[20:23], v[206:209], v[188:191], v[20:23]
	v_mfma_f32_16x16x32_bf16 v[12:15], v[214:217], v[188:191], v[12:15]
	v_mfma_f32_16x16x32_bf16 v[4:7], v[206:209], v[196:199], v[4:7]
	v_mfma_f32_16x16x32_bf16 v[0:3], v[214:217], v[196:199], v[0:3]
	s_setprio 0
	s_add_i32 s68, s68, 2
	s_add_u32 s0, s0, 0x100
	s_addc_u32 s67, s67, 0
	s_cmp_gt_u32 s68, 41
	s_mov_b64 s[26:27], s[28:29]
	s_barrier
.LBB0_305:
	ds_read_b128 v[144:147], v165
	ds_read_b128 v[148:151], v165 offset:1024
	ds_read_b128 v[152:155], v165 offset:2048
	ds_read_b128 v[156:159], v165 offset:3072
	s_add_u32 s28, s26, 0x100
	s_addc_u32 s29, s27, 0
	s_cmp_eq_u32 s68, 40
	s_cselect_b32 s37, s5, s29
	s_cselect_b32 s36, s4, s28
	s_cselect_b32 s35, s7, s67
	s_cselect_b32 s34, s6, s0
	v_lshl_add_u64 v[160:161], s[26:27], 0, v[136:137]
	s_add_i32 m0, s42, 0xc000
	ds_read_b128 v[168:171], v166
	ds_read_b128 v[172:175], v166 offset:1024
	ds_read_b128 v[176:179], v166 offset:2048
	ds_read_b128 v[180:183], v166 offset:3072
	ds_read_b128 v[184:187], v166 offset:4096
	ds_read_b128 v[188:191], v166 offset:5120
	ds_read_b128 v[192:195], v166 offset:6144
	ds_read_b128 v[196:199], v166 offset:7168
	global_load_lds_dwordx4 v[160:161], off
	v_lshl_add_u64 v[160:161], s[26:27], 0, v[138:139]
	s_add_i32 m0, s42, 0xe000
	s_nop 0
	global_load_lds_dwordx4 v[160:161], off
	s_waitcnt vmcnt(10)
	s_barrier
	s_waitcnt lgkmcnt(0)
	s_setprio 1
	s_waitcnt lgkmcnt(0)
	v_mfma_f32_16x16x32_bf16 v[124:127], v[144:147], v[168:171], v[124:127]
	v_mfma_f32_16x16x32_bf16 v[120:123], v[152:155], v[168:171], v[120:123]
	v_mfma_f32_16x16x32_bf16 v[116:119], v[144:147], v[176:179], v[116:119]
	v_mfma_f32_16x16x32_bf16 v[104:107], v[152:155], v[176:179], v[104:107]
	v_mfma_f32_16x16x32_bf16 v[96:99], v[144:147], v[184:187], v[96:99]
	v_mfma_f32_16x16x32_bf16 v[88:91], v[152:155], v[184:187], v[88:91]
	v_mfma_f32_16x16x32_bf16 v[80:83], v[144:147], v[192:195], v[80:83]
	v_mfma_f32_16x16x32_bf16 v[72:75], v[152:155], v[192:195], v[72:75]
	v_mfma_f32_16x16x32_bf16 v[124:127], v[148:151], v[172:175], v[124:127]
	v_mfma_f32_16x16x32_bf16 v[120:123], v[156:159], v[172:175], v[120:123]
	v_mfma_f32_16x16x32_bf16 v[116:119], v[148:151], v[180:183], v[116:119]
	v_mfma_f32_16x16x32_bf16 v[104:107], v[156:159], v[180:183], v[104:107]
	v_mfma_f32_16x16x32_bf16 v[96:99], v[148:151], v[188:191], v[96:99]
	v_mfma_f32_16x16x32_bf16 v[88:91], v[156:159], v[188:191], v[88:91]
	v_mfma_f32_16x16x32_bf16 v[80:83], v[148:151], v[196:199], v[80:83]
	v_mfma_f32_16x16x32_bf16 v[72:75], v[156:159], v[196:199], v[72:75]
	s_setprio 0
	s_barrier
	s_add_i32 s16, s58, s40
	s_mov_b32 m0, s16
	ds_read_b128 v[202:205], v167
	ds_read_b128 v[206:209], v167 offset:1024
	ds_read_b128 v[210:213], v167 offset:2048
	ds_read_b128 v[214:217], v167 offset:3072
	global_load_lds_dwordx4 v132, s[34:35]
	s_add_i32 m0, s16, 0x2000
	s_nop 0
	global_load_lds_dwordx4 v128, s[34:35]
	s_waitcnt vmcnt(10)
	s_barrier
; #define PG8_STAGE(bufoff, gbase, voff) do { _Pragma("unroll") for (int _i = 0; _i < 2; ++_i) \
;         __builtin_amdgcn_global_load_lds((const unsigned*)((const char*)(gbase) + (voff)[_i]), (LAS unsigned*)(lds + (bufoff) + ldsw + _i * 8192), 16, 0, 0); } while (0)
; #define PG8_LDA(dst, b, h) do { _Pragma("unroll") for (int m = 0; m < 4; ++m) _Pragma("unroll") for (int k = 0; k < 2; ++k) dst[m][k] = *(const LAS bf16x8*)(lds + PG8_SA(b, h) + aoff + m * 2048 + k * 1024); } while (0)
; #define PG8_LDB(dst, b, h) do { _Pragma("unroll") for (int n = 0; n < 2; ++n) _Pragma("unroll") for (int k = 0; k < 2; ++k) dst[n][k] = *(const LAS bf16x8*)(lds + PG8_SB(b, h) + boff + n * 2048 + k * 1024); } while (0)
; #define PG8_MMA(ai, bj, At, Bt) do { __builtin_amdgcn_s_setprio(1); _Pragma("unroll") for (int m = 0; m < 4; ++m) _Pragma("unroll") for (int n = 0; n < 2; ++n) _Pragma("unroll") for (int k = 0; k < 2; ++k) \
;         acc[ai][bj][m][n] = __builtin_amdgcn_mfma_f32_16x16x32_bf16(Bt[n][k], At[m][k], acc[ai][bj][m][n], 0, 0, 0); __builtin_amdgcn_s_setprio(0); } while (0)
; #define PG8_WAIT_V(n) asm volatile("s_waitcnt vmcnt(" #n ")" ::: "memory")
; #define PG8_WAIT_L(n) asm volatile("s_waitcnt lgkmcnt(" #n ")" ::: "memory")
; #define PG8_BAR __builtin_amdgcn_s_barrier()
; #define PG8_SCHED __builtin_amdgcn_sched_barrier(0)
; template <class Epi, class Sched>
; __device__ __forceinline__ void gemm_phase(LAS unsigned char* lds, const Gemm g, const Sched& S, const Epi& E) {
;     ...
;             PG8_LDB(B1, 0, 1); PG8_STAGE(PG8_SB(0, 0), b2, voffB);
;             PG8_BAR; PG8_WAIT_L(0); PG8_MMA(0, 1, At, B1); PG8_BAR;
;             PG8_LDA(At, 0, 1); PG8_STAGE(PG8_SA(0, 0), a2, voffA);
;             PG8_BAR; PG8_WAIT_L(0); PG8_MMA(1, 0, At, B0); PG8_BAR; PG8_SCHED;
;             PG8_STAGE(PG8_SB(0, 1), b2 + hstep, voffB);
;             PG8_WAIT_V(6); PG8_BAR; PG8_MMA(1, 1, At, B1); PG8_BAR;
;             PG8_LDB(B0, 1, 0); PG8_SCHED; PG8_LDA(At, 1, 0); PG8_STAGE(PG8_SA(0, 1), a2 + hstep, voffA);
;             PG8_WAIT_L(8); PG8_BAR; PG8_WAIT_L(0); PG8_MMA(0, 0, At, B0); PG8_BAR; PG8_SCHED;
	s_waitcnt lgkmcnt(0)
	s_setprio 1
	s_waitcnt lgkmcnt(0)
	v_mfma_f32_16x16x32_bf16 v[112:115], v[202:205], v[168:171], v[112:115]
	v_mfma_f32_16x16x32_bf16 v[108:111], v[210:213], v[168:171], v[108:111]
	v_mfma_f32_16x16x32_bf16 v[100:103], v[202:205], v[176:179], v[100:103]
	v_mfma_f32_16x16x32_bf16 v[92:95], v[210:213], v[176:179], v[92:95]
	v_mfma_f32_16x16x32_bf16 v[84:87], v[202:205], v[184:187], v[84:87]
	v_mfma_f32_16x16x32_bf16 v[76:79], v[210:213], v[184:187], v[76:79]
	v_mfma_f32_16x16x32_bf16 v[68:71], v[202:205], v[192:195], v[68:71]
	v_mfma_f32_16x16x32_bf16 v[64:67], v[210:213], v[192:195], v[64:67]
	v_mfma_f32_16x16x32_bf16 v[112:115], v[206:209], v[172:175], v[112:115]
	v_mfma_f32_16x16x32_bf16 v[108:111], v[214:217], v[172:175], v[108:111]
	v_mfma_f32_16x16x32_bf16 v[100:103], v[206:209], v[180:183], v[100:103]
	v_mfma_f32_16x16x32_bf16 v[92:95], v[214:217], v[180:183], v[92:95]
	v_mfma_f32_16x16x32_bf16 v[84:87], v[206:209], v[188:191], v[84:87]
	v_mfma_f32_16x16x32_bf16 v[76:79], v[214:217], v[188:191], v[76:79]
	v_mfma_f32_16x16x32_bf16 v[68:71], v[206:209], v[196:199], v[68:71]
	v_mfma_f32_16x16x32_bf16 v[64:67], v[214:217], v[196:199], v[64:67]
	s_setprio 0
	s_mov_b32 m0, s42
	s_barrier
	ds_read_b128 v[168:171], v166 offset:16384
	ds_read_b128 v[172:175], v166 offset:17408
	ds_read_b128 v[176:179], v166 offset:18432
	ds_read_b128 v[180:183], v166 offset:19456
	ds_read_b128 v[184:187], v166 offset:20480
	ds_read_b128 v[188:191], v166 offset:21504
	ds_read_b128 v[192:195], v166 offset:22528
	ds_read_b128 v[196:199], v166 offset:23552
	global_load_lds_dwordx4 v134, s[36:37]
	s_mov_b32 m0, s43
	s_nop 0
	global_load_lds_dwordx4 v130, s[36:37]
	s_barrier
	s_waitcnt lgkmcnt(0)
	s_setprio 1
	s_waitcnt lgkmcnt(0)
	v_mfma_f32_16x16x32_bf16 v[60:63], v[144:147], v[168:171], v[60:63]
	v_mfma_f32_16x16x32_bf16 v[56:59], v[152:155], v[168:171], v[56:59]
	v_mfma_f32_16x16x32_bf16 v[48:51], v[144:147], v[176:179], v[48:51]
	v_mfma_f32_16x16x32_bf16 v[40:43], v[152:155], v[176:179], v[40:43]
	v_mfma_f32_16x16x32_bf16 v[32:35], v[144:147], v[184:187], v[32:35]
	v_mfma_f32_16x16x32_bf16 v[24:27], v[152:155], v[184:187], v[24:27]
	v_mfma_f32_16x16x32_bf16 v[16:19], v[144:147], v[192:195], v[16:19]
	v_mfma_f32_16x16x32_bf16 v[8:11], v[152:155], v[192:195], v[8:11]
	v_mfma_f32_16x16x32_bf16 v[60:63], v[148:151], v[172:175], v[60:63]
	v_mfma_f32_16x16x32_bf16 v[56:59], v[156:159], v[172:175], v[56:59]
	v_mfma_f32_16x16x32_bf16 v[48:51], v[148:151], v[180:183], v[48:51]
	v_mfma_f32_16x16x32_bf16 v[40:43], v[156:159], v[180:183], v[40:43]
	v_mfma_f32_16x16x32_bf16 v[32:35], v[148:151], v[188:191], v[32:35]
	v_mfma_f32_16x16x32_bf16 v[24:27], v[156:159], v[188:191], v[24:27]
	v_mfma_f32_16x16x32_bf16 v[16:19], v[148:151], v[196:199], v[16:19]
	v_mfma_f32_16x16x32_bf16 v[8:11], v[156:159], v[196:199], v[8:11]
	s_setprio 0
	s_barrier
	s_add_u32 s16, s34, 0xb0000
	s_addc_u32 s17, s35, 0
	s_add_i32 s20, s59, s40
	s_mov_b32 m0, s20
	s_nop 0
	global_load_lds_dwordx4 v132, s[16:17]
	s_add_i32 m0, s20, 0x2000
	s_nop 0
	global_load_lds_dwordx4 v128, s[16:17]
	s_add_u32 s16, s36, 0xb0000
	s_addc_u32 s17, s37, 0
	s_mov_b32 m0, s44
	s_nop 0
	global_load_lds_dwordx4 v134, s[16:17]
	s_mov_b32 m0, s45
	s_nop 0
	global_load_lds_dwordx4 v130, s[16:17]
	s_waitcnt vmcnt(12)
	s_barrier
	s_setprio 1
	v_mfma_f32_16x16x32_bf16 v[52:55], v[202:205], v[168:171], v[52:55]
	v_mfma_f32_16x16x32_bf16 v[44:47], v[210:213], v[168:171], v[44:47]
	v_mfma_f32_16x16x32_bf16 v[36:39], v[202:205], v[176:179], v[36:39]
	v_mfma_f32_16x16x32_bf16 v[28:31], v[210:213], v[176:179], v[28:31]
	v_mfma_f32_16x16x32_bf16 v[20:23], v[202:205], v[184:187], v[20:23]
	v_mfma_f32_16x16x32_bf16 v[12:15], v[210:213], v[184:187], v[12:15]
	v_mfma_f32_16x16x32_bf16 v[4:7], v[202:205], v[192:195], v[4:7]
	v_mfma_f32_16x16x32_bf16 v[0:3], v[210:213], v[192:195], v[0:3]
	v_mfma_f32_16x16x32_bf16 v[52:55], v[206:209], v[172:175], v[52:55]
	v_mfma_f32_16x16x32_bf16 v[44:47], v[214:217], v[172:175], v[44:47]
	v_mfma_f32_16x16x32_bf16 v[36:39], v[206:209], v[180:183], v[36:39]
	v_mfma_f32_16x16x32_bf16 v[28:31], v[214:217], v[180:183], v[28:31]
	v_mfma_f32_16x16x32_bf16 v[20:23], v[206:209], v[188:191], v[20:23]
	v_mfma_f32_16x16x32_bf16 v[12:15], v[214:217], v[188:191], v[12:15]
	v_mfma_f32_16x16x32_bf16 v[4:7], v[206:209], v[196:199], v[4:7]
	v_mfma_f32_16x16x32_bf16 v[0:3], v[214:217], v[196:199], v[0:3]
	s_setprio 0
	s_add_i32 s20, 0, 0x18000
	v_add_u32_e32 v156, s20, v164
	s_barrier
	ds_read_b128 v[144:147], v156
	ds_read_b128 v[148:151], v156 offset:1024
	ds_read_b128 v[152:155], v156 offset:2048
	ds_read_b128 v[156:159], v156 offset:3072
	ds_read_b128 v[168:171], v166 offset:32768
	ds_read_b128 v[172:175], v166 offset:33792
	ds_read_b128 v[176:179], v166 offset:34816
	ds_read_b128 v[180:183], v166 offset:35840
	ds_read_b128 v[184:187], v166 offset:36864
	ds_read_b128 v[188:191], v166 offset:37888
	ds_read_b128 v[192:195], v166 offset:38912
	ds_read_b128 v[196:199], v166 offset:39936
	s_waitcnt vmcnt(10)
	s_barrier
; #define PG8_STAGE(bufoff, gbase, voff) do { _Pragma("unroll") for (int _i = 0; _i < 2; ++_i) \
;         __builtin_amdgcn_global_load_lds((const unsigned*)((const char*)(gbase) + (voff)[_i]), (LAS unsigned*)(lds + (bufoff) + ldsw + _i * 8192), 16, 0, 0); } while (0)
; #define PG8_LDA(dst, b, h) do { _Pragma("unroll") for (int m = 0; m < 4; ++m) _Pragma("unroll") for (int k = 0; k < 2; ++k) dst[m][k] = *(const LAS bf16x8*)(lds + PG8_SA(b, h) + aoff + m * 2048 + k * 1024); } while (0)
; #define PG8_LDB(dst, b, h) do { _Pragma("unroll") for (int n = 0; n < 2; ++n) _Pragma("unroll") for (int k = 0; k < 2; ++k) dst[n][k] = *(const LAS bf16x8*)(lds + PG8_SB(b, h) + boff + n * 2048 + k * 1024); } while (0)
; #define PG8_MMA(ai, bj, At, Bt) do { __builtin_amdgcn_s_setprio(1); _Pragma("unroll") for (int m = 0; m < 4; ++m) _Pragma("unroll") for (int n = 0; n < 2; ++n) _Pragma("unroll") for (int k = 0; k < 2; ++k) \
;         acc[ai][bj][m][n] = __builtin_amdgcn_mfma_f32_16x16x32_bf16(Bt[n][k], At[m][k], acc[ai][bj][m][n], 0, 0, 0); __builtin_amdgcn_s_setprio(0); } while (0)
; #define PG8_WAIT_V(n) asm volatile("s_waitcnt vmcnt(" #n ")" ::: "memory")
; #define PG8_WAIT_L(n) asm volatile("s_waitcnt lgkmcnt(" #n ")" ::: "memory")
; #define PG8_BAR __builtin_amdgcn_s_barrier()
; #define PG8_SCHED __builtin_amdgcn_sched_barrier(0)
; template <class Epi, class Sched>
; __device__ __forceinline__ void gemm_phase(LAS unsigned char* lds, const Gemm g, const Sched& S, const Epi& E) {
;     ...
;             PG8_WAIT_L(8); PG8_BAR; PG8_WAIT_L(0); PG8_MMA(0, 0, At, B0); PG8_BAR; PG8_SCHED;
;             PG8_LDB(B1, 1, 1); PG8_STAGE(PG8_SB(1, 0), b3, voffB);
;             PG8_BAR; PG8_WAIT_L(0); PG8_MMA(0, 1, At, B1); PG8_BAR;
;             PG8_LDA(At, 1, 1); PG8_STAGE(PG8_SA(1, 0), a3, voffA);
;             PG8_BAR; PG8_WAIT_L(0); PG8_MMA(1, 0, At, B0); PG8_BAR; PG8_SCHED;
;             PG8_STAGE(PG8_SB(1, 1), b3 + hstep, voffB);
;             PG8_WAIT_V(6); PG8_BAR; PG8_MMA(1, 1, At, B1); PG8_BAR;
;     __device__ __forceinline__ void operator()(const AccT& acc, const Unit& u, int wr, int wc, int fr, int fq) const {
;     ...
;         const int rowt = u.pm * 256; const bool isc = rowt >= MX; const int b = isc ? 32 : (rowt >> 11);
;         const float* res = isc ? res_c + (size_t)(rowt - MX) * DM : res_x + (size_t)rowt * DM; bf16_t* out = hb + (size_t)rowt * DM;
	s_waitcnt lgkmcnt(0)
	s_setprio 1
	s_waitcnt lgkmcnt(0)
	v_mfma_f32_16x16x32_bf16 v[124:127], v[144:147], v[168:171], v[124:127]
	v_mfma_f32_16x16x32_bf16 v[120:123], v[152:155], v[168:171], v[120:123]
	v_mfma_f32_16x16x32_bf16 v[116:119], v[144:147], v[176:179], v[116:119]
	v_mfma_f32_16x16x32_bf16 v[104:107], v[152:155], v[176:179], v[104:107]
	v_mfma_f32_16x16x32_bf16 v[96:99], v[144:147], v[184:187], v[96:99]
	v_mfma_f32_16x16x32_bf16 v[88:91], v[152:155], v[184:187], v[88:91]
	v_mfma_f32_16x16x32_bf16 v[80:83], v[144:147], v[192:195], v[80:83]
	v_mfma_f32_16x16x32_bf16 v[72:75], v[152:155], v[192:195], v[72:75]
	v_mfma_f32_16x16x32_bf16 v[124:127], v[148:151], v[172:175], v[124:127]
	v_mfma_f32_16x16x32_bf16 v[120:123], v[156:159], v[172:175], v[120:123]
	v_mfma_f32_16x16x32_bf16 v[116:119], v[148:151], v[180:183], v[116:119]
	v_mfma_f32_16x16x32_bf16 v[104:107], v[156:159], v[180:183], v[104:107]
	v_mfma_f32_16x16x32_bf16 v[96:99], v[148:151], v[188:191], v[96:99]
	v_mfma_f32_16x16x32_bf16 v[88:91], v[156:159], v[188:191], v[88:91]
	v_mfma_f32_16x16x32_bf16 v[80:83], v[148:151], v[196:199], v[80:83]
	v_mfma_f32_16x16x32_bf16 v[72:75], v[156:159], v[196:199], v[72:75]
	s_setprio 0
	s_barrier
	s_add_i32 s21, 0, 0x1c000
	s_add_i32 s16, s20, s40
	v_add_u32_e32 v214, s21, v164
	s_add_u32 s8, s34, 0x80
	s_addc_u32 s9, s35, 0
	s_mov_b32 m0, s16
	ds_read_b128 v[202:205], v214
	ds_read_b128 v[206:209], v214 offset:1024
	ds_read_b128 v[210:213], v214 offset:2048
	ds_read_b128 v[214:217], v214 offset:3072
	global_load_lds_dwordx4 v132, s[8:9]
	s_add_i32 m0, s16, 0x2000
	s_nop 0
	global_load_lds_dwordx4 v128, s[8:9]
	s_waitcnt vmcnt(10)
	s_barrier
	s_waitcnt lgkmcnt(0)
	s_setprio 1
	s_waitcnt lgkmcnt(0)
	v_mfma_f32_16x16x32_bf16 v[112:115], v[202:205], v[168:171], v[112:115]
	v_mfma_f32_16x16x32_bf16 v[108:111], v[210:213], v[168:171], v[108:111]
	v_mfma_f32_16x16x32_bf16 v[100:103], v[202:205], v[176:179], v[100:103]
	v_mfma_f32_16x16x32_bf16 v[92:95], v[210:213], v[176:179], v[92:95]
	v_mfma_f32_16x16x32_bf16 v[84:87], v[202:205], v[184:187], v[84:87]
	v_mfma_f32_16x16x32_bf16 v[76:79], v[210:213], v[184:187], v[76:79]
	v_mfma_f32_16x16x32_bf16 v[68:71], v[202:205], v[192:195], v[68:71]
	v_mfma_f32_16x16x32_bf16 v[64:67], v[210:213], v[192:195], v[64:67]
	v_mfma_f32_16x16x32_bf16 v[112:115], v[206:209], v[172:175], v[112:115]
	v_mfma_f32_16x16x32_bf16 v[108:111], v[214:217], v[172:175], v[108:111]
	v_mfma_f32_16x16x32_bf16 v[100:103], v[206:209], v[180:183], v[100:103]
	v_mfma_f32_16x16x32_bf16 v[92:95], v[214:217], v[180:183], v[92:95]
	v_mfma_f32_16x16x32_bf16 v[84:87], v[206:209], v[188:191], v[84:87]
	v_mfma_f32_16x16x32_bf16 v[76:79], v[214:217], v[188:191], v[76:79]
	v_mfma_f32_16x16x32_bf16 v[68:71], v[206:209], v[196:199], v[68:71]
	v_mfma_f32_16x16x32_bf16 v[64:67], v[214:217], v[196:199], v[64:67]
	s_setprio 0
	s_mov_b32 m0, s52
	s_add_u32 s8, s36, 0x80
	s_addc_u32 s9, s37, 0
	s_barrier
	ds_read_b128 v[168:171], v166 offset:49152
	ds_read_b128 v[172:175], v166 offset:50176
	ds_read_b128 v[176:179], v166 offset:51200
	ds_read_b128 v[180:183], v166 offset:52224
	ds_read_b128 v[184:187], v166 offset:53248
	ds_read_b128 v[188:191], v166 offset:54272
	ds_read_b128 v[192:195], v166 offset:55296
	ds_read_b128 v[196:199], v166 offset:56320
	global_load_lds_dwordx4 v134, s[8:9]
	s_mov_b32 m0, s53
	s_nop 0
	global_load_lds_dwordx4 v130, s[8:9]
	s_barrier
	s_waitcnt lgkmcnt(0)
	s_setprio 1
	s_waitcnt lgkmcnt(0)
	v_mfma_f32_16x16x32_bf16 v[60:63], v[144:147], v[168:171], v[60:63]
	v_mfma_f32_16x16x32_bf16 v[56:59], v[152:155], v[168:171], v[56:59]
	v_mfma_f32_16x16x32_bf16 v[48:51], v[144:147], v[176:179], v[48:51]
	v_mfma_f32_16x16x32_bf16 v[40:43], v[152:155], v[176:179], v[40:43]
	v_mfma_f32_16x16x32_bf16 v[32:35], v[144:147], v[184:187], v[32:35]
	v_mfma_f32_16x16x32_bf16 v[24:27], v[152:155], v[184:187], v[24:27]
	v_mfma_f32_16x16x32_bf16 v[16:19], v[144:147], v[192:195], v[16:19]
	v_mfma_f32_16x16x32_bf16 v[8:11], v[152:155], v[192:195], v[8:11]
	v_mfma_f32_16x16x32_bf16 v[60:63], v[148:151], v[172:175], v[60:63]
	v_mfma_f32_16x16x32_bf16 v[56:59], v[156:159], v[172:175], v[56:59]
	v_mfma_f32_16x16x32_bf16 v[48:51], v[148:151], v[180:183], v[48:51]
	v_mfma_f32_16x16x32_bf16 v[40:43], v[156:159], v[180:183], v[40:43]
	v_mfma_f32_16x16x32_bf16 v[32:35], v[148:151], v[188:191], v[32:35]
	v_mfma_f32_16x16x32_bf16 v[24:27], v[156:159], v[188:191], v[24:27]
	v_mfma_f32_16x16x32_bf16 v[16:19], v[148:151], v[196:199], v[16:19]
	v_mfma_f32_16x16x32_bf16 v[8:11], v[156:159], v[196:199], v[8:11]
	s_setprio 0
	s_barrier
	s_add_u32 s16, s34, 0xb0080
	s_addc_u32 s17, s35, 0
	s_add_i32 s20, s21, s40
	s_mov_b32 m0, s20
	s_nop 0
	global_load_lds_dwordx4 v132, s[16:17]
	s_add_i32 m0, s20, 0x2000
	s_nop 0
	global_load_lds_dwordx4 v128, s[16:17]
	s_waitcnt vmcnt(10)
	s_barrier
	s_setprio 1
	v_mfma_f32_16x16x32_bf16 v[52:55], v[202:205], v[168:171], v[52:55]
	v_mfma_f32_16x16x32_bf16 v[44:47], v[210:213], v[168:171], v[44:47]
	v_mfma_f32_16x16x32_bf16 v[36:39], v[202:205], v[176:179], v[36:39]
	v_mfma_f32_16x16x32_bf16 v[28:31], v[210:213], v[176:179], v[28:31]
	v_mfma_f32_16x16x32_bf16 v[20:23], v[202:205], v[184:187], v[20:23]
	v_mfma_f32_16x16x32_bf16 v[12:15], v[210:213], v[184:187], v[12:15]
	v_mfma_f32_16x16x32_bf16 v[4:7], v[202:205], v[192:195], v[4:7]
	v_mfma_f32_16x16x32_bf16 v[0:3], v[210:213], v[192:195], v[0:3]
	v_mfma_f32_16x16x32_bf16 v[52:55], v[206:209], v[172:175], v[52:55]
	v_mfma_f32_16x16x32_bf16 v[44:47], v[214:217], v[172:175], v[44:47]
	v_mfma_f32_16x16x32_bf16 v[36:39], v[206:209], v[180:183], v[36:39]
	v_mfma_f32_16x16x32_bf16 v[28:31], v[214:217], v[180:183], v[28:31]
	v_mfma_f32_16x16x32_bf16 v[20:23], v[206:209], v[188:191], v[20:23]
	v_mfma_f32_16x16x32_bf16 v[12:15], v[214:217], v[188:191], v[12:15]
	v_mfma_f32_16x16x32_bf16 v[4:7], v[206:209], v[196:199], v[4:7]
	v_mfma_f32_16x16x32_bf16 v[0:3], v[214:217], v[196:199], v[0:3]
	s_setprio 0
	s_add_i32 s68, s68, 2
	s_add_u32 s0, s0, 0x100
	s_addc_u32 s67, s67, 0
	s_cmp_gt_u32 s68, 41
	s_mov_b64 s[26:27], s[28:29]
	s_barrier
	s_cbranch_scc0 .LBB0_305
	s_lshl_b32 s0, s66, 8
	v_mov_b32_e32 v145, v163
	v_mov_b32_e32 v144, v162
	s_cmpk_lt_i32 s66, 0x100
	s_cbranch_scc0 .LBB0_308
	s_ashr_i32 s29, s0, 31
	s_mov_b32 s28, s0
	s_lshl_b64 s[16:17], s[28:29], 12
	v_readlane_b32 s80, v254, 23
	v_readlane_b32 s81, v254, 24
	s_add_u32 s26, s80, s16
	v_readlane_b32 s82, v254, 25
	v_readlane_b32 s83, v254, 26
	v_readlane_b32 s84, v254, 27
	v_readlane_b32 s85, v254, 28
	v_readlane_b32 s86, v254, 29
	v_readlane_b32 s87, v254, 30
	v_readlane_b32 s88, v254, 31
	v_readlane_b32 s89, v254, 32
	v_readlane_b32 s90, v254, 33
	v_readlane_b32 s91, v254, 34
	v_readlane_b32 s92, v254, 35
	v_readlane_b32 s93, v254, 36
	v_readlane_b32 s94, v254, 37
	v_readlane_b32 s95, v254, 38
	s_addc_u32 s27, s81, s17
	s_cbranch_execnz .LBB0_297
	s_branch .LBB0_296

; #define PG8_STAGE(bufoff, gbase, voff) do { _Pragma("unroll") for (int _i = 0; _i < 2; ++_i) \
;         __builtin_amdgcn_global_load_lds((const unsigned*)((const char*)(gbase) + (voff)[_i]), (LAS unsigned*)(lds + (bufoff) + ldsw + _i * 8192), 16, 0, 0); } while (0)
; #define PG8_LDA(dst, b, h) do { _Pragma("unroll") for (int m = 0; m < 4; ++m) _Pragma("unroll") for (int k = 0; k < 2; ++k) dst[m][k] = *(const LAS bf16x8*)(lds + PG8_SA(b, h) + aoff + m * 2048 + k * 1024); } while (0)
; #define PG8_LDB(dst, b, h) do { _Pragma("unroll") for (int n = 0; n < 2; ++n) _Pragma("unroll") for (int k = 0; k < 2; ++k) dst[n][k] = *(const LAS bf16x8*)(lds + PG8_SB(b, h) + boff + n * 2048 + k * 1024); } while (0)
; #define PG8_MMA(ai, bj, At, Bt) do { __builtin_amdgcn_s_setprio(1); _Pragma("unroll") for (int m = 0; m < 4; ++m) _Pragma("unroll") for (int n = 0; n < 2; ++n) _Pragma("unroll") for (int k = 0; k < 2; ++k) \
;         acc[ai][bj][m][n] = __builtin_amdgcn_mfma_f32_16x16x32_bf16(Bt[n][k], At[m][k], acc[ai][bj][m][n], 0, 0, 0); __builtin_amdgcn_s_setprio(0); } while (0)
; template <class Epi, class Sched>
; __device__ __forceinline__ void gemm_phase(LAS unsigned char* lds, const Gemm g, const Sched& S, const Epi& E) {
;     ...
;         const char* nA = has_next ? (const char*)g.A + (size_t)nxt.pm * tstep : cA; const char* nB = has_next ? (const char*)g.Bt + (size_t)nxt.pn * tstep : cB;
;         for (int t = 0; t < nt; t += 2) {
;             const bool last = (t == nt - 2);
;             const char* a1 = cA + (size_t)(t + 1) * kstep;
;             const char* a2 = last ? nA : cA + (size_t)(t + 2) * kstep; const char* b2 = last ? nB : cB + (size_t)(t + 2) * kstep;
;             const char* a3 = a2 + kstep; const char* b3 = b2 + kstep;
;             PG8_LDB(B0, 0, 0); PG8_SCHED; PG8_LDA(At, 0, 0); PG8_STAGE(PG8_SA(1, 1), a1 + hstep, voffA);
;             PG8_WAIT_L(8); PG8_BAR; PG8_WAIT_L(0); PG8_MMA(0, 0, At, B0); PG8_BAR; PG8_SCHED;
;             PG8_LDB(B1, 0, 1); PG8_STAGE(PG8_SB(0, 0), b2, voffB);
;             PG8_BAR; PG8_WAIT_L(0); PG8_MMA(0, 1, At, B1); PG8_BAR;
;             PG8_LDA(At, 0, 1); PG8_STAGE(PG8_SA(0, 0), a2, voffA);
;             PG8_BAR; PG8_WAIT_L(0); PG8_MMA(1, 0, At, B0); PG8_BAR; PG8_SCHED;
;             PG8_STAGE(PG8_SB(0, 1), b2 + hstep, voffB);
;             PG8_WAIT_V(6); PG8_BAR; PG8_MMA(1, 1, At, B1); PG8_BAR;
.LBB0_577:
	s_ashr_i32 s21, s20, 31
	v_cmp_lt_i64_e32 vcc, s[22:23], v[156:157]
	s_lshl_b64 s[22:23], s[20:21], 19
	s_add_u32 s22, s96, s22
	s_addc_u32 s23, s97, s23
	s_and_b64 s[24:25], vcc, exec
	s_cselect_b32 s5, s23, s7
	s_cselect_b32 s21, s22, s6
	s_ashr_i32 s19, s18, 31
	s_lshl_b64 s[24:25], s[18:19], 19
	s_add_u32 s24, s31, s24
	s_addc_u32 s25, s33, s25
	s_and_b64 s[28:29], vcc, exec
	s_cselect_b32 s19, s25, s27
	s_cselect_b32 s53, s24, s26
	s_add_u32 s6, s6, 0x40080
	s_addc_u32 s7, s7, 0
	s_add_u32 s54, s26, 0x100
	s_addc_u32 s55, s27, 0
	s_mov_b32 s56, -2
	s_waitcnt lgkmcnt(0)
	ds_read_b128 v[128:131], v167
	ds_read_b128 v[132:135], v167 offset:1024
	ds_read_b128 v[136:139], v167 offset:2048
	ds_read_b128 v[160:163], v167 offset:3072
	s_add_u32 s26, s6, 0xfffc0080
	s_addc_u32 s27, s7, -1
	s_cmp_eq_u32 s56, 12
	s_cselect_b32 s29, s5, s27
	s_cselect_b32 s28, s21, s26
	s_cselect_b32 s27, s19, s55
	s_cselect_b32 s26, s53, s54
	s_add_i32 m0, s37, 0xc000
	ds_read_b128 v[170:173], v168
	ds_read_b128 v[174:177], v168 offset:1024
	ds_read_b128 v[178:181], v168 offset:2048
	ds_read_b128 v[182:185], v168 offset:3072
	ds_read_b128 v[186:189], v168 offset:4096
	ds_read_b128 v[190:193], v168 offset:5120
	ds_read_b128 v[194:197], v168 offset:6144
	ds_read_b128 v[202:205], v168 offset:7168
	global_load_lds_dwordx4 v152, s[6:7]
	s_add_i32 m0, s37, 0xe000
	s_nop 0
	global_load_lds_dwordx4 v154, s[6:7]
	s_waitcnt vmcnt(10)
	s_barrier
	s_waitcnt lgkmcnt(0)
	s_setprio 1
	s_waitcnt lgkmcnt(0)
	v_mfma_f32_16x16x32_bf16 v[124:127], v[128:131], v[170:173], 0
	v_mfma_f32_16x16x32_bf16 v[120:123], v[136:139], v[170:173], 0
	v_mfma_f32_16x16x32_bf16 v[108:111], v[128:131], v[178:181], 0
	v_mfma_f32_16x16x32_bf16 v[104:107], v[136:139], v[178:181], 0
	v_mfma_f32_16x16x32_bf16 v[92:95], v[128:131], v[186:189], 0
	v_mfma_f32_16x16x32_bf16 v[88:91], v[136:139], v[186:189], 0
	v_mfma_f32_16x16x32_bf16 v[76:79], v[128:131], v[194:197], 0
	v_mfma_f32_16x16x32_bf16 v[72:75], v[136:139], v[194:197], 0
	v_mfma_f32_16x16x32_bf16 v[124:127], v[132:135], v[174:177], v[124:127]
	v_mfma_f32_16x16x32_bf16 v[120:123], v[160:163], v[174:177], v[120:123]
	v_mfma_f32_16x16x32_bf16 v[108:111], v[132:135], v[182:185], v[108:111]
	v_mfma_f32_16x16x32_bf16 v[104:107], v[160:163], v[182:185], v[104:107]
	v_mfma_f32_16x16x32_bf16 v[92:95], v[132:135], v[190:193], v[92:95]
	v_mfma_f32_16x16x32_bf16 v[88:91], v[160:163], v[190:193], v[88:91]
	v_mfma_f32_16x16x32_bf16 v[76:79], v[132:135], v[202:205], v[76:79]
	v_mfma_f32_16x16x32_bf16 v[72:75], v[160:163], v[202:205], v[72:75]
	s_setprio 0
	s_barrier
	s_add_i32 s57, s48, s34
	s_mov_b32 m0, s57
	ds_read_b128 v[206:209], v169
	ds_read_b128 v[210:213], v169 offset:1024
	ds_read_b128 v[214:217], v169 offset:2048
	ds_read_b128 v[218:221], v169 offset:3072
	global_load_lds_dwordx4 v146, s[26:27]
	s_add_i32 m0, s57, 0x2000
	s_nop 0
	global_load_lds_dwordx4 v142, s[26:27]
	s_waitcnt vmcnt(10)
	s_barrier
	s_waitcnt lgkmcnt(0)
	s_setprio 1
	s_waitcnt lgkmcnt(0)
	v_mfma_f32_16x16x32_bf16 v[116:119], v[206:209], v[170:173], 0
	v_mfma_f32_16x16x32_bf16 v[112:115], v[214:217], v[170:173], 0
	v_mfma_f32_16x16x32_bf16 v[100:103], v[206:209], v[178:181], 0
	v_mfma_f32_16x16x32_bf16 v[96:99], v[214:217], v[178:181], 0
	v_mfma_f32_16x16x32_bf16 v[84:87], v[206:209], v[186:189], 0
	v_mfma_f32_16x16x32_bf16 v[80:83], v[214:217], v[186:189], 0
	v_mfma_f32_16x16x32_bf16 v[68:71], v[206:209], v[194:197], 0
	v_mfma_f32_16x16x32_bf16 v[64:67], v[214:217], v[194:197], 0
	v_mfma_f32_16x16x32_bf16 v[116:119], v[210:213], v[174:177], v[116:119]
	v_mfma_f32_16x16x32_bf16 v[112:115], v[218:221], v[174:177], v[112:115]
	v_mfma_f32_16x16x32_bf16 v[100:103], v[210:213], v[182:185], v[100:103]
	v_mfma_f32_16x16x32_bf16 v[96:99], v[218:221], v[182:185], v[96:99]
	v_mfma_f32_16x16x32_bf16 v[84:87], v[210:213], v[190:193], v[84:87]
	v_mfma_f32_16x16x32_bf16 v[80:83], v[218:221], v[190:193], v[80:83]
	v_mfma_f32_16x16x32_bf16 v[68:71], v[210:213], v[202:205], v[68:71]
	v_mfma_f32_16x16x32_bf16 v[64:67], v[218:221], v[202:205], v[64:67]
	s_setprio 0
	s_mov_b32 m0, s37
	v_lshl_add_u64 v[222:223], s[28:29], 0, v[148:149]
	s_barrier
	ds_read_b128 v[170:173], v168 offset:16384
	ds_read_b128 v[174:177], v168 offset:17408
	ds_read_b128 v[178:181], v168 offset:18432
	ds_read_b128 v[182:185], v168 offset:19456
	ds_read_b128 v[186:189], v168 offset:20480
	ds_read_b128 v[190:193], v168 offset:21504
	ds_read_b128 v[194:197], v168 offset:22528
	ds_read_b128 v[202:205], v168 offset:23552
	global_load_lds_dwordx4 v148, s[28:29]
	v_lshl_add_u64 v[224:225], s[28:29], 0, v[144:145]
	s_mov_b32 m0, s38
	s_nop 0
	global_load_lds_dwordx4 v144, s[28:29]
	s_barrier
	s_waitcnt lgkmcnt(0)
	s_setprio 1
	s_waitcnt lgkmcnt(0)
	v_mfma_f32_16x16x32_bf16 v[60:63], v[128:131], v[170:173], 0
	v_mfma_f32_16x16x32_bf16 v[56:59], v[136:139], v[170:173], 0
	v_mfma_f32_16x16x32_bf16 v[44:47], v[128:131], v[178:181], 0
	v_mfma_f32_16x16x32_bf16 v[40:43], v[136:139], v[178:181], 0
	v_mfma_f32_16x16x32_bf16 v[28:31], v[128:131], v[186:189], 0
	v_mfma_f32_16x16x32_bf16 v[24:27], v[136:139], v[186:189], 0
	v_mfma_f32_16x16x32_bf16 v[12:15], v[128:131], v[194:197], 0
	v_mfma_f32_16x16x32_bf16 v[8:11], v[136:139], v[194:197], 0
	v_mfma_f32_16x16x32_bf16 v[60:63], v[132:135], v[174:177], v[60:63]
	v_mfma_f32_16x16x32_bf16 v[56:59], v[160:163], v[174:177], v[56:59]
	v_mfma_f32_16x16x32_bf16 v[44:47], v[132:135], v[182:185], v[44:47]
	v_mfma_f32_16x16x32_bf16 v[40:43], v[160:163], v[182:185], v[40:43]
	v_mfma_f32_16x16x32_bf16 v[28:31], v[132:135], v[190:193], v[28:31]
	v_mfma_f32_16x16x32_bf16 v[24:27], v[160:163], v[190:193], v[24:27]
	v_mfma_f32_16x16x32_bf16 v[12:15], v[132:135], v[202:205], v[12:15]
	v_mfma_f32_16x16x32_bf16 v[8:11], v[160:163], v[202:205], v[8:11]
	s_setprio 0
	s_barrier
; #define PG8_STAGE(bufoff, gbase, voff) do { _Pragma("unroll") for (int _i = 0; _i < 2; ++_i) \
;         __builtin_amdgcn_global_load_lds((const unsigned*)((const char*)(gbase) + (voff)[_i]), (LAS unsigned*)(lds + (bufoff) + ldsw + _i * 8192), 16, 0, 0); } while (0)
; #define PG8_LDA(dst, b, h) do { _Pragma("unroll") for (int m = 0; m < 4; ++m) _Pragma("unroll") for (int k = 0; k < 2; ++k) dst[m][k] = *(const LAS bf16x8*)(lds + PG8_SA(b, h) + aoff + m * 2048 + k * 1024); } while (0)
; #define PG8_LDB(dst, b, h) do { _Pragma("unroll") for (int n = 0; n < 2; ++n) _Pragma("unroll") for (int k = 0; k < 2; ++k) dst[n][k] = *(const LAS bf16x8*)(lds + PG8_SB(b, h) + boff + n * 2048 + k * 1024); } while (0)
; #define PG8_MMA(ai, bj, At, Bt) do { __builtin_amdgcn_s_setprio(1); _Pragma("unroll") for (int m = 0; m < 4; ++m) _Pragma("unroll") for (int n = 0; n < 2; ++n) _Pragma("unroll") for (int k = 0; k < 2; ++k) \
;         acc[ai][bj][m][n] = __builtin_amdgcn_mfma_f32_16x16x32_bf16(Bt[n][k], At[m][k], acc[ai][bj][m][n], 0, 0, 0); __builtin_amdgcn_s_setprio(0); } while (0)
; #define PG8_WAIT_V(n) asm volatile("s_waitcnt vmcnt(" #n ")" ::: "memory")
; #define PG8_WAIT_L(n) asm volatile("s_waitcnt lgkmcnt(" #n ")" ::: "memory")
; #define PG8_BAR __builtin_amdgcn_s_barrier()
; #define PG8_SCHED __builtin_amdgcn_sched_barrier(0)
; template <class Epi, class Sched>
; __device__ __forceinline__ void gemm_phase(LAS unsigned char* lds, const Gemm g, const Sched& S, const Epi& E) {
;     ...
;             PG8_STAGE(PG8_SB(0, 1), b2 + hstep, voffB);
;             PG8_WAIT_V(6); PG8_BAR; PG8_MMA(1, 1, At, B1); PG8_BAR;
;             PG8_LDB(B0, 1, 0); PG8_SCHED; PG8_LDA(At, 1, 0); PG8_STAGE(PG8_SA(0, 1), a2 + hstep, voffA);
;             PG8_WAIT_L(8); PG8_BAR; PG8_WAIT_L(0); PG8_MMA(0, 0, At, B0); PG8_BAR; PG8_SCHED;
;             PG8_LDB(B1, 1, 1); PG8_STAGE(PG8_SB(1, 0), b3, voffB);
;             PG8_BAR; PG8_WAIT_L(0); PG8_MMA(0, 1, At, B1); PG8_BAR;
;             PG8_LDA(At, 1, 1); PG8_STAGE(PG8_SA(1, 0), a3, voffA);
;             PG8_BAR; PG8_WAIT_L(0); PG8_MMA(1, 0, At, B0); PG8_BAR; PG8_SCHED;
	s_add_u32 s58, s26, 0x40000
	s_addc_u32 s59, s27, 0
	s_add_i32 s57, s49, s34
	s_mov_b32 m0, s57
	s_nop 0
	global_load_lds_dwordx4 v146, s[58:59]
	s_add_i32 m0, s57, 0x2000
	s_nop 0
	global_load_lds_dwordx4 v142, s[58:59]
	s_add_u32 s28, s28, 0x40000
	s_addc_u32 s29, s29, 0
	s_mov_b32 m0, s39
	s_nop 0
	global_load_lds_dwordx4 v148, s[28:29]
	s_mov_b32 m0, s40
	s_nop 0
	global_load_lds_dwordx4 v144, s[28:29]
	s_waitcnt vmcnt(12)
	s_barrier
	s_setprio 1
	v_mfma_f32_16x16x32_bf16 v[52:55], v[206:209], v[170:173], 0
	v_mfma_f32_16x16x32_bf16 v[48:51], v[214:217], v[170:173], 0
	v_mfma_f32_16x16x32_bf16 v[36:39], v[206:209], v[178:181], 0
	v_mfma_f32_16x16x32_bf16 v[32:35], v[214:217], v[178:181], 0
	v_mfma_f32_16x16x32_bf16 v[20:23], v[206:209], v[186:189], 0
	v_mfma_f32_16x16x32_bf16 v[16:19], v[214:217], v[186:189], 0
	v_mfma_f32_16x16x32_bf16 v[4:7], v[206:209], v[194:197], 0
	v_mfma_f32_16x16x32_bf16 v[0:3], v[214:217], v[194:197], 0
	v_mfma_f32_16x16x32_bf16 v[52:55], v[210:213], v[174:177], v[52:55]
	v_mfma_f32_16x16x32_bf16 v[48:51], v[218:221], v[174:177], v[48:51]
	v_mfma_f32_16x16x32_bf16 v[36:39], v[210:213], v[182:185], v[36:39]
	v_mfma_f32_16x16x32_bf16 v[32:35], v[218:221], v[182:185], v[32:35]
	v_mfma_f32_16x16x32_bf16 v[20:23], v[210:213], v[190:193], v[20:23]
	v_mfma_f32_16x16x32_bf16 v[16:19], v[218:221], v[190:193], v[16:19]
	v_mfma_f32_16x16x32_bf16 v[4:7], v[210:213], v[202:205], v[4:7]
	v_mfma_f32_16x16x32_bf16 v[0:3], v[218:221], v[202:205], v[0:3]
	s_setprio 0
	s_add_i32 s57, 0, 0x18000
	v_add_u32_e32 v150, s57, v166
	s_barrier
	ds_read_b128 v[128:131], v150
	ds_read_b128 v[132:135], v150 offset:1024
	ds_read_b128 v[136:139], v150 offset:2048
	ds_read_b128 v[160:163], v150 offset:3072
	ds_read_b128 v[170:173], v168 offset:32768
	ds_read_b128 v[174:177], v168 offset:33792
	ds_read_b128 v[178:181], v168 offset:34816
	ds_read_b128 v[182:185], v168 offset:35840
	ds_read_b128 v[186:189], v168 offset:36864
	ds_read_b128 v[190:193], v168 offset:37888
	ds_read_b128 v[194:197], v168 offset:38912
	ds_read_b128 v[202:205], v168 offset:39936
	s_waitcnt vmcnt(10)
	s_barrier
	s_waitcnt lgkmcnt(0)
	s_setprio 1
	s_waitcnt lgkmcnt(0)
	v_mfma_f32_16x16x32_bf16 v[124:127], v[128:131], v[170:173], v[124:127]
	v_mfma_f32_16x16x32_bf16 v[120:123], v[136:139], v[170:173], v[120:123]
	v_mfma_f32_16x16x32_bf16 v[108:111], v[128:131], v[178:181], v[108:111]
	v_mfma_f32_16x16x32_bf16 v[104:107], v[136:139], v[178:181], v[104:107]
	v_mfma_f32_16x16x32_bf16 v[92:95], v[128:131], v[186:189], v[92:95]
	v_mfma_f32_16x16x32_bf16 v[88:91], v[136:139], v[186:189], v[88:91]
	v_mfma_f32_16x16x32_bf16 v[76:79], v[128:131], v[194:197], v[76:79]
	v_mfma_f32_16x16x32_bf16 v[72:75], v[136:139], v[194:197], v[72:75]
	v_mfma_f32_16x16x32_bf16 v[124:127], v[132:135], v[174:177], v[124:127]
	v_mfma_f32_16x16x32_bf16 v[120:123], v[160:163], v[174:177], v[120:123]
	v_mfma_f32_16x16x32_bf16 v[108:111], v[132:135], v[182:185], v[108:111]
	v_mfma_f32_16x16x32_bf16 v[104:107], v[160:163], v[182:185], v[104:107]
	v_mfma_f32_16x16x32_bf16 v[92:95], v[132:135], v[190:193], v[92:95]
	v_mfma_f32_16x16x32_bf16 v[88:91], v[160:163], v[190:193], v[88:91]
	v_mfma_f32_16x16x32_bf16 v[76:79], v[132:135], v[202:205], v[76:79]
	v_mfma_f32_16x16x32_bf16 v[72:75], v[160:163], v[202:205], v[72:75]
	s_setprio 0
	s_barrier
	s_add_i32 s28, 0, 0x1c000
	s_add_i32 s29, s57, s34
	v_add_u32_e32 v150, s28, v166
	s_add_u32 s0, s26, 0x80
	s_addc_u32 s1, s27, 0
	s_mov_b32 m0, s29
	ds_read_b128 v[206:209], v150
	ds_read_b128 v[210:213], v150 offset:1024
	ds_read_b128 v[214:217], v150 offset:2048
	ds_read_b128 v[218:221], v150 offset:3072
	global_load_lds_dwordx4 v146, s[0:1]
	s_add_i32 m0, s29, 0x2000
	s_nop 0
	global_load_lds_dwordx4 v142, s[0:1]
	s_waitcnt vmcnt(10)
	s_barrier
	s_waitcnt lgkmcnt(0)
	s_setprio 1
	s_waitcnt lgkmcnt(0)
	v_mfma_f32_16x16x32_bf16 v[116:119], v[206:209], v[170:173], v[116:119]
	v_mfma_f32_16x16x32_bf16 v[112:115], v[214:217], v[170:173], v[112:115]
	v_mfma_f32_16x16x32_bf16 v[100:103], v[206:209], v[178:181], v[100:103]
	v_mfma_f32_16x16x32_bf16 v[96:99], v[214:217], v[178:181], v[96:99]
	v_mfma_f32_16x16x32_bf16 v[84:87], v[206:209], v[186:189], v[84:87]
	v_mfma_f32_16x16x32_bf16 v[80:83], v[214:217], v[186:189], v[80:83]
	v_mfma_f32_16x16x32_bf16 v[68:71], v[206:209], v[194:197], v[68:71]
	v_mfma_f32_16x16x32_bf16 v[64:67], v[214:217], v[194:197], v[64:67]
	v_mfma_f32_16x16x32_bf16 v[116:119], v[210:213], v[174:177], v[116:119]
	v_mfma_f32_16x16x32_bf16 v[112:115], v[218:221], v[174:177], v[112:115]
	v_mfma_f32_16x16x32_bf16 v[100:103], v[210:213], v[182:185], v[100:103]
	v_mfma_f32_16x16x32_bf16 v[96:99], v[218:221], v[182:185], v[96:99]
	v_mfma_f32_16x16x32_bf16 v[84:87], v[210:213], v[190:193], v[84:87]
	v_mfma_f32_16x16x32_bf16 v[80:83], v[218:221], v[190:193], v[80:83]
	v_mfma_f32_16x16x32_bf16 v[68:71], v[210:213], v[202:205], v[68:71]
	v_mfma_f32_16x16x32_bf16 v[64:67], v[218:221], v[202:205], v[64:67]
	s_setprio 0
	s_mov_b32 m0, s44
	s_mov_b64 s[0:1], 0x80
	v_lshl_add_u64 v[140:141], v[222:223], 0, s[0:1]
	s_barrier
	ds_read_b128 v[170:173], v168 offset:49152
	ds_read_b128 v[174:177], v168 offset:50176
	ds_read_b128 v[178:181], v168 offset:51200
	ds_read_b128 v[182:185], v168 offset:52224
	ds_read_b128 v[186:189], v168 offset:53248
	ds_read_b128 v[190:193], v168 offset:54272
	ds_read_b128 v[194:197], v168 offset:55296
	ds_read_b128 v[202:205], v168 offset:56320
	global_load_lds_dwordx4 v[140:141], off
	v_lshl_add_u64 v[140:141], v[224:225], 0, s[0:1]
	s_mov_b32 m0, s45
	s_nop 0
	global_load_lds_dwordx4 v[140:141], off
	s_barrier
; #define PG8_STAGE(bufoff, gbase, voff) do { _Pragma("unroll") for (int _i = 0; _i < 2; ++_i) \
;         __builtin_amdgcn_global_load_lds((const unsigned*)((const char*)(gbase) + (voff)[_i]), (LAS unsigned*)(lds + (bufoff) + ldsw + _i * 8192), 16, 0, 0); } while (0)
; #define PG8_LDA(dst, b, h) do { _Pragma("unroll") for (int m = 0; m < 4; ++m) _Pragma("unroll") for (int k = 0; k < 2; ++k) dst[m][k] = *(const LAS bf16x8*)(lds + PG8_SA(b, h) + aoff + m * 2048 + k * 1024); } while (0)
; #define PG8_LDB(dst, b, h) do { _Pragma("unroll") for (int n = 0; n < 2; ++n) _Pragma("unroll") for (int k = 0; k < 2; ++k) dst[n][k] = *(const LAS bf16x8*)(lds + PG8_SB(b, h) + boff + n * 2048 + k * 1024); } while (0)
; #define PG8_MMA(ai, bj, At, Bt) do { __builtin_amdgcn_s_setprio(1); _Pragma("unroll") for (int m = 0; m < 4; ++m) _Pragma("unroll") for (int n = 0; n < 2; ++n) _Pragma("unroll") for (int k = 0; k < 2; ++k) \
;         acc[ai][bj][m][n] = __builtin_amdgcn_mfma_f32_16x16x32_bf16(Bt[n][k], At[m][k], acc[ai][bj][m][n], 0, 0, 0); __builtin_amdgcn_s_setprio(0); } while (0)
; #define PG8_WAIT_V(n) asm volatile("s_waitcnt vmcnt(" #n ")" ::: "memory")
; #define PG8_WAIT_L(n) asm volatile("s_waitcnt lgkmcnt(" #n ")" ::: "memory")
; #define PG8_BAR __builtin_amdgcn_s_barrier()
; #define PG8_SCHED __builtin_amdgcn_sched_barrier(0)
; template <class Epi, class Sched>
; __device__ __forceinline__ void gemm_phase(LAS unsigned char* lds, const Gemm g, const Sched& S, const Epi& E) {
;     ...
;             PG8_LDB(B0, 0, 0); PG8_SCHED; PG8_LDA(At, 0, 0); PG8_STAGE(PG8_SA(1, 1), a1 + hstep, voffA);
;             PG8_WAIT_L(8); PG8_BAR; PG8_WAIT_L(0); PG8_MMA(0, 0, At, B0); PG8_BAR; PG8_SCHED;
;             PG8_LDB(B1, 0, 1); PG8_STAGE(PG8_SB(0, 0), b2, voffB);
;             PG8_BAR; PG8_WAIT_L(0); PG8_MMA(0, 1, At, B1); PG8_BAR;
;             PG8_LDA(At, 0, 1); PG8_STAGE(PG8_SA(0, 0), a2, voffA);
;             PG8_BAR; PG8_WAIT_L(0); PG8_MMA(1, 0, At, B0); PG8_BAR; PG8_SCHED;
;     ...
;             PG8_BAR; PG8_WAIT_L(0); PG8_MMA(1, 0, At, B0); PG8_BAR; PG8_SCHED;
;             PG8_STAGE(PG8_SB(1, 1), b3 + hstep, voffB);
;             PG8_WAIT_V(6); PG8_BAR; PG8_MMA(1, 1, At, B1); PG8_BAR;
	s_waitcnt lgkmcnt(0)
	s_setprio 1
	s_waitcnt lgkmcnt(0)
	v_mfma_f32_16x16x32_bf16 v[60:63], v[128:131], v[170:173], v[60:63]
	v_mfma_f32_16x16x32_bf16 v[56:59], v[136:139], v[170:173], v[56:59]
	v_mfma_f32_16x16x32_bf16 v[44:47], v[128:131], v[178:181], v[44:47]
	v_mfma_f32_16x16x32_bf16 v[40:43], v[136:139], v[178:181], v[40:43]
	v_mfma_f32_16x16x32_bf16 v[28:31], v[128:131], v[186:189], v[28:31]
	v_mfma_f32_16x16x32_bf16 v[24:27], v[136:139], v[186:189], v[24:27]
	v_mfma_f32_16x16x32_bf16 v[12:15], v[128:131], v[194:197], v[12:15]
	v_mfma_f32_16x16x32_bf16 v[8:11], v[136:139], v[194:197], v[8:11]
	v_mfma_f32_16x16x32_bf16 v[60:63], v[132:135], v[174:177], v[60:63]
	v_mfma_f32_16x16x32_bf16 v[56:59], v[160:163], v[174:177], v[56:59]
	v_mfma_f32_16x16x32_bf16 v[44:47], v[132:135], v[182:185], v[44:47]
	v_mfma_f32_16x16x32_bf16 v[40:43], v[160:163], v[182:185], v[40:43]
	v_mfma_f32_16x16x32_bf16 v[28:31], v[132:135], v[190:193], v[28:31]
	v_mfma_f32_16x16x32_bf16 v[24:27], v[160:163], v[190:193], v[24:27]
	v_mfma_f32_16x16x32_bf16 v[12:15], v[132:135], v[202:205], v[12:15]
	v_mfma_f32_16x16x32_bf16 v[8:11], v[160:163], v[202:205], v[8:11]
	s_setprio 0
	s_barrier
	s_add_u32 s26, s26, 0x40080
	s_addc_u32 s27, s27, 0
	s_add_i32 s28, s28, s34
	s_mov_b32 m0, s28
	s_nop 0
	global_load_lds_dwordx4 v146, s[26:27]
	s_add_i32 m0, s28, 0x2000
	s_nop 0
	global_load_lds_dwordx4 v142, s[26:27]
	s_waitcnt vmcnt(10)
	s_barrier
	s_setprio 1
	v_mfma_f32_16x16x32_bf16 v[52:55], v[206:209], v[170:173], v[52:55]
	v_mfma_f32_16x16x32_bf16 v[48:51], v[214:217], v[170:173], v[48:51]
	v_mfma_f32_16x16x32_bf16 v[36:39], v[206:209], v[178:181], v[36:39]
	v_mfma_f32_16x16x32_bf16 v[32:35], v[214:217], v[178:181], v[32:35]
	v_mfma_f32_16x16x32_bf16 v[20:23], v[206:209], v[186:189], v[20:23]
	v_mfma_f32_16x16x32_bf16 v[16:19], v[214:217], v[186:189], v[16:19]
	v_mfma_f32_16x16x32_bf16 v[4:7], v[206:209], v[194:197], v[4:7]
	v_mfma_f32_16x16x32_bf16 v[0:3], v[214:217], v[194:197], v[0:3]
	v_mfma_f32_16x16x32_bf16 v[52:55], v[210:213], v[174:177], v[52:55]
	v_mfma_f32_16x16x32_bf16 v[48:51], v[218:221], v[174:177], v[48:51]
	v_mfma_f32_16x16x32_bf16 v[36:39], v[210:213], v[182:185], v[36:39]
	v_mfma_f32_16x16x32_bf16 v[32:35], v[218:221], v[182:185], v[32:35]
	v_mfma_f32_16x16x32_bf16 v[20:23], v[210:213], v[190:193], v[20:23]
	v_mfma_f32_16x16x32_bf16 v[16:19], v[218:221], v[190:193], v[16:19]
	v_mfma_f32_16x16x32_bf16 v[4:7], v[210:213], v[202:205], v[4:7]
	v_mfma_f32_16x16x32_bf16 v[0:3], v[218:221], v[202:205], v[0:3]
	s_setprio 0
	s_add_i32 s56, s56, 2
	s_add_u32 s6, s6, 0x100
	s_addc_u32 s7, s7, 0
	s_add_u32 s54, s54, 0x100
	s_addc_u32 s55, s55, 0
	s_cmp_gt_u32 s56, 13
	s_barrier
.LBB0_578:
	ds_read_b128 v[128:131], v167
	ds_read_b128 v[132:135], v167 offset:1024
	ds_read_b128 v[136:139], v167 offset:2048
	ds_read_b128 v[160:163], v167 offset:3072
	s_add_u32 s26, s6, 0xfffc0080
	s_addc_u32 s27, s7, -1
	s_cmp_eq_u32 s56, 12
	s_cselect_b32 s29, s5, s27
	s_cselect_b32 s28, s21, s26
	s_cselect_b32 s27, s19, s55
	s_cselect_b32 s26, s53, s54
	s_add_i32 m0, s37, 0xc000
	ds_read_b128 v[170:173], v168
	ds_read_b128 v[174:177], v168 offset:1024
	ds_read_b128 v[178:181], v168 offset:2048
	ds_read_b128 v[182:185], v168 offset:3072
	ds_read_b128 v[186:189], v168 offset:4096
	ds_read_b128 v[190:193], v168 offset:5120
	ds_read_b128 v[194:197], v168 offset:6144
	ds_read_b128 v[202:205], v168 offset:7168
	global_load_lds_dwordx4 v152, s[6:7]
	s_add_i32 m0, s37, 0xe000
	s_nop 0
	global_load_lds_dwordx4 v154, s[6:7]
	s_waitcnt vmcnt(10)
	s_barrier
	s_waitcnt lgkmcnt(0)
	s_setprio 1
	s_waitcnt lgkmcnt(0)
	v_mfma_f32_16x16x32_bf16 v[124:127], v[128:131], v[170:173], v[124:127]
	v_mfma_f32_16x16x32_bf16 v[120:123], v[136:139], v[170:173], v[120:123]
	v_mfma_f32_16x16x32_bf16 v[108:111], v[128:131], v[178:181], v[108:111]
	v_mfma_f32_16x16x32_bf16 v[104:107], v[136:139], v[178:181], v[104:107]
	v_mfma_f32_16x16x32_bf16 v[92:95], v[128:131], v[186:189], v[92:95]
	v_mfma_f32_16x16x32_bf16 v[88:91], v[136:139], v[186:189], v[88:91]
	v_mfma_f32_16x16x32_bf16 v[76:79], v[128:131], v[194:197], v[76:79]
	v_mfma_f32_16x16x32_bf16 v[72:75], v[136:139], v[194:197], v[72:75]
	v_mfma_f32_16x16x32_bf16 v[124:127], v[132:135], v[174:177], v[124:127]
	v_mfma_f32_16x16x32_bf16 v[120:123], v[160:163], v[174:177], v[120:123]
	v_mfma_f32_16x16x32_bf16 v[108:111], v[132:135], v[182:185], v[108:111]
	v_mfma_f32_16x16x32_bf16 v[104:107], v[160:163], v[182:185], v[104:107]
	v_mfma_f32_16x16x32_bf16 v[92:95], v[132:135], v[190:193], v[92:95]
	v_mfma_f32_16x16x32_bf16 v[88:91], v[160:163], v[190:193], v[88:91]
	v_mfma_f32_16x16x32_bf16 v[76:79], v[132:135], v[202:205], v[76:79]
	v_mfma_f32_16x16x32_bf16 v[72:75], v[160:163], v[202:205], v[72:75]
	s_setprio 0
	s_barrier
	s_add_i32 s57, s48, s34
	s_mov_b32 m0, s57
	ds_read_b128 v[206:209], v169
	ds_read_b128 v[210:213], v169 offset:1024
	ds_read_b128 v[214:217], v169 offset:2048
	ds_read_b128 v[218:221], v169 offset:3072
	global_load_lds_dwordx4 v146, s[26:27]
	s_add_i32 m0, s57, 0x2000
	s_nop 0
	global_load_lds_dwordx4 v142, s[26:27]
	s_waitcnt vmcnt(10)
	s_barrier
; #define PG8_STAGE(bufoff, gbase, voff) do { _Pragma("unroll") for (int _i = 0; _i < 2; ++_i) \
;         __builtin_amdgcn_global_load_lds((const unsigned*)((const char*)(gbase) + (voff)[_i]), (LAS unsigned*)(lds + (bufoff) + ldsw + _i * 8192), 16, 0, 0); } while (0)
; #define PG8_LDA(dst, b, h) do { _Pragma("unroll") for (int m = 0; m < 4; ++m) _Pragma("unroll") for (int k = 0; k < 2; ++k) dst[m][k] = *(const LAS bf16x8*)(lds + PG8_SA(b, h) + aoff + m * 2048 + k * 1024); } while (0)
; #define PG8_LDB(dst, b, h) do { _Pragma("unroll") for (int n = 0; n < 2; ++n) _Pragma("unroll") for (int k = 0; k < 2; ++k) dst[n][k] = *(const LAS bf16x8*)(lds + PG8_SB(b, h) + boff + n * 2048 + k * 1024); } while (0)
; #define PG8_MMA(ai, bj, At, Bt) do { __builtin_amdgcn_s_setprio(1); _Pragma("unroll") for (int m = 0; m < 4; ++m) _Pragma("unroll") for (int n = 0; n < 2; ++n) _Pragma("unroll") for (int k = 0; k < 2; ++k) \
;         acc[ai][bj][m][n] = __builtin_amdgcn_mfma_f32_16x16x32_bf16(Bt[n][k], At[m][k], acc[ai][bj][m][n], 0, 0, 0); __builtin_amdgcn_s_setprio(0); } while (0)
; #define PG8_WAIT_V(n) asm volatile("s_waitcnt vmcnt(" #n ")" ::: "memory")
; #define PG8_WAIT_L(n) asm volatile("s_waitcnt lgkmcnt(" #n ")" ::: "memory")
; #define PG8_BAR __builtin_amdgcn_s_barrier()
; #define PG8_SCHED __builtin_amdgcn_sched_barrier(0)
; template <class Epi, class Sched>
; __device__ __forceinline__ void gemm_phase(LAS unsigned char* lds, const Gemm g, const Sched& S, const Epi& E) {
;     ...
;             PG8_BAR; PG8_WAIT_L(0); PG8_MMA(1, 0, At, B0); PG8_BAR; PG8_SCHED;
;             PG8_STAGE(PG8_SB(0, 1), b2 + hstep, voffB);
;             PG8_WAIT_V(6); PG8_BAR; PG8_MMA(1, 1, At, B1); PG8_BAR;
;             PG8_LDB(B0, 1, 0); PG8_SCHED; PG8_LDA(At, 1, 0); PG8_STAGE(PG8_SA(0, 1), a2 + hstep, voffA);
;             PG8_WAIT_L(8); PG8_BAR; PG8_WAIT_L(0); PG8_MMA(0, 0, At, B0); PG8_BAR; PG8_SCHED;
	s_waitcnt lgkmcnt(0)
	s_setprio 1
	s_waitcnt lgkmcnt(0)
	v_mfma_f32_16x16x32_bf16 v[116:119], v[206:209], v[170:173], v[116:119]
	v_mfma_f32_16x16x32_bf16 v[112:115], v[214:217], v[170:173], v[112:115]
	v_mfma_f32_16x16x32_bf16 v[100:103], v[206:209], v[178:181], v[100:103]
	v_mfma_f32_16x16x32_bf16 v[96:99], v[214:217], v[178:181], v[96:99]
	v_mfma_f32_16x16x32_bf16 v[84:87], v[206:209], v[186:189], v[84:87]
	v_mfma_f32_16x16x32_bf16 v[80:83], v[214:217], v[186:189], v[80:83]
	v_mfma_f32_16x16x32_bf16 v[68:71], v[206:209], v[194:197], v[68:71]
	v_mfma_f32_16x16x32_bf16 v[64:67], v[214:217], v[194:197], v[64:67]
	v_mfma_f32_16x16x32_bf16 v[116:119], v[210:213], v[174:177], v[116:119]
	v_mfma_f32_16x16x32_bf16 v[112:115], v[218:221], v[174:177], v[112:115]
	v_mfma_f32_16x16x32_bf16 v[100:103], v[210:213], v[182:185], v[100:103]
	v_mfma_f32_16x16x32_bf16 v[96:99], v[218:221], v[182:185], v[96:99]
	v_mfma_f32_16x16x32_bf16 v[84:87], v[210:213], v[190:193], v[84:87]
	v_mfma_f32_16x16x32_bf16 v[80:83], v[218:221], v[190:193], v[80:83]
	v_mfma_f32_16x16x32_bf16 v[68:71], v[210:213], v[202:205], v[68:71]
	v_mfma_f32_16x16x32_bf16 v[64:67], v[218:221], v[202:205], v[64:67]
	s_setprio 0
	s_mov_b32 m0, s37
	v_lshl_add_u64 v[222:223], s[28:29], 0, v[148:149]
	s_barrier
	ds_read_b128 v[170:173], v168 offset:16384
	ds_read_b128 v[174:177], v168 offset:17408
	ds_read_b128 v[178:181], v168 offset:18432
	ds_read_b128 v[182:185], v168 offset:19456
	ds_read_b128 v[186:189], v168 offset:20480
	ds_read_b128 v[190:193], v168 offset:21504
	ds_read_b128 v[194:197], v168 offset:22528
	ds_read_b128 v[202:205], v168 offset:23552
	global_load_lds_dwordx4 v148, s[28:29]
	v_lshl_add_u64 v[224:225], s[28:29], 0, v[144:145]
	s_mov_b32 m0, s38
	s_nop 0
	global_load_lds_dwordx4 v144, s[28:29]
	s_barrier
	s_waitcnt lgkmcnt(0)
	s_setprio 1
	s_waitcnt lgkmcnt(0)
	v_mfma_f32_16x16x32_bf16 v[60:63], v[128:131], v[170:173], v[60:63]
	v_mfma_f32_16x16x32_bf16 v[56:59], v[136:139], v[170:173], v[56:59]
	v_mfma_f32_16x16x32_bf16 v[44:47], v[128:131], v[178:181], v[44:47]
	v_mfma_f32_16x16x32_bf16 v[40:43], v[136:139], v[178:181], v[40:43]
	v_mfma_f32_16x16x32_bf16 v[28:31], v[128:131], v[186:189], v[28:31]
	v_mfma_f32_16x16x32_bf16 v[24:27], v[136:139], v[186:189], v[24:27]
	v_mfma_f32_16x16x32_bf16 v[12:15], v[128:131], v[194:197], v[12:15]
	v_mfma_f32_16x16x32_bf16 v[8:11], v[136:139], v[194:197], v[8:11]
	v_mfma_f32_16x16x32_bf16 v[60:63], v[132:135], v[174:177], v[60:63]
	v_mfma_f32_16x16x32_bf16 v[56:59], v[160:163], v[174:177], v[56:59]
	v_mfma_f32_16x16x32_bf16 v[44:47], v[132:135], v[182:185], v[44:47]
	v_mfma_f32_16x16x32_bf16 v[40:43], v[160:163], v[182:185], v[40:43]
	v_mfma_f32_16x16x32_bf16 v[28:31], v[132:135], v[190:193], v[28:31]
	v_mfma_f32_16x16x32_bf16 v[24:27], v[160:163], v[190:193], v[24:27]
	v_mfma_f32_16x16x32_bf16 v[12:15], v[132:135], v[202:205], v[12:15]
	v_mfma_f32_16x16x32_bf16 v[8:11], v[160:163], v[202:205], v[8:11]
	s_setprio 0
	s_barrier
	s_add_u32 s58, s26, 0x40000
	s_addc_u32 s59, s27, 0
	s_add_i32 s57, s49, s34
	s_mov_b32 m0, s57
	s_nop 0
	global_load_lds_dwordx4 v146, s[58:59]
	s_add_i32 m0, s57, 0x2000
	s_nop 0
	global_load_lds_dwordx4 v142, s[58:59]
	s_add_u32 s28, s28, 0x40000
	s_addc_u32 s29, s29, 0
	s_mov_b32 m0, s39
	s_nop 0
	global_load_lds_dwordx4 v148, s[28:29]
	s_mov_b32 m0, s40
	s_nop 0
	global_load_lds_dwordx4 v144, s[28:29]
	s_waitcnt vmcnt(12)
	s_barrier
	s_setprio 1
	v_mfma_f32_16x16x32_bf16 v[52:55], v[206:209], v[170:173], v[52:55]
	v_mfma_f32_16x16x32_bf16 v[48:51], v[214:217], v[170:173], v[48:51]
	v_mfma_f32_16x16x32_bf16 v[36:39], v[206:209], v[178:181], v[36:39]
	v_mfma_f32_16x16x32_bf16 v[32:35], v[214:217], v[178:181], v[32:35]
	v_mfma_f32_16x16x32_bf16 v[20:23], v[206:209], v[186:189], v[20:23]
	v_mfma_f32_16x16x32_bf16 v[16:19], v[214:217], v[186:189], v[16:19]
	v_mfma_f32_16x16x32_bf16 v[4:7], v[206:209], v[194:197], v[4:7]
	v_mfma_f32_16x16x32_bf16 v[0:3], v[214:217], v[194:197], v[0:3]
	v_mfma_f32_16x16x32_bf16 v[52:55], v[210:213], v[174:177], v[52:55]
	v_mfma_f32_16x16x32_bf16 v[48:51], v[218:221], v[174:177], v[48:51]
	v_mfma_f32_16x16x32_bf16 v[36:39], v[210:213], v[182:185], v[36:39]
	v_mfma_f32_16x16x32_bf16 v[32:35], v[218:221], v[182:185], v[32:35]
	v_mfma_f32_16x16x32_bf16 v[20:23], v[210:213], v[190:193], v[20:23]
	v_mfma_f32_16x16x32_bf16 v[16:19], v[218:221], v[190:193], v[16:19]
	v_mfma_f32_16x16x32_bf16 v[4:7], v[210:213], v[202:205], v[4:7]
	v_mfma_f32_16x16x32_bf16 v[0:3], v[218:221], v[202:205], v[0:3]
	s_setprio 0
	s_add_i32 s57, 0, 0x18000
	v_add_u32_e32 v150, s57, v166
	s_barrier
	ds_read_b128 v[128:131], v150
	ds_read_b128 v[132:135], v150 offset:1024
	ds_read_b128 v[136:139], v150 offset:2048
	ds_read_b128 v[160:163], v150 offset:3072
	ds_read_b128 v[170:173], v168 offset:32768
	ds_read_b128 v[174:177], v168 offset:33792
	ds_read_b128 v[178:181], v168 offset:34816
	ds_read_b128 v[182:185], v168 offset:35840
	ds_read_b128 v[186:189], v168 offset:36864
	ds_read_b128 v[190:193], v168 offset:37888
	ds_read_b128 v[194:197], v168 offset:38912
	ds_read_b128 v[202:205], v168 offset:39936
	s_waitcnt vmcnt(10)
	s_barrier
; #define PG8_STAGE(bufoff, gbase, voff) do { _Pragma("unroll") for (int _i = 0; _i < 2; ++_i) \
;         __builtin_amdgcn_global_load_lds((const unsigned*)((const char*)(gbase) + (voff)[_i]), (LAS unsigned*)(lds + (bufoff) + ldsw + _i * 8192), 16, 0, 0); } while (0)
; #define PG8_LDA(dst, b, h) do { _Pragma("unroll") for (int m = 0; m < 4; ++m) _Pragma("unroll") for (int k = 0; k < 2; ++k) dst[m][k] = *(const LAS bf16x8*)(lds + PG8_SA(b, h) + aoff + m * 2048 + k * 1024); } while (0)
; #define PG8_LDB(dst, b, h) do { _Pragma("unroll") for (int n = 0; n < 2; ++n) _Pragma("unroll") for (int k = 0; k < 2; ++k) dst[n][k] = *(const LAS bf16x8*)(lds + PG8_SB(b, h) + boff + n * 2048 + k * 1024); } while (0)
; #define PG8_MMA(ai, bj, At, Bt) do { __builtin_amdgcn_s_setprio(1); _Pragma("unroll") for (int m = 0; m < 4; ++m) _Pragma("unroll") for (int n = 0; n < 2; ++n) _Pragma("unroll") for (int k = 0; k < 2; ++k) \
;         acc[ai][bj][m][n] = __builtin_amdgcn_mfma_f32_16x16x32_bf16(Bt[n][k], At[m][k], acc[ai][bj][m][n], 0, 0, 0); __builtin_amdgcn_s_setprio(0); } while (0)
; #define PG8_WAIT_L(n) asm volatile("s_waitcnt lgkmcnt(" #n ")" ::: "memory")
; #define PG8_BAR __builtin_amdgcn_s_barrier()
; #define PG8_SCHED __builtin_amdgcn_sched_barrier(0)
; template <class Epi, class Sched>
; __device__ __forceinline__ void gemm_phase(LAS unsigned char* lds, const Gemm g, const Sched& S, const Epi& E) {
;     ...
;             PG8_WAIT_L(8); PG8_BAR; PG8_WAIT_L(0); PG8_MMA(0, 0, At, B0); PG8_BAR; PG8_SCHED;
;             PG8_LDB(B1, 1, 1); PG8_STAGE(PG8_SB(1, 0), b3, voffB);
;             PG8_BAR; PG8_WAIT_L(0); PG8_MMA(0, 1, At, B1); PG8_BAR;
;             PG8_LDA(At, 1, 1); PG8_STAGE(PG8_SA(1, 0), a3, voffA);
	s_waitcnt lgkmcnt(0)
	s_setprio 1
	s_waitcnt lgkmcnt(0)
	v_mfma_f32_16x16x32_bf16 v[124:127], v[128:131], v[170:173], v[124:127]
	v_mfma_f32_16x16x32_bf16 v[120:123], v[136:139], v[170:173], v[120:123]
	v_mfma_f32_16x16x32_bf16 v[108:111], v[128:131], v[178:181], v[108:111]
	v_mfma_f32_16x16x32_bf16 v[104:107], v[136:139], v[178:181], v[104:107]
	v_mfma_f32_16x16x32_bf16 v[92:95], v[128:131], v[186:189], v[92:95]
	v_mfma_f32_16x16x32_bf16 v[88:91], v[136:139], v[186:189], v[88:91]
	v_mfma_f32_16x16x32_bf16 v[76:79], v[128:131], v[194:197], v[76:79]
	v_mfma_f32_16x16x32_bf16 v[72:75], v[136:139], v[194:197], v[72:75]
	v_mfma_f32_16x16x32_bf16 v[124:127], v[132:135], v[174:177], v[124:127]
	v_mfma_f32_16x16x32_bf16 v[120:123], v[160:163], v[174:177], v[120:123]
	v_mfma_f32_16x16x32_bf16 v[108:111], v[132:135], v[182:185], v[108:111]
	v_mfma_f32_16x16x32_bf16 v[104:107], v[160:163], v[182:185], v[104:107]
	v_mfma_f32_16x16x32_bf16 v[92:95], v[132:135], v[190:193], v[92:95]
	v_mfma_f32_16x16x32_bf16 v[88:91], v[160:163], v[190:193], v[88:91]
	v_mfma_f32_16x16x32_bf16 v[76:79], v[132:135], v[202:205], v[76:79]
	v_mfma_f32_16x16x32_bf16 v[72:75], v[160:163], v[202:205], v[72:75]
	s_setprio 0
	s_barrier
	s_add_i32 s28, 0, 0x1c000
	s_add_i32 s29, s57, s34
	v_add_u32_e32 v150, s28, v166
	s_add_u32 s0, s26, 0x80
	s_addc_u32 s1, s27, 0
	s_mov_b32 m0, s29
	ds_read_b128 v[206:209], v150
	ds_read_b128 v[210:213], v150 offset:1024
	ds_read_b128 v[214:217], v150 offset:2048
	ds_read_b128 v[218:221], v150 offset:3072
	global_load_lds_dwordx4 v146, s[0:1]
	s_add_i32 m0, s29, 0x2000
	s_nop 0
	global_load_lds_dwordx4 v142, s[0:1]
	s_waitcnt vmcnt(10)
	s_barrier
	s_waitcnt lgkmcnt(0)
	s_setprio 1
	s_waitcnt lgkmcnt(0)
	v_mfma_f32_16x16x32_bf16 v[116:119], v[206:209], v[170:173], v[116:119]
	v_mfma_f32_16x16x32_bf16 v[112:115], v[214:217], v[170:173], v[112:115]
	v_mfma_f32_16x16x32_bf16 v[100:103], v[206:209], v[178:181], v[100:103]
	v_mfma_f32_16x16x32_bf16 v[96:99], v[214:217], v[178:181], v[96:99]
	v_mfma_f32_16x16x32_bf16 v[84:87], v[206:209], v[186:189], v[84:87]
	v_mfma_f32_16x16x32_bf16 v[80:83], v[214:217], v[186:189], v[80:83]
	v_mfma_f32_16x16x32_bf16 v[68:71], v[206:209], v[194:197], v[68:71]
	v_mfma_f32_16x16x32_bf16 v[64:67], v[214:217], v[194:197], v[64:67]
	v_mfma_f32_16x16x32_bf16 v[116:119], v[210:213], v[174:177], v[116:119]
	v_mfma_f32_16x16x32_bf16 v[112:115], v[218:221], v[174:177], v[112:115]
	v_mfma_f32_16x16x32_bf16 v[100:103], v[210:213], v[182:185], v[100:103]
	v_mfma_f32_16x16x32_bf16 v[96:99], v[218:221], v[182:185], v[96:99]
	v_mfma_f32_16x16x32_bf16 v[84:87], v[210:213], v[190:193], v[84:87]
	v_mfma_f32_16x16x32_bf16 v[80:83], v[218:221], v[190:193], v[80:83]
	v_mfma_f32_16x16x32_bf16 v[68:71], v[210:213], v[202:205], v[68:71]
	v_mfma_f32_16x16x32_bf16 v[64:67], v[218:221], v[202:205], v[64:67]
	s_setprio 0
	s_mov_b32 m0, s44
	s_mov_b64 s[0:1], 0x80
	v_lshl_add_u64 v[140:141], v[222:223], 0, s[0:1]
	s_barrier
	ds_read_b128 v[170:173], v168 offset:49152
	ds_read_b128 v[174:177], v168 offset:50176
	ds_read_b128 v[178:181], v168 offset:51200
	ds_read_b128 v[182:185], v168 offset:52224
	ds_read_b128 v[186:189], v168 offset:53248
	ds_read_b128 v[190:193], v168 offset:54272
	ds_read_b128 v[194:197], v168 offset:55296
	ds_read_b128 v[202:205], v168 offset:56320
	global_load_lds_dwordx4 v[140:141], off
	v_lshl_add_u64 v[140:141], v[224:225], 0, s[0:1]
	s_mov_b32 m0, s45
	s_nop 0
	global_load_lds_dwordx4 v[140:141], off
	s_barrier
; #define PG8_STAGE(bufoff, gbase, voff) do { _Pragma("unroll") for (int _i = 0; _i < 2; ++_i) \
;         __builtin_amdgcn_global_load_lds((const unsigned*)((const char*)(gbase) + (voff)[_i]), (LAS unsigned*)(lds + (bufoff) + ldsw + _i * 8192), 16, 0, 0); } while (0)
; #define PG8_MMA(ai, bj, At, Bt) do { __builtin_amdgcn_s_setprio(1); _Pragma("unroll") for (int m = 0; m < 4; ++m) _Pragma("unroll") for (int n = 0; n < 2; ++n) _Pragma("unroll") for (int k = 0; k < 2; ++k) \
;         acc[ai][bj][m][n] = __builtin_amdgcn_mfma_f32_16x16x32_bf16(Bt[n][k], At[m][k], acc[ai][bj][m][n], 0, 0, 0); __builtin_amdgcn_s_setprio(0); } while (0)
; #define PG8_WAIT_V(n) asm volatile("s_waitcnt vmcnt(" #n ")" ::: "memory")
; #define PG8_WAIT_L(n) asm volatile("s_waitcnt lgkmcnt(" #n ")" ::: "memory")
; #define PG8_BAR __builtin_amdgcn_s_barrier()
; #define PG8_SCHED __builtin_amdgcn_sched_barrier(0)
; template <class Epi, class Sched>
; __device__ __forceinline__ void gemm_phase(LAS unsigned char* lds, const Gemm g, const Sched& S, const Epi& E) {
;     ...
;             PG8_BAR; PG8_WAIT_L(0); PG8_MMA(1, 0, At, B0); PG8_BAR; PG8_SCHED;
;             PG8_STAGE(PG8_SB(1, 1), b3 + hstep, voffB);
;             PG8_WAIT_V(6); PG8_BAR; PG8_MMA(1, 1, At, B1); PG8_BAR;
;     __device__ __forceinline__ void operator()(const AccT& acc, const Unit& u, int wr, int wc, int fr, int fq) const {
;     ...
;         const int row0 = u.pm * 256 + wr * 64 + fr, col0 = u.pn * 256 + wc * 32 + 8 * fq;
;         const bool rope = u.pn < 2;
;         const int i = 4 * (wc & 1) + fq;
; #pragma unroll
;         for (int ai = 0; ai < 2; ++ai)
; #pragma unroll
;             for (int m = 0; m < 4; ++m) {
;                 const int row = row0 + ai * 128 + m * 16;
;                 f32x4 cs = {1.f, 1.f, 1.f, 1.f}, sn = {0.f, 0.f, 0.f, 0.f};
;                 if (rope) { const int t = row & 2047; const int pos = (i < 4) ? (t >> 6) : (t & 63);
;                     cs = *(const f32x4*)(ropeA + pos * 16 + ((4 * i) & 15)); sn = *(const f32x4*)(ropeA + 1024 + pos * 16 + ((4 * i) & 15)); }
	s_waitcnt lgkmcnt(0)
	s_setprio 1
	s_waitcnt lgkmcnt(0)
	v_mfma_f32_16x16x32_bf16 v[60:63], v[128:131], v[170:173], v[60:63]
	v_mfma_f32_16x16x32_bf16 v[56:59], v[136:139], v[170:173], v[56:59]
	v_mfma_f32_16x16x32_bf16 v[44:47], v[128:131], v[178:181], v[44:47]
	v_mfma_f32_16x16x32_bf16 v[40:43], v[136:139], v[178:181], v[40:43]
	v_mfma_f32_16x16x32_bf16 v[28:31], v[128:131], v[186:189], v[28:31]
	v_mfma_f32_16x16x32_bf16 v[24:27], v[136:139], v[186:189], v[24:27]
	v_mfma_f32_16x16x32_bf16 v[12:15], v[128:131], v[194:197], v[12:15]
	v_mfma_f32_16x16x32_bf16 v[8:11], v[136:139], v[194:197], v[8:11]
	v_mfma_f32_16x16x32_bf16 v[60:63], v[132:135], v[174:177], v[60:63]
	v_mfma_f32_16x16x32_bf16 v[56:59], v[160:163], v[174:177], v[56:59]
	v_mfma_f32_16x16x32_bf16 v[44:47], v[132:135], v[182:185], v[44:47]
	v_mfma_f32_16x16x32_bf16 v[40:43], v[160:163], v[182:185], v[40:43]
	v_mfma_f32_16x16x32_bf16 v[28:31], v[132:135], v[190:193], v[28:31]
	v_mfma_f32_16x16x32_bf16 v[24:27], v[160:163], v[190:193], v[24:27]
	v_mfma_f32_16x16x32_bf16 v[12:15], v[132:135], v[202:205], v[12:15]
	v_mfma_f32_16x16x32_bf16 v[8:11], v[160:163], v[202:205], v[8:11]
	s_setprio 0
	s_barrier
	s_add_u32 s26, s26, 0x40080
	s_addc_u32 s27, s27, 0
	s_add_i32 s28, s28, s34
	s_mov_b32 m0, s28
	s_nop 0
	global_load_lds_dwordx4 v146, s[26:27]
	s_add_i32 m0, s28, 0x2000
	s_nop 0
	global_load_lds_dwordx4 v142, s[26:27]
	s_waitcnt vmcnt(10)
	s_barrier
	s_setprio 1
	v_mfma_f32_16x16x32_bf16 v[52:55], v[206:209], v[170:173], v[52:55]
	v_mfma_f32_16x16x32_bf16 v[48:51], v[214:217], v[170:173], v[48:51]
	v_mfma_f32_16x16x32_bf16 v[36:39], v[206:209], v[178:181], v[36:39]
	v_mfma_f32_16x16x32_bf16 v[32:35], v[214:217], v[178:181], v[32:35]
	v_mfma_f32_16x16x32_bf16 v[20:23], v[206:209], v[186:189], v[20:23]
	v_mfma_f32_16x16x32_bf16 v[16:19], v[214:217], v[186:189], v[16:19]
	v_mfma_f32_16x16x32_bf16 v[4:7], v[206:209], v[194:197], v[4:7]
	v_mfma_f32_16x16x32_bf16 v[0:3], v[214:217], v[194:197], v[0:3]
	v_mfma_f32_16x16x32_bf16 v[52:55], v[210:213], v[174:177], v[52:55]
	v_mfma_f32_16x16x32_bf16 v[48:51], v[218:221], v[174:177], v[48:51]
	v_mfma_f32_16x16x32_bf16 v[36:39], v[210:213], v[182:185], v[36:39]
	v_mfma_f32_16x16x32_bf16 v[32:35], v[218:221], v[182:185], v[32:35]
	v_mfma_f32_16x16x32_bf16 v[20:23], v[210:213], v[190:193], v[20:23]
	v_mfma_f32_16x16x32_bf16 v[16:19], v[218:221], v[190:193], v[16:19]
	v_mfma_f32_16x16x32_bf16 v[4:7], v[210:213], v[202:205], v[4:7]
	v_mfma_f32_16x16x32_bf16 v[0:3], v[218:221], v[202:205], v[0:3]
	s_setprio 0
	s_add_i32 s56, s56, 2
	s_add_u32 s6, s6, 0x100
	s_addc_u32 s7, s7, 0
	s_add_u32 s54, s54, 0x100
	s_addc_u32 s55, s55, 0
	s_cmp_gt_u32 s56, 13
	s_barrier
	s_cbranch_scc0 .LBB0_578
	v_mov_b32_e32 v129, v165
	v_mov_b32_e32 v173, v164
	s_lshl_b32 s4, s4, 8
	s_add_i32 s4, s4, s42
	v_add_u32_e32 v128, s46, v129
	v_add_u32_e32 v170, s4, v173
	v_cmp_gt_i32_e64 s[4:5], 4, v128
	v_lshlrev_b32_e32 v128, 2, v128
	s_cmp_lt_i32 s52, 2
	v_and_b32_e32 v130, 12, v128
	s_cselect_b64 s[26:27], -1, 0
	s_cmp_gt_i32 s52, 1
	v_and_b32_e32 v172, 63, v173
	v_mov_b32_e32 v128, 1.0
	v_mov_b32_e32 v132, 0
	v_lshlrev_b32_e32 v162, 2, v130
	v_mov_b32_e32 v134, 0
	v_mov_b32_e32 v135, 0
	v_mov_b32_e32 v136, 0
	v_mov_b32_e32 v137, 0
	v_mov_b32_e32 v138, 1.0
	v_mov_b32_e32 v139, 1.0
	v_mov_b32_e32 v140, 1.0
	v_mov_b32_e32 v141, 1.0
	s_cbranch_scc1 .LBB0_581
	v_bfe_u32 v130, v170, 6, 5
	v_cndmask_b32_e64 v130, v172, v130, s[4:5]
	v_lshlrev_b32_e32 v150, 6, v130
	v_lshl_add_u64 v[130:131], s[16:17], 0, v[150:151]
	v_mov_b32_e32 v163, v151
	v_lshl_add_u64 v[134:135], s[8:9], 0, v[150:151]
	v_lshl_add_u64 v[130:131], v[130:131], 0, v[162:163]
	v_lshl_add_u64 v[134:135], v[134:135], 0, v[162:163]
	global_load_dwordx4 v[138:141], v[130:131], off
	s_nop 0
	global_load_dwordx4 v[134:137], v[134:135], off
	s_waitcnt vmcnt(0)

; #define PG8_STAGE(bufoff, gbase, voff) do { _Pragma("unroll") for (int _i = 0; _i < 2; ++_i) \
;         __builtin_amdgcn_global_load_lds((const unsigned*)((const char*)(gbase) + (voff)[_i]), (LAS unsigned*)(lds + (bufoff) + ldsw + _i * 8192), 16, 0, 0); } while (0)
; #define PG8_LDA(dst, b, h) do { _Pragma("unroll") for (int m = 0; m < 4; ++m) _Pragma("unroll") for (int k = 0; k < 2; ++k) dst[m][k] = *(const LAS bf16x8*)(lds + PG8_SA(b, h) + aoff + m * 2048 + k * 1024); } while (0)
; #define PG8_LDB(dst, b, h) do { _Pragma("unroll") for (int n = 0; n < 2; ++n) _Pragma("unroll") for (int k = 0; k < 2; ++k) dst[n][k] = *(const LAS bf16x8*)(lds + PG8_SB(b, h) + boff + n * 2048 + k * 1024); } while (0)
; #define PG8_MMA(ai, bj, At, Bt) do { __builtin_amdgcn_s_setprio(1); _Pragma("unroll") for (int m = 0; m < 4; ++m) _Pragma("unroll") for (int n = 0; n < 2; ++n) _Pragma("unroll") for (int k = 0; k < 2; ++k) \
;         acc[ai][bj][m][n] = __builtin_amdgcn_mfma_f32_16x16x32_bf16(Bt[n][k], At[m][k], acc[ai][bj][m][n], 0, 0, 0); __builtin_amdgcn_s_setprio(0); } while (0)
; template <class Epi, class Sched>
; __device__ __forceinline__ void gemm_phase(LAS unsigned char* lds, const Gemm g, const Sched& S, const Epi& E) {
;     ...
;         const char* nA = has_next ? (const char*)g.A + (size_t)nxt.pm * tstep : cA; const char* nB = has_next ? (const char*)g.Bt + (size_t)nxt.pn * tstep : cB;
;         for (int t = 0; t < nt; t += 2) {
;             const bool last = (t == nt - 2);
;             const char* a1 = cA + (size_t)(t + 1) * kstep;
;             const char* a2 = last ? nA : cA + (size_t)(t + 2) * kstep; const char* b2 = last ? nB : cB + (size_t)(t + 2) * kstep;
;             const char* a3 = a2 + kstep; const char* b3 = b2 + kstep;
;             PG8_LDB(B0, 0, 0); PG8_SCHED; PG8_LDA(At, 0, 0); PG8_STAGE(PG8_SA(1, 1), a1 + hstep, voffA);
;             PG8_WAIT_L(8); PG8_BAR; PG8_WAIT_L(0); PG8_MMA(0, 0, At, B0); PG8_BAR; PG8_SCHED;
;             PG8_LDB(B1, 0, 1); PG8_STAGE(PG8_SB(0, 0), b2, voffB);
;             PG8_BAR; PG8_WAIT_L(0); PG8_MMA(0, 1, At, B1); PG8_BAR;
;             PG8_LDA(At, 0, 1); PG8_STAGE(PG8_SA(0, 0), a2, voffA);
;             PG8_BAR; PG8_WAIT_L(0); PG8_MMA(1, 0, At, B0); PG8_BAR; PG8_SCHED;
;             PG8_STAGE(PG8_SB(0, 1), b2 + hstep, voffB);
;             PG8_WAIT_V(6); PG8_BAR; PG8_MMA(1, 1, At, B1); PG8_BAR;
.LBB0_612:
	s_ashr_i32 s35, s34, 31
	v_cmp_lt_i64_e32 vcc, s[6:7], v[142:143]
	s_lshl_b64 s[6:7], s[34:35], 19
	s_add_u32 s36, s40, s6
	s_addc_u32 s37, s41, s7
	s_and_b64 s[6:7], vcc, exec
	s_cselect_b32 s8, s37, s1
	s_cselect_b32 s9, s36, s0
	s_ashr_i32 s31, s30, 31
	s_lshl_b64 s[6:7], s[30:31], 19
	s_add_u32 s38, s96, s6
	s_addc_u32 s39, s97, s7
	s_and_b64 s[6:7], vcc, exec
	s_cselect_b32 s31, s39, s5
	s_cselect_b32 s35, s38, s4
	s_add_u32 s0, s0, 0x40080
	s_addc_u32 s1, s1, 0
	s_add_u32 s65, s4, 0x100
	s_addc_u32 s66, s5, 0
	s_mov_b32 s67, -2
	s_waitcnt lgkmcnt(0)
	ds_read_b128 v[146:149], v171
	ds_read_b128 v[150:153], v171 offset:1024
	ds_read_b128 v[154:157], v171 offset:2048
	ds_read_b128 v[158:161], v171 offset:3072
	s_add_u32 s4, s0, 0xfffc0080
	s_addc_u32 s5, s1, -1
	s_cmp_eq_u32 s67, 12
	s_cselect_b32 s7, s8, s5
	s_cselect_b32 s6, s9, s4
	s_cselect_b32 s5, s31, s66
	s_cselect_b32 s4, s35, s65
	s_add_i32 m0, s45, 0xc000
	ds_read_b128 v[162:165], v172
	ds_read_b128 v[178:181], v172 offset:1024
	ds_read_b128 v[182:185], v172 offset:2048
	ds_read_b128 v[186:189], v172 offset:3072
	ds_read_b128 v[190:193], v172 offset:4096
	ds_read_b128 v[194:197], v172 offset:5120
	ds_read_b128 v[202:205], v172 offset:6144
	ds_read_b128 v[206:209], v172 offset:7168
	global_load_lds_dwordx4 v138, s[0:1]
	s_add_i32 m0, s45, 0xe000
	s_nop 0
	global_load_lds_dwordx4 v140, s[0:1]
	s_waitcnt vmcnt(10)
	s_barrier
	s_waitcnt lgkmcnt(0)
	s_setprio 1
	s_waitcnt lgkmcnt(0)
	v_mfma_f32_16x16x32_bf16 v[124:127], v[146:149], v[162:165], 0
	v_mfma_f32_16x16x32_bf16 v[120:123], v[154:157], v[162:165], 0
	v_mfma_f32_16x16x32_bf16 v[108:111], v[146:149], v[182:185], 0
	v_mfma_f32_16x16x32_bf16 v[104:107], v[154:157], v[182:185], 0
	v_mfma_f32_16x16x32_bf16 v[92:95], v[146:149], v[190:193], 0
	v_mfma_f32_16x16x32_bf16 v[88:91], v[154:157], v[190:193], 0
	v_mfma_f32_16x16x32_bf16 v[76:79], v[146:149], v[202:205], 0
	v_mfma_f32_16x16x32_bf16 v[72:75], v[154:157], v[202:205], 0
	v_mfma_f32_16x16x32_bf16 v[124:127], v[150:153], v[178:181], v[124:127]
	v_mfma_f32_16x16x32_bf16 v[120:123], v[158:161], v[178:181], v[120:123]
	v_mfma_f32_16x16x32_bf16 v[108:111], v[150:153], v[186:189], v[108:111]
	v_mfma_f32_16x16x32_bf16 v[104:107], v[158:161], v[186:189], v[104:107]
	v_mfma_f32_16x16x32_bf16 v[92:95], v[150:153], v[194:197], v[92:95]
	v_mfma_f32_16x16x32_bf16 v[88:91], v[158:161], v[194:197], v[88:91]
	v_mfma_f32_16x16x32_bf16 v[76:79], v[150:153], v[206:209], v[76:79]
	v_mfma_f32_16x16x32_bf16 v[72:75], v[158:161], v[206:209], v[72:75]
	s_setprio 0
	s_barrier
	s_add_i32 s68, s57, s44
	s_mov_b32 m0, s68
	ds_read_b128 v[210:213], v173
	ds_read_b128 v[214:217], v173 offset:1024
	ds_read_b128 v[218:221], v173 offset:2048
	ds_read_b128 v[222:225], v173 offset:3072
	global_load_lds_dwordx4 v130, s[4:5]
	s_add_i32 m0, s68, 0x2000
	s_nop 0
	global_load_lds_dwordx4 v134, s[4:5]
	s_waitcnt vmcnt(10)
	s_barrier
	s_waitcnt lgkmcnt(0)
	s_setprio 1
	s_waitcnt lgkmcnt(0)
	v_mfma_f32_16x16x32_bf16 v[116:119], v[210:213], v[162:165], 0
	v_mfma_f32_16x16x32_bf16 v[112:115], v[218:221], v[162:165], 0
	v_mfma_f32_16x16x32_bf16 v[100:103], v[210:213], v[182:185], 0
	v_mfma_f32_16x16x32_bf16 v[96:99], v[218:221], v[182:185], 0
	v_mfma_f32_16x16x32_bf16 v[84:87], v[210:213], v[190:193], 0
	v_mfma_f32_16x16x32_bf16 v[80:83], v[218:221], v[190:193], 0
	v_mfma_f32_16x16x32_bf16 v[68:71], v[210:213], v[202:205], 0
	v_mfma_f32_16x16x32_bf16 v[64:67], v[218:221], v[202:205], 0
	v_mfma_f32_16x16x32_bf16 v[116:119], v[214:217], v[178:181], v[116:119]
	v_mfma_f32_16x16x32_bf16 v[112:115], v[222:225], v[178:181], v[112:115]
	v_mfma_f32_16x16x32_bf16 v[100:103], v[214:217], v[186:189], v[100:103]
	v_mfma_f32_16x16x32_bf16 v[96:99], v[222:225], v[186:189], v[96:99]
	v_mfma_f32_16x16x32_bf16 v[84:87], v[214:217], v[194:197], v[84:87]
	v_mfma_f32_16x16x32_bf16 v[80:83], v[222:225], v[194:197], v[80:83]
	v_mfma_f32_16x16x32_bf16 v[68:71], v[214:217], v[206:209], v[68:71]
	v_mfma_f32_16x16x32_bf16 v[64:67], v[222:225], v[206:209], v[64:67]
	s_setprio 0
	s_mov_b32 m0, s45
	v_lshl_add_u64 v[226:227], s[6:7], 0, v[128:129]
	s_barrier
	ds_read_b128 v[162:165], v172 offset:16384
	ds_read_b128 v[178:181], v172 offset:17408
	ds_read_b128 v[182:185], v172 offset:18432
	ds_read_b128 v[186:189], v172 offset:19456
	ds_read_b128 v[190:193], v172 offset:20480
	ds_read_b128 v[194:197], v172 offset:21504
	ds_read_b128 v[202:205], v172 offset:22528
	ds_read_b128 v[206:209], v172 offset:23552
	global_load_lds_dwordx4 v128, s[6:7]
	v_lshl_add_u64 v[228:229], s[6:7], 0, v[132:133]
	s_mov_b32 m0, s46
	s_nop 0
	global_load_lds_dwordx4 v132, s[6:7]
	s_barrier
	s_waitcnt lgkmcnt(0)
	s_setprio 1
	s_waitcnt lgkmcnt(0)
	v_mfma_f32_16x16x32_bf16 v[60:63], v[146:149], v[162:165], 0
	v_mfma_f32_16x16x32_bf16 v[56:59], v[154:157], v[162:165], 0
	v_mfma_f32_16x16x32_bf16 v[44:47], v[146:149], v[182:185], 0
	v_mfma_f32_16x16x32_bf16 v[40:43], v[154:157], v[182:185], 0
	v_mfma_f32_16x16x32_bf16 v[28:31], v[146:149], v[190:193], 0
	v_mfma_f32_16x16x32_bf16 v[24:27], v[154:157], v[190:193], 0
	v_mfma_f32_16x16x32_bf16 v[12:15], v[146:149], v[202:205], 0
	v_mfma_f32_16x16x32_bf16 v[8:11], v[154:157], v[202:205], 0
	v_mfma_f32_16x16x32_bf16 v[60:63], v[150:153], v[178:181], v[60:63]
	v_mfma_f32_16x16x32_bf16 v[56:59], v[158:161], v[178:181], v[56:59]
	v_mfma_f32_16x16x32_bf16 v[44:47], v[150:153], v[186:189], v[44:47]
	v_mfma_f32_16x16x32_bf16 v[40:43], v[158:161], v[186:189], v[40:43]
	v_mfma_f32_16x16x32_bf16 v[28:31], v[150:153], v[194:197], v[28:31]
	v_mfma_f32_16x16x32_bf16 v[24:27], v[158:161], v[194:197], v[24:27]
	v_mfma_f32_16x16x32_bf16 v[12:15], v[150:153], v[206:209], v[12:15]
	v_mfma_f32_16x16x32_bf16 v[8:11], v[158:161], v[206:209], v[8:11]
	s_setprio 0
	s_barrier
; #define PG8_STAGE(bufoff, gbase, voff) do { _Pragma("unroll") for (int _i = 0; _i < 2; ++_i) \
;         __builtin_amdgcn_global_load_lds((const unsigned*)((const char*)(gbase) + (voff)[_i]), (LAS unsigned*)(lds + (bufoff) + ldsw + _i * 8192), 16, 0, 0); } while (0)
; #define PG8_LDA(dst, b, h) do { _Pragma("unroll") for (int m = 0; m < 4; ++m) _Pragma("unroll") for (int k = 0; k < 2; ++k) dst[m][k] = *(const LAS bf16x8*)(lds + PG8_SA(b, h) + aoff + m * 2048 + k * 1024); } while (0)
; #define PG8_LDB(dst, b, h) do { _Pragma("unroll") for (int n = 0; n < 2; ++n) _Pragma("unroll") for (int k = 0; k < 2; ++k) dst[n][k] = *(const LAS bf16x8*)(lds + PG8_SB(b, h) + boff + n * 2048 + k * 1024); } while (0)
; #define PG8_MMA(ai, bj, At, Bt) do { __builtin_amdgcn_s_setprio(1); _Pragma("unroll") for (int m = 0; m < 4; ++m) _Pragma("unroll") for (int n = 0; n < 2; ++n) _Pragma("unroll") for (int k = 0; k < 2; ++k) \
;         acc[ai][bj][m][n] = __builtin_amdgcn_mfma_f32_16x16x32_bf16(Bt[n][k], At[m][k], acc[ai][bj][m][n], 0, 0, 0); __builtin_amdgcn_s_setprio(0); } while (0)
; #define PG8_WAIT_V(n) asm volatile("s_waitcnt vmcnt(" #n ")" ::: "memory")
; #define PG8_WAIT_L(n) asm volatile("s_waitcnt lgkmcnt(" #n ")" ::: "memory")
; #define PG8_BAR __builtin_amdgcn_s_barrier()
; #define PG8_SCHED __builtin_amdgcn_sched_barrier(0)
; template <class Epi, class Sched>
; __device__ __forceinline__ void gemm_phase(LAS unsigned char* lds, const Gemm g, const Sched& S, const Epi& E) {
;     ...
;             PG8_STAGE(PG8_SB(0, 1), b2 + hstep, voffB);
;             PG8_WAIT_V(6); PG8_BAR; PG8_MMA(1, 1, At, B1); PG8_BAR;
;             PG8_LDB(B0, 1, 0); PG8_SCHED; PG8_LDA(At, 1, 0); PG8_STAGE(PG8_SA(0, 1), a2 + hstep, voffA);
;             PG8_WAIT_L(8); PG8_BAR; PG8_WAIT_L(0); PG8_MMA(0, 0, At, B0); PG8_BAR; PG8_SCHED;
;             PG8_LDB(B1, 1, 1); PG8_STAGE(PG8_SB(1, 0), b3, voffB);
;             PG8_BAR; PG8_WAIT_L(0); PG8_MMA(0, 1, At, B1); PG8_BAR;
;             PG8_LDA(At, 1, 1); PG8_STAGE(PG8_SA(1, 0), a3, voffA);
;             PG8_BAR; PG8_WAIT_L(0); PG8_MMA(1, 0, At, B0); PG8_BAR; PG8_SCHED;
	s_add_u32 s68, s4, 0x40000
	s_addc_u32 s69, s5, 0
	s_add_i32 s70, s58, s44
	s_mov_b32 m0, s70
	s_nop 0
	global_load_lds_dwordx4 v130, s[68:69]
	s_add_i32 m0, s70, 0x2000
	s_nop 0
	global_load_lds_dwordx4 v134, s[68:69]
	s_add_u32 s6, s6, 0x40000
	s_addc_u32 s7, s7, 0
	s_mov_b32 m0, s47
	s_nop 0
	global_load_lds_dwordx4 v128, s[6:7]
	s_mov_b32 m0, s48
	s_nop 0
	global_load_lds_dwordx4 v132, s[6:7]
	s_waitcnt vmcnt(12)
	s_barrier
	s_setprio 1
	v_mfma_f32_16x16x32_bf16 v[52:55], v[210:213], v[162:165], 0
	v_mfma_f32_16x16x32_bf16 v[48:51], v[218:221], v[162:165], 0
	v_mfma_f32_16x16x32_bf16 v[36:39], v[210:213], v[182:185], 0
	v_mfma_f32_16x16x32_bf16 v[32:35], v[218:221], v[182:185], 0
	v_mfma_f32_16x16x32_bf16 v[20:23], v[210:213], v[190:193], 0
	v_mfma_f32_16x16x32_bf16 v[16:19], v[218:221], v[190:193], 0
	v_mfma_f32_16x16x32_bf16 v[4:7], v[210:213], v[202:205], 0
	v_mfma_f32_16x16x32_bf16 v[0:3], v[218:221], v[202:205], 0
	v_mfma_f32_16x16x32_bf16 v[52:55], v[214:217], v[178:181], v[52:55]
	v_mfma_f32_16x16x32_bf16 v[48:51], v[222:225], v[178:181], v[48:51]
	v_mfma_f32_16x16x32_bf16 v[36:39], v[214:217], v[186:189], v[36:39]
	v_mfma_f32_16x16x32_bf16 v[32:35], v[222:225], v[186:189], v[32:35]
	v_mfma_f32_16x16x32_bf16 v[20:23], v[214:217], v[194:197], v[20:23]
	v_mfma_f32_16x16x32_bf16 v[16:19], v[222:225], v[194:197], v[16:19]
	v_mfma_f32_16x16x32_bf16 v[4:7], v[214:217], v[206:209], v[4:7]
	v_mfma_f32_16x16x32_bf16 v[0:3], v[222:225], v[206:209], v[0:3]
	s_setprio 0
	s_add_i32 s68, 0, 0x18000
	v_add_u32_e32 v136, s68, v170
	s_barrier
	ds_read_b128 v[146:149], v136
	ds_read_b128 v[150:153], v136 offset:1024
	ds_read_b128 v[154:157], v136 offset:2048
	ds_read_b128 v[158:161], v136 offset:3072
	ds_read_b128 v[162:165], v172 offset:32768
	ds_read_b128 v[178:181], v172 offset:33792
	ds_read_b128 v[182:185], v172 offset:34816
	ds_read_b128 v[186:189], v172 offset:35840
	ds_read_b128 v[190:193], v172 offset:36864
	ds_read_b128 v[194:197], v172 offset:37888
	ds_read_b128 v[202:205], v172 offset:38912
	ds_read_b128 v[206:209], v172 offset:39936
	s_waitcnt vmcnt(10)
	s_barrier
	s_waitcnt lgkmcnt(0)
	s_setprio 1
	s_waitcnt lgkmcnt(0)
	v_mfma_f32_16x16x32_bf16 v[124:127], v[146:149], v[162:165], v[124:127]
	v_mfma_f32_16x16x32_bf16 v[120:123], v[154:157], v[162:165], v[120:123]
	v_mfma_f32_16x16x32_bf16 v[108:111], v[146:149], v[182:185], v[108:111]
	v_mfma_f32_16x16x32_bf16 v[104:107], v[154:157], v[182:185], v[104:107]
	v_mfma_f32_16x16x32_bf16 v[92:95], v[146:149], v[190:193], v[92:95]
	v_mfma_f32_16x16x32_bf16 v[88:91], v[154:157], v[190:193], v[88:91]
	v_mfma_f32_16x16x32_bf16 v[76:79], v[146:149], v[202:205], v[76:79]
	v_mfma_f32_16x16x32_bf16 v[72:75], v[154:157], v[202:205], v[72:75]
	v_mfma_f32_16x16x32_bf16 v[124:127], v[150:153], v[178:181], v[124:127]
	v_mfma_f32_16x16x32_bf16 v[120:123], v[158:161], v[178:181], v[120:123]
	v_mfma_f32_16x16x32_bf16 v[108:111], v[150:153], v[186:189], v[108:111]
	v_mfma_f32_16x16x32_bf16 v[104:107], v[158:161], v[186:189], v[104:107]
	v_mfma_f32_16x16x32_bf16 v[92:95], v[150:153], v[194:197], v[92:95]
	v_mfma_f32_16x16x32_bf16 v[88:91], v[158:161], v[194:197], v[88:91]
	v_mfma_f32_16x16x32_bf16 v[76:79], v[150:153], v[206:209], v[76:79]
	v_mfma_f32_16x16x32_bf16 v[72:75], v[158:161], v[206:209], v[72:75]
	s_setprio 0
	s_barrier
	s_add_i32 s6, 0, 0x1c000
	s_add_i32 s7, s68, s44
	v_add_u32_e32 v136, s6, v170
	s_add_u32 s20, s4, 0x80
	s_addc_u32 s21, s5, 0
	s_mov_b32 m0, s7
	ds_read_b128 v[210:213], v136
	ds_read_b128 v[214:217], v136 offset:1024
	ds_read_b128 v[218:221], v136 offset:2048
	ds_read_b128 v[222:225], v136 offset:3072
	global_load_lds_dwordx4 v130, s[20:21]
	s_add_i32 m0, s7, 0x2000
	s_nop 0
	global_load_lds_dwordx4 v134, s[20:21]
	s_waitcnt vmcnt(10)
	s_barrier
	s_waitcnt lgkmcnt(0)
	s_setprio 1
	s_waitcnt lgkmcnt(0)
	v_mfma_f32_16x16x32_bf16 v[116:119], v[210:213], v[162:165], v[116:119]
	v_mfma_f32_16x16x32_bf16 v[112:115], v[218:221], v[162:165], v[112:115]
	v_mfma_f32_16x16x32_bf16 v[100:103], v[210:213], v[182:185], v[100:103]
	v_mfma_f32_16x16x32_bf16 v[96:99], v[218:221], v[182:185], v[96:99]
	v_mfma_f32_16x16x32_bf16 v[84:87], v[210:213], v[190:193], v[84:87]
	v_mfma_f32_16x16x32_bf16 v[80:83], v[218:221], v[190:193], v[80:83]
	v_mfma_f32_16x16x32_bf16 v[68:71], v[210:213], v[202:205], v[68:71]
	v_mfma_f32_16x16x32_bf16 v[64:67], v[218:221], v[202:205], v[64:67]
	v_mfma_f32_16x16x32_bf16 v[116:119], v[214:217], v[178:181], v[116:119]
	v_mfma_f32_16x16x32_bf16 v[112:115], v[222:225], v[178:181], v[112:115]
	v_mfma_f32_16x16x32_bf16 v[100:103], v[214:217], v[186:189], v[100:103]
	v_mfma_f32_16x16x32_bf16 v[96:99], v[222:225], v[186:189], v[96:99]
	v_mfma_f32_16x16x32_bf16 v[84:87], v[214:217], v[194:197], v[84:87]
	v_mfma_f32_16x16x32_bf16 v[80:83], v[222:225], v[194:197], v[80:83]
	v_mfma_f32_16x16x32_bf16 v[68:71], v[214:217], v[206:209], v[68:71]
	v_mfma_f32_16x16x32_bf16 v[64:67], v[222:225], v[206:209], v[64:67]
	s_setprio 0
	s_mov_b32 m0, s54
	s_mov_b64 s[20:21], 0x80
	v_lshl_add_u64 v[166:167], v[226:227], 0, s[20:21]
	s_barrier
	ds_read_b128 v[162:165], v172 offset:49152
	ds_read_b128 v[178:181], v172 offset:50176
	ds_read_b128 v[182:185], v172 offset:51200
	ds_read_b128 v[186:189], v172 offset:52224
	ds_read_b128 v[190:193], v172 offset:53248
	ds_read_b128 v[194:197], v172 offset:54272
	ds_read_b128 v[202:205], v172 offset:55296
	ds_read_b128 v[206:209], v172 offset:56320
	global_load_lds_dwordx4 v[166:167], off
	v_lshl_add_u64 v[166:167], v[228:229], 0, s[20:21]
	s_mov_b32 m0, s55
	s_nop 0
	global_load_lds_dwordx4 v[166:167], off
	s_barrier
; #define PG8_STAGE(bufoff, gbase, voff) do { _Pragma("unroll") for (int _i = 0; _i < 2; ++_i) \
;         __builtin_amdgcn_global_load_lds((const unsigned*)((const char*)(gbase) + (voff)[_i]), (LAS unsigned*)(lds + (bufoff) + ldsw + _i * 8192), 16, 0, 0); } while (0)
; #define PG8_LDA(dst, b, h) do { _Pragma("unroll") for (int m = 0; m < 4; ++m) _Pragma("unroll") for (int k = 0; k < 2; ++k) dst[m][k] = *(const LAS bf16x8*)(lds + PG8_SA(b, h) + aoff + m * 2048 + k * 1024); } while (0)
; #define PG8_LDB(dst, b, h) do { _Pragma("unroll") for (int n = 0; n < 2; ++n) _Pragma("unroll") for (int k = 0; k < 2; ++k) dst[n][k] = *(const LAS bf16x8*)(lds + PG8_SB(b, h) + boff + n * 2048 + k * 1024); } while (0)
; #define PG8_MMA(ai, bj, At, Bt) do { __builtin_amdgcn_s_setprio(1); _Pragma("unroll") for (int m = 0; m < 4; ++m) _Pragma("unroll") for (int n = 0; n < 2; ++n) _Pragma("unroll") for (int k = 0; k < 2; ++k) \
;         acc[ai][bj][m][n] = __builtin_amdgcn_mfma_f32_16x16x32_bf16(Bt[n][k], At[m][k], acc[ai][bj][m][n], 0, 0, 0); __builtin_amdgcn_s_setprio(0); } while (0)
; #define PG8_WAIT_V(n) asm volatile("s_waitcnt vmcnt(" #n ")" ::: "memory")
; #define PG8_WAIT_L(n) asm volatile("s_waitcnt lgkmcnt(" #n ")" ::: "memory")
; #define PG8_BAR __builtin_amdgcn_s_barrier()
; #define PG8_SCHED __builtin_amdgcn_sched_barrier(0)
; template <class Epi, class Sched>
; __device__ __forceinline__ void gemm_phase(LAS unsigned char* lds, const Gemm g, const Sched& S, const Epi& E) {
;     ...
;             PG8_LDB(B0, 0, 0); PG8_SCHED; PG8_LDA(At, 0, 0); PG8_STAGE(PG8_SA(1, 1), a1 + hstep, voffA);
;             PG8_WAIT_L(8); PG8_BAR; PG8_WAIT_L(0); PG8_MMA(0, 0, At, B0); PG8_BAR; PG8_SCHED;
;             PG8_LDB(B1, 0, 1); PG8_STAGE(PG8_SB(0, 0), b2, voffB);
;             PG8_BAR; PG8_WAIT_L(0); PG8_MMA(0, 1, At, B1); PG8_BAR;
;             PG8_LDA(At, 0, 1); PG8_STAGE(PG8_SA(0, 0), a2, voffA);
;             PG8_BAR; PG8_WAIT_L(0); PG8_MMA(1, 0, At, B0); PG8_BAR; PG8_SCHED;
;     ...
;             PG8_BAR; PG8_WAIT_L(0); PG8_MMA(1, 0, At, B0); PG8_BAR; PG8_SCHED;
;             PG8_STAGE(PG8_SB(1, 1), b3 + hstep, voffB);
;             PG8_WAIT_V(6); PG8_BAR; PG8_MMA(1, 1, At, B1); PG8_BAR;
	s_waitcnt lgkmcnt(0)
	s_setprio 1
	s_waitcnt lgkmcnt(0)
	v_mfma_f32_16x16x32_bf16 v[60:63], v[146:149], v[162:165], v[60:63]
	v_mfma_f32_16x16x32_bf16 v[56:59], v[154:157], v[162:165], v[56:59]
	v_mfma_f32_16x16x32_bf16 v[44:47], v[146:149], v[182:185], v[44:47]
	v_mfma_f32_16x16x32_bf16 v[40:43], v[154:157], v[182:185], v[40:43]
	v_mfma_f32_16x16x32_bf16 v[28:31], v[146:149], v[190:193], v[28:31]
	v_mfma_f32_16x16x32_bf16 v[24:27], v[154:157], v[190:193], v[24:27]
	v_mfma_f32_16x16x32_bf16 v[12:15], v[146:149], v[202:205], v[12:15]
	v_mfma_f32_16x16x32_bf16 v[8:11], v[154:157], v[202:205], v[8:11]
	v_mfma_f32_16x16x32_bf16 v[60:63], v[150:153], v[178:181], v[60:63]
	v_mfma_f32_16x16x32_bf16 v[56:59], v[158:161], v[178:181], v[56:59]
	v_mfma_f32_16x16x32_bf16 v[44:47], v[150:153], v[186:189], v[44:47]
	v_mfma_f32_16x16x32_bf16 v[40:43], v[158:161], v[186:189], v[40:43]
	v_mfma_f32_16x16x32_bf16 v[28:31], v[150:153], v[194:197], v[28:31]
	v_mfma_f32_16x16x32_bf16 v[24:27], v[158:161], v[194:197], v[24:27]
	v_mfma_f32_16x16x32_bf16 v[12:15], v[150:153], v[206:209], v[12:15]
	v_mfma_f32_16x16x32_bf16 v[8:11], v[158:161], v[206:209], v[8:11]
	s_setprio 0
	s_barrier
	s_add_u32 s4, s4, 0x40080
	s_addc_u32 s5, s5, 0
	s_add_i32 s6, s6, s44
	s_mov_b32 m0, s6
	s_nop 0
	global_load_lds_dwordx4 v130, s[4:5]
	s_add_i32 m0, s6, 0x2000
	s_nop 0
	global_load_lds_dwordx4 v134, s[4:5]
	s_waitcnt vmcnt(10)
	s_barrier
	s_setprio 1
	v_mfma_f32_16x16x32_bf16 v[52:55], v[210:213], v[162:165], v[52:55]
	v_mfma_f32_16x16x32_bf16 v[48:51], v[218:221], v[162:165], v[48:51]
	v_mfma_f32_16x16x32_bf16 v[36:39], v[210:213], v[182:185], v[36:39]
	v_mfma_f32_16x16x32_bf16 v[32:35], v[218:221], v[182:185], v[32:35]
	v_mfma_f32_16x16x32_bf16 v[20:23], v[210:213], v[190:193], v[20:23]
	v_mfma_f32_16x16x32_bf16 v[16:19], v[218:221], v[190:193], v[16:19]
	v_mfma_f32_16x16x32_bf16 v[4:7], v[210:213], v[202:205], v[4:7]
	v_mfma_f32_16x16x32_bf16 v[0:3], v[218:221], v[202:205], v[0:3]
	v_mfma_f32_16x16x32_bf16 v[52:55], v[214:217], v[178:181], v[52:55]
	v_mfma_f32_16x16x32_bf16 v[48:51], v[222:225], v[178:181], v[48:51]
	v_mfma_f32_16x16x32_bf16 v[36:39], v[214:217], v[186:189], v[36:39]
	v_mfma_f32_16x16x32_bf16 v[32:35], v[222:225], v[186:189], v[32:35]
	v_mfma_f32_16x16x32_bf16 v[20:23], v[214:217], v[194:197], v[20:23]
	v_mfma_f32_16x16x32_bf16 v[16:19], v[222:225], v[194:197], v[16:19]
	v_mfma_f32_16x16x32_bf16 v[4:7], v[214:217], v[206:209], v[4:7]
	v_mfma_f32_16x16x32_bf16 v[0:3], v[222:225], v[206:209], v[0:3]
	s_setprio 0
	s_add_i32 s67, s67, 2
	s_add_u32 s0, s0, 0x100
	s_addc_u32 s1, s1, 0
	s_add_u32 s65, s65, 0x100
	s_addc_u32 s66, s66, 0
	s_cmp_gt_u32 s67, 13
	s_barrier
.LBB0_613:
	ds_read_b128 v[146:149], v171
	ds_read_b128 v[150:153], v171 offset:1024
	ds_read_b128 v[154:157], v171 offset:2048
	ds_read_b128 v[158:161], v171 offset:3072
	s_add_u32 s4, s0, 0xfffc0080
	s_addc_u32 s5, s1, -1
	s_cmp_eq_u32 s67, 12
	s_cselect_b32 s7, s8, s5
	s_cselect_b32 s6, s9, s4
	s_cselect_b32 s5, s31, s66
	s_cselect_b32 s4, s35, s65
	s_add_i32 m0, s45, 0xc000
	ds_read_b128 v[162:165], v172
	ds_read_b128 v[178:181], v172 offset:1024
	ds_read_b128 v[182:185], v172 offset:2048
	ds_read_b128 v[186:189], v172 offset:3072
	ds_read_b128 v[190:193], v172 offset:4096
	ds_read_b128 v[194:197], v172 offset:5120
	ds_read_b128 v[202:205], v172 offset:6144
	ds_read_b128 v[206:209], v172 offset:7168
	global_load_lds_dwordx4 v138, s[0:1]
	s_add_i32 m0, s45, 0xe000
	s_nop 0
	global_load_lds_dwordx4 v140, s[0:1]
	s_waitcnt vmcnt(10)
	s_barrier
	s_waitcnt lgkmcnt(0)
	s_setprio 1
	s_waitcnt lgkmcnt(0)
	v_mfma_f32_16x16x32_bf16 v[124:127], v[146:149], v[162:165], v[124:127]
	v_mfma_f32_16x16x32_bf16 v[120:123], v[154:157], v[162:165], v[120:123]
	v_mfma_f32_16x16x32_bf16 v[108:111], v[146:149], v[182:185], v[108:111]
	v_mfma_f32_16x16x32_bf16 v[104:107], v[154:157], v[182:185], v[104:107]
	v_mfma_f32_16x16x32_bf16 v[92:95], v[146:149], v[190:193], v[92:95]
	v_mfma_f32_16x16x32_bf16 v[88:91], v[154:157], v[190:193], v[88:91]
	v_mfma_f32_16x16x32_bf16 v[76:79], v[146:149], v[202:205], v[76:79]
	v_mfma_f32_16x16x32_bf16 v[72:75], v[154:157], v[202:205], v[72:75]
	v_mfma_f32_16x16x32_bf16 v[124:127], v[150:153], v[178:181], v[124:127]
	v_mfma_f32_16x16x32_bf16 v[120:123], v[158:161], v[178:181], v[120:123]
	v_mfma_f32_16x16x32_bf16 v[108:111], v[150:153], v[186:189], v[108:111]
	v_mfma_f32_16x16x32_bf16 v[104:107], v[158:161], v[186:189], v[104:107]
	v_mfma_f32_16x16x32_bf16 v[92:95], v[150:153], v[194:197], v[92:95]
	v_mfma_f32_16x16x32_bf16 v[88:91], v[158:161], v[194:197], v[88:91]
	v_mfma_f32_16x16x32_bf16 v[76:79], v[150:153], v[206:209], v[76:79]
	v_mfma_f32_16x16x32_bf16 v[72:75], v[158:161], v[206:209], v[72:75]
	s_setprio 0
	s_barrier
	s_add_i32 s68, s57, s44
	s_mov_b32 m0, s68
	ds_read_b128 v[210:213], v173
	ds_read_b128 v[214:217], v173 offset:1024
	ds_read_b128 v[218:221], v173 offset:2048
	ds_read_b128 v[222:225], v173 offset:3072
	global_load_lds_dwordx4 v130, s[4:5]
	s_add_i32 m0, s68, 0x2000
	s_nop 0
	global_load_lds_dwordx4 v134, s[4:5]
	s_waitcnt vmcnt(10)
	s_barrier
; #define PG8_STAGE(bufoff, gbase, voff) do { _Pragma("unroll") for (int _i = 0; _i < 2; ++_i) \
;         __builtin_amdgcn_global_load_lds((const unsigned*)((const char*)(gbase) + (voff)[_i]), (LAS unsigned*)(lds + (bufoff) + ldsw + _i * 8192), 16, 0, 0); } while (0)
; #define PG8_LDA(dst, b, h) do { _Pragma("unroll") for (int m = 0; m < 4; ++m) _Pragma("unroll") for (int k = 0; k < 2; ++k) dst[m][k] = *(const LAS bf16x8*)(lds + PG8_SA(b, h) + aoff + m * 2048 + k * 1024); } while (0)
; #define PG8_LDB(dst, b, h) do { _Pragma("unroll") for (int n = 0; n < 2; ++n) _Pragma("unroll") for (int k = 0; k < 2; ++k) dst[n][k] = *(const LAS bf16x8*)(lds + PG8_SB(b, h) + boff + n * 2048 + k * 1024); } while (0)
; #define PG8_MMA(ai, bj, At, Bt) do { __builtin_amdgcn_s_setprio(1); _Pragma("unroll") for (int m = 0; m < 4; ++m) _Pragma("unroll") for (int n = 0; n < 2; ++n) _Pragma("unroll") for (int k = 0; k < 2; ++k) \
;         acc[ai][bj][m][n] = __builtin_amdgcn_mfma_f32_16x16x32_bf16(Bt[n][k], At[m][k], acc[ai][bj][m][n], 0, 0, 0); __builtin_amdgcn_s_setprio(0); } while (0)
; #define PG8_WAIT_V(n) asm volatile("s_waitcnt vmcnt(" #n ")" ::: "memory")
; #define PG8_WAIT_L(n) asm volatile("s_waitcnt lgkmcnt(" #n ")" ::: "memory")
; #define PG8_BAR __builtin_amdgcn_s_barrier()
; #define PG8_SCHED __builtin_amdgcn_sched_barrier(0)
; template <class Epi, class Sched>
; __device__ __forceinline__ void gemm_phase(LAS unsigned char* lds, const Gemm g, const Sched& S, const Epi& E) {
;     ...
;             PG8_BAR; PG8_WAIT_L(0); PG8_MMA(1, 0, At, B0); PG8_BAR; PG8_SCHED;
;             PG8_STAGE(PG8_SB(0, 1), b2 + hstep, voffB);
;             PG8_WAIT_V(6); PG8_BAR; PG8_MMA(1, 1, At, B1); PG8_BAR;
;             PG8_LDB(B0, 1, 0); PG8_SCHED; PG8_LDA(At, 1, 0); PG8_STAGE(PG8_SA(0, 1), a2 + hstep, voffA);
;             PG8_WAIT_L(8); PG8_BAR; PG8_WAIT_L(0); PG8_MMA(0, 0, At, B0); PG8_BAR; PG8_SCHED;
	s_waitcnt lgkmcnt(0)
	s_setprio 1
	s_waitcnt lgkmcnt(0)
	v_mfma_f32_16x16x32_bf16 v[116:119], v[210:213], v[162:165], v[116:119]
	v_mfma_f32_16x16x32_bf16 v[112:115], v[218:221], v[162:165], v[112:115]
	v_mfma_f32_16x16x32_bf16 v[100:103], v[210:213], v[182:185], v[100:103]
	v_mfma_f32_16x16x32_bf16 v[96:99], v[218:221], v[182:185], v[96:99]
	v_mfma_f32_16x16x32_bf16 v[84:87], v[210:213], v[190:193], v[84:87]
	v_mfma_f32_16x16x32_bf16 v[80:83], v[218:221], v[190:193], v[80:83]
	v_mfma_f32_16x16x32_bf16 v[68:71], v[210:213], v[202:205], v[68:71]
	v_mfma_f32_16x16x32_bf16 v[64:67], v[218:221], v[202:205], v[64:67]
	v_mfma_f32_16x16x32_bf16 v[116:119], v[214:217], v[178:181], v[116:119]
	v_mfma_f32_16x16x32_bf16 v[112:115], v[222:225], v[178:181], v[112:115]
	v_mfma_f32_16x16x32_bf16 v[100:103], v[214:217], v[186:189], v[100:103]
	v_mfma_f32_16x16x32_bf16 v[96:99], v[222:225], v[186:189], v[96:99]
	v_mfma_f32_16x16x32_bf16 v[84:87], v[214:217], v[194:197], v[84:87]
	v_mfma_f32_16x16x32_bf16 v[80:83], v[222:225], v[194:197], v[80:83]
	v_mfma_f32_16x16x32_bf16 v[68:71], v[214:217], v[206:209], v[68:71]
	v_mfma_f32_16x16x32_bf16 v[64:67], v[222:225], v[206:209], v[64:67]
	s_setprio 0
	s_mov_b32 m0, s45
	v_lshl_add_u64 v[226:227], s[6:7], 0, v[128:129]
	s_barrier
	ds_read_b128 v[162:165], v172 offset:16384
	ds_read_b128 v[178:181], v172 offset:17408
	ds_read_b128 v[182:185], v172 offset:18432
	ds_read_b128 v[186:189], v172 offset:19456
	ds_read_b128 v[190:193], v172 offset:20480
	ds_read_b128 v[194:197], v172 offset:21504
	ds_read_b128 v[202:205], v172 offset:22528
	ds_read_b128 v[206:209], v172 offset:23552
	global_load_lds_dwordx4 v128, s[6:7]
	v_lshl_add_u64 v[228:229], s[6:7], 0, v[132:133]
	s_mov_b32 m0, s46
	s_nop 0
	global_load_lds_dwordx4 v132, s[6:7]
	s_barrier
	s_waitcnt lgkmcnt(0)
	s_setprio 1
	s_waitcnt lgkmcnt(0)
	v_mfma_f32_16x16x32_bf16 v[60:63], v[146:149], v[162:165], v[60:63]
	v_mfma_f32_16x16x32_bf16 v[56:59], v[154:157], v[162:165], v[56:59]
	v_mfma_f32_16x16x32_bf16 v[44:47], v[146:149], v[182:185], v[44:47]
	v_mfma_f32_16x16x32_bf16 v[40:43], v[154:157], v[182:185], v[40:43]
	v_mfma_f32_16x16x32_bf16 v[28:31], v[146:149], v[190:193], v[28:31]
	v_mfma_f32_16x16x32_bf16 v[24:27], v[154:157], v[190:193], v[24:27]
	v_mfma_f32_16x16x32_bf16 v[12:15], v[146:149], v[202:205], v[12:15]
	v_mfma_f32_16x16x32_bf16 v[8:11], v[154:157], v[202:205], v[8:11]
	v_mfma_f32_16x16x32_bf16 v[60:63], v[150:153], v[178:181], v[60:63]
	v_mfma_f32_16x16x32_bf16 v[56:59], v[158:161], v[178:181], v[56:59]
	v_mfma_f32_16x16x32_bf16 v[44:47], v[150:153], v[186:189], v[44:47]
	v_mfma_f32_16x16x32_bf16 v[40:43], v[158:161], v[186:189], v[40:43]
	v_mfma_f32_16x16x32_bf16 v[28:31], v[150:153], v[194:197], v[28:31]
	v_mfma_f32_16x16x32_bf16 v[24:27], v[158:161], v[194:197], v[24:27]
	v_mfma_f32_16x16x32_bf16 v[12:15], v[150:153], v[206:209], v[12:15]
	v_mfma_f32_16x16x32_bf16 v[8:11], v[158:161], v[206:209], v[8:11]
	s_setprio 0
	s_barrier
	s_add_u32 s68, s4, 0x40000
	s_addc_u32 s69, s5, 0
	s_add_i32 s70, s58, s44
	s_mov_b32 m0, s70
	s_nop 0
	global_load_lds_dwordx4 v130, s[68:69]
	s_add_i32 m0, s70, 0x2000
	s_nop 0
	global_load_lds_dwordx4 v134, s[68:69]
	s_add_u32 s6, s6, 0x40000
	s_addc_u32 s7, s7, 0
	s_mov_b32 m0, s47
	s_nop 0
	global_load_lds_dwordx4 v128, s[6:7]
	s_mov_b32 m0, s48
	s_nop 0
	global_load_lds_dwordx4 v132, s[6:7]
	s_waitcnt vmcnt(12)
	s_barrier
	s_setprio 1
	v_mfma_f32_16x16x32_bf16 v[52:55], v[210:213], v[162:165], v[52:55]
	v_mfma_f32_16x16x32_bf16 v[48:51], v[218:221], v[162:165], v[48:51]
	v_mfma_f32_16x16x32_bf16 v[36:39], v[210:213], v[182:185], v[36:39]
	v_mfma_f32_16x16x32_bf16 v[32:35], v[218:221], v[182:185], v[32:35]
	v_mfma_f32_16x16x32_bf16 v[20:23], v[210:213], v[190:193], v[20:23]
	v_mfma_f32_16x16x32_bf16 v[16:19], v[218:221], v[190:193], v[16:19]
	v_mfma_f32_16x16x32_bf16 v[4:7], v[210:213], v[202:205], v[4:7]
	v_mfma_f32_16x16x32_bf16 v[0:3], v[218:221], v[202:205], v[0:3]
	v_mfma_f32_16x16x32_bf16 v[52:55], v[214:217], v[178:181], v[52:55]
	v_mfma_f32_16x16x32_bf16 v[48:51], v[222:225], v[178:181], v[48:51]
	v_mfma_f32_16x16x32_bf16 v[36:39], v[214:217], v[186:189], v[36:39]
	v_mfma_f32_16x16x32_bf16 v[32:35], v[222:225], v[186:189], v[32:35]
	v_mfma_f32_16x16x32_bf16 v[20:23], v[214:217], v[194:197], v[20:23]
	v_mfma_f32_16x16x32_bf16 v[16:19], v[222:225], v[194:197], v[16:19]
	v_mfma_f32_16x16x32_bf16 v[4:7], v[214:217], v[206:209], v[4:7]
	v_mfma_f32_16x16x32_bf16 v[0:3], v[222:225], v[206:209], v[0:3]
	s_setprio 0
	s_add_i32 s68, 0, 0x18000
	v_add_u32_e32 v136, s68, v170
	s_barrier
	ds_read_b128 v[146:149], v136
	ds_read_b128 v[150:153], v136 offset:1024
	ds_read_b128 v[154:157], v136 offset:2048
	ds_read_b128 v[158:161], v136 offset:3072
	ds_read_b128 v[162:165], v172 offset:32768
	ds_read_b128 v[178:181], v172 offset:33792
	ds_read_b128 v[182:185], v172 offset:34816
	ds_read_b128 v[186:189], v172 offset:35840
	ds_read_b128 v[190:193], v172 offset:36864
	ds_read_b128 v[194:197], v172 offset:37888
	ds_read_b128 v[202:205], v172 offset:38912
	ds_read_b128 v[206:209], v172 offset:39936
	s_waitcnt vmcnt(10)
	s_barrier
; #define PG8_STAGE(bufoff, gbase, voff) do { _Pragma("unroll") for (int _i = 0; _i < 2; ++_i) \
;         __builtin_amdgcn_global_load_lds((const unsigned*)((const char*)(gbase) + (voff)[_i]), (LAS unsigned*)(lds + (bufoff) + ldsw + _i * 8192), 16, 0, 0); } while (0)
; #define PG8_LDA(dst, b, h) do { _Pragma("unroll") for (int m = 0; m < 4; ++m) _Pragma("unroll") for (int k = 0; k < 2; ++k) dst[m][k] = *(const LAS bf16x8*)(lds + PG8_SA(b, h) + aoff + m * 2048 + k * 1024); } while (0)
; #define PG8_LDB(dst, b, h) do { _Pragma("unroll") for (int n = 0; n < 2; ++n) _Pragma("unroll") for (int k = 0; k < 2; ++k) dst[n][k] = *(const LAS bf16x8*)(lds + PG8_SB(b, h) + boff + n * 2048 + k * 1024); } while (0)
; #define PG8_MMA(ai, bj, At, Bt) do { __builtin_amdgcn_s_setprio(1); _Pragma("unroll") for (int m = 0; m < 4; ++m) _Pragma("unroll") for (int n = 0; n < 2; ++n) _Pragma("unroll") for (int k = 0; k < 2; ++k) \
;         acc[ai][bj][m][n] = __builtin_amdgcn_mfma_f32_16x16x32_bf16(Bt[n][k], At[m][k], acc[ai][bj][m][n], 0, 0, 0); __builtin_amdgcn_s_setprio(0); } while (0)
; #define PG8_WAIT_V(n) asm volatile("s_waitcnt vmcnt(" #n ")" ::: "memory")
; #define PG8_WAIT_L(n) asm volatile("s_waitcnt lgkmcnt(" #n ")" ::: "memory")
; #define PG8_BAR __builtin_amdgcn_s_barrier()
; #define PG8_SCHED __builtin_amdgcn_sched_barrier(0)
; template <class Epi, class Sched>
; __device__ __forceinline__ void gemm_phase(LAS unsigned char* lds, const Gemm g, const Sched& S, const Epi& E) {
;     ...
;             PG8_WAIT_L(8); PG8_BAR; PG8_WAIT_L(0); PG8_MMA(0, 0, At, B0); PG8_BAR; PG8_SCHED;
;             PG8_LDB(B1, 1, 1); PG8_STAGE(PG8_SB(1, 0), b3, voffB);
;             PG8_BAR; PG8_WAIT_L(0); PG8_MMA(0, 1, At, B1); PG8_BAR;
;             PG8_LDA(At, 1, 1); PG8_STAGE(PG8_SA(1, 0), a3, voffA);
;             PG8_BAR; PG8_WAIT_L(0); PG8_MMA(1, 0, At, B0); PG8_BAR; PG8_SCHED;
;             PG8_STAGE(PG8_SB(1, 1), b3 + hstep, voffB);
;             PG8_WAIT_V(6); PG8_BAR; PG8_MMA(1, 1, At, B1); PG8_BAR;
	s_waitcnt lgkmcnt(0)
	s_setprio 1
	s_waitcnt lgkmcnt(0)
	v_mfma_f32_16x16x32_bf16 v[124:127], v[146:149], v[162:165], v[124:127]
	v_mfma_f32_16x16x32_bf16 v[120:123], v[154:157], v[162:165], v[120:123]
	v_mfma_f32_16x16x32_bf16 v[108:111], v[146:149], v[182:185], v[108:111]
	v_mfma_f32_16x16x32_bf16 v[104:107], v[154:157], v[182:185], v[104:107]
	v_mfma_f32_16x16x32_bf16 v[92:95], v[146:149], v[190:193], v[92:95]
	v_mfma_f32_16x16x32_bf16 v[88:91], v[154:157], v[190:193], v[88:91]
	v_mfma_f32_16x16x32_bf16 v[76:79], v[146:149], v[202:205], v[76:79]
	v_mfma_f32_16x16x32_bf16 v[72:75], v[154:157], v[202:205], v[72:75]
	v_mfma_f32_16x16x32_bf16 v[124:127], v[150:153], v[178:181], v[124:127]
	v_mfma_f32_16x16x32_bf16 v[120:123], v[158:161], v[178:181], v[120:123]
	v_mfma_f32_16x16x32_bf16 v[108:111], v[150:153], v[186:189], v[108:111]
	v_mfma_f32_16x16x32_bf16 v[104:107], v[158:161], v[186:189], v[104:107]
	v_mfma_f32_16x16x32_bf16 v[92:95], v[150:153], v[194:197], v[92:95]
	v_mfma_f32_16x16x32_bf16 v[88:91], v[158:161], v[194:197], v[88:91]
	v_mfma_f32_16x16x32_bf16 v[76:79], v[150:153], v[206:209], v[76:79]
	v_mfma_f32_16x16x32_bf16 v[72:75], v[158:161], v[206:209], v[72:75]
	s_setprio 0
	s_barrier
	s_add_i32 s6, 0, 0x1c000
	s_add_i32 s7, s68, s44
	v_add_u32_e32 v136, s6, v170
	s_add_u32 s20, s4, 0x80
	s_addc_u32 s21, s5, 0
	s_mov_b32 m0, s7
	ds_read_b128 v[210:213], v136
	ds_read_b128 v[214:217], v136 offset:1024
	ds_read_b128 v[218:221], v136 offset:2048
	ds_read_b128 v[222:225], v136 offset:3072
	global_load_lds_dwordx4 v130, s[20:21]
	s_add_i32 m0, s7, 0x2000
	s_nop 0
	global_load_lds_dwordx4 v134, s[20:21]
	s_waitcnt vmcnt(10)
	s_barrier
	s_waitcnt lgkmcnt(0)
	s_setprio 1
	s_waitcnt lgkmcnt(0)
	v_mfma_f32_16x16x32_bf16 v[116:119], v[210:213], v[162:165], v[116:119]
	v_mfma_f32_16x16x32_bf16 v[112:115], v[218:221], v[162:165], v[112:115]
	v_mfma_f32_16x16x32_bf16 v[100:103], v[210:213], v[182:185], v[100:103]
	v_mfma_f32_16x16x32_bf16 v[96:99], v[218:221], v[182:185], v[96:99]
	v_mfma_f32_16x16x32_bf16 v[84:87], v[210:213], v[190:193], v[84:87]
	v_mfma_f32_16x16x32_bf16 v[80:83], v[218:221], v[190:193], v[80:83]
	v_mfma_f32_16x16x32_bf16 v[68:71], v[210:213], v[202:205], v[68:71]
	v_mfma_f32_16x16x32_bf16 v[64:67], v[218:221], v[202:205], v[64:67]
	v_mfma_f32_16x16x32_bf16 v[116:119], v[214:217], v[178:181], v[116:119]
	v_mfma_f32_16x16x32_bf16 v[112:115], v[222:225], v[178:181], v[112:115]
	v_mfma_f32_16x16x32_bf16 v[100:103], v[214:217], v[186:189], v[100:103]
	v_mfma_f32_16x16x32_bf16 v[96:99], v[222:225], v[186:189], v[96:99]
	v_mfma_f32_16x16x32_bf16 v[84:87], v[214:217], v[194:197], v[84:87]
	v_mfma_f32_16x16x32_bf16 v[80:83], v[222:225], v[194:197], v[80:83]
	v_mfma_f32_16x16x32_bf16 v[68:71], v[214:217], v[206:209], v[68:71]
	v_mfma_f32_16x16x32_bf16 v[64:67], v[222:225], v[206:209], v[64:67]
	s_setprio 0
	s_mov_b32 m0, s54
	s_mov_b64 s[20:21], 0x80
	v_lshl_add_u64 v[166:167], v[226:227], 0, s[20:21]
	s_barrier
	ds_read_b128 v[162:165], v172 offset:49152
	ds_read_b128 v[178:181], v172 offset:50176
	ds_read_b128 v[182:185], v172 offset:51200
	ds_read_b128 v[186:189], v172 offset:52224
	ds_read_b128 v[190:193], v172 offset:53248
	ds_read_b128 v[194:197], v172 offset:54272
	ds_read_b128 v[202:205], v172 offset:55296
	ds_read_b128 v[206:209], v172 offset:56320
	global_load_lds_dwordx4 v[166:167], off
	v_lshl_add_u64 v[166:167], v[228:229], 0, s[20:21]
	s_mov_b32 m0, s55
	s_nop 0
	global_load_lds_dwordx4 v[166:167], off
	s_barrier
	s_waitcnt lgkmcnt(0)
	s_setprio 1
	s_waitcnt lgkmcnt(0)
	v_mfma_f32_16x16x32_bf16 v[60:63], v[146:149], v[162:165], v[60:63]
	v_mfma_f32_16x16x32_bf16 v[56:59], v[154:157], v[162:165], v[56:59]
	v_mfma_f32_16x16x32_bf16 v[44:47], v[146:149], v[182:185], v[44:47]
	v_mfma_f32_16x16x32_bf16 v[40:43], v[154:157], v[182:185], v[40:43]
	v_mfma_f32_16x16x32_bf16 v[28:31], v[146:149], v[190:193], v[28:31]
	v_mfma_f32_16x16x32_bf16 v[24:27], v[154:157], v[190:193], v[24:27]
	v_mfma_f32_16x16x32_bf16 v[12:15], v[146:149], v[202:205], v[12:15]
	v_mfma_f32_16x16x32_bf16 v[8:11], v[154:157], v[202:205], v[8:11]
	v_mfma_f32_16x16x32_bf16 v[60:63], v[150:153], v[178:181], v[60:63]
	v_mfma_f32_16x16x32_bf16 v[56:59], v[158:161], v[178:181], v[56:59]
	v_mfma_f32_16x16x32_bf16 v[44:47], v[150:153], v[186:189], v[44:47]
	v_mfma_f32_16x16x32_bf16 v[40:43], v[158:161], v[186:189], v[40:43]
	v_mfma_f32_16x16x32_bf16 v[28:31], v[150:153], v[194:197], v[28:31]
	v_mfma_f32_16x16x32_bf16 v[24:27], v[158:161], v[194:197], v[24:27]
	v_mfma_f32_16x16x32_bf16 v[12:15], v[150:153], v[206:209], v[12:15]
	v_mfma_f32_16x16x32_bf16 v[8:11], v[158:161], v[206:209], v[8:11]
	s_setprio 0
	s_barrier
	s_add_u32 s4, s4, 0x40080
	s_addc_u32 s5, s5, 0
	s_add_i32 s6, s6, s44
	s_mov_b32 m0, s6
	s_nop 0
	global_load_lds_dwordx4 v130, s[4:5]
	s_add_i32 m0, s6, 0x2000
	s_nop 0
	global_load_lds_dwordx4 v134, s[4:5]
	s_waitcnt vmcnt(10)
	s_barrier
	s_setprio 1
	v_mfma_f32_16x16x32_bf16 v[52:55], v[210:213], v[162:165], v[52:55]
	v_mfma_f32_16x16x32_bf16 v[48:51], v[218:221], v[162:165], v[48:51]
	v_mfma_f32_16x16x32_bf16 v[36:39], v[210:213], v[182:185], v[36:39]
	v_mfma_f32_16x16x32_bf16 v[32:35], v[218:221], v[182:185], v[32:35]
	v_mfma_f32_16x16x32_bf16 v[20:23], v[210:213], v[190:193], v[20:23]
	v_mfma_f32_16x16x32_bf16 v[16:19], v[218:221], v[190:193], v[16:19]
	v_mfma_f32_16x16x32_bf16 v[4:7], v[210:213], v[202:205], v[4:7]
	v_mfma_f32_16x16x32_bf16 v[0:3], v[218:221], v[202:205], v[0:3]
	v_mfma_f32_16x16x32_bf16 v[52:55], v[214:217], v[178:181], v[52:55]
	v_mfma_f32_16x16x32_bf16 v[48:51], v[222:225], v[178:181], v[48:51]
	v_mfma_f32_16x16x32_bf16 v[36:39], v[214:217], v[186:189], v[36:39]
	v_mfma_f32_16x16x32_bf16 v[32:35], v[222:225], v[186:189], v[32:35]
	v_mfma_f32_16x16x32_bf16 v[20:23], v[214:217], v[194:197], v[20:23]
	v_mfma_f32_16x16x32_bf16 v[16:19], v[222:225], v[194:197], v[16:19]
	v_mfma_f32_16x16x32_bf16 v[4:7], v[214:217], v[206:209], v[4:7]
	v_mfma_f32_16x16x32_bf16 v[0:3], v[222:225], v[206:209], v[0:3]
	s_setprio 0
	s_add_i32 s67, s67, 2
	s_add_u32 s0, s0, 0x100
	s_addc_u32 s1, s1, 0
	s_add_u32 s65, s65, 0x100
	s_addc_u32 s66, s66, 0
	s_cmp_gt_u32 s67, 13
	s_barrier
;     __device__ __forceinline__ void operator()(const AccT& acc, const Unit& u, int wr, int wc, int fr, int fq) const {
;     ...
;         const int rbase = wr * 64 + fr;
;         const int tb = u.pn * 256 + wc * 32 + 8 * fq;
;         const int o0 = wc * 32 + 8 * fq;
;         const int j = fr & 3; const float sgn = ((fr >> 2) & 1) ? 1.0f : -1.0f;
; #pragma unroll
;         for (int ai = 0; ai < 2; ++ai) {
;             const int hh = 2 * ai + wr;
;             const float l2f = lgd[hh] * 1.4426950408889634f, l2b = lgd[4 + hh] * 1.4426950408889634f;
;             const float zf0 = exp2f((float)(127 - o0) * l2f), zfs = exp2f(-l2f), zb0 = exp2f((float)o0 * l2b), zbs = exp2f(l2b);
; #pragma unroll
;             for (int m = 0; m < 4; ++m) {
;                 const int r = rbase + ai * 128 + m * 16;
;                 const int d = 4 * (2 * m + (fr >> 3)) + j;
; #pragma unroll
;                 for (int bj = 0; bj < 2; ++bj) {
;                     const int t0 = tb + bj * 128;
;                     float v[8];
; #pragma unroll
;                     for (int jj = 0; jj < 4; ++jj) { v[jj] = acc[ai][bj][m][0][jj]; v[4 + jj] = acc[ai][bj][m][1][jj]; }
;                     if constexpr (ROPE) {
;                         const int t = t0 & 2047;
; #pragma unroll
;                         for (int hf = 0; hf < 2; ++hf) {
;                             f32x4 cs, sn;
;                             if (m < 2) { const float c1 = ropeA[(t >> 6) * 16 + d], s1 = ropeA[1024 + (t >> 6) * 16 + d]; cs = (f32x4){c1, c1, c1, c1}; sn = (f32x4){s1, s1, s1, s1}; }
;                             else { const float* cb = ropeA + 2048 + (d - 16) * 64 + (t & 63) + 4 * hf; cs = *(const f32x4*)(cb); sn = *(const f32x4*)(cb + 1024); }
; #pragma unroll
;                             for (int jj = 0; jj < 4; ++jj) { const float pr = __shfl_xor(v[4 * hf + jj], 4); v[4 * hf + jj] = v[4 * hf + jj] * cs[jj] + sgn * pr * sn[jj]; }
;                             __builtin_amdgcn_sched_barrier(0);
;                         }
;                     }
;                     float zf[8], zb[8]; zf[0] = zf0; zb[0] = zb0;
; #pragma unroll
;                     for (int jj = 1; jj < 8; ++jj) { zf[jj] = zf[jj - 1] * zfs; zb[jj] = zb[jj - 1] * zbs; }
;                     u32x4 wf, wb;
	s_cbranch_scc0 .LBB0_613
	v_mov_b32_e32 v136, v169
	v_mov_b32_e32 v150, v168
	s_lshl_b32 s0, s33, 8
	global_load_dword v154, v137, s[22:23]
	global_load_dword v155, v137, s[22:23] offset:16
	s_or_b32 s0, s0, s53
	v_lshlrev_b32_e32 v151, 3, v136
	v_ashrrev_i32_e32 v136, 1, v150
	v_add_u32_e32 v162, s0, v151
	v_bfi_b32 v136, -4, v136, v150
	v_lshrrev_b32_e32 v146, 2, v162
	v_add_u32_e32 v192, 0x400, v136
	v_and_b32_e32 v187, 0x1f0, v146
	v_add_u32_e32 v146, v192, v187
	v_add_u32_e32 v148, v187, v136
	v_ashrrev_i32_e32 v147, 31, v146
	v_ashrrev_i32_e32 v149, 31, v148
	v_lshl_add_u64 v[146:147], v[146:147], 2, s[16:17]
	v_lshl_add_u64 v[148:149], v[148:149], 2, s[16:17]
	global_load_dword v153, v[146:147], off
	global_load_dword v166, v[148:149], off
	v_and_b32_e32 v157, 64, v174
	v_xor_b32_e32 v156, 4, v174
	v_add_u32_e32 v157, 64, v157
	v_cmp_lt_i32_e32 vcc, v156, v157
	v_mov_b32_e32 v152, v124
	v_add_u32_e32 v151, s53, v151
	v_cndmask_b32_e32 v156, v174, v156, vcc
	v_lshlrev_b32_e32 v177, 2, v156
	ds_bpermute_b32 v124, v177, v124
	v_sub_u32_e32 v156, 0x7f, v151
	v_add_u32_e32 v164, s52, v150
	v_and_b32_e32 v150, 4, v150
	v_cvt_f32_i32_e32 v179, v156
	v_cvt_f32_i32_e32 v178, v151
	v_cmp_eq_u32_e32 vcc, 0, v150
	ds_bpermute_b32 v157, v177, v125
	ds_bpermute_b32 v158, v177, v127
	s_waitcnt lgkmcnt(0)
	v_cndmask_b32_e64 v167, v124, -v124, vcc
	ds_bpermute_b32 v151, v177, v126
	v_ashrrev_i32_e32 v165, 31, v164
	v_and_b32_e32 v186, 56, v162
	s_waitcnt lgkmcnt(0)
	v_cndmask_b32_e64 v151, v151, -v151, vcc
	s_waitcnt vmcnt(0)
	v_mul_f32_e32 v124, 0x3fb8aa3b, v154
	v_mul_f32_e32 v150, 0x3fb8aa3b, v155
	v_cmp_lt_f32_e64 s[4:5], s60, v124
	v_mul_f32_e32 v156, v124, v179
	v_cmp_gt_f32_e64 s[6:7], s59, v150
	v_cndmask_b32_e64 v159, 0, v176, s[4:5]
	v_mul_f32_e32 v160, v150, v178
	v_cndmask_b32_e64 v161, 0, v176, s[6:7]
	v_cmp_gt_f32_e64 s[8:9], s59, v156
	v_fmac_f32_e32 v159, 0xbfb8aa3b, v154
	s_and_b64 s[0:1], s[4:5], exec
	v_cmp_gt_f32_e64 s[4:5], s59, v160
	v_fmac_f32_e32 v161, 0x3fb8aa3b, v155
	v_cndmask_b32_e64 v154, 0, v176, s[8:9]
	v_exp_f32_e32 v155, v159
	v_cndmask_b32_e64 v159, 0, v176, s[4:5]
	v_fmac_f32_e32 v154, v124, v179
	v_fmac_f32_e32 v159, v150, v178
	v_exp_f32_e32 v150, v154
	v_cndmask_b32_e64 v156, 0, v175, s[8:9]
	s_cselect_b32 s8, 0xffffffc0, 0
	v_exp_f32_e32 v161, v161
	v_exp_f32_e32 v159, v159
	v_ldexp_f32 v163, v155, s8
	v_pk_mul_f32 v[154:155], v[152:153], v[166:167]
	v_cndmask_b32_e64 v167, v157, -v157, vcc
	v_mov_b32_e32 v152, v125
	s_and_b64 s[0:1], s[6:7], exec
	v_add_f32_e32 v190, v154, v155
	v_pk_mul_f32 v[154:155], v[152:153], v[166:167]
	v_cndmask_b32_e64 v167, v158, -v158, vcc
	v_mov_b32_e32 v152, v127
	v_cndmask_b32_e64 v160, 0, v175, s[4:5]
	s_cselect_b32 s0, 0xffffffc0, 0
	v_ldexp_f32 v180, v150, v156
	v_add_f32_e32 v191, v154, v155
	v_pk_mul_f32 v[154:155], v[152:153], v[166:167]
	v_ldexp_f32 v124, v161, s0
	v_mul_f32_e32 v161, v126, v166
	v_ldexp_f32 v150, v159, v160
	v_mul_f32_e32 v181, v163, v180
	v_add_f32_e32 v193, v154, v155
	global_load_dword v188, v[148:149], off
	global_load_dword v157, v[146:147], off
	ds_bpermute_b32 v127, v177, v121
	v_mov_b32_e32 v156, v121
	ds_bpermute_b32 v121, v177, v123
	ds_bpermute_b32 v125, v177, v120
	ds_bpermute_b32 v152, v177, v122
	s_waitcnt lgkmcnt(3)
	v_cndmask_b32_e64 v189, v127, -v127, vcc
	s_waitcnt lgkmcnt(1)
	v_cndmask_b32_e64 v158, v125, -v125, vcc
	s_waitcnt lgkmcnt(0)
	v_cndmask_b32_e64 v127, v152, -v152, vcc
	s_waitcnt vmcnt(1)
	v_mul_f32_e32 v159, v120, v188
	s_waitcnt vmcnt(0)
	v_pk_mul_f32 v[154:155], v[156:157], v[188:189]
	v_cndmask_b32_e64 v189, v121, -v121, vcc
	v_mov_b32_e32 v156, v123
	v_add_f32_e32 v121, v154, v155
	v_pk_mul_f32 v[154:155], v[156:157], v[188:189]
	s_nop 0
	v_add_f32_e32 v123, v154, v155
	v_mov_b32_e32 v125, v153
	v_pk_mul_f32 v[152:153], v[124:125], v[150:151]
	v_mov_b32_e32 v125, v161
	v_pk_mul_f32 v[154:155], v[124:125], v[152:153]
	v_mov_b32_e32 v125, v157
	v_mov_b32_e32 v155, v158
	v_pk_mul_f32 v[156:157], v[124:125], v[154:155]
	v_mov_b32_e32 v158, v124
	v_pk_mul_f32 v[158:159], v[158:159], v[156:157]
	v_mul_f32_e32 v167, v163, v181
	v_mov_b32_e32 v159, v127
	v_mul_f32_e32 v183, v163, v167
	v_pk_mul_f32 v[160:161], v[124:125], v[158:159]
	v_mul_f32_e32 v182, v163, v183
	v_mul_f32_e32 v151, v124, v160
	v_mul_f32_e32 v185, v163, v182
	v_mul_f32_e32 v155, v124, v151
	v_mul_f32_e32 v124, v180, v190
	v_mul_f32_e32 v125, v181, v191
	v_fma_f32 v153, v126, v166, v153
	v_mul_f32_e32 v184, v163, v185
	v_cvt_pk_bf16_f32 v124, v124, v125
	v_mul_f32_e32 v125, v167, v153
	v_mul_f32_e32 v126, v183, v193
	v_fma_f32 v120, v120, v188, v157
	v_mul_f32_e32 v159, v163, v184
	v_cvt_pk_bf16_f32 v125, v125, v126
	v_mul_f32_e32 v126, v182, v120
	v_mul_f32_e32 v127, v185, v121
	v_fma_f32 v122, v122, v188, v161
	v_cvt_pk_bf16_f32 v126, v126, v127
	v_mul_f32_e32 v127, v184, v122
	v_mul_f32_e32 v157, v159, v123
	v_cvt_pk_bf16_f32 v127, v127, v157
	v_mul_f32_e32 v157, v150, v190
	v_mul_f32_e32 v120, v158, v120
	v_mul_f32_e32 v121, v160, v121
	v_mul_f32_e32 v161, v152, v191
	v_cvt_pk_bf16_f32 v188, v157, v161
	v_mul_f32_e32 v153, v154, v153
	v_mul_f32_e32 v157, v156, v193
	v_cvt_pk_bf16_f32 v189, v153, v157
	v_cvt_pk_bf16_f32 v190, v120, v121
	v_mul_f32_e32 v120, v151, v122
	v_mul_f32_e32 v121, v155, v123
	v_cvt_pk_bf16_f32 v191, v120, v121
	v_lshlrev_b64 v[120:121], 17, v[164:165]
	v_lshl_add_u64 v[120:121], s[80:81], 0, v[120:121]
	v_ashrrev_i32_e32 v163, 31, v162
	v_lshl_add_u64 v[120:121], v[162:163], 1, v[120:121]
	s_mov_b64 s[0:1], 0x2000000
	global_store_dwordx4 v[120:121], v[124:127], off
	s_nop 1
	v_lshl_add_u64 v[126:127], v[120:121], 0, s[0:1]
	s_brev_b32 s0, 64
	v_add_co_u32_e64 v122, s[4:5], s0, v120
	s_nop 1
	v_addc_co_u32_e64 v123, s[4:5], 0, v121, s[4:5]
	global_store_dwordx4 v[122:123], v[188:191], off
	v_add_u32_e32 v122, 0x80, v162
	v_lshrrev_b32_e32 v122, 2, v122
	v_and_b32_e32 v153, 0x1f0, v122
	v_add_u32_e32 v122, v153, v192
	v_add_u32_e32 v124, v153, v136
	v_ashrrev_i32_e32 v123, 31, v122
	v_ashrrev_i32_e32 v125, 31, v124
	v_lshl_add_u64 v[122:123], v[122:123], 2, s[16:17]
	v_lshl_add_u64 v[124:125], v[124:125], 2, s[16:17]
	global_load_dword v163, v[122:123], off
	global_load_dword v164, v[124:125], off
	ds_bpermute_b32 v157, v177, v116
	v_mov_b32_e32 v162, v116
	ds_bpermute_b32 v116, v177, v117
	ds_bpermute_b32 v161, v177, v118
	ds_bpermute_b32 v166, v177, v119
	s_waitcnt lgkmcnt(3)
; __device__ __forceinline__ unsigned cvt_pk_bf16(float lo, float hi) { unsigned r; asm volatile("v_cvt_pk_bf16_f32 %0, %1, %2" : "=v"(r) : "v"(lo), "v"(hi)); return r; }
;     __device__ __forceinline__ void operator()(const AccT& acc, const Unit& u, int wr, int wc, int fr, int fq) const {
;     ...
;                 const int r = rbase + ai * 128 + m * 16;
;                 const int d = 4 * (2 * m + (fr >> 3)) + j;
; #pragma unroll
;                 for (int bj = 0; bj < 2; ++bj) {
;                     const int t0 = tb + bj * 128;
;                     float v[8];
; #pragma unroll
;                     for (int jj = 0; jj < 4; ++jj) { v[jj] = acc[ai][bj][m][0][jj]; v[4 + jj] = acc[ai][bj][m][1][jj]; }
;                     if constexpr (ROPE) {
;                         const int t = t0 & 2047;
; #pragma unroll
;                         for (int hf = 0; hf < 2; ++hf) {
;                             f32x4 cs, sn;
;                             if (m < 2) { const float c1 = ropeA[(t >> 6) * 16 + d], s1 = ropeA[1024 + (t >> 6) * 16 + d]; cs = (f32x4){c1, c1, c1, c1}; sn = (f32x4){s1, s1, s1, s1}; }
;                             else { const float* cb = ropeA + 2048 + (d - 16) * 64 + (t & 63) + 4 * hf; cs = *(const f32x4*)(cb); sn = *(const f32x4*)(cb + 1024); }
; #pragma unroll
;                             for (int jj = 0; jj < 4; ++jj) { const float pr = __shfl_xor(v[4 * hf + jj], 4); v[4 * hf + jj] = v[4 * hf + jj] * cs[jj] + sgn * pr * sn[jj]; }
;                             __builtin_amdgcn_sched_barrier(0);
;                         }
;                     }
;                     float zf[8], zb[8]; zf[0] = zf0; zb[0] = zb0;
; #pragma unroll
;                     for (int jj = 1; jj < 8; ++jj) { zf[jj] = zf[jj - 1] * zfs; zb[jj] = zb[jj - 1] * zbs; }
;                     u32x4 wf, wb;
;                     wf.x = cvt_pk_bf16(v[0] * zf[0], v[1] * zf[1]); wf.y = cvt_pk_bf16(v[2] * zf[2], v[3] * zf[3]); wf.z = cvt_pk_bf16(v[4] * zf[4], v[5] * zf[5]); wf.w = cvt_pk_bf16(v[6] * zf[6], v[7] * zf[7]);
;                     wb.x = cvt_pk_bf16(v[0] * zb[0], v[1] * zb[1]); wb.y = cvt_pk_bf16(v[2] * zb[2], v[3] * zb[3]); wb.z = cvt_pk_bf16(v[4] * zb[4], v[5] * zb[5]); wb.w = cvt_pk_bf16(v[6] * zb[6], v[7] * zb[7]);
;                     *(u32x4*)(KTZ + (size_t)r * NT + t0) = wf;
;                     *(u32x4*)(KTZ + (size_t)(256 + r) * NT + t0) = wb;
	v_cndmask_b32_e64 v165, v157, -v157, vcc
	s_waitcnt vmcnt(0)
	v_pk_mul_f32 v[188:189], v[162:163], v[164:165]
	s_waitcnt lgkmcnt(2)
	v_cndmask_b32_e64 v165, v116, -v116, vcc
	v_mov_b32_e32 v162, v117
	v_pk_mul_f32 v[116:117], v[162:163], v[164:165]
	s_waitcnt lgkmcnt(1)
	v_cndmask_b32_e64 v165, v161, -v161, vcc
	v_mov_b32_e32 v162, v118
	v_add_f32_e32 v161, v116, v117
	v_pk_mul_f32 v[116:117], v[162:163], v[164:165]
	s_waitcnt lgkmcnt(0)
	v_cndmask_b32_e64 v165, v166, -v166, vcc
	v_mov_b32_e32 v162, v119
	v_add_f32_e32 v166, v116, v117
	v_pk_mul_f32 v[116:117], v[162:163], v[164:165]
	v_add_f32_e32 v157, v188, v189
	v_add_f32_e32 v164, v116, v117
	global_load_dword v117, v[122:123], off
	global_load_dword v118, v[124:125], off
	ds_bpermute_b32 v119, v177, v112
	v_mov_b32_e32 v116, v112
	ds_bpermute_b32 v112, v177, v113
	ds_bpermute_b32 v165, v177, v114
	ds_bpermute_b32 v188, v177, v115
	s_waitcnt lgkmcnt(3)
	v_cndmask_b32_e64 v119, v119, -v119, vcc
	s_waitcnt vmcnt(0)
	v_pk_mul_f32 v[162:163], v[116:117], v[118:119]
	s_waitcnt lgkmcnt(2)
	v_cndmask_b32_e64 v119, v112, -v112, vcc
	v_mov_b32_e32 v116, v113
	v_pk_mul_f32 v[112:113], v[116:117], v[118:119]
	s_waitcnt lgkmcnt(1)
	v_cndmask_b32_e64 v119, v165, -v165, vcc
	v_mov_b32_e32 v116, v114
	v_add_f32_e32 v162, v162, v163
	v_add_f32_e32 v163, v112, v113
	v_pk_mul_f32 v[112:113], v[116:117], v[118:119]
	s_waitcnt lgkmcnt(0)
	v_cndmask_b32_e64 v119, v188, -v188, vcc
	v_mov_b32_e32 v116, v115
	v_add_f32_e32 v165, v112, v113
	v_pk_mul_f32 v[112:113], v[116:117], v[118:119]
	s_nop 0
	v_add_f32_e32 v119, v112, v113
	v_mul_f32_e32 v112, v180, v157
	v_mul_f32_e32 v113, v181, v161
	v_cvt_pk_bf16_f32 v112, v112, v113
	v_mul_f32_e32 v113, v167, v166
	v_mul_f32_e32 v114, v183, v164
	v_cvt_pk_bf16_f32 v113, v113, v114
	v_mul_f32_e32 v114, v182, v162
	v_mul_f32_e32 v115, v185, v163
	v_cvt_pk_bf16_f32 v114, v114, v115
	v_mul_f32_e32 v115, v184, v165
	v_mul_f32_e32 v116, v159, v119
	v_cvt_pk_bf16_f32 v115, v115, v116
	v_mul_f32_e32 v116, v150, v157
	v_mul_f32_e32 v117, v152, v161
	v_cvt_pk_bf16_f32 v116, v116, v117
	v_mul_f32_e32 v117, v154, v166
	v_mul_f32_e32 v118, v156, v164
	v_cvt_pk_bf16_f32 v117, v117, v118
	v_mul_f32_e32 v118, v158, v162
	v_mul_f32_e32 v157, v160, v163
	v_mul_f32_e32 v119, v155, v119
	v_cvt_pk_bf16_f32 v118, v118, v157
	v_mul_f32_e32 v157, v151, v165
	v_cvt_pk_bf16_f32 v119, v157, v119
	global_store_dwordx4 v[120:121], v[112:115], off offset:256
	global_store_dwordx4 v[126:127], v[116:119], off offset:256
	v_add_u32_e32 v161, 0x408, v136
	v_add_u32_e32 v157, 8, v136
	v_add_u32_e32 v112, v161, v187
	v_add_u32_e32 v114, v187, v157
	v_ashrrev_i32_e32 v113, 31, v112
	v_ashrrev_i32_e32 v115, 31, v114
	v_lshl_add_u64 v[112:113], v[112:113], 2, s[16:17]
	v_lshl_add_u64 v[114:115], v[114:115], 2, s[16:17]
	global_load_dword v117, v[112:113], off
	global_load_dword v118, v[114:115], off
	ds_bpermute_b32 v119, v177, v108
	v_mov_b32_e32 v116, v108
	ds_bpermute_b32 v108, v177, v109
	ds_bpermute_b32 v162, v177, v110
	ds_bpermute_b32 v163, v177, v111
	s_waitcnt lgkmcnt(3)
	v_cndmask_b32_e64 v119, v119, -v119, vcc
	s_waitcnt vmcnt(0)
	v_pk_mul_f32 v[126:127], v[116:117], v[118:119]
	s_waitcnt lgkmcnt(2)
	v_cndmask_b32_e64 v119, v108, -v108, vcc
	v_mov_b32_e32 v116, v109
	v_pk_mul_f32 v[108:109], v[116:117], v[118:119]
	s_waitcnt lgkmcnt(1)
	v_cndmask_b32_e64 v119, v162, -v162, vcc
	v_mov_b32_e32 v116, v110
	v_add_f32_e32 v126, v126, v127
	v_add_f32_e32 v127, v108, v109
	v_pk_mul_f32 v[108:109], v[116:117], v[118:119]
	s_waitcnt lgkmcnt(0)
	v_cndmask_b32_e64 v119, v163, -v163, vcc
	v_mov_b32_e32 v116, v111
	v_add_f32_e32 v162, v108, v109
	v_pk_mul_f32 v[108:109], v[116:117], v[118:119]
	s_nop 0
	v_add_f32_e32 v118, v108, v109
	global_load_dword v109, v[112:113], off
	global_load_dword v110, v[114:115], off
	ds_bpermute_b32 v111, v177, v104
	v_mov_b32_e32 v108, v104
	ds_bpermute_b32 v104, v177, v105
	ds_bpermute_b32 v119, v177, v106
	ds_bpermute_b32 v163, v177, v107
	s_waitcnt lgkmcnt(3)
	v_cndmask_b32_e64 v111, v111, -v111, vcc
	s_waitcnt vmcnt(0)
	v_pk_mul_f32 v[116:117], v[108:109], v[110:111]
	s_waitcnt lgkmcnt(2)
	v_cndmask_b32_e64 v111, v104, -v104, vcc
	v_mov_b32_e32 v108, v105
	v_pk_mul_f32 v[104:105], v[108:109], v[110:111]
	s_waitcnt lgkmcnt(1)
	v_cndmask_b32_e64 v111, v119, -v119, vcc
	v_mov_b32_e32 v108, v106
	v_add_f32_e32 v119, v104, v105
	v_pk_mul_f32 v[104:105], v[108:109], v[110:111]
	s_waitcnt lgkmcnt(0)
	v_cndmask_b32_e64 v111, v163, -v163, vcc
	v_mov_b32_e32 v108, v107
	v_add_f32_e32 v163, v104, v105
	v_pk_mul_f32 v[104:105], v[108:109], v[110:111]
	v_add_f32_e32 v164, v116, v117
	v_add_f32_e32 v108, v104, v105
	v_mul_f32_e32 v104, v180, v126
	v_mul_f32_e32 v105, v181, v127
	v_cvt_pk_bf16_f32 v104, v104, v105
	v_mul_f32_e32 v105, v167, v162
	v_mul_f32_e32 v106, v183, v118
	v_cvt_pk_bf16_f32 v105, v105, v106
	v_mul_f32_e32 v106, v182, v164
	v_mul_f32_e32 v107, v185, v119
	v_cvt_pk_bf16_f32 v106, v106, v107
	v_mul_f32_e32 v107, v184, v163
	v_mul_f32_e32 v109, v159, v108
	v_cvt_pk_bf16_f32 v107, v107, v109
	v_mul_f32_e32 v109, v150, v126
	v_mul_f32_e32 v110, v152, v127
	v_cvt_pk_bf16_f32 v116, v109, v110
	v_mul_f32_e32 v109, v154, v162
	v_mul_f32_e32 v110, v156, v118
	v_cvt_pk_bf16_f32 v117, v109, v110
	v_mul_f32_e32 v109, v158, v164
	v_mul_f32_e32 v110, v160, v119
	v_cvt_pk_bf16_f32 v118, v109, v110
	v_mul_f32_e32 v109, v151, v163
	v_mul_f32_e32 v108, v155, v108
	s_mov_b64 s[0:1], 0x200000
	v_cvt_pk_bf16_f32 v119, v109, v108
	v_lshl_add_u64 v[108:109], v[120:121], 0, s[0:1]
	s_mov_b32 s0, 0x200000
	v_add_co_u32_e64 v110, s[4:5], s0, v120
	s_mov_b64 s[0:1], 0x2200000
	s_nop 0
	v_addc_co_u32_e64 v111, s[4:5], 0, v121, s[4:5]
	global_store_dwordx4 v[110:111], v[104:107], off
	v_lshl_add_u64 v[110:111], v[120:121], 0, s[0:1]
	s_mov_b32 s0, 0x2200000
	v_add_co_u32_e64 v104, s[4:5], s0, v120
	s_nop 1
	v_addc_co_u32_e64 v105, s[4:5], 0, v121, s[4:5]
	global_store_dwordx4 v[104:105], v[116:119], off
	v_add_u32_e32 v104, v153, v161
	v_add_u32_e32 v106, v153, v157
	v_ashrrev_i32_e32 v105, 31, v104
	v_ashrrev_i32_e32 v107, 31, v106
	v_lshl_add_u64 v[104:105], v[104:105], 2, s[16:17]
	v_lshl_add_u64 v[106:107], v[106:107], 2, s[16:17]
	global_load_dword v117, v[104:105], off
	global_load_dword v118, v[106:107], off
	ds_bpermute_b32 v119, v177, v100
	v_mov_b32_e32 v116, v100
	ds_bpermute_b32 v100, v177, v101
	ds_bpermute_b32 v153, v177, v102
	ds_bpermute_b32 v157, v177, v103
	s_waitcnt lgkmcnt(3)
; __device__ __forceinline__ unsigned cvt_pk_bf16(float lo, float hi) { unsigned r; asm volatile("v_cvt_pk_bf16_f32 %0, %1, %2" : "=v"(r) : "v"(lo), "v"(hi)); return r; }
;     __device__ __forceinline__ void operator()(const AccT& acc, const Unit& u, int wr, int wc, int fr, int fq) const {
;     ...
;                         const int t = t0 & 2047;
; #pragma unroll
;                         for (int hf = 0; hf < 2; ++hf) {
;                             f32x4 cs, sn;
;                             if (m < 2) { const float c1 = ropeA[(t >> 6) * 16 + d], s1 = ropeA[1024 + (t >> 6) * 16 + d]; cs = (f32x4){c1, c1, c1, c1}; sn = (f32x4){s1, s1, s1, s1}; }
;                             else { const float* cb = ropeA + 2048 + (d - 16) * 64 + (t & 63) + 4 * hf; cs = *(const f32x4*)(cb); sn = *(const f32x4*)(cb + 1024); }
; #pragma unroll
;                             for (int jj = 0; jj < 4; ++jj) { const float pr = __shfl_xor(v[4 * hf + jj], 4); v[4 * hf + jj] = v[4 * hf + jj] * cs[jj] + sgn * pr * sn[jj]; }
;                             __builtin_amdgcn_sched_barrier(0);
;                         }
;                     }
;                     float zf[8], zb[8]; zf[0] = zf0; zb[0] = zb0;
; #pragma unroll
;                     for (int jj = 1; jj < 8; ++jj) { zf[jj] = zf[jj - 1] * zfs; zb[jj] = zb[jj - 1] * zbs; }
;                     u32x4 wf, wb;
;                     wf.x = cvt_pk_bf16(v[0] * zf[0], v[1] * zf[1]); wf.y = cvt_pk_bf16(v[2] * zf[2], v[3] * zf[3]); wf.z = cvt_pk_bf16(v[4] * zf[4], v[5] * zf[5]); wf.w = cvt_pk_bf16(v[6] * zf[6], v[7] * zf[7]);
;                     wb.x = cvt_pk_bf16(v[0] * zb[0], v[1] * zb[1]); wb.y = cvt_pk_bf16(v[2] * zb[2], v[3] * zb[3]); wb.z = cvt_pk_bf16(v[4] * zb[4], v[5] * zb[5]); wb.w = cvt_pk_bf16(v[6] * zb[6], v[7] * zb[7]);
;                     *(u32x4*)(KTZ + (size_t)r * NT + t0) = wf;
;                     *(u32x4*)(KTZ + (size_t)(256 + r) * NT + t0) = wb;
	v_cndmask_b32_e64 v119, v119, -v119, vcc
	s_waitcnt vmcnt(0)
	v_pk_mul_f32 v[126:127], v[116:117], v[118:119]
	s_waitcnt lgkmcnt(2)
	v_cndmask_b32_e64 v119, v100, -v100, vcc
	v_mov_b32_e32 v116, v101
	v_pk_mul_f32 v[100:101], v[116:117], v[118:119]
	s_waitcnt lgkmcnt(1)
	v_cndmask_b32_e64 v119, v153, -v153, vcc
	v_mov_b32_e32 v116, v102
	v_add_f32_e32 v126, v126, v127
	v_add_f32_e32 v127, v100, v101
	v_pk_mul_f32 v[100:101], v[116:117], v[118:119]
	s_waitcnt lgkmcnt(0)
	v_cndmask_b32_e64 v119, v157, -v157, vcc
	v_mov_b32_e32 v116, v103
	v_add_f32_e32 v153, v100, v101
	v_pk_mul_f32 v[100:101], v[116:117], v[118:119]
	s_nop 0
	v_add_f32_e32 v118, v100, v101
	global_load_dword v101, v[104:105], off
	global_load_dword v102, v[106:107], off
	ds_bpermute_b32 v103, v177, v96
	v_mov_b32_e32 v100, v96
	ds_bpermute_b32 v96, v177, v97
	ds_bpermute_b32 v119, v177, v98
	ds_bpermute_b32 v157, v177, v99
	s_waitcnt lgkmcnt(3)
	v_cndmask_b32_e64 v103, v103, -v103, vcc
	s_waitcnt vmcnt(0)
	v_pk_mul_f32 v[116:117], v[100:101], v[102:103]
	s_waitcnt lgkmcnt(2)
	v_cndmask_b32_e64 v103, v96, -v96, vcc
	v_mov_b32_e32 v100, v97
	v_pk_mul_f32 v[96:97], v[100:101], v[102:103]
	s_waitcnt lgkmcnt(1)
	v_cndmask_b32_e64 v103, v119, -v119, vcc
	v_mov_b32_e32 v100, v98
	v_add_f32_e32 v116, v116, v117
	v_add_f32_e32 v117, v96, v97
	v_pk_mul_f32 v[96:97], v[100:101], v[102:103]
	s_waitcnt lgkmcnt(0)
	v_cndmask_b32_e64 v103, v157, -v157, vcc
	v_mov_b32_e32 v100, v99
	v_add_f32_e32 v119, v96, v97
	v_pk_mul_f32 v[96:97], v[100:101], v[102:103]
	s_nop 0
	v_add_f32_e32 v103, v96, v97
	v_mul_f32_e32 v96, v180, v126
	v_mul_f32_e32 v97, v181, v127
	v_cvt_pk_bf16_f32 v96, v96, v97
	v_mul_f32_e32 v97, v167, v153
	v_mul_f32_e32 v98, v183, v118
	v_cvt_pk_bf16_f32 v97, v97, v98
	v_mul_f32_e32 v98, v182, v116
	v_mul_f32_e32 v99, v185, v117
	v_cvt_pk_bf16_f32 v98, v98, v99
	v_mul_f32_e32 v99, v184, v119
	v_mul_f32_e32 v100, v159, v103
	v_cvt_pk_bf16_f32 v99, v99, v100
	v_mul_f32_e32 v100, v150, v126
	v_mul_f32_e32 v101, v152, v127
	v_cvt_pk_bf16_f32 v100, v100, v101
	v_mul_f32_e32 v101, v154, v153
	v_mul_f32_e32 v102, v156, v118
	v_cvt_pk_bf16_f32 v101, v101, v102
	v_mul_f32_e32 v102, v158, v116
	v_mul_f32_e32 v116, v160, v117
	v_mul_f32_e32 v103, v155, v103
	v_cvt_pk_bf16_f32 v102, v102, v116
	v_mul_f32_e32 v116, v151, v119
	v_cvt_pk_bf16_f32 v103, v116, v103
	global_store_dwordx4 v[108:109], v[96:99], off offset:256
	global_store_dwordx4 v[110:111], v[100:103], off offset:256
	s_nop 1
	v_lshlrev_b32_e32 v100, 6, v136
	v_ashrrev_i32_e32 v101, 31, v100
	v_lshlrev_b64 v[102:103], 2, v[100:101]
	v_lshl_add_u64 v[96:97], s[24:25], 0, v[102:103]
	v_lshlrev_b32_e32 v136, 2, v186
	v_lshl_add_u64 v[96:97], v[96:97], 0, v[136:137]
	v_add_co_u32_e64 v98, s[4:5], s61, v96
	ds_bpermute_b32 v101, v177, v92
	s_nop 0
	v_addc_co_u32_e64 v99, s[4:5], 0, v97, s[4:5]
	global_load_dwordx4 v[108:111], v[98:99], off
	global_load_dwordx4 v[116:119], v[96:97], off
	ds_bpermute_b32 v127, v177, v93
	ds_bpermute_b32 v153, v177, v94
	ds_bpermute_b32 v157, v177, v95
	v_mov_b32_e32 v126, v92
	v_mov_b32_e32 v92, v94
	s_waitcnt lgkmcnt(3)
	v_cndmask_b32_e64 v163, v101, -v101, vcc
	s_waitcnt lgkmcnt(2)
	v_cndmask_b32_e64 v165, v127, -v127, vcc
	s_waitcnt lgkmcnt(1)
	v_cndmask_b32_e64 v187, v153, -v153, vcc
	s_waitcnt lgkmcnt(0)
	v_cndmask_b32_e64 v189, v157, -v157, vcc
	s_waitcnt vmcnt(1)
	v_mov_b32_e32 v127, v108
	s_waitcnt vmcnt(0)
	v_mov_b32_e32 v162, v116
	v_mov_b32_e32 v108, v93
	v_mov_b32_e32 v164, v117
	v_mov_b32_e32 v93, v110
	v_mov_b32_e32 v186, v118
	v_mov_b32_e32 v110, v95
	v_mov_b32_e32 v188, v119
	v_pk_mul_f32 v[94:95], v[126:127], v[162:163]
	v_pk_mul_f32 v[108:109], v[108:109], v[164:165]
	v_pk_mul_f32 v[92:93], v[92:93], v[186:187]
	v_pk_mul_f32 v[110:111], v[110:111], v[188:189]
	v_add_f32_e32 v101, v94, v95
	v_add_f32_e32 v153, v108, v109
	v_add_f32_e32 v157, v92, v93
	v_add_f32_e32 v161, v110, v111
	v_lshl_add_u64 v[92:93], s[16:17], 0, v[102:103]
	v_lshl_add_u64 v[94:95], v[92:93], 0, v[136:137]
	v_add_co_u32_e64 v92, s[4:5], s62, v94
	ds_bpermute_b32 v103, v177, v88
	s_nop 0
	v_addc_co_u32_e64 v93, s[4:5], 0, v95, s[4:5]
	v_add_co_u32_e64 v94, s[4:5], s49, v94
	ds_bpermute_b32 v126, v177, v89
	s_nop 0
	v_addc_co_u32_e64 v95, s[4:5], 0, v95, s[4:5]
	global_load_dwordx4 v[108:111], v[92:93], off offset:16
	global_load_dwordx4 v[116:119], v[94:95], off offset:16
	ds_bpermute_b32 v162, v177, v90
	ds_bpermute_b32 v164, v177, v91
	v_mov_b32_e32 v102, v88
	v_mov_b32_e32 v88, v90
	s_waitcnt lgkmcnt(3)
	v_cndmask_b32_e64 v127, v103, -v103, vcc
	s_waitcnt lgkmcnt(2)
	v_cndmask_b32_e64 v163, v126, -v126, vcc
	s_waitcnt lgkmcnt(1)
	v_cndmask_b32_e64 v165, v162, -v162, vcc
	s_waitcnt lgkmcnt(0)
	v_cndmask_b32_e64 v187, v164, -v164, vcc
	s_waitcnt vmcnt(1)
	v_mov_b32_e32 v103, v108
	s_waitcnt vmcnt(0)
; __device__ __forceinline__ unsigned cvt_pk_bf16(float lo, float hi) { unsigned r; asm volatile("v_cvt_pk_bf16_f32 %0, %1, %2" : "=v"(r) : "v"(lo), "v"(hi)); return r; }
;     __device__ __forceinline__ void operator()(const AccT& acc, const Unit& u, int wr, int wc, int fr, int fq) const {
;     ...
;                         const int t = t0 & 2047;
; #pragma unroll
;                         for (int hf = 0; hf < 2; ++hf) {
;                             f32x4 cs, sn;
;                             if (m < 2) { const float c1 = ropeA[(t >> 6) * 16 + d], s1 = ropeA[1024 + (t >> 6) * 16 + d]; cs = (f32x4){c1, c1, c1, c1}; sn = (f32x4){s1, s1, s1, s1}; }
;                             else { const float* cb = ropeA + 2048 + (d - 16) * 64 + (t & 63) + 4 * hf; cs = *(const f32x4*)(cb); sn = *(const f32x4*)(cb + 1024); }
; #pragma unroll
;                             for (int jj = 0; jj < 4; ++jj) { const float pr = __shfl_xor(v[4 * hf + jj], 4); v[4 * hf + jj] = v[4 * hf + jj] * cs[jj] + sgn * pr * sn[jj]; }
;                             __builtin_amdgcn_sched_barrier(0);
;                         }
;                     }
;                     float zf[8], zb[8]; zf[0] = zf0; zb[0] = zb0;
; #pragma unroll
;                     for (int jj = 1; jj < 8; ++jj) { zf[jj] = zf[jj - 1] * zfs; zb[jj] = zb[jj - 1] * zbs; }
;                     u32x4 wf, wb;
;                     wf.x = cvt_pk_bf16(v[0] * zf[0], v[1] * zf[1]); wf.y = cvt_pk_bf16(v[2] * zf[2], v[3] * zf[3]); wf.z = cvt_pk_bf16(v[4] * zf[4], v[5] * zf[5]); wf.w = cvt_pk_bf16(v[6] * zf[6], v[7] * zf[7]);
;                     wb.x = cvt_pk_bf16(v[0] * zb[0], v[1] * zb[1]); wb.y = cvt_pk_bf16(v[2] * zb[2], v[3] * zb[3]); wb.z = cvt_pk_bf16(v[4] * zb[4], v[5] * zb[5]); wb.w = cvt_pk_bf16(v[6] * zb[6], v[7] * zb[7]);
;                     *(u32x4*)(KTZ + (size_t)r * NT + t0) = wf;
;                     *(u32x4*)(KTZ + (size_t)(256 + r) * NT + t0) = wb;
	v_mov_b32_e32 v126, v116
	v_mov_b32_e32 v108, v89
	v_mov_b32_e32 v162, v117
	v_mov_b32_e32 v89, v110
	v_mov_b32_e32 v164, v118
	v_mov_b32_e32 v110, v91
	v_mov_b32_e32 v186, v119
	v_pk_mul_f32 v[90:91], v[102:103], v[126:127]
	v_pk_mul_f32 v[102:103], v[108:109], v[162:163]
	v_pk_mul_f32 v[88:89], v[88:89], v[164:165]
	v_pk_mul_f32 v[108:109], v[110:111], v[186:187]
	v_add_f32_e32 v90, v90, v91
	v_add_f32_e32 v91, v102, v103
	v_add_f32_e32 v88, v88, v89
	v_add_f32_e32 v89, v108, v109
	v_mul_f32_e32 v102, v180, v101
	v_mul_f32_e32 v103, v181, v153
	v_cvt_pk_bf16_f32 v108, v102, v103
	v_mul_f32_e32 v102, v167, v157
	v_mul_f32_e32 v103, v183, v161
	v_cvt_pk_bf16_f32 v109, v102, v103
	v_mul_f32_e32 v102, v182, v90
	v_mul_f32_e32 v103, v185, v91
	v_cvt_pk_bf16_f32 v110, v102, v103
	v_mul_f32_e32 v102, v184, v88
	v_mul_f32_e32 v103, v159, v89
	v_cvt_pk_bf16_f32 v111, v102, v103
	v_mul_f32_e32 v101, v150, v101
	v_mul_f32_e32 v102, v152, v153
	v_mul_f32_e32 v88, v151, v88
	v_mul_f32_e32 v89, v155, v89
	s_mov_b64 s[0:1], 0x400000
	v_cvt_pk_bf16_f32 v116, v101, v102
	v_mul_f32_e32 v101, v154, v157
	v_mul_f32_e32 v102, v156, v161
	v_cvt_pk_bf16_f32 v117, v101, v102
	v_mul_f32_e32 v90, v158, v90
	v_mul_f32_e32 v91, v160, v91
	v_cvt_pk_bf16_f32 v118, v90, v91
	v_cvt_pk_bf16_f32 v119, v88, v89
	v_lshl_add_u64 v[88:89], v[120:121], 0, s[0:1]
	s_mov_b32 s0, 0x400000
	v_add_co_u32_e64 v90, s[4:5], s0, v120
	s_mov_b64 s[0:1], 0x2400000
	s_nop 0
	v_addc_co_u32_e64 v91, s[4:5], 0, v121, s[4:5]
	global_store_dwordx4 v[90:91], v[108:111], off
	v_lshl_add_u64 v[90:91], v[120:121], 0, s[0:1]
	s_mov_b32 s0, 0x2400000
	v_add_co_u32_e64 v102, s[4:5], s0, v120
	s_nop 1
	v_addc_co_u32_e64 v103, s[4:5], 0, v121, s[4:5]
	global_store_dwordx4 v[102:103], v[116:119], off
	global_load_dwordx4 v[108:111], v[98:99], off
	s_nop 0
	global_load_dwordx4 v[116:119], v[96:97], off
	ds_bpermute_b32 v101, v177, v84
	ds_bpermute_b32 v103, v177, v85
	ds_bpermute_b32 v126, v177, v86
	ds_bpermute_b32 v153, v177, v87
	v_mov_b32_e32 v102, v84
	v_mov_b32_e32 v84, v86
	s_waitcnt lgkmcnt(3)
	v_cndmask_b32_e64 v127, v101, -v101, vcc
	s_waitcnt lgkmcnt(2)
	v_cndmask_b32_e64 v163, v103, -v103, vcc
	s_waitcnt lgkmcnt(1)
	v_cndmask_b32_e64 v165, v126, -v126, vcc
	s_waitcnt lgkmcnt(0)
	v_cndmask_b32_e64 v187, v153, -v153, vcc
	s_waitcnt vmcnt(1)
	v_mov_b32_e32 v103, v108
	s_waitcnt vmcnt(0)
	v_mov_b32_e32 v126, v116
	v_mov_b32_e32 v108, v85
	v_mov_b32_e32 v162, v117
	v_mov_b32_e32 v85, v110
	v_mov_b32_e32 v164, v118
	v_mov_b32_e32 v110, v87
	v_mov_b32_e32 v186, v119
	v_pk_mul_f32 v[86:87], v[102:103], v[126:127]
	v_pk_mul_f32 v[102:103], v[108:109], v[162:163]
	v_pk_mul_f32 v[84:85], v[84:85], v[164:165]
	v_pk_mul_f32 v[108:109], v[110:111], v[186:187]
	v_add_f32_e32 v101, v86, v87
	v_add_f32_e32 v153, v102, v103
	v_add_f32_e32 v157, v84, v85
	v_add_f32_e32 v161, v108, v109
	global_load_dwordx4 v[84:87], v[92:93], off offset:16
	global_load_dwordx4 v[108:111], v[94:95], off offset:16
	ds_bpermute_b32 v103, v177, v80
	ds_bpermute_b32 v116, v177, v81
	ds_bpermute_b32 v118, v177, v82
	ds_bpermute_b32 v126, v177, v83
	v_mov_b32_e32 v102, v80
	v_mov_b32_e32 v80, v82
	s_waitcnt lgkmcnt(3)
	v_cndmask_b32_e64 v117, v103, -v103, vcc
	s_waitcnt lgkmcnt(2)
	v_cndmask_b32_e64 v119, v116, -v116, vcc
	s_waitcnt lgkmcnt(1)
	v_cndmask_b32_e64 v127, v118, -v118, vcc
	s_waitcnt lgkmcnt(0)
	v_cndmask_b32_e64 v163, v126, -v126, vcc
	s_waitcnt vmcnt(1)
	v_mov_b32_e32 v103, v84
	s_waitcnt vmcnt(0)
	v_mov_b32_e32 v116, v108
	v_mov_b32_e32 v84, v81
	v_mov_b32_e32 v118, v109
	v_mov_b32_e32 v81, v86
	v_mov_b32_e32 v126, v110
	v_mov_b32_e32 v86, v83
	v_mov_b32_e32 v162, v111
	v_pk_mul_f32 v[82:83], v[102:103], v[116:117]
	v_pk_mul_f32 v[84:85], v[84:85], v[118:119]
	v_pk_mul_f32 v[80:81], v[80:81], v[126:127]
	v_pk_mul_f32 v[86:87], v[86:87], v[162:163]
	v_add_f32_e32 v102, v82, v83
	v_add_f32_e32 v103, v84, v85
	v_add_f32_e32 v108, v80, v81
	v_add_f32_e32 v87, v86, v87
	v_mul_f32_e32 v80, v180, v101
	v_mul_f32_e32 v81, v181, v153
	v_cvt_pk_bf16_f32 v80, v80, v81
	v_mul_f32_e32 v81, v167, v157
	v_mul_f32_e32 v82, v183, v161
	v_cvt_pk_bf16_f32 v81, v81, v82
	v_mul_f32_e32 v82, v182, v102
	v_mul_f32_e32 v83, v185, v103
	v_cvt_pk_bf16_f32 v82, v82, v83
	v_mul_f32_e32 v83, v184, v108
	v_mul_f32_e32 v84, v159, v87
	v_cvt_pk_bf16_f32 v83, v83, v84
	v_mul_f32_e32 v84, v150, v101
	v_mul_f32_e32 v85, v152, v153
	v_cvt_pk_bf16_f32 v84, v84, v85
	v_mul_f32_e32 v85, v154, v157
	v_mul_f32_e32 v86, v156, v161
	v_cvt_pk_bf16_f32 v85, v85, v86
	v_mul_f32_e32 v86, v158, v102
	v_mul_f32_e32 v101, v160, v103
	v_mul_f32_e32 v87, v155, v87
	v_cvt_pk_bf16_f32 v86, v86, v101
	v_mul_f32_e32 v101, v151, v108
	v_cvt_pk_bf16_f32 v87, v101, v87
	global_store_dwordx4 v[88:89], v[80:83], off offset:256
	global_store_dwordx4 v[90:91], v[84:87], off offset:256
	s_nop 0
	v_add_u32_e32 v80, 0x200, v100
	v_ashrrev_i32_e32 v81, 31, v80
	v_lshl_add_u64 v[82:83], s[24:25], 0, v[136:137]
	v_lshlrev_b64 v[100:101], 2, v[80:81]
	v_lshl_add_u64 v[80:81], v[82:83], 0, v[100:101]
	v_add_co_u32_e64 v82, s[4:5], s61, v80
	ds_bpermute_b32 v103, v177, v76
	s_nop 0
	v_addc_co_u32_e64 v83, s[4:5], 0, v81, s[4:5]
	global_load_dwordx4 v[84:87], v[82:83], off
	global_load_dwordx4 v[88:91], v[80:81], off
	ds_bpermute_b32 v108, v177, v77
	ds_bpermute_b32 v110, v177, v78
	ds_bpermute_b32 v116, v177, v79
	v_mov_b32_e32 v102, v76
	v_mov_b32_e32 v76, v78
	s_waitcnt lgkmcnt(3)
	v_cndmask_b32_e64 v109, v103, -v103, vcc
	s_waitcnt lgkmcnt(2)
	v_cndmask_b32_e64 v111, v108, -v108, vcc
	s_waitcnt lgkmcnt(1)
	v_cndmask_b32_e64 v117, v110, -v110, vcc
	s_waitcnt lgkmcnt(0)
; __device__ __forceinline__ unsigned cvt_pk_bf16(float lo, float hi) { unsigned r; asm volatile("v_cvt_pk_bf16_f32 %0, %1, %2" : "=v"(r) : "v"(lo), "v"(hi)); return r; }
;     __device__ __forceinline__ void operator()(const AccT& acc, const Unit& u, int wr, int wc, int fr, int fq) const {
;     ...
;                         const int t = t0 & 2047;
; #pragma unroll
;                         for (int hf = 0; hf < 2; ++hf) {
;                             f32x4 cs, sn;
;                             if (m < 2) { const float c1 = ropeA[(t >> 6) * 16 + d], s1 = ropeA[1024 + (t >> 6) * 16 + d]; cs = (f32x4){c1, c1, c1, c1}; sn = (f32x4){s1, s1, s1, s1}; }
;                             else { const float* cb = ropeA + 2048 + (d - 16) * 64 + (t & 63) + 4 * hf; cs = *(const f32x4*)(cb); sn = *(const f32x4*)(cb + 1024); }
; #pragma unroll
;                             for (int jj = 0; jj < 4; ++jj) { const float pr = __shfl_xor(v[4 * hf + jj], 4); v[4 * hf + jj] = v[4 * hf + jj] * cs[jj] + sgn * pr * sn[jj]; }
;                             __builtin_amdgcn_sched_barrier(0);
;                         }
;                     }
;                     float zf[8], zb[8]; zf[0] = zf0; zb[0] = zb0;
; #pragma unroll
;                     for (int jj = 1; jj < 8; ++jj) { zf[jj] = zf[jj - 1] * zfs; zb[jj] = zb[jj - 1] * zbs; }
;                     u32x4 wf, wb;
;                     wf.x = cvt_pk_bf16(v[0] * zf[0], v[1] * zf[1]); wf.y = cvt_pk_bf16(v[2] * zf[2], v[3] * zf[3]); wf.z = cvt_pk_bf16(v[4] * zf[4], v[5] * zf[5]); wf.w = cvt_pk_bf16(v[6] * zf[6], v[7] * zf[7]);
;                     wb.x = cvt_pk_bf16(v[0] * zb[0], v[1] * zb[1]); wb.y = cvt_pk_bf16(v[2] * zb[2], v[3] * zb[3]); wb.z = cvt_pk_bf16(v[4] * zb[4], v[5] * zb[5]); wb.w = cvt_pk_bf16(v[6] * zb[6], v[7] * zb[7]);
;                     *(u32x4*)(KTZ + (size_t)r * NT + t0) = wf;
;                     *(u32x4*)(KTZ + (size_t)(256 + r) * NT + t0) = wb;
	v_cndmask_b32_e64 v119, v116, -v116, vcc
	s_waitcnt vmcnt(1)
	v_mov_b32_e32 v103, v84
	s_waitcnt vmcnt(0)
	v_mov_b32_e32 v108, v88
	v_mov_b32_e32 v84, v77
	v_mov_b32_e32 v110, v89
	v_mov_b32_e32 v77, v86
	v_mov_b32_e32 v116, v90
	v_mov_b32_e32 v86, v79
	v_mov_b32_e32 v118, v91
	v_pk_mul_f32 v[78:79], v[102:103], v[108:109]
	v_pk_mul_f32 v[84:85], v[84:85], v[110:111]
	v_pk_mul_f32 v[76:77], v[76:77], v[116:117]
	v_pk_mul_f32 v[86:87], v[86:87], v[118:119]
	v_add_f32_e32 v118, v78, v79
	v_add_f32_e32 v119, v84, v85
	v_add_f32_e32 v126, v76, v77
	v_add_f32_e32 v127, v86, v87
	v_lshl_add_u64 v[76:77], s[16:17], 0, v[100:101]
	v_lshl_add_u64 v[78:79], v[76:77], 0, v[136:137]
	v_add_co_u32_e64 v76, s[4:5], s62, v78
	ds_bpermute_b32 v101, v177, v72
	s_nop 0
	v_addc_co_u32_e64 v77, s[4:5], 0, v79, s[4:5]
	v_add_co_u32_e64 v78, s[4:5], s49, v78
	ds_bpermute_b32 v102, v177, v73
	s_nop 0
	v_addc_co_u32_e64 v79, s[4:5], 0, v79, s[4:5]
	global_load_dwordx4 v[84:87], v[76:77], off offset:16
	global_load_dwordx4 v[88:91], v[78:79], off offset:16
	ds_bpermute_b32 v108, v177, v74
	ds_bpermute_b32 v110, v177, v75
	v_mov_b32_e32 v100, v72
	v_mov_b32_e32 v72, v74
	s_waitcnt lgkmcnt(3)
	v_cndmask_b32_e64 v103, v101, -v101, vcc
	s_waitcnt lgkmcnt(2)
	v_cndmask_b32_e64 v109, v102, -v102, vcc
	s_waitcnt lgkmcnt(1)
	v_cndmask_b32_e64 v111, v108, -v108, vcc
	s_waitcnt lgkmcnt(0)
	v_cndmask_b32_e64 v117, v110, -v110, vcc
	s_waitcnt vmcnt(1)
	v_mov_b32_e32 v101, v84
	s_waitcnt vmcnt(0)
	v_mov_b32_e32 v102, v88
	v_mov_b32_e32 v84, v73
	v_mov_b32_e32 v108, v89
	v_mov_b32_e32 v73, v86
	v_mov_b32_e32 v110, v90
	v_mov_b32_e32 v86, v75
	v_mov_b32_e32 v116, v91
	v_pk_mul_f32 v[74:75], v[100:101], v[102:103]
	v_pk_mul_f32 v[84:85], v[84:85], v[108:109]
	v_pk_mul_f32 v[72:73], v[72:73], v[110:111]
	v_pk_mul_f32 v[86:87], v[86:87], v[116:117]
	v_add_f32_e32 v74, v74, v75
	v_add_f32_e32 v75, v84, v85
	v_add_f32_e32 v72, v72, v73
	v_add_f32_e32 v73, v86, v87
	v_mul_f32_e32 v84, v180, v118
	v_mul_f32_e32 v85, v181, v119
	v_cvt_pk_bf16_f32 v84, v84, v85
	v_mul_f32_e32 v85, v167, v126
	v_mul_f32_e32 v86, v183, v127
	v_cvt_pk_bf16_f32 v85, v85, v86
	v_mul_f32_e32 v86, v182, v74
	v_mul_f32_e32 v87, v185, v75
	v_cvt_pk_bf16_f32 v86, v86, v87
	v_mul_f32_e32 v87, v184, v72
	v_mul_f32_e32 v88, v159, v73
	v_cvt_pk_bf16_f32 v87, v87, v88
	v_mul_f32_e32 v88, v150, v118
	v_mul_f32_e32 v89, v152, v119
	v_cvt_pk_bf16_f32 v88, v88, v89
	v_mul_f32_e32 v89, v154, v126
	v_mul_f32_e32 v90, v156, v127
	v_mul_f32_e32 v72, v151, v72
	v_mul_f32_e32 v73, v155, v73
	s_mov_b64 s[0:1], 0x600000
	v_cvt_pk_bf16_f32 v89, v89, v90
	v_mul_f32_e32 v74, v158, v74
	v_mul_f32_e32 v75, v160, v75
	v_cvt_pk_bf16_f32 v90, v74, v75
	v_cvt_pk_bf16_f32 v91, v72, v73
	v_lshl_add_u64 v[72:73], v[120:121], 0, s[0:1]
	s_mov_b32 s0, 0x600000
	v_add_co_u32_e64 v74, s[4:5], s0, v120
	s_mov_b64 s[0:1], 0x2600000
	s_nop 0
	v_addc_co_u32_e64 v75, s[4:5], 0, v121, s[4:5]
	global_store_dwordx4 v[74:75], v[84:87], off
	v_lshl_add_u64 v[74:75], v[120:121], 0, s[0:1]
	s_mov_b32 s0, 0x2600000
	v_add_co_u32_e64 v84, s[4:5], s0, v120
	s_nop 1
	v_addc_co_u32_e64 v85, s[4:5], 0, v121, s[4:5]
	global_store_dwordx4 v[84:85], v[88:91], off
	global_load_dwordx4 v[84:87], v[82:83], off
	s_nop 0
	global_load_dwordx4 v[88:91], v[80:81], off
	ds_bpermute_b32 v101, v177, v68
	ds_bpermute_b32 v102, v177, v69
	ds_bpermute_b32 v108, v177, v70
	ds_bpermute_b32 v110, v177, v71
	v_mov_b32_e32 v100, v68
	v_mov_b32_e32 v68, v70
	s_waitcnt lgkmcnt(3)
	v_cndmask_b32_e64 v103, v101, -v101, vcc
	s_waitcnt lgkmcnt(2)
	v_cndmask_b32_e64 v109, v102, -v102, vcc
	s_waitcnt lgkmcnt(1)
	v_cndmask_b32_e64 v111, v108, -v108, vcc
	s_waitcnt lgkmcnt(0)
	v_cndmask_b32_e64 v117, v110, -v110, vcc
	s_waitcnt vmcnt(1)
	v_mov_b32_e32 v101, v84
	s_waitcnt vmcnt(0)
	v_mov_b32_e32 v102, v88
	v_mov_b32_e32 v84, v69
	v_mov_b32_e32 v108, v89
	v_mov_b32_e32 v69, v86
	v_mov_b32_e32 v110, v90
	v_mov_b32_e32 v86, v71
	v_mov_b32_e32 v116, v91
	v_pk_mul_f32 v[70:71], v[100:101], v[102:103]
	v_pk_mul_f32 v[84:85], v[84:85], v[108:109]
	v_pk_mul_f32 v[68:69], v[68:69], v[110:111]
	v_pk_mul_f32 v[86:87], v[86:87], v[116:117]
	v_add_f32_e32 v110, v70, v71
	v_add_f32_e32 v111, v84, v85
	v_add_f32_e32 v116, v68, v69
	v_add_f32_e32 v117, v86, v87
	global_load_dwordx4 v[68:71], v[76:77], off offset:16
	global_load_dwordx4 v[84:87], v[78:79], off offset:16
	ds_bpermute_b32 v89, v177, v64
	ds_bpermute_b32 v90, v177, v65
	ds_bpermute_b32 v100, v177, v66
	ds_bpermute_b32 v102, v177, v67
	v_mov_b32_e32 v88, v64
	v_mov_b32_e32 v64, v66
	s_waitcnt lgkmcnt(3)
	v_cndmask_b32_e64 v91, v89, -v89, vcc
	s_waitcnt lgkmcnt(2)
	v_cndmask_b32_e64 v101, v90, -v90, vcc
	s_waitcnt lgkmcnt(1)
	v_cndmask_b32_e64 v103, v100, -v100, vcc
	s_waitcnt lgkmcnt(0)
	v_cndmask_b32_e64 v109, v102, -v102, vcc
	s_waitcnt vmcnt(1)
	v_mov_b32_e32 v89, v68
	s_waitcnt vmcnt(0)
;     __device__ __forceinline__ void operator()(const AccT& acc, const Unit& u, int wr, int wc, int fr, int fq) const {
;     ...
;         for (int ai = 0; ai < 2; ++ai) {
;             const int hh = 2 * ai + wr;
;             const float l2f = lgd[hh] * 1.4426950408889634f, l2b = lgd[4 + hh] * 1.4426950408889634f;
;             const float zf0 = exp2f((float)(127 - o0) * l2f), zfs = exp2f(-l2f), zb0 = exp2f((float)o0 * l2b), zbs = exp2f(l2b);
; #pragma unroll
;             for (int m = 0; m < 4; ++m) {
;                 const int r = rbase + ai * 128 + m * 16;
;                 const int d = 4 * (2 * m + (fr >> 3)) + j;
; #pragma unroll
;                 for (int bj = 0; bj < 2; ++bj) {
;                     const int t0 = tb + bj * 128;
;                     float v[8];
; #pragma unroll
;                     for (int jj = 0; jj < 4; ++jj) { v[jj] = acc[ai][bj][m][0][jj]; v[4 + jj] = acc[ai][bj][m][1][jj]; }
;                     if constexpr (ROPE) {
;                         const int t = t0 & 2047;
; #pragma unroll
;                         for (int hf = 0; hf < 2; ++hf) {
;                             f32x4 cs, sn;
;                             if (m < 2) { const float c1 = ropeA[(t >> 6) * 16 + d], s1 = ropeA[1024 + (t >> 6) * 16 + d]; cs = (f32x4){c1, c1, c1, c1}; sn = (f32x4){s1, s1, s1, s1}; }
;                             else { const float* cb = ropeA + 2048 + (d - 16) * 64 + (t & 63) + 4 * hf; cs = *(const f32x4*)(cb); sn = *(const f32x4*)(cb + 1024); }
; #pragma unroll
;                             for (int jj = 0; jj < 4; ++jj) { const float pr = __shfl_xor(v[4 * hf + jj], 4); v[4 * hf + jj] = v[4 * hf + jj] * cs[jj] + sgn * pr * sn[jj]; }
;                             __builtin_amdgcn_sched_barrier(0);
;                         }
;                     }
;                     float zf[8], zb[8]; zf[0] = zf0; zb[0] = zb0;
; #pragma unroll
;                     for (int jj = 1; jj < 8; ++jj) { zf[jj] = zf[jj - 1] * zfs; zb[jj] = zb[jj - 1] * zbs; }
;                     u32x4 wf, wb;
;                     wf.x = cvt_pk_bf16(v[0] * zf[0], v[1] * zf[1]); wf.y = cvt_pk_bf16(v[2] * zf[2], v[3] * zf[3]); wf.z = cvt_pk_bf16(v[4] * zf[4], v[5] * zf[5]); wf.w = cvt_pk_bf16(v[6] * zf[6], v[7] * zf[7]);
	v_mov_b32_e32 v90, v84
	v_mov_b32_e32 v68, v65
	v_mov_b32_e32 v100, v85
	v_mov_b32_e32 v65, v70
	v_mov_b32_e32 v102, v86
	v_mov_b32_e32 v70, v67
	v_mov_b32_e32 v108, v87
	v_pk_mul_f32 v[66:67], v[88:89], v[90:91]
	v_pk_mul_f32 v[68:69], v[68:69], v[100:101]
	v_pk_mul_f32 v[64:65], v[64:65], v[102:103]
	v_pk_mul_f32 v[70:71], v[70:71], v[108:109]
	v_add_f32_e32 v84, v66, v67
	v_add_f32_e32 v85, v68, v69
	v_add_f32_e32 v86, v64, v65
	v_add_f32_e32 v71, v70, v71
	v_mul_f32_e32 v64, v180, v110
	v_mul_f32_e32 v65, v181, v111
	v_cvt_pk_bf16_f32 v64, v64, v65
	v_mul_f32_e32 v65, v167, v116
	v_mul_f32_e32 v66, v183, v117
	v_cvt_pk_bf16_f32 v65, v65, v66
	v_mul_f32_e32 v66, v182, v84
	v_mul_f32_e32 v67, v185, v85
	v_cvt_pk_bf16_f32 v66, v66, v67
	v_mul_f32_e32 v67, v184, v86
	v_mul_f32_e32 v68, v159, v71
	v_cvt_pk_bf16_f32 v67, v67, v68
	v_mul_f32_e32 v68, v150, v110
	v_mul_f32_e32 v69, v152, v111
	v_cvt_pk_bf16_f32 v68, v68, v69
	v_mul_f32_e32 v69, v154, v116
	v_mul_f32_e32 v70, v156, v117
	v_cvt_pk_bf16_f32 v69, v69, v70
	v_mul_f32_e32 v70, v158, v84
	v_mul_f32_e32 v84, v160, v85
	v_mul_f32_e32 v71, v155, v71
	v_cvt_pk_bf16_f32 v70, v70, v84
	v_mul_f32_e32 v84, v151, v86
	v_cvt_pk_bf16_f32 v71, v84, v71
	global_store_dwordx4 v[72:73], v[64:67], off offset:256
	global_store_dwordx4 v[74:75], v[68:71], off offset:256
	global_load_dword v64, v137, s[22:23] offset:8
	s_nop 0
	global_load_dword v70, v137, s[22:23] offset:24
	global_load_dword v67, v[146:147], off
	global_load_dword v74, v[148:149], off
	ds_bpermute_b32 v65, v177, v60
	ds_bpermute_b32 v68, v177, v62
	v_mov_b32_e32 v66, v60
	ds_bpermute_b32 v60, v177, v61
	ds_bpermute_b32 v71, v177, v63
	s_waitcnt lgkmcnt(3)
	v_cndmask_b32_e64 v75, v65, -v65, vcc
	s_waitcnt lgkmcnt(2)
	v_cndmask_b32_e64 v65, v68, -v68, vcc
	s_waitcnt vmcnt(3)
	v_mul_f32_e32 v72, 0x3fb8aa3b, v64
	s_waitcnt vmcnt(2)
	v_mul_f32_e32 v73, 0x3fb8aa3b, v70
	v_mul_f32_e32 v84, v72, v179
	s_waitcnt vmcnt(0)
	v_pk_mul_f32 v[68:69], v[66:67], v[74:75]
	s_waitcnt lgkmcnt(1)
	v_cndmask_b32_e64 v75, v60, -v60, vcc
	v_mov_b32_e32 v66, v61
	v_cmp_lt_f32_e64 s[4:5], s60, v72
	v_mul_f32_e32 v87, v73, v178
	v_pk_mul_f32 v[60:61], v[66:67], v[74:75]
	s_waitcnt lgkmcnt(0)
	v_cndmask_b32_e64 v75, v71, -v71, vcc
	v_mov_b32_e32 v66, v63
	v_cmp_gt_f32_e64 s[8:9], s59, v84
	v_cndmask_b32_e64 v86, 0, v176, s[4:5]
	v_cmp_gt_f32_e64 s[6:7], s59, v73
	s_and_b64 s[0:1], s[4:5], exec
	v_cmp_gt_f32_e64 s[4:5], s59, v87
	v_add_f32_e32 v110, v60, v61
	v_pk_mul_f32 v[60:61], v[66:67], v[74:75]
	v_cndmask_b32_e64 v66, 0, v176, s[8:9]
	v_cndmask_b32_e64 v88, 0, v176, s[6:7]
	v_add_f32_e32 v89, v68, v69
	v_fmac_f32_e32 v86, 0xbfb8aa3b, v64
	v_cndmask_b32_e64 v69, 0, v176, s[4:5]
	v_fmac_f32_e32 v66, v72, v179
	v_fmac_f32_e32 v88, 0x3fb8aa3b, v70
	v_exp_f32_e32 v68, v86
	v_fmac_f32_e32 v69, v73, v178
	v_exp_f32_e32 v66, v66
	v_exp_f32_e32 v70, v88
	v_exp_f32_e32 v69, v69
	v_cndmask_b32_e64 v63, 0, v175, s[8:9]
	s_cselect_b32 s8, 0xffffffc0, 0
	s_and_b64 s[0:1], s[6:7], exec
	v_cndmask_b32_e64 v64, 0, v175, s[4:5]
	s_cselect_b32 s0, 0xffffffc0, 0
	v_ldexp_f32 v100, v68, s8
	v_ldexp_f32 v63, v66, v63
	v_mul_f32_e32 v85, v62, v74
	v_ldexp_f32 v90, v70, s0
	v_ldexp_f32 v64, v69, v64
	v_mul_f32_e32 v75, v100, v63
	v_add_f32_e32 v111, v60, v61
	global_load_dword v108, v[148:149], off
	global_load_dword v69, v[146:147], off
	ds_bpermute_b32 v61, v177, v57
	ds_bpermute_b32 v60, v177, v56
	v_mov_b32_e32 v68, v57
	ds_bpermute_b32 v57, v177, v59
	ds_bpermute_b32 v66, v177, v58
	s_waitcnt lgkmcnt(3)
	v_cndmask_b32_e64 v109, v61, -v61, vcc
	s_waitcnt lgkmcnt(2)
	v_cndmask_b32_e64 v70, v60, -v60, vcc
	s_waitcnt lgkmcnt(0)
	v_cndmask_b32_e64 v72, v66, -v66, vcc
	s_waitcnt vmcnt(1)
	v_mul_f32_e32 v71, v56, v108
	s_waitcnt vmcnt(0)
	v_pk_mul_f32 v[60:61], v[68:69], v[108:109]
	v_cndmask_b32_e64 v109, v57, -v57, vcc
	v_mov_b32_e32 v68, v59
	v_add_f32_e32 v57, v60, v61
	v_pk_mul_f32 v[60:61], v[68:69], v[108:109]
	s_nop 0
	v_add_f32_e32 v59, v60, v61
	v_mov_b32_e32 v91, v67
	v_pk_mul_f32 v[60:61], v[90:91], v[64:65]
	v_mov_b32_e32 v91, v85
	v_pk_mul_f32 v[66:67], v[90:91], v[60:61]
	v_mov_b32_e32 v91, v69
	v_mov_b32_e32 v67, v70
	v_mul_f32_e32 v84, v100, v75
	v_pk_mul_f32 v[68:69], v[90:91], v[66:67]
	v_mov_b32_e32 v70, v90
	v_mul_f32_e32 v86, v100, v84
	v_pk_mul_f32 v[70:71], v[70:71], v[68:69]
	v_mul_f32_e32 v85, v100, v86
	v_mov_b32_e32 v71, v72
	v_mul_f32_e32 v88, v100, v85
	v_pk_mul_f32 v[72:73], v[90:91], v[70:71]
	v_fma_f32 v61, v62, v74, v61
	v_mul_f32_e32 v87, v100, v88
	v_mul_f32_e32 v65, v90, v72
	v_mul_f32_e32 v62, v84, v61
	v_fma_f32 v56, v56, v108, v69
	v_mul_f32_e32 v71, v100, v87
	v_mul_f32_e32 v67, v90, v65
	v_mul_f32_e32 v90, v63, v89
	v_mul_f32_e32 v91, v75, v110
	v_cvt_pk_bf16_f32 v100, v90, v91
	v_mul_f32_e32 v74, v86, v111
	v_cvt_pk_bf16_f32 v101, v62, v74
	v_mul_f32_e32 v62, v85, v56
	v_fma_f32 v58, v58, v108, v73
	v_mul_f32_e32 v69, v88, v57
	v_cvt_pk_bf16_f32 v102, v62, v69
	v_mul_f32_e32 v62, v87, v58
	v_mul_f32_e32 v69, v71, v59
	v_cvt_pk_bf16_f32 v103, v62, v69
	v_mul_f32_e32 v62, v64, v89
	v_mul_f32_e32 v56, v70, v56
	v_mul_f32_e32 v57, v72, v57
	v_mul_f32_e32 v69, v60, v110
	v_cvt_pk_bf16_f32 v108, v62, v69
	v_mul_f32_e32 v61, v66, v61
	v_mul_f32_e32 v62, v68, v111
	v_cvt_pk_bf16_f32 v109, v61, v62
	v_cvt_pk_bf16_f32 v110, v56, v57
	v_mul_f32_e32 v56, v65, v58
	v_mul_f32_e32 v57, v67, v59
	s_mov_b64 s[0:1], 0x1000000
	v_cvt_pk_bf16_f32 v111, v56, v57
	v_lshl_add_u64 v[56:57], v[120:121], 0, s[0:1]
	s_mov_b32 s0, 0x1000000
	v_add_co_u32_e64 v58, s[4:5], s0, v120
	s_mov_b64 s[0:1], 0x3000000
	s_nop 0
	v_addc_co_u32_e64 v59, s[4:5], 0, v121, s[4:5]
	global_store_dwordx4 v[58:59], v[100:103], off
	v_lshl_add_u64 v[58:59], v[120:121], 0, s[0:1]
	s_mov_b32 s0, 0x3000000
	v_add_co_u32_e64 v90, s[4:5], s0, v120
	s_nop 1
	v_addc_co_u32_e64 v91, s[4:5], 0, v121, s[4:5]
	global_store_dwordx4 v[90:91], v[108:111], off
	global_load_dword v91, v[122:123], off
	s_nop 0
	global_load_dword v100, v[124:125], off
	ds_bpermute_b32 v61, v177, v52
	v_mov_b32_e32 v90, v52
	ds_bpermute_b32 v52, v177, v53
	ds_bpermute_b32 v62, v177, v54
	ds_bpermute_b32 v69, v177, v55
	s_waitcnt lgkmcnt(3)
; __device__ __forceinline__ unsigned cvt_pk_bf16(float lo, float hi) { unsigned r; asm volatile("v_cvt_pk_bf16_f32 %0, %1, %2" : "=v"(r) : "v"(lo), "v"(hi)); return r; }
;     __device__ __forceinline__ void operator()(const AccT& acc, const Unit& u, int wr, int wc, int fr, int fq) const {
;     ...
;                 const int r = rbase + ai * 128 + m * 16;
;                 const int d = 4 * (2 * m + (fr >> 3)) + j;
; #pragma unroll
;                 for (int bj = 0; bj < 2; ++bj) {
;                     const int t0 = tb + bj * 128;
;                     float v[8];
; #pragma unroll
;                     for (int jj = 0; jj < 4; ++jj) { v[jj] = acc[ai][bj][m][0][jj]; v[4 + jj] = acc[ai][bj][m][1][jj]; }
;                     if constexpr (ROPE) {
;                         const int t = t0 & 2047;
; #pragma unroll
;                         for (int hf = 0; hf < 2; ++hf) {
;                             f32x4 cs, sn;
;                             if (m < 2) { const float c1 = ropeA[(t >> 6) * 16 + d], s1 = ropeA[1024 + (t >> 6) * 16 + d]; cs = (f32x4){c1, c1, c1, c1}; sn = (f32x4){s1, s1, s1, s1}; }
;                             else { const float* cb = ropeA + 2048 + (d - 16) * 64 + (t & 63) + 4 * hf; cs = *(const f32x4*)(cb); sn = *(const f32x4*)(cb + 1024); }
; #pragma unroll
;                             for (int jj = 0; jj < 4; ++jj) { const float pr = __shfl_xor(v[4 * hf + jj], 4); v[4 * hf + jj] = v[4 * hf + jj] * cs[jj] + sgn * pr * sn[jj]; }
;                             __builtin_amdgcn_sched_barrier(0);
;                         }
;                     }
;                     float zf[8], zb[8]; zf[0] = zf0; zb[0] = zb0;
; #pragma unroll
;                     for (int jj = 1; jj < 8; ++jj) { zf[jj] = zf[jj - 1] * zfs; zb[jj] = zb[jj - 1] * zbs; }
;                     u32x4 wf, wb;
;                     wf.x = cvt_pk_bf16(v[0] * zf[0], v[1] * zf[1]); wf.y = cvt_pk_bf16(v[2] * zf[2], v[3] * zf[3]); wf.z = cvt_pk_bf16(v[4] * zf[4], v[5] * zf[5]); wf.w = cvt_pk_bf16(v[6] * zf[6], v[7] * zf[7]);
;                     wb.x = cvt_pk_bf16(v[0] * zb[0], v[1] * zb[1]); wb.y = cvt_pk_bf16(v[2] * zb[2], v[3] * zb[3]); wb.z = cvt_pk_bf16(v[4] * zb[4], v[5] * zb[5]); wb.w = cvt_pk_bf16(v[6] * zb[6], v[7] * zb[7]);
;                     *(u32x4*)(KTZ + (size_t)r * NT + t0) = wf;
;                     *(u32x4*)(KTZ + (size_t)(256 + r) * NT + t0) = wb;
	v_cndmask_b32_e64 v101, v61, -v61, vcc
	s_waitcnt vmcnt(0)
	v_pk_mul_f32 v[102:103], v[90:91], v[100:101]
	s_waitcnt lgkmcnt(2)
	v_cndmask_b32_e64 v101, v52, -v52, vcc
	v_mov_b32_e32 v90, v53
	v_pk_mul_f32 v[52:53], v[90:91], v[100:101]
	s_waitcnt lgkmcnt(1)
	v_cndmask_b32_e64 v101, v62, -v62, vcc
	v_mov_b32_e32 v90, v54
	v_add_f32_e32 v62, v52, v53
	v_pk_mul_f32 v[52:53], v[90:91], v[100:101]
	s_waitcnt lgkmcnt(0)
	v_cndmask_b32_e64 v101, v69, -v69, vcc
	v_mov_b32_e32 v90, v55
	v_add_f32_e32 v69, v52, v53
	v_pk_mul_f32 v[52:53], v[90:91], v[100:101]
	v_add_f32_e32 v61, v102, v103
	v_add_f32_e32 v73, v52, v53
	global_load_dword v53, v[122:123], off
	global_load_dword v54, v[124:125], off
	ds_bpermute_b32 v55, v177, v48
	v_mov_b32_e32 v52, v48
	ds_bpermute_b32 v48, v177, v49
	ds_bpermute_b32 v74, v177, v50
	ds_bpermute_b32 v89, v177, v51
	s_waitcnt lgkmcnt(3)
	v_cndmask_b32_e64 v55, v55, -v55, vcc
	s_waitcnt vmcnt(0)
	v_pk_mul_f32 v[90:91], v[52:53], v[54:55]
	s_waitcnt lgkmcnt(2)
	v_cndmask_b32_e64 v55, v48, -v48, vcc
	v_mov_b32_e32 v52, v49
	v_pk_mul_f32 v[48:49], v[52:53], v[54:55]
	s_waitcnt lgkmcnt(1)
	v_cndmask_b32_e64 v55, v74, -v74, vcc
	v_mov_b32_e32 v52, v50
	v_add_f32_e32 v74, v48, v49
	v_pk_mul_f32 v[48:49], v[52:53], v[54:55]
	s_waitcnt lgkmcnt(0)
	v_cndmask_b32_e64 v55, v89, -v89, vcc
	v_mov_b32_e32 v52, v51
	v_add_f32_e32 v89, v48, v49
	v_pk_mul_f32 v[48:49], v[52:53], v[54:55]
	v_add_f32_e32 v90, v90, v91
	v_add_f32_e32 v55, v48, v49
	v_mul_f32_e32 v48, v63, v61
	v_mul_f32_e32 v49, v75, v62
	v_cvt_pk_bf16_f32 v48, v48, v49
	v_mul_f32_e32 v49, v84, v69
	v_mul_f32_e32 v50, v86, v73
	v_cvt_pk_bf16_f32 v49, v49, v50
	v_mul_f32_e32 v50, v85, v90
	v_mul_f32_e32 v51, v88, v74
	v_cvt_pk_bf16_f32 v50, v50, v51
	v_mul_f32_e32 v51, v87, v89
	v_mul_f32_e32 v52, v71, v55
	v_cvt_pk_bf16_f32 v51, v51, v52
	v_mul_f32_e32 v52, v64, v61
	v_mul_f32_e32 v53, v60, v62
	v_cvt_pk_bf16_f32 v52, v52, v53
	v_mul_f32_e32 v53, v66, v69
	v_mul_f32_e32 v54, v68, v73
	v_cvt_pk_bf16_f32 v53, v53, v54
	v_mul_f32_e32 v54, v70, v90
	v_mul_f32_e32 v61, v72, v74
	v_mul_f32_e32 v55, v67, v55
	v_cvt_pk_bf16_f32 v54, v54, v61
	v_mul_f32_e32 v61, v65, v89
	v_cvt_pk_bf16_f32 v55, v61, v55
	global_store_dwordx4 v[56:57], v[48:51], off offset:256
	global_store_dwordx4 v[58:59], v[52:55], off offset:256
	global_load_dword v49, v[112:113], off
	s_nop 0
	global_load_dword v50, v[114:115], off
	ds_bpermute_b32 v51, v177, v44
	v_mov_b32_e32 v48, v44
	ds_bpermute_b32 v44, v177, v45
	ds_bpermute_b32 v54, v177, v46
	ds_bpermute_b32 v55, v177, v47
	s_waitcnt lgkmcnt(3)
	v_cndmask_b32_e64 v51, v51, -v51, vcc
	s_waitcnt vmcnt(0)
	v_pk_mul_f32 v[52:53], v[48:49], v[50:51]
	s_waitcnt lgkmcnt(2)
	v_cndmask_b32_e64 v51, v44, -v44, vcc
	v_mov_b32_e32 v48, v45
	v_pk_mul_f32 v[44:45], v[48:49], v[50:51]
	s_waitcnt lgkmcnt(1)
	v_cndmask_b32_e64 v51, v54, -v54, vcc
	v_mov_b32_e32 v48, v46
	v_add_f32_e32 v52, v52, v53
	v_add_f32_e32 v53, v44, v45
	v_pk_mul_f32 v[44:45], v[48:49], v[50:51]
	s_waitcnt lgkmcnt(0)
	v_cndmask_b32_e64 v51, v55, -v55, vcc
	v_mov_b32_e32 v48, v47
	v_add_f32_e32 v54, v44, v45
	v_pk_mul_f32 v[44:45], v[48:49], v[50:51]
	s_nop 0
	v_add_f32_e32 v50, v44, v45
	global_load_dword v45, v[112:113], off
	global_load_dword v46, v[114:115], off
	ds_bpermute_b32 v47, v177, v40
	v_mov_b32_e32 v44, v40
	ds_bpermute_b32 v40, v177, v41
	ds_bpermute_b32 v51, v177, v42
	ds_bpermute_b32 v55, v177, v43
	s_waitcnt lgkmcnt(3)
	v_cndmask_b32_e64 v47, v47, -v47, vcc
	s_waitcnt vmcnt(0)
	v_pk_mul_f32 v[48:49], v[44:45], v[46:47]
	s_waitcnt lgkmcnt(2)
	v_cndmask_b32_e64 v47, v40, -v40, vcc
	v_mov_b32_e32 v44, v41
	v_pk_mul_f32 v[40:41], v[44:45], v[46:47]
	s_waitcnt lgkmcnt(1)
	v_cndmask_b32_e64 v47, v51, -v51, vcc
	v_mov_b32_e32 v44, v42
	v_add_f32_e32 v48, v48, v49
	v_add_f32_e32 v49, v40, v41
	v_pk_mul_f32 v[40:41], v[44:45], v[46:47]
	s_waitcnt lgkmcnt(0)
	v_cndmask_b32_e64 v47, v55, -v55, vcc
	v_mov_b32_e32 v44, v43
	v_add_f32_e32 v51, v40, v41
	v_pk_mul_f32 v[40:41], v[44:45], v[46:47]
	s_nop 0
	v_add_f32_e32 v40, v40, v41
	v_mul_f32_e32 v41, v63, v52
	v_mul_f32_e32 v42, v75, v53
	v_cvt_pk_bf16_f32 v42, v41, v42
	v_mul_f32_e32 v41, v84, v54
	v_mul_f32_e32 v43, v86, v50
	v_cvt_pk_bf16_f32 v43, v41, v43
	v_mul_f32_e32 v41, v85, v48
	v_mul_f32_e32 v44, v88, v49
	v_cvt_pk_bf16_f32 v44, v41, v44
	v_mul_f32_e32 v41, v87, v51
	v_mul_f32_e32 v45, v71, v40
	v_cvt_pk_bf16_f32 v45, v41, v45
	v_mul_f32_e32 v41, v64, v52
	v_mul_f32_e32 v46, v60, v53
	v_cvt_pk_bf16_f32 v46, v41, v46
	v_mul_f32_e32 v41, v66, v54
	v_mul_f32_e32 v47, v68, v50
	v_cvt_pk_bf16_f32 v47, v41, v47
	v_mul_f32_e32 v41, v70, v48
	v_mul_f32_e32 v48, v72, v49
	v_cvt_pk_bf16_f32 v48, v41, v48
	v_mul_f32_e32 v41, v65, v51
	v_mul_f32_e32 v40, v67, v40
	s_mov_b64 s[0:1], 0x1200000
	v_cvt_pk_bf16_f32 v49, v41, v40
	v_lshl_add_u64 v[40:41], v[120:121], 0, s[0:1]
	s_mov_b32 s0, 0x1200000
	v_add_co_u32_e64 v50, s[4:5], s0, v120
	s_mov_b64 s[0:1], 0x3200000
	s_nop 0
	v_addc_co_u32_e64 v51, s[4:5], 0, v121, s[4:5]
	global_store_dwordx4 v[50:51], v[42:45], off
	s_nop 1
	v_lshl_add_u64 v[42:43], v[120:121], 0, s[0:1]
	s_mov_b32 s0, 0x3200000
	v_add_co_u32_e64 v44, s[4:5], s0, v120
	s_nop 1
	v_addc_co_u32_e64 v45, s[4:5], 0, v121, s[4:5]
	global_store_dwordx4 v[44:45], v[46:49], off
	global_load_dword v45, v[104:105], off
	s_nop 0
	global_load_dword v46, v[106:107], off
	ds_bpermute_b32 v47, v177, v36
	v_mov_b32_e32 v44, v36
	ds_bpermute_b32 v36, v177, v37
	ds_bpermute_b32 v50, v177, v38
	ds_bpermute_b32 v51, v177, v39
	s_waitcnt lgkmcnt(3)
	v_cndmask_b32_e64 v47, v47, -v47, vcc
	s_waitcnt vmcnt(0)
	v_pk_mul_f32 v[48:49], v[44:45], v[46:47]
	s_waitcnt lgkmcnt(2)
; __device__ __forceinline__ unsigned cvt_pk_bf16(float lo, float hi) { unsigned r; asm volatile("v_cvt_pk_bf16_f32 %0, %1, %2" : "=v"(r) : "v"(lo), "v"(hi)); return r; }
;     __device__ __forceinline__ void operator()(const AccT& acc, const Unit& u, int wr, int wc, int fr, int fq) const {
;     ...
;                 const int r = rbase + ai * 128 + m * 16;
;                 const int d = 4 * (2 * m + (fr >> 3)) + j;
; #pragma unroll
;                 for (int bj = 0; bj < 2; ++bj) {
;                     const int t0 = tb + bj * 128;
;                     float v[8];
; #pragma unroll
;                     for (int jj = 0; jj < 4; ++jj) { v[jj] = acc[ai][bj][m][0][jj]; v[4 + jj] = acc[ai][bj][m][1][jj]; }
;                     if constexpr (ROPE) {
;                         const int t = t0 & 2047;
; #pragma unroll
;                         for (int hf = 0; hf < 2; ++hf) {
;                             f32x4 cs, sn;
;                             if (m < 2) { const float c1 = ropeA[(t >> 6) * 16 + d], s1 = ropeA[1024 + (t >> 6) * 16 + d]; cs = (f32x4){c1, c1, c1, c1}; sn = (f32x4){s1, s1, s1, s1}; }
;                             else { const float* cb = ropeA + 2048 + (d - 16) * 64 + (t & 63) + 4 * hf; cs = *(const f32x4*)(cb); sn = *(const f32x4*)(cb + 1024); }
; #pragma unroll
;                             for (int jj = 0; jj < 4; ++jj) { const float pr = __shfl_xor(v[4 * hf + jj], 4); v[4 * hf + jj] = v[4 * hf + jj] * cs[jj] + sgn * pr * sn[jj]; }
;                             __builtin_amdgcn_sched_barrier(0);
;                         }
;                     }
;                     float zf[8], zb[8]; zf[0] = zf0; zb[0] = zb0;
; #pragma unroll
;                     for (int jj = 1; jj < 8; ++jj) { zf[jj] = zf[jj - 1] * zfs; zb[jj] = zb[jj - 1] * zbs; }
;                     u32x4 wf, wb;
;                     wf.x = cvt_pk_bf16(v[0] * zf[0], v[1] * zf[1]); wf.y = cvt_pk_bf16(v[2] * zf[2], v[3] * zf[3]); wf.z = cvt_pk_bf16(v[4] * zf[4], v[5] * zf[5]); wf.w = cvt_pk_bf16(v[6] * zf[6], v[7] * zf[7]);
;                     wb.x = cvt_pk_bf16(v[0] * zb[0], v[1] * zb[1]); wb.y = cvt_pk_bf16(v[2] * zb[2], v[3] * zb[3]); wb.z = cvt_pk_bf16(v[4] * zb[4], v[5] * zb[5]); wb.w = cvt_pk_bf16(v[6] * zb[6], v[7] * zb[7]);
;                     *(u32x4*)(KTZ + (size_t)r * NT + t0) = wf;
;                     *(u32x4*)(KTZ + (size_t)(256 + r) * NT + t0) = wb;
	v_cndmask_b32_e64 v47, v36, -v36, vcc
	v_mov_b32_e32 v44, v37
	v_pk_mul_f32 v[36:37], v[44:45], v[46:47]
	s_waitcnt lgkmcnt(1)
	v_cndmask_b32_e64 v47, v50, -v50, vcc
	v_mov_b32_e32 v44, v38
	v_add_f32_e32 v48, v48, v49
	v_add_f32_e32 v49, v36, v37
	v_pk_mul_f32 v[36:37], v[44:45], v[46:47]
	s_waitcnt lgkmcnt(0)
	v_cndmask_b32_e64 v47, v51, -v51, vcc
	v_mov_b32_e32 v44, v39
	v_add_f32_e32 v50, v36, v37
	v_pk_mul_f32 v[36:37], v[44:45], v[46:47]
	s_nop 0
	v_add_f32_e32 v46, v36, v37
	global_load_dword v37, v[104:105], off
	global_load_dword v38, v[106:107], off
	ds_bpermute_b32 v39, v177, v32
	v_mov_b32_e32 v36, v32
	ds_bpermute_b32 v32, v177, v33
	ds_bpermute_b32 v47, v177, v34
	ds_bpermute_b32 v51, v177, v35
	s_waitcnt lgkmcnt(3)
	v_cndmask_b32_e64 v39, v39, -v39, vcc
	s_waitcnt vmcnt(0)
	v_pk_mul_f32 v[44:45], v[36:37], v[38:39]
	s_waitcnt lgkmcnt(2)
	v_cndmask_b32_e64 v39, v32, -v32, vcc
	v_mov_b32_e32 v36, v33
	v_pk_mul_f32 v[32:33], v[36:37], v[38:39]
	s_waitcnt lgkmcnt(1)
	v_cndmask_b32_e64 v39, v47, -v47, vcc
	v_mov_b32_e32 v36, v34
	v_add_f32_e32 v44, v44, v45
	v_add_f32_e32 v45, v32, v33
	v_pk_mul_f32 v[32:33], v[36:37], v[38:39]
	s_waitcnt lgkmcnt(0)
	v_cndmask_b32_e64 v39, v51, -v51, vcc
	v_mov_b32_e32 v36, v35
	v_add_f32_e32 v47, v32, v33
	v_pk_mul_f32 v[32:33], v[36:37], v[38:39]
	s_nop 0
	v_add_f32_e32 v39, v32, v33
	v_mul_f32_e32 v32, v63, v48
	v_mul_f32_e32 v33, v75, v49
	v_cvt_pk_bf16_f32 v32, v32, v33
	v_mul_f32_e32 v33, v84, v50
	v_mul_f32_e32 v34, v86, v46
	v_cvt_pk_bf16_f32 v33, v33, v34
	v_mul_f32_e32 v34, v85, v44
	v_mul_f32_e32 v35, v88, v45
	v_cvt_pk_bf16_f32 v34, v34, v35
	v_mul_f32_e32 v35, v87, v47
	v_mul_f32_e32 v36, v71, v39
	v_cvt_pk_bf16_f32 v35, v35, v36
	v_mul_f32_e32 v36, v64, v48
	v_mul_f32_e32 v37, v60, v49
	v_cvt_pk_bf16_f32 v36, v36, v37
	v_mul_f32_e32 v37, v66, v50
	v_mul_f32_e32 v38, v68, v46
	v_cvt_pk_bf16_f32 v37, v37, v38
	v_mul_f32_e32 v38, v70, v44
	v_mul_f32_e32 v44, v72, v45
	v_mul_f32_e32 v39, v67, v39
	v_cvt_pk_bf16_f32 v38, v38, v44
	v_mul_f32_e32 v44, v65, v47
	v_cvt_pk_bf16_f32 v39, v44, v39
	global_store_dwordx4 v[40:41], v[32:35], off offset:256
	global_store_dwordx4 v[42:43], v[36:39], off offset:256
	global_load_dwordx4 v[32:35], v[98:99], off
	s_nop 0
	global_load_dwordx4 v[36:39], v[96:97], off
	ds_bpermute_b32 v41, v177, v28
	ds_bpermute_b32 v42, v177, v29
	ds_bpermute_b32 v44, v177, v30
	ds_bpermute_b32 v46, v177, v31
	v_mov_b32_e32 v40, v28
	v_mov_b32_e32 v28, v30
	s_waitcnt lgkmcnt(3)
	v_cndmask_b32_e64 v43, v41, -v41, vcc
	s_waitcnt lgkmcnt(2)
	v_cndmask_b32_e64 v45, v42, -v42, vcc
	s_waitcnt lgkmcnt(1)
	v_cndmask_b32_e64 v47, v44, -v44, vcc
	s_waitcnt lgkmcnt(0)
	v_cndmask_b32_e64 v49, v46, -v46, vcc
	s_waitcnt vmcnt(1)
	v_mov_b32_e32 v41, v32
	s_waitcnt vmcnt(0)
	v_mov_b32_e32 v42, v36
	v_mov_b32_e32 v32, v29
	v_mov_b32_e32 v44, v37
	v_mov_b32_e32 v29, v34
	v_mov_b32_e32 v46, v38
	v_mov_b32_e32 v34, v31
	v_mov_b32_e32 v48, v39
	v_pk_mul_f32 v[30:31], v[40:41], v[42:43]
	v_pk_mul_f32 v[32:33], v[32:33], v[44:45]
	v_pk_mul_f32 v[28:29], v[28:29], v[46:47]
	v_pk_mul_f32 v[34:35], v[34:35], v[48:49]
	v_add_f32_e32 v46, v30, v31
	v_add_f32_e32 v47, v32, v33
	v_add_f32_e32 v48, v28, v29
	v_add_f32_e32 v49, v34, v35
	global_load_dwordx4 v[28:31], v[92:93], off offset:16
	global_load_dwordx4 v[32:35], v[94:95], off offset:16
	ds_bpermute_b32 v37, v177, v24
	ds_bpermute_b32 v38, v177, v25
	ds_bpermute_b32 v40, v177, v26
	ds_bpermute_b32 v42, v177, v27
	v_mov_b32_e32 v36, v24
	v_mov_b32_e32 v24, v26
	s_waitcnt lgkmcnt(3)
	v_cndmask_b32_e64 v39, v37, -v37, vcc
	s_waitcnt lgkmcnt(2)
	v_cndmask_b32_e64 v41, v38, -v38, vcc
	s_waitcnt lgkmcnt(1)
	v_cndmask_b32_e64 v43, v40, -v40, vcc
	s_waitcnt lgkmcnt(0)
	v_cndmask_b32_e64 v45, v42, -v42, vcc
	s_waitcnt vmcnt(1)
	v_mov_b32_e32 v37, v28
	s_waitcnt vmcnt(0)
	v_mov_b32_e32 v38, v32
	v_mov_b32_e32 v28, v25
	v_mov_b32_e32 v40, v33
	v_mov_b32_e32 v25, v30
	v_mov_b32_e32 v42, v34
	v_mov_b32_e32 v30, v27
	v_mov_b32_e32 v44, v35
	v_pk_mul_f32 v[26:27], v[36:37], v[38:39]
	v_pk_mul_f32 v[28:29], v[28:29], v[40:41]
	v_pk_mul_f32 v[24:25], v[24:25], v[42:43]
	v_pk_mul_f32 v[30:31], v[30:31], v[44:45]
	v_add_f32_e32 v32, v26, v27
	v_add_f32_e32 v33, v28, v29
	v_add_f32_e32 v24, v24, v25
	v_add_f32_e32 v25, v30, v31
	v_mul_f32_e32 v26, v63, v46
	v_mul_f32_e32 v27, v75, v47
	v_cvt_pk_bf16_f32 v26, v26, v27
	v_mul_f32_e32 v27, v84, v48
	v_mul_f32_e32 v28, v86, v49
	v_cvt_pk_bf16_f32 v27, v27, v28
	v_mul_f32_e32 v28, v85, v32
	v_mul_f32_e32 v29, v88, v33
	v_cvt_pk_bf16_f32 v28, v28, v29
	v_mul_f32_e32 v29, v87, v24
	v_mul_f32_e32 v30, v71, v25
	v_cvt_pk_bf16_f32 v29, v29, v30
	v_mul_f32_e32 v30, v64, v46
	v_mul_f32_e32 v31, v60, v47
	v_cvt_pk_bf16_f32 v30, v30, v31
	v_mul_f32_e32 v31, v66, v48
	v_mul_f32_e32 v32, v70, v32
	v_mul_f32_e32 v33, v72, v33
	v_mul_f32_e32 v24, v65, v24
	v_mul_f32_e32 v25, v67, v25
	s_mov_b64 s[0:1], 0x1400000
	v_mul_f32_e32 v34, v68, v49
	v_cvt_pk_bf16_f32 v31, v31, v34
	v_cvt_pk_bf16_f32 v32, v32, v33
	v_cvt_pk_bf16_f32 v33, v24, v25
	v_lshl_add_u64 v[24:25], v[120:121], 0, s[0:1]
	s_mov_b32 s0, 0x1400000
	v_add_co_u32_e64 v34, s[4:5], s0, v120
	s_mov_b64 s[0:1], 0x3400000
	s_nop 0
	v_addc_co_u32_e64 v35, s[4:5], 0, v121, s[4:5]
	global_store_dwordx4 v[34:35], v[26:29], off
	s_nop 1
	v_lshl_add_u64 v[26:27], v[120:121], 0, s[0:1]
	s_mov_b32 s0, 0x3400000
	v_add_co_u32_e64 v28, s[4:5], s0, v120
	s_nop 1
	v_addc_co_u32_e64 v29, s[4:5], 0, v121, s[4:5]
	global_store_dwordx4 v[28:29], v[30:33], off
	global_load_dwordx4 v[28:31], v[98:99], off
	s_nop 0
	global_load_dwordx4 v[32:35], v[96:97], off
	ds_bpermute_b32 v37, v177, v20
	ds_bpermute_b32 v38, v177, v21
	ds_bpermute_b32 v40, v177, v22
	ds_bpermute_b32 v42, v177, v23
	v_mov_b32_e32 v36, v20
	v_mov_b32_e32 v20, v22
	s_waitcnt lgkmcnt(3)
; __device__ __forceinline__ unsigned cvt_pk_bf16(float lo, float hi) { unsigned r; asm volatile("v_cvt_pk_bf16_f32 %0, %1, %2" : "=v"(r) : "v"(lo), "v"(hi)); return r; }
;     __device__ __forceinline__ void operator()(const AccT& acc, const Unit& u, int wr, int wc, int fr, int fq) const {
;     ...
;                         const int t = t0 & 2047;
; #pragma unroll
;                         for (int hf = 0; hf < 2; ++hf) {
;                             f32x4 cs, sn;
;                             if (m < 2) { const float c1 = ropeA[(t >> 6) * 16 + d], s1 = ropeA[1024 + (t >> 6) * 16 + d]; cs = (f32x4){c1, c1, c1, c1}; sn = (f32x4){s1, s1, s1, s1}; }
;                             else { const float* cb = ropeA + 2048 + (d - 16) * 64 + (t & 63) + 4 * hf; cs = *(const f32x4*)(cb); sn = *(const f32x4*)(cb + 1024); }
; #pragma unroll
;                             for (int jj = 0; jj < 4; ++jj) { const float pr = __shfl_xor(v[4 * hf + jj], 4); v[4 * hf + jj] = v[4 * hf + jj] * cs[jj] + sgn * pr * sn[jj]; }
;                             __builtin_amdgcn_sched_barrier(0);
;                         }
;                     }
;                     float zf[8], zb[8]; zf[0] = zf0; zb[0] = zb0;
; #pragma unroll
;                     for (int jj = 1; jj < 8; ++jj) { zf[jj] = zf[jj - 1] * zfs; zb[jj] = zb[jj - 1] * zbs; }
;                     u32x4 wf, wb;
;                     wf.x = cvt_pk_bf16(v[0] * zf[0], v[1] * zf[1]); wf.y = cvt_pk_bf16(v[2] * zf[2], v[3] * zf[3]); wf.z = cvt_pk_bf16(v[4] * zf[4], v[5] * zf[5]); wf.w = cvt_pk_bf16(v[6] * zf[6], v[7] * zf[7]);
;                     wb.x = cvt_pk_bf16(v[0] * zb[0], v[1] * zb[1]); wb.y = cvt_pk_bf16(v[2] * zb[2], v[3] * zb[3]); wb.z = cvt_pk_bf16(v[4] * zb[4], v[5] * zb[5]); wb.w = cvt_pk_bf16(v[6] * zb[6], v[7] * zb[7]);
;                     *(u32x4*)(KTZ + (size_t)r * NT + t0) = wf;
;                     *(u32x4*)(KTZ + (size_t)(256 + r) * NT + t0) = wb;
	v_cndmask_b32_e64 v39, v37, -v37, vcc
	s_waitcnt lgkmcnt(2)
	v_cndmask_b32_e64 v41, v38, -v38, vcc
	s_waitcnt lgkmcnt(1)
	v_cndmask_b32_e64 v43, v40, -v40, vcc
	s_waitcnt lgkmcnt(0)
	v_cndmask_b32_e64 v45, v42, -v42, vcc
	s_waitcnt vmcnt(1)
	v_mov_b32_e32 v37, v28
	s_waitcnt vmcnt(0)
	v_mov_b32_e32 v38, v32
	v_mov_b32_e32 v28, v21
	v_mov_b32_e32 v40, v33
	v_mov_b32_e32 v21, v30
	v_mov_b32_e32 v42, v34
	v_mov_b32_e32 v30, v23
	v_mov_b32_e32 v44, v35
	v_pk_mul_f32 v[22:23], v[36:37], v[38:39]
	v_pk_mul_f32 v[28:29], v[28:29], v[40:41]
	v_pk_mul_f32 v[20:21], v[20:21], v[42:43]
	v_pk_mul_f32 v[30:31], v[30:31], v[44:45]
	v_add_f32_e32 v42, v22, v23
	v_add_f32_e32 v43, v28, v29
	v_add_f32_e32 v44, v20, v21
	v_add_f32_e32 v45, v30, v31
	global_load_dwordx4 v[20:23], v[92:93], off offset:16
	global_load_dwordx4 v[28:31], v[94:95], off offset:16
	ds_bpermute_b32 v33, v177, v16
	ds_bpermute_b32 v34, v177, v17
	ds_bpermute_b32 v36, v177, v18
	ds_bpermute_b32 v38, v177, v19
	v_mov_b32_e32 v32, v16
	v_mov_b32_e32 v16, v18
	s_waitcnt lgkmcnt(3)
	v_cndmask_b32_e64 v35, v33, -v33, vcc
	s_waitcnt lgkmcnt(2)
	v_cndmask_b32_e64 v37, v34, -v34, vcc
	s_waitcnt lgkmcnt(1)
	v_cndmask_b32_e64 v39, v36, -v36, vcc
	s_waitcnt lgkmcnt(0)
	v_cndmask_b32_e64 v41, v38, -v38, vcc
	s_waitcnt vmcnt(1)
	v_mov_b32_e32 v33, v20
	s_waitcnt vmcnt(0)
	v_mov_b32_e32 v34, v28
	v_mov_b32_e32 v20, v17
	v_mov_b32_e32 v36, v29
	v_mov_b32_e32 v17, v22
	v_mov_b32_e32 v38, v30
	v_mov_b32_e32 v22, v19
	v_mov_b32_e32 v40, v31
	v_pk_mul_f32 v[18:19], v[32:33], v[34:35]
	v_pk_mul_f32 v[20:21], v[20:21], v[36:37]
	v_pk_mul_f32 v[16:17], v[16:17], v[38:39]
	v_pk_mul_f32 v[22:23], v[22:23], v[40:41]
	v_add_f32_e32 v28, v18, v19
	v_add_f32_e32 v29, v20, v21
	v_add_f32_e32 v30, v16, v17
	v_add_f32_e32 v23, v22, v23
	v_mul_f32_e32 v16, v63, v42
	v_mul_f32_e32 v17, v75, v43
	v_cvt_pk_bf16_f32 v16, v16, v17
	v_mul_f32_e32 v17, v84, v44
	v_mul_f32_e32 v18, v86, v45
	v_cvt_pk_bf16_f32 v17, v17, v18
	v_mul_f32_e32 v18, v85, v28
	v_mul_f32_e32 v19, v88, v29
	v_cvt_pk_bf16_f32 v18, v18, v19
	v_mul_f32_e32 v19, v87, v30
	v_mul_f32_e32 v20, v71, v23
	v_cvt_pk_bf16_f32 v19, v19, v20
	v_mul_f32_e32 v20, v64, v42
	v_mul_f32_e32 v21, v60, v43
	v_cvt_pk_bf16_f32 v20, v20, v21
	v_mul_f32_e32 v21, v66, v44
	v_mul_f32_e32 v22, v68, v45
	v_cvt_pk_bf16_f32 v21, v21, v22
	v_mul_f32_e32 v22, v70, v28
	v_mul_f32_e32 v28, v72, v29
	v_mul_f32_e32 v23, v67, v23
	v_cvt_pk_bf16_f32 v22, v22, v28
	v_mul_f32_e32 v28, v65, v30
	v_cvt_pk_bf16_f32 v23, v28, v23
	global_store_dwordx4 v[24:25], v[16:19], off offset:256
	global_store_dwordx4 v[26:27], v[20:23], off offset:256
	global_load_dwordx4 v[16:19], v[82:83], off
	s_nop 0
	global_load_dwordx4 v[20:23], v[80:81], off
	ds_bpermute_b32 v25, v177, v12
	ds_bpermute_b32 v26, v177, v13
	ds_bpermute_b32 v28, v177, v14
	ds_bpermute_b32 v30, v177, v15
	v_mov_b32_e32 v24, v12
	v_mov_b32_e32 v12, v14
	s_waitcnt lgkmcnt(3)
	v_cndmask_b32_e64 v27, v25, -v25, vcc
	s_waitcnt lgkmcnt(2)
	v_cndmask_b32_e64 v29, v26, -v26, vcc
	s_waitcnt lgkmcnt(1)
	v_cndmask_b32_e64 v31, v28, -v28, vcc
	s_waitcnt lgkmcnt(0)
	v_cndmask_b32_e64 v33, v30, -v30, vcc
	s_waitcnt vmcnt(1)
	v_mov_b32_e32 v25, v16
	s_waitcnt vmcnt(0)
	v_mov_b32_e32 v26, v20
	v_mov_b32_e32 v16, v13
	v_mov_b32_e32 v28, v21
	v_mov_b32_e32 v13, v18
	v_mov_b32_e32 v30, v22
	v_mov_b32_e32 v18, v15
	v_mov_b32_e32 v32, v23
	v_pk_mul_f32 v[14:15], v[24:25], v[26:27]
	v_pk_mul_f32 v[16:17], v[16:17], v[28:29]
	v_pk_mul_f32 v[12:13], v[12:13], v[30:31]
	v_pk_mul_f32 v[18:19], v[18:19], v[32:33]
	v_add_f32_e32 v30, v14, v15
	v_add_f32_e32 v31, v16, v17
	v_add_f32_e32 v32, v12, v13
	v_add_f32_e32 v33, v18, v19
	global_load_dwordx4 v[12:15], v[76:77], off offset:16
	global_load_dwordx4 v[16:19], v[78:79], off offset:16
	ds_bpermute_b32 v21, v177, v8
	ds_bpermute_b32 v22, v177, v9
	ds_bpermute_b32 v24, v177, v10
	ds_bpermute_b32 v26, v177, v11
	v_mov_b32_e32 v20, v8
	v_mov_b32_e32 v8, v10
	s_waitcnt lgkmcnt(3)
	v_cndmask_b32_e64 v23, v21, -v21, vcc
	s_waitcnt lgkmcnt(2)
	v_cndmask_b32_e64 v25, v22, -v22, vcc
	s_waitcnt lgkmcnt(1)
	v_cndmask_b32_e64 v27, v24, -v24, vcc
	s_waitcnt lgkmcnt(0)
	v_cndmask_b32_e64 v29, v26, -v26, vcc
	s_waitcnt vmcnt(1)
	v_mov_b32_e32 v21, v12
	s_waitcnt vmcnt(0)
; template <class Epi, class Sched>
; __device__ __forceinline__ void gemm_phase(LAS unsigned char* lds, const Gemm g, const Sched& S, const Epi& E) {
;     ...
;         if (!has_next) break;
;     __device__ __forceinline__ void operator()(const AccT& acc, const Unit& u, int wr, int wc, int fr, int fq) const {
;     ...
;                 const int r = rbase + ai * 128 + m * 16;
;                 const int d = 4 * (2 * m + (fr >> 3)) + j;
; #pragma unroll
;                 for (int bj = 0; bj < 2; ++bj) {
;                     const int t0 = tb + bj * 128;
;                     float v[8];
; #pragma unroll
;                     for (int jj = 0; jj < 4; ++jj) { v[jj] = acc[ai][bj][m][0][jj]; v[4 + jj] = acc[ai][bj][m][1][jj]; }
;                     if constexpr (ROPE) {
;                         const int t = t0 & 2047;
; #pragma unroll
;                         for (int hf = 0; hf < 2; ++hf) {
;                             f32x4 cs, sn;
;                             if (m < 2) { const float c1 = ropeA[(t >> 6) * 16 + d], s1 = ropeA[1024 + (t >> 6) * 16 + d]; cs = (f32x4){c1, c1, c1, c1}; sn = (f32x4){s1, s1, s1, s1}; }
;                             else { const float* cb = ropeA + 2048 + (d - 16) * 64 + (t & 63) + 4 * hf; cs = *(const f32x4*)(cb); sn = *(const f32x4*)(cb + 1024); }
; #pragma unroll
;                             for (int jj = 0; jj < 4; ++jj) { const float pr = __shfl_xor(v[4 * hf + jj], 4); v[4 * hf + jj] = v[4 * hf + jj] * cs[jj] + sgn * pr * sn[jj]; }
;                             __builtin_amdgcn_sched_barrier(0);
;                         }
;                     }
;                     float zf[8], zb[8]; zf[0] = zf0; zb[0] = zb0;
; #pragma unroll
;                     for (int jj = 1; jj < 8; ++jj) { zf[jj] = zf[jj - 1] * zfs; zb[jj] = zb[jj - 1] * zbs; }
;                     u32x4 wf, wb;
;                     wf.x = cvt_pk_bf16(v[0] * zf[0], v[1] * zf[1]); wf.y = cvt_pk_bf16(v[2] * zf[2], v[3] * zf[3]); wf.z = cvt_pk_bf16(v[4] * zf[4], v[5] * zf[5]); wf.w = cvt_pk_bf16(v[6] * zf[6], v[7] * zf[7]);
;                     wb.x = cvt_pk_bf16(v[0] * zb[0], v[1] * zb[1]); wb.y = cvt_pk_bf16(v[2] * zb[2], v[3] * zb[3]); wb.z = cvt_pk_bf16(v[4] * zb[4], v[5] * zb[5]); wb.w = cvt_pk_bf16(v[6] * zb[6], v[7] * zb[7]);
;                     *(u32x4*)(KTZ + (size_t)r * NT + t0) = wf;
;                     *(u32x4*)(KTZ + (size_t)(256 + r) * NT + t0) = wb;
	v_mov_b32_e32 v22, v16
	v_mov_b32_e32 v12, v9
	v_mov_b32_e32 v24, v17
	v_mov_b32_e32 v9, v14
	v_mov_b32_e32 v26, v18
	v_mov_b32_e32 v14, v11
	v_mov_b32_e32 v28, v19
	v_pk_mul_f32 v[10:11], v[20:21], v[22:23]
	v_pk_mul_f32 v[12:13], v[12:13], v[24:25]
	v_pk_mul_f32 v[8:9], v[8:9], v[26:27]
	v_pk_mul_f32 v[14:15], v[14:15], v[28:29]
	v_add_f32_e32 v16, v10, v11
	v_add_f32_e32 v17, v12, v13
	v_add_f32_e32 v8, v8, v9
	v_add_f32_e32 v9, v14, v15
	v_mul_f32_e32 v10, v63, v30
	v_mul_f32_e32 v11, v75, v31
	v_cvt_pk_bf16_f32 v10, v10, v11
	v_mul_f32_e32 v11, v84, v32
	v_mul_f32_e32 v12, v86, v33
	v_cvt_pk_bf16_f32 v11, v11, v12
	v_mul_f32_e32 v12, v85, v16
	v_mul_f32_e32 v13, v88, v17
	v_cvt_pk_bf16_f32 v12, v12, v13
	v_mul_f32_e32 v13, v87, v8
	v_mul_f32_e32 v14, v71, v9
	v_cvt_pk_bf16_f32 v13, v13, v14
	v_mul_f32_e32 v14, v64, v30
	v_mul_f32_e32 v15, v60, v31
	v_cvt_pk_bf16_f32 v14, v14, v15
	v_mul_f32_e32 v15, v66, v32
	v_mul_f32_e32 v18, v68, v33
	v_cvt_pk_bf16_f32 v15, v15, v18
	v_add_co_u32_e64 v18, s[4:5], s63, v120
	v_mul_f32_e32 v16, v70, v16
	v_mul_f32_e32 v17, v72, v17
	v_addc_co_u32_e64 v19, s[4:5], 0, v121, s[4:5]
	v_cvt_pk_bf16_f32 v16, v16, v17
	v_mul_f32_e32 v8, v65, v8
	v_mul_f32_e32 v9, v67, v9
	v_cvt_pk_bf16_f32 v17, v8, v9
	global_store_dwordx4 v[18:19], v[10:13], off
	v_lshl_add_u64 v[8:9], v[120:121], 0, s[26:27]
	s_nop 0
	v_add_co_u32_e64 v12, s[4:5], s64, v120
	v_lshl_add_u64 v[10:11], v[120:121], 0, s[28:29]
	s_nop 0
	v_addc_co_u32_e64 v13, s[4:5], 0, v121, s[4:5]
	global_store_dwordx4 v[12:13], v[14:17], off
	global_load_dwordx4 v[12:15], v[82:83], off
	s_nop 0
	global_load_dwordx4 v[16:19], v[80:81], off
	ds_bpermute_b32 v34, v177, v4
	ds_bpermute_b32 v32, v177, v5
	ds_bpermute_b32 v33, v177, v6
	ds_bpermute_b32 v28, v177, v7
	global_load_dwordx4 v[20:23], v[76:77], off offset:16
	global_load_dwordx4 v[24:27], v[78:79], off offset:16
	s_waitcnt lgkmcnt(0)
	v_cndmask_b32_e64 v29, v28, -v28, vcc
	v_mov_b32_e32 v30, v7
	s_waitcnt vmcnt(3)
	v_mov_b32_e32 v31, v15
	s_waitcnt vmcnt(2)
	v_mov_b32_e32 v28, v19
	v_cndmask_b32_e64 v19, v33, -v33, vcc
	v_mov_b32_e32 v7, v14
	v_cndmask_b32_e64 v15, v32, -v32, vcc
	v_mov_b32_e32 v32, v5
	v_mov_b32_e32 v33, v13
	v_mov_b32_e32 v14, v17
	v_cndmask_b32_e64 v17, v34, -v34, vcc
	v_mov_b32_e32 v5, v12
	ds_bpermute_b32 v13, v177, v0
	v_mov_b32_e32 v12, v0
	ds_bpermute_b32 v34, v177, v1
	ds_bpermute_b32 v35, v177, v2
	v_mov_b32_e32 v0, v2
	ds_bpermute_b32 v2, v177, v3
	v_pk_mul_f32 v[28:29], v[30:31], v[28:29]
	v_pk_mul_f32 v[6:7], v[6:7], v[18:19]
	v_pk_mul_f32 v[14:15], v[32:33], v[14:15]
	v_pk_mul_f32 v[4:5], v[4:5], v[16:17]
	v_add_f32_e32 v18, v28, v29
	v_add_f32_e32 v19, v6, v7
	v_add_f32_e32 v28, v14, v15
	v_add_f32_e32 v29, v4, v5
	s_waitcnt lgkmcnt(3)
	v_cndmask_b32_e64 v5, v13, -v13, vcc
	s_waitcnt lgkmcnt(2)
	v_cndmask_b32_e64 v7, v34, -v34, vcc
	s_waitcnt lgkmcnt(1)
	v_cndmask_b32_e64 v15, v35, -v35, vcc
	s_waitcnt lgkmcnt(0)
	v_cndmask_b32_e64 v17, v2, -v2, vcc
	s_waitcnt vmcnt(1)
	v_mov_b32_e32 v13, v20
	s_waitcnt vmcnt(0)
	v_mov_b32_e32 v4, v24
	v_mov_b32_e32 v20, v1
	v_mov_b32_e32 v6, v25
	v_mov_b32_e32 v1, v22
	v_mov_b32_e32 v14, v26
	v_mov_b32_e32 v22, v3
	v_mov_b32_e32 v16, v27
	v_pk_mul_f32 v[2:3], v[12:13], v[4:5]
	v_pk_mul_f32 v[4:5], v[20:21], v[6:7]
	v_pk_mul_f32 v[0:1], v[0:1], v[14:15]
	v_pk_mul_f32 v[6:7], v[22:23], v[16:17]
	v_add_f32_e32 v12, v2, v3
	v_add_f32_e32 v13, v4, v5
	v_add_f32_e32 v14, v0, v1
	v_add_f32_e32 v7, v6, v7
	v_mul_f32_e32 v0, v63, v29
	v_mul_f32_e32 v1, v75, v28
	v_cvt_pk_bf16_f32 v0, v0, v1
	v_mul_f32_e32 v1, v84, v19
	v_mul_f32_e32 v2, v86, v18
	v_cvt_pk_bf16_f32 v1, v1, v2
	v_mul_f32_e32 v2, v85, v12
	v_mul_f32_e32 v3, v88, v13
	v_cvt_pk_bf16_f32 v2, v2, v3
	v_mul_f32_e32 v3, v87, v14
	v_mul_f32_e32 v4, v71, v7
	v_cvt_pk_bf16_f32 v3, v3, v4
	v_mul_f32_e32 v4, v64, v29
	v_mul_f32_e32 v5, v60, v28
	v_cvt_pk_bf16_f32 v4, v4, v5
	v_mul_f32_e32 v5, v66, v19
	v_mul_f32_e32 v6, v68, v18
	v_cvt_pk_bf16_f32 v5, v5, v6
	v_mul_f32_e32 v6, v70, v12
	v_mul_f32_e32 v12, v72, v13
	v_mul_f32_e32 v7, v67, v7
	v_cvt_pk_bf16_f32 v6, v6, v12
	v_mul_f32_e32 v12, v65, v14
	v_cvt_pk_bf16_f32 v7, v12, v7
	global_store_dwordx4 v[8:9], v[0:3], off offset:256
	global_store_dwordx4 v[10:11], v[4:7], off offset:256
	s_and_b64 vcc, exec, s[2:3]
	s_mov_b32 s33, s30
	s_mov_b64 s[4:5], s[38:39]
	s_mov_b64 s[0:1], s[36:37]
	s_cbranch_vccz .LBB0_606
	s_waitcnt vmcnt(0)
	s_cmpk_gt_u32 s42, 0xff
	s_cbranch_scc1 .LBB0_617
	s_barrier

; #define PG8_STAGE(bufoff, gbase, voff) do { _Pragma("unroll") for (int _i = 0; _i < 2; ++_i) \
;         __builtin_amdgcn_global_load_lds((const unsigned*)((const char*)(gbase) + (voff)[_i]), (LAS unsigned*)(lds + (bufoff) + ldsw + _i * 8192), 16, 0, 0); } while (0)
; #define PG8_LDA(dst, b, h) do { _Pragma("unroll") for (int m = 0; m < 4; ++m) _Pragma("unroll") for (int k = 0; k < 2; ++k) dst[m][k] = *(const LAS bf16x8*)(lds + PG8_SA(b, h) + aoff + m * 2048 + k * 1024); } while (0)
; #define PG8_LDB(dst, b, h) do { _Pragma("unroll") for (int n = 0; n < 2; ++n) _Pragma("unroll") for (int k = 0; k < 2; ++k) dst[n][k] = *(const LAS bf16x8*)(lds + PG8_SB(b, h) + boff + n * 2048 + k * 1024); } while (0)
; #define PG8_MMA(ai, bj, At, Bt) do { __builtin_amdgcn_s_setprio(1); _Pragma("unroll") for (int m = 0; m < 4; ++m) _Pragma("unroll") for (int n = 0; n < 2; ++n) _Pragma("unroll") for (int k = 0; k < 2; ++k) \
;         acc[ai][bj][m][n] = __builtin_amdgcn_mfma_f32_16x16x32_bf16(Bt[n][k], At[m][k], acc[ai][bj][m][n], 0, 0, 0); __builtin_amdgcn_s_setprio(0); } while (0)
; #define PG8_WAIT_L(n) asm volatile("s_waitcnt lgkmcnt(" #n ")" ::: "memory")
; template <class Epi, class Sched>
; __device__ __forceinline__ void gemm_phase(LAS unsigned char* lds, const Gemm g, const Sched& S, const Epi& E) {
;     ...
;         const bool has_next = S.next(ui + 1, nxt);
;         const char* nA = has_next ? (const char*)g.A + (size_t)nxt.pm * tstep : cA; const char* nB = has_next ? (const char*)g.Bt + (size_t)nxt.pn * tstep : cB;
;         for (int t = 0; t < nt; t += 2) {
;             const bool last = (t == nt - 2);
;             const char* a1 = cA + (size_t)(t + 1) * kstep;
;             const char* a2 = last ? nA : cA + (size_t)(t + 2) * kstep; const char* b2 = last ? nB : cB + (size_t)(t + 2) * kstep;
;             const char* a3 = a2 + kstep; const char* b3 = b2 + kstep;
;             PG8_LDB(B0, 0, 0); PG8_SCHED; PG8_LDA(At, 0, 0); PG8_STAGE(PG8_SA(1, 1), a1 + hstep, voffA);
;             PG8_WAIT_L(8); PG8_BAR; PG8_WAIT_L(0); PG8_MMA(0, 0, At, B0); PG8_BAR; PG8_SCHED;
;             PG8_LDB(B1, 0, 1); PG8_STAGE(PG8_SB(0, 0), b2, voffB);
;             PG8_BAR; PG8_WAIT_L(0); PG8_MMA(0, 1, At, B1); PG8_BAR;
;             PG8_LDA(At, 0, 1); PG8_STAGE(PG8_SA(0, 0), a2, voffA);
;             PG8_BAR; PG8_WAIT_L(0); PG8_MMA(1, 0, At, B0); PG8_BAR; PG8_SCHED;
.LBB0_632:
	s_ashr_i32 s23, s22, 31
	v_cmp_lt_i64_e32 vcc, s[24:25], v[140:141]
	s_lshl_b64 s[24:25], s[22:23], 19
	s_add_u32 s24, s38, s24
	s_addc_u32 s25, s39, s25
	s_and_b64 s[26:27], vcc, exec
	s_cselect_b32 s23, s25, s31
	s_cselect_b32 s61, s24, s30
	s_ashr_i32 s21, s20, 31
	s_lshl_b64 s[26:27], s[20:21], 19
	s_add_u32 s26, s96, s26
	s_addc_u32 s27, s97, s27
	s_and_b64 s[36:37], vcc, exec
	s_cselect_b32 s21, s27, s35
	s_cselect_b32 s62, s26, s34
	s_add_u32 s30, s30, 0x40080
	s_addc_u32 s31, s31, 0
	s_add_u32 s63, s34, 0x100
	s_addc_u32 s64, s35, 0
	s_mov_b32 s65, -2
	s_waitcnt lgkmcnt(0)
	ds_read_b128 v[150:153], v147
	ds_read_b128 v[154:157], v147 offset:1024
	ds_read_b128 v[158:161], v147 offset:2048
	ds_read_b128 v[162:165], v147 offset:3072
	s_add_u32 s34, s30, 0xfffc0080
	s_addc_u32 s35, s31, -1
	s_cmp_eq_u32 s65, 12
	s_cselect_b32 s37, s23, s35
	s_cselect_b32 s36, s61, s34
	s_cselect_b32 s35, s21, s64
	s_cselect_b32 s34, s62, s63
	s_add_i32 m0, s29, 0xc000
	ds_read_b128 v[166:169], v148
	ds_read_b128 v[170:173], v148 offset:1024
	ds_read_b128 v[174:177], v148 offset:2048
	ds_read_b128 v[178:181], v148 offset:3072
	ds_read_b128 v[182:185], v148 offset:4096
	ds_read_b128 v[186:189], v148 offset:5120
	ds_read_b128 v[190:193], v148 offset:6144
	ds_read_b128 v[194:197], v148 offset:7168
	global_load_lds_dwordx4 v136, s[30:31]
	s_add_i32 m0, s29, 0xe000
	s_nop 0
	global_load_lds_dwordx4 v138, s[30:31]
	s_waitcnt vmcnt(10)
	s_barrier
	s_waitcnt lgkmcnt(0)
	s_setprio 1
	s_waitcnt lgkmcnt(0)
	v_mfma_f32_16x16x32_bf16 v[124:127], v[150:153], v[166:169], 0
	v_mfma_f32_16x16x32_bf16 v[120:123], v[158:161], v[166:169], 0
	v_mfma_f32_16x16x32_bf16 v[116:119], v[150:153], v[174:177], 0
	v_mfma_f32_16x16x32_bf16 v[108:111], v[158:161], v[174:177], 0
	v_mfma_f32_16x16x32_bf16 v[100:103], v[150:153], v[182:185], 0
	v_mfma_f32_16x16x32_bf16 v[92:95], v[158:161], v[182:185], 0
	v_mfma_f32_16x16x32_bf16 v[84:87], v[150:153], v[190:193], 0
	v_mfma_f32_16x16x32_bf16 v[76:79], v[158:161], v[190:193], 0
	v_mfma_f32_16x16x32_bf16 v[124:127], v[154:157], v[170:173], v[124:127]
	v_mfma_f32_16x16x32_bf16 v[120:123], v[162:165], v[170:173], v[120:123]
	v_mfma_f32_16x16x32_bf16 v[116:119], v[154:157], v[178:181], v[116:119]
	v_mfma_f32_16x16x32_bf16 v[108:111], v[162:165], v[178:181], v[108:111]
	v_mfma_f32_16x16x32_bf16 v[100:103], v[154:157], v[186:189], v[100:103]
	v_mfma_f32_16x16x32_bf16 v[92:95], v[162:165], v[186:189], v[92:95]
	v_mfma_f32_16x16x32_bf16 v[84:87], v[154:157], v[194:197], v[84:87]
	v_mfma_f32_16x16x32_bf16 v[76:79], v[162:165], v[194:197], v[76:79]
	s_setprio 0
	s_barrier
	s_add_i32 s66, s54, s43
	s_mov_b32 m0, s66
	ds_read_b128 v[202:205], v149
	ds_read_b128 v[206:209], v149 offset:1024
	ds_read_b128 v[210:213], v149 offset:2048
	ds_read_b128 v[214:217], v149 offset:3072
	global_load_lds_dwordx4 v130, s[34:35]
	s_add_i32 m0, s66, 0x2000
	s_nop 0
	global_load_lds_dwordx4 v134, s[34:35]
	s_waitcnt vmcnt(10)
	s_barrier
	s_waitcnt lgkmcnt(0)
	s_setprio 1
	s_waitcnt lgkmcnt(0)
	v_mfma_f32_16x16x32_bf16 v[112:115], v[202:205], v[166:169], 0
	v_mfma_f32_16x16x32_bf16 v[104:107], v[210:213], v[166:169], 0
	v_mfma_f32_16x16x32_bf16 v[96:99], v[202:205], v[174:177], 0
	v_mfma_f32_16x16x32_bf16 v[88:91], v[210:213], v[174:177], 0
	v_mfma_f32_16x16x32_bf16 v[80:83], v[202:205], v[182:185], 0
	v_mfma_f32_16x16x32_bf16 v[72:75], v[210:213], v[182:185], 0
	v_mfma_f32_16x16x32_bf16 v[68:71], v[202:205], v[190:193], 0
	v_mfma_f32_16x16x32_bf16 v[64:67], v[210:213], v[190:193], 0
	v_mfma_f32_16x16x32_bf16 v[112:115], v[206:209], v[170:173], v[112:115]
	v_mfma_f32_16x16x32_bf16 v[104:107], v[214:217], v[170:173], v[104:107]
	v_mfma_f32_16x16x32_bf16 v[96:99], v[206:209], v[178:181], v[96:99]
	v_mfma_f32_16x16x32_bf16 v[88:91], v[214:217], v[178:181], v[88:91]
	v_mfma_f32_16x16x32_bf16 v[80:83], v[206:209], v[186:189], v[80:83]
	v_mfma_f32_16x16x32_bf16 v[72:75], v[214:217], v[186:189], v[72:75]
	v_mfma_f32_16x16x32_bf16 v[68:71], v[206:209], v[194:197], v[68:71]
	v_mfma_f32_16x16x32_bf16 v[64:67], v[214:217], v[194:197], v[64:67]
	s_setprio 0
	s_mov_b32 m0, s29
	v_lshl_add_u64 v[220:221], s[36:37], 0, v[128:129]
	s_barrier
	ds_read_b128 v[166:169], v148 offset:16384
	ds_read_b128 v[170:173], v148 offset:17408
	ds_read_b128 v[174:177], v148 offset:18432
	ds_read_b128 v[178:181], v148 offset:19456
	ds_read_b128 v[182:185], v148 offset:20480
	ds_read_b128 v[186:189], v148 offset:21504
	ds_read_b128 v[190:193], v148 offset:22528
	ds_read_b128 v[194:197], v148 offset:23552
	global_load_lds_dwordx4 v128, s[36:37]
	v_lshl_add_u64 v[222:223], s[36:37], 0, v[132:133]
	s_mov_b32 m0, s44
	s_nop 0
	global_load_lds_dwordx4 v132, s[36:37]
	s_barrier
	s_waitcnt lgkmcnt(0)
	s_setprio 1
	s_waitcnt lgkmcnt(0)
	v_mfma_f32_16x16x32_bf16 v[60:63], v[150:153], v[166:169], 0
	v_mfma_f32_16x16x32_bf16 v[56:59], v[158:161], v[166:169], 0
	v_mfma_f32_16x16x32_bf16 v[52:55], v[150:153], v[174:177], 0
	v_mfma_f32_16x16x32_bf16 v[44:47], v[158:161], v[174:177], 0
	v_mfma_f32_16x16x32_bf16 v[36:39], v[150:153], v[182:185], 0
	v_mfma_f32_16x16x32_bf16 v[28:31], v[158:161], v[182:185], 0
	v_mfma_f32_16x16x32_bf16 v[20:23], v[150:153], v[190:193], 0
	v_mfma_f32_16x16x32_bf16 v[12:15], v[158:161], v[190:193], 0
	v_mfma_f32_16x16x32_bf16 v[60:63], v[154:157], v[170:173], v[60:63]
	v_mfma_f32_16x16x32_bf16 v[56:59], v[162:165], v[170:173], v[56:59]
	v_mfma_f32_16x16x32_bf16 v[52:55], v[154:157], v[178:181], v[52:55]
	v_mfma_f32_16x16x32_bf16 v[44:47], v[162:165], v[178:181], v[44:47]
	v_mfma_f32_16x16x32_bf16 v[36:39], v[154:157], v[186:189], v[36:39]
	v_mfma_f32_16x16x32_bf16 v[28:31], v[162:165], v[186:189], v[28:31]
	v_mfma_f32_16x16x32_bf16 v[20:23], v[154:157], v[194:197], v[20:23]
	v_mfma_f32_16x16x32_bf16 v[12:15], v[162:165], v[194:197], v[12:15]
	s_setprio 0
	s_barrier
; #define PG8_STAGE(bufoff, gbase, voff) do { _Pragma("unroll") for (int _i = 0; _i < 2; ++_i) \
;         __builtin_amdgcn_global_load_lds((const unsigned*)((const char*)(gbase) + (voff)[_i]), (LAS unsigned*)(lds + (bufoff) + ldsw + _i * 8192), 16, 0, 0); } while (0)
; #define PG8_LDA(dst, b, h) do { _Pragma("unroll") for (int m = 0; m < 4; ++m) _Pragma("unroll") for (int k = 0; k < 2; ++k) dst[m][k] = *(const LAS bf16x8*)(lds + PG8_SA(b, h) + aoff + m * 2048 + k * 1024); } while (0)
; #define PG8_LDB(dst, b, h) do { _Pragma("unroll") for (int n = 0; n < 2; ++n) _Pragma("unroll") for (int k = 0; k < 2; ++k) dst[n][k] = *(const LAS bf16x8*)(lds + PG8_SB(b, h) + boff + n * 2048 + k * 1024); } while (0)
; #define PG8_MMA(ai, bj, At, Bt) do { __builtin_amdgcn_s_setprio(1); _Pragma("unroll") for (int m = 0; m < 4; ++m) _Pragma("unroll") for (int n = 0; n < 2; ++n) _Pragma("unroll") for (int k = 0; k < 2; ++k) \
;         acc[ai][bj][m][n] = __builtin_amdgcn_mfma_f32_16x16x32_bf16(Bt[n][k], At[m][k], acc[ai][bj][m][n], 0, 0, 0); __builtin_amdgcn_s_setprio(0); } while (0)
; #define PG8_WAIT_V(n) asm volatile("s_waitcnt vmcnt(" #n ")" ::: "memory")
; #define PG8_WAIT_L(n) asm volatile("s_waitcnt lgkmcnt(" #n ")" ::: "memory")
; #define PG8_BAR __builtin_amdgcn_s_barrier()
; #define PG8_SCHED __builtin_amdgcn_sched_barrier(0)
; template <class Epi, class Sched>
; __device__ __forceinline__ void gemm_phase(LAS unsigned char* lds, const Gemm g, const Sched& S, const Epi& E) {
;     ...
;             PG8_STAGE(PG8_SB(0, 1), b2 + hstep, voffB);
;             PG8_WAIT_V(6); PG8_BAR; PG8_MMA(1, 1, At, B1); PG8_BAR;
;             PG8_LDB(B0, 1, 0); PG8_SCHED; PG8_LDA(At, 1, 0); PG8_STAGE(PG8_SA(0, 1), a2 + hstep, voffA);
;             PG8_WAIT_L(8); PG8_BAR; PG8_WAIT_L(0); PG8_MMA(0, 0, At, B0); PG8_BAR; PG8_SCHED;
;             PG8_LDB(B1, 1, 1); PG8_STAGE(PG8_SB(1, 0), b3, voffB);
;             PG8_BAR; PG8_WAIT_L(0); PG8_MMA(0, 1, At, B1); PG8_BAR;
;             PG8_LDA(At, 1, 1); PG8_STAGE(PG8_SA(1, 0), a3, voffA);
;             PG8_BAR; PG8_WAIT_L(0); PG8_MMA(1, 0, At, B0); PG8_BAR; PG8_SCHED;
	s_add_u32 s66, s34, 0x40000
	s_addc_u32 s67, s35, 0
	s_add_i32 s68, s55, s43
	s_mov_b32 m0, s68
	s_nop 0
	global_load_lds_dwordx4 v130, s[66:67]
	s_add_i32 m0, s68, 0x2000
	s_nop 0
	global_load_lds_dwordx4 v134, s[66:67]
	s_add_u32 s36, s36, 0x40000
	s_addc_u32 s37, s37, 0
	s_mov_b32 m0, s45
	s_nop 0
	global_load_lds_dwordx4 v128, s[36:37]
	s_mov_b32 m0, s46
	s_nop 0
	global_load_lds_dwordx4 v132, s[36:37]
	s_waitcnt vmcnt(12)
	s_barrier
	s_setprio 1
	v_mfma_f32_16x16x32_bf16 v[48:51], v[202:205], v[166:169], 0
	v_mfma_f32_16x16x32_bf16 v[40:43], v[210:213], v[166:169], 0
	v_mfma_f32_16x16x32_bf16 v[32:35], v[202:205], v[174:177], 0
	v_mfma_f32_16x16x32_bf16 v[24:27], v[210:213], v[174:177], 0
	v_mfma_f32_16x16x32_bf16 v[16:19], v[202:205], v[182:185], 0
	v_mfma_f32_16x16x32_bf16 v[8:11], v[210:213], v[182:185], 0
	v_mfma_f32_16x16x32_bf16 v[4:7], v[202:205], v[190:193], 0
	v_mfma_f32_16x16x32_bf16 v[0:3], v[210:213], v[190:193], 0
	v_mfma_f32_16x16x32_bf16 v[48:51], v[206:209], v[170:173], v[48:51]
	v_mfma_f32_16x16x32_bf16 v[40:43], v[214:217], v[170:173], v[40:43]
	v_mfma_f32_16x16x32_bf16 v[32:35], v[206:209], v[178:181], v[32:35]
	v_mfma_f32_16x16x32_bf16 v[24:27], v[214:217], v[178:181], v[24:27]
	v_mfma_f32_16x16x32_bf16 v[16:19], v[206:209], v[186:189], v[16:19]
	v_mfma_f32_16x16x32_bf16 v[8:11], v[214:217], v[186:189], v[8:11]
	v_mfma_f32_16x16x32_bf16 v[4:7], v[206:209], v[194:197], v[4:7]
	v_mfma_f32_16x16x32_bf16 v[0:3], v[214:217], v[194:197], v[0:3]
	s_setprio 0
	s_add_i32 s66, 0, 0x18000
	v_add_u32_e32 v162, s66, v146
	s_barrier
	ds_read_b128 v[150:153], v162
	ds_read_b128 v[154:157], v162 offset:1024
	ds_read_b128 v[158:161], v162 offset:2048
	ds_read_b128 v[162:165], v162 offset:3072
	ds_read_b128 v[166:169], v148 offset:32768
	ds_read_b128 v[170:173], v148 offset:33792
	ds_read_b128 v[174:177], v148 offset:34816
	ds_read_b128 v[178:181], v148 offset:35840
	ds_read_b128 v[182:185], v148 offset:36864
	ds_read_b128 v[186:189], v148 offset:37888
	ds_read_b128 v[190:193], v148 offset:38912
	ds_read_b128 v[194:197], v148 offset:39936
	s_waitcnt vmcnt(10)
	s_barrier
	s_waitcnt lgkmcnt(0)
	s_setprio 1
	s_waitcnt lgkmcnt(0)
	v_mfma_f32_16x16x32_bf16 v[124:127], v[150:153], v[166:169], v[124:127]
	v_mfma_f32_16x16x32_bf16 v[120:123], v[158:161], v[166:169], v[120:123]
	v_mfma_f32_16x16x32_bf16 v[116:119], v[150:153], v[174:177], v[116:119]
	v_mfma_f32_16x16x32_bf16 v[108:111], v[158:161], v[174:177], v[108:111]
	v_mfma_f32_16x16x32_bf16 v[100:103], v[150:153], v[182:185], v[100:103]
	v_mfma_f32_16x16x32_bf16 v[92:95], v[158:161], v[182:185], v[92:95]
	v_mfma_f32_16x16x32_bf16 v[84:87], v[150:153], v[190:193], v[84:87]
	v_mfma_f32_16x16x32_bf16 v[76:79], v[158:161], v[190:193], v[76:79]
	v_mfma_f32_16x16x32_bf16 v[124:127], v[154:157], v[170:173], v[124:127]
	v_mfma_f32_16x16x32_bf16 v[120:123], v[162:165], v[170:173], v[120:123]
	v_mfma_f32_16x16x32_bf16 v[116:119], v[154:157], v[178:181], v[116:119]
	v_mfma_f32_16x16x32_bf16 v[108:111], v[162:165], v[178:181], v[108:111]
	v_mfma_f32_16x16x32_bf16 v[100:103], v[154:157], v[186:189], v[100:103]
	v_mfma_f32_16x16x32_bf16 v[92:95], v[162:165], v[186:189], v[92:95]
	v_mfma_f32_16x16x32_bf16 v[84:87], v[154:157], v[194:197], v[84:87]
	v_mfma_f32_16x16x32_bf16 v[76:79], v[162:165], v[194:197], v[76:79]
	s_setprio 0
	s_barrier
	s_add_i32 s36, 0, 0x1c000
	s_add_i32 s37, s66, s43
	v_add_u32_e32 v214, s36, v146
	s_add_u32 s4, s34, 0x80
	s_addc_u32 s5, s35, 0
	s_mov_b32 m0, s37
	ds_read_b128 v[202:205], v214
	ds_read_b128 v[206:209], v214 offset:1024
	ds_read_b128 v[210:213], v214 offset:2048
	ds_read_b128 v[214:217], v214 offset:3072
	global_load_lds_dwordx4 v130, s[4:5]
	s_add_i32 m0, s37, 0x2000
	s_nop 0
	global_load_lds_dwordx4 v134, s[4:5]
	s_waitcnt vmcnt(10)
	s_barrier
	s_waitcnt lgkmcnt(0)
	s_setprio 1
	s_waitcnt lgkmcnt(0)
	v_mfma_f32_16x16x32_bf16 v[112:115], v[202:205], v[166:169], v[112:115]
	v_mfma_f32_16x16x32_bf16 v[104:107], v[210:213], v[166:169], v[104:107]
	v_mfma_f32_16x16x32_bf16 v[96:99], v[202:205], v[174:177], v[96:99]
	v_mfma_f32_16x16x32_bf16 v[88:91], v[210:213], v[174:177], v[88:91]
	v_mfma_f32_16x16x32_bf16 v[80:83], v[202:205], v[182:185], v[80:83]
	v_mfma_f32_16x16x32_bf16 v[72:75], v[210:213], v[182:185], v[72:75]
	v_mfma_f32_16x16x32_bf16 v[68:71], v[202:205], v[190:193], v[68:71]
	v_mfma_f32_16x16x32_bf16 v[64:67], v[210:213], v[190:193], v[64:67]
	v_mfma_f32_16x16x32_bf16 v[112:115], v[206:209], v[170:173], v[112:115]
	v_mfma_f32_16x16x32_bf16 v[104:107], v[214:217], v[170:173], v[104:107]
	v_mfma_f32_16x16x32_bf16 v[96:99], v[206:209], v[178:181], v[96:99]
	v_mfma_f32_16x16x32_bf16 v[88:91], v[214:217], v[178:181], v[88:91]
	v_mfma_f32_16x16x32_bf16 v[80:83], v[206:209], v[186:189], v[80:83]
	v_mfma_f32_16x16x32_bf16 v[72:75], v[214:217], v[186:189], v[72:75]
	v_mfma_f32_16x16x32_bf16 v[68:71], v[206:209], v[194:197], v[68:71]
	v_mfma_f32_16x16x32_bf16 v[64:67], v[214:217], v[194:197], v[64:67]
	s_setprio 0
	s_mov_b32 m0, s51
	s_mov_b64 s[4:5], 0x80
	v_lshl_add_u64 v[198:199], v[220:221], 0, s[4:5]
	s_barrier
	ds_read_b128 v[166:169], v148 offset:49152
	ds_read_b128 v[170:173], v148 offset:50176
	ds_read_b128 v[174:177], v148 offset:51200
	ds_read_b128 v[178:181], v148 offset:52224
	ds_read_b128 v[182:185], v148 offset:53248
	ds_read_b128 v[186:189], v148 offset:54272
	ds_read_b128 v[190:193], v148 offset:55296
	ds_read_b128 v[194:197], v148 offset:56320
	global_load_lds_dwordx4 v[198:199], off
	v_lshl_add_u64 v[198:199], v[222:223], 0, s[4:5]
	s_mov_b32 m0, s52
	s_nop 0
	global_load_lds_dwordx4 v[198:199], off
	s_barrier
; #define PG8_STAGE(bufoff, gbase, voff) do { _Pragma("unroll") for (int _i = 0; _i < 2; ++_i) \
;         __builtin_amdgcn_global_load_lds((const unsigned*)((const char*)(gbase) + (voff)[_i]), (LAS unsigned*)(lds + (bufoff) + ldsw + _i * 8192), 16, 0, 0); } while (0)
; #define PG8_LDA(dst, b, h) do { _Pragma("unroll") for (int m = 0; m < 4; ++m) _Pragma("unroll") for (int k = 0; k < 2; ++k) dst[m][k] = *(const LAS bf16x8*)(lds + PG8_SA(b, h) + aoff + m * 2048 + k * 1024); } while (0)
; #define PG8_LDB(dst, b, h) do { _Pragma("unroll") for (int n = 0; n < 2; ++n) _Pragma("unroll") for (int k = 0; k < 2; ++k) dst[n][k] = *(const LAS bf16x8*)(lds + PG8_SB(b, h) + boff + n * 2048 + k * 1024); } while (0)
; #define PG8_MMA(ai, bj, At, Bt) do { __builtin_amdgcn_s_setprio(1); _Pragma("unroll") for (int m = 0; m < 4; ++m) _Pragma("unroll") for (int n = 0; n < 2; ++n) _Pragma("unroll") for (int k = 0; k < 2; ++k) \
;         acc[ai][bj][m][n] = __builtin_amdgcn_mfma_f32_16x16x32_bf16(Bt[n][k], At[m][k], acc[ai][bj][m][n], 0, 0, 0); __builtin_amdgcn_s_setprio(0); } while (0)
; #define PG8_WAIT_V(n) asm volatile("s_waitcnt vmcnt(" #n ")" ::: "memory")
; #define PG8_WAIT_L(n) asm volatile("s_waitcnt lgkmcnt(" #n ")" ::: "memory")
; #define PG8_BAR __builtin_amdgcn_s_barrier()
; #define PG8_SCHED __builtin_amdgcn_sched_barrier(0)
; template <class Epi, class Sched>
; __device__ __forceinline__ void gemm_phase(LAS unsigned char* lds, const Gemm g, const Sched& S, const Epi& E) {
;     ...
;         for (int t = 0; t < nt; t += 2) {
;             const bool last = (t == nt - 2);
;             const char* a1 = cA + (size_t)(t + 1) * kstep;
;             const char* a2 = last ? nA : cA + (size_t)(t + 2) * kstep; const char* b2 = last ? nB : cB + (size_t)(t + 2) * kstep;
;             const char* a3 = a2 + kstep; const char* b3 = b2 + kstep;
;             PG8_LDB(B0, 0, 0); PG8_SCHED; PG8_LDA(At, 0, 0); PG8_STAGE(PG8_SA(1, 1), a1 + hstep, voffA);
;             PG8_WAIT_L(8); PG8_BAR; PG8_WAIT_L(0); PG8_MMA(0, 0, At, B0); PG8_BAR; PG8_SCHED;
;             PG8_LDB(B1, 0, 1); PG8_STAGE(PG8_SB(0, 0), b2, voffB);
;     ...
;             PG8_BAR; PG8_WAIT_L(0); PG8_MMA(1, 0, At, B0); PG8_BAR; PG8_SCHED;
;             PG8_STAGE(PG8_SB(1, 1), b3 + hstep, voffB);
;             PG8_WAIT_V(6); PG8_BAR; PG8_MMA(1, 1, At, B1); PG8_BAR;
	s_waitcnt lgkmcnt(0)
	s_setprio 1
	s_waitcnt lgkmcnt(0)
	v_mfma_f32_16x16x32_bf16 v[60:63], v[150:153], v[166:169], v[60:63]
	v_mfma_f32_16x16x32_bf16 v[56:59], v[158:161], v[166:169], v[56:59]
	v_mfma_f32_16x16x32_bf16 v[52:55], v[150:153], v[174:177], v[52:55]
	v_mfma_f32_16x16x32_bf16 v[44:47], v[158:161], v[174:177], v[44:47]
	v_mfma_f32_16x16x32_bf16 v[36:39], v[150:153], v[182:185], v[36:39]
	v_mfma_f32_16x16x32_bf16 v[28:31], v[158:161], v[182:185], v[28:31]
	v_mfma_f32_16x16x32_bf16 v[20:23], v[150:153], v[190:193], v[20:23]
	v_mfma_f32_16x16x32_bf16 v[12:15], v[158:161], v[190:193], v[12:15]
	v_mfma_f32_16x16x32_bf16 v[60:63], v[154:157], v[170:173], v[60:63]
	v_mfma_f32_16x16x32_bf16 v[56:59], v[162:165], v[170:173], v[56:59]
	v_mfma_f32_16x16x32_bf16 v[52:55], v[154:157], v[178:181], v[52:55]
	v_mfma_f32_16x16x32_bf16 v[44:47], v[162:165], v[178:181], v[44:47]
	v_mfma_f32_16x16x32_bf16 v[36:39], v[154:157], v[186:189], v[36:39]
	v_mfma_f32_16x16x32_bf16 v[28:31], v[162:165], v[186:189], v[28:31]
	v_mfma_f32_16x16x32_bf16 v[20:23], v[154:157], v[194:197], v[20:23]
	v_mfma_f32_16x16x32_bf16 v[12:15], v[162:165], v[194:197], v[12:15]
	s_setprio 0
	s_barrier
	s_add_u32 s34, s34, 0x40080
	s_addc_u32 s35, s35, 0
	s_add_i32 s36, s36, s43
	s_mov_b32 m0, s36
	s_nop 0
	global_load_lds_dwordx4 v130, s[34:35]
	s_add_i32 m0, s36, 0x2000
	s_nop 0
	global_load_lds_dwordx4 v134, s[34:35]
	s_waitcnt vmcnt(10)
	s_barrier
	s_setprio 1
	v_mfma_f32_16x16x32_bf16 v[48:51], v[202:205], v[166:169], v[48:51]
	v_mfma_f32_16x16x32_bf16 v[40:43], v[210:213], v[166:169], v[40:43]
	v_mfma_f32_16x16x32_bf16 v[32:35], v[202:205], v[174:177], v[32:35]
	v_mfma_f32_16x16x32_bf16 v[24:27], v[210:213], v[174:177], v[24:27]
	v_mfma_f32_16x16x32_bf16 v[16:19], v[202:205], v[182:185], v[16:19]
	v_mfma_f32_16x16x32_bf16 v[8:11], v[210:213], v[182:185], v[8:11]
	v_mfma_f32_16x16x32_bf16 v[4:7], v[202:205], v[190:193], v[4:7]
	v_mfma_f32_16x16x32_bf16 v[0:3], v[210:213], v[190:193], v[0:3]
	v_mfma_f32_16x16x32_bf16 v[48:51], v[206:209], v[170:173], v[48:51]
	v_mfma_f32_16x16x32_bf16 v[40:43], v[214:217], v[170:173], v[40:43]
	v_mfma_f32_16x16x32_bf16 v[32:35], v[206:209], v[178:181], v[32:35]
	v_mfma_f32_16x16x32_bf16 v[24:27], v[214:217], v[178:181], v[24:27]
	v_mfma_f32_16x16x32_bf16 v[16:19], v[206:209], v[186:189], v[16:19]
	v_mfma_f32_16x16x32_bf16 v[8:11], v[214:217], v[186:189], v[8:11]
	v_mfma_f32_16x16x32_bf16 v[4:7], v[206:209], v[194:197], v[4:7]
	v_mfma_f32_16x16x32_bf16 v[0:3], v[214:217], v[194:197], v[0:3]
	s_setprio 0
	s_add_i32 s65, s65, 2
	s_add_u32 s30, s30, 0x100
	s_addc_u32 s31, s31, 0
	s_add_u32 s63, s63, 0x100
	s_addc_u32 s64, s64, 0
	s_cmp_gt_u32 s65, 13
	s_barrier
.LBB0_633:
	ds_read_b128 v[150:153], v147
	ds_read_b128 v[154:157], v147 offset:1024
	ds_read_b128 v[158:161], v147 offset:2048
	ds_read_b128 v[162:165], v147 offset:3072
	s_add_u32 s34, s30, 0xfffc0080
	s_addc_u32 s35, s31, -1
	s_cmp_eq_u32 s65, 12
	s_cselect_b32 s37, s23, s35
	s_cselect_b32 s36, s61, s34
	s_cselect_b32 s35, s21, s64
	s_cselect_b32 s34, s62, s63
	s_add_i32 m0, s29, 0xc000
	ds_read_b128 v[166:169], v148
	ds_read_b128 v[170:173], v148 offset:1024
	ds_read_b128 v[174:177], v148 offset:2048
	ds_read_b128 v[178:181], v148 offset:3072
	ds_read_b128 v[182:185], v148 offset:4096
	ds_read_b128 v[186:189], v148 offset:5120
	ds_read_b128 v[190:193], v148 offset:6144
	ds_read_b128 v[194:197], v148 offset:7168
	global_load_lds_dwordx4 v136, s[30:31]
	s_add_i32 m0, s29, 0xe000
	s_nop 0
	global_load_lds_dwordx4 v138, s[30:31]
	s_waitcnt vmcnt(10)
	s_barrier
	s_waitcnt lgkmcnt(0)
	s_setprio 1
	s_waitcnt lgkmcnt(0)
	v_mfma_f32_16x16x32_bf16 v[124:127], v[150:153], v[166:169], v[124:127]
	v_mfma_f32_16x16x32_bf16 v[120:123], v[158:161], v[166:169], v[120:123]
	v_mfma_f32_16x16x32_bf16 v[116:119], v[150:153], v[174:177], v[116:119]
	v_mfma_f32_16x16x32_bf16 v[108:111], v[158:161], v[174:177], v[108:111]
	v_mfma_f32_16x16x32_bf16 v[100:103], v[150:153], v[182:185], v[100:103]
	v_mfma_f32_16x16x32_bf16 v[92:95], v[158:161], v[182:185], v[92:95]
	v_mfma_f32_16x16x32_bf16 v[84:87], v[150:153], v[190:193], v[84:87]
	v_mfma_f32_16x16x32_bf16 v[76:79], v[158:161], v[190:193], v[76:79]
	v_mfma_f32_16x16x32_bf16 v[124:127], v[154:157], v[170:173], v[124:127]
	v_mfma_f32_16x16x32_bf16 v[120:123], v[162:165], v[170:173], v[120:123]
	v_mfma_f32_16x16x32_bf16 v[116:119], v[154:157], v[178:181], v[116:119]
	v_mfma_f32_16x16x32_bf16 v[108:111], v[162:165], v[178:181], v[108:111]
	v_mfma_f32_16x16x32_bf16 v[100:103], v[154:157], v[186:189], v[100:103]
	v_mfma_f32_16x16x32_bf16 v[92:95], v[162:165], v[186:189], v[92:95]
	v_mfma_f32_16x16x32_bf16 v[84:87], v[154:157], v[194:197], v[84:87]
	v_mfma_f32_16x16x32_bf16 v[76:79], v[162:165], v[194:197], v[76:79]
	s_setprio 0
	s_barrier
	s_add_i32 s66, s54, s43
	s_mov_b32 m0, s66
	ds_read_b128 v[202:205], v149
	ds_read_b128 v[206:209], v149 offset:1024
	ds_read_b128 v[210:213], v149 offset:2048
	ds_read_b128 v[214:217], v149 offset:3072
	global_load_lds_dwordx4 v130, s[34:35]
	s_add_i32 m0, s66, 0x2000
	s_nop 0
	global_load_lds_dwordx4 v134, s[34:35]
	s_waitcnt vmcnt(10)
	s_barrier
; #define PG8_STAGE(bufoff, gbase, voff) do { _Pragma("unroll") for (int _i = 0; _i < 2; ++_i) \
;         __builtin_amdgcn_global_load_lds((const unsigned*)((const char*)(gbase) + (voff)[_i]), (LAS unsigned*)(lds + (bufoff) + ldsw + _i * 8192), 16, 0, 0); } while (0)
; #define PG8_LDA(dst, b, h) do { _Pragma("unroll") for (int m = 0; m < 4; ++m) _Pragma("unroll") for (int k = 0; k < 2; ++k) dst[m][k] = *(const LAS bf16x8*)(lds + PG8_SA(b, h) + aoff + m * 2048 + k * 1024); } while (0)
; #define PG8_LDB(dst, b, h) do { _Pragma("unroll") for (int n = 0; n < 2; ++n) _Pragma("unroll") for (int k = 0; k < 2; ++k) dst[n][k] = *(const LAS bf16x8*)(lds + PG8_SB(b, h) + boff + n * 2048 + k * 1024); } while (0)
; #define PG8_MMA(ai, bj, At, Bt) do { __builtin_amdgcn_s_setprio(1); _Pragma("unroll") for (int m = 0; m < 4; ++m) _Pragma("unroll") for (int n = 0; n < 2; ++n) _Pragma("unroll") for (int k = 0; k < 2; ++k) \
;         acc[ai][bj][m][n] = __builtin_amdgcn_mfma_f32_16x16x32_bf16(Bt[n][k], At[m][k], acc[ai][bj][m][n], 0, 0, 0); __builtin_amdgcn_s_setprio(0); } while (0)
; #define PG8_WAIT_V(n) asm volatile("s_waitcnt vmcnt(" #n ")" ::: "memory")
; #define PG8_WAIT_L(n) asm volatile("s_waitcnt lgkmcnt(" #n ")" ::: "memory")
; #define PG8_BAR __builtin_amdgcn_s_barrier()
; #define PG8_SCHED __builtin_amdgcn_sched_barrier(0)
; template <class Epi, class Sched>
; __device__ __forceinline__ void gemm_phase(LAS unsigned char* lds, const Gemm g, const Sched& S, const Epi& E) {
;     ...
;             PG8_LDB(B1, 0, 1); PG8_STAGE(PG8_SB(0, 0), b2, voffB);
;             PG8_BAR; PG8_WAIT_L(0); PG8_MMA(0, 1, At, B1); PG8_BAR;
;             PG8_LDA(At, 0, 1); PG8_STAGE(PG8_SA(0, 0), a2, voffA);
;             PG8_BAR; PG8_WAIT_L(0); PG8_MMA(1, 0, At, B0); PG8_BAR; PG8_SCHED;
;             PG8_STAGE(PG8_SB(0, 1), b2 + hstep, voffB);
;             PG8_WAIT_V(6); PG8_BAR; PG8_MMA(1, 1, At, B1); PG8_BAR;
;             PG8_LDB(B0, 1, 0); PG8_SCHED; PG8_LDA(At, 1, 0); PG8_STAGE(PG8_SA(0, 1), a2 + hstep, voffA);
;             PG8_WAIT_L(8); PG8_BAR; PG8_WAIT_L(0); PG8_MMA(0, 0, At, B0); PG8_BAR; PG8_SCHED;
	s_waitcnt lgkmcnt(0)
	s_setprio 1
	s_waitcnt lgkmcnt(0)
	v_mfma_f32_16x16x32_bf16 v[112:115], v[202:205], v[166:169], v[112:115]
	v_mfma_f32_16x16x32_bf16 v[104:107], v[210:213], v[166:169], v[104:107]
	v_mfma_f32_16x16x32_bf16 v[96:99], v[202:205], v[174:177], v[96:99]
	v_mfma_f32_16x16x32_bf16 v[88:91], v[210:213], v[174:177], v[88:91]
	v_mfma_f32_16x16x32_bf16 v[80:83], v[202:205], v[182:185], v[80:83]
	v_mfma_f32_16x16x32_bf16 v[72:75], v[210:213], v[182:185], v[72:75]
	v_mfma_f32_16x16x32_bf16 v[68:71], v[202:205], v[190:193], v[68:71]
	v_mfma_f32_16x16x32_bf16 v[64:67], v[210:213], v[190:193], v[64:67]
	v_mfma_f32_16x16x32_bf16 v[112:115], v[206:209], v[170:173], v[112:115]
	v_mfma_f32_16x16x32_bf16 v[104:107], v[214:217], v[170:173], v[104:107]
	v_mfma_f32_16x16x32_bf16 v[96:99], v[206:209], v[178:181], v[96:99]
	v_mfma_f32_16x16x32_bf16 v[88:91], v[214:217], v[178:181], v[88:91]
	v_mfma_f32_16x16x32_bf16 v[80:83], v[206:209], v[186:189], v[80:83]
	v_mfma_f32_16x16x32_bf16 v[72:75], v[214:217], v[186:189], v[72:75]
	v_mfma_f32_16x16x32_bf16 v[68:71], v[206:209], v[194:197], v[68:71]
	v_mfma_f32_16x16x32_bf16 v[64:67], v[214:217], v[194:197], v[64:67]
	s_setprio 0
	s_mov_b32 m0, s29
	v_lshl_add_u64 v[220:221], s[36:37], 0, v[128:129]
	s_barrier
	ds_read_b128 v[166:169], v148 offset:16384
	ds_read_b128 v[170:173], v148 offset:17408
	ds_read_b128 v[174:177], v148 offset:18432
	ds_read_b128 v[178:181], v148 offset:19456
	ds_read_b128 v[182:185], v148 offset:20480
	ds_read_b128 v[186:189], v148 offset:21504
	ds_read_b128 v[190:193], v148 offset:22528
	ds_read_b128 v[194:197], v148 offset:23552
	global_load_lds_dwordx4 v128, s[36:37]
	v_lshl_add_u64 v[222:223], s[36:37], 0, v[132:133]
	s_mov_b32 m0, s44
	s_nop 0
	global_load_lds_dwordx4 v132, s[36:37]
	s_barrier
	s_waitcnt lgkmcnt(0)
	s_setprio 1
	s_waitcnt lgkmcnt(0)
	v_mfma_f32_16x16x32_bf16 v[60:63], v[150:153], v[166:169], v[60:63]
	v_mfma_f32_16x16x32_bf16 v[56:59], v[158:161], v[166:169], v[56:59]
	v_mfma_f32_16x16x32_bf16 v[52:55], v[150:153], v[174:177], v[52:55]
	v_mfma_f32_16x16x32_bf16 v[44:47], v[158:161], v[174:177], v[44:47]
	v_mfma_f32_16x16x32_bf16 v[36:39], v[150:153], v[182:185], v[36:39]
	v_mfma_f32_16x16x32_bf16 v[28:31], v[158:161], v[182:185], v[28:31]
	v_mfma_f32_16x16x32_bf16 v[20:23], v[150:153], v[190:193], v[20:23]
	v_mfma_f32_16x16x32_bf16 v[12:15], v[158:161], v[190:193], v[12:15]
	v_mfma_f32_16x16x32_bf16 v[60:63], v[154:157], v[170:173], v[60:63]
	v_mfma_f32_16x16x32_bf16 v[56:59], v[162:165], v[170:173], v[56:59]
	v_mfma_f32_16x16x32_bf16 v[52:55], v[154:157], v[178:181], v[52:55]
	v_mfma_f32_16x16x32_bf16 v[44:47], v[162:165], v[178:181], v[44:47]
	v_mfma_f32_16x16x32_bf16 v[36:39], v[154:157], v[186:189], v[36:39]
	v_mfma_f32_16x16x32_bf16 v[28:31], v[162:165], v[186:189], v[28:31]
	v_mfma_f32_16x16x32_bf16 v[20:23], v[154:157], v[194:197], v[20:23]
	v_mfma_f32_16x16x32_bf16 v[12:15], v[162:165], v[194:197], v[12:15]
	s_setprio 0
	s_barrier
	s_add_u32 s66, s34, 0x40000
	s_addc_u32 s67, s35, 0
	s_add_i32 s68, s55, s43
	s_mov_b32 m0, s68
	s_nop 0
	global_load_lds_dwordx4 v130, s[66:67]
	s_add_i32 m0, s68, 0x2000
	s_nop 0
	global_load_lds_dwordx4 v134, s[66:67]
	s_add_u32 s36, s36, 0x40000
	s_addc_u32 s37, s37, 0
	s_mov_b32 m0, s45
	s_nop 0
	global_load_lds_dwordx4 v128, s[36:37]
	s_mov_b32 m0, s46
	s_nop 0
	global_load_lds_dwordx4 v132, s[36:37]
	s_waitcnt vmcnt(12)
	s_barrier
	s_setprio 1
	v_mfma_f32_16x16x32_bf16 v[48:51], v[202:205], v[166:169], v[48:51]
	v_mfma_f32_16x16x32_bf16 v[40:43], v[210:213], v[166:169], v[40:43]
	v_mfma_f32_16x16x32_bf16 v[32:35], v[202:205], v[174:177], v[32:35]
	v_mfma_f32_16x16x32_bf16 v[24:27], v[210:213], v[174:177], v[24:27]
	v_mfma_f32_16x16x32_bf16 v[16:19], v[202:205], v[182:185], v[16:19]
	v_mfma_f32_16x16x32_bf16 v[8:11], v[210:213], v[182:185], v[8:11]
	v_mfma_f32_16x16x32_bf16 v[4:7], v[202:205], v[190:193], v[4:7]
	v_mfma_f32_16x16x32_bf16 v[0:3], v[210:213], v[190:193], v[0:3]
	v_mfma_f32_16x16x32_bf16 v[48:51], v[206:209], v[170:173], v[48:51]
	v_mfma_f32_16x16x32_bf16 v[40:43], v[214:217], v[170:173], v[40:43]
	v_mfma_f32_16x16x32_bf16 v[32:35], v[206:209], v[178:181], v[32:35]
	v_mfma_f32_16x16x32_bf16 v[24:27], v[214:217], v[178:181], v[24:27]
	v_mfma_f32_16x16x32_bf16 v[16:19], v[206:209], v[186:189], v[16:19]
	v_mfma_f32_16x16x32_bf16 v[8:11], v[214:217], v[186:189], v[8:11]
	v_mfma_f32_16x16x32_bf16 v[4:7], v[206:209], v[194:197], v[4:7]
	v_mfma_f32_16x16x32_bf16 v[0:3], v[214:217], v[194:197], v[0:3]
	s_setprio 0
	s_add_i32 s66, 0, 0x18000
	v_add_u32_e32 v162, s66, v146
	s_barrier
	ds_read_b128 v[150:153], v162
	ds_read_b128 v[154:157], v162 offset:1024
	ds_read_b128 v[158:161], v162 offset:2048
	ds_read_b128 v[162:165], v162 offset:3072
	ds_read_b128 v[166:169], v148 offset:32768
	ds_read_b128 v[170:173], v148 offset:33792
	ds_read_b128 v[174:177], v148 offset:34816
	ds_read_b128 v[178:181], v148 offset:35840
	ds_read_b128 v[182:185], v148 offset:36864
	ds_read_b128 v[186:189], v148 offset:37888
	ds_read_b128 v[190:193], v148 offset:38912
	ds_read_b128 v[194:197], v148 offset:39936
	s_waitcnt vmcnt(10)
	s_barrier
; #define PG8_STAGE(bufoff, gbase, voff) do { _Pragma("unroll") for (int _i = 0; _i < 2; ++_i) \
;         __builtin_amdgcn_global_load_lds((const unsigned*)((const char*)(gbase) + (voff)[_i]), (LAS unsigned*)(lds + (bufoff) + ldsw + _i * 8192), 16, 0, 0); } while (0)
; #define PG8_LDA(dst, b, h) do { _Pragma("unroll") for (int m = 0; m < 4; ++m) _Pragma("unroll") for (int k = 0; k < 2; ++k) dst[m][k] = *(const LAS bf16x8*)(lds + PG8_SA(b, h) + aoff + m * 2048 + k * 1024); } while (0)
; #define PG8_LDB(dst, b, h) do { _Pragma("unroll") for (int n = 0; n < 2; ++n) _Pragma("unroll") for (int k = 0; k < 2; ++k) dst[n][k] = *(const LAS bf16x8*)(lds + PG8_SB(b, h) + boff + n * 2048 + k * 1024); } while (0)
; #define PG8_MMA(ai, bj, At, Bt) do { __builtin_amdgcn_s_setprio(1); _Pragma("unroll") for (int m = 0; m < 4; ++m) _Pragma("unroll") for (int n = 0; n < 2; ++n) _Pragma("unroll") for (int k = 0; k < 2; ++k) \
;         acc[ai][bj][m][n] = __builtin_amdgcn_mfma_f32_16x16x32_bf16(Bt[n][k], At[m][k], acc[ai][bj][m][n], 0, 0, 0); __builtin_amdgcn_s_setprio(0); } while (0)
; #define PG8_WAIT_V(n) asm volatile("s_waitcnt vmcnt(" #n ")" ::: "memory")
; #define PG8_WAIT_L(n) asm volatile("s_waitcnt lgkmcnt(" #n ")" ::: "memory")
; #define PG8_BAR __builtin_amdgcn_s_barrier()
; #define PG8_SCHED __builtin_amdgcn_sched_barrier(0)
; template <class Epi, class Sched>
; __device__ __forceinline__ void gemm_phase(LAS unsigned char* lds, const Gemm g, const Sched& S, const Epi& E) {
;     ...
;             PG8_WAIT_L(8); PG8_BAR; PG8_WAIT_L(0); PG8_MMA(0, 0, At, B0); PG8_BAR; PG8_SCHED;
;             PG8_LDB(B1, 1, 1); PG8_STAGE(PG8_SB(1, 0), b3, voffB);
;             PG8_BAR; PG8_WAIT_L(0); PG8_MMA(0, 1, At, B1); PG8_BAR;
;             PG8_LDA(At, 1, 1); PG8_STAGE(PG8_SA(1, 0), a3, voffA);
;             PG8_BAR; PG8_WAIT_L(0); PG8_MMA(1, 0, At, B0); PG8_BAR; PG8_SCHED;
;             PG8_STAGE(PG8_SB(1, 1), b3 + hstep, voffB);
;             PG8_WAIT_V(6); PG8_BAR; PG8_MMA(1, 1, At, B1); PG8_BAR;
	s_waitcnt lgkmcnt(0)
	s_setprio 1
	s_waitcnt lgkmcnt(0)
	v_mfma_f32_16x16x32_bf16 v[124:127], v[150:153], v[166:169], v[124:127]
	v_mfma_f32_16x16x32_bf16 v[120:123], v[158:161], v[166:169], v[120:123]
	v_mfma_f32_16x16x32_bf16 v[116:119], v[150:153], v[174:177], v[116:119]
	v_mfma_f32_16x16x32_bf16 v[108:111], v[158:161], v[174:177], v[108:111]
	v_mfma_f32_16x16x32_bf16 v[100:103], v[150:153], v[182:185], v[100:103]
	v_mfma_f32_16x16x32_bf16 v[92:95], v[158:161], v[182:185], v[92:95]
	v_mfma_f32_16x16x32_bf16 v[84:87], v[150:153], v[190:193], v[84:87]
	v_mfma_f32_16x16x32_bf16 v[76:79], v[158:161], v[190:193], v[76:79]
	v_mfma_f32_16x16x32_bf16 v[124:127], v[154:157], v[170:173], v[124:127]
	v_mfma_f32_16x16x32_bf16 v[120:123], v[162:165], v[170:173], v[120:123]
	v_mfma_f32_16x16x32_bf16 v[116:119], v[154:157], v[178:181], v[116:119]
	v_mfma_f32_16x16x32_bf16 v[108:111], v[162:165], v[178:181], v[108:111]
	v_mfma_f32_16x16x32_bf16 v[100:103], v[154:157], v[186:189], v[100:103]
	v_mfma_f32_16x16x32_bf16 v[92:95], v[162:165], v[186:189], v[92:95]
	v_mfma_f32_16x16x32_bf16 v[84:87], v[154:157], v[194:197], v[84:87]
	v_mfma_f32_16x16x32_bf16 v[76:79], v[162:165], v[194:197], v[76:79]
	s_setprio 0
	s_barrier
	s_add_i32 s36, 0, 0x1c000
	s_add_i32 s37, s66, s43
	v_add_u32_e32 v214, s36, v146
	s_add_u32 s4, s34, 0x80
	s_addc_u32 s5, s35, 0
	s_mov_b32 m0, s37
	ds_read_b128 v[202:205], v214
	ds_read_b128 v[206:209], v214 offset:1024
	ds_read_b128 v[210:213], v214 offset:2048
	ds_read_b128 v[214:217], v214 offset:3072
	global_load_lds_dwordx4 v130, s[4:5]
	s_add_i32 m0, s37, 0x2000
	s_nop 0
	global_load_lds_dwordx4 v134, s[4:5]
	s_waitcnt vmcnt(10)
	s_barrier
	s_waitcnt lgkmcnt(0)
	s_setprio 1
	s_waitcnt lgkmcnt(0)
	v_mfma_f32_16x16x32_bf16 v[112:115], v[202:205], v[166:169], v[112:115]
	v_mfma_f32_16x16x32_bf16 v[104:107], v[210:213], v[166:169], v[104:107]
	v_mfma_f32_16x16x32_bf16 v[96:99], v[202:205], v[174:177], v[96:99]
	v_mfma_f32_16x16x32_bf16 v[88:91], v[210:213], v[174:177], v[88:91]
	v_mfma_f32_16x16x32_bf16 v[80:83], v[202:205], v[182:185], v[80:83]
	v_mfma_f32_16x16x32_bf16 v[72:75], v[210:213], v[182:185], v[72:75]
	v_mfma_f32_16x16x32_bf16 v[68:71], v[202:205], v[190:193], v[68:71]
	v_mfma_f32_16x16x32_bf16 v[64:67], v[210:213], v[190:193], v[64:67]
	v_mfma_f32_16x16x32_bf16 v[112:115], v[206:209], v[170:173], v[112:115]
	v_mfma_f32_16x16x32_bf16 v[104:107], v[214:217], v[170:173], v[104:107]
	v_mfma_f32_16x16x32_bf16 v[96:99], v[206:209], v[178:181], v[96:99]
	v_mfma_f32_16x16x32_bf16 v[88:91], v[214:217], v[178:181], v[88:91]
	v_mfma_f32_16x16x32_bf16 v[80:83], v[206:209], v[186:189], v[80:83]
	v_mfma_f32_16x16x32_bf16 v[72:75], v[214:217], v[186:189], v[72:75]
	v_mfma_f32_16x16x32_bf16 v[68:71], v[206:209], v[194:197], v[68:71]
	v_mfma_f32_16x16x32_bf16 v[64:67], v[214:217], v[194:197], v[64:67]
	s_setprio 0
	s_mov_b32 m0, s51
	s_mov_b64 s[4:5], 0x80
	v_lshl_add_u64 v[198:199], v[220:221], 0, s[4:5]
	s_barrier
	ds_read_b128 v[166:169], v148 offset:49152
	ds_read_b128 v[170:173], v148 offset:50176
	ds_read_b128 v[174:177], v148 offset:51200
	ds_read_b128 v[178:181], v148 offset:52224
	ds_read_b128 v[182:185], v148 offset:53248
	ds_read_b128 v[186:189], v148 offset:54272
	ds_read_b128 v[190:193], v148 offset:55296
	ds_read_b128 v[194:197], v148 offset:56320
	global_load_lds_dwordx4 v[198:199], off
	v_lshl_add_u64 v[198:199], v[222:223], 0, s[4:5]
	s_mov_b32 m0, s52
	s_nop 0
	global_load_lds_dwordx4 v[198:199], off
	s_barrier
	s_waitcnt lgkmcnt(0)
	s_setprio 1
	s_waitcnt lgkmcnt(0)
	v_mfma_f32_16x16x32_bf16 v[60:63], v[150:153], v[166:169], v[60:63]
	v_mfma_f32_16x16x32_bf16 v[56:59], v[158:161], v[166:169], v[56:59]
	v_mfma_f32_16x16x32_bf16 v[52:55], v[150:153], v[174:177], v[52:55]
	v_mfma_f32_16x16x32_bf16 v[44:47], v[158:161], v[174:177], v[44:47]
	v_mfma_f32_16x16x32_bf16 v[36:39], v[150:153], v[182:185], v[36:39]
	v_mfma_f32_16x16x32_bf16 v[28:31], v[158:161], v[182:185], v[28:31]
	v_mfma_f32_16x16x32_bf16 v[20:23], v[150:153], v[190:193], v[20:23]
	v_mfma_f32_16x16x32_bf16 v[12:15], v[158:161], v[190:193], v[12:15]
	v_mfma_f32_16x16x32_bf16 v[60:63], v[154:157], v[170:173], v[60:63]
	v_mfma_f32_16x16x32_bf16 v[56:59], v[162:165], v[170:173], v[56:59]
	v_mfma_f32_16x16x32_bf16 v[52:55], v[154:157], v[178:181], v[52:55]
	v_mfma_f32_16x16x32_bf16 v[44:47], v[162:165], v[178:181], v[44:47]
	v_mfma_f32_16x16x32_bf16 v[36:39], v[154:157], v[186:189], v[36:39]
	v_mfma_f32_16x16x32_bf16 v[28:31], v[162:165], v[186:189], v[28:31]
	v_mfma_f32_16x16x32_bf16 v[20:23], v[154:157], v[194:197], v[20:23]
	v_mfma_f32_16x16x32_bf16 v[12:15], v[162:165], v[194:197], v[12:15]
	s_setprio 0
	s_barrier
	s_add_u32 s34, s34, 0x40080
	s_addc_u32 s35, s35, 0
	s_add_i32 s36, s36, s43
	s_mov_b32 m0, s36
	s_nop 0
	global_load_lds_dwordx4 v130, s[34:35]
	s_add_i32 m0, s36, 0x2000
	s_nop 0
	global_load_lds_dwordx4 v134, s[34:35]
	s_waitcnt vmcnt(10)
	s_barrier
; __device__ __forceinline__ unsigned cvt_pk_bf16(float lo, float hi) { unsigned r; asm volatile("v_cvt_pk_bf16_f32 %0, %1, %2" : "=v"(r) : "v"(lo), "v"(hi)); return r; }
; #define PG8_MMA(ai, bj, At, Bt) do { __builtin_amdgcn_s_setprio(1); _Pragma("unroll") for (int m = 0; m < 4; ++m) _Pragma("unroll") for (int n = 0; n < 2; ++n) _Pragma("unroll") for (int k = 0; k < 2; ++k) \
;         acc[ai][bj][m][n] = __builtin_amdgcn_mfma_f32_16x16x32_bf16(Bt[n][k], At[m][k], acc[ai][bj][m][n], 0, 0, 0); __builtin_amdgcn_s_setprio(0); } while (0)
; #define PG8_WAIT_V(n) asm volatile("s_waitcnt vmcnt(" #n ")" ::: "memory")
; #define PG8_BAR __builtin_amdgcn_s_barrier()
; template <class Epi, class Sched>
; __device__ __forceinline__ void gemm_phase(LAS unsigned char* lds, const Gemm g, const Sched& S, const Epi& E) {
;     ...
;             PG8_WAIT_V(6); PG8_BAR; PG8_MMA(1, 1, At, B1); PG8_BAR;
;         }
;         E(acc, cur, wr, wc, fr, fq);
;         if (!has_next) break;
; #pragma unroll
;         for (int a = 0; a < 2; ++a)
; #pragma unroll
;             for (int b = 0; b < 2; ++b)
; #pragma unroll
;                 for (int m = 0; m < 4; ++m)
; #pragma unroll
;                     for (int n = 0; n < 2; ++n) acc[a][b][m][n] = (f32x4){0.f, 0.f, 0.f, 0.f};
;         cur = nxt; cA = nA; cB = nB; ++ui;
;     }
;     PG8_WAIT_V(0);
;     if (wr == 0) PG8_BAR;
;     PG8_BAR;
;     __device__ __forceinline__ void operator()(const AccT& acc, const Unit& u, int wr, int wc, int fr, int fq) const {
;         asm volatile("" : "+v"(fr), "+v"(fq));
;         const int rbase = u.pm * 256 + wr * 64 + fr;
;         const int tb = u.pn * 256 + wc * 32 + 8 * fq;
; #pragma unroll
;         for (int ai = 0; ai < 2; ++ai)
; #pragma unroll
;             for (int m = 0; m < 4; ++m) {
;                 const int r = rbase + ai * 128 + m * 16;
; #pragma unroll
;                 for (int bj = 0; bj < 2; ++bj) {
;                     const int t0 = tb + bj * 128;
;                     const f32x4 v0 = acc[ai][bj][m][0], v1 = acc[ai][bj][m][1];
;                     u32x4 w; w.x = cvt_pk_bf16(v0[0], v0[1]); w.y = cvt_pk_bf16(v0[2], v0[3]); w.z = cvt_pk_bf16(v1[0], v1[1]); w.w = cvt_pk_bf16(v1[2], v1[3]);
;                     *(u32x4*)(VT + (size_t)r * NT + t0) = w;
;                 }
;             }
;     }
	s_setprio 1
	v_mfma_f32_16x16x32_bf16 v[48:51], v[202:205], v[166:169], v[48:51]
	v_mfma_f32_16x16x32_bf16 v[40:43], v[210:213], v[166:169], v[40:43]
	v_mfma_f32_16x16x32_bf16 v[32:35], v[202:205], v[174:177], v[32:35]
	v_mfma_f32_16x16x32_bf16 v[24:27], v[210:213], v[174:177], v[24:27]
	v_mfma_f32_16x16x32_bf16 v[16:19], v[202:205], v[182:185], v[16:19]
	v_mfma_f32_16x16x32_bf16 v[8:11], v[210:213], v[182:185], v[8:11]
	v_mfma_f32_16x16x32_bf16 v[4:7], v[202:205], v[190:193], v[4:7]
	v_mfma_f32_16x16x32_bf16 v[0:3], v[210:213], v[190:193], v[0:3]
	v_mfma_f32_16x16x32_bf16 v[48:51], v[206:209], v[170:173], v[48:51]
	v_mfma_f32_16x16x32_bf16 v[40:43], v[214:217], v[170:173], v[40:43]
	v_mfma_f32_16x16x32_bf16 v[32:35], v[206:209], v[178:181], v[32:35]
	v_mfma_f32_16x16x32_bf16 v[24:27], v[214:217], v[178:181], v[24:27]
	v_mfma_f32_16x16x32_bf16 v[16:19], v[206:209], v[186:189], v[16:19]
	v_mfma_f32_16x16x32_bf16 v[8:11], v[214:217], v[186:189], v[8:11]
	v_mfma_f32_16x16x32_bf16 v[4:7], v[206:209], v[194:197], v[4:7]
	v_mfma_f32_16x16x32_bf16 v[0:3], v[214:217], v[194:197], v[0:3]
	s_setprio 0
	s_add_i32 s65, s65, 2
	s_add_u32 s30, s30, 0x100
	s_addc_u32 s31, s31, 0
	s_add_u32 s63, s63, 0x100
	s_addc_u32 s64, s64, 0
	s_cmp_gt_u32 s65, 13
	s_barrier
	s_cbranch_scc0 .LBB0_633
	v_mov_b32_e32 v150, v144
	v_mov_b32_e32 v151, v145
	s_lshl_b32 s21, s28, 8
	s_add_i32 s21, s21, s48
	v_add_u32_e32 v150, s21, v150
	s_lshl_b32 s21, s60, 8
	s_or_b32 s21, s21, s49
	v_lshl_add_u32 v152, v151, 3, s21
	v_ashrrev_i32_e32 v151, 31, v150
	v_cvt_pk_bf16_f32 v124, v124, v125
	v_cvt_pk_bf16_f32 v125, v126, v127
	v_cvt_pk_bf16_f32 v126, v120, v121
	v_lshlrev_b64 v[120:121], 17, v[150:151]
	v_lshl_add_u64 v[120:121], s[0:1], 0, v[120:121]
	v_ashrrev_i32_e32 v153, 31, v152
	v_lshl_add_u64 v[120:121], v[152:153], 1, v[120:121]
	s_mov_b32 s21, 0x200000
	v_cvt_pk_bf16_f32 v127, v122, v123
	global_store_dwordx4 v[120:121], v[124:127], off
	v_cvt_pk_bf16_f32 v112, v112, v113
	v_cvt_pk_bf16_f32 v113, v114, v115
	v_cvt_pk_bf16_f32 v114, v104, v105
	v_cvt_pk_bf16_f32 v115, v106, v107
	global_store_dwordx4 v[120:121], v[112:115], off offset:256
	v_cvt_pk_bf16_f32 v104, v116, v117
	v_cvt_pk_bf16_f32 v105, v118, v119
	v_cvt_pk_bf16_f32 v106, v108, v109
	v_cvt_pk_bf16_f32 v107, v110, v111
	s_mov_b64 s[30:31], 0x200000
	v_add_co_u32_e32 v110, vcc, s21, v120
	v_lshl_add_u64 v[108:109], v[120:121], 0, s[30:31]
	s_nop 0
	v_addc_co_u32_e32 v111, vcc, 0, v121, vcc
	s_mov_b32 s21, 0x400000
	global_store_dwordx4 v[110:111], v[104:107], off
	v_cvt_pk_bf16_f32 v96, v96, v97
	v_cvt_pk_bf16_f32 v97, v98, v99
	v_cvt_pk_bf16_f32 v98, v88, v89
	v_cvt_pk_bf16_f32 v99, v90, v91
	global_store_dwordx4 v[108:109], v[96:99], off offset:256
	v_cvt_pk_bf16_f32 v88, v100, v101
	v_cvt_pk_bf16_f32 v89, v102, v103
	v_cvt_pk_bf16_f32 v90, v92, v93
	v_cvt_pk_bf16_f32 v91, v94, v95
	s_mov_b64 s[30:31], 0x400000
	v_add_co_u32_e32 v94, vcc, s21, v120
	v_lshl_add_u64 v[92:93], v[120:121], 0, s[30:31]
	s_nop 0
	v_addc_co_u32_e32 v95, vcc, 0, v121, vcc
	s_mov_b32 s21, 0x600000
	global_store_dwordx4 v[94:95], v[88:91], off
	v_cvt_pk_bf16_f32 v80, v80, v81
	v_cvt_pk_bf16_f32 v81, v82, v83
	v_cvt_pk_bf16_f32 v82, v72, v73
	v_cvt_pk_bf16_f32 v83, v74, v75
	global_store_dwordx4 v[92:93], v[80:83], off offset:256
	v_cvt_pk_bf16_f32 v72, v84, v85
	v_cvt_pk_bf16_f32 v73, v86, v87
	v_cvt_pk_bf16_f32 v74, v76, v77
	v_cvt_pk_bf16_f32 v75, v78, v79
	s_mov_b64 s[30:31], 0x600000
	v_add_co_u32_e32 v78, vcc, s21, v120
	v_lshl_add_u64 v[76:77], v[120:121], 0, s[30:31]
	s_nop 0
	v_addc_co_u32_e32 v79, vcc, 0, v121, vcc
	global_store_dwordx4 v[78:79], v[72:75], off
	v_cvt_pk_bf16_f32 v68, v68, v69
	v_cvt_pk_bf16_f32 v69, v70, v71
	v_cvt_pk_bf16_f32 v70, v64, v65
	v_cvt_pk_bf16_f32 v71, v66, v67
	global_store_dwordx4 v[76:77], v[68:71], off offset:256
	v_cvt_pk_bf16_f32 v60, v60, v61
	v_cvt_pk_bf16_f32 v61, v62, v63
	v_cvt_pk_bf16_f32 v62, v56, v57
	v_cvt_pk_bf16_f32 v63, v58, v59
	s_mov_b64 s[30:31], 0x1000000
	v_add_co_u32_e32 v58, vcc, s56, v120
	v_lshl_add_u64 v[56:57], v[120:121], 0, s[30:31]
	s_nop 0
	v_addc_co_u32_e32 v59, vcc, 0, v121, vcc
	global_store_dwordx4 v[58:59], v[60:63], off
	v_cvt_pk_bf16_f32 v48, v48, v49
	v_cvt_pk_bf16_f32 v49, v50, v51
	v_cvt_pk_bf16_f32 v50, v40, v41
	v_cvt_pk_bf16_f32 v51, v42, v43
	global_store_dwordx4 v[56:57], v[48:51], off offset:256
	v_cvt_pk_bf16_f32 v40, v52, v53
	v_cvt_pk_bf16_f32 v41, v54, v55
	v_cvt_pk_bf16_f32 v42, v44, v45
	v_cvt_pk_bf16_f32 v43, v46, v47
	v_add_co_u32_e32 v46, vcc, s57, v120
	v_lshl_add_u64 v[44:45], v[120:121], 0, s[6:7]
	s_nop 0
	v_addc_co_u32_e32 v47, vcc, 0, v121, vcc
	global_store_dwordx4 v[46:47], v[40:43], off
	v_cvt_pk_bf16_f32 v32, v32, v33
	v_cvt_pk_bf16_f32 v33, v34, v35
	v_cvt_pk_bf16_f32 v34, v24, v25
	v_cvt_pk_bf16_f32 v35, v26, v27
	global_store_dwordx4 v[44:45], v[32:35], off offset:256
	v_cvt_pk_bf16_f32 v24, v36, v37
	v_cvt_pk_bf16_f32 v25, v38, v39
	v_cvt_pk_bf16_f32 v26, v28, v29
	v_cvt_pk_bf16_f32 v27, v30, v31
	v_add_co_u32_e32 v30, vcc, s58, v120
	v_lshl_add_u64 v[28:29], v[120:121], 0, s[8:9]
	s_nop 0
	v_addc_co_u32_e32 v31, vcc, 0, v121, vcc
	global_store_dwordx4 v[30:31], v[24:27], off
	v_cvt_pk_bf16_f32 v16, v16, v17
	v_cvt_pk_bf16_f32 v17, v18, v19
	v_cvt_pk_bf16_f32 v18, v8, v9
	v_cvt_pk_bf16_f32 v19, v10, v11
	global_store_dwordx4 v[28:29], v[16:19], off offset:256
	v_cvt_pk_bf16_f32 v8, v20, v21
	v_cvt_pk_bf16_f32 v9, v22, v23
	v_cvt_pk_bf16_f32 v10, v12, v13
	v_cvt_pk_bf16_f32 v11, v14, v15
	v_add_co_u32_e32 v14, vcc, s59, v120
	v_lshl_add_u64 v[12:13], v[120:121], 0, s[16:17]
	s_nop 0
	v_addc_co_u32_e32 v15, vcc, 0, v121, vcc
	s_and_b64 vcc, exec, s[2:3]
	s_mov_b32 s60, s20
	s_mov_b32 s28, s22
	s_mov_b64 s[34:35], s[26:27]
	s_mov_b64 s[30:31], s[24:25]
	global_store_dwordx4 v[14:15], v[8:11], off
	v_cvt_pk_bf16_f32 v4, v4, v5
	v_cvt_pk_bf16_f32 v5, v6, v7
	v_cvt_pk_bf16_f32 v6, v0, v1
	v_cvt_pk_bf16_f32 v7, v2, v3
	global_store_dwordx4 v[12:13], v[4:7], off offset:256
	s_cbranch_vccz .LBB0_626
	s_waitcnt vmcnt(0)
	s_cmpk_gt_u32 s33, 0xff
	s_cbranch_scc1 .LBB0_637
	s_barrier

; #define PG8_STAGE(bufoff, gbase, voff) do { _Pragma("unroll") for (int _i = 0; _i < 2; ++_i) \
;         __builtin_amdgcn_global_load_lds((const unsigned*)((const char*)(gbase) + (voff)[_i]), (LAS unsigned*)(lds + (bufoff) + ldsw + _i * 8192), 16, 0, 0); } while (0)
; #define PG8_LDA(dst, b, h) do { _Pragma("unroll") for (int m = 0; m < 4; ++m) _Pragma("unroll") for (int k = 0; k < 2; ++k) dst[m][k] = *(const LAS bf16x8*)(lds + PG8_SA(b, h) + aoff + m * 2048 + k * 1024); } while (0)
; #define PG8_LDB(dst, b, h) do { _Pragma("unroll") for (int n = 0; n < 2; ++n) _Pragma("unroll") for (int k = 0; k < 2; ++k) dst[n][k] = *(const LAS bf16x8*)(lds + PG8_SB(b, h) + boff + n * 2048 + k * 1024); } while (0)
; #define PG8_MMA(ai, bj, At, Bt) do { __builtin_amdgcn_s_setprio(1); _Pragma("unroll") for (int m = 0; m < 4; ++m) _Pragma("unroll") for (int n = 0; n < 2; ++n) _Pragma("unroll") for (int k = 0; k < 2; ++k) \
;         acc[ai][bj][m][n] = __builtin_amdgcn_mfma_f32_16x16x32_bf16(Bt[n][k], At[m][k], acc[ai][bj][m][n], 0, 0, 0); __builtin_amdgcn_s_setprio(0); } while (0)
; #define PG8_WAIT_L(n) asm volatile("s_waitcnt lgkmcnt(" #n ")" ::: "memory")
; template <class Epi, class Sched>
; __device__ __forceinline__ void gemm_phase(LAS unsigned char* lds, const Gemm g, const Sched& S, const Epi& E) {
;     ...
;         const bool has_next = S.next(ui + 1, nxt);
;         const char* nA = has_next ? (const char*)g.A + (size_t)nxt.pm * tstep : cA; const char* nB = has_next ? (const char*)g.Bt + (size_t)nxt.pn * tstep : cB;
;         for (int t = 0; t < nt; t += 2) {
;             const bool last = (t == nt - 2);
;             const char* a1 = cA + (size_t)(t + 1) * kstep;
;             const char* a2 = last ? nA : cA + (size_t)(t + 2) * kstep; const char* b2 = last ? nB : cB + (size_t)(t + 2) * kstep;
;             const char* a3 = a2 + kstep; const char* b3 = b2 + kstep;
;             PG8_LDB(B0, 0, 0); PG8_SCHED; PG8_LDA(At, 0, 0); PG8_STAGE(PG8_SA(1, 1), a1 + hstep, voffA);
;             PG8_WAIT_L(8); PG8_BAR; PG8_WAIT_L(0); PG8_MMA(0, 0, At, B0); PG8_BAR; PG8_SCHED;
;             PG8_LDB(B1, 0, 1); PG8_STAGE(PG8_SB(0, 0), b2, voffB);
;             PG8_BAR; PG8_WAIT_L(0); PG8_MMA(0, 1, At, B1); PG8_BAR;
;             PG8_LDA(At, 0, 1); PG8_STAGE(PG8_SA(0, 0), a2, voffA);
;             PG8_BAR; PG8_WAIT_L(0); PG8_MMA(1, 0, At, B0); PG8_BAR; PG8_SCHED;
.LBB0_652:
	s_ashr_i32 s9, s8, 31
	v_cmp_lt_i64_e32 vcc, s[16:17], v[142:143]
	s_lshl_b64 s[16:17], s[8:9], 19
	s_add_u32 s16, s14, s16
	s_addc_u32 s17, s15, s17
	s_and_b64 s[18:19], vcc, exec
	s_cselect_b32 s9, s17, s23
	s_cselect_b32 s48, s16, s22
	s_ashr_i32 s7, s6, 31
	s_lshl_b64 s[18:19], s[6:7], 19
	s_add_u32 s18, s12, s18
	s_addc_u32 s19, s13, s19
	s_and_b64 s[26:27], vcc, exec
	s_cselect_b32 s7, s19, s25
	s_cselect_b32 s49, s18, s24
	s_add_u32 s22, s22, 0x40080
	s_addc_u32 s23, s23, 0
	s_add_u32 s51, s24, 0x100
	s_addc_u32 s52, s25, 0
	s_mov_b32 s53, -2
	s_waitcnt lgkmcnt(0)
	ds_read_b128 v[152:155], v149
	ds_read_b128 v[156:159], v149 offset:1024
	ds_read_b128 v[160:163], v149 offset:2048
	ds_read_b128 v[164:167], v149 offset:3072
	s_add_u32 s24, s22, 0xfffc0080
	s_addc_u32 s25, s23, -1
	s_cmp_eq_u32 s53, 12
	s_cselect_b32 s27, s9, s25
	s_cselect_b32 s26, s48, s24
	s_cselect_b32 s25, s7, s52
	s_cselect_b32 s24, s49, s51
	s_add_i32 m0, s21, 0xc000
	ds_read_b128 v[168:171], v150
	ds_read_b128 v[172:175], v150 offset:1024
	ds_read_b128 v[176:179], v150 offset:2048
	ds_read_b128 v[180:183], v150 offset:3072
	ds_read_b128 v[184:187], v150 offset:4096
	ds_read_b128 v[188:191], v150 offset:5120
	ds_read_b128 v[192:195], v150 offset:6144
	ds_read_b128 v[196:199], v150 offset:7168
	global_load_lds_dwordx4 v138, s[22:23]
	s_add_i32 m0, s21, 0xe000
	s_nop 0
	global_load_lds_dwordx4 v140, s[22:23]
	s_waitcnt vmcnt(10)
	s_barrier
	s_waitcnt lgkmcnt(0)
	s_setprio 1
	s_waitcnt lgkmcnt(0)
	v_mfma_f32_16x16x32_bf16 v[124:127], v[152:155], v[168:171], 0
	v_mfma_f32_16x16x32_bf16 v[120:123], v[160:163], v[168:171], 0
	v_mfma_f32_16x16x32_bf16 v[112:115], v[152:155], v[176:179], 0
	v_mfma_f32_16x16x32_bf16 v[104:107], v[160:163], v[176:179], 0
	v_mfma_f32_16x16x32_bf16 v[96:99], v[152:155], v[184:187], 0
	v_mfma_f32_16x16x32_bf16 v[88:91], v[160:163], v[184:187], 0
	v_mfma_f32_16x16x32_bf16 v[80:83], v[152:155], v[192:195], 0
	v_mfma_f32_16x16x32_bf16 v[72:75], v[160:163], v[192:195], 0
	v_mfma_f32_16x16x32_bf16 v[124:127], v[156:159], v[172:175], v[124:127]
	v_mfma_f32_16x16x32_bf16 v[120:123], v[164:167], v[172:175], v[120:123]
	v_mfma_f32_16x16x32_bf16 v[112:115], v[156:159], v[180:183], v[112:115]
	v_mfma_f32_16x16x32_bf16 v[104:107], v[164:167], v[180:183], v[104:107]
	v_mfma_f32_16x16x32_bf16 v[96:99], v[156:159], v[188:191], v[96:99]
	v_mfma_f32_16x16x32_bf16 v[88:91], v[164:167], v[188:191], v[88:91]
	v_mfma_f32_16x16x32_bf16 v[80:83], v[156:159], v[196:199], v[80:83]
	v_mfma_f32_16x16x32_bf16 v[72:75], v[164:167], v[196:199], v[72:75]
	s_setprio 0
	s_barrier
	s_add_i32 s54, s45, s30
	s_mov_b32 m0, s54
	ds_read_b128 v[202:205], v151
	ds_read_b128 v[206:209], v151 offset:1024
	ds_read_b128 v[210:213], v151 offset:2048
	ds_read_b128 v[214:217], v151 offset:3072
	global_load_lds_dwordx4 v130, s[24:25]
	s_add_i32 m0, s54, 0x2000
	s_nop 0
	global_load_lds_dwordx4 v134, s[24:25]
	s_waitcnt vmcnt(10)
	s_barrier
	s_waitcnt lgkmcnt(0)
	s_setprio 1
	s_waitcnt lgkmcnt(0)
	v_mfma_f32_16x16x32_bf16 v[116:119], v[202:205], v[168:171], 0
	v_mfma_f32_16x16x32_bf16 v[108:111], v[210:213], v[168:171], 0
	v_mfma_f32_16x16x32_bf16 v[100:103], v[202:205], v[176:179], 0
	v_mfma_f32_16x16x32_bf16 v[92:95], v[210:213], v[176:179], 0
	v_mfma_f32_16x16x32_bf16 v[84:87], v[202:205], v[184:187], 0
	v_mfma_f32_16x16x32_bf16 v[76:79], v[210:213], v[184:187], 0
	v_mfma_f32_16x16x32_bf16 v[68:71], v[202:205], v[192:195], 0
	v_mfma_f32_16x16x32_bf16 v[64:67], v[210:213], v[192:195], 0
	v_mfma_f32_16x16x32_bf16 v[116:119], v[206:209], v[172:175], v[116:119]
	v_mfma_f32_16x16x32_bf16 v[108:111], v[214:217], v[172:175], v[108:111]
	v_mfma_f32_16x16x32_bf16 v[100:103], v[206:209], v[180:183], v[100:103]
	v_mfma_f32_16x16x32_bf16 v[92:95], v[214:217], v[180:183], v[92:95]
	v_mfma_f32_16x16x32_bf16 v[84:87], v[206:209], v[188:191], v[84:87]
	v_mfma_f32_16x16x32_bf16 v[76:79], v[214:217], v[188:191], v[76:79]
	v_mfma_f32_16x16x32_bf16 v[68:71], v[206:209], v[196:199], v[68:71]
	v_mfma_f32_16x16x32_bf16 v[64:67], v[214:217], v[196:199], v[64:67]
	s_setprio 0
	s_mov_b32 m0, s21
	v_lshl_add_u64 v[222:223], s[26:27], 0, v[128:129]
	s_barrier
	ds_read_b128 v[168:171], v150 offset:16384
	ds_read_b128 v[172:175], v150 offset:17408
	ds_read_b128 v[176:179], v150 offset:18432
	ds_read_b128 v[180:183], v150 offset:19456
	ds_read_b128 v[184:187], v150 offset:20480
	ds_read_b128 v[188:191], v150 offset:21504
	ds_read_b128 v[192:195], v150 offset:22528
	ds_read_b128 v[196:199], v150 offset:23552
	global_load_lds_dwordx4 v128, s[26:27]
	v_lshl_add_u64 v[224:225], s[26:27], 0, v[132:133]
	s_mov_b32 m0, s31
	s_nop 0
	global_load_lds_dwordx4 v132, s[26:27]
	s_barrier
	s_waitcnt lgkmcnt(0)
	s_setprio 1
	s_waitcnt lgkmcnt(0)
	v_mfma_f32_16x16x32_bf16 v[60:63], v[152:155], v[168:171], 0
	v_mfma_f32_16x16x32_bf16 v[56:59], v[160:163], v[168:171], 0
	v_mfma_f32_16x16x32_bf16 v[48:51], v[152:155], v[176:179], 0
	v_mfma_f32_16x16x32_bf16 v[40:43], v[160:163], v[176:179], 0
	v_mfma_f32_16x16x32_bf16 v[32:35], v[152:155], v[184:187], 0
	v_mfma_f32_16x16x32_bf16 v[24:27], v[160:163], v[184:187], 0
	v_mfma_f32_16x16x32_bf16 v[16:19], v[152:155], v[192:195], 0
	v_mfma_f32_16x16x32_bf16 v[8:11], v[160:163], v[192:195], 0
	v_mfma_f32_16x16x32_bf16 v[60:63], v[156:159], v[172:175], v[60:63]
	v_mfma_f32_16x16x32_bf16 v[56:59], v[164:167], v[172:175], v[56:59]
	v_mfma_f32_16x16x32_bf16 v[48:51], v[156:159], v[180:183], v[48:51]
	v_mfma_f32_16x16x32_bf16 v[40:43], v[164:167], v[180:183], v[40:43]
	v_mfma_f32_16x16x32_bf16 v[32:35], v[156:159], v[188:191], v[32:35]
	v_mfma_f32_16x16x32_bf16 v[24:27], v[164:167], v[188:191], v[24:27]
	v_mfma_f32_16x16x32_bf16 v[16:19], v[156:159], v[196:199], v[16:19]
	v_mfma_f32_16x16x32_bf16 v[8:11], v[164:167], v[196:199], v[8:11]
	s_setprio 0
	s_barrier
; #define PG8_STAGE(bufoff, gbase, voff) do { _Pragma("unroll") for (int _i = 0; _i < 2; ++_i) \
;         __builtin_amdgcn_global_load_lds((const unsigned*)((const char*)(gbase) + (voff)[_i]), (LAS unsigned*)(lds + (bufoff) + ldsw + _i * 8192), 16, 0, 0); } while (0)
; #define PG8_LDA(dst, b, h) do { _Pragma("unroll") for (int m = 0; m < 4; ++m) _Pragma("unroll") for (int k = 0; k < 2; ++k) dst[m][k] = *(const LAS bf16x8*)(lds + PG8_SA(b, h) + aoff + m * 2048 + k * 1024); } while (0)
; #define PG8_LDB(dst, b, h) do { _Pragma("unroll") for (int n = 0; n < 2; ++n) _Pragma("unroll") for (int k = 0; k < 2; ++k) dst[n][k] = *(const LAS bf16x8*)(lds + PG8_SB(b, h) + boff + n * 2048 + k * 1024); } while (0)
; #define PG8_MMA(ai, bj, At, Bt) do { __builtin_amdgcn_s_setprio(1); _Pragma("unroll") for (int m = 0; m < 4; ++m) _Pragma("unroll") for (int n = 0; n < 2; ++n) _Pragma("unroll") for (int k = 0; k < 2; ++k) \
;         acc[ai][bj][m][n] = __builtin_amdgcn_mfma_f32_16x16x32_bf16(Bt[n][k], At[m][k], acc[ai][bj][m][n], 0, 0, 0); __builtin_amdgcn_s_setprio(0); } while (0)
; #define PG8_WAIT_V(n) asm volatile("s_waitcnt vmcnt(" #n ")" ::: "memory")
; #define PG8_WAIT_L(n) asm volatile("s_waitcnt lgkmcnt(" #n ")" ::: "memory")
; #define PG8_BAR __builtin_amdgcn_s_barrier()
; #define PG8_SCHED __builtin_amdgcn_sched_barrier(0)
; template <class Epi, class Sched>
; __device__ __forceinline__ void gemm_phase(LAS unsigned char* lds, const Gemm g, const Sched& S, const Epi& E) {
;     ...
;             PG8_STAGE(PG8_SB(0, 1), b2 + hstep, voffB);
;             PG8_WAIT_V(6); PG8_BAR; PG8_MMA(1, 1, At, B1); PG8_BAR;
;             PG8_LDB(B0, 1, 0); PG8_SCHED; PG8_LDA(At, 1, 0); PG8_STAGE(PG8_SA(0, 1), a2 + hstep, voffA);
;             PG8_WAIT_L(8); PG8_BAR; PG8_WAIT_L(0); PG8_MMA(0, 0, At, B0); PG8_BAR; PG8_SCHED;
;             PG8_LDB(B1, 1, 1); PG8_STAGE(PG8_SB(1, 0), b3, voffB);
;             PG8_BAR; PG8_WAIT_L(0); PG8_MMA(0, 1, At, B1); PG8_BAR;
;             PG8_LDA(At, 1, 1); PG8_STAGE(PG8_SA(1, 0), a3, voffA);
;             PG8_BAR; PG8_WAIT_L(0); PG8_MMA(1, 0, At, B0); PG8_BAR; PG8_SCHED;
	s_add_u32 s54, s24, 0x40000
	s_addc_u32 s55, s25, 0
	s_add_i32 s56, s46, s30
	s_mov_b32 m0, s56
	s_nop 0
	global_load_lds_dwordx4 v130, s[54:55]
	s_add_i32 m0, s56, 0x2000
	s_nop 0
	global_load_lds_dwordx4 v134, s[54:55]
	s_add_u32 s26, s26, 0x40000
	s_addc_u32 s27, s27, 0
	s_mov_b32 m0, s33
	s_nop 0
	global_load_lds_dwordx4 v128, s[26:27]
	s_mov_b32 m0, s34
	s_nop 0
	global_load_lds_dwordx4 v132, s[26:27]
	s_waitcnt vmcnt(12)
	s_barrier
	s_setprio 1
	v_mfma_f32_16x16x32_bf16 v[52:55], v[202:205], v[168:171], 0
	v_mfma_f32_16x16x32_bf16 v[44:47], v[210:213], v[168:171], 0
	v_mfma_f32_16x16x32_bf16 v[36:39], v[202:205], v[176:179], 0
	v_mfma_f32_16x16x32_bf16 v[28:31], v[210:213], v[176:179], 0
	v_mfma_f32_16x16x32_bf16 v[20:23], v[202:205], v[184:187], 0
	v_mfma_f32_16x16x32_bf16 v[12:15], v[210:213], v[184:187], 0
	v_mfma_f32_16x16x32_bf16 v[4:7], v[202:205], v[192:195], 0
	v_mfma_f32_16x16x32_bf16 v[0:3], v[210:213], v[192:195], 0
	v_mfma_f32_16x16x32_bf16 v[52:55], v[206:209], v[172:175], v[52:55]
	v_mfma_f32_16x16x32_bf16 v[44:47], v[214:217], v[172:175], v[44:47]
	v_mfma_f32_16x16x32_bf16 v[36:39], v[206:209], v[180:183], v[36:39]
	v_mfma_f32_16x16x32_bf16 v[28:31], v[214:217], v[180:183], v[28:31]
	v_mfma_f32_16x16x32_bf16 v[20:23], v[206:209], v[188:191], v[20:23]
	v_mfma_f32_16x16x32_bf16 v[12:15], v[214:217], v[188:191], v[12:15]
	v_mfma_f32_16x16x32_bf16 v[4:7], v[206:209], v[196:199], v[4:7]
	v_mfma_f32_16x16x32_bf16 v[0:3], v[214:217], v[196:199], v[0:3]
	s_setprio 0
	s_add_i32 s54, 0, 0x18000
	v_add_u32_e32 v136, s54, v148
	s_barrier
	ds_read_b128 v[152:155], v136
	ds_read_b128 v[156:159], v136 offset:1024
	ds_read_b128 v[160:163], v136 offset:2048
	ds_read_b128 v[164:167], v136 offset:3072
	ds_read_b128 v[168:171], v150 offset:32768
	ds_read_b128 v[172:175], v150 offset:33792
	ds_read_b128 v[176:179], v150 offset:34816
	ds_read_b128 v[180:183], v150 offset:35840
	ds_read_b128 v[184:187], v150 offset:36864
	ds_read_b128 v[188:191], v150 offset:37888
	ds_read_b128 v[192:195], v150 offset:38912
	ds_read_b128 v[196:199], v150 offset:39936
	s_waitcnt vmcnt(10)
	s_barrier
	s_waitcnt lgkmcnt(0)
	s_setprio 1
	s_waitcnt lgkmcnt(0)
	v_mfma_f32_16x16x32_bf16 v[124:127], v[152:155], v[168:171], v[124:127]
	v_mfma_f32_16x16x32_bf16 v[120:123], v[160:163], v[168:171], v[120:123]
	v_mfma_f32_16x16x32_bf16 v[112:115], v[152:155], v[176:179], v[112:115]
	v_mfma_f32_16x16x32_bf16 v[104:107], v[160:163], v[176:179], v[104:107]
	v_mfma_f32_16x16x32_bf16 v[96:99], v[152:155], v[184:187], v[96:99]
	v_mfma_f32_16x16x32_bf16 v[88:91], v[160:163], v[184:187], v[88:91]
	v_mfma_f32_16x16x32_bf16 v[80:83], v[152:155], v[192:195], v[80:83]
	v_mfma_f32_16x16x32_bf16 v[72:75], v[160:163], v[192:195], v[72:75]
	v_mfma_f32_16x16x32_bf16 v[124:127], v[156:159], v[172:175], v[124:127]
	v_mfma_f32_16x16x32_bf16 v[120:123], v[164:167], v[172:175], v[120:123]
	v_mfma_f32_16x16x32_bf16 v[112:115], v[156:159], v[180:183], v[112:115]
	v_mfma_f32_16x16x32_bf16 v[104:107], v[164:167], v[180:183], v[104:107]
	v_mfma_f32_16x16x32_bf16 v[96:99], v[156:159], v[188:191], v[96:99]
	v_mfma_f32_16x16x32_bf16 v[88:91], v[164:167], v[188:191], v[88:91]
	v_mfma_f32_16x16x32_bf16 v[80:83], v[156:159], v[196:199], v[80:83]
	v_mfma_f32_16x16x32_bf16 v[72:75], v[164:167], v[196:199], v[72:75]
	s_setprio 0
	s_barrier
	s_add_i32 s26, 0, 0x1c000
	s_add_i32 s27, s54, s30
	v_add_u32_e32 v136, s26, v148
	s_add_u32 s0, s24, 0x80
	s_addc_u32 s1, s25, 0
	s_mov_b32 m0, s27
	ds_read_b128 v[202:205], v136
	ds_read_b128 v[206:209], v136 offset:1024
	ds_read_b128 v[210:213], v136 offset:2048
	ds_read_b128 v[214:217], v136 offset:3072
	global_load_lds_dwordx4 v130, s[0:1]
	s_add_i32 m0, s27, 0x2000
	s_nop 0
	global_load_lds_dwordx4 v134, s[0:1]
	s_waitcnt vmcnt(10)
	s_barrier
	s_waitcnt lgkmcnt(0)
	s_setprio 1
	s_waitcnt lgkmcnt(0)
	v_mfma_f32_16x16x32_bf16 v[116:119], v[202:205], v[168:171], v[116:119]
	v_mfma_f32_16x16x32_bf16 v[108:111], v[210:213], v[168:171], v[108:111]
	v_mfma_f32_16x16x32_bf16 v[100:103], v[202:205], v[176:179], v[100:103]
	v_mfma_f32_16x16x32_bf16 v[92:95], v[210:213], v[176:179], v[92:95]
	v_mfma_f32_16x16x32_bf16 v[84:87], v[202:205], v[184:187], v[84:87]
	v_mfma_f32_16x16x32_bf16 v[76:79], v[210:213], v[184:187], v[76:79]
	v_mfma_f32_16x16x32_bf16 v[68:71], v[202:205], v[192:195], v[68:71]
	v_mfma_f32_16x16x32_bf16 v[64:67], v[210:213], v[192:195], v[64:67]
	v_mfma_f32_16x16x32_bf16 v[116:119], v[206:209], v[172:175], v[116:119]
	v_mfma_f32_16x16x32_bf16 v[108:111], v[214:217], v[172:175], v[108:111]
	v_mfma_f32_16x16x32_bf16 v[100:103], v[206:209], v[180:183], v[100:103]
	v_mfma_f32_16x16x32_bf16 v[92:95], v[214:217], v[180:183], v[92:95]
	v_mfma_f32_16x16x32_bf16 v[84:87], v[206:209], v[188:191], v[84:87]
	v_mfma_f32_16x16x32_bf16 v[76:79], v[214:217], v[188:191], v[76:79]
	v_mfma_f32_16x16x32_bf16 v[68:71], v[206:209], v[196:199], v[68:71]
	v_mfma_f32_16x16x32_bf16 v[64:67], v[214:217], v[196:199], v[64:67]
	s_setprio 0
	s_mov_b32 m0, s42
	s_mov_b64 s[0:1], 0x80
	v_lshl_add_u64 v[218:219], v[222:223], 0, s[0:1]
	s_barrier
	ds_read_b128 v[168:171], v150 offset:49152
	ds_read_b128 v[172:175], v150 offset:50176
	ds_read_b128 v[176:179], v150 offset:51200
	ds_read_b128 v[180:183], v150 offset:52224
	ds_read_b128 v[184:187], v150 offset:53248
	ds_read_b128 v[188:191], v150 offset:54272
	ds_read_b128 v[192:195], v150 offset:55296
	ds_read_b128 v[196:199], v150 offset:56320
	global_load_lds_dwordx4 v[218:219], off
	v_lshl_add_u64 v[218:219], v[224:225], 0, s[0:1]
	s_mov_b32 m0, s43
	s_nop 0
	global_load_lds_dwordx4 v[218:219], off
	s_barrier
; #define PG8_STAGE(bufoff, gbase, voff) do { _Pragma("unroll") for (int _i = 0; _i < 2; ++_i) \
;         __builtin_amdgcn_global_load_lds((const unsigned*)((const char*)(gbase) + (voff)[_i]), (LAS unsigned*)(lds + (bufoff) + ldsw + _i * 8192), 16, 0, 0); } while (0)
; #define PG8_LDA(dst, b, h) do { _Pragma("unroll") for (int m = 0; m < 4; ++m) _Pragma("unroll") for (int k = 0; k < 2; ++k) dst[m][k] = *(const LAS bf16x8*)(lds + PG8_SA(b, h) + aoff + m * 2048 + k * 1024); } while (0)
; #define PG8_LDB(dst, b, h) do { _Pragma("unroll") for (int n = 0; n < 2; ++n) _Pragma("unroll") for (int k = 0; k < 2; ++k) dst[n][k] = *(const LAS bf16x8*)(lds + PG8_SB(b, h) + boff + n * 2048 + k * 1024); } while (0)
; #define PG8_MMA(ai, bj, At, Bt) do { __builtin_amdgcn_s_setprio(1); _Pragma("unroll") for (int m = 0; m < 4; ++m) _Pragma("unroll") for (int n = 0; n < 2; ++n) _Pragma("unroll") for (int k = 0; k < 2; ++k) \
;         acc[ai][bj][m][n] = __builtin_amdgcn_mfma_f32_16x16x32_bf16(Bt[n][k], At[m][k], acc[ai][bj][m][n], 0, 0, 0); __builtin_amdgcn_s_setprio(0); } while (0)
; #define PG8_WAIT_V(n) asm volatile("s_waitcnt vmcnt(" #n ")" ::: "memory")
; #define PG8_WAIT_L(n) asm volatile("s_waitcnt lgkmcnt(" #n ")" ::: "memory")
; #define PG8_BAR __builtin_amdgcn_s_barrier()
; #define PG8_SCHED __builtin_amdgcn_sched_barrier(0)
; template <class Epi, class Sched>
; __device__ __forceinline__ void gemm_phase(LAS unsigned char* lds, const Gemm g, const Sched& S, const Epi& E) {
;     ...
;         for (int t = 0; t < nt; t += 2) {
;             const bool last = (t == nt - 2);
;             const char* a1 = cA + (size_t)(t + 1) * kstep;
;             const char* a2 = last ? nA : cA + (size_t)(t + 2) * kstep; const char* b2 = last ? nB : cB + (size_t)(t + 2) * kstep;
;             const char* a3 = a2 + kstep; const char* b3 = b2 + kstep;
;             PG8_LDB(B0, 0, 0); PG8_SCHED; PG8_LDA(At, 0, 0); PG8_STAGE(PG8_SA(1, 1), a1 + hstep, voffA);
;             PG8_WAIT_L(8); PG8_BAR; PG8_WAIT_L(0); PG8_MMA(0, 0, At, B0); PG8_BAR; PG8_SCHED;
;             PG8_LDB(B1, 0, 1); PG8_STAGE(PG8_SB(0, 0), b2, voffB);
;     ...
;             PG8_BAR; PG8_WAIT_L(0); PG8_MMA(1, 0, At, B0); PG8_BAR; PG8_SCHED;
;             PG8_STAGE(PG8_SB(1, 1), b3 + hstep, voffB);
;             PG8_WAIT_V(6); PG8_BAR; PG8_MMA(1, 1, At, B1); PG8_BAR;
	s_waitcnt lgkmcnt(0)
	s_setprio 1
	s_waitcnt lgkmcnt(0)
	v_mfma_f32_16x16x32_bf16 v[60:63], v[152:155], v[168:171], v[60:63]
	v_mfma_f32_16x16x32_bf16 v[56:59], v[160:163], v[168:171], v[56:59]
	v_mfma_f32_16x16x32_bf16 v[48:51], v[152:155], v[176:179], v[48:51]
	v_mfma_f32_16x16x32_bf16 v[40:43], v[160:163], v[176:179], v[40:43]
	v_mfma_f32_16x16x32_bf16 v[32:35], v[152:155], v[184:187], v[32:35]
	v_mfma_f32_16x16x32_bf16 v[24:27], v[160:163], v[184:187], v[24:27]
	v_mfma_f32_16x16x32_bf16 v[16:19], v[152:155], v[192:195], v[16:19]
	v_mfma_f32_16x16x32_bf16 v[8:11], v[160:163], v[192:195], v[8:11]
	v_mfma_f32_16x16x32_bf16 v[60:63], v[156:159], v[172:175], v[60:63]
	v_mfma_f32_16x16x32_bf16 v[56:59], v[164:167], v[172:175], v[56:59]
	v_mfma_f32_16x16x32_bf16 v[48:51], v[156:159], v[180:183], v[48:51]
	v_mfma_f32_16x16x32_bf16 v[40:43], v[164:167], v[180:183], v[40:43]
	v_mfma_f32_16x16x32_bf16 v[32:35], v[156:159], v[188:191], v[32:35]
	v_mfma_f32_16x16x32_bf16 v[24:27], v[164:167], v[188:191], v[24:27]
	v_mfma_f32_16x16x32_bf16 v[16:19], v[156:159], v[196:199], v[16:19]
	v_mfma_f32_16x16x32_bf16 v[8:11], v[164:167], v[196:199], v[8:11]
	s_setprio 0
	s_barrier
	s_add_u32 s24, s24, 0x40080
	s_addc_u32 s25, s25, 0
	s_add_i32 s26, s26, s30
	s_mov_b32 m0, s26
	s_nop 0
	global_load_lds_dwordx4 v130, s[24:25]
	s_add_i32 m0, s26, 0x2000
	s_nop 0
	global_load_lds_dwordx4 v134, s[24:25]
	s_waitcnt vmcnt(10)
	s_barrier
	s_setprio 1
	v_mfma_f32_16x16x32_bf16 v[52:55], v[202:205], v[168:171], v[52:55]
	v_mfma_f32_16x16x32_bf16 v[44:47], v[210:213], v[168:171], v[44:47]
	v_mfma_f32_16x16x32_bf16 v[36:39], v[202:205], v[176:179], v[36:39]
	v_mfma_f32_16x16x32_bf16 v[28:31], v[210:213], v[176:179], v[28:31]
	v_mfma_f32_16x16x32_bf16 v[20:23], v[202:205], v[184:187], v[20:23]
	v_mfma_f32_16x16x32_bf16 v[12:15], v[210:213], v[184:187], v[12:15]
	v_mfma_f32_16x16x32_bf16 v[4:7], v[202:205], v[192:195], v[4:7]
	v_mfma_f32_16x16x32_bf16 v[0:3], v[210:213], v[192:195], v[0:3]
	v_mfma_f32_16x16x32_bf16 v[52:55], v[206:209], v[172:175], v[52:55]
	v_mfma_f32_16x16x32_bf16 v[44:47], v[214:217], v[172:175], v[44:47]
	v_mfma_f32_16x16x32_bf16 v[36:39], v[206:209], v[180:183], v[36:39]
	v_mfma_f32_16x16x32_bf16 v[28:31], v[214:217], v[180:183], v[28:31]
	v_mfma_f32_16x16x32_bf16 v[20:23], v[206:209], v[188:191], v[20:23]
	v_mfma_f32_16x16x32_bf16 v[12:15], v[214:217], v[188:191], v[12:15]
	v_mfma_f32_16x16x32_bf16 v[4:7], v[206:209], v[196:199], v[4:7]
	v_mfma_f32_16x16x32_bf16 v[0:3], v[214:217], v[196:199], v[0:3]
	s_setprio 0
	s_add_i32 s53, s53, 2
	s_add_u32 s22, s22, 0x100
	s_addc_u32 s23, s23, 0
	s_add_u32 s51, s51, 0x100
	s_addc_u32 s52, s52, 0
	s_cmp_gt_u32 s53, 13
	s_barrier
.LBB0_653:
	ds_read_b128 v[152:155], v149
	ds_read_b128 v[156:159], v149 offset:1024
	ds_read_b128 v[160:163], v149 offset:2048
	ds_read_b128 v[164:167], v149 offset:3072
	s_add_u32 s24, s22, 0xfffc0080
	s_addc_u32 s25, s23, -1
	s_cmp_eq_u32 s53, 12
	s_cselect_b32 s27, s9, s25
	s_cselect_b32 s26, s48, s24
	s_cselect_b32 s25, s7, s52
	s_cselect_b32 s24, s49, s51
	s_add_i32 m0, s21, 0xc000
	ds_read_b128 v[168:171], v150
	ds_read_b128 v[172:175], v150 offset:1024
	ds_read_b128 v[176:179], v150 offset:2048
	ds_read_b128 v[180:183], v150 offset:3072
	ds_read_b128 v[184:187], v150 offset:4096
	ds_read_b128 v[188:191], v150 offset:5120
	ds_read_b128 v[192:195], v150 offset:6144
	ds_read_b128 v[196:199], v150 offset:7168
	global_load_lds_dwordx4 v138, s[22:23]
	s_add_i32 m0, s21, 0xe000
	s_nop 0
	global_load_lds_dwordx4 v140, s[22:23]
	s_waitcnt vmcnt(10)
	s_barrier
	s_waitcnt lgkmcnt(0)
	s_setprio 1
	s_waitcnt lgkmcnt(0)
	v_mfma_f32_16x16x32_bf16 v[124:127], v[152:155], v[168:171], v[124:127]
	v_mfma_f32_16x16x32_bf16 v[120:123], v[160:163], v[168:171], v[120:123]
	v_mfma_f32_16x16x32_bf16 v[112:115], v[152:155], v[176:179], v[112:115]
	v_mfma_f32_16x16x32_bf16 v[104:107], v[160:163], v[176:179], v[104:107]
	v_mfma_f32_16x16x32_bf16 v[96:99], v[152:155], v[184:187], v[96:99]
	v_mfma_f32_16x16x32_bf16 v[88:91], v[160:163], v[184:187], v[88:91]
	v_mfma_f32_16x16x32_bf16 v[80:83], v[152:155], v[192:195], v[80:83]
	v_mfma_f32_16x16x32_bf16 v[72:75], v[160:163], v[192:195], v[72:75]
	v_mfma_f32_16x16x32_bf16 v[124:127], v[156:159], v[172:175], v[124:127]
	v_mfma_f32_16x16x32_bf16 v[120:123], v[164:167], v[172:175], v[120:123]
	v_mfma_f32_16x16x32_bf16 v[112:115], v[156:159], v[180:183], v[112:115]
	v_mfma_f32_16x16x32_bf16 v[104:107], v[164:167], v[180:183], v[104:107]
	v_mfma_f32_16x16x32_bf16 v[96:99], v[156:159], v[188:191], v[96:99]
	v_mfma_f32_16x16x32_bf16 v[88:91], v[164:167], v[188:191], v[88:91]
	v_mfma_f32_16x16x32_bf16 v[80:83], v[156:159], v[196:199], v[80:83]
	v_mfma_f32_16x16x32_bf16 v[72:75], v[164:167], v[196:199], v[72:75]
	s_setprio 0
	s_barrier
	s_add_i32 s54, s45, s30
	s_mov_b32 m0, s54
	ds_read_b128 v[202:205], v151
	ds_read_b128 v[206:209], v151 offset:1024
	ds_read_b128 v[210:213], v151 offset:2048
	ds_read_b128 v[214:217], v151 offset:3072
	global_load_lds_dwordx4 v130, s[24:25]
	s_add_i32 m0, s54, 0x2000
	s_nop 0
	global_load_lds_dwordx4 v134, s[24:25]
	s_waitcnt vmcnt(10)
	s_barrier
; #define PG8_STAGE(bufoff, gbase, voff) do { _Pragma("unroll") for (int _i = 0; _i < 2; ++_i) \
;         __builtin_amdgcn_global_load_lds((const unsigned*)((const char*)(gbase) + (voff)[_i]), (LAS unsigned*)(lds + (bufoff) + ldsw + _i * 8192), 16, 0, 0); } while (0)
; #define PG8_LDA(dst, b, h) do { _Pragma("unroll") for (int m = 0; m < 4; ++m) _Pragma("unroll") for (int k = 0; k < 2; ++k) dst[m][k] = *(const LAS bf16x8*)(lds + PG8_SA(b, h) + aoff + m * 2048 + k * 1024); } while (0)
; #define PG8_LDB(dst, b, h) do { _Pragma("unroll") for (int n = 0; n < 2; ++n) _Pragma("unroll") for (int k = 0; k < 2; ++k) dst[n][k] = *(const LAS bf16x8*)(lds + PG8_SB(b, h) + boff + n * 2048 + k * 1024); } while (0)
; #define PG8_MMA(ai, bj, At, Bt) do { __builtin_amdgcn_s_setprio(1); _Pragma("unroll") for (int m = 0; m < 4; ++m) _Pragma("unroll") for (int n = 0; n < 2; ++n) _Pragma("unroll") for (int k = 0; k < 2; ++k) \
;         acc[ai][bj][m][n] = __builtin_amdgcn_mfma_f32_16x16x32_bf16(Bt[n][k], At[m][k], acc[ai][bj][m][n], 0, 0, 0); __builtin_amdgcn_s_setprio(0); } while (0)
; #define PG8_WAIT_V(n) asm volatile("s_waitcnt vmcnt(" #n ")" ::: "memory")
; #define PG8_WAIT_L(n) asm volatile("s_waitcnt lgkmcnt(" #n ")" ::: "memory")
; #define PG8_BAR __builtin_amdgcn_s_barrier()
; #define PG8_SCHED __builtin_amdgcn_sched_barrier(0)
; template <class Epi, class Sched>
; __device__ __forceinline__ void gemm_phase(LAS unsigned char* lds, const Gemm g, const Sched& S, const Epi& E) {
;     ...
;             PG8_LDB(B1, 0, 1); PG8_STAGE(PG8_SB(0, 0), b2, voffB);
;             PG8_BAR; PG8_WAIT_L(0); PG8_MMA(0, 1, At, B1); PG8_BAR;
;             PG8_LDA(At, 0, 1); PG8_STAGE(PG8_SA(0, 0), a2, voffA);
;             PG8_BAR; PG8_WAIT_L(0); PG8_MMA(1, 0, At, B0); PG8_BAR; PG8_SCHED;
;             PG8_STAGE(PG8_SB(0, 1), b2 + hstep, voffB);
;             PG8_WAIT_V(6); PG8_BAR; PG8_MMA(1, 1, At, B1); PG8_BAR;
;             PG8_LDB(B0, 1, 0); PG8_SCHED; PG8_LDA(At, 1, 0); PG8_STAGE(PG8_SA(0, 1), a2 + hstep, voffA);
;             PG8_WAIT_L(8); PG8_BAR; PG8_WAIT_L(0); PG8_MMA(0, 0, At, B0); PG8_BAR; PG8_SCHED;
	s_waitcnt lgkmcnt(0)
	s_setprio 1
	s_waitcnt lgkmcnt(0)
	v_mfma_f32_16x16x32_bf16 v[116:119], v[202:205], v[168:171], v[116:119]
	v_mfma_f32_16x16x32_bf16 v[108:111], v[210:213], v[168:171], v[108:111]
	v_mfma_f32_16x16x32_bf16 v[100:103], v[202:205], v[176:179], v[100:103]
	v_mfma_f32_16x16x32_bf16 v[92:95], v[210:213], v[176:179], v[92:95]
	v_mfma_f32_16x16x32_bf16 v[84:87], v[202:205], v[184:187], v[84:87]
	v_mfma_f32_16x16x32_bf16 v[76:79], v[210:213], v[184:187], v[76:79]
	v_mfma_f32_16x16x32_bf16 v[68:71], v[202:205], v[192:195], v[68:71]
	v_mfma_f32_16x16x32_bf16 v[64:67], v[210:213], v[192:195], v[64:67]
	v_mfma_f32_16x16x32_bf16 v[116:119], v[206:209], v[172:175], v[116:119]
	v_mfma_f32_16x16x32_bf16 v[108:111], v[214:217], v[172:175], v[108:111]
	v_mfma_f32_16x16x32_bf16 v[100:103], v[206:209], v[180:183], v[100:103]
	v_mfma_f32_16x16x32_bf16 v[92:95], v[214:217], v[180:183], v[92:95]
	v_mfma_f32_16x16x32_bf16 v[84:87], v[206:209], v[188:191], v[84:87]
	v_mfma_f32_16x16x32_bf16 v[76:79], v[214:217], v[188:191], v[76:79]
	v_mfma_f32_16x16x32_bf16 v[68:71], v[206:209], v[196:199], v[68:71]
	v_mfma_f32_16x16x32_bf16 v[64:67], v[214:217], v[196:199], v[64:67]
	s_setprio 0
	s_mov_b32 m0, s21
	v_lshl_add_u64 v[222:223], s[26:27], 0, v[128:129]
	s_barrier
	ds_read_b128 v[168:171], v150 offset:16384
	ds_read_b128 v[172:175], v150 offset:17408
	ds_read_b128 v[176:179], v150 offset:18432
	ds_read_b128 v[180:183], v150 offset:19456
	ds_read_b128 v[184:187], v150 offset:20480
	ds_read_b128 v[188:191], v150 offset:21504
	ds_read_b128 v[192:195], v150 offset:22528
	ds_read_b128 v[196:199], v150 offset:23552
	global_load_lds_dwordx4 v128, s[26:27]
	v_lshl_add_u64 v[224:225], s[26:27], 0, v[132:133]
	s_mov_b32 m0, s31
	s_nop 0
	global_load_lds_dwordx4 v132, s[26:27]
	s_barrier
	s_waitcnt lgkmcnt(0)
	s_setprio 1
	s_waitcnt lgkmcnt(0)
	v_mfma_f32_16x16x32_bf16 v[60:63], v[152:155], v[168:171], v[60:63]
	v_mfma_f32_16x16x32_bf16 v[56:59], v[160:163], v[168:171], v[56:59]
	v_mfma_f32_16x16x32_bf16 v[48:51], v[152:155], v[176:179], v[48:51]
	v_mfma_f32_16x16x32_bf16 v[40:43], v[160:163], v[176:179], v[40:43]
	v_mfma_f32_16x16x32_bf16 v[32:35], v[152:155], v[184:187], v[32:35]
	v_mfma_f32_16x16x32_bf16 v[24:27], v[160:163], v[184:187], v[24:27]
	v_mfma_f32_16x16x32_bf16 v[16:19], v[152:155], v[192:195], v[16:19]
	v_mfma_f32_16x16x32_bf16 v[8:11], v[160:163], v[192:195], v[8:11]
	v_mfma_f32_16x16x32_bf16 v[60:63], v[156:159], v[172:175], v[60:63]
	v_mfma_f32_16x16x32_bf16 v[56:59], v[164:167], v[172:175], v[56:59]
	v_mfma_f32_16x16x32_bf16 v[48:51], v[156:159], v[180:183], v[48:51]
	v_mfma_f32_16x16x32_bf16 v[40:43], v[164:167], v[180:183], v[40:43]
	v_mfma_f32_16x16x32_bf16 v[32:35], v[156:159], v[188:191], v[32:35]
	v_mfma_f32_16x16x32_bf16 v[24:27], v[164:167], v[188:191], v[24:27]
	v_mfma_f32_16x16x32_bf16 v[16:19], v[156:159], v[196:199], v[16:19]
	v_mfma_f32_16x16x32_bf16 v[8:11], v[164:167], v[196:199], v[8:11]
	s_setprio 0
	s_barrier
	s_add_u32 s54, s24, 0x40000
	s_addc_u32 s55, s25, 0
	s_add_i32 s56, s46, s30
	s_mov_b32 m0, s56
	s_nop 0
	global_load_lds_dwordx4 v130, s[54:55]
	s_add_i32 m0, s56, 0x2000
	s_nop 0
	global_load_lds_dwordx4 v134, s[54:55]
	s_add_u32 s26, s26, 0x40000
	s_addc_u32 s27, s27, 0
	s_mov_b32 m0, s33
	s_nop 0
	global_load_lds_dwordx4 v128, s[26:27]
	s_mov_b32 m0, s34
	s_nop 0
	global_load_lds_dwordx4 v132, s[26:27]
	s_waitcnt vmcnt(12)
	s_barrier
	s_setprio 1
	v_mfma_f32_16x16x32_bf16 v[52:55], v[202:205], v[168:171], v[52:55]
	v_mfma_f32_16x16x32_bf16 v[44:47], v[210:213], v[168:171], v[44:47]
	v_mfma_f32_16x16x32_bf16 v[36:39], v[202:205], v[176:179], v[36:39]
	v_mfma_f32_16x16x32_bf16 v[28:31], v[210:213], v[176:179], v[28:31]
	v_mfma_f32_16x16x32_bf16 v[20:23], v[202:205], v[184:187], v[20:23]
	v_mfma_f32_16x16x32_bf16 v[12:15], v[210:213], v[184:187], v[12:15]
	v_mfma_f32_16x16x32_bf16 v[4:7], v[202:205], v[192:195], v[4:7]
	v_mfma_f32_16x16x32_bf16 v[0:3], v[210:213], v[192:195], v[0:3]
	v_mfma_f32_16x16x32_bf16 v[52:55], v[206:209], v[172:175], v[52:55]
	v_mfma_f32_16x16x32_bf16 v[44:47], v[214:217], v[172:175], v[44:47]
	v_mfma_f32_16x16x32_bf16 v[36:39], v[206:209], v[180:183], v[36:39]
	v_mfma_f32_16x16x32_bf16 v[28:31], v[214:217], v[180:183], v[28:31]
	v_mfma_f32_16x16x32_bf16 v[20:23], v[206:209], v[188:191], v[20:23]
	v_mfma_f32_16x16x32_bf16 v[12:15], v[214:217], v[188:191], v[12:15]
	v_mfma_f32_16x16x32_bf16 v[4:7], v[206:209], v[196:199], v[4:7]
	v_mfma_f32_16x16x32_bf16 v[0:3], v[214:217], v[196:199], v[0:3]
	s_setprio 0
	s_add_i32 s54, 0, 0x18000
	v_add_u32_e32 v136, s54, v148
	s_barrier
	ds_read_b128 v[152:155], v136
	ds_read_b128 v[156:159], v136 offset:1024
	ds_read_b128 v[160:163], v136 offset:2048
	ds_read_b128 v[164:167], v136 offset:3072
	ds_read_b128 v[168:171], v150 offset:32768
	ds_read_b128 v[172:175], v150 offset:33792
	ds_read_b128 v[176:179], v150 offset:34816
	ds_read_b128 v[180:183], v150 offset:35840
	ds_read_b128 v[184:187], v150 offset:36864
	ds_read_b128 v[188:191], v150 offset:37888
	ds_read_b128 v[192:195], v150 offset:38912
	ds_read_b128 v[196:199], v150 offset:39936
	s_waitcnt vmcnt(10)
	s_barrier
; #define PG8_STAGE(bufoff, gbase, voff) do { _Pragma("unroll") for (int _i = 0; _i < 2; ++_i) \
;         __builtin_amdgcn_global_load_lds((const unsigned*)((const char*)(gbase) + (voff)[_i]), (LAS unsigned*)(lds + (bufoff) + ldsw + _i * 8192), 16, 0, 0); } while (0)
; #define PG8_LDA(dst, b, h) do { _Pragma("unroll") for (int m = 0; m < 4; ++m) _Pragma("unroll") for (int k = 0; k < 2; ++k) dst[m][k] = *(const LAS bf16x8*)(lds + PG8_SA(b, h) + aoff + m * 2048 + k * 1024); } while (0)
; #define PG8_LDB(dst, b, h) do { _Pragma("unroll") for (int n = 0; n < 2; ++n) _Pragma("unroll") for (int k = 0; k < 2; ++k) dst[n][k] = *(const LAS bf16x8*)(lds + PG8_SB(b, h) + boff + n * 2048 + k * 1024); } while (0)
; #define PG8_MMA(ai, bj, At, Bt) do { __builtin_amdgcn_s_setprio(1); _Pragma("unroll") for (int m = 0; m < 4; ++m) _Pragma("unroll") for (int n = 0; n < 2; ++n) _Pragma("unroll") for (int k = 0; k < 2; ++k) \
;         acc[ai][bj][m][n] = __builtin_amdgcn_mfma_f32_16x16x32_bf16(Bt[n][k], At[m][k], acc[ai][bj][m][n], 0, 0, 0); __builtin_amdgcn_s_setprio(0); } while (0)
; #define PG8_WAIT_V(n) asm volatile("s_waitcnt vmcnt(" #n ")" ::: "memory")
; #define PG8_WAIT_L(n) asm volatile("s_waitcnt lgkmcnt(" #n ")" ::: "memory")
; #define PG8_BAR __builtin_amdgcn_s_barrier()
; #define PG8_SCHED __builtin_amdgcn_sched_barrier(0)
; template <class Epi, class Sched>
; __device__ __forceinline__ void gemm_phase(LAS unsigned char* lds, const Gemm g, const Sched& S, const Epi& E) {
;     ...
;             PG8_WAIT_L(8); PG8_BAR; PG8_WAIT_L(0); PG8_MMA(0, 0, At, B0); PG8_BAR; PG8_SCHED;
;             PG8_LDB(B1, 1, 1); PG8_STAGE(PG8_SB(1, 0), b3, voffB);
;             PG8_BAR; PG8_WAIT_L(0); PG8_MMA(0, 1, At, B1); PG8_BAR;
;             PG8_LDA(At, 1, 1); PG8_STAGE(PG8_SA(1, 0), a3, voffA);
;             PG8_BAR; PG8_WAIT_L(0); PG8_MMA(1, 0, At, B0); PG8_BAR; PG8_SCHED;
;             PG8_STAGE(PG8_SB(1, 1), b3 + hstep, voffB);
;             PG8_WAIT_V(6); PG8_BAR; PG8_MMA(1, 1, At, B1); PG8_BAR;
	s_waitcnt lgkmcnt(0)
	s_setprio 1
	s_waitcnt lgkmcnt(0)
	v_mfma_f32_16x16x32_bf16 v[124:127], v[152:155], v[168:171], v[124:127]
	v_mfma_f32_16x16x32_bf16 v[120:123], v[160:163], v[168:171], v[120:123]
	v_mfma_f32_16x16x32_bf16 v[112:115], v[152:155], v[176:179], v[112:115]
	v_mfma_f32_16x16x32_bf16 v[104:107], v[160:163], v[176:179], v[104:107]
	v_mfma_f32_16x16x32_bf16 v[96:99], v[152:155], v[184:187], v[96:99]
	v_mfma_f32_16x16x32_bf16 v[88:91], v[160:163], v[184:187], v[88:91]
	v_mfma_f32_16x16x32_bf16 v[80:83], v[152:155], v[192:195], v[80:83]
	v_mfma_f32_16x16x32_bf16 v[72:75], v[160:163], v[192:195], v[72:75]
	v_mfma_f32_16x16x32_bf16 v[124:127], v[156:159], v[172:175], v[124:127]
	v_mfma_f32_16x16x32_bf16 v[120:123], v[164:167], v[172:175], v[120:123]
	v_mfma_f32_16x16x32_bf16 v[112:115], v[156:159], v[180:183], v[112:115]
	v_mfma_f32_16x16x32_bf16 v[104:107], v[164:167], v[180:183], v[104:107]
	v_mfma_f32_16x16x32_bf16 v[96:99], v[156:159], v[188:191], v[96:99]
	v_mfma_f32_16x16x32_bf16 v[88:91], v[164:167], v[188:191], v[88:91]
	v_mfma_f32_16x16x32_bf16 v[80:83], v[156:159], v[196:199], v[80:83]
	v_mfma_f32_16x16x32_bf16 v[72:75], v[164:167], v[196:199], v[72:75]
	s_setprio 0
	s_barrier
	s_add_i32 s26, 0, 0x1c000
	s_add_i32 s27, s54, s30
	v_add_u32_e32 v136, s26, v148
	s_add_u32 s0, s24, 0x80
	s_addc_u32 s1, s25, 0
	s_mov_b32 m0, s27
	ds_read_b128 v[202:205], v136
	ds_read_b128 v[206:209], v136 offset:1024
	ds_read_b128 v[210:213], v136 offset:2048
	ds_read_b128 v[214:217], v136 offset:3072
	global_load_lds_dwordx4 v130, s[0:1]
	s_add_i32 m0, s27, 0x2000
	s_nop 0
	global_load_lds_dwordx4 v134, s[0:1]
	s_waitcnt vmcnt(10)
	s_barrier
	s_waitcnt lgkmcnt(0)
	s_setprio 1
	s_waitcnt lgkmcnt(0)
	v_mfma_f32_16x16x32_bf16 v[116:119], v[202:205], v[168:171], v[116:119]
	v_mfma_f32_16x16x32_bf16 v[108:111], v[210:213], v[168:171], v[108:111]
	v_mfma_f32_16x16x32_bf16 v[100:103], v[202:205], v[176:179], v[100:103]
	v_mfma_f32_16x16x32_bf16 v[92:95], v[210:213], v[176:179], v[92:95]
	v_mfma_f32_16x16x32_bf16 v[84:87], v[202:205], v[184:187], v[84:87]
	v_mfma_f32_16x16x32_bf16 v[76:79], v[210:213], v[184:187], v[76:79]
	v_mfma_f32_16x16x32_bf16 v[68:71], v[202:205], v[192:195], v[68:71]
	v_mfma_f32_16x16x32_bf16 v[64:67], v[210:213], v[192:195], v[64:67]
	v_mfma_f32_16x16x32_bf16 v[116:119], v[206:209], v[172:175], v[116:119]
	v_mfma_f32_16x16x32_bf16 v[108:111], v[214:217], v[172:175], v[108:111]
	v_mfma_f32_16x16x32_bf16 v[100:103], v[206:209], v[180:183], v[100:103]
	v_mfma_f32_16x16x32_bf16 v[92:95], v[214:217], v[180:183], v[92:95]
	v_mfma_f32_16x16x32_bf16 v[84:87], v[206:209], v[188:191], v[84:87]
	v_mfma_f32_16x16x32_bf16 v[76:79], v[214:217], v[188:191], v[76:79]
	v_mfma_f32_16x16x32_bf16 v[68:71], v[206:209], v[196:199], v[68:71]
	v_mfma_f32_16x16x32_bf16 v[64:67], v[214:217], v[196:199], v[64:67]
	s_setprio 0
	s_mov_b32 m0, s42
	s_mov_b64 s[0:1], 0x80
	v_lshl_add_u64 v[218:219], v[222:223], 0, s[0:1]
	s_barrier
	ds_read_b128 v[168:171], v150 offset:49152
	ds_read_b128 v[172:175], v150 offset:50176
	ds_read_b128 v[176:179], v150 offset:51200
	ds_read_b128 v[180:183], v150 offset:52224
	ds_read_b128 v[184:187], v150 offset:53248
	ds_read_b128 v[188:191], v150 offset:54272
	ds_read_b128 v[192:195], v150 offset:55296
	ds_read_b128 v[196:199], v150 offset:56320
	global_load_lds_dwordx4 v[218:219], off
	v_lshl_add_u64 v[218:219], v[224:225], 0, s[0:1]
	s_mov_b32 m0, s43
	s_nop 0
	global_load_lds_dwordx4 v[218:219], off
	s_barrier
	s_waitcnt lgkmcnt(0)
	s_setprio 1
	s_waitcnt lgkmcnt(0)
	v_mfma_f32_16x16x32_bf16 v[60:63], v[152:155], v[168:171], v[60:63]
	v_mfma_f32_16x16x32_bf16 v[56:59], v[160:163], v[168:171], v[56:59]
	v_mfma_f32_16x16x32_bf16 v[48:51], v[152:155], v[176:179], v[48:51]
	v_mfma_f32_16x16x32_bf16 v[40:43], v[160:163], v[176:179], v[40:43]
	v_mfma_f32_16x16x32_bf16 v[32:35], v[152:155], v[184:187], v[32:35]
	v_mfma_f32_16x16x32_bf16 v[24:27], v[160:163], v[184:187], v[24:27]
	v_mfma_f32_16x16x32_bf16 v[16:19], v[152:155], v[192:195], v[16:19]
	v_mfma_f32_16x16x32_bf16 v[8:11], v[160:163], v[192:195], v[8:11]
	v_mfma_f32_16x16x32_bf16 v[60:63], v[156:159], v[172:175], v[60:63]
	v_mfma_f32_16x16x32_bf16 v[56:59], v[164:167], v[172:175], v[56:59]
	v_mfma_f32_16x16x32_bf16 v[48:51], v[156:159], v[180:183], v[48:51]
	v_mfma_f32_16x16x32_bf16 v[40:43], v[164:167], v[180:183], v[40:43]
	v_mfma_f32_16x16x32_bf16 v[32:35], v[156:159], v[188:191], v[32:35]
	v_mfma_f32_16x16x32_bf16 v[24:27], v[164:167], v[188:191], v[24:27]
	v_mfma_f32_16x16x32_bf16 v[16:19], v[156:159], v[196:199], v[16:19]
	v_mfma_f32_16x16x32_bf16 v[8:11], v[164:167], v[196:199], v[8:11]
	s_setprio 0
	s_barrier
	s_add_u32 s24, s24, 0x40080
	s_addc_u32 s25, s25, 0
	s_add_i32 s26, s26, s30
	s_mov_b32 m0, s26
	s_nop 0
	global_load_lds_dwordx4 v130, s[24:25]
	s_add_i32 m0, s26, 0x2000
	s_nop 0
	global_load_lds_dwordx4 v134, s[24:25]
	s_waitcnt vmcnt(10)
	s_barrier
	s_setprio 1
	v_mfma_f32_16x16x32_bf16 v[52:55], v[202:205], v[168:171], v[52:55]
	v_mfma_f32_16x16x32_bf16 v[44:47], v[210:213], v[168:171], v[44:47]
	v_mfma_f32_16x16x32_bf16 v[36:39], v[202:205], v[176:179], v[36:39]
	v_mfma_f32_16x16x32_bf16 v[28:31], v[210:213], v[176:179], v[28:31]
	v_mfma_f32_16x16x32_bf16 v[20:23], v[202:205], v[184:187], v[20:23]
	v_mfma_f32_16x16x32_bf16 v[12:15], v[210:213], v[184:187], v[12:15]
	v_mfma_f32_16x16x32_bf16 v[4:7], v[202:205], v[192:195], v[4:7]
	v_mfma_f32_16x16x32_bf16 v[0:3], v[210:213], v[192:195], v[0:3]
	v_mfma_f32_16x16x32_bf16 v[52:55], v[206:209], v[172:175], v[52:55]
	v_mfma_f32_16x16x32_bf16 v[44:47], v[214:217], v[172:175], v[44:47]
	v_mfma_f32_16x16x32_bf16 v[36:39], v[206:209], v[180:183], v[36:39]
	v_mfma_f32_16x16x32_bf16 v[28:31], v[214:217], v[180:183], v[28:31]
	v_mfma_f32_16x16x32_bf16 v[20:23], v[206:209], v[188:191], v[20:23]
	v_mfma_f32_16x16x32_bf16 v[12:15], v[214:217], v[188:191], v[12:15]
	v_mfma_f32_16x16x32_bf16 v[4:7], v[206:209], v[196:199], v[4:7]
	v_mfma_f32_16x16x32_bf16 v[0:3], v[214:217], v[196:199], v[0:3]
	s_setprio 0
	s_add_i32 s53, s53, 2
	s_add_u32 s22, s22, 0x100
	s_addc_u32 s23, s23, 0
	s_add_u32 s51, s51, 0x100
	s_addc_u32 s52, s52, 0
	s_cmp_gt_u32 s53, 13
	s_barrier
; __device__ __forceinline__ unsigned cvt_pk_bf16(float lo, float hi) { unsigned r; asm volatile("v_cvt_pk_bf16_f32 %0, %1, %2" : "=v"(r) : "v"(lo), "v"(hi)); return r; }
; #define PG8_MMA(ai, bj, At, Bt) do { __builtin_amdgcn_s_setprio(1); _Pragma("unroll") for (int m = 0; m < 4; ++m) _Pragma("unroll") for (int n = 0; n < 2; ++n) _Pragma("unroll") for (int k = 0; k < 2; ++k) \
;         acc[ai][bj][m][n] = __builtin_amdgcn_mfma_f32_16x16x32_bf16(Bt[n][k], At[m][k], acc[ai][bj][m][n], 0, 0, 0); __builtin_amdgcn_s_setprio(0); } while (0)
; #define PG8_WAIT_V(n) asm volatile("s_waitcnt vmcnt(" #n ")" ::: "memory")
; #define PG8_BAR __builtin_amdgcn_s_barrier()
; template <class Epi, class Sched>
; __device__ __forceinline__ void gemm_phase(LAS unsigned char* lds, const Gemm g, const Sched& S, const Epi& E) {
;     ...
;             PG8_WAIT_V(6); PG8_BAR; PG8_MMA(1, 1, At, B1); PG8_BAR;
;         }
;         E(acc, cur, wr, wc, fr, fq);
;     __device__ __forceinline__ void operator()(const AccT& acc, const Unit& u, int wr, int wc, int fr, int fq) const {
;         asm volatile("" : "+v"(fr), "+v"(fq));
;         const int rbase = u.pm * 256 + wr * 64 + fr;
;         const int tb = u.pn * 256 + wc * 32 + 8 * fq;
; #pragma unroll
;         for (int ai = 0; ai < 2; ++ai)
; #pragma unroll
;             for (int m = 0; m < 4; ++m) {
;                 const int gm = rbase + ai * 128 + m * 16;
; #pragma unroll
;                 for (int bj = 0; bj < 2; ++bj) {
;                     const int t0 = tb + bj * 128;
;                     const f32x4 v0 = acc[ai][bj][m][0], v1 = acc[ai][bj][m][1];
;                     u32x4 w; w.x = cvt_pk_bf16(v0[0], v0[1]); w.y = cvt_pk_bf16(v0[2], v0[3]); w.z = cvt_pk_bf16(v1[0], v1[1]); w.w = cvt_pk_bf16(v1[2], v1[3]);
;                     *(u32x4*)(YT + ((size_t)((t0 >> 10) * 512 + gm)) * 2048 + part * 1024 + (t0 & 1023)) = w;
;                 }
;             }
;     }
	s_cbranch_scc0 .LBB0_653
	v_mov_b32_e32 v136, v147
	v_mov_b32_e32 v152, v146
	s_lshl_b32 s7, s20, 8
	s_add_i32 s7, s7, s36
	v_add_u32_e32 v152, s7, v152
	s_lshl_b32 s7, s47, 8
	s_or_b32 s7, s7, s37
	v_lshl_add_u32 v153, v136, 3, s7
	v_cvt_pk_bf16_f32 v124, v124, v125
	v_cvt_pk_bf16_f32 v125, v126, v127
	v_cvt_pk_bf16_f32 v126, v120, v121
	v_ashrrev_i32_e32 v120, 1, v153
	v_cvt_pk_bf16_f32 v127, v122, v123
	v_and_b32_e32 v122, 0xfffffe00, v120
	v_add_u32_e32 v120, v122, v152
	v_ashrrev_i32_e32 v121, 31, v120
	v_lshlrev_b64 v[120:121], 12, v[120:121]
	v_and_b32_e32 v123, 0x3f8, v153
	v_lshl_add_u64 v[120:121], s[68:69], 0, v[120:121]
	v_lshlrev_b32_e32 v136, 1, v123
	v_lshl_add_u64 v[120:121], v[120:121], 0, v[136:137]
	global_store_dwordx4 v[120:121], v[124:127], off
	v_add_u32_e32 v120, 0x80, v153
	v_cvt_pk_bf16_f32 v116, v116, v117
	v_cvt_pk_bf16_f32 v117, v118, v119
	v_cvt_pk_bf16_f32 v118, v108, v109
	v_ashrrev_i32_e32 v108, 1, v120
	v_and_b32_e32 v121, 0xfffffe00, v108
	v_add_u32_e32 v108, v121, v152
	v_ashrrev_i32_e32 v109, 31, v108
	v_lshlrev_b64 v[108:109], 12, v[108:109]
	v_cvt_pk_bf16_f32 v119, v110, v111
	v_lshl_add_u64 v[110:111], s[68:69], 0, v[108:109]
	v_and_b32_e32 v108, 0x3f8, v120
	v_lshlrev_b32_e32 v108, 1, v108
	v_mov_b32_e32 v109, v137
	v_lshl_add_u64 v[110:111], v[110:111], 0, v[108:109]
	global_store_dwordx4 v[110:111], v[116:119], off
	v_cvt_pk_bf16_f32 v110, v112, v113
	v_cvt_pk_bf16_f32 v111, v114, v115
	v_cvt_pk_bf16_f32 v112, v104, v105
	v_cvt_pk_bf16_f32 v113, v106, v107
	s_and_b64 vcc, exec, s[4:5]
	s_nop 0
	v_add_u32_e32 v116, 16, v152
	v_add_u32_e32 v104, v122, v116
	v_ashrrev_i32_e32 v105, 31, v104
	v_lshlrev_b64 v[104:105], 12, v[104:105]
	v_lshl_add_u64 v[104:105], s[68:69], 0, v[104:105]
	v_lshl_add_u64 v[104:105], v[104:105], 0, v[136:137]
	global_store_dwordx4 v[104:105], v[110:113], off
	v_cvt_pk_bf16_f32 v100, v100, v101
	v_cvt_pk_bf16_f32 v101, v102, v103
	v_cvt_pk_bf16_f32 v102, v92, v93
	v_add_u32_e32 v92, v121, v116
	v_ashrrev_i32_e32 v93, 31, v92
	v_lshlrev_b64 v[92:93], 12, v[92:93]
	v_lshl_add_u64 v[92:93], s[68:69], 0, v[92:93]
	v_lshl_add_u64 v[92:93], v[92:93], 0, v[108:109]
	v_cvt_pk_bf16_f32 v103, v94, v95
	global_store_dwordx4 v[92:93], v[100:103], off
	v_cvt_pk_bf16_f32 v92, v96, v97
	v_cvt_pk_bf16_f32 v93, v98, v99
	v_cvt_pk_bf16_f32 v94, v88, v89
	v_cvt_pk_bf16_f32 v95, v90, v91
	s_mov_b32 s47, s6
	s_nop 0
	v_add_u32_e32 v100, 32, v152
	v_add_u32_e32 v88, v122, v100
	v_ashrrev_i32_e32 v89, 31, v88
	v_lshlrev_b64 v[88:89], 12, v[88:89]
	v_lshl_add_u64 v[88:89], s[68:69], 0, v[88:89]
	v_lshl_add_u64 v[88:89], v[88:89], 0, v[136:137]
	global_store_dwordx4 v[88:89], v[92:95], off
	v_cvt_pk_bf16_f32 v84, v84, v85
	v_cvt_pk_bf16_f32 v85, v86, v87
	v_cvt_pk_bf16_f32 v86, v76, v77
	v_add_u32_e32 v76, v121, v100
	v_ashrrev_i32_e32 v77, 31, v76
	v_lshlrev_b64 v[76:77], 12, v[76:77]
	v_lshl_add_u64 v[76:77], s[68:69], 0, v[76:77]
	v_lshl_add_u64 v[76:77], v[76:77], 0, v[108:109]
	v_cvt_pk_bf16_f32 v87, v78, v79
	global_store_dwordx4 v[76:77], v[84:87], off
	v_cvt_pk_bf16_f32 v76, v80, v81
	v_cvt_pk_bf16_f32 v77, v82, v83
	v_cvt_pk_bf16_f32 v78, v72, v73
	v_cvt_pk_bf16_f32 v79, v74, v75
	s_mov_b32 s20, s8
	s_nop 0
	v_add_u32_e32 v84, 48, v152
	v_add_u32_e32 v72, v122, v84
	v_ashrrev_i32_e32 v73, 31, v72
	v_lshlrev_b64 v[72:73], 12, v[72:73]
	v_lshl_add_u64 v[72:73], s[68:69], 0, v[72:73]
	v_lshl_add_u64 v[72:73], v[72:73], 0, v[136:137]
	global_store_dwordx4 v[72:73], v[76:79], off
	v_cvt_pk_bf16_f32 v68, v68, v69
	v_cvt_pk_bf16_f32 v69, v70, v71
; __device__ __forceinline__ unsigned cvt_pk_bf16(float lo, float hi) { unsigned r; asm volatile("v_cvt_pk_bf16_f32 %0, %1, %2" : "=v"(r) : "v"(lo), "v"(hi)); return r; }
; #define PG8_WAIT_V(n) asm volatile("s_waitcnt vmcnt(" #n ")" ::: "memory")
; #define PG8_BAR __builtin_amdgcn_s_barrier()
; template <class Epi, class Sched>
; __device__ __forceinline__ void gemm_phase(LAS unsigned char* lds, const Gemm g, const Sched& S, const Epi& E) {
;     ...
;         E(acc, cur, wr, wc, fr, fq);
;         if (!has_next) break;
; #pragma unroll
;         for (int a = 0; a < 2; ++a)
; #pragma unroll
;             for (int b = 0; b < 2; ++b)
; #pragma unroll
;                 for (int m = 0; m < 4; ++m)
; #pragma unroll
;                     for (int n = 0; n < 2; ++n) acc[a][b][m][n] = (f32x4){0.f, 0.f, 0.f, 0.f};
;         cur = nxt; cA = nA; cB = nB; ++ui;
;     }
;     PG8_WAIT_V(0);
;     if (wr == 0) PG8_BAR;
;     PG8_BAR;
;     __device__ __forceinline__ void operator()(const AccT& acc, const Unit& u, int wr, int wc, int fr, int fq) const {
;         asm volatile("" : "+v"(fr), "+v"(fq));
;         const int rbase = u.pm * 256 + wr * 64 + fr;
;         const int tb = u.pn * 256 + wc * 32 + 8 * fq;
; #pragma unroll
;         for (int ai = 0; ai < 2; ++ai)
; #pragma unroll
;             for (int m = 0; m < 4; ++m) {
;                 const int gm = rbase + ai * 128 + m * 16;
; #pragma unroll
;                 for (int bj = 0; bj < 2; ++bj) {
;                     const int t0 = tb + bj * 128;
;                     const f32x4 v0 = acc[ai][bj][m][0], v1 = acc[ai][bj][m][1];
;                     u32x4 w; w.x = cvt_pk_bf16(v0[0], v0[1]); w.y = cvt_pk_bf16(v0[2], v0[3]); w.z = cvt_pk_bf16(v1[0], v1[1]); w.w = cvt_pk_bf16(v1[2], v1[3]);
;                     *(u32x4*)(YT + ((size_t)((t0 >> 10) * 512 + gm)) * 2048 + part * 1024 + (t0 & 1023)) = w;
;                 }
;             }
;     }
	v_cvt_pk_bf16_f32 v70, v64, v65
	v_add_u32_e32 v64, v121, v84
	v_ashrrev_i32_e32 v65, 31, v64
	v_lshlrev_b64 v[64:65], 12, v[64:65]
	v_lshl_add_u64 v[64:65], s[68:69], 0, v[64:65]
	v_lshl_add_u64 v[64:65], v[64:65], 0, v[108:109]
	v_cvt_pk_bf16_f32 v71, v66, v67
	global_store_dwordx4 v[64:65], v[68:71], off
	v_add_u32_e32 v64, 0x80, v152
	v_cvt_pk_bf16_f32 v60, v60, v61
	v_cvt_pk_bf16_f32 v61, v62, v63
	v_cvt_pk_bf16_f32 v62, v56, v57
	v_add_u32_e32 v56, v122, v64
	v_ashrrev_i32_e32 v57, 31, v56
	v_lshlrev_b64 v[56:57], 12, v[56:57]
	v_lshl_add_u64 v[56:57], s[68:69], 0, v[56:57]
	v_lshl_add_u64 v[56:57], v[56:57], 0, v[136:137]
	v_cvt_pk_bf16_f32 v63, v58, v59
	global_store_dwordx4 v[56:57], v[60:63], off
	v_cvt_pk_bf16_f32 v52, v52, v53
	v_cvt_pk_bf16_f32 v53, v54, v55
	v_cvt_pk_bf16_f32 v54, v44, v45
	v_add_u32_e32 v44, v121, v64
	v_ashrrev_i32_e32 v45, 31, v44
	v_lshlrev_b64 v[44:45], 12, v[44:45]
	v_lshl_add_u64 v[44:45], s[68:69], 0, v[44:45]
	v_lshl_add_u64 v[44:45], v[44:45], 0, v[108:109]
	v_cvt_pk_bf16_f32 v55, v46, v47
	global_store_dwordx4 v[44:45], v[52:55], off
	v_cvt_pk_bf16_f32 v44, v48, v49
	v_cvt_pk_bf16_f32 v45, v50, v51
	v_cvt_pk_bf16_f32 v46, v40, v41
	v_cvt_pk_bf16_f32 v47, v42, v43
	s_mov_b64 s[24:25], s[18:19]
	s_nop 0
	v_add_u32_e32 v52, 0x90, v152
	v_add_u32_e32 v40, v122, v52
	v_ashrrev_i32_e32 v41, 31, v40
	v_lshlrev_b64 v[40:41], 12, v[40:41]
	v_lshl_add_u64 v[40:41], s[68:69], 0, v[40:41]
	v_lshl_add_u64 v[40:41], v[40:41], 0, v[136:137]
	global_store_dwordx4 v[40:41], v[44:47], off
	v_cvt_pk_bf16_f32 v36, v36, v37
	v_cvt_pk_bf16_f32 v37, v38, v39
	v_cvt_pk_bf16_f32 v38, v28, v29
	v_add_u32_e32 v28, v121, v52
	v_ashrrev_i32_e32 v29, 31, v28
	v_lshlrev_b64 v[28:29], 12, v[28:29]
	v_lshl_add_u64 v[28:29], s[68:69], 0, v[28:29]
	v_lshl_add_u64 v[28:29], v[28:29], 0, v[108:109]
	v_cvt_pk_bf16_f32 v39, v30, v31
	global_store_dwordx4 v[28:29], v[36:39], off
	v_cvt_pk_bf16_f32 v28, v32, v33
	v_cvt_pk_bf16_f32 v29, v34, v35
	v_cvt_pk_bf16_f32 v30, v24, v25
	v_cvt_pk_bf16_f32 v31, v26, v27
	s_mov_b64 s[22:23], s[16:17]
	s_nop 0
	v_add_u32_e32 v36, 0xa0, v152
	v_add_u32_e32 v24, v122, v36
	v_ashrrev_i32_e32 v25, 31, v24
	v_lshlrev_b64 v[24:25], 12, v[24:25]
	v_lshl_add_u64 v[24:25], s[68:69], 0, v[24:25]
	v_lshl_add_u64 v[24:25], v[24:25], 0, v[136:137]
	global_store_dwordx4 v[24:25], v[28:31], off
	v_cvt_pk_bf16_f32 v20, v20, v21
	v_cvt_pk_bf16_f32 v21, v22, v23
	v_cvt_pk_bf16_f32 v22, v12, v13
	v_add_u32_e32 v12, v121, v36
	v_ashrrev_i32_e32 v13, 31, v12
	v_lshlrev_b64 v[12:13], 12, v[12:13]
	v_lshl_add_u64 v[12:13], s[68:69], 0, v[12:13]
	v_lshl_add_u64 v[12:13], v[12:13], 0, v[108:109]
	v_cvt_pk_bf16_f32 v23, v14, v15
	global_store_dwordx4 v[12:13], v[20:23], off
	v_cvt_pk_bf16_f32 v12, v16, v17
	v_cvt_pk_bf16_f32 v13, v18, v19
	v_cvt_pk_bf16_f32 v14, v8, v9
	v_cvt_pk_bf16_f32 v15, v10, v11
	s_nop 1
	v_add_u32_e32 v20, 0xb0, v152
	v_add_u32_e32 v8, v122, v20
	v_ashrrev_i32_e32 v9, 31, v8
	v_lshlrev_b64 v[8:9], 12, v[8:9]
	v_lshl_add_u64 v[8:9], s[68:69], 0, v[8:9]
	v_lshl_add_u64 v[8:9], v[8:9], 0, v[136:137]
	global_store_dwordx4 v[8:9], v[12:15], off
	v_cvt_pk_bf16_f32 v4, v4, v5
	v_cvt_pk_bf16_f32 v5, v6, v7
	v_cvt_pk_bf16_f32 v6, v0, v1
	v_add_u32_e32 v0, v121, v20
	v_ashrrev_i32_e32 v1, 31, v0
	v_lshlrev_b64 v[0:1], 12, v[0:1]
	v_lshl_add_u64 v[0:1], s[68:69], 0, v[0:1]
	v_lshl_add_u64 v[0:1], v[0:1], 0, v[108:109]
	v_cvt_pk_bf16_f32 v7, v2, v3
	global_store_dwordx4 v[0:1], v[4:7], off
	s_cbranch_vccz .LBB0_646
	s_waitcnt vmcnt(0)
	s_cmpk_gt_u32 s28, 0xff
	s_cbranch_scc1 .LBB0_657
	s_barrier

; #define PG8_STAGE(bufoff, gbase, voff) do { _Pragma("unroll") for (int _i = 0; _i < 2; ++_i) \
;         __builtin_amdgcn_global_load_lds((const unsigned*)((const char*)(gbase) + (voff)[_i]), (LAS unsigned*)(lds + (bufoff) + ldsw + _i * 8192), 16, 0, 0); } while (0)
; #define PG8_LDA(dst, b, h) do { _Pragma("unroll") for (int m = 0; m < 4; ++m) _Pragma("unroll") for (int k = 0; k < 2; ++k) dst[m][k] = *(const LAS bf16x8*)(lds + PG8_SA(b, h) + aoff + m * 2048 + k * 1024); } while (0)
; #define PG8_LDB(dst, b, h) do { _Pragma("unroll") for (int n = 0; n < 2; ++n) _Pragma("unroll") for (int k = 0; k < 2; ++k) dst[n][k] = *(const LAS bf16x8*)(lds + PG8_SB(b, h) + boff + n * 2048 + k * 1024); } while (0)
; #define PG8_MMA(ai, bj, At, Bt) do { __builtin_amdgcn_s_setprio(1); _Pragma("unroll") for (int m = 0; m < 4; ++m) _Pragma("unroll") for (int n = 0; n < 2; ++n) _Pragma("unroll") for (int k = 0; k < 2; ++k) \
;         acc[ai][bj][m][n] = __builtin_amdgcn_mfma_f32_16x16x32_bf16(Bt[n][k], At[m][k], acc[ai][bj][m][n], 0, 0, 0); __builtin_amdgcn_s_setprio(0); } while (0)
; #define PG8_WAIT_L(n) asm volatile("s_waitcnt lgkmcnt(" #n ")" ::: "memory")
; template <class Epi, class Sched>
; __device__ __forceinline__ void gemm_phase(LAS unsigned char* lds, const Gemm g, const Sched& S, const Epi& E) {
;     ...
;         const bool has_next = S.next(ui + 1, nxt);
;         const char* nA = has_next ? (const char*)g.A + (size_t)nxt.pm * tstep : cA; const char* nB = has_next ? (const char*)g.Bt + (size_t)nxt.pn * tstep : cB;
;         for (int t = 0; t < nt; t += 2) {
;             const bool last = (t == nt - 2);
;             const char* a1 = cA + (size_t)(t + 1) * kstep;
;             const char* a2 = last ? nA : cA + (size_t)(t + 2) * kstep; const char* b2 = last ? nB : cB + (size_t)(t + 2) * kstep;
;             const char* a3 = a2 + kstep; const char* b3 = b2 + kstep;
;             PG8_LDB(B0, 0, 0); PG8_SCHED; PG8_LDA(At, 0, 0); PG8_STAGE(PG8_SA(1, 1), a1 + hstep, voffA);
;             PG8_WAIT_L(8); PG8_BAR; PG8_WAIT_L(0); PG8_MMA(0, 0, At, B0); PG8_BAR; PG8_SCHED;
;             PG8_LDB(B1, 0, 1); PG8_STAGE(PG8_SB(0, 0), b2, voffB);
;             PG8_BAR; PG8_WAIT_L(0); PG8_MMA(0, 1, At, B1); PG8_BAR;
;             PG8_LDA(At, 0, 1); PG8_STAGE(PG8_SA(0, 0), a2, voffA);
;             PG8_BAR; PG8_WAIT_L(0); PG8_MMA(1, 0, At, B0); PG8_BAR; PG8_SCHED;
.LBB0_672:
	s_ashr_i32 s9, s8, 31
	v_cmp_lt_i64_e32 vcc, s[12:13], v[142:143]
	s_lshl_b64 s[12:13], s[8:9], 19
	s_add_u32 s12, s26, s12
	s_addc_u32 s13, s27, s13
	s_and_b64 s[14:15], vcc, exec
	s_cselect_b32 s9, s13, s19
	s_cselect_b32 s46, s12, s18
	s_ashr_i32 s7, s6, 31
	s_lshl_b64 s[14:15], s[6:7], 19
	s_add_u32 s14, s10, s14
	s_addc_u32 s15, s11, s15
	s_and_b64 s[22:23], vcc, exec
	s_cselect_b32 s7, s15, s21
	s_cselect_b32 s47, s14, s20
	s_add_u32 s18, s18, 0x40080
	s_addc_u32 s19, s19, 0
	s_add_u32 s48, s20, 0x100
	s_addc_u32 s49, s21, 0
	s_mov_b32 s51, -2
	s_waitcnt lgkmcnt(0)
	ds_read_b128 v[152:155], v149
	ds_read_b128 v[156:159], v149 offset:1024
	ds_read_b128 v[160:163], v149 offset:2048
	ds_read_b128 v[164:167], v149 offset:3072
	s_add_u32 s20, s18, 0xfffc0080
	s_addc_u32 s21, s19, -1
	s_cmp_eq_u32 s51, 12
	s_cselect_b32 s23, s9, s21
	s_cselect_b32 s22, s46, s20
	s_cselect_b32 s21, s7, s49
	s_cselect_b32 s20, s47, s48
	s_add_i32 m0, s17, 0xc000
	ds_read_b128 v[168:171], v150
	ds_read_b128 v[172:175], v150 offset:1024
	ds_read_b128 v[176:179], v150 offset:2048
	ds_read_b128 v[180:183], v150 offset:3072
	ds_read_b128 v[184:187], v150 offset:4096
	ds_read_b128 v[188:191], v150 offset:5120
	ds_read_b128 v[192:195], v150 offset:6144
	ds_read_b128 v[196:199], v150 offset:7168
	global_load_lds_dwordx4 v138, s[18:19]
	s_add_i32 m0, s17, 0xe000
	s_nop 0
	global_load_lds_dwordx4 v140, s[18:19]
	s_waitcnt vmcnt(10)
	s_barrier
	s_waitcnt lgkmcnt(0)
	s_setprio 1
	s_waitcnt lgkmcnt(0)
	v_mfma_f32_16x16x32_bf16 v[124:127], v[152:155], v[168:171], 0
	v_mfma_f32_16x16x32_bf16 v[120:123], v[160:163], v[168:171], 0
	v_mfma_f32_16x16x32_bf16 v[112:115], v[152:155], v[176:179], 0
	v_mfma_f32_16x16x32_bf16 v[104:107], v[160:163], v[176:179], 0
	v_mfma_f32_16x16x32_bf16 v[96:99], v[152:155], v[184:187], 0
	v_mfma_f32_16x16x32_bf16 v[88:91], v[160:163], v[184:187], 0
	v_mfma_f32_16x16x32_bf16 v[80:83], v[152:155], v[192:195], 0
	v_mfma_f32_16x16x32_bf16 v[72:75], v[160:163], v[192:195], 0
	v_mfma_f32_16x16x32_bf16 v[124:127], v[156:159], v[172:175], v[124:127]
	v_mfma_f32_16x16x32_bf16 v[120:123], v[164:167], v[172:175], v[120:123]
	v_mfma_f32_16x16x32_bf16 v[112:115], v[156:159], v[180:183], v[112:115]
	v_mfma_f32_16x16x32_bf16 v[104:107], v[164:167], v[180:183], v[104:107]
	v_mfma_f32_16x16x32_bf16 v[96:99], v[156:159], v[188:191], v[96:99]
	v_mfma_f32_16x16x32_bf16 v[88:91], v[164:167], v[188:191], v[88:91]
	v_mfma_f32_16x16x32_bf16 v[80:83], v[156:159], v[196:199], v[80:83]
	v_mfma_f32_16x16x32_bf16 v[72:75], v[164:167], v[196:199], v[72:75]
	s_setprio 0
	s_barrier
	s_add_i32 s52, s43, s28
	s_mov_b32 m0, s52
	ds_read_b128 v[202:205], v151
	ds_read_b128 v[206:209], v151 offset:1024
	ds_read_b128 v[210:213], v151 offset:2048
	ds_read_b128 v[214:217], v151 offset:3072
	global_load_lds_dwordx4 v130, s[20:21]
	s_add_i32 m0, s52, 0x2000
	s_nop 0
	global_load_lds_dwordx4 v134, s[20:21]
	s_waitcnt vmcnt(10)
	s_barrier
	s_waitcnt lgkmcnt(0)
	s_setprio 1
	s_waitcnt lgkmcnt(0)
	v_mfma_f32_16x16x32_bf16 v[116:119], v[202:205], v[168:171], 0
	v_mfma_f32_16x16x32_bf16 v[108:111], v[210:213], v[168:171], 0
	v_mfma_f32_16x16x32_bf16 v[100:103], v[202:205], v[176:179], 0
	v_mfma_f32_16x16x32_bf16 v[92:95], v[210:213], v[176:179], 0
	v_mfma_f32_16x16x32_bf16 v[84:87], v[202:205], v[184:187], 0
	v_mfma_f32_16x16x32_bf16 v[76:79], v[210:213], v[184:187], 0
	v_mfma_f32_16x16x32_bf16 v[68:71], v[202:205], v[192:195], 0
	v_mfma_f32_16x16x32_bf16 v[64:67], v[210:213], v[192:195], 0
	v_mfma_f32_16x16x32_bf16 v[116:119], v[206:209], v[172:175], v[116:119]
	v_mfma_f32_16x16x32_bf16 v[108:111], v[214:217], v[172:175], v[108:111]
	v_mfma_f32_16x16x32_bf16 v[100:103], v[206:209], v[180:183], v[100:103]
	v_mfma_f32_16x16x32_bf16 v[92:95], v[214:217], v[180:183], v[92:95]
	v_mfma_f32_16x16x32_bf16 v[84:87], v[206:209], v[188:191], v[84:87]
	v_mfma_f32_16x16x32_bf16 v[76:79], v[214:217], v[188:191], v[76:79]
	v_mfma_f32_16x16x32_bf16 v[68:71], v[206:209], v[196:199], v[68:71]
	v_mfma_f32_16x16x32_bf16 v[64:67], v[214:217], v[196:199], v[64:67]
	s_setprio 0
	s_mov_b32 m0, s17
	v_lshl_add_u64 v[222:223], s[22:23], 0, v[128:129]
	s_barrier
	ds_read_b128 v[168:171], v150 offset:16384
	ds_read_b128 v[172:175], v150 offset:17408
	ds_read_b128 v[176:179], v150 offset:18432
	ds_read_b128 v[180:183], v150 offset:19456
	ds_read_b128 v[184:187], v150 offset:20480
	ds_read_b128 v[188:191], v150 offset:21504
	ds_read_b128 v[192:195], v150 offset:22528
	ds_read_b128 v[196:199], v150 offset:23552
	global_load_lds_dwordx4 v128, s[22:23]
	v_lshl_add_u64 v[224:225], s[22:23], 0, v[132:133]
	s_mov_b32 m0, s29
	s_nop 0
	global_load_lds_dwordx4 v132, s[22:23]
	s_barrier
	s_waitcnt lgkmcnt(0)
	s_setprio 1
	s_waitcnt lgkmcnt(0)
	v_mfma_f32_16x16x32_bf16 v[60:63], v[152:155], v[168:171], 0
	v_mfma_f32_16x16x32_bf16 v[56:59], v[160:163], v[168:171], 0
	v_mfma_f32_16x16x32_bf16 v[48:51], v[152:155], v[176:179], 0
	v_mfma_f32_16x16x32_bf16 v[40:43], v[160:163], v[176:179], 0
	v_mfma_f32_16x16x32_bf16 v[32:35], v[152:155], v[184:187], 0
	v_mfma_f32_16x16x32_bf16 v[24:27], v[160:163], v[184:187], 0
	v_mfma_f32_16x16x32_bf16 v[16:19], v[152:155], v[192:195], 0
	v_mfma_f32_16x16x32_bf16 v[8:11], v[160:163], v[192:195], 0
	v_mfma_f32_16x16x32_bf16 v[60:63], v[156:159], v[172:175], v[60:63]
	v_mfma_f32_16x16x32_bf16 v[56:59], v[164:167], v[172:175], v[56:59]
	v_mfma_f32_16x16x32_bf16 v[48:51], v[156:159], v[180:183], v[48:51]
	v_mfma_f32_16x16x32_bf16 v[40:43], v[164:167], v[180:183], v[40:43]
	v_mfma_f32_16x16x32_bf16 v[32:35], v[156:159], v[188:191], v[32:35]
	v_mfma_f32_16x16x32_bf16 v[24:27], v[164:167], v[188:191], v[24:27]
	v_mfma_f32_16x16x32_bf16 v[16:19], v[156:159], v[196:199], v[16:19]
	v_mfma_f32_16x16x32_bf16 v[8:11], v[164:167], v[196:199], v[8:11]
	s_setprio 0
	s_barrier
; #define PG8_STAGE(bufoff, gbase, voff) do { _Pragma("unroll") for (int _i = 0; _i < 2; ++_i) \
;         __builtin_amdgcn_global_load_lds((const unsigned*)((const char*)(gbase) + (voff)[_i]), (LAS unsigned*)(lds + (bufoff) + ldsw + _i * 8192), 16, 0, 0); } while (0)
; #define PG8_LDA(dst, b, h) do { _Pragma("unroll") for (int m = 0; m < 4; ++m) _Pragma("unroll") for (int k = 0; k < 2; ++k) dst[m][k] = *(const LAS bf16x8*)(lds + PG8_SA(b, h) + aoff + m * 2048 + k * 1024); } while (0)
; #define PG8_LDB(dst, b, h) do { _Pragma("unroll") for (int n = 0; n < 2; ++n) _Pragma("unroll") for (int k = 0; k < 2; ++k) dst[n][k] = *(const LAS bf16x8*)(lds + PG8_SB(b, h) + boff + n * 2048 + k * 1024); } while (0)
; #define PG8_MMA(ai, bj, At, Bt) do { __builtin_amdgcn_s_setprio(1); _Pragma("unroll") for (int m = 0; m < 4; ++m) _Pragma("unroll") for (int n = 0; n < 2; ++n) _Pragma("unroll") for (int k = 0; k < 2; ++k) \
;         acc[ai][bj][m][n] = __builtin_amdgcn_mfma_f32_16x16x32_bf16(Bt[n][k], At[m][k], acc[ai][bj][m][n], 0, 0, 0); __builtin_amdgcn_s_setprio(0); } while (0)
; #define PG8_WAIT_V(n) asm volatile("s_waitcnt vmcnt(" #n ")" ::: "memory")
; #define PG8_WAIT_L(n) asm volatile("s_waitcnt lgkmcnt(" #n ")" ::: "memory")
; #define PG8_BAR __builtin_amdgcn_s_barrier()
; #define PG8_SCHED __builtin_amdgcn_sched_barrier(0)
; template <class Epi, class Sched>
; __device__ __forceinline__ void gemm_phase(LAS unsigned char* lds, const Gemm g, const Sched& S, const Epi& E) {
;     ...
;             PG8_STAGE(PG8_SB(0, 1), b2 + hstep, voffB);
;             PG8_WAIT_V(6); PG8_BAR; PG8_MMA(1, 1, At, B1); PG8_BAR;
;             PG8_LDB(B0, 1, 0); PG8_SCHED; PG8_LDA(At, 1, 0); PG8_STAGE(PG8_SA(0, 1), a2 + hstep, voffA);
;             PG8_WAIT_L(8); PG8_BAR; PG8_WAIT_L(0); PG8_MMA(0, 0, At, B0); PG8_BAR; PG8_SCHED;
;             PG8_LDB(B1, 1, 1); PG8_STAGE(PG8_SB(1, 0), b3, voffB);
;             PG8_BAR; PG8_WAIT_L(0); PG8_MMA(0, 1, At, B1); PG8_BAR;
;             PG8_LDA(At, 1, 1); PG8_STAGE(PG8_SA(1, 0), a3, voffA);
;             PG8_BAR; PG8_WAIT_L(0); PG8_MMA(1, 0, At, B0); PG8_BAR; PG8_SCHED;
	s_add_u32 s52, s20, 0x40000
	s_addc_u32 s53, s21, 0
	s_add_i32 s54, s44, s28
	s_mov_b32 m0, s54
	s_nop 0
	global_load_lds_dwordx4 v130, s[52:53]
	s_add_i32 m0, s54, 0x2000
	s_nop 0
	global_load_lds_dwordx4 v134, s[52:53]
	s_add_u32 s22, s22, 0x40000
	s_addc_u32 s23, s23, 0
	s_mov_b32 m0, s30
	s_nop 0
	global_load_lds_dwordx4 v128, s[22:23]
	s_mov_b32 m0, s31
	s_nop 0
	global_load_lds_dwordx4 v132, s[22:23]
	s_waitcnt vmcnt(12)
	s_barrier
	s_setprio 1
	v_mfma_f32_16x16x32_bf16 v[52:55], v[202:205], v[168:171], 0
	v_mfma_f32_16x16x32_bf16 v[44:47], v[210:213], v[168:171], 0
	v_mfma_f32_16x16x32_bf16 v[36:39], v[202:205], v[176:179], 0
	v_mfma_f32_16x16x32_bf16 v[28:31], v[210:213], v[176:179], 0
	v_mfma_f32_16x16x32_bf16 v[20:23], v[202:205], v[184:187], 0
	v_mfma_f32_16x16x32_bf16 v[12:15], v[210:213], v[184:187], 0
	v_mfma_f32_16x16x32_bf16 v[4:7], v[202:205], v[192:195], 0
	v_mfma_f32_16x16x32_bf16 v[0:3], v[210:213], v[192:195], 0
	v_mfma_f32_16x16x32_bf16 v[52:55], v[206:209], v[172:175], v[52:55]
	v_mfma_f32_16x16x32_bf16 v[44:47], v[214:217], v[172:175], v[44:47]
	v_mfma_f32_16x16x32_bf16 v[36:39], v[206:209], v[180:183], v[36:39]
	v_mfma_f32_16x16x32_bf16 v[28:31], v[214:217], v[180:183], v[28:31]
	v_mfma_f32_16x16x32_bf16 v[20:23], v[206:209], v[188:191], v[20:23]
	v_mfma_f32_16x16x32_bf16 v[12:15], v[214:217], v[188:191], v[12:15]
	v_mfma_f32_16x16x32_bf16 v[4:7], v[206:209], v[196:199], v[4:7]
	v_mfma_f32_16x16x32_bf16 v[0:3], v[214:217], v[196:199], v[0:3]
	s_setprio 0
	s_add_i32 s52, 0, 0x18000
	v_add_u32_e32 v136, s52, v148
	s_barrier
	ds_read_b128 v[152:155], v136
	ds_read_b128 v[156:159], v136 offset:1024
	ds_read_b128 v[160:163], v136 offset:2048
	ds_read_b128 v[164:167], v136 offset:3072
	ds_read_b128 v[168:171], v150 offset:32768
	ds_read_b128 v[172:175], v150 offset:33792
	ds_read_b128 v[176:179], v150 offset:34816
	ds_read_b128 v[180:183], v150 offset:35840
	ds_read_b128 v[184:187], v150 offset:36864
	ds_read_b128 v[188:191], v150 offset:37888
	ds_read_b128 v[192:195], v150 offset:38912
	ds_read_b128 v[196:199], v150 offset:39936
	s_waitcnt vmcnt(10)
	s_barrier
	s_waitcnt lgkmcnt(0)
	s_setprio 1
	s_waitcnt lgkmcnt(0)
	v_mfma_f32_16x16x32_bf16 v[124:127], v[152:155], v[168:171], v[124:127]
	v_mfma_f32_16x16x32_bf16 v[120:123], v[160:163], v[168:171], v[120:123]
	v_mfma_f32_16x16x32_bf16 v[112:115], v[152:155], v[176:179], v[112:115]
	v_mfma_f32_16x16x32_bf16 v[104:107], v[160:163], v[176:179], v[104:107]
	v_mfma_f32_16x16x32_bf16 v[96:99], v[152:155], v[184:187], v[96:99]
	v_mfma_f32_16x16x32_bf16 v[88:91], v[160:163], v[184:187], v[88:91]
	v_mfma_f32_16x16x32_bf16 v[80:83], v[152:155], v[192:195], v[80:83]
	v_mfma_f32_16x16x32_bf16 v[72:75], v[160:163], v[192:195], v[72:75]
	v_mfma_f32_16x16x32_bf16 v[124:127], v[156:159], v[172:175], v[124:127]
	v_mfma_f32_16x16x32_bf16 v[120:123], v[164:167], v[172:175], v[120:123]
	v_mfma_f32_16x16x32_bf16 v[112:115], v[156:159], v[180:183], v[112:115]
	v_mfma_f32_16x16x32_bf16 v[104:107], v[164:167], v[180:183], v[104:107]
	v_mfma_f32_16x16x32_bf16 v[96:99], v[156:159], v[188:191], v[96:99]
	v_mfma_f32_16x16x32_bf16 v[88:91], v[164:167], v[188:191], v[88:91]
	v_mfma_f32_16x16x32_bf16 v[80:83], v[156:159], v[196:199], v[80:83]
	v_mfma_f32_16x16x32_bf16 v[72:75], v[164:167], v[196:199], v[72:75]
	s_setprio 0
	s_barrier
	s_add_i32 s22, 0, 0x1c000
	s_add_i32 s23, s52, s28
	v_add_u32_e32 v136, s22, v148
	s_add_u32 s0, s20, 0x80
	s_addc_u32 s1, s21, 0
	s_mov_b32 m0, s23
	ds_read_b128 v[202:205], v136
	ds_read_b128 v[206:209], v136 offset:1024
	ds_read_b128 v[210:213], v136 offset:2048
	ds_read_b128 v[214:217], v136 offset:3072
	global_load_lds_dwordx4 v130, s[0:1]
	s_add_i32 m0, s23, 0x2000
	s_nop 0
	global_load_lds_dwordx4 v134, s[0:1]
	s_waitcnt vmcnt(10)
	s_barrier
	s_waitcnt lgkmcnt(0)
	s_setprio 1
	s_waitcnt lgkmcnt(0)
	v_mfma_f32_16x16x32_bf16 v[116:119], v[202:205], v[168:171], v[116:119]
	v_mfma_f32_16x16x32_bf16 v[108:111], v[210:213], v[168:171], v[108:111]
	v_mfma_f32_16x16x32_bf16 v[100:103], v[202:205], v[176:179], v[100:103]
	v_mfma_f32_16x16x32_bf16 v[92:95], v[210:213], v[176:179], v[92:95]
	v_mfma_f32_16x16x32_bf16 v[84:87], v[202:205], v[184:187], v[84:87]
	v_mfma_f32_16x16x32_bf16 v[76:79], v[210:213], v[184:187], v[76:79]
	v_mfma_f32_16x16x32_bf16 v[68:71], v[202:205], v[192:195], v[68:71]
	v_mfma_f32_16x16x32_bf16 v[64:67], v[210:213], v[192:195], v[64:67]
	v_mfma_f32_16x16x32_bf16 v[116:119], v[206:209], v[172:175], v[116:119]
	v_mfma_f32_16x16x32_bf16 v[108:111], v[214:217], v[172:175], v[108:111]
	v_mfma_f32_16x16x32_bf16 v[100:103], v[206:209], v[180:183], v[100:103]
	v_mfma_f32_16x16x32_bf16 v[92:95], v[214:217], v[180:183], v[92:95]
	v_mfma_f32_16x16x32_bf16 v[84:87], v[206:209], v[188:191], v[84:87]
	v_mfma_f32_16x16x32_bf16 v[76:79], v[214:217], v[188:191], v[76:79]
	v_mfma_f32_16x16x32_bf16 v[68:71], v[206:209], v[196:199], v[68:71]
	v_mfma_f32_16x16x32_bf16 v[64:67], v[214:217], v[196:199], v[64:67]
	s_setprio 0
	s_mov_b32 m0, s36
	s_mov_b64 s[0:1], 0x80
	v_lshl_add_u64 v[218:219], v[222:223], 0, s[0:1]
	s_barrier
	ds_read_b128 v[168:171], v150 offset:49152
	ds_read_b128 v[172:175], v150 offset:50176
	ds_read_b128 v[176:179], v150 offset:51200
	ds_read_b128 v[180:183], v150 offset:52224
	ds_read_b128 v[184:187], v150 offset:53248
	ds_read_b128 v[188:191], v150 offset:54272
	ds_read_b128 v[192:195], v150 offset:55296
	ds_read_b128 v[196:199], v150 offset:56320
	global_load_lds_dwordx4 v[218:219], off
	v_lshl_add_u64 v[218:219], v[224:225], 0, s[0:1]
	s_mov_b32 m0, s37
	s_nop 0
	global_load_lds_dwordx4 v[218:219], off
	s_barrier
; #define PG8_STAGE(bufoff, gbase, voff) do { _Pragma("unroll") for (int _i = 0; _i < 2; ++_i) \
;         __builtin_amdgcn_global_load_lds((const unsigned*)((const char*)(gbase) + (voff)[_i]), (LAS unsigned*)(lds + (bufoff) + ldsw + _i * 8192), 16, 0, 0); } while (0)
; #define PG8_LDA(dst, b, h) do { _Pragma("unroll") for (int m = 0; m < 4; ++m) _Pragma("unroll") for (int k = 0; k < 2; ++k) dst[m][k] = *(const LAS bf16x8*)(lds + PG8_SA(b, h) + aoff + m * 2048 + k * 1024); } while (0)
; #define PG8_LDB(dst, b, h) do { _Pragma("unroll") for (int n = 0; n < 2; ++n) _Pragma("unroll") for (int k = 0; k < 2; ++k) dst[n][k] = *(const LAS bf16x8*)(lds + PG8_SB(b, h) + boff + n * 2048 + k * 1024); } while (0)
; #define PG8_MMA(ai, bj, At, Bt) do { __builtin_amdgcn_s_setprio(1); _Pragma("unroll") for (int m = 0; m < 4; ++m) _Pragma("unroll") for (int n = 0; n < 2; ++n) _Pragma("unroll") for (int k = 0; k < 2; ++k) \
;         acc[ai][bj][m][n] = __builtin_amdgcn_mfma_f32_16x16x32_bf16(Bt[n][k], At[m][k], acc[ai][bj][m][n], 0, 0, 0); __builtin_amdgcn_s_setprio(0); } while (0)
; #define PG8_WAIT_V(n) asm volatile("s_waitcnt vmcnt(" #n ")" ::: "memory")
; #define PG8_WAIT_L(n) asm volatile("s_waitcnt lgkmcnt(" #n ")" ::: "memory")
; #define PG8_BAR __builtin_amdgcn_s_barrier()
; #define PG8_SCHED __builtin_amdgcn_sched_barrier(0)
; template <class Epi, class Sched>
; __device__ __forceinline__ void gemm_phase(LAS unsigned char* lds, const Gemm g, const Sched& S, const Epi& E) {
;     ...
;         for (int t = 0; t < nt; t += 2) {
;             const bool last = (t == nt - 2);
;             const char* a1 = cA + (size_t)(t + 1) * kstep;
;             const char* a2 = last ? nA : cA + (size_t)(t + 2) * kstep; const char* b2 = last ? nB : cB + (size_t)(t + 2) * kstep;
;             const char* a3 = a2 + kstep; const char* b3 = b2 + kstep;
;             PG8_LDB(B0, 0, 0); PG8_SCHED; PG8_LDA(At, 0, 0); PG8_STAGE(PG8_SA(1, 1), a1 + hstep, voffA);
;             PG8_WAIT_L(8); PG8_BAR; PG8_WAIT_L(0); PG8_MMA(0, 0, At, B0); PG8_BAR; PG8_SCHED;
;             PG8_LDB(B1, 0, 1); PG8_STAGE(PG8_SB(0, 0), b2, voffB);
;     ...
;             PG8_BAR; PG8_WAIT_L(0); PG8_MMA(1, 0, At, B0); PG8_BAR; PG8_SCHED;
;             PG8_STAGE(PG8_SB(1, 1), b3 + hstep, voffB);
;             PG8_WAIT_V(6); PG8_BAR; PG8_MMA(1, 1, At, B1); PG8_BAR;
	s_waitcnt lgkmcnt(0)
	s_setprio 1
	s_waitcnt lgkmcnt(0)
	v_mfma_f32_16x16x32_bf16 v[60:63], v[152:155], v[168:171], v[60:63]
	v_mfma_f32_16x16x32_bf16 v[56:59], v[160:163], v[168:171], v[56:59]
	v_mfma_f32_16x16x32_bf16 v[48:51], v[152:155], v[176:179], v[48:51]
	v_mfma_f32_16x16x32_bf16 v[40:43], v[160:163], v[176:179], v[40:43]
	v_mfma_f32_16x16x32_bf16 v[32:35], v[152:155], v[184:187], v[32:35]
	v_mfma_f32_16x16x32_bf16 v[24:27], v[160:163], v[184:187], v[24:27]
	v_mfma_f32_16x16x32_bf16 v[16:19], v[152:155], v[192:195], v[16:19]
	v_mfma_f32_16x16x32_bf16 v[8:11], v[160:163], v[192:195], v[8:11]
	v_mfma_f32_16x16x32_bf16 v[60:63], v[156:159], v[172:175], v[60:63]
	v_mfma_f32_16x16x32_bf16 v[56:59], v[164:167], v[172:175], v[56:59]
	v_mfma_f32_16x16x32_bf16 v[48:51], v[156:159], v[180:183], v[48:51]
	v_mfma_f32_16x16x32_bf16 v[40:43], v[164:167], v[180:183], v[40:43]
	v_mfma_f32_16x16x32_bf16 v[32:35], v[156:159], v[188:191], v[32:35]
	v_mfma_f32_16x16x32_bf16 v[24:27], v[164:167], v[188:191], v[24:27]
	v_mfma_f32_16x16x32_bf16 v[16:19], v[156:159], v[196:199], v[16:19]
	v_mfma_f32_16x16x32_bf16 v[8:11], v[164:167], v[196:199], v[8:11]
	s_setprio 0
	s_barrier
	s_add_u32 s20, s20, 0x40080
	s_addc_u32 s21, s21, 0
	s_add_i32 s22, s22, s28
	s_mov_b32 m0, s22
	s_nop 0
	global_load_lds_dwordx4 v130, s[20:21]
	s_add_i32 m0, s22, 0x2000
	s_nop 0
	global_load_lds_dwordx4 v134, s[20:21]
	s_waitcnt vmcnt(10)
	s_barrier
	s_setprio 1
	v_mfma_f32_16x16x32_bf16 v[52:55], v[202:205], v[168:171], v[52:55]
	v_mfma_f32_16x16x32_bf16 v[44:47], v[210:213], v[168:171], v[44:47]
	v_mfma_f32_16x16x32_bf16 v[36:39], v[202:205], v[176:179], v[36:39]
	v_mfma_f32_16x16x32_bf16 v[28:31], v[210:213], v[176:179], v[28:31]
	v_mfma_f32_16x16x32_bf16 v[20:23], v[202:205], v[184:187], v[20:23]
	v_mfma_f32_16x16x32_bf16 v[12:15], v[210:213], v[184:187], v[12:15]
	v_mfma_f32_16x16x32_bf16 v[4:7], v[202:205], v[192:195], v[4:7]
	v_mfma_f32_16x16x32_bf16 v[0:3], v[210:213], v[192:195], v[0:3]
	v_mfma_f32_16x16x32_bf16 v[52:55], v[206:209], v[172:175], v[52:55]
	v_mfma_f32_16x16x32_bf16 v[44:47], v[214:217], v[172:175], v[44:47]
	v_mfma_f32_16x16x32_bf16 v[36:39], v[206:209], v[180:183], v[36:39]
	v_mfma_f32_16x16x32_bf16 v[28:31], v[214:217], v[180:183], v[28:31]
	v_mfma_f32_16x16x32_bf16 v[20:23], v[206:209], v[188:191], v[20:23]
	v_mfma_f32_16x16x32_bf16 v[12:15], v[214:217], v[188:191], v[12:15]
	v_mfma_f32_16x16x32_bf16 v[4:7], v[206:209], v[196:199], v[4:7]
	v_mfma_f32_16x16x32_bf16 v[0:3], v[214:217], v[196:199], v[0:3]
	s_setprio 0
	s_add_i32 s51, s51, 2
	s_add_u32 s18, s18, 0x100
	s_addc_u32 s19, s19, 0
	s_add_u32 s48, s48, 0x100
	s_addc_u32 s49, s49, 0
	s_cmp_gt_u32 s51, 13
	s_barrier
.LBB0_673:
	ds_read_b128 v[152:155], v149
	ds_read_b128 v[156:159], v149 offset:1024
	ds_read_b128 v[160:163], v149 offset:2048
	ds_read_b128 v[164:167], v149 offset:3072
	s_add_u32 s20, s18, 0xfffc0080
	s_addc_u32 s21, s19, -1
	s_cmp_eq_u32 s51, 12
	s_cselect_b32 s23, s9, s21
	s_cselect_b32 s22, s46, s20
	s_cselect_b32 s21, s7, s49
	s_cselect_b32 s20, s47, s48
	s_add_i32 m0, s17, 0xc000
	ds_read_b128 v[168:171], v150
	ds_read_b128 v[172:175], v150 offset:1024
	ds_read_b128 v[176:179], v150 offset:2048
	ds_read_b128 v[180:183], v150 offset:3072
	ds_read_b128 v[184:187], v150 offset:4096
	ds_read_b128 v[188:191], v150 offset:5120
	ds_read_b128 v[192:195], v150 offset:6144
	ds_read_b128 v[196:199], v150 offset:7168
	global_load_lds_dwordx4 v138, s[18:19]
	s_add_i32 m0, s17, 0xe000
	s_nop 0
	global_load_lds_dwordx4 v140, s[18:19]
	s_waitcnt vmcnt(10)
	s_barrier
	s_waitcnt lgkmcnt(0)
	s_setprio 1
	s_waitcnt lgkmcnt(0)
	v_mfma_f32_16x16x32_bf16 v[124:127], v[152:155], v[168:171], v[124:127]
	v_mfma_f32_16x16x32_bf16 v[120:123], v[160:163], v[168:171], v[120:123]
	v_mfma_f32_16x16x32_bf16 v[112:115], v[152:155], v[176:179], v[112:115]
	v_mfma_f32_16x16x32_bf16 v[104:107], v[160:163], v[176:179], v[104:107]
	v_mfma_f32_16x16x32_bf16 v[96:99], v[152:155], v[184:187], v[96:99]
	v_mfma_f32_16x16x32_bf16 v[88:91], v[160:163], v[184:187], v[88:91]
	v_mfma_f32_16x16x32_bf16 v[80:83], v[152:155], v[192:195], v[80:83]
	v_mfma_f32_16x16x32_bf16 v[72:75], v[160:163], v[192:195], v[72:75]
	v_mfma_f32_16x16x32_bf16 v[124:127], v[156:159], v[172:175], v[124:127]
	v_mfma_f32_16x16x32_bf16 v[120:123], v[164:167], v[172:175], v[120:123]
	v_mfma_f32_16x16x32_bf16 v[112:115], v[156:159], v[180:183], v[112:115]
	v_mfma_f32_16x16x32_bf16 v[104:107], v[164:167], v[180:183], v[104:107]
	v_mfma_f32_16x16x32_bf16 v[96:99], v[156:159], v[188:191], v[96:99]
	v_mfma_f32_16x16x32_bf16 v[88:91], v[164:167], v[188:191], v[88:91]
	v_mfma_f32_16x16x32_bf16 v[80:83], v[156:159], v[196:199], v[80:83]
	v_mfma_f32_16x16x32_bf16 v[72:75], v[164:167], v[196:199], v[72:75]
	s_setprio 0
	s_barrier
	s_add_i32 s52, s43, s28
	s_mov_b32 m0, s52
	ds_read_b128 v[202:205], v151
	ds_read_b128 v[206:209], v151 offset:1024
	ds_read_b128 v[210:213], v151 offset:2048
	ds_read_b128 v[214:217], v151 offset:3072
	global_load_lds_dwordx4 v130, s[20:21]
	s_add_i32 m0, s52, 0x2000
	s_nop 0
	global_load_lds_dwordx4 v134, s[20:21]
	s_waitcnt vmcnt(10)
	s_barrier
; #define PG8_STAGE(bufoff, gbase, voff) do { _Pragma("unroll") for (int _i = 0; _i < 2; ++_i) \
;         __builtin_amdgcn_global_load_lds((const unsigned*)((const char*)(gbase) + (voff)[_i]), (LAS unsigned*)(lds + (bufoff) + ldsw + _i * 8192), 16, 0, 0); } while (0)
; #define PG8_LDA(dst, b, h) do { _Pragma("unroll") for (int m = 0; m < 4; ++m) _Pragma("unroll") for (int k = 0; k < 2; ++k) dst[m][k] = *(const LAS bf16x8*)(lds + PG8_SA(b, h) + aoff + m * 2048 + k * 1024); } while (0)
; #define PG8_LDB(dst, b, h) do { _Pragma("unroll") for (int n = 0; n < 2; ++n) _Pragma("unroll") for (int k = 0; k < 2; ++k) dst[n][k] = *(const LAS bf16x8*)(lds + PG8_SB(b, h) + boff + n * 2048 + k * 1024); } while (0)
; #define PG8_MMA(ai, bj, At, Bt) do { __builtin_amdgcn_s_setprio(1); _Pragma("unroll") for (int m = 0; m < 4; ++m) _Pragma("unroll") for (int n = 0; n < 2; ++n) _Pragma("unroll") for (int k = 0; k < 2; ++k) \
;         acc[ai][bj][m][n] = __builtin_amdgcn_mfma_f32_16x16x32_bf16(Bt[n][k], At[m][k], acc[ai][bj][m][n], 0, 0, 0); __builtin_amdgcn_s_setprio(0); } while (0)
; #define PG8_WAIT_V(n) asm volatile("s_waitcnt vmcnt(" #n ")" ::: "memory")
; #define PG8_WAIT_L(n) asm volatile("s_waitcnt lgkmcnt(" #n ")" ::: "memory")
; #define PG8_BAR __builtin_amdgcn_s_barrier()
; #define PG8_SCHED __builtin_amdgcn_sched_barrier(0)
; template <class Epi, class Sched>
; __device__ __forceinline__ void gemm_phase(LAS unsigned char* lds, const Gemm g, const Sched& S, const Epi& E) {
;     ...
;             PG8_LDB(B1, 0, 1); PG8_STAGE(PG8_SB(0, 0), b2, voffB);
;             PG8_BAR; PG8_WAIT_L(0); PG8_MMA(0, 1, At, B1); PG8_BAR;
;             PG8_LDA(At, 0, 1); PG8_STAGE(PG8_SA(0, 0), a2, voffA);
;             PG8_BAR; PG8_WAIT_L(0); PG8_MMA(1, 0, At, B0); PG8_BAR; PG8_SCHED;
;             PG8_STAGE(PG8_SB(0, 1), b2 + hstep, voffB);
;             PG8_WAIT_V(6); PG8_BAR; PG8_MMA(1, 1, At, B1); PG8_BAR;
;             PG8_LDB(B0, 1, 0); PG8_SCHED; PG8_LDA(At, 1, 0); PG8_STAGE(PG8_SA(0, 1), a2 + hstep, voffA);
;             PG8_WAIT_L(8); PG8_BAR; PG8_WAIT_L(0); PG8_MMA(0, 0, At, B0); PG8_BAR; PG8_SCHED;
	s_waitcnt lgkmcnt(0)
	s_setprio 1
	s_waitcnt lgkmcnt(0)
	v_mfma_f32_16x16x32_bf16 v[116:119], v[202:205], v[168:171], v[116:119]
	v_mfma_f32_16x16x32_bf16 v[108:111], v[210:213], v[168:171], v[108:111]
	v_mfma_f32_16x16x32_bf16 v[100:103], v[202:205], v[176:179], v[100:103]
	v_mfma_f32_16x16x32_bf16 v[92:95], v[210:213], v[176:179], v[92:95]
	v_mfma_f32_16x16x32_bf16 v[84:87], v[202:205], v[184:187], v[84:87]
	v_mfma_f32_16x16x32_bf16 v[76:79], v[210:213], v[184:187], v[76:79]
	v_mfma_f32_16x16x32_bf16 v[68:71], v[202:205], v[192:195], v[68:71]
	v_mfma_f32_16x16x32_bf16 v[64:67], v[210:213], v[192:195], v[64:67]
	v_mfma_f32_16x16x32_bf16 v[116:119], v[206:209], v[172:175], v[116:119]
	v_mfma_f32_16x16x32_bf16 v[108:111], v[214:217], v[172:175], v[108:111]
	v_mfma_f32_16x16x32_bf16 v[100:103], v[206:209], v[180:183], v[100:103]
	v_mfma_f32_16x16x32_bf16 v[92:95], v[214:217], v[180:183], v[92:95]
	v_mfma_f32_16x16x32_bf16 v[84:87], v[206:209], v[188:191], v[84:87]
	v_mfma_f32_16x16x32_bf16 v[76:79], v[214:217], v[188:191], v[76:79]
	v_mfma_f32_16x16x32_bf16 v[68:71], v[206:209], v[196:199], v[68:71]
	v_mfma_f32_16x16x32_bf16 v[64:67], v[214:217], v[196:199], v[64:67]
	s_setprio 0
	s_mov_b32 m0, s17
	v_lshl_add_u64 v[222:223], s[22:23], 0, v[128:129]
	s_barrier
	ds_read_b128 v[168:171], v150 offset:16384
	ds_read_b128 v[172:175], v150 offset:17408
	ds_read_b128 v[176:179], v150 offset:18432
	ds_read_b128 v[180:183], v150 offset:19456
	ds_read_b128 v[184:187], v150 offset:20480
	ds_read_b128 v[188:191], v150 offset:21504
	ds_read_b128 v[192:195], v150 offset:22528
	ds_read_b128 v[196:199], v150 offset:23552
	global_load_lds_dwordx4 v128, s[22:23]
	v_lshl_add_u64 v[224:225], s[22:23], 0, v[132:133]
	s_mov_b32 m0, s29
	s_nop 0
	global_load_lds_dwordx4 v132, s[22:23]
	s_barrier
	s_waitcnt lgkmcnt(0)
	s_setprio 1
	s_waitcnt lgkmcnt(0)
	v_mfma_f32_16x16x32_bf16 v[60:63], v[152:155], v[168:171], v[60:63]
	v_mfma_f32_16x16x32_bf16 v[56:59], v[160:163], v[168:171], v[56:59]
	v_mfma_f32_16x16x32_bf16 v[48:51], v[152:155], v[176:179], v[48:51]
	v_mfma_f32_16x16x32_bf16 v[40:43], v[160:163], v[176:179], v[40:43]
	v_mfma_f32_16x16x32_bf16 v[32:35], v[152:155], v[184:187], v[32:35]
	v_mfma_f32_16x16x32_bf16 v[24:27], v[160:163], v[184:187], v[24:27]
	v_mfma_f32_16x16x32_bf16 v[16:19], v[152:155], v[192:195], v[16:19]
	v_mfma_f32_16x16x32_bf16 v[8:11], v[160:163], v[192:195], v[8:11]
	v_mfma_f32_16x16x32_bf16 v[60:63], v[156:159], v[172:175], v[60:63]
	v_mfma_f32_16x16x32_bf16 v[56:59], v[164:167], v[172:175], v[56:59]
	v_mfma_f32_16x16x32_bf16 v[48:51], v[156:159], v[180:183], v[48:51]
	v_mfma_f32_16x16x32_bf16 v[40:43], v[164:167], v[180:183], v[40:43]
	v_mfma_f32_16x16x32_bf16 v[32:35], v[156:159], v[188:191], v[32:35]
	v_mfma_f32_16x16x32_bf16 v[24:27], v[164:167], v[188:191], v[24:27]
	v_mfma_f32_16x16x32_bf16 v[16:19], v[156:159], v[196:199], v[16:19]
	v_mfma_f32_16x16x32_bf16 v[8:11], v[164:167], v[196:199], v[8:11]
	s_setprio 0
	s_barrier
	s_add_u32 s52, s20, 0x40000
	s_addc_u32 s53, s21, 0
	s_add_i32 s54, s44, s28
	s_mov_b32 m0, s54
	s_nop 0
	global_load_lds_dwordx4 v130, s[52:53]
	s_add_i32 m0, s54, 0x2000
	s_nop 0
	global_load_lds_dwordx4 v134, s[52:53]
	s_add_u32 s22, s22, 0x40000
	s_addc_u32 s23, s23, 0
	s_mov_b32 m0, s30
	s_nop 0
	global_load_lds_dwordx4 v128, s[22:23]
	s_mov_b32 m0, s31
	s_nop 0
	global_load_lds_dwordx4 v132, s[22:23]
	s_waitcnt vmcnt(12)
	s_barrier
	s_setprio 1
	v_mfma_f32_16x16x32_bf16 v[52:55], v[202:205], v[168:171], v[52:55]
	v_mfma_f32_16x16x32_bf16 v[44:47], v[210:213], v[168:171], v[44:47]
	v_mfma_f32_16x16x32_bf16 v[36:39], v[202:205], v[176:179], v[36:39]
	v_mfma_f32_16x16x32_bf16 v[28:31], v[210:213], v[176:179], v[28:31]
	v_mfma_f32_16x16x32_bf16 v[20:23], v[202:205], v[184:187], v[20:23]
	v_mfma_f32_16x16x32_bf16 v[12:15], v[210:213], v[184:187], v[12:15]
	v_mfma_f32_16x16x32_bf16 v[4:7], v[202:205], v[192:195], v[4:7]
	v_mfma_f32_16x16x32_bf16 v[0:3], v[210:213], v[192:195], v[0:3]
	v_mfma_f32_16x16x32_bf16 v[52:55], v[206:209], v[172:175], v[52:55]
	v_mfma_f32_16x16x32_bf16 v[44:47], v[214:217], v[172:175], v[44:47]
	v_mfma_f32_16x16x32_bf16 v[36:39], v[206:209], v[180:183], v[36:39]
	v_mfma_f32_16x16x32_bf16 v[28:31], v[214:217], v[180:183], v[28:31]
	v_mfma_f32_16x16x32_bf16 v[20:23], v[206:209], v[188:191], v[20:23]
	v_mfma_f32_16x16x32_bf16 v[12:15], v[214:217], v[188:191], v[12:15]
	v_mfma_f32_16x16x32_bf16 v[4:7], v[206:209], v[196:199], v[4:7]
	v_mfma_f32_16x16x32_bf16 v[0:3], v[214:217], v[196:199], v[0:3]
	s_setprio 0
	s_add_i32 s52, 0, 0x18000
	v_add_u32_e32 v136, s52, v148
	s_barrier
	ds_read_b128 v[152:155], v136
	ds_read_b128 v[156:159], v136 offset:1024
	ds_read_b128 v[160:163], v136 offset:2048
	ds_read_b128 v[164:167], v136 offset:3072
	ds_read_b128 v[168:171], v150 offset:32768
	ds_read_b128 v[172:175], v150 offset:33792
	ds_read_b128 v[176:179], v150 offset:34816
	ds_read_b128 v[180:183], v150 offset:35840
	ds_read_b128 v[184:187], v150 offset:36864
	ds_read_b128 v[188:191], v150 offset:37888
	ds_read_b128 v[192:195], v150 offset:38912
	ds_read_b128 v[196:199], v150 offset:39936
	s_waitcnt vmcnt(10)
	s_barrier
; #define PG8_STAGE(bufoff, gbase, voff) do { _Pragma("unroll") for (int _i = 0; _i < 2; ++_i) \
;         __builtin_amdgcn_global_load_lds((const unsigned*)((const char*)(gbase) + (voff)[_i]), (LAS unsigned*)(lds + (bufoff) + ldsw + _i * 8192), 16, 0, 0); } while (0)
; #define PG8_LDA(dst, b, h) do { _Pragma("unroll") for (int m = 0; m < 4; ++m) _Pragma("unroll") for (int k = 0; k < 2; ++k) dst[m][k] = *(const LAS bf16x8*)(lds + PG8_SA(b, h) + aoff + m * 2048 + k * 1024); } while (0)
; #define PG8_LDB(dst, b, h) do { _Pragma("unroll") for (int n = 0; n < 2; ++n) _Pragma("unroll") for (int k = 0; k < 2; ++k) dst[n][k] = *(const LAS bf16x8*)(lds + PG8_SB(b, h) + boff + n * 2048 + k * 1024); } while (0)
; #define PG8_MMA(ai, bj, At, Bt) do { __builtin_amdgcn_s_setprio(1); _Pragma("unroll") for (int m = 0; m < 4; ++m) _Pragma("unroll") for (int n = 0; n < 2; ++n) _Pragma("unroll") for (int k = 0; k < 2; ++k) \
;         acc[ai][bj][m][n] = __builtin_amdgcn_mfma_f32_16x16x32_bf16(Bt[n][k], At[m][k], acc[ai][bj][m][n], 0, 0, 0); __builtin_amdgcn_s_setprio(0); } while (0)
; #define PG8_WAIT_V(n) asm volatile("s_waitcnt vmcnt(" #n ")" ::: "memory")
; #define PG8_WAIT_L(n) asm volatile("s_waitcnt lgkmcnt(" #n ")" ::: "memory")
; #define PG8_BAR __builtin_amdgcn_s_barrier()
; #define PG8_SCHED __builtin_amdgcn_sched_barrier(0)
; template <class Epi, class Sched>
; __device__ __forceinline__ void gemm_phase(LAS unsigned char* lds, const Gemm g, const Sched& S, const Epi& E) {
;     ...
;             PG8_WAIT_L(8); PG8_BAR; PG8_WAIT_L(0); PG8_MMA(0, 0, At, B0); PG8_BAR; PG8_SCHED;
;             PG8_LDB(B1, 1, 1); PG8_STAGE(PG8_SB(1, 0), b3, voffB);
;             PG8_BAR; PG8_WAIT_L(0); PG8_MMA(0, 1, At, B1); PG8_BAR;
;             PG8_LDA(At, 1, 1); PG8_STAGE(PG8_SA(1, 0), a3, voffA);
;             PG8_BAR; PG8_WAIT_L(0); PG8_MMA(1, 0, At, B0); PG8_BAR; PG8_SCHED;
;             PG8_STAGE(PG8_SB(1, 1), b3 + hstep, voffB);
;             PG8_WAIT_V(6); PG8_BAR; PG8_MMA(1, 1, At, B1); PG8_BAR;
	s_waitcnt lgkmcnt(0)
	s_setprio 1
	s_waitcnt lgkmcnt(0)
	v_mfma_f32_16x16x32_bf16 v[124:127], v[152:155], v[168:171], v[124:127]
	v_mfma_f32_16x16x32_bf16 v[120:123], v[160:163], v[168:171], v[120:123]
	v_mfma_f32_16x16x32_bf16 v[112:115], v[152:155], v[176:179], v[112:115]
	v_mfma_f32_16x16x32_bf16 v[104:107], v[160:163], v[176:179], v[104:107]
	v_mfma_f32_16x16x32_bf16 v[96:99], v[152:155], v[184:187], v[96:99]
	v_mfma_f32_16x16x32_bf16 v[88:91], v[160:163], v[184:187], v[88:91]
	v_mfma_f32_16x16x32_bf16 v[80:83], v[152:155], v[192:195], v[80:83]
	v_mfma_f32_16x16x32_bf16 v[72:75], v[160:163], v[192:195], v[72:75]
	v_mfma_f32_16x16x32_bf16 v[124:127], v[156:159], v[172:175], v[124:127]
	v_mfma_f32_16x16x32_bf16 v[120:123], v[164:167], v[172:175], v[120:123]
	v_mfma_f32_16x16x32_bf16 v[112:115], v[156:159], v[180:183], v[112:115]
	v_mfma_f32_16x16x32_bf16 v[104:107], v[164:167], v[180:183], v[104:107]
	v_mfma_f32_16x16x32_bf16 v[96:99], v[156:159], v[188:191], v[96:99]
	v_mfma_f32_16x16x32_bf16 v[88:91], v[164:167], v[188:191], v[88:91]
	v_mfma_f32_16x16x32_bf16 v[80:83], v[156:159], v[196:199], v[80:83]
	v_mfma_f32_16x16x32_bf16 v[72:75], v[164:167], v[196:199], v[72:75]
	s_setprio 0
	s_barrier
	s_add_i32 s22, 0, 0x1c000
	s_add_i32 s23, s52, s28
	v_add_u32_e32 v136, s22, v148
	s_add_u32 s0, s20, 0x80
	s_addc_u32 s1, s21, 0
	s_mov_b32 m0, s23
	ds_read_b128 v[202:205], v136
	ds_read_b128 v[206:209], v136 offset:1024
	ds_read_b128 v[210:213], v136 offset:2048
	ds_read_b128 v[214:217], v136 offset:3072
	global_load_lds_dwordx4 v130, s[0:1]
	s_add_i32 m0, s23, 0x2000
	s_nop 0
	global_load_lds_dwordx4 v134, s[0:1]
	s_waitcnt vmcnt(10)
	s_barrier
	s_waitcnt lgkmcnt(0)
	s_setprio 1
	s_waitcnt lgkmcnt(0)
	v_mfma_f32_16x16x32_bf16 v[116:119], v[202:205], v[168:171], v[116:119]
	v_mfma_f32_16x16x32_bf16 v[108:111], v[210:213], v[168:171], v[108:111]
	v_mfma_f32_16x16x32_bf16 v[100:103], v[202:205], v[176:179], v[100:103]
	v_mfma_f32_16x16x32_bf16 v[92:95], v[210:213], v[176:179], v[92:95]
	v_mfma_f32_16x16x32_bf16 v[84:87], v[202:205], v[184:187], v[84:87]
	v_mfma_f32_16x16x32_bf16 v[76:79], v[210:213], v[184:187], v[76:79]
	v_mfma_f32_16x16x32_bf16 v[68:71], v[202:205], v[192:195], v[68:71]
	v_mfma_f32_16x16x32_bf16 v[64:67], v[210:213], v[192:195], v[64:67]
	v_mfma_f32_16x16x32_bf16 v[116:119], v[206:209], v[172:175], v[116:119]
	v_mfma_f32_16x16x32_bf16 v[108:111], v[214:217], v[172:175], v[108:111]
	v_mfma_f32_16x16x32_bf16 v[100:103], v[206:209], v[180:183], v[100:103]
	v_mfma_f32_16x16x32_bf16 v[92:95], v[214:217], v[180:183], v[92:95]
	v_mfma_f32_16x16x32_bf16 v[84:87], v[206:209], v[188:191], v[84:87]
	v_mfma_f32_16x16x32_bf16 v[76:79], v[214:217], v[188:191], v[76:79]
	v_mfma_f32_16x16x32_bf16 v[68:71], v[206:209], v[196:199], v[68:71]
	v_mfma_f32_16x16x32_bf16 v[64:67], v[214:217], v[196:199], v[64:67]
	s_setprio 0
	s_mov_b32 m0, s36
	s_mov_b64 s[0:1], 0x80
	v_lshl_add_u64 v[218:219], v[222:223], 0, s[0:1]
	s_barrier
	ds_read_b128 v[168:171], v150 offset:49152
	ds_read_b128 v[172:175], v150 offset:50176
	ds_read_b128 v[176:179], v150 offset:51200
	ds_read_b128 v[180:183], v150 offset:52224
	ds_read_b128 v[184:187], v150 offset:53248
	ds_read_b128 v[188:191], v150 offset:54272
	ds_read_b128 v[192:195], v150 offset:55296
	ds_read_b128 v[196:199], v150 offset:56320
	global_load_lds_dwordx4 v[218:219], off
	v_lshl_add_u64 v[218:219], v[224:225], 0, s[0:1]
	s_mov_b32 m0, s37
	s_nop 0
	global_load_lds_dwordx4 v[218:219], off
	s_barrier
	s_waitcnt lgkmcnt(0)
	s_setprio 1
	s_waitcnt lgkmcnt(0)
	v_mfma_f32_16x16x32_bf16 v[60:63], v[152:155], v[168:171], v[60:63]
	v_mfma_f32_16x16x32_bf16 v[56:59], v[160:163], v[168:171], v[56:59]
	v_mfma_f32_16x16x32_bf16 v[48:51], v[152:155], v[176:179], v[48:51]
	v_mfma_f32_16x16x32_bf16 v[40:43], v[160:163], v[176:179], v[40:43]
	v_mfma_f32_16x16x32_bf16 v[32:35], v[152:155], v[184:187], v[32:35]
	v_mfma_f32_16x16x32_bf16 v[24:27], v[160:163], v[184:187], v[24:27]
	v_mfma_f32_16x16x32_bf16 v[16:19], v[152:155], v[192:195], v[16:19]
	v_mfma_f32_16x16x32_bf16 v[8:11], v[160:163], v[192:195], v[8:11]
	v_mfma_f32_16x16x32_bf16 v[60:63], v[156:159], v[172:175], v[60:63]
	v_mfma_f32_16x16x32_bf16 v[56:59], v[164:167], v[172:175], v[56:59]
	v_mfma_f32_16x16x32_bf16 v[48:51], v[156:159], v[180:183], v[48:51]
	v_mfma_f32_16x16x32_bf16 v[40:43], v[164:167], v[180:183], v[40:43]
	v_mfma_f32_16x16x32_bf16 v[32:35], v[156:159], v[188:191], v[32:35]
	v_mfma_f32_16x16x32_bf16 v[24:27], v[164:167], v[188:191], v[24:27]
	v_mfma_f32_16x16x32_bf16 v[16:19], v[156:159], v[196:199], v[16:19]
	v_mfma_f32_16x16x32_bf16 v[8:11], v[164:167], v[196:199], v[8:11]
	s_setprio 0
	s_barrier
	s_add_u32 s20, s20, 0x40080
	s_addc_u32 s21, s21, 0
	s_add_i32 s22, s22, s28
	s_mov_b32 m0, s22
	s_nop 0
	global_load_lds_dwordx4 v130, s[20:21]
	s_add_i32 m0, s22, 0x2000
	s_nop 0
	global_load_lds_dwordx4 v134, s[20:21]
	s_waitcnt vmcnt(10)
	s_barrier
	s_setprio 1
	v_mfma_f32_16x16x32_bf16 v[52:55], v[202:205], v[168:171], v[52:55]
	v_mfma_f32_16x16x32_bf16 v[44:47], v[210:213], v[168:171], v[44:47]
	v_mfma_f32_16x16x32_bf16 v[36:39], v[202:205], v[176:179], v[36:39]
	v_mfma_f32_16x16x32_bf16 v[28:31], v[210:213], v[176:179], v[28:31]
	v_mfma_f32_16x16x32_bf16 v[20:23], v[202:205], v[184:187], v[20:23]
	v_mfma_f32_16x16x32_bf16 v[12:15], v[210:213], v[184:187], v[12:15]
	v_mfma_f32_16x16x32_bf16 v[4:7], v[202:205], v[192:195], v[4:7]
	v_mfma_f32_16x16x32_bf16 v[0:3], v[210:213], v[192:195], v[0:3]
	v_mfma_f32_16x16x32_bf16 v[52:55], v[206:209], v[172:175], v[52:55]
	v_mfma_f32_16x16x32_bf16 v[44:47], v[214:217], v[172:175], v[44:47]
	v_mfma_f32_16x16x32_bf16 v[36:39], v[206:209], v[180:183], v[36:39]
	v_mfma_f32_16x16x32_bf16 v[28:31], v[214:217], v[180:183], v[28:31]
	v_mfma_f32_16x16x32_bf16 v[20:23], v[206:209], v[188:191], v[20:23]
	v_mfma_f32_16x16x32_bf16 v[12:15], v[214:217], v[188:191], v[12:15]
	v_mfma_f32_16x16x32_bf16 v[4:7], v[206:209], v[196:199], v[4:7]
	v_mfma_f32_16x16x32_bf16 v[0:3], v[214:217], v[196:199], v[0:3]
	s_setprio 0
	s_add_i32 s51, s51, 2
	s_add_u32 s18, s18, 0x100
	s_addc_u32 s19, s19, 0
	s_add_u32 s48, s48, 0x100
	s_addc_u32 s49, s49, 0
	s_cmp_gt_u32 s51, 13
	s_barrier
; __device__ __forceinline__ unsigned cvt_pk_bf16(float lo, float hi) { unsigned r; asm volatile("v_cvt_pk_bf16_f32 %0, %1, %2" : "=v"(r) : "v"(lo), "v"(hi)); return r; }
;     __device__ __forceinline__ void operator()(const AccT& acc, const Unit& u, int wr, int wc, int fr, int fq) const {
;         asm volatile("" : "+v"(fr), "+v"(fq));
;         const int rbase = u.pm * 256 + wr * 64 + fr;
;         const int tb = u.pn * 256 + wc * 32 + 8 * fq;
; #pragma unroll
;         for (int ai = 0; ai < 2; ++ai)
; #pragma unroll
;             for (int m = 0; m < 4; ++m) {
;                 const int gm = rbase + ai * 128 + m * 16;
; #pragma unroll
;                 for (int bj = 0; bj < 2; ++bj) {
;                     const int t0 = tb + bj * 128;
;                     const f32x4 v0 = acc[ai][bj][m][0], v1 = acc[ai][bj][m][1];
;                     u32x4 w; w.x = cvt_pk_bf16(v0[0], v0[1]); w.y = cvt_pk_bf16(v0[2], v0[3]); w.z = cvt_pk_bf16(v1[0], v1[1]); w.w = cvt_pk_bf16(v1[2], v1[3]);
;                     *(u32x4*)(YT + ((size_t)((t0 >> 10) * 512 + gm)) * 2048 + part * 1024 + (t0 & 1023)) = w;
;                 }
;             }
;     }
	s_cbranch_scc0 .LBB0_673
	v_mov_b32_e32 v136, v147
	v_mov_b32_e32 v152, v146
	s_lshl_b32 s7, s16, 8
	s_add_i32 s7, s7, s34
	v_add_u32_e32 v152, s7, v152
	s_lshl_b32 s7, s45, 8
	s_or_b32 s7, s7, s35
	v_lshl_add_u32 v153, v136, 3, s7
	v_cvt_pk_bf16_f32 v124, v124, v125
	v_cvt_pk_bf16_f32 v125, v126, v127
	v_cvt_pk_bf16_f32 v126, v120, v121
	v_ashrrev_i32_e32 v120, 1, v153
	v_cvt_pk_bf16_f32 v127, v122, v123
	v_and_b32_e32 v122, 0xfffffe00, v120
	v_add_u32_e32 v120, v122, v152
	v_ashrrev_i32_e32 v121, 31, v120
	v_lshlrev_b64 v[120:121], 12, v[120:121]
	v_and_b32_e32 v123, 0x3f8, v153
	v_lshl_add_u64 v[120:121], s[4:5], 0, v[120:121]
	v_lshlrev_b32_e32 v136, 1, v123
	v_lshl_add_u64 v[120:121], v[120:121], 0, v[136:137]
	global_store_dwordx4 v[120:121], v[124:127], off
	v_add_u32_e32 v120, 0x80, v153
	v_cvt_pk_bf16_f32 v116, v116, v117
	v_cvt_pk_bf16_f32 v117, v118, v119
	v_cvt_pk_bf16_f32 v118, v108, v109
	v_ashrrev_i32_e32 v108, 1, v120
	v_and_b32_e32 v121, 0xfffffe00, v108
	v_add_u32_e32 v108, v121, v152
	v_ashrrev_i32_e32 v109, 31, v108
	v_lshlrev_b64 v[108:109], 12, v[108:109]
	v_cvt_pk_bf16_f32 v119, v110, v111
	v_lshl_add_u64 v[110:111], s[4:5], 0, v[108:109]
	v_and_b32_e32 v108, 0x3f8, v120
	v_lshlrev_b32_e32 v108, 1, v108
	v_mov_b32_e32 v109, v137
	v_lshl_add_u64 v[110:111], v[110:111], 0, v[108:109]
	global_store_dwordx4 v[110:111], v[116:119], off
	v_cvt_pk_bf16_f32 v110, v112, v113
	v_cvt_pk_bf16_f32 v111, v114, v115
	v_cvt_pk_bf16_f32 v112, v104, v105
	v_cvt_pk_bf16_f32 v113, v106, v107
	s_and_b64 vcc, exec, s[2:3]
	s_nop 0
	v_add_u32_e32 v116, 16, v152
	v_add_u32_e32 v104, v122, v116
	v_ashrrev_i32_e32 v105, 31, v104
	v_lshlrev_b64 v[104:105], 12, v[104:105]
	v_lshl_add_u64 v[104:105], s[4:5], 0, v[104:105]
	v_lshl_add_u64 v[104:105], v[104:105], 0, v[136:137]
	global_store_dwordx4 v[104:105], v[110:113], off
	v_cvt_pk_bf16_f32 v100, v100, v101
	v_cvt_pk_bf16_f32 v101, v102, v103
	v_cvt_pk_bf16_f32 v102, v92, v93
	v_add_u32_e32 v92, v121, v116
	v_ashrrev_i32_e32 v93, 31, v92
	v_lshlrev_b64 v[92:93], 12, v[92:93]
	v_lshl_add_u64 v[92:93], s[4:5], 0, v[92:93]
	v_lshl_add_u64 v[92:93], v[92:93], 0, v[108:109]
	v_cvt_pk_bf16_f32 v103, v94, v95
	global_store_dwordx4 v[92:93], v[100:103], off
	v_cvt_pk_bf16_f32 v92, v96, v97
	v_cvt_pk_bf16_f32 v93, v98, v99
	v_cvt_pk_bf16_f32 v94, v88, v89
	v_cvt_pk_bf16_f32 v95, v90, v91
	s_mov_b32 s45, s6
	s_nop 0
	v_add_u32_e32 v100, 32, v152
	v_add_u32_e32 v88, v122, v100
	v_ashrrev_i32_e32 v89, 31, v88
	v_lshlrev_b64 v[88:89], 12, v[88:89]
	v_lshl_add_u64 v[88:89], s[4:5], 0, v[88:89]
	v_lshl_add_u64 v[88:89], v[88:89], 0, v[136:137]
	global_store_dwordx4 v[88:89], v[92:95], off
	v_cvt_pk_bf16_f32 v84, v84, v85
	v_cvt_pk_bf16_f32 v85, v86, v87
	v_cvt_pk_bf16_f32 v86, v76, v77
	v_add_u32_e32 v76, v121, v100
	v_ashrrev_i32_e32 v77, 31, v76
	v_lshlrev_b64 v[76:77], 12, v[76:77]
	v_lshl_add_u64 v[76:77], s[4:5], 0, v[76:77]
	v_lshl_add_u64 v[76:77], v[76:77], 0, v[108:109]
	v_cvt_pk_bf16_f32 v87, v78, v79
	global_store_dwordx4 v[76:77], v[84:87], off
	v_cvt_pk_bf16_f32 v76, v80, v81
	v_cvt_pk_bf16_f32 v77, v82, v83
	v_cvt_pk_bf16_f32 v78, v72, v73
	v_cvt_pk_bf16_f32 v79, v74, v75
	s_mov_b32 s16, s8
	s_nop 0
	v_add_u32_e32 v84, 48, v152
	v_add_u32_e32 v72, v122, v84
	v_ashrrev_i32_e32 v73, 31, v72
	v_lshlrev_b64 v[72:73], 12, v[72:73]
	v_lshl_add_u64 v[72:73], s[4:5], 0, v[72:73]
	v_lshl_add_u64 v[72:73], v[72:73], 0, v[136:137]
	global_store_dwordx4 v[72:73], v[76:79], off
	v_cvt_pk_bf16_f32 v68, v68, v69
	v_cvt_pk_bf16_f32 v69, v70, v71
	v_cvt_pk_bf16_f32 v70, v64, v65
	v_add_u32_e32 v64, v121, v84
	v_ashrrev_i32_e32 v65, 31, v64
	v_lshlrev_b64 v[64:65], 12, v[64:65]
	v_lshl_add_u64 v[64:65], s[4:5], 0, v[64:65]
	v_lshl_add_u64 v[64:65], v[64:65], 0, v[108:109]
	v_cvt_pk_bf16_f32 v71, v66, v67
	global_store_dwordx4 v[64:65], v[68:71], off
	v_add_u32_e32 v64, 0x80, v152
	v_cvt_pk_bf16_f32 v60, v60, v61
	v_cvt_pk_bf16_f32 v61, v62, v63
	v_cvt_pk_bf16_f32 v62, v56, v57
	v_add_u32_e32 v56, v122, v64
	v_ashrrev_i32_e32 v57, 31, v56
	v_lshlrev_b64 v[56:57], 12, v[56:57]
	v_lshl_add_u64 v[56:57], s[4:5], 0, v[56:57]
	v_lshl_add_u64 v[56:57], v[56:57], 0, v[136:137]
	v_cvt_pk_bf16_f32 v63, v58, v59
	global_store_dwordx4 v[56:57], v[60:63], off
	v_cvt_pk_bf16_f32 v52, v52, v53
	v_cvt_pk_bf16_f32 v53, v54, v55
	v_cvt_pk_bf16_f32 v54, v44, v45
	v_add_u32_e32 v44, v121, v64
	v_ashrrev_i32_e32 v45, 31, v44
	v_lshlrev_b64 v[44:45], 12, v[44:45]
	v_lshl_add_u64 v[44:45], s[4:5], 0, v[44:45]
	v_lshl_add_u64 v[44:45], v[44:45], 0, v[108:109]
	v_cvt_pk_bf16_f32 v55, v46, v47
	global_store_dwordx4 v[44:45], v[52:55], off
	v_cvt_pk_bf16_f32 v44, v48, v49
	v_cvt_pk_bf16_f32 v45, v50, v51
	v_cvt_pk_bf16_f32 v46, v40, v41
	v_cvt_pk_bf16_f32 v47, v42, v43
	s_mov_b64 s[20:21], s[14:15]
	s_nop 0
	v_add_u32_e32 v52, 0x90, v152
	v_add_u32_e32 v40, v122, v52
	v_ashrrev_i32_e32 v41, 31, v40
	v_lshlrev_b64 v[40:41], 12, v[40:41]
	v_lshl_add_u64 v[40:41], s[4:5], 0, v[40:41]
	v_lshl_add_u64 v[40:41], v[40:41], 0, v[136:137]
	global_store_dwordx4 v[40:41], v[44:47], off
	v_cvt_pk_bf16_f32 v36, v36, v37
	v_cvt_pk_bf16_f32 v37, v38, v39
	v_cvt_pk_bf16_f32 v38, v28, v29
	v_add_u32_e32 v28, v121, v52
	v_ashrrev_i32_e32 v29, 31, v28
	v_lshlrev_b64 v[28:29], 12, v[28:29]
	v_lshl_add_u64 v[28:29], s[4:5], 0, v[28:29]
	v_lshl_add_u64 v[28:29], v[28:29], 0, v[108:109]
	v_cvt_pk_bf16_f32 v39, v30, v31
	global_store_dwordx4 v[28:29], v[36:39], off
	v_cvt_pk_bf16_f32 v28, v32, v33
	v_cvt_pk_bf16_f32 v29, v34, v35
	v_cvt_pk_bf16_f32 v30, v24, v25
	v_cvt_pk_bf16_f32 v31, v26, v27
	s_mov_b64 s[18:19], s[12:13]
	s_nop 0
	v_add_u32_e32 v36, 0xa0, v152
	v_add_u32_e32 v24, v122, v36
	v_ashrrev_i32_e32 v25, 31, v24
	v_lshlrev_b64 v[24:25], 12, v[24:25]
	v_lshl_add_u64 v[24:25], s[4:5], 0, v[24:25]
	v_lshl_add_u64 v[24:25], v[24:25], 0, v[136:137]
	global_store_dwordx4 v[24:25], v[28:31], off
	v_cvt_pk_bf16_f32 v20, v20, v21
	v_cvt_pk_bf16_f32 v21, v22, v23
	v_cvt_pk_bf16_f32 v22, v12, v13
	v_add_u32_e32 v12, v121, v36
	v_ashrrev_i32_e32 v13, 31, v12
	v_lshlrev_b64 v[12:13], 12, v[12:13]
	v_lshl_add_u64 v[12:13], s[4:5], 0, v[12:13]
	v_lshl_add_u64 v[12:13], v[12:13], 0, v[108:109]
	v_cvt_pk_bf16_f32 v23, v14, v15
	global_store_dwordx4 v[12:13], v[20:23], off
	v_cvt_pk_bf16_f32 v12, v16, v17
	v_cvt_pk_bf16_f32 v13, v18, v19
	v_cvt_pk_bf16_f32 v14, v8, v9
	v_cvt_pk_bf16_f32 v15, v10, v11
	s_nop 1
	v_add_u32_e32 v20, 0xb0, v152
	v_add_u32_e32 v8, v122, v20
	v_ashrrev_i32_e32 v9, 31, v8
	v_lshlrev_b64 v[8:9], 12, v[8:9]
	v_lshl_add_u64 v[8:9], s[4:5], 0, v[8:9]
	v_lshl_add_u64 v[8:9], v[8:9], 0, v[136:137]
	global_store_dwordx4 v[8:9], v[12:15], off
	v_cvt_pk_bf16_f32 v4, v4, v5
	v_cvt_pk_bf16_f32 v5, v6, v7
	v_cvt_pk_bf16_f32 v6, v0, v1
	v_add_u32_e32 v0, v121, v20
	v_ashrrev_i32_e32 v1, 31, v0
	v_lshlrev_b64 v[0:1], 12, v[0:1]
	v_lshl_add_u64 v[0:1], s[4:5], 0, v[0:1]
	v_lshl_add_u64 v[0:1], v[0:1], 0, v[108:109]
	v_cvt_pk_bf16_f32 v7, v2, v3
	global_store_dwordx4 v[0:1], v[4:7], off
	s_cbranch_vccz .LBB0_666
; #define PG8_WAIT_V(n) asm volatile("s_waitcnt vmcnt(" #n ")" ::: "memory")
; #define PG8_BAR __builtin_amdgcn_s_barrier()
; template <class Epi, class Sched>
; __device__ __forceinline__ void gemm_phase(LAS unsigned char* lds, const Gemm g, const Sched& S, const Epi& E) {
;     ...
;     PG8_WAIT_V(0);
;     if (wr == 0) PG8_BAR;
;     PG8_BAR;
	s_waitcnt vmcnt(0)
	s_cmpk_gt_u32 s24, 0xff
	s_cbranch_scc1 .LBB0_677
	s_barrier

; #define PG8_STAGE(bufoff, gbase, voff) do { _Pragma("unroll") for (int _i = 0; _i < 2; ++_i) \
;         __builtin_amdgcn_global_load_lds((const unsigned*)((const char*)(gbase) + (voff)[_i]), (LAS unsigned*)(lds + (bufoff) + ldsw + _i * 8192), 16, 0, 0); } while (0)
; #define PG8_LDA(dst, b, h) do { _Pragma("unroll") for (int m = 0; m < 4; ++m) _Pragma("unroll") for (int k = 0; k < 2; ++k) dst[m][k] = *(const LAS bf16x8*)(lds + PG8_SA(b, h) + aoff + m * 2048 + k * 1024); } while (0)
; #define PG8_LDB(dst, b, h) do { _Pragma("unroll") for (int n = 0; n < 2; ++n) _Pragma("unroll") for (int k = 0; k < 2; ++k) dst[n][k] = *(const LAS bf16x8*)(lds + PG8_SB(b, h) + boff + n * 2048 + k * 1024); } while (0)
; #define PG8_MMA(ai, bj, At, Bt) do { __builtin_amdgcn_s_setprio(1); _Pragma("unroll") for (int m = 0; m < 4; ++m) _Pragma("unroll") for (int n = 0; n < 2; ++n) _Pragma("unroll") for (int k = 0; k < 2; ++k) \
;         acc[ai][bj][m][n] = __builtin_amdgcn_mfma_f32_16x16x32_bf16(Bt[n][k], At[m][k], acc[ai][bj][m][n], 0, 0, 0); __builtin_amdgcn_s_setprio(0); } while (0)
; #define PG8_WAIT_L(n) asm volatile("s_waitcnt lgkmcnt(" #n ")" ::: "memory")
; template <class Epi, class Sched>
; __device__ __forceinline__ void gemm_phase(LAS unsigned char* lds, const Gemm g, const Sched& S, const Epi& E) {
;     ...
;         const bool has_next = S.next(ui + 1, nxt);
;         const char* nA = has_next ? (const char*)g.A + (size_t)nxt.pm * tstep : cA; const char* nB = has_next ? (const char*)g.Bt + (size_t)nxt.pn * tstep : cB;
;         for (int t = 0; t < nt; t += 2) {
;             const bool last = (t == nt - 2);
;             const char* a1 = cA + (size_t)(t + 1) * kstep;
;             const char* a2 = last ? nA : cA + (size_t)(t + 2) * kstep; const char* b2 = last ? nB : cB + (size_t)(t + 2) * kstep;
;             const char* a3 = a2 + kstep; const char* b3 = b2 + kstep;
;             PG8_LDB(B0, 0, 0); PG8_SCHED; PG8_LDA(At, 0, 0); PG8_STAGE(PG8_SA(1, 1), a1 + hstep, voffA);
;             PG8_WAIT_L(8); PG8_BAR; PG8_WAIT_L(0); PG8_MMA(0, 0, At, B0); PG8_BAR; PG8_SCHED;
;             PG8_LDB(B1, 0, 1); PG8_STAGE(PG8_SB(0, 0), b2, voffB);
;             PG8_BAR; PG8_WAIT_L(0); PG8_MMA(0, 1, At, B1); PG8_BAR;
;             PG8_LDA(At, 0, 1); PG8_STAGE(PG8_SA(0, 0), a2, voffA);
;             PG8_BAR; PG8_WAIT_L(0); PG8_MMA(1, 0, At, B0); PG8_BAR; PG8_SCHED;
.LBB0_692:
	s_ashr_i32 s19, s18, 31
	v_cmp_lt_i64_e64 s[24:25], s[20:21], 32
	s_lshl_b64 s[20:21], s[18:19], 19
	s_add_u32 s20, s40, s20
	s_addc_u32 s21, s41, s21
	s_and_b64 s[22:23], s[24:25], exec
	s_cselect_b32 s19, s21, s3
	s_cselect_b32 s57, s20, s2
	s_ashr_i32 s17, s16, 31
	s_lshl_b64 s[22:23], s[16:17], 19
	s_add_u32 s22, s28, s22
	s_addc_u32 s23, s29, s23
	s_and_b64 s[24:25], s[24:25], exec
	s_cselect_b32 s17, s23, s5
	s_cselect_b32 s58, s22, s4
	s_add_u32 s2, s2, 0x40080
	s_addc_u32 s3, s3, 0
	s_add_u32 s59, s4, 0x100
	s_addc_u32 s60, s5, 0
	s_mov_b32 s61, -2
	s_waitcnt lgkmcnt(0)
	ds_read_b128 v[140:143], v149
	ds_read_b128 v[154:157], v149 offset:1024
	ds_read_b128 v[158:161], v149 offset:2048
	ds_read_b128 v[162:165], v149 offset:3072
	s_add_u32 s4, s2, 0xfffc0080
	s_addc_u32 s5, s3, -1
	s_cmp_eq_u32 s61, 12
	s_cselect_b32 s25, s19, s5
	s_cselect_b32 s24, s57, s4
	s_cselect_b32 s5, s17, s60
	s_cselect_b32 s4, s58, s59
	s_add_i32 m0, s33, 0xc000
	ds_read_b128 v[166:169], v150
	ds_read_b128 v[170:173], v150 offset:1024
	ds_read_b128 v[174:177], v150 offset:2048
	ds_read_b128 v[178:181], v150 offset:3072
	ds_read_b128 v[182:185], v150 offset:4096
	ds_read_b128 v[186:189], v150 offset:5120
	ds_read_b128 v[190:193], v150 offset:6144
	ds_read_b128 v[194:197], v150 offset:7168
	global_load_lds_dwordx4 v136, s[2:3]
	s_add_i32 m0, s33, 0xe000
	s_nop 0
	global_load_lds_dwordx4 v138, s[2:3]
	s_waitcnt vmcnt(10)
	s_barrier
	s_waitcnt lgkmcnt(0)
	s_setprio 1
	s_waitcnt lgkmcnt(0)
	v_mfma_f32_16x16x32_bf16 v[124:127], v[140:143], v[166:169], 0
	v_mfma_f32_16x16x32_bf16 v[120:123], v[158:161], v[166:169], 0
	v_mfma_f32_16x16x32_bf16 v[108:111], v[140:143], v[174:177], 0
	v_mfma_f32_16x16x32_bf16 v[104:107], v[158:161], v[174:177], 0
	v_mfma_f32_16x16x32_bf16 v[92:95], v[140:143], v[182:185], 0
	v_mfma_f32_16x16x32_bf16 v[88:91], v[158:161], v[182:185], 0
	v_mfma_f32_16x16x32_bf16 v[76:79], v[140:143], v[190:193], 0
	v_mfma_f32_16x16x32_bf16 v[72:75], v[158:161], v[190:193], 0
	v_mfma_f32_16x16x32_bf16 v[124:127], v[154:157], v[170:173], v[124:127]
	v_mfma_f32_16x16x32_bf16 v[120:123], v[162:165], v[170:173], v[120:123]
	v_mfma_f32_16x16x32_bf16 v[108:111], v[154:157], v[178:181], v[108:111]
	v_mfma_f32_16x16x32_bf16 v[104:107], v[162:165], v[178:181], v[104:107]
	v_mfma_f32_16x16x32_bf16 v[92:95], v[154:157], v[186:189], v[92:95]
	v_mfma_f32_16x16x32_bf16 v[88:91], v[162:165], v[186:189], v[88:91]
	v_mfma_f32_16x16x32_bf16 v[76:79], v[154:157], v[194:197], v[76:79]
	v_mfma_f32_16x16x32_bf16 v[72:75], v[162:165], v[194:197], v[72:75]
	s_setprio 0
	s_barrier
	s_add_i32 s62, s47, s31
	s_mov_b32 m0, s62
	ds_read_b128 v[202:205], v151
	ds_read_b128 v[206:209], v151 offset:1024
	ds_read_b128 v[210:213], v151 offset:2048
	ds_read_b128 v[214:217], v151 offset:3072
	global_load_lds_dwordx4 v130, s[4:5]
	s_add_i32 m0, s62, 0x2000
	s_nop 0
	global_load_lds_dwordx4 v134, s[4:5]
	s_waitcnt vmcnt(10)
	s_barrier
	s_waitcnt lgkmcnt(0)
	s_setprio 1
	s_waitcnt lgkmcnt(0)
	v_mfma_f32_16x16x32_bf16 v[116:119], v[202:205], v[166:169], 0
	v_mfma_f32_16x16x32_bf16 v[112:115], v[210:213], v[166:169], 0
	v_mfma_f32_16x16x32_bf16 v[100:103], v[202:205], v[174:177], 0
	v_mfma_f32_16x16x32_bf16 v[96:99], v[210:213], v[174:177], 0
	v_mfma_f32_16x16x32_bf16 v[84:87], v[202:205], v[182:185], 0
	v_mfma_f32_16x16x32_bf16 v[80:83], v[210:213], v[182:185], 0
	v_mfma_f32_16x16x32_bf16 v[68:71], v[202:205], v[190:193], 0
	v_mfma_f32_16x16x32_bf16 v[64:67], v[210:213], v[190:193], 0
	v_mfma_f32_16x16x32_bf16 v[116:119], v[206:209], v[170:173], v[116:119]
	v_mfma_f32_16x16x32_bf16 v[112:115], v[214:217], v[170:173], v[112:115]
	v_mfma_f32_16x16x32_bf16 v[100:103], v[206:209], v[178:181], v[100:103]
	v_mfma_f32_16x16x32_bf16 v[96:99], v[214:217], v[178:181], v[96:99]
	v_mfma_f32_16x16x32_bf16 v[84:87], v[206:209], v[186:189], v[84:87]
	v_mfma_f32_16x16x32_bf16 v[80:83], v[214:217], v[186:189], v[80:83]
	v_mfma_f32_16x16x32_bf16 v[68:71], v[206:209], v[194:197], v[68:71]
	v_mfma_f32_16x16x32_bf16 v[64:67], v[214:217], v[194:197], v[64:67]
	s_setprio 0
	s_mov_b32 m0, s33
	v_lshl_add_u64 v[218:219], s[24:25], 0, v[128:129]
	s_barrier
	ds_read_b128 v[166:169], v150 offset:16384
	ds_read_b128 v[170:173], v150 offset:17408
	ds_read_b128 v[174:177], v150 offset:18432
	ds_read_b128 v[178:181], v150 offset:19456
	ds_read_b128 v[182:185], v150 offset:20480
	ds_read_b128 v[186:189], v150 offset:21504
	ds_read_b128 v[190:193], v150 offset:22528
	ds_read_b128 v[194:197], v150 offset:23552
	global_load_lds_dwordx4 v128, s[24:25]
	v_lshl_add_u64 v[220:221], s[24:25], 0, v[132:133]
	s_mov_b32 m0, s34
	s_nop 0
	global_load_lds_dwordx4 v132, s[24:25]
	s_barrier
	s_waitcnt lgkmcnt(0)
	s_setprio 1
	s_waitcnt lgkmcnt(0)
	v_mfma_f32_16x16x32_bf16 v[60:63], v[140:143], v[166:169], 0
	v_mfma_f32_16x16x32_bf16 v[56:59], v[158:161], v[166:169], 0
	v_mfma_f32_16x16x32_bf16 v[44:47], v[140:143], v[174:177], 0
	v_mfma_f32_16x16x32_bf16 v[40:43], v[158:161], v[174:177], 0
	v_mfma_f32_16x16x32_bf16 v[28:31], v[140:143], v[182:185], 0
	v_mfma_f32_16x16x32_bf16 v[24:27], v[158:161], v[182:185], 0
	v_mfma_f32_16x16x32_bf16 v[12:15], v[140:143], v[190:193], 0
	v_mfma_f32_16x16x32_bf16 v[8:11], v[158:161], v[190:193], 0
	v_mfma_f32_16x16x32_bf16 v[60:63], v[154:157], v[170:173], v[60:63]
	v_mfma_f32_16x16x32_bf16 v[56:59], v[162:165], v[170:173], v[56:59]
	v_mfma_f32_16x16x32_bf16 v[44:47], v[154:157], v[178:181], v[44:47]
	v_mfma_f32_16x16x32_bf16 v[40:43], v[162:165], v[178:181], v[40:43]
	v_mfma_f32_16x16x32_bf16 v[28:31], v[154:157], v[186:189], v[28:31]
	v_mfma_f32_16x16x32_bf16 v[24:27], v[162:165], v[186:189], v[24:27]
	v_mfma_f32_16x16x32_bf16 v[12:15], v[154:157], v[194:197], v[12:15]
	v_mfma_f32_16x16x32_bf16 v[8:11], v[162:165], v[194:197], v[8:11]
	s_setprio 0
	s_barrier
; #define PG8_STAGE(bufoff, gbase, voff) do { _Pragma("unroll") for (int _i = 0; _i < 2; ++_i) \
;         __builtin_amdgcn_global_load_lds((const unsigned*)((const char*)(gbase) + (voff)[_i]), (LAS unsigned*)(lds + (bufoff) + ldsw + _i * 8192), 16, 0, 0); } while (0)
; #define PG8_LDA(dst, b, h) do { _Pragma("unroll") for (int m = 0; m < 4; ++m) _Pragma("unroll") for (int k = 0; k < 2; ++k) dst[m][k] = *(const LAS bf16x8*)(lds + PG8_SA(b, h) + aoff + m * 2048 + k * 1024); } while (0)
; #define PG8_LDB(dst, b, h) do { _Pragma("unroll") for (int n = 0; n < 2; ++n) _Pragma("unroll") for (int k = 0; k < 2; ++k) dst[n][k] = *(const LAS bf16x8*)(lds + PG8_SB(b, h) + boff + n * 2048 + k * 1024); } while (0)
; #define PG8_MMA(ai, bj, At, Bt) do { __builtin_amdgcn_s_setprio(1); _Pragma("unroll") for (int m = 0; m < 4; ++m) _Pragma("unroll") for (int n = 0; n < 2; ++n) _Pragma("unroll") for (int k = 0; k < 2; ++k) \
;         acc[ai][bj][m][n] = __builtin_amdgcn_mfma_f32_16x16x32_bf16(Bt[n][k], At[m][k], acc[ai][bj][m][n], 0, 0, 0); __builtin_amdgcn_s_setprio(0); } while (0)
; #define PG8_WAIT_V(n) asm volatile("s_waitcnt vmcnt(" #n ")" ::: "memory")
; #define PG8_WAIT_L(n) asm volatile("s_waitcnt lgkmcnt(" #n ")" ::: "memory")
; #define PG8_BAR __builtin_amdgcn_s_barrier()
; #define PG8_SCHED __builtin_amdgcn_sched_barrier(0)
; template <class Epi, class Sched>
; __device__ __forceinline__ void gemm_phase(LAS unsigned char* lds, const Gemm g, const Sched& S, const Epi& E) {
;     ...
;             PG8_STAGE(PG8_SB(0, 1), b2 + hstep, voffB);
;             PG8_WAIT_V(6); PG8_BAR; PG8_MMA(1, 1, At, B1); PG8_BAR;
;             PG8_LDB(B0, 1, 0); PG8_SCHED; PG8_LDA(At, 1, 0); PG8_STAGE(PG8_SA(0, 1), a2 + hstep, voffA);
;             PG8_WAIT_L(8); PG8_BAR; PG8_WAIT_L(0); PG8_MMA(0, 0, At, B0); PG8_BAR; PG8_SCHED;
;             PG8_LDB(B1, 1, 1); PG8_STAGE(PG8_SB(1, 0), b3, voffB);
;             PG8_BAR; PG8_WAIT_L(0); PG8_MMA(0, 1, At, B1); PG8_BAR;
;             PG8_LDA(At, 1, 1); PG8_STAGE(PG8_SA(1, 0), a3, voffA);
;             PG8_BAR; PG8_WAIT_L(0); PG8_MMA(1, 0, At, B0); PG8_BAR; PG8_SCHED;
	s_add_u32 s62, s4, 0x40000
	s_addc_u32 s63, s5, 0
	s_add_i32 s64, s48, s31
	s_mov_b32 m0, s64
	s_nop 0
	global_load_lds_dwordx4 v130, s[62:63]
	s_add_i32 m0, s64, 0x2000
	s_nop 0
	global_load_lds_dwordx4 v134, s[62:63]
	s_add_u32 s24, s24, 0x40000
	s_addc_u32 s25, s25, 0
	s_mov_b32 m0, s35
	s_nop 0
	global_load_lds_dwordx4 v128, s[24:25]
	s_mov_b32 m0, s36
	s_nop 0
	global_load_lds_dwordx4 v132, s[24:25]
	s_waitcnt vmcnt(12)
	s_barrier
	s_setprio 1
	v_mfma_f32_16x16x32_bf16 v[52:55], v[202:205], v[166:169], 0
	v_mfma_f32_16x16x32_bf16 v[48:51], v[210:213], v[166:169], 0
	v_mfma_f32_16x16x32_bf16 v[36:39], v[202:205], v[174:177], 0
	v_mfma_f32_16x16x32_bf16 v[32:35], v[210:213], v[174:177], 0
	v_mfma_f32_16x16x32_bf16 v[20:23], v[202:205], v[182:185], 0
	v_mfma_f32_16x16x32_bf16 v[16:19], v[210:213], v[182:185], 0
	v_mfma_f32_16x16x32_bf16 v[4:7], v[202:205], v[190:193], 0
	v_mfma_f32_16x16x32_bf16 v[0:3], v[210:213], v[190:193], 0
	v_mfma_f32_16x16x32_bf16 v[52:55], v[206:209], v[170:173], v[52:55]
	v_mfma_f32_16x16x32_bf16 v[48:51], v[214:217], v[170:173], v[48:51]
	v_mfma_f32_16x16x32_bf16 v[36:39], v[206:209], v[178:181], v[36:39]
	v_mfma_f32_16x16x32_bf16 v[32:35], v[214:217], v[178:181], v[32:35]
	v_mfma_f32_16x16x32_bf16 v[20:23], v[206:209], v[186:189], v[20:23]
	v_mfma_f32_16x16x32_bf16 v[16:19], v[214:217], v[186:189], v[16:19]
	v_mfma_f32_16x16x32_bf16 v[4:7], v[206:209], v[194:197], v[4:7]
	v_mfma_f32_16x16x32_bf16 v[0:3], v[214:217], v[194:197], v[0:3]
	s_setprio 0
	s_add_i32 s62, 0, 0x18000
	v_add_u32_e32 v162, s62, v148
	s_barrier
	ds_read_b128 v[140:143], v162
	ds_read_b128 v[154:157], v162 offset:1024
	ds_read_b128 v[158:161], v162 offset:2048
	ds_read_b128 v[162:165], v162 offset:3072
	ds_read_b128 v[166:169], v150 offset:32768
	ds_read_b128 v[170:173], v150 offset:33792
	ds_read_b128 v[174:177], v150 offset:34816
	ds_read_b128 v[178:181], v150 offset:35840
	ds_read_b128 v[182:185], v150 offset:36864
	ds_read_b128 v[186:189], v150 offset:37888
	ds_read_b128 v[190:193], v150 offset:38912
	ds_read_b128 v[194:197], v150 offset:39936
	s_waitcnt vmcnt(10)
	s_barrier
	s_waitcnt lgkmcnt(0)
	s_setprio 1
	s_waitcnt lgkmcnt(0)
	v_mfma_f32_16x16x32_bf16 v[124:127], v[140:143], v[166:169], v[124:127]
	v_mfma_f32_16x16x32_bf16 v[120:123], v[158:161], v[166:169], v[120:123]
	v_mfma_f32_16x16x32_bf16 v[108:111], v[140:143], v[174:177], v[108:111]
	v_mfma_f32_16x16x32_bf16 v[104:107], v[158:161], v[174:177], v[104:107]
	v_mfma_f32_16x16x32_bf16 v[92:95], v[140:143], v[182:185], v[92:95]
	v_mfma_f32_16x16x32_bf16 v[88:91], v[158:161], v[182:185], v[88:91]
	v_mfma_f32_16x16x32_bf16 v[76:79], v[140:143], v[190:193], v[76:79]
	v_mfma_f32_16x16x32_bf16 v[72:75], v[158:161], v[190:193], v[72:75]
	v_mfma_f32_16x16x32_bf16 v[124:127], v[154:157], v[170:173], v[124:127]
	v_mfma_f32_16x16x32_bf16 v[120:123], v[162:165], v[170:173], v[120:123]
	v_mfma_f32_16x16x32_bf16 v[108:111], v[154:157], v[178:181], v[108:111]
	v_mfma_f32_16x16x32_bf16 v[104:107], v[162:165], v[178:181], v[104:107]
	v_mfma_f32_16x16x32_bf16 v[92:95], v[154:157], v[186:189], v[92:95]
	v_mfma_f32_16x16x32_bf16 v[88:91], v[162:165], v[186:189], v[88:91]
	v_mfma_f32_16x16x32_bf16 v[76:79], v[154:157], v[194:197], v[76:79]
	v_mfma_f32_16x16x32_bf16 v[72:75], v[162:165], v[194:197], v[72:75]
	s_setprio 0
	s_barrier
	s_add_i32 s24, 0, 0x1c000
	s_add_i32 s25, s62, s31
	v_add_u32_e32 v214, s24, v148
	s_add_u32 s0, s4, 0x80
	s_addc_u32 s1, s5, 0
	s_mov_b32 m0, s25
	ds_read_b128 v[202:205], v214
	ds_read_b128 v[206:209], v214 offset:1024
	ds_read_b128 v[210:213], v214 offset:2048
	ds_read_b128 v[214:217], v214 offset:3072
	global_load_lds_dwordx4 v130, s[0:1]
	s_add_i32 m0, s25, 0x2000
	s_nop 0
	global_load_lds_dwordx4 v134, s[0:1]
	s_waitcnt vmcnt(10)
	s_barrier
	s_waitcnt lgkmcnt(0)
	s_setprio 1
	s_waitcnt lgkmcnt(0)
	v_mfma_f32_16x16x32_bf16 v[116:119], v[202:205], v[166:169], v[116:119]
	v_mfma_f32_16x16x32_bf16 v[112:115], v[210:213], v[166:169], v[112:115]
	v_mfma_f32_16x16x32_bf16 v[100:103], v[202:205], v[174:177], v[100:103]
	v_mfma_f32_16x16x32_bf16 v[96:99], v[210:213], v[174:177], v[96:99]
	v_mfma_f32_16x16x32_bf16 v[84:87], v[202:205], v[182:185], v[84:87]
	v_mfma_f32_16x16x32_bf16 v[80:83], v[210:213], v[182:185], v[80:83]
	v_mfma_f32_16x16x32_bf16 v[68:71], v[202:205], v[190:193], v[68:71]
	v_mfma_f32_16x16x32_bf16 v[64:67], v[210:213], v[190:193], v[64:67]
	v_mfma_f32_16x16x32_bf16 v[116:119], v[206:209], v[170:173], v[116:119]
	v_mfma_f32_16x16x32_bf16 v[112:115], v[214:217], v[170:173], v[112:115]
	v_mfma_f32_16x16x32_bf16 v[100:103], v[206:209], v[178:181], v[100:103]
	v_mfma_f32_16x16x32_bf16 v[96:99], v[214:217], v[178:181], v[96:99]
	v_mfma_f32_16x16x32_bf16 v[84:87], v[206:209], v[186:189], v[84:87]
	v_mfma_f32_16x16x32_bf16 v[80:83], v[214:217], v[186:189], v[80:83]
	v_mfma_f32_16x16x32_bf16 v[68:71], v[206:209], v[194:197], v[68:71]
	v_mfma_f32_16x16x32_bf16 v[64:67], v[214:217], v[194:197], v[64:67]
	s_setprio 0
	s_mov_b32 m0, s44
	s_mov_b64 s[0:1], 0x80
	v_lshl_add_u64 v[144:145], v[218:219], 0, s[0:1]
	s_barrier
	ds_read_b128 v[166:169], v150 offset:49152
	ds_read_b128 v[170:173], v150 offset:50176
	ds_read_b128 v[174:177], v150 offset:51200
	ds_read_b128 v[178:181], v150 offset:52224
	ds_read_b128 v[182:185], v150 offset:53248
	ds_read_b128 v[186:189], v150 offset:54272
	ds_read_b128 v[190:193], v150 offset:55296
	ds_read_b128 v[194:197], v150 offset:56320
	global_load_lds_dwordx4 v[144:145], off
	v_lshl_add_u64 v[144:145], v[220:221], 0, s[0:1]
	s_mov_b32 m0, s45
	s_nop 0
	global_load_lds_dwordx4 v[144:145], off
	s_barrier
; #define PG8_STAGE(bufoff, gbase, voff) do { _Pragma("unroll") for (int _i = 0; _i < 2; ++_i) \
;         __builtin_amdgcn_global_load_lds((const unsigned*)((const char*)(gbase) + (voff)[_i]), (LAS unsigned*)(lds + (bufoff) + ldsw + _i * 8192), 16, 0, 0); } while (0)
; #define PG8_LDA(dst, b, h) do { _Pragma("unroll") for (int m = 0; m < 4; ++m) _Pragma("unroll") for (int k = 0; k < 2; ++k) dst[m][k] = *(const LAS bf16x8*)(lds + PG8_SA(b, h) + aoff + m * 2048 + k * 1024); } while (0)
; #define PG8_LDB(dst, b, h) do { _Pragma("unroll") for (int n = 0; n < 2; ++n) _Pragma("unroll") for (int k = 0; k < 2; ++k) dst[n][k] = *(const LAS bf16x8*)(lds + PG8_SB(b, h) + boff + n * 2048 + k * 1024); } while (0)
; #define PG8_MMA(ai, bj, At, Bt) do { __builtin_amdgcn_s_setprio(1); _Pragma("unroll") for (int m = 0; m < 4; ++m) _Pragma("unroll") for (int n = 0; n < 2; ++n) _Pragma("unroll") for (int k = 0; k < 2; ++k) \
;         acc[ai][bj][m][n] = __builtin_amdgcn_mfma_f32_16x16x32_bf16(Bt[n][k], At[m][k], acc[ai][bj][m][n], 0, 0, 0); __builtin_amdgcn_s_setprio(0); } while (0)
; #define PG8_WAIT_V(n) asm volatile("s_waitcnt vmcnt(" #n ")" ::: "memory")
; #define PG8_WAIT_L(n) asm volatile("s_waitcnt lgkmcnt(" #n ")" ::: "memory")
; #define PG8_BAR __builtin_amdgcn_s_barrier()
; #define PG8_SCHED __builtin_amdgcn_sched_barrier(0)
; template <class Epi, class Sched>
; __device__ __forceinline__ void gemm_phase(LAS unsigned char* lds, const Gemm g, const Sched& S, const Epi& E) {
;     ...
;         for (int t = 0; t < nt; t += 2) {
;             const bool last = (t == nt - 2);
;             const char* a1 = cA + (size_t)(t + 1) * kstep;
;             const char* a2 = last ? nA : cA + (size_t)(t + 2) * kstep; const char* b2 = last ? nB : cB + (size_t)(t + 2) * kstep;
;             const char* a3 = a2 + kstep; const char* b3 = b2 + kstep;
;             PG8_LDB(B0, 0, 0); PG8_SCHED; PG8_LDA(At, 0, 0); PG8_STAGE(PG8_SA(1, 1), a1 + hstep, voffA);
;             PG8_WAIT_L(8); PG8_BAR; PG8_WAIT_L(0); PG8_MMA(0, 0, At, B0); PG8_BAR; PG8_SCHED;
;             PG8_LDB(B1, 0, 1); PG8_STAGE(PG8_SB(0, 0), b2, voffB);
;     ...
;             PG8_BAR; PG8_WAIT_L(0); PG8_MMA(1, 0, At, B0); PG8_BAR; PG8_SCHED;
;             PG8_STAGE(PG8_SB(1, 1), b3 + hstep, voffB);
;             PG8_WAIT_V(6); PG8_BAR; PG8_MMA(1, 1, At, B1); PG8_BAR;
	s_waitcnt lgkmcnt(0)
	s_setprio 1
	s_waitcnt lgkmcnt(0)
	v_mfma_f32_16x16x32_bf16 v[60:63], v[140:143], v[166:169], v[60:63]
	v_mfma_f32_16x16x32_bf16 v[56:59], v[158:161], v[166:169], v[56:59]
	v_mfma_f32_16x16x32_bf16 v[44:47], v[140:143], v[174:177], v[44:47]
	v_mfma_f32_16x16x32_bf16 v[40:43], v[158:161], v[174:177], v[40:43]
	v_mfma_f32_16x16x32_bf16 v[28:31], v[140:143], v[182:185], v[28:31]
	v_mfma_f32_16x16x32_bf16 v[24:27], v[158:161], v[182:185], v[24:27]
	v_mfma_f32_16x16x32_bf16 v[12:15], v[140:143], v[190:193], v[12:15]
	v_mfma_f32_16x16x32_bf16 v[8:11], v[158:161], v[190:193], v[8:11]
	v_mfma_f32_16x16x32_bf16 v[60:63], v[154:157], v[170:173], v[60:63]
	v_mfma_f32_16x16x32_bf16 v[56:59], v[162:165], v[170:173], v[56:59]
	v_mfma_f32_16x16x32_bf16 v[44:47], v[154:157], v[178:181], v[44:47]
	v_mfma_f32_16x16x32_bf16 v[40:43], v[162:165], v[178:181], v[40:43]
	v_mfma_f32_16x16x32_bf16 v[28:31], v[154:157], v[186:189], v[28:31]
	v_mfma_f32_16x16x32_bf16 v[24:27], v[162:165], v[186:189], v[24:27]
	v_mfma_f32_16x16x32_bf16 v[12:15], v[154:157], v[194:197], v[12:15]
	v_mfma_f32_16x16x32_bf16 v[8:11], v[162:165], v[194:197], v[8:11]
	s_setprio 0
	s_barrier
	s_add_u32 s4, s4, 0x40080
	s_addc_u32 s5, s5, 0
	s_add_i32 s24, s24, s31
	s_mov_b32 m0, s24
	s_nop 0
	global_load_lds_dwordx4 v130, s[4:5]
	s_add_i32 m0, s24, 0x2000
	s_nop 0
	global_load_lds_dwordx4 v134, s[4:5]
	s_waitcnt vmcnt(10)
	s_barrier
	s_setprio 1
	v_mfma_f32_16x16x32_bf16 v[52:55], v[202:205], v[166:169], v[52:55]
	v_mfma_f32_16x16x32_bf16 v[48:51], v[210:213], v[166:169], v[48:51]
	v_mfma_f32_16x16x32_bf16 v[36:39], v[202:205], v[174:177], v[36:39]
	v_mfma_f32_16x16x32_bf16 v[32:35], v[210:213], v[174:177], v[32:35]
	v_mfma_f32_16x16x32_bf16 v[20:23], v[202:205], v[182:185], v[20:23]
	v_mfma_f32_16x16x32_bf16 v[16:19], v[210:213], v[182:185], v[16:19]
	v_mfma_f32_16x16x32_bf16 v[4:7], v[202:205], v[190:193], v[4:7]
	v_mfma_f32_16x16x32_bf16 v[0:3], v[210:213], v[190:193], v[0:3]
	v_mfma_f32_16x16x32_bf16 v[52:55], v[206:209], v[170:173], v[52:55]
	v_mfma_f32_16x16x32_bf16 v[48:51], v[214:217], v[170:173], v[48:51]
	v_mfma_f32_16x16x32_bf16 v[36:39], v[206:209], v[178:181], v[36:39]
	v_mfma_f32_16x16x32_bf16 v[32:35], v[214:217], v[178:181], v[32:35]
	v_mfma_f32_16x16x32_bf16 v[20:23], v[206:209], v[186:189], v[20:23]
	v_mfma_f32_16x16x32_bf16 v[16:19], v[214:217], v[186:189], v[16:19]
	v_mfma_f32_16x16x32_bf16 v[4:7], v[206:209], v[194:197], v[4:7]
	v_mfma_f32_16x16x32_bf16 v[0:3], v[214:217], v[194:197], v[0:3]
	s_setprio 0
	s_add_i32 s61, s61, 2
	s_add_u32 s2, s2, 0x100
	s_addc_u32 s3, s3, 0
	s_add_u32 s59, s59, 0x100
	s_addc_u32 s60, s60, 0
	s_cmp_gt_u32 s61, 13
	s_barrier
.LBB0_693:
	ds_read_b128 v[140:143], v149
	ds_read_b128 v[154:157], v149 offset:1024
	ds_read_b128 v[158:161], v149 offset:2048
	ds_read_b128 v[162:165], v149 offset:3072
	s_add_u32 s4, s2, 0xfffc0080
	s_addc_u32 s5, s3, -1
	s_cmp_eq_u32 s61, 12
	s_cselect_b32 s25, s19, s5
	s_cselect_b32 s24, s57, s4
	s_cselect_b32 s5, s17, s60
	s_cselect_b32 s4, s58, s59
	s_add_i32 m0, s33, 0xc000
	ds_read_b128 v[166:169], v150
	ds_read_b128 v[170:173], v150 offset:1024
	ds_read_b128 v[174:177], v150 offset:2048
	ds_read_b128 v[178:181], v150 offset:3072
	ds_read_b128 v[182:185], v150 offset:4096
	ds_read_b128 v[186:189], v150 offset:5120
	ds_read_b128 v[190:193], v150 offset:6144
	ds_read_b128 v[194:197], v150 offset:7168
	global_load_lds_dwordx4 v136, s[2:3]
	s_add_i32 m0, s33, 0xe000
	s_nop 0
	global_load_lds_dwordx4 v138, s[2:3]
	s_waitcnt vmcnt(10)
	s_barrier
	s_waitcnt lgkmcnt(0)
	s_setprio 1
	s_waitcnt lgkmcnt(0)
	v_mfma_f32_16x16x32_bf16 v[124:127], v[140:143], v[166:169], v[124:127]
	v_mfma_f32_16x16x32_bf16 v[120:123], v[158:161], v[166:169], v[120:123]
	v_mfma_f32_16x16x32_bf16 v[108:111], v[140:143], v[174:177], v[108:111]
	v_mfma_f32_16x16x32_bf16 v[104:107], v[158:161], v[174:177], v[104:107]
	v_mfma_f32_16x16x32_bf16 v[92:95], v[140:143], v[182:185], v[92:95]
	v_mfma_f32_16x16x32_bf16 v[88:91], v[158:161], v[182:185], v[88:91]
	v_mfma_f32_16x16x32_bf16 v[76:79], v[140:143], v[190:193], v[76:79]
	v_mfma_f32_16x16x32_bf16 v[72:75], v[158:161], v[190:193], v[72:75]
	v_mfma_f32_16x16x32_bf16 v[124:127], v[154:157], v[170:173], v[124:127]
	v_mfma_f32_16x16x32_bf16 v[120:123], v[162:165], v[170:173], v[120:123]
	v_mfma_f32_16x16x32_bf16 v[108:111], v[154:157], v[178:181], v[108:111]
	v_mfma_f32_16x16x32_bf16 v[104:107], v[162:165], v[178:181], v[104:107]
	v_mfma_f32_16x16x32_bf16 v[92:95], v[154:157], v[186:189], v[92:95]
	v_mfma_f32_16x16x32_bf16 v[88:91], v[162:165], v[186:189], v[88:91]
	v_mfma_f32_16x16x32_bf16 v[76:79], v[154:157], v[194:197], v[76:79]
	v_mfma_f32_16x16x32_bf16 v[72:75], v[162:165], v[194:197], v[72:75]
	s_setprio 0
	s_barrier
	s_add_i32 s62, s47, s31
	s_mov_b32 m0, s62
	ds_read_b128 v[202:205], v151
	ds_read_b128 v[206:209], v151 offset:1024
	ds_read_b128 v[210:213], v151 offset:2048
	ds_read_b128 v[214:217], v151 offset:3072
	global_load_lds_dwordx4 v130, s[4:5]
	s_add_i32 m0, s62, 0x2000
	s_nop 0
	global_load_lds_dwordx4 v134, s[4:5]
	s_waitcnt vmcnt(10)
	s_barrier
; #define PG8_STAGE(bufoff, gbase, voff) do { _Pragma("unroll") for (int _i = 0; _i < 2; ++_i) \
;         __builtin_amdgcn_global_load_lds((const unsigned*)((const char*)(gbase) + (voff)[_i]), (LAS unsigned*)(lds + (bufoff) + ldsw + _i * 8192), 16, 0, 0); } while (0)
; #define PG8_LDA(dst, b, h) do { _Pragma("unroll") for (int m = 0; m < 4; ++m) _Pragma("unroll") for (int k = 0; k < 2; ++k) dst[m][k] = *(const LAS bf16x8*)(lds + PG8_SA(b, h) + aoff + m * 2048 + k * 1024); } while (0)
; #define PG8_LDB(dst, b, h) do { _Pragma("unroll") for (int n = 0; n < 2; ++n) _Pragma("unroll") for (int k = 0; k < 2; ++k) dst[n][k] = *(const LAS bf16x8*)(lds + PG8_SB(b, h) + boff + n * 2048 + k * 1024); } while (0)
; #define PG8_MMA(ai, bj, At, Bt) do { __builtin_amdgcn_s_setprio(1); _Pragma("unroll") for (int m = 0; m < 4; ++m) _Pragma("unroll") for (int n = 0; n < 2; ++n) _Pragma("unroll") for (int k = 0; k < 2; ++k) \
;         acc[ai][bj][m][n] = __builtin_amdgcn_mfma_f32_16x16x32_bf16(Bt[n][k], At[m][k], acc[ai][bj][m][n], 0, 0, 0); __builtin_amdgcn_s_setprio(0); } while (0)
; #define PG8_WAIT_V(n) asm volatile("s_waitcnt vmcnt(" #n ")" ::: "memory")
; #define PG8_WAIT_L(n) asm volatile("s_waitcnt lgkmcnt(" #n ")" ::: "memory")
; #define PG8_BAR __builtin_amdgcn_s_barrier()
; #define PG8_SCHED __builtin_amdgcn_sched_barrier(0)
; template <class Epi, class Sched>
; __device__ __forceinline__ void gemm_phase(LAS unsigned char* lds, const Gemm g, const Sched& S, const Epi& E) {
;     ...
;             PG8_BAR; PG8_WAIT_L(0); PG8_MMA(0, 1, At, B1); PG8_BAR;
;             PG8_LDA(At, 0, 1); PG8_STAGE(PG8_SA(0, 0), a2, voffA);
;             PG8_BAR; PG8_WAIT_L(0); PG8_MMA(1, 0, At, B0); PG8_BAR; PG8_SCHED;
;             PG8_STAGE(PG8_SB(0, 1), b2 + hstep, voffB);
;             PG8_WAIT_V(6); PG8_BAR; PG8_MMA(1, 1, At, B1); PG8_BAR;
;             PG8_LDB(B0, 1, 0); PG8_SCHED; PG8_LDA(At, 1, 0); PG8_STAGE(PG8_SA(0, 1), a2 + hstep, voffA);
;             PG8_WAIT_L(8); PG8_BAR; PG8_WAIT_L(0); PG8_MMA(0, 0, At, B0); PG8_BAR; PG8_SCHED;
	s_waitcnt lgkmcnt(0)
	s_setprio 1
	s_waitcnt lgkmcnt(0)
	v_mfma_f32_16x16x32_bf16 v[116:119], v[202:205], v[166:169], v[116:119]
	v_mfma_f32_16x16x32_bf16 v[112:115], v[210:213], v[166:169], v[112:115]
	v_mfma_f32_16x16x32_bf16 v[100:103], v[202:205], v[174:177], v[100:103]
	v_mfma_f32_16x16x32_bf16 v[96:99], v[210:213], v[174:177], v[96:99]
	v_mfma_f32_16x16x32_bf16 v[84:87], v[202:205], v[182:185], v[84:87]
	v_mfma_f32_16x16x32_bf16 v[80:83], v[210:213], v[182:185], v[80:83]
	v_mfma_f32_16x16x32_bf16 v[68:71], v[202:205], v[190:193], v[68:71]
	v_mfma_f32_16x16x32_bf16 v[64:67], v[210:213], v[190:193], v[64:67]
	v_mfma_f32_16x16x32_bf16 v[116:119], v[206:209], v[170:173], v[116:119]
	v_mfma_f32_16x16x32_bf16 v[112:115], v[214:217], v[170:173], v[112:115]
	v_mfma_f32_16x16x32_bf16 v[100:103], v[206:209], v[178:181], v[100:103]
	v_mfma_f32_16x16x32_bf16 v[96:99], v[214:217], v[178:181], v[96:99]
	v_mfma_f32_16x16x32_bf16 v[84:87], v[206:209], v[186:189], v[84:87]
	v_mfma_f32_16x16x32_bf16 v[80:83], v[214:217], v[186:189], v[80:83]
	v_mfma_f32_16x16x32_bf16 v[68:71], v[206:209], v[194:197], v[68:71]
	v_mfma_f32_16x16x32_bf16 v[64:67], v[214:217], v[194:197], v[64:67]
	s_setprio 0
	s_mov_b32 m0, s33
	v_lshl_add_u64 v[218:219], s[24:25], 0, v[128:129]
	s_barrier
	ds_read_b128 v[166:169], v150 offset:16384
	ds_read_b128 v[170:173], v150 offset:17408
	ds_read_b128 v[174:177], v150 offset:18432
	ds_read_b128 v[178:181], v150 offset:19456
	ds_read_b128 v[182:185], v150 offset:20480
	ds_read_b128 v[186:189], v150 offset:21504
	ds_read_b128 v[190:193], v150 offset:22528
	ds_read_b128 v[194:197], v150 offset:23552
	global_load_lds_dwordx4 v128, s[24:25]
	v_lshl_add_u64 v[220:221], s[24:25], 0, v[132:133]
	s_mov_b32 m0, s34
	s_nop 0
	global_load_lds_dwordx4 v132, s[24:25]
	s_barrier
	s_waitcnt lgkmcnt(0)
	s_setprio 1
	s_waitcnt lgkmcnt(0)
	v_mfma_f32_16x16x32_bf16 v[60:63], v[140:143], v[166:169], v[60:63]
	v_mfma_f32_16x16x32_bf16 v[56:59], v[158:161], v[166:169], v[56:59]
	v_mfma_f32_16x16x32_bf16 v[44:47], v[140:143], v[174:177], v[44:47]
	v_mfma_f32_16x16x32_bf16 v[40:43], v[158:161], v[174:177], v[40:43]
	v_mfma_f32_16x16x32_bf16 v[28:31], v[140:143], v[182:185], v[28:31]
	v_mfma_f32_16x16x32_bf16 v[24:27], v[158:161], v[182:185], v[24:27]
	v_mfma_f32_16x16x32_bf16 v[12:15], v[140:143], v[190:193], v[12:15]
	v_mfma_f32_16x16x32_bf16 v[8:11], v[158:161], v[190:193], v[8:11]
	v_mfma_f32_16x16x32_bf16 v[60:63], v[154:157], v[170:173], v[60:63]
	v_mfma_f32_16x16x32_bf16 v[56:59], v[162:165], v[170:173], v[56:59]
	v_mfma_f32_16x16x32_bf16 v[44:47], v[154:157], v[178:181], v[44:47]
	v_mfma_f32_16x16x32_bf16 v[40:43], v[162:165], v[178:181], v[40:43]
	v_mfma_f32_16x16x32_bf16 v[28:31], v[154:157], v[186:189], v[28:31]
	v_mfma_f32_16x16x32_bf16 v[24:27], v[162:165], v[186:189], v[24:27]
	v_mfma_f32_16x16x32_bf16 v[12:15], v[154:157], v[194:197], v[12:15]
	v_mfma_f32_16x16x32_bf16 v[8:11], v[162:165], v[194:197], v[8:11]
	s_setprio 0
	s_barrier
	s_add_u32 s62, s4, 0x40000
	s_addc_u32 s63, s5, 0
	s_add_i32 s64, s48, s31
	s_mov_b32 m0, s64
	s_nop 0
	global_load_lds_dwordx4 v130, s[62:63]
	s_add_i32 m0, s64, 0x2000
	s_nop 0
	global_load_lds_dwordx4 v134, s[62:63]
	s_add_u32 s24, s24, 0x40000
	s_addc_u32 s25, s25, 0
	s_mov_b32 m0, s35
	s_nop 0
	global_load_lds_dwordx4 v128, s[24:25]
	s_mov_b32 m0, s36
	s_nop 0
	global_load_lds_dwordx4 v132, s[24:25]
	s_waitcnt vmcnt(12)
	s_barrier
	s_setprio 1
	v_mfma_f32_16x16x32_bf16 v[52:55], v[202:205], v[166:169], v[52:55]
	v_mfma_f32_16x16x32_bf16 v[48:51], v[210:213], v[166:169], v[48:51]
	v_mfma_f32_16x16x32_bf16 v[36:39], v[202:205], v[174:177], v[36:39]
	v_mfma_f32_16x16x32_bf16 v[32:35], v[210:213], v[174:177], v[32:35]
	v_mfma_f32_16x16x32_bf16 v[20:23], v[202:205], v[182:185], v[20:23]
	v_mfma_f32_16x16x32_bf16 v[16:19], v[210:213], v[182:185], v[16:19]
	v_mfma_f32_16x16x32_bf16 v[4:7], v[202:205], v[190:193], v[4:7]
	v_mfma_f32_16x16x32_bf16 v[0:3], v[210:213], v[190:193], v[0:3]
	v_mfma_f32_16x16x32_bf16 v[52:55], v[206:209], v[170:173], v[52:55]
	v_mfma_f32_16x16x32_bf16 v[48:51], v[214:217], v[170:173], v[48:51]
	v_mfma_f32_16x16x32_bf16 v[36:39], v[206:209], v[178:181], v[36:39]
	v_mfma_f32_16x16x32_bf16 v[32:35], v[214:217], v[178:181], v[32:35]
	v_mfma_f32_16x16x32_bf16 v[20:23], v[206:209], v[186:189], v[20:23]
	v_mfma_f32_16x16x32_bf16 v[16:19], v[214:217], v[186:189], v[16:19]
	v_mfma_f32_16x16x32_bf16 v[4:7], v[206:209], v[194:197], v[4:7]
	v_mfma_f32_16x16x32_bf16 v[0:3], v[214:217], v[194:197], v[0:3]
	s_setprio 0
	s_add_i32 s62, 0, 0x18000
	v_add_u32_e32 v162, s62, v148
	s_barrier
	ds_read_b128 v[140:143], v162
	ds_read_b128 v[154:157], v162 offset:1024
	ds_read_b128 v[158:161], v162 offset:2048
	ds_read_b128 v[162:165], v162 offset:3072
	ds_read_b128 v[166:169], v150 offset:32768
	ds_read_b128 v[170:173], v150 offset:33792
	ds_read_b128 v[174:177], v150 offset:34816
	ds_read_b128 v[178:181], v150 offset:35840
	ds_read_b128 v[182:185], v150 offset:36864
	ds_read_b128 v[186:189], v150 offset:37888
	ds_read_b128 v[190:193], v150 offset:38912
	ds_read_b128 v[194:197], v150 offset:39936
	s_waitcnt vmcnt(10)
	s_barrier
; #define PG8_STAGE(bufoff, gbase, voff) do { _Pragma("unroll") for (int _i = 0; _i < 2; ++_i) \
;         __builtin_amdgcn_global_load_lds((const unsigned*)((const char*)(gbase) + (voff)[_i]), (LAS unsigned*)(lds + (bufoff) + ldsw + _i * 8192), 16, 0, 0); } while (0)
; #define PG8_LDA(dst, b, h) do { _Pragma("unroll") for (int m = 0; m < 4; ++m) _Pragma("unroll") for (int k = 0; k < 2; ++k) dst[m][k] = *(const LAS bf16x8*)(lds + PG8_SA(b, h) + aoff + m * 2048 + k * 1024); } while (0)
; #define PG8_LDB(dst, b, h) do { _Pragma("unroll") for (int n = 0; n < 2; ++n) _Pragma("unroll") for (int k = 0; k < 2; ++k) dst[n][k] = *(const LAS bf16x8*)(lds + PG8_SB(b, h) + boff + n * 2048 + k * 1024); } while (0)
; #define PG8_MMA(ai, bj, At, Bt) do { __builtin_amdgcn_s_setprio(1); _Pragma("unroll") for (int m = 0; m < 4; ++m) _Pragma("unroll") for (int n = 0; n < 2; ++n) _Pragma("unroll") for (int k = 0; k < 2; ++k) \
;         acc[ai][bj][m][n] = __builtin_amdgcn_mfma_f32_16x16x32_bf16(Bt[n][k], At[m][k], acc[ai][bj][m][n], 0, 0, 0); __builtin_amdgcn_s_setprio(0); } while (0)
; #define PG8_WAIT_V(n) asm volatile("s_waitcnt vmcnt(" #n ")" ::: "memory")
; #define PG8_WAIT_L(n) asm volatile("s_waitcnt lgkmcnt(" #n ")" ::: "memory")
; #define PG8_BAR __builtin_amdgcn_s_barrier()
; #define PG8_SCHED __builtin_amdgcn_sched_barrier(0)
; template <class Epi, class Sched>
; __device__ __forceinline__ void gemm_phase(LAS unsigned char* lds, const Gemm g, const Sched& S, const Epi& E) {
;     ...
;             PG8_WAIT_L(8); PG8_BAR; PG8_WAIT_L(0); PG8_MMA(0, 0, At, B0); PG8_BAR; PG8_SCHED;
;             PG8_LDB(B1, 1, 1); PG8_STAGE(PG8_SB(1, 0), b3, voffB);
;             PG8_BAR; PG8_WAIT_L(0); PG8_MMA(0, 1, At, B1); PG8_BAR;
;             PG8_LDA(At, 1, 1); PG8_STAGE(PG8_SA(1, 0), a3, voffA);
;             PG8_BAR; PG8_WAIT_L(0); PG8_MMA(1, 0, At, B0); PG8_BAR; PG8_SCHED;
;             PG8_STAGE(PG8_SB(1, 1), b3 + hstep, voffB);
;             PG8_WAIT_V(6); PG8_BAR; PG8_MMA(1, 1, At, B1); PG8_BAR;
	s_waitcnt lgkmcnt(0)
	s_setprio 1
	s_waitcnt lgkmcnt(0)
	v_mfma_f32_16x16x32_bf16 v[124:127], v[140:143], v[166:169], v[124:127]
	v_mfma_f32_16x16x32_bf16 v[120:123], v[158:161], v[166:169], v[120:123]
	v_mfma_f32_16x16x32_bf16 v[108:111], v[140:143], v[174:177], v[108:111]
	v_mfma_f32_16x16x32_bf16 v[104:107], v[158:161], v[174:177], v[104:107]
	v_mfma_f32_16x16x32_bf16 v[92:95], v[140:143], v[182:185], v[92:95]
	v_mfma_f32_16x16x32_bf16 v[88:91], v[158:161], v[182:185], v[88:91]
	v_mfma_f32_16x16x32_bf16 v[76:79], v[140:143], v[190:193], v[76:79]
	v_mfma_f32_16x16x32_bf16 v[72:75], v[158:161], v[190:193], v[72:75]
	v_mfma_f32_16x16x32_bf16 v[124:127], v[154:157], v[170:173], v[124:127]
	v_mfma_f32_16x16x32_bf16 v[120:123], v[162:165], v[170:173], v[120:123]
	v_mfma_f32_16x16x32_bf16 v[108:111], v[154:157], v[178:181], v[108:111]
	v_mfma_f32_16x16x32_bf16 v[104:107], v[162:165], v[178:181], v[104:107]
	v_mfma_f32_16x16x32_bf16 v[92:95], v[154:157], v[186:189], v[92:95]
	v_mfma_f32_16x16x32_bf16 v[88:91], v[162:165], v[186:189], v[88:91]
	v_mfma_f32_16x16x32_bf16 v[76:79], v[154:157], v[194:197], v[76:79]
	v_mfma_f32_16x16x32_bf16 v[72:75], v[162:165], v[194:197], v[72:75]
	s_setprio 0
	s_barrier
	s_add_i32 s24, 0, 0x1c000
	s_add_i32 s25, s62, s31
	v_add_u32_e32 v214, s24, v148
	s_add_u32 s0, s4, 0x80
	s_addc_u32 s1, s5, 0
	s_mov_b32 m0, s25
	ds_read_b128 v[202:205], v214
	ds_read_b128 v[206:209], v214 offset:1024
	ds_read_b128 v[210:213], v214 offset:2048
	ds_read_b128 v[214:217], v214 offset:3072
	global_load_lds_dwordx4 v130, s[0:1]
	s_add_i32 m0, s25, 0x2000
	s_nop 0
	global_load_lds_dwordx4 v134, s[0:1]
	s_waitcnt vmcnt(10)
	s_barrier
	s_waitcnt lgkmcnt(0)
	s_setprio 1
	s_waitcnt lgkmcnt(0)
	v_mfma_f32_16x16x32_bf16 v[116:119], v[202:205], v[166:169], v[116:119]
	v_mfma_f32_16x16x32_bf16 v[112:115], v[210:213], v[166:169], v[112:115]
	v_mfma_f32_16x16x32_bf16 v[100:103], v[202:205], v[174:177], v[100:103]
	v_mfma_f32_16x16x32_bf16 v[96:99], v[210:213], v[174:177], v[96:99]
	v_mfma_f32_16x16x32_bf16 v[84:87], v[202:205], v[182:185], v[84:87]
	v_mfma_f32_16x16x32_bf16 v[80:83], v[210:213], v[182:185], v[80:83]
	v_mfma_f32_16x16x32_bf16 v[68:71], v[202:205], v[190:193], v[68:71]
	v_mfma_f32_16x16x32_bf16 v[64:67], v[210:213], v[190:193], v[64:67]
	v_mfma_f32_16x16x32_bf16 v[116:119], v[206:209], v[170:173], v[116:119]
	v_mfma_f32_16x16x32_bf16 v[112:115], v[214:217], v[170:173], v[112:115]
	v_mfma_f32_16x16x32_bf16 v[100:103], v[206:209], v[178:181], v[100:103]
	v_mfma_f32_16x16x32_bf16 v[96:99], v[214:217], v[178:181], v[96:99]
	v_mfma_f32_16x16x32_bf16 v[84:87], v[206:209], v[186:189], v[84:87]
	v_mfma_f32_16x16x32_bf16 v[80:83], v[214:217], v[186:189], v[80:83]
	v_mfma_f32_16x16x32_bf16 v[68:71], v[206:209], v[194:197], v[68:71]
	v_mfma_f32_16x16x32_bf16 v[64:67], v[214:217], v[194:197], v[64:67]
	s_setprio 0
	s_mov_b32 m0, s44
	s_mov_b64 s[0:1], 0x80
	v_lshl_add_u64 v[144:145], v[218:219], 0, s[0:1]
	s_barrier
	ds_read_b128 v[166:169], v150 offset:49152
	ds_read_b128 v[170:173], v150 offset:50176
	ds_read_b128 v[174:177], v150 offset:51200
	ds_read_b128 v[178:181], v150 offset:52224
	ds_read_b128 v[182:185], v150 offset:53248
	ds_read_b128 v[186:189], v150 offset:54272
	ds_read_b128 v[190:193], v150 offset:55296
	ds_read_b128 v[194:197], v150 offset:56320
	global_load_lds_dwordx4 v[144:145], off
	v_lshl_add_u64 v[144:145], v[220:221], 0, s[0:1]
	s_mov_b32 m0, s45
	s_nop 0
	global_load_lds_dwordx4 v[144:145], off
	s_barrier
	s_waitcnt lgkmcnt(0)
	s_setprio 1
	s_waitcnt lgkmcnt(0)
	v_mfma_f32_16x16x32_bf16 v[60:63], v[140:143], v[166:169], v[60:63]
	v_mfma_f32_16x16x32_bf16 v[56:59], v[158:161], v[166:169], v[56:59]
	v_mfma_f32_16x16x32_bf16 v[44:47], v[140:143], v[174:177], v[44:47]
	v_mfma_f32_16x16x32_bf16 v[40:43], v[158:161], v[174:177], v[40:43]
	v_mfma_f32_16x16x32_bf16 v[28:31], v[140:143], v[182:185], v[28:31]
	v_mfma_f32_16x16x32_bf16 v[24:27], v[158:161], v[182:185], v[24:27]
	v_mfma_f32_16x16x32_bf16 v[12:15], v[140:143], v[190:193], v[12:15]
	v_mfma_f32_16x16x32_bf16 v[8:11], v[158:161], v[190:193], v[8:11]
	v_mfma_f32_16x16x32_bf16 v[60:63], v[154:157], v[170:173], v[60:63]
	v_mfma_f32_16x16x32_bf16 v[56:59], v[162:165], v[170:173], v[56:59]
	v_mfma_f32_16x16x32_bf16 v[44:47], v[154:157], v[178:181], v[44:47]
	v_mfma_f32_16x16x32_bf16 v[40:43], v[162:165], v[178:181], v[40:43]
	v_mfma_f32_16x16x32_bf16 v[28:31], v[154:157], v[186:189], v[28:31]
	v_mfma_f32_16x16x32_bf16 v[24:27], v[162:165], v[186:189], v[24:27]
	v_mfma_f32_16x16x32_bf16 v[12:15], v[154:157], v[194:197], v[12:15]
	v_mfma_f32_16x16x32_bf16 v[8:11], v[162:165], v[194:197], v[8:11]
	s_setprio 0
	s_barrier
	s_add_u32 s4, s4, 0x40080
	s_addc_u32 s5, s5, 0
	s_add_i32 s24, s24, s31
	s_mov_b32 m0, s24
	s_nop 0
	global_load_lds_dwordx4 v130, s[4:5]
	s_add_i32 m0, s24, 0x2000
	s_nop 0
	global_load_lds_dwordx4 v134, s[4:5]
	s_waitcnt vmcnt(10)
	s_barrier
	s_setprio 1
	v_mfma_f32_16x16x32_bf16 v[52:55], v[202:205], v[166:169], v[52:55]
	v_mfma_f32_16x16x32_bf16 v[48:51], v[210:213], v[166:169], v[48:51]
	v_mfma_f32_16x16x32_bf16 v[36:39], v[202:205], v[174:177], v[36:39]
	v_mfma_f32_16x16x32_bf16 v[32:35], v[210:213], v[174:177], v[32:35]
	v_mfma_f32_16x16x32_bf16 v[20:23], v[202:205], v[182:185], v[20:23]
	v_mfma_f32_16x16x32_bf16 v[16:19], v[210:213], v[182:185], v[16:19]
	v_mfma_f32_16x16x32_bf16 v[4:7], v[202:205], v[190:193], v[4:7]
	v_mfma_f32_16x16x32_bf16 v[0:3], v[210:213], v[190:193], v[0:3]
	v_mfma_f32_16x16x32_bf16 v[52:55], v[206:209], v[170:173], v[52:55]
	v_mfma_f32_16x16x32_bf16 v[48:51], v[214:217], v[170:173], v[48:51]
	v_mfma_f32_16x16x32_bf16 v[36:39], v[206:209], v[178:181], v[36:39]
	v_mfma_f32_16x16x32_bf16 v[32:35], v[214:217], v[178:181], v[32:35]
	v_mfma_f32_16x16x32_bf16 v[20:23], v[206:209], v[186:189], v[20:23]
	v_mfma_f32_16x16x32_bf16 v[16:19], v[214:217], v[186:189], v[16:19]
	v_mfma_f32_16x16x32_bf16 v[4:7], v[206:209], v[194:197], v[4:7]
	v_mfma_f32_16x16x32_bf16 v[0:3], v[214:217], v[194:197], v[0:3]
	s_setprio 0
	s_add_i32 s61, s61, 2
	s_add_u32 s2, s2, 0x100
	s_addc_u32 s3, s3, 0
	s_add_u32 s59, s59, 0x100
	s_addc_u32 s60, s60, 0
	s_cmp_gt_u32 s61, 13
	s_barrier
;     __device__ __forceinline__ void operator()(const AccT& acc, const Unit& u, int wr, int wc, int fr, int fq) const {
;     ...
;         const int rbase = wr * 64 + fr;
;         const int tb = u.pn * 256 + wc * 32 + 8 * fq;
;         const int o0 = wc * 32 + 8 * fq;
;         const int j = fr & 3; const float sgn = ((fr >> 2) & 1) ? 1.0f : -1.0f;
; #pragma unroll
;         for (int ai = 0; ai < 2; ++ai) {
;             const int hh = 2 * ai + wr;
;             const float l2f = lgd[hh] * 1.4426950408889634f, l2b = lgd[4 + hh] * 1.4426950408889634f;
;             const float zf0 = exp2f((float)(127 - o0) * l2f), zfs = exp2f(-l2f), zb0 = exp2f((float)o0 * l2b), zbs = exp2f(l2b);
; #pragma unroll
;             for (int m = 0; m < 4; ++m) {
;                 const int r = rbase + ai * 128 + m * 16;
;                 const int d = 4 * (2 * m + (fr >> 3)) + j;
; #pragma unroll
;                 for (int bj = 0; bj < 2; ++bj) {
;                     const int t0 = tb + bj * 128;
;                     float v[8];
; #pragma unroll
;                     for (int jj = 0; jj < 4; ++jj) { v[jj] = acc[ai][bj][m][0][jj]; v[4 + jj] = acc[ai][bj][m][1][jj]; }
;                     if constexpr (ROPE) {
;                         const int t = t0 & 2047;
; #pragma unroll
;                         for (int hf = 0; hf < 2; ++hf) {
;                             f32x4 cs, sn;
;                             if (m < 2) { const float c1 = ropeA[(t >> 6) * 16 + d], s1 = ropeA[1024 + (t >> 6) * 16 + d]; cs = (f32x4){c1, c1, c1, c1}; sn = (f32x4){s1, s1, s1, s1}; }
;                             else { const float* cb = ropeA + 2048 + (d - 16) * 64 + (t & 63) + 4 * hf; cs = *(const f32x4*)(cb); sn = *(const f32x4*)(cb + 1024); }
; #pragma unroll
;                             for (int jj = 0; jj < 4; ++jj) { const float pr = __shfl_xor(v[4 * hf + jj], 4); v[4 * hf + jj] = v[4 * hf + jj] * cs[jj] + sgn * pr * sn[jj]; }
;                             __builtin_amdgcn_sched_barrier(0);
;                         }
;                     }
;                     float zf[8], zb[8]; zf[0] = zf0; zb[0] = zb0;
; #pragma unroll
;                     for (int jj = 1; jj < 8; ++jj) { zf[jj] = zf[jj - 1] * zfs; zb[jj] = zb[jj - 1] * zbs; }
;                     u32x4 wf, wb;
	s_cbranch_scc0 .LBB0_693
	v_mov_b32_e32 v141, v147
	v_mov_b32_e32 v140, v146
	global_load_dword v156, v131, s[6:7]
	global_load_dword v157, v131, s[6:7] offset:16
	s_lshl_b32 s2, s56, 8
	s_or_b32 s2, s2, s43
	v_add_u32_e32 v140, s42, v140
	v_lshlrev_b32_e32 v141, 3, v141
	v_add_u32_e32 v142, s2, v141
	v_add_u32_e32 v143, s43, v141
	v_ashrrev_i32_e32 v141, 31, v140
	v_sub_u32_e32 v144, 0x7f, v143
	v_lshlrev_b64 v[140:141], 14, v[140:141]
	v_cvt_f32_i32_e32 v154, v143
	v_ashrrev_i32_e32 v143, 31, v142
	v_cvt_f32_i32_e32 v155, v144
	v_lshl_add_u64 v[140:141], s[70:71], 0, v[140:141]
	s_mov_b32 s3, 0x400000
	v_lshl_add_u64 v[140:141], v[142:143], 1, v[140:141]
	v_add_co_u32_e32 v144, vcc, s3, v140
	s_mov_b64 s[4:5], 0x400000
	s_nop 0
	v_addc_co_u32_e32 v145, vcc, 0, v141, vcc
	v_lshl_add_u64 v[142:143], v[140:141], 0, s[4:5]
	s_waitcnt vmcnt(0)
	v_mul_f32_e32 v158, 0x3fb8aa3b, v156
	v_mul_f32_e32 v159, 0x3fb8aa3b, v157
	v_mul_f32_e32 v160, v158, v155
	v_cmp_lt_f32_e32 vcc, s51, v158
	v_mul_f32_e32 v162, v159, v154
	v_cmp_gt_f32_e64 s[2:3], s49, v159
	v_cndmask_b32_e32 v161, 0, v153, vcc
	v_cmp_gt_f32_e64 s[4:5], s49, v160
	v_cndmask_b32_e64 v163, 0, v153, s[2:3]
	s_and_b64 s[24:25], vcc, exec
	v_cmp_gt_f32_e32 vcc, s49, v162
	v_fmac_f32_e32 v163, 0x3fb8aa3b, v157
	v_cndmask_b32_e64 v157, 0, v153, s[4:5]
	v_cndmask_b32_e32 v162, 0, v153, vcc
	v_fmac_f32_e32 v161, 0xbfb8aa3b, v156
	v_fmac_f32_e32 v157, v158, v155
	v_fmac_f32_e32 v162, v159, v154
	v_exp_f32_e32 v161, v161
	v_exp_f32_e32 v163, v163
	v_exp_f32_e32 v157, v157
	v_exp_f32_e32 v158, v162
	v_cndmask_b32_e64 v160, 0, v152, s[4:5]
	s_cselect_b32 s4, 0xffffffc0, 0
	s_and_b64 s[2:3], s[2:3], exec
	v_cndmask_b32_e32 v156, 0, v152, vcc
	s_cselect_b32 s2, 0xffffffc0, 0
	v_ldexp_f32 v161, v161, s4
	v_ldexp_f32 v162, v163, s2
	v_ldexp_f32 v163, v157, v160
	v_ldexp_f32 v156, v158, v156
	v_mul_f32_e32 v164, v161, v163
	v_mul_f32_e32 v157, v162, v156
	v_mul_f32_e32 v158, v124, v163
	v_mul_f32_e32 v165, v124, v156
	v_mul_f32_e32 v166, v161, v164
	v_mul_f32_e32 v124, v162, v157
	v_mul_f32_e32 v159, v125, v164
	v_mul_f32_e32 v167, v125, v157
	v_mul_f32_e32 v168, v161, v166
	v_mul_f32_e32 v125, v162, v124
	v_cvt_pk_bf16_f32 v158, v158, v159
	v_mul_f32_e32 v159, v126, v166
	v_mul_f32_e32 v169, v126, v124
	v_mul_f32_e32 v170, v161, v168
	v_mul_f32_e32 v126, v162, v125
	v_mul_f32_e32 v171, v161, v170
	v_mul_f32_e32 v172, v162, v126
	v_mul_f32_e32 v160, v127, v168
	v_mul_f32_e32 v174, v161, v171
	v_mul_f32_e32 v175, v162, v172
	v_cvt_pk_bf16_f32 v159, v159, v160
	v_mul_f32_e32 v160, v120, v170
	v_mul_f32_e32 v173, v120, v126
	v_mul_f32_e32 v120, v121, v171
	v_mul_f32_e32 v177, v161, v174
	v_mul_f32_e32 v162, v162, v175
	v_mul_f32_e32 v176, v121, v172
	v_cvt_pk_bf16_f32 v160, v160, v120
	v_mul_f32_e32 v120, v122, v174
	v_mul_f32_e32 v121, v123, v177
	v_mul_f32_e32 v123, v123, v162
	v_cvt_pk_bf16_f32 v161, v120, v121
	v_mul_f32_e32 v127, v127, v125
	v_mul_f32_e32 v178, v122, v175
	v_cvt_pk_bf16_f32 v120, v165, v167
	v_cvt_pk_bf16_f32 v121, v169, v127
	v_cvt_pk_bf16_f32 v122, v173, v176
	v_cvt_pk_bf16_f32 v123, v178, v123
	global_store_dwordx4 v[140:141], v[158:161], off
	global_store_dwordx4 v[144:145], v[120:123], off
	s_nop 1
	v_mul_f32_e32 v120, v116, v163
	v_mul_f32_e32 v121, v117, v164
	v_cvt_pk_bf16_f32 v120, v120, v121
	v_mul_f32_e32 v121, v118, v166
	v_mul_f32_e32 v122, v119, v168
	v_cvt_pk_bf16_f32 v121, v121, v122
	v_mul_f32_e32 v122, v112, v170
	v_mul_f32_e32 v123, v113, v171
	v_cvt_pk_bf16_f32 v122, v122, v123
	v_mul_f32_e32 v123, v114, v174
	v_mul_f32_e32 v116, v116, v156
	v_mul_f32_e32 v117, v117, v157
	v_mul_f32_e32 v127, v115, v177
	v_cvt_pk_bf16_f32 v123, v123, v127
	v_cvt_pk_bf16_f32 v116, v116, v117
	v_mul_f32_e32 v117, v118, v124
	v_mul_f32_e32 v118, v119, v125
	v_mul_f32_e32 v112, v112, v126
	v_mul_f32_e32 v113, v113, v172
	v_cvt_pk_bf16_f32 v117, v117, v118
	v_cvt_pk_bf16_f32 v118, v112, v113
	v_mul_f32_e32 v112, v114, v175
	v_mul_f32_e32 v113, v115, v162
	v_cvt_pk_bf16_f32 v119, v112, v113
	global_store_dwordx4 v[140:141], v[120:123], off offset:256
	global_store_dwordx4 v[142:143], v[116:119], off offset:256
	v_mul_f32_e32 v112, v108, v163
	v_mul_f32_e32 v113, v109, v164
	v_cvt_pk_bf16_f32 v112, v112, v113
	v_mul_f32_e32 v113, v110, v166
	v_mul_f32_e32 v114, v111, v168
	v_cvt_pk_bf16_f32 v113, v113, v114
	v_mul_f32_e32 v114, v104, v170
	v_mul_f32_e32 v115, v105, v171
	v_cvt_pk_bf16_f32 v114, v114, v115
	v_mul_f32_e32 v115, v106, v174
	v_mul_f32_e32 v108, v108, v156
	v_mul_f32_e32 v109, v109, v157
	v_mul_f32_e32 v116, v107, v177
	v_cvt_pk_bf16_f32 v115, v115, v116
	v_cvt_pk_bf16_f32 v108, v108, v109
	v_mul_f32_e32 v109, v110, v124
	v_mul_f32_e32 v110, v111, v125
	v_mul_f32_e32 v104, v104, v126
	s_mov_b64 s[2:3], 0x40000
	v_cvt_pk_bf16_f32 v109, v109, v110
	v_mul_f32_e32 v105, v105, v172
	v_cvt_pk_bf16_f32 v110, v104, v105
	v_mul_f32_e32 v104, v106, v175
	v_lshl_add_u64 v[116:117], v[140:141], 0, s[2:3]
	s_mov_b32 s2, 0x40000
	v_mul_f32_e32 v105, v107, v162
	v_cvt_pk_bf16_f32 v111, v104, v105
	v_add_co_u32_e32 v104, vcc, s2, v140
	s_mov_b64 s[2:3], 0x440000
	s_nop 0
	v_addc_co_u32_e32 v105, vcc, 0, v141, vcc
	global_store_dwordx4 v[104:105], v[112:115], off
	s_nop 1
	v_lshl_add_u64 v[112:113], v[140:141], 0, s[2:3]
	s_mov_b32 s2, 0x440000
	v_add_co_u32_e32 v104, vcc, s2, v140
	s_nop 1
	v_addc_co_u32_e32 v105, vcc, 0, v141, vcc
	global_store_dwordx4 v[104:105], v[108:111], off
	v_mul_f32_e32 v104, v100, v163
	v_mul_f32_e32 v105, v101, v164
	v_cvt_pk_bf16_f32 v104, v104, v105
	v_mul_f32_e32 v105, v102, v166
	v_mul_f32_e32 v106, v103, v168
	v_cvt_pk_bf16_f32 v105, v105, v106
;     __device__ __forceinline__ void operator()(const AccT& acc, const Unit& u, int wr, int wc, int fr, int fq) const {
;     ...
;             for (int m = 0; m < 4; ++m) {
;                 const int r = rbase + ai * 128 + m * 16;
;                 const int d = 4 * (2 * m + (fr >> 3)) + j;
; #pragma unroll
;                 for (int bj = 0; bj < 2; ++bj) {
;                     const int t0 = tb + bj * 128;
;                     float v[8];
; #pragma unroll
;                     for (int jj = 0; jj < 4; ++jj) { v[jj] = acc[ai][bj][m][0][jj]; v[4 + jj] = acc[ai][bj][m][1][jj]; }
;                     if constexpr (ROPE) {
;                         const int t = t0 & 2047;
; #pragma unroll
;                         for (int hf = 0; hf < 2; ++hf) {
;                             f32x4 cs, sn;
;                             if (m < 2) { const float c1 = ropeA[(t >> 6) * 16 + d], s1 = ropeA[1024 + (t >> 6) * 16 + d]; cs = (f32x4){c1, c1, c1, c1}; sn = (f32x4){s1, s1, s1, s1}; }
;                             else { const float* cb = ropeA + 2048 + (d - 16) * 64 + (t & 63) + 4 * hf; cs = *(const f32x4*)(cb); sn = *(const f32x4*)(cb + 1024); }
; #pragma unroll
;                             for (int jj = 0; jj < 4; ++jj) { const float pr = __shfl_xor(v[4 * hf + jj], 4); v[4 * hf + jj] = v[4 * hf + jj] * cs[jj] + sgn * pr * sn[jj]; }
;                             __builtin_amdgcn_sched_barrier(0);
;                         }
;                     }
;                     float zf[8], zb[8]; zf[0] = zf0; zb[0] = zb0;
; #pragma unroll
;                     for (int jj = 1; jj < 8; ++jj) { zf[jj] = zf[jj - 1] * zfs; zb[jj] = zb[jj - 1] * zbs; }
;                     u32x4 wf, wb;
;                     wf.x = cvt_pk_bf16(v[0] * zf[0], v[1] * zf[1]); wf.y = cvt_pk_bf16(v[2] * zf[2], v[3] * zf[3]); wf.z = cvt_pk_bf16(v[4] * zf[4], v[5] * zf[5]); wf.w = cvt_pk_bf16(v[6] * zf[6], v[7] * zf[7]);
;                     wb.x = cvt_pk_bf16(v[0] * zb[0], v[1] * zb[1]); wb.y = cvt_pk_bf16(v[2] * zb[2], v[3] * zb[3]); wb.z = cvt_pk_bf16(v[4] * zb[4], v[5] * zb[5]); wb.w = cvt_pk_bf16(v[6] * zb[6], v[7] * zb[7]);
;                     *(u32x4*)(KTZ + (size_t)r * NT + t0) = wf;
;                     *(u32x4*)(KTZ + (size_t)(256 + r) * NT + t0) = wb;
	v_mul_f32_e32 v106, v96, v170
	v_mul_f32_e32 v107, v97, v171
	v_cvt_pk_bf16_f32 v106, v106, v107
	v_mul_f32_e32 v107, v98, v174
	v_mul_f32_e32 v100, v100, v156
	v_mul_f32_e32 v101, v101, v157
	v_mul_f32_e32 v108, v99, v177
	v_cvt_pk_bf16_f32 v107, v107, v108
	v_cvt_pk_bf16_f32 v100, v100, v101
	v_mul_f32_e32 v101, v102, v124
	v_mul_f32_e32 v102, v103, v125
	v_mul_f32_e32 v96, v96, v126
	v_mul_f32_e32 v97, v97, v172
	v_cvt_pk_bf16_f32 v101, v101, v102
	v_cvt_pk_bf16_f32 v102, v96, v97
	v_mul_f32_e32 v96, v98, v175
	v_mul_f32_e32 v97, v99, v162
	v_cvt_pk_bf16_f32 v103, v96, v97
	global_store_dwordx4 v[116:117], v[104:107], off offset:256
	global_store_dwordx4 v[112:113], v[100:103], off offset:256
	v_mul_f32_e32 v96, v92, v163
	v_mul_f32_e32 v97, v93, v164
	v_cvt_pk_bf16_f32 v96, v96, v97
	v_mul_f32_e32 v97, v94, v166
	v_mul_f32_e32 v98, v95, v168
	v_cvt_pk_bf16_f32 v97, v97, v98
	v_mul_f32_e32 v98, v88, v170
	v_mul_f32_e32 v99, v89, v171
	v_cvt_pk_bf16_f32 v98, v98, v99
	v_mul_f32_e32 v99, v90, v174
	v_mul_f32_e32 v92, v92, v156
	v_mul_f32_e32 v93, v93, v157
	v_mul_f32_e32 v100, v91, v177
	v_cvt_pk_bf16_f32 v99, v99, v100
	v_cvt_pk_bf16_f32 v92, v92, v93
	v_mul_f32_e32 v93, v94, v124
	v_mul_f32_e32 v94, v95, v125
	v_mul_f32_e32 v88, v88, v126
	s_mov_b64 s[2:3], 0x80000
	v_cvt_pk_bf16_f32 v93, v93, v94
	v_mul_f32_e32 v89, v89, v172
	v_cvt_pk_bf16_f32 v94, v88, v89
	v_mul_f32_e32 v88, v90, v175
	v_lshl_add_u64 v[100:101], v[140:141], 0, s[2:3]
	s_mov_b32 s2, 0x80000
	v_mul_f32_e32 v89, v91, v162
	v_cvt_pk_bf16_f32 v95, v88, v89
	v_add_co_u32_e32 v88, vcc, s2, v140
	s_mov_b64 s[2:3], 0x480000
	s_nop 0
	v_addc_co_u32_e32 v89, vcc, 0, v141, vcc
	global_store_dwordx4 v[88:89], v[96:99], off
	s_nop 1
	v_lshl_add_u64 v[96:97], v[140:141], 0, s[2:3]
	s_mov_b32 s2, 0x480000
	v_add_co_u32_e32 v88, vcc, s2, v140
	s_nop 1
	v_addc_co_u32_e32 v89, vcc, 0, v141, vcc
	global_store_dwordx4 v[88:89], v[92:95], off
	v_mul_f32_e32 v88, v84, v163
	v_mul_f32_e32 v89, v85, v164
	v_cvt_pk_bf16_f32 v88, v88, v89
	v_mul_f32_e32 v89, v86, v166
	v_mul_f32_e32 v90, v87, v168
	v_cvt_pk_bf16_f32 v89, v89, v90
	v_mul_f32_e32 v90, v80, v170
	v_mul_f32_e32 v91, v81, v171
	v_cvt_pk_bf16_f32 v90, v90, v91
	v_mul_f32_e32 v91, v82, v174
	v_mul_f32_e32 v84, v84, v156
	v_mul_f32_e32 v85, v85, v157
	v_mul_f32_e32 v92, v83, v177
	v_cvt_pk_bf16_f32 v91, v91, v92
	v_cvt_pk_bf16_f32 v84, v84, v85
	v_mul_f32_e32 v85, v86, v124
	v_mul_f32_e32 v86, v87, v125
	v_mul_f32_e32 v80, v80, v126
	v_mul_f32_e32 v81, v81, v172
	v_cvt_pk_bf16_f32 v85, v85, v86
	v_cvt_pk_bf16_f32 v86, v80, v81
	v_mul_f32_e32 v80, v82, v175
	v_mul_f32_e32 v81, v83, v162
	v_cvt_pk_bf16_f32 v87, v80, v81
	global_store_dwordx4 v[100:101], v[88:91], off offset:256
	global_store_dwordx4 v[96:97], v[84:87], off offset:256
	v_mul_f32_e32 v80, v76, v163
	v_mul_f32_e32 v81, v77, v164
	v_cvt_pk_bf16_f32 v80, v80, v81
	v_mul_f32_e32 v81, v78, v166
	v_mul_f32_e32 v82, v79, v168
	v_cvt_pk_bf16_f32 v81, v81, v82
	v_mul_f32_e32 v82, v72, v170
	v_mul_f32_e32 v83, v73, v171
	v_cvt_pk_bf16_f32 v82, v82, v83
	v_mul_f32_e32 v83, v74, v174
	v_mul_f32_e32 v76, v76, v156
	v_mul_f32_e32 v77, v77, v157
	v_mul_f32_e32 v84, v75, v177
	v_cvt_pk_bf16_f32 v83, v83, v84
	v_cvt_pk_bf16_f32 v76, v76, v77
	v_mul_f32_e32 v77, v78, v124
	v_mul_f32_e32 v78, v79, v125
	v_mul_f32_e32 v72, v72, v126
	s_mov_b64 s[2:3], 0xc0000
	v_cvt_pk_bf16_f32 v77, v77, v78
	v_mul_f32_e32 v73, v73, v172
	v_cvt_pk_bf16_f32 v78, v72, v73
	v_mul_f32_e32 v72, v74, v175
	v_lshl_add_u64 v[84:85], v[140:141], 0, s[2:3]
	s_mov_b32 s2, 0xc0000
	v_mul_f32_e32 v73, v75, v162
	v_cvt_pk_bf16_f32 v79, v72, v73
	v_add_co_u32_e32 v72, vcc, s2, v140
	s_mov_b64 s[2:3], 0x4c0000
	s_nop 0
	v_addc_co_u32_e32 v73, vcc, 0, v141, vcc
	global_store_dwordx4 v[72:73], v[80:83], off
	s_nop 1
	v_lshl_add_u64 v[80:81], v[140:141], 0, s[2:3]
	s_mov_b32 s2, 0x4c0000
	v_add_co_u32_e32 v72, vcc, s2, v140
	s_nop 1
	v_addc_co_u32_e32 v73, vcc, 0, v141, vcc
	global_store_dwordx4 v[72:73], v[76:79], off
	v_mul_f32_e32 v72, v68, v163
	v_mul_f32_e32 v73, v69, v164
	v_cvt_pk_bf16_f32 v72, v72, v73
	v_mul_f32_e32 v73, v70, v166
	v_mul_f32_e32 v74, v71, v168
	v_cvt_pk_bf16_f32 v73, v73, v74
	v_mul_f32_e32 v74, v64, v170
	v_mul_f32_e32 v75, v65, v171
	v_cvt_pk_bf16_f32 v74, v74, v75
	v_mul_f32_e32 v75, v66, v174
	v_mul_f32_e32 v68, v68, v156
	v_mul_f32_e32 v69, v69, v157
	v_mul_f32_e32 v76, v67, v177
	v_cvt_pk_bf16_f32 v75, v75, v76
	v_cvt_pk_bf16_f32 v68, v68, v69
	v_mul_f32_e32 v69, v70, v124
	v_mul_f32_e32 v70, v71, v125
	v_mul_f32_e32 v64, v64, v126
	v_mul_f32_e32 v65, v65, v172
	v_cvt_pk_bf16_f32 v69, v69, v70
	v_cvt_pk_bf16_f32 v70, v64, v65
	v_mul_f32_e32 v64, v66, v175
	v_mul_f32_e32 v65, v67, v162
	v_cvt_pk_bf16_f32 v71, v64, v65
	global_store_dwordx4 v[84:85], v[72:75], off offset:256
	global_store_dwordx4 v[80:81], v[68:71], off offset:256
	global_load_dword v70, v131, s[6:7] offset:8
	s_nop 0
	global_load_dword v71, v131, s[6:7] offset:24
	s_mov_b32 s17, 0x200000
	v_add_co_u32_e32 v76, vcc, s17, v140
	s_mov_b32 s19, 0x600000
	s_nop 0
	v_addc_co_u32_e32 v77, vcc, 0, v141, vcc
	v_add_co_u32_e32 v68, vcc, s19, v140
	s_mov_b64 s[2:3], 0x200000
	s_nop 0
	v_addc_co_u32_e32 v69, vcc, 0, v141, vcc
	s_mov_b64 s[4:5], 0x600000
	v_lshl_add_u64 v[64:65], v[140:141], 0, s[2:3]
	v_lshl_add_u64 v[66:67], v[140:141], 0, s[4:5]
	s_waitcnt vmcnt(0)
; __device__ __forceinline__ unsigned cvt_pk_bf16(float lo, float hi) { unsigned r; asm volatile("v_cvt_pk_bf16_f32 %0, %1, %2" : "=v"(r) : "v"(lo), "v"(hi)); return r; }
;     __device__ __forceinline__ void operator()(const AccT& acc, const Unit& u, int wr, int wc, int fr, int fq) const {
;     ...
;             const int hh = 2 * ai + wr;
;             const float l2f = lgd[hh] * 1.4426950408889634f, l2b = lgd[4 + hh] * 1.4426950408889634f;
;             const float zf0 = exp2f((float)(127 - o0) * l2f), zfs = exp2f(-l2f), zb0 = exp2f((float)o0 * l2b), zbs = exp2f(l2b);
; #pragma unroll
;             for (int m = 0; m < 4; ++m) {
;                 const int r = rbase + ai * 128 + m * 16;
;                 const int d = 4 * (2 * m + (fr >> 3)) + j;
; #pragma unroll
;                 for (int bj = 0; bj < 2; ++bj) {
;                     const int t0 = tb + bj * 128;
;                     float v[8];
; #pragma unroll
;                     for (int jj = 0; jj < 4; ++jj) { v[jj] = acc[ai][bj][m][0][jj]; v[4 + jj] = acc[ai][bj][m][1][jj]; }
;                     if constexpr (ROPE) {
;                         const int t = t0 & 2047;
; #pragma unroll
;                         for (int hf = 0; hf < 2; ++hf) {
;                             f32x4 cs, sn;
;                             if (m < 2) { const float c1 = ropeA[(t >> 6) * 16 + d], s1 = ropeA[1024 + (t >> 6) * 16 + d]; cs = (f32x4){c1, c1, c1, c1}; sn = (f32x4){s1, s1, s1, s1}; }
;                             else { const float* cb = ropeA + 2048 + (d - 16) * 64 + (t & 63) + 4 * hf; cs = *(const f32x4*)(cb); sn = *(const f32x4*)(cb + 1024); }
; #pragma unroll
;                             for (int jj = 0; jj < 4; ++jj) { const float pr = __shfl_xor(v[4 * hf + jj], 4); v[4 * hf + jj] = v[4 * hf + jj] * cs[jj] + sgn * pr * sn[jj]; }
;                             __builtin_amdgcn_sched_barrier(0);
;                         }
;                     }
;                     float zf[8], zb[8]; zf[0] = zf0; zb[0] = zb0;
; #pragma unroll
;                     for (int jj = 1; jj < 8; ++jj) { zf[jj] = zf[jj - 1] * zfs; zb[jj] = zb[jj - 1] * zbs; }
;                     u32x4 wf, wb;
;                     wf.x = cvt_pk_bf16(v[0] * zf[0], v[1] * zf[1]); wf.y = cvt_pk_bf16(v[2] * zf[2], v[3] * zf[3]); wf.z = cvt_pk_bf16(v[4] * zf[4], v[5] * zf[5]); wf.w = cvt_pk_bf16(v[6] * zf[6], v[7] * zf[7]);
	v_mul_f32_e32 v72, 0x3fb8aa3b, v70
	v_mul_f32_e32 v73, 0x3fb8aa3b, v71
	v_mul_f32_e32 v74, v72, v155
	v_cmp_lt_f32_e32 vcc, s51, v72
	v_mul_f32_e32 v78, v73, v154
	v_cmp_gt_f32_e64 s[2:3], s49, v73
	v_cndmask_b32_e32 v75, 0, v153, vcc
	v_cmp_gt_f32_e64 s[4:5], s49, v74
	v_cndmask_b32_e64 v79, 0, v153, s[2:3]
	s_and_b64 s[24:25], vcc, exec
	v_cmp_gt_f32_e32 vcc, s49, v78
	v_fmac_f32_e32 v79, 0x3fb8aa3b, v71
	v_cndmask_b32_e64 v71, 0, v153, s[4:5]
	v_cndmask_b32_e32 v78, 0, v153, vcc
	v_fmac_f32_e32 v75, 0xbfb8aa3b, v70
	v_fmac_f32_e32 v71, v72, v155
	v_fmac_f32_e32 v78, v73, v154
	v_exp_f32_e32 v75, v75
	v_exp_f32_e32 v79, v79
	v_exp_f32_e32 v71, v71
	v_exp_f32_e32 v72, v78
	v_cndmask_b32_e64 v74, 0, v152, s[4:5]
	s_cselect_b32 s4, 0xffffffc0, 0
	s_and_b64 s[2:3], s[2:3], exec
	v_cndmask_b32_e32 v70, 0, v152, vcc
	s_cselect_b32 s2, 0xffffffc0, 0
	v_ldexp_f32 v75, v75, s4
	v_ldexp_f32 v78, v79, s2
	v_ldexp_f32 v79, v71, v74
	v_ldexp_f32 v70, v72, v70
	v_mul_f32_e32 v80, v75, v79
	v_mul_f32_e32 v71, v78, v70
	v_mul_f32_e32 v72, v60, v79
	v_mul_f32_e32 v81, v60, v70
	v_mul_f32_e32 v82, v75, v80
	v_mul_f32_e32 v60, v78, v71
	v_mul_f32_e32 v83, v75, v82
	v_mul_f32_e32 v84, v78, v60
	v_mul_f32_e32 v85, v75, v83
	v_mul_f32_e32 v86, v78, v84
	v_mul_f32_e32 v73, v61, v80
	v_mul_f32_e32 v87, v75, v85
	v_mul_f32_e32 v88, v78, v86
	v_cvt_pk_bf16_f32 v72, v72, v73
	v_mul_f32_e32 v73, v62, v82
	v_mul_f32_e32 v74, v63, v83
	v_mul_f32_e32 v90, v75, v87
	v_mul_f32_e32 v91, v78, v88
	v_cvt_pk_bf16_f32 v73, v73, v74
	v_mul_f32_e32 v74, v56, v85
	v_mul_f32_e32 v89, v56, v86
	v_mul_f32_e32 v56, v57, v87
	v_mul_f32_e32 v93, v75, v90
	v_mul_f32_e32 v78, v78, v91
	v_mul_f32_e32 v92, v57, v88
	v_cvt_pk_bf16_f32 v74, v74, v56
	v_mul_f32_e32 v56, v58, v90
	v_mul_f32_e32 v57, v59, v93
	v_mul_f32_e32 v59, v59, v78
	v_cvt_pk_bf16_f32 v75, v56, v57
	v_mul_f32_e32 v61, v61, v71
	v_mul_f32_e32 v62, v62, v60
	v_mul_f32_e32 v63, v63, v84
	v_mul_f32_e32 v94, v58, v91
	v_cvt_pk_bf16_f32 v56, v81, v61
	v_cvt_pk_bf16_f32 v57, v62, v63
	v_cvt_pk_bf16_f32 v58, v89, v92
	v_cvt_pk_bf16_f32 v59, v94, v59
	global_store_dwordx4 v[76:77], v[72:75], off
	global_store_dwordx4 v[68:69], v[56:59], off
	s_nop 1
	v_mul_f32_e32 v56, v52, v79
	v_mul_f32_e32 v57, v53, v80
	v_cvt_pk_bf16_f32 v56, v56, v57
	v_mul_f32_e32 v57, v54, v82
	v_mul_f32_e32 v58, v55, v83
	v_cvt_pk_bf16_f32 v57, v57, v58
	v_mul_f32_e32 v58, v48, v85
	v_mul_f32_e32 v59, v49, v87
	v_cvt_pk_bf16_f32 v58, v58, v59
	v_mul_f32_e32 v59, v50, v90
	v_mul_f32_e32 v52, v52, v70
	v_mul_f32_e32 v53, v53, v71
	v_mul_f32_e32 v61, v51, v93
	v_cvt_pk_bf16_f32 v59, v59, v61
	v_cvt_pk_bf16_f32 v52, v52, v53
	v_mul_f32_e32 v53, v54, v60
	v_mul_f32_e32 v54, v55, v84
	v_mul_f32_e32 v48, v48, v86
	v_mul_f32_e32 v49, v49, v88
	v_cvt_pk_bf16_f32 v53, v53, v54
	v_cvt_pk_bf16_f32 v54, v48, v49
	v_mul_f32_e32 v48, v50, v91
	v_mul_f32_e32 v49, v51, v78
	v_cvt_pk_bf16_f32 v55, v48, v49
	global_store_dwordx4 v[64:65], v[56:59], off offset:256
	global_store_dwordx4 v[66:67], v[52:55], off offset:256
	v_mul_f32_e32 v48, v44, v79
	v_mul_f32_e32 v49, v45, v80
	v_cvt_pk_bf16_f32 v48, v48, v49
	v_mul_f32_e32 v49, v46, v82
	v_mul_f32_e32 v50, v47, v83
	v_cvt_pk_bf16_f32 v49, v49, v50
	v_mul_f32_e32 v50, v40, v85
	v_mul_f32_e32 v51, v41, v87
	v_cvt_pk_bf16_f32 v50, v50, v51
	v_mul_f32_e32 v51, v42, v90
	v_mul_f32_e32 v44, v44, v70
	v_mul_f32_e32 v45, v45, v71
	v_mul_f32_e32 v52, v43, v93
	v_cvt_pk_bf16_f32 v51, v51, v52
	v_cvt_pk_bf16_f32 v44, v44, v45
	v_mul_f32_e32 v45, v46, v60
	v_mul_f32_e32 v46, v47, v84
	v_mul_f32_e32 v40, v40, v86
	s_mov_b64 s[2:3], 0x240000
	v_cvt_pk_bf16_f32 v45, v45, v46
	v_mul_f32_e32 v41, v41, v88
	v_cvt_pk_bf16_f32 v46, v40, v41
	v_mul_f32_e32 v40, v42, v91
	v_lshl_add_u64 v[52:53], v[140:141], 0, s[2:3]
	s_mov_b32 s2, 0x240000
	v_mul_f32_e32 v41, v43, v78
	v_cvt_pk_bf16_f32 v47, v40, v41
	v_add_co_u32_e32 v40, vcc, s2, v140
	s_mov_b64 s[2:3], 0x640000
	s_nop 0
	v_addc_co_u32_e32 v41, vcc, 0, v141, vcc
	global_store_dwordx4 v[40:41], v[48:51], off
	s_nop 1
	v_lshl_add_u64 v[48:49], v[140:141], 0, s[2:3]
	s_mov_b32 s2, 0x640000
	v_add_co_u32_e32 v40, vcc, s2, v140
	s_nop 1
	v_addc_co_u32_e32 v41, vcc, 0, v141, vcc
	global_store_dwordx4 v[40:41], v[44:47], off
	v_mul_f32_e32 v40, v36, v79
	v_mul_f32_e32 v41, v37, v80
	v_cvt_pk_bf16_f32 v40, v40, v41
	v_mul_f32_e32 v41, v38, v82
	v_mul_f32_e32 v42, v39, v83
	v_cvt_pk_bf16_f32 v41, v41, v42
	v_mul_f32_e32 v42, v32, v85
	v_mul_f32_e32 v43, v33, v87
	v_cvt_pk_bf16_f32 v42, v42, v43
	v_mul_f32_e32 v43, v34, v90
	v_mul_f32_e32 v36, v36, v70
;     __device__ __forceinline__ void operator()(const AccT& acc, const Unit& u, int wr, int wc, int fr, int fq) const {
;     ...
;             for (int m = 0; m < 4; ++m) {
;                 const int r = rbase + ai * 128 + m * 16;
;                 const int d = 4 * (2 * m + (fr >> 3)) + j;
; #pragma unroll
;                 for (int bj = 0; bj < 2; ++bj) {
;                     const int t0 = tb + bj * 128;
;                     float v[8];
; #pragma unroll
;                     for (int jj = 0; jj < 4; ++jj) { v[jj] = acc[ai][bj][m][0][jj]; v[4 + jj] = acc[ai][bj][m][1][jj]; }
;                     if constexpr (ROPE) {
;                         const int t = t0 & 2047;
; #pragma unroll
;                         for (int hf = 0; hf < 2; ++hf) {
;                             f32x4 cs, sn;
;                             if (m < 2) { const float c1 = ropeA[(t >> 6) * 16 + d], s1 = ropeA[1024 + (t >> 6) * 16 + d]; cs = (f32x4){c1, c1, c1, c1}; sn = (f32x4){s1, s1, s1, s1}; }
;                             else { const float* cb = ropeA + 2048 + (d - 16) * 64 + (t & 63) + 4 * hf; cs = *(const f32x4*)(cb); sn = *(const f32x4*)(cb + 1024); }
; #pragma unroll
;                             for (int jj = 0; jj < 4; ++jj) { const float pr = __shfl_xor(v[4 * hf + jj], 4); v[4 * hf + jj] = v[4 * hf + jj] * cs[jj] + sgn * pr * sn[jj]; }
;                             __builtin_amdgcn_sched_barrier(0);
;                         }
;                     }
;                     float zf[8], zb[8]; zf[0] = zf0; zb[0] = zb0;
; #pragma unroll
;                     for (int jj = 1; jj < 8; ++jj) { zf[jj] = zf[jj - 1] * zfs; zb[jj] = zb[jj - 1] * zbs; }
;                     u32x4 wf, wb;
;                     wf.x = cvt_pk_bf16(v[0] * zf[0], v[1] * zf[1]); wf.y = cvt_pk_bf16(v[2] * zf[2], v[3] * zf[3]); wf.z = cvt_pk_bf16(v[4] * zf[4], v[5] * zf[5]); wf.w = cvt_pk_bf16(v[6] * zf[6], v[7] * zf[7]);
;                     wb.x = cvt_pk_bf16(v[0] * zb[0], v[1] * zb[1]); wb.y = cvt_pk_bf16(v[2] * zb[2], v[3] * zb[3]); wb.z = cvt_pk_bf16(v[4] * zb[4], v[5] * zb[5]); wb.w = cvt_pk_bf16(v[6] * zb[6], v[7] * zb[7]);
;                     *(u32x4*)(KTZ + (size_t)r * NT + t0) = wf;
;                     *(u32x4*)(KTZ + (size_t)(256 + r) * NT + t0) = wb;
	v_mul_f32_e32 v37, v37, v71
	v_mul_f32_e32 v44, v35, v93
	v_cvt_pk_bf16_f32 v43, v43, v44
	v_cvt_pk_bf16_f32 v36, v36, v37
	v_mul_f32_e32 v37, v38, v60
	v_mul_f32_e32 v38, v39, v84
	v_mul_f32_e32 v32, v32, v86
	v_mul_f32_e32 v33, v33, v88
	v_cvt_pk_bf16_f32 v37, v37, v38
	v_cvt_pk_bf16_f32 v38, v32, v33
	v_mul_f32_e32 v32, v34, v91
	v_mul_f32_e32 v33, v35, v78
	v_cvt_pk_bf16_f32 v39, v32, v33
	global_store_dwordx4 v[52:53], v[40:43], off offset:256
	global_store_dwordx4 v[48:49], v[36:39], off offset:256
	v_mul_f32_e32 v32, v28, v79
	v_mul_f32_e32 v33, v29, v80
	v_cvt_pk_bf16_f32 v32, v32, v33
	v_mul_f32_e32 v33, v30, v82
	v_mul_f32_e32 v34, v31, v83
	v_cvt_pk_bf16_f32 v33, v33, v34
	v_mul_f32_e32 v34, v24, v85
	v_mul_f32_e32 v35, v25, v87
	v_cvt_pk_bf16_f32 v34, v34, v35
	v_mul_f32_e32 v35, v26, v90
	v_mul_f32_e32 v28, v28, v70
	v_mul_f32_e32 v29, v29, v71
	v_mul_f32_e32 v36, v27, v93
	v_cvt_pk_bf16_f32 v35, v35, v36
	v_cvt_pk_bf16_f32 v28, v28, v29
	v_mul_f32_e32 v29, v30, v60
	v_mul_f32_e32 v30, v31, v84
	v_mul_f32_e32 v24, v24, v86
	v_cvt_pk_bf16_f32 v29, v29, v30
	v_mul_f32_e32 v25, v25, v88
	v_cvt_pk_bf16_f32 v30, v24, v25
	v_mul_f32_e32 v24, v26, v91
	v_mul_f32_e32 v25, v27, v78
	v_cvt_pk_bf16_f32 v31, v24, v25
	v_add_co_u32_e32 v24, vcc, s52, v140
	s_mov_b64 s[2:3], 0x280000
	s_nop 0
	v_addc_co_u32_e32 v25, vcc, 0, v141, vcc
	global_store_dwordx4 v[24:25], v[32:35], off
	v_add_co_u32_e32 v24, vcc, s53, v140
	v_lshl_add_u64 v[36:37], v[140:141], 0, s[2:3]
	s_nop 0
	v_addc_co_u32_e32 v25, vcc, 0, v141, vcc
	v_lshl_add_u64 v[32:33], v[140:141], 0, s[8:9]
	global_store_dwordx4 v[24:25], v[28:31], off
	v_mul_f32_e32 v24, v20, v79
	v_mul_f32_e32 v25, v21, v80
	v_cvt_pk_bf16_f32 v24, v24, v25
	v_mul_f32_e32 v25, v22, v82
	v_mul_f32_e32 v26, v23, v83
	v_cvt_pk_bf16_f32 v25, v25, v26
	v_mul_f32_e32 v26, v16, v85
	v_mul_f32_e32 v27, v17, v87
	v_cvt_pk_bf16_f32 v26, v26, v27
	v_mul_f32_e32 v27, v18, v90
	v_mul_f32_e32 v20, v20, v70
	v_mul_f32_e32 v21, v21, v71
	v_mul_f32_e32 v28, v19, v93
	v_cvt_pk_bf16_f32 v27, v27, v28
	v_cvt_pk_bf16_f32 v20, v20, v21
	v_mul_f32_e32 v21, v22, v60
	v_mul_f32_e32 v22, v23, v84
	v_mul_f32_e32 v16, v16, v86
	v_mul_f32_e32 v17, v17, v88
	v_cvt_pk_bf16_f32 v21, v21, v22
	v_cvt_pk_bf16_f32 v22, v16, v17
	v_mul_f32_e32 v16, v18, v91
	v_mul_f32_e32 v17, v19, v78
	v_cvt_pk_bf16_f32 v23, v16, v17
	global_store_dwordx4 v[36:37], v[24:27], off offset:256
	global_store_dwordx4 v[32:33], v[20:23], off offset:256
	v_mul_f32_e32 v16, v12, v79
	v_mul_f32_e32 v17, v13, v80
	v_cvt_pk_bf16_f32 v16, v16, v17
	v_mul_f32_e32 v17, v14, v82
	v_mul_f32_e32 v18, v15, v83
	v_cvt_pk_bf16_f32 v17, v17, v18
	v_mul_f32_e32 v18, v8, v85
	v_mul_f32_e32 v19, v9, v87
	v_cvt_pk_bf16_f32 v18, v18, v19
	v_mul_f32_e32 v19, v10, v90
	v_mul_f32_e32 v12, v12, v70
	v_mul_f32_e32 v13, v13, v71
	v_mul_f32_e32 v20, v11, v93
	v_cvt_pk_bf16_f32 v19, v19, v20
	v_cvt_pk_bf16_f32 v12, v12, v13
	v_mul_f32_e32 v13, v14, v60
	v_mul_f32_e32 v14, v15, v84
	v_mul_f32_e32 v8, v8, v86
	v_cvt_pk_bf16_f32 v13, v13, v14
	v_mul_f32_e32 v9, v9, v88
	v_cvt_pk_bf16_f32 v14, v8, v9
	v_mul_f32_e32 v8, v10, v91
	v_mul_f32_e32 v9, v11, v78
	v_cvt_pk_bf16_f32 v15, v8, v9
	v_add_co_u32_e32 v8, vcc, s54, v140
	v_lshl_add_u64 v[20:21], v[140:141], 0, s[10:11]
	s_nop 0
	v_addc_co_u32_e32 v9, vcc, 0, v141, vcc
	global_store_dwordx4 v[8:9], v[16:19], off
	v_add_co_u32_e32 v8, vcc, s55, v140
	s_nop 0
	v_lshl_add_u64 v[16:17], v[140:141], 0, s[12:13]
	v_addc_co_u32_e32 v9, vcc, 0, v141, vcc
	global_store_dwordx4 v[8:9], v[12:15], off
	v_mul_f32_e32 v8, v4, v79
	v_mul_f32_e32 v9, v5, v80
	v_cvt_pk_bf16_f32 v8, v8, v9
	v_mul_f32_e32 v9, v6, v82
	v_mul_f32_e32 v10, v7, v83
	v_cvt_pk_bf16_f32 v9, v9, v10
	v_mul_f32_e32 v10, v0, v85
	v_mul_f32_e32 v11, v1, v87
	v_cvt_pk_bf16_f32 v10, v10, v11
	v_mul_f32_e32 v11, v2, v90
	v_mul_f32_e32 v4, v4, v70
	v_mul_f32_e32 v5, v5, v71
	v_mul_f32_e32 v12, v3, v93
	v_cvt_pk_bf16_f32 v11, v11, v12
	v_cvt_pk_bf16_f32 v4, v4, v5
	v_mul_f32_e32 v5, v6, v60
	v_mul_f32_e32 v6, v7, v84
	v_mul_f32_e32 v0, v0, v86
	v_mul_f32_e32 v1, v1, v88
	v_cvt_pk_bf16_f32 v5, v5, v6
	v_cvt_pk_bf16_f32 v6, v0, v1
	v_mul_f32_e32 v0, v2, v91
	v_mul_f32_e32 v1, v3, v78
	v_cvt_pk_bf16_f32 v7, v0, v1
	global_store_dwordx4 v[20:21], v[8:11], off offset:256
	global_store_dwordx4 v[16:17], v[4:7], off offset:256
	s_and_b64 vcc, exec, s[14:15]
	s_mov_b32 s56, s16
	s_mov_b64 s[4:5], s[22:23]
	s_mov_b64 s[2:3], s[20:21]
	s_cbranch_vccz .LBB0_686
	s_waitcnt vmcnt(0)
	s_cmpk_gt_u32 s27, 0xff
	s_cbranch_scc1 .LBB0_697
	s_barrier

; #define PG8_STAGE(bufoff, gbase, voff) do { _Pragma("unroll") for (int _i = 0; _i < 2; ++_i) \
;         __builtin_amdgcn_global_load_lds((const unsigned*)((const char*)(gbase) + (voff)[_i]), (LAS unsigned*)(lds + (bufoff) + ldsw + _i * 8192), 16, 0, 0); } while (0)
; #define PG8_LDA(dst, b, h) do { _Pragma("unroll") for (int m = 0; m < 4; ++m) _Pragma("unroll") for (int k = 0; k < 2; ++k) dst[m][k] = *(const LAS bf16x8*)(lds + PG8_SA(b, h) + aoff + m * 2048 + k * 1024); } while (0)
; #define PG8_LDB(dst, b, h) do { _Pragma("unroll") for (int n = 0; n < 2; ++n) _Pragma("unroll") for (int k = 0; k < 2; ++k) dst[n][k] = *(const LAS bf16x8*)(lds + PG8_SB(b, h) + boff + n * 2048 + k * 1024); } while (0)
; #define PG8_WAIT_V(n) asm volatile("s_waitcnt vmcnt(" #n ")" ::: "memory")
; #define PG8_BAR __builtin_amdgcn_s_barrier()
; template <class Epi, class Sched>
; __device__ __forceinline__ void gemm_phase(LAS unsigned char* lds, const Gemm g, const Sched& S, const Epi& E) {
;     ...
;         const bool has_next = S.next(ui + 1, nxt);
;         const char* nA = has_next ? (const char*)g.A + (size_t)nxt.pm * tstep : cA; const char* nB = has_next ? (const char*)g.Bt + (size_t)nxt.pn * tstep : cB;
;         for (int t = 0; t < nt; t += 2) {
;             const bool last = (t == nt - 2);
;             const char* a1 = cA + (size_t)(t + 1) * kstep;
;             const char* a2 = last ? nA : cA + (size_t)(t + 2) * kstep; const char* b2 = last ? nB : cB + (size_t)(t + 2) * kstep;
;             const char* a3 = a2 + kstep; const char* b3 = b2 + kstep;
;             PG8_LDB(B0, 0, 0); PG8_SCHED; PG8_LDA(At, 0, 0); PG8_STAGE(PG8_SA(1, 1), a1 + hstep, voffA);
;             PG8_WAIT_L(8); PG8_BAR; PG8_WAIT_L(0); PG8_MMA(0, 0, At, B0); PG8_BAR; PG8_SCHED;
;             PG8_LDB(B1, 0, 1); PG8_STAGE(PG8_SB(0, 0), b2, voffB);
;             PG8_BAR; PG8_WAIT_L(0); PG8_MMA(0, 1, At, B1); PG8_BAR;
;             PG8_LDA(At, 0, 1); PG8_STAGE(PG8_SA(0, 0), a2, voffA);
;             PG8_BAR; PG8_WAIT_L(0); PG8_MMA(1, 0, At, B0); PG8_BAR; PG8_SCHED;
;             PG8_STAGE(PG8_SB(0, 1), b2 + hstep, voffB);
;             PG8_WAIT_V(6); PG8_BAR; PG8_MMA(1, 1, At, B1); PG8_BAR;
;             PG8_LDB(B0, 1, 0); PG8_SCHED; PG8_LDA(At, 1, 0); PG8_STAGE(PG8_SA(0, 1), a2 + hstep, voffA);
;             PG8_WAIT_L(8); PG8_BAR; PG8_WAIT_L(0); PG8_MMA(0, 0, At, B0); PG8_BAR; PG8_SCHED;
.LBB0_712:
	s_ashr_i32 s15, s14, 31
	v_cmp_lt_i64_e64 s[26:27], s[16:17], 64
	s_lshl_b64 s[16:17], s[14:15], 19
	s_add_u32 s16, s38, s16
	s_addc_u32 s17, s39, s17
	s_and_b64 s[18:19], s[26:27], exec
	s_cselect_b32 s15, s17, s23
	s_cselect_b32 s54, s16, s22
	s_ashr_i32 s13, s12, 31
	s_lshl_b64 s[18:19], s[12:13], 19
	s_add_u32 s18, s28, s18
	s_addc_u32 s19, s29, s19
	s_and_b64 s[26:27], s[26:27], exec
	s_cselect_b32 s13, s19, s25
	s_cselect_b32 s55, s18, s24
	s_add_u32 s22, s22, 0x40080
	s_addc_u32 s23, s23, 0
	s_add_u32 s56, s24, 0x100
	s_addc_u32 s57, s25, 0
	s_mov_b32 s58, -2
	s_waitcnt lgkmcnt(0)
	ds_read_b128 v[146:149], v143
	ds_read_b128 v[150:153], v143 offset:1024
	ds_read_b128 v[154:157], v143 offset:2048
	ds_read_b128 v[158:161], v143 offset:3072
	s_add_u32 s24, s22, 0xfffc0080
	s_addc_u32 s25, s23, -1
	s_cmp_eq_u32 s58, 12
	s_cselect_b32 s27, s15, s25
	s_cselect_b32 s26, s54, s24
	s_cselect_b32 s25, s13, s57
	s_cselect_b32 s24, s55, s56
	s_add_i32 m0, s21, 0xc000
	ds_read_b128 v[162:165], v144
	ds_read_b128 v[166:169], v144 offset:1024
	ds_read_b128 v[170:173], v144 offset:2048
	ds_read_b128 v[174:177], v144 offset:3072
	ds_read_b128 v[178:181], v144 offset:4096
	ds_read_b128 v[182:185], v144 offset:5120
	ds_read_b128 v[186:189], v144 offset:6144
	ds_read_b128 v[190:193], v144 offset:7168
	global_load_lds_dwordx4 v136, s[22:23]
	s_add_i32 m0, s21, 0xe000
	s_nop 0
	global_load_lds_dwordx4 v138, s[22:23]
	s_waitcnt vmcnt(10)
	s_barrier
	s_waitcnt lgkmcnt(0)
	s_setprio 1
	s_waitcnt lgkmcnt(0)
	v_mfma_f32_16x16x32_bf16 v[124:127], v[146:149], v[162:165], 0
	v_mfma_f32_16x16x32_bf16 v[120:123], v[154:157], v[162:165], 0
	v_mfma_f32_16x16x32_bf16 v[116:119], v[146:149], v[170:173], 0
	v_mfma_f32_16x16x32_bf16 v[108:111], v[154:157], v[170:173], 0
	v_mfma_f32_16x16x32_bf16 v[100:103], v[146:149], v[178:181], 0
	v_mfma_f32_16x16x32_bf16 v[92:95], v[154:157], v[178:181], 0
	v_mfma_f32_16x16x32_bf16 v[84:87], v[146:149], v[186:189], 0
	v_mfma_f32_16x16x32_bf16 v[76:79], v[154:157], v[186:189], 0
	v_mfma_f32_16x16x32_bf16 v[124:127], v[150:153], v[166:169], v[124:127]
	v_mfma_f32_16x16x32_bf16 v[120:123], v[158:161], v[166:169], v[120:123]
	v_mfma_f32_16x16x32_bf16 v[116:119], v[150:153], v[174:177], v[116:119]
	v_mfma_f32_16x16x32_bf16 v[108:111], v[158:161], v[174:177], v[108:111]
	v_mfma_f32_16x16x32_bf16 v[100:103], v[150:153], v[182:185], v[100:103]
	v_mfma_f32_16x16x32_bf16 v[92:95], v[158:161], v[182:185], v[92:95]
	v_mfma_f32_16x16x32_bf16 v[84:87], v[150:153], v[190:193], v[84:87]
	v_mfma_f32_16x16x32_bf16 v[76:79], v[158:161], v[190:193], v[76:79]
	s_setprio 0
	s_barrier
	s_add_i32 s59, s46, s34
	s_mov_b32 m0, s59
	ds_read_b128 v[194:197], v145
	ds_read_b128 v[202:205], v145 offset:1024
	ds_read_b128 v[206:209], v145 offset:2048
	ds_read_b128 v[210:213], v145 offset:3072
	global_load_lds_dwordx4 v130, s[24:25]
	s_add_i32 m0, s59, 0x2000
	s_nop 0
	global_load_lds_dwordx4 v134, s[24:25]
	s_waitcnt vmcnt(10)
	s_barrier
	s_waitcnt lgkmcnt(0)
	s_setprio 1
	s_waitcnt lgkmcnt(0)
	v_mfma_f32_16x16x32_bf16 v[112:115], v[194:197], v[162:165], 0
	v_mfma_f32_16x16x32_bf16 v[104:107], v[206:209], v[162:165], 0
	v_mfma_f32_16x16x32_bf16 v[96:99], v[194:197], v[170:173], 0
	v_mfma_f32_16x16x32_bf16 v[88:91], v[206:209], v[170:173], 0
	v_mfma_f32_16x16x32_bf16 v[80:83], v[194:197], v[178:181], 0
	v_mfma_f32_16x16x32_bf16 v[72:75], v[206:209], v[178:181], 0
	v_mfma_f32_16x16x32_bf16 v[68:71], v[194:197], v[186:189], 0
	v_mfma_f32_16x16x32_bf16 v[64:67], v[206:209], v[186:189], 0
	v_mfma_f32_16x16x32_bf16 v[112:115], v[202:205], v[166:169], v[112:115]
	v_mfma_f32_16x16x32_bf16 v[104:107], v[210:213], v[166:169], v[104:107]
	v_mfma_f32_16x16x32_bf16 v[96:99], v[202:205], v[174:177], v[96:99]
	v_mfma_f32_16x16x32_bf16 v[88:91], v[210:213], v[174:177], v[88:91]
	v_mfma_f32_16x16x32_bf16 v[80:83], v[202:205], v[182:185], v[80:83]
	v_mfma_f32_16x16x32_bf16 v[72:75], v[210:213], v[182:185], v[72:75]
	v_mfma_f32_16x16x32_bf16 v[68:71], v[202:205], v[190:193], v[68:71]
	v_mfma_f32_16x16x32_bf16 v[64:67], v[210:213], v[190:193], v[64:67]
	s_setprio 0
	s_mov_b32 m0, s21
	v_lshl_add_u64 v[216:217], s[26:27], 0, v[128:129]
	s_barrier
	ds_read_b128 v[162:165], v144 offset:16384
	ds_read_b128 v[166:169], v144 offset:17408
	ds_read_b128 v[170:173], v144 offset:18432
	ds_read_b128 v[174:177], v144 offset:19456
	ds_read_b128 v[178:181], v144 offset:20480
	ds_read_b128 v[182:185], v144 offset:21504
	ds_read_b128 v[186:189], v144 offset:22528
	ds_read_b128 v[190:193], v144 offset:23552
	global_load_lds_dwordx4 v128, s[26:27]
	v_lshl_add_u64 v[218:219], s[26:27], 0, v[132:133]
	s_mov_b32 m0, s35
	s_nop 0
	global_load_lds_dwordx4 v132, s[26:27]
	s_barrier
	s_waitcnt lgkmcnt(0)
	s_setprio 1
	s_waitcnt lgkmcnt(0)
	v_mfma_f32_16x16x32_bf16 v[60:63], v[146:149], v[162:165], 0
	v_mfma_f32_16x16x32_bf16 v[56:59], v[154:157], v[162:165], 0
	v_mfma_f32_16x16x32_bf16 v[52:55], v[146:149], v[170:173], 0
	v_mfma_f32_16x16x32_bf16 v[44:47], v[154:157], v[170:173], 0
	v_mfma_f32_16x16x32_bf16 v[36:39], v[146:149], v[178:181], 0
	v_mfma_f32_16x16x32_bf16 v[28:31], v[154:157], v[178:181], 0
	v_mfma_f32_16x16x32_bf16 v[20:23], v[146:149], v[186:189], 0
	v_mfma_f32_16x16x32_bf16 v[12:15], v[154:157], v[186:189], 0
	v_mfma_f32_16x16x32_bf16 v[60:63], v[150:153], v[166:169], v[60:63]
	v_mfma_f32_16x16x32_bf16 v[56:59], v[158:161], v[166:169], v[56:59]
	v_mfma_f32_16x16x32_bf16 v[52:55], v[150:153], v[174:177], v[52:55]
	v_mfma_f32_16x16x32_bf16 v[44:47], v[158:161], v[174:177], v[44:47]
	v_mfma_f32_16x16x32_bf16 v[36:39], v[150:153], v[182:185], v[36:39]
	v_mfma_f32_16x16x32_bf16 v[28:31], v[158:161], v[182:185], v[28:31]
	v_mfma_f32_16x16x32_bf16 v[20:23], v[150:153], v[190:193], v[20:23]
	v_mfma_f32_16x16x32_bf16 v[12:15], v[158:161], v[190:193], v[12:15]
	s_setprio 0
	s_barrier
; #define PG8_STAGE(bufoff, gbase, voff) do { _Pragma("unroll") for (int _i = 0; _i < 2; ++_i) \
;         __builtin_amdgcn_global_load_lds((const unsigned*)((const char*)(gbase) + (voff)[_i]), (LAS unsigned*)(lds + (bufoff) + ldsw + _i * 8192), 16, 0, 0); } while (0)
; #define PG8_LDA(dst, b, h) do { _Pragma("unroll") for (int m = 0; m < 4; ++m) _Pragma("unroll") for (int k = 0; k < 2; ++k) dst[m][k] = *(const LAS bf16x8*)(lds + PG8_SA(b, h) + aoff + m * 2048 + k * 1024); } while (0)
; #define PG8_LDB(dst, b, h) do { _Pragma("unroll") for (int n = 0; n < 2; ++n) _Pragma("unroll") for (int k = 0; k < 2; ++k) dst[n][k] = *(const LAS bf16x8*)(lds + PG8_SB(b, h) + boff + n * 2048 + k * 1024); } while (0)
; #define PG8_MMA(ai, bj, At, Bt) do { __builtin_amdgcn_s_setprio(1); _Pragma("unroll") for (int m = 0; m < 4; ++m) _Pragma("unroll") for (int n = 0; n < 2; ++n) _Pragma("unroll") for (int k = 0; k < 2; ++k) \
;         acc[ai][bj][m][n] = __builtin_amdgcn_mfma_f32_16x16x32_bf16(Bt[n][k], At[m][k], acc[ai][bj][m][n], 0, 0, 0); __builtin_amdgcn_s_setprio(0); } while (0)
; #define PG8_WAIT_V(n) asm volatile("s_waitcnt vmcnt(" #n ")" ::: "memory")
; #define PG8_WAIT_L(n) asm volatile("s_waitcnt lgkmcnt(" #n ")" ::: "memory")
; #define PG8_BAR __builtin_amdgcn_s_barrier()
; #define PG8_SCHED __builtin_amdgcn_sched_barrier(0)
; template <class Epi, class Sched>
; __device__ __forceinline__ void gemm_phase(LAS unsigned char* lds, const Gemm g, const Sched& S, const Epi& E) {
;     ...
;             PG8_STAGE(PG8_SB(0, 1), b2 + hstep, voffB);
;             PG8_WAIT_V(6); PG8_BAR; PG8_MMA(1, 1, At, B1); PG8_BAR;
;             PG8_LDB(B0, 1, 0); PG8_SCHED; PG8_LDA(At, 1, 0); PG8_STAGE(PG8_SA(0, 1), a2 + hstep, voffA);
;             PG8_WAIT_L(8); PG8_BAR; PG8_WAIT_L(0); PG8_MMA(0, 0, At, B0); PG8_BAR; PG8_SCHED;
;             PG8_LDB(B1, 1, 1); PG8_STAGE(PG8_SB(1, 0), b3, voffB);
;             PG8_BAR; PG8_WAIT_L(0); PG8_MMA(0, 1, At, B1); PG8_BAR;
;             PG8_LDA(At, 1, 1); PG8_STAGE(PG8_SA(1, 0), a3, voffA);
	s_add_u32 s60, s24, 0x40000
	s_addc_u32 s61, s25, 0
	s_add_i32 s59, s47, s34
	s_mov_b32 m0, s59
	s_nop 0
	global_load_lds_dwordx4 v130, s[60:61]
	s_add_i32 m0, s59, 0x2000
	s_nop 0
	global_load_lds_dwordx4 v134, s[60:61]
	s_add_u32 s26, s26, 0x40000
	s_addc_u32 s27, s27, 0
	s_mov_b32 m0, s36
	s_nop 0
	global_load_lds_dwordx4 v128, s[26:27]
	s_mov_b32 m0, s37
	s_nop 0
	global_load_lds_dwordx4 v132, s[26:27]
	s_waitcnt vmcnt(12)
	s_barrier
	s_setprio 1
	v_mfma_f32_16x16x32_bf16 v[48:51], v[194:197], v[162:165], 0
	v_mfma_f32_16x16x32_bf16 v[40:43], v[206:209], v[162:165], 0
	v_mfma_f32_16x16x32_bf16 v[32:35], v[194:197], v[170:173], 0
	v_mfma_f32_16x16x32_bf16 v[24:27], v[206:209], v[170:173], 0
	v_mfma_f32_16x16x32_bf16 v[16:19], v[194:197], v[178:181], 0
	v_mfma_f32_16x16x32_bf16 v[8:11], v[206:209], v[178:181], 0
	v_mfma_f32_16x16x32_bf16 v[4:7], v[194:197], v[186:189], 0
	v_mfma_f32_16x16x32_bf16 v[0:3], v[206:209], v[186:189], 0
	v_mfma_f32_16x16x32_bf16 v[48:51], v[202:205], v[166:169], v[48:51]
	v_mfma_f32_16x16x32_bf16 v[40:43], v[210:213], v[166:169], v[40:43]
	v_mfma_f32_16x16x32_bf16 v[32:35], v[202:205], v[174:177], v[32:35]
	v_mfma_f32_16x16x32_bf16 v[24:27], v[210:213], v[174:177], v[24:27]
	v_mfma_f32_16x16x32_bf16 v[16:19], v[202:205], v[182:185], v[16:19]
	v_mfma_f32_16x16x32_bf16 v[8:11], v[210:213], v[182:185], v[8:11]
	v_mfma_f32_16x16x32_bf16 v[4:7], v[202:205], v[190:193], v[4:7]
	v_mfma_f32_16x16x32_bf16 v[0:3], v[210:213], v[190:193], v[0:3]
	s_setprio 0
	s_add_i32 s59, 0, 0x18000
	v_add_u32_e32 v158, s59, v142
	s_barrier
	ds_read_b128 v[146:149], v158
	ds_read_b128 v[150:153], v158 offset:1024
	ds_read_b128 v[154:157], v158 offset:2048
	ds_read_b128 v[158:161], v158 offset:3072
	ds_read_b128 v[162:165], v144 offset:32768
	ds_read_b128 v[166:169], v144 offset:33792
	ds_read_b128 v[170:173], v144 offset:34816
	ds_read_b128 v[174:177], v144 offset:35840
	ds_read_b128 v[178:181], v144 offset:36864
	ds_read_b128 v[182:185], v144 offset:37888
	ds_read_b128 v[186:189], v144 offset:38912
	ds_read_b128 v[190:193], v144 offset:39936
	s_waitcnt vmcnt(10)
	s_barrier
	s_waitcnt lgkmcnt(0)
	s_setprio 1
	s_waitcnt lgkmcnt(0)
	v_mfma_f32_16x16x32_bf16 v[124:127], v[146:149], v[162:165], v[124:127]
	v_mfma_f32_16x16x32_bf16 v[120:123], v[154:157], v[162:165], v[120:123]
	v_mfma_f32_16x16x32_bf16 v[116:119], v[146:149], v[170:173], v[116:119]
	v_mfma_f32_16x16x32_bf16 v[108:111], v[154:157], v[170:173], v[108:111]
	v_mfma_f32_16x16x32_bf16 v[100:103], v[146:149], v[178:181], v[100:103]
	v_mfma_f32_16x16x32_bf16 v[92:95], v[154:157], v[178:181], v[92:95]
	v_mfma_f32_16x16x32_bf16 v[84:87], v[146:149], v[186:189], v[84:87]
	v_mfma_f32_16x16x32_bf16 v[76:79], v[154:157], v[186:189], v[76:79]
	v_mfma_f32_16x16x32_bf16 v[124:127], v[150:153], v[166:169], v[124:127]
	v_mfma_f32_16x16x32_bf16 v[120:123], v[158:161], v[166:169], v[120:123]
	v_mfma_f32_16x16x32_bf16 v[116:119], v[150:153], v[174:177], v[116:119]
	v_mfma_f32_16x16x32_bf16 v[108:111], v[158:161], v[174:177], v[108:111]
	v_mfma_f32_16x16x32_bf16 v[100:103], v[150:153], v[182:185], v[100:103]
	v_mfma_f32_16x16x32_bf16 v[92:95], v[158:161], v[182:185], v[92:95]
	v_mfma_f32_16x16x32_bf16 v[84:87], v[150:153], v[190:193], v[84:87]
	v_mfma_f32_16x16x32_bf16 v[76:79], v[158:161], v[190:193], v[76:79]
	s_setprio 0
	s_barrier
	s_add_i32 s26, 0, 0x1c000
	s_add_i32 s27, s59, s34
	v_add_u32_e32 v210, s26, v142
	s_add_u32 s0, s24, 0x80
	s_addc_u32 s1, s25, 0
	s_mov_b32 m0, s27
	ds_read_b128 v[194:197], v210
	ds_read_b128 v[202:205], v210 offset:1024
	ds_read_b128 v[206:209], v210 offset:2048
	ds_read_b128 v[210:213], v210 offset:3072
	global_load_lds_dwordx4 v130, s[0:1]
	s_add_i32 m0, s27, 0x2000
	s_nop 0
	global_load_lds_dwordx4 v134, s[0:1]
	s_waitcnt vmcnt(10)
	s_barrier
	s_waitcnt lgkmcnt(0)
	s_setprio 1
	s_waitcnt lgkmcnt(0)
	v_mfma_f32_16x16x32_bf16 v[112:115], v[194:197], v[162:165], v[112:115]
	v_mfma_f32_16x16x32_bf16 v[104:107], v[206:209], v[162:165], v[104:107]
	v_mfma_f32_16x16x32_bf16 v[96:99], v[194:197], v[170:173], v[96:99]
	v_mfma_f32_16x16x32_bf16 v[88:91], v[206:209], v[170:173], v[88:91]
	v_mfma_f32_16x16x32_bf16 v[80:83], v[194:197], v[178:181], v[80:83]
	v_mfma_f32_16x16x32_bf16 v[72:75], v[206:209], v[178:181], v[72:75]
	v_mfma_f32_16x16x32_bf16 v[68:71], v[194:197], v[186:189], v[68:71]
	v_mfma_f32_16x16x32_bf16 v[64:67], v[206:209], v[186:189], v[64:67]
	v_mfma_f32_16x16x32_bf16 v[112:115], v[202:205], v[166:169], v[112:115]
	v_mfma_f32_16x16x32_bf16 v[104:107], v[210:213], v[166:169], v[104:107]
	v_mfma_f32_16x16x32_bf16 v[96:99], v[202:205], v[174:177], v[96:99]
	v_mfma_f32_16x16x32_bf16 v[88:91], v[210:213], v[174:177], v[88:91]
	v_mfma_f32_16x16x32_bf16 v[80:83], v[202:205], v[182:185], v[80:83]
	v_mfma_f32_16x16x32_bf16 v[72:75], v[210:213], v[182:185], v[72:75]
	v_mfma_f32_16x16x32_bf16 v[68:71], v[202:205], v[190:193], v[68:71]
	v_mfma_f32_16x16x32_bf16 v[64:67], v[210:213], v[190:193], v[64:67]
	s_setprio 0
	s_mov_b32 m0, s43
	s_mov_b64 s[0:1], 0x80
	v_lshl_add_u64 v[198:199], v[216:217], 0, s[0:1]
	s_barrier
	ds_read_b128 v[162:165], v144 offset:49152
	ds_read_b128 v[166:169], v144 offset:50176
	ds_read_b128 v[170:173], v144 offset:51200
	ds_read_b128 v[174:177], v144 offset:52224
	ds_read_b128 v[178:181], v144 offset:53248
	ds_read_b128 v[182:185], v144 offset:54272
	ds_read_b128 v[186:189], v144 offset:55296
	ds_read_b128 v[190:193], v144 offset:56320
	global_load_lds_dwordx4 v[198:199], off
	v_lshl_add_u64 v[198:199], v[218:219], 0, s[0:1]
	s_mov_b32 m0, s44
	s_nop 0
	global_load_lds_dwordx4 v[198:199], off
	s_barrier
; #define PG8_STAGE(bufoff, gbase, voff) do { _Pragma("unroll") for (int _i = 0; _i < 2; ++_i) \
;         __builtin_amdgcn_global_load_lds((const unsigned*)((const char*)(gbase) + (voff)[_i]), (LAS unsigned*)(lds + (bufoff) + ldsw + _i * 8192), 16, 0, 0); } while (0)
; #define PG8_LDA(dst, b, h) do { _Pragma("unroll") for (int m = 0; m < 4; ++m) _Pragma("unroll") for (int k = 0; k < 2; ++k) dst[m][k] = *(const LAS bf16x8*)(lds + PG8_SA(b, h) + aoff + m * 2048 + k * 1024); } while (0)
; #define PG8_LDB(dst, b, h) do { _Pragma("unroll") for (int n = 0; n < 2; ++n) _Pragma("unroll") for (int k = 0; k < 2; ++k) dst[n][k] = *(const LAS bf16x8*)(lds + PG8_SB(b, h) + boff + n * 2048 + k * 1024); } while (0)
; #define PG8_MMA(ai, bj, At, Bt) do { __builtin_amdgcn_s_setprio(1); _Pragma("unroll") for (int m = 0; m < 4; ++m) _Pragma("unroll") for (int n = 0; n < 2; ++n) _Pragma("unroll") for (int k = 0; k < 2; ++k) \
;         acc[ai][bj][m][n] = __builtin_amdgcn_mfma_f32_16x16x32_bf16(Bt[n][k], At[m][k], acc[ai][bj][m][n], 0, 0, 0); __builtin_amdgcn_s_setprio(0); } while (0)
; #define PG8_WAIT_V(n) asm volatile("s_waitcnt vmcnt(" #n ")" ::: "memory")
; #define PG8_WAIT_L(n) asm volatile("s_waitcnt lgkmcnt(" #n ")" ::: "memory")
; #define PG8_BAR __builtin_amdgcn_s_barrier()
; #define PG8_SCHED __builtin_amdgcn_sched_barrier(0)
; template <class Epi, class Sched>
; __device__ __forceinline__ void gemm_phase(LAS unsigned char* lds, const Gemm g, const Sched& S, const Epi& E) {
;     ...
;             PG8_LDB(B0, 0, 0); PG8_SCHED; PG8_LDA(At, 0, 0); PG8_STAGE(PG8_SA(1, 1), a1 + hstep, voffA);
;             PG8_WAIT_L(8); PG8_BAR; PG8_WAIT_L(0); PG8_MMA(0, 0, At, B0); PG8_BAR; PG8_SCHED;
;             PG8_LDB(B1, 0, 1); PG8_STAGE(PG8_SB(0, 0), b2, voffB);
;             PG8_BAR; PG8_WAIT_L(0); PG8_MMA(0, 1, At, B1); PG8_BAR;
;             PG8_LDA(At, 0, 1); PG8_STAGE(PG8_SA(0, 0), a2, voffA);
;             PG8_BAR; PG8_WAIT_L(0); PG8_MMA(1, 0, At, B0); PG8_BAR; PG8_SCHED;
;     ...
;             PG8_BAR; PG8_WAIT_L(0); PG8_MMA(1, 0, At, B0); PG8_BAR; PG8_SCHED;
;             PG8_STAGE(PG8_SB(1, 1), b3 + hstep, voffB);
;             PG8_WAIT_V(6); PG8_BAR; PG8_MMA(1, 1, At, B1); PG8_BAR;
	s_waitcnt lgkmcnt(0)
	s_setprio 1
	s_waitcnt lgkmcnt(0)
	v_mfma_f32_16x16x32_bf16 v[60:63], v[146:149], v[162:165], v[60:63]
	v_mfma_f32_16x16x32_bf16 v[56:59], v[154:157], v[162:165], v[56:59]
	v_mfma_f32_16x16x32_bf16 v[52:55], v[146:149], v[170:173], v[52:55]
	v_mfma_f32_16x16x32_bf16 v[44:47], v[154:157], v[170:173], v[44:47]
	v_mfma_f32_16x16x32_bf16 v[36:39], v[146:149], v[178:181], v[36:39]
	v_mfma_f32_16x16x32_bf16 v[28:31], v[154:157], v[178:181], v[28:31]
	v_mfma_f32_16x16x32_bf16 v[20:23], v[146:149], v[186:189], v[20:23]
	v_mfma_f32_16x16x32_bf16 v[12:15], v[154:157], v[186:189], v[12:15]
	v_mfma_f32_16x16x32_bf16 v[60:63], v[150:153], v[166:169], v[60:63]
	v_mfma_f32_16x16x32_bf16 v[56:59], v[158:161], v[166:169], v[56:59]
	v_mfma_f32_16x16x32_bf16 v[52:55], v[150:153], v[174:177], v[52:55]
	v_mfma_f32_16x16x32_bf16 v[44:47], v[158:161], v[174:177], v[44:47]
	v_mfma_f32_16x16x32_bf16 v[36:39], v[150:153], v[182:185], v[36:39]
	v_mfma_f32_16x16x32_bf16 v[28:31], v[158:161], v[182:185], v[28:31]
	v_mfma_f32_16x16x32_bf16 v[20:23], v[150:153], v[190:193], v[20:23]
	v_mfma_f32_16x16x32_bf16 v[12:15], v[158:161], v[190:193], v[12:15]
	s_setprio 0
	s_barrier
	s_add_u32 s24, s24, 0x40080
	s_addc_u32 s25, s25, 0
	s_add_i32 s26, s26, s34
	s_mov_b32 m0, s26
	s_nop 0
	global_load_lds_dwordx4 v130, s[24:25]
	s_add_i32 m0, s26, 0x2000
	s_nop 0
	global_load_lds_dwordx4 v134, s[24:25]
	s_waitcnt vmcnt(10)
	s_barrier
	s_setprio 1
	v_mfma_f32_16x16x32_bf16 v[48:51], v[194:197], v[162:165], v[48:51]
	v_mfma_f32_16x16x32_bf16 v[40:43], v[206:209], v[162:165], v[40:43]
	v_mfma_f32_16x16x32_bf16 v[32:35], v[194:197], v[170:173], v[32:35]
	v_mfma_f32_16x16x32_bf16 v[24:27], v[206:209], v[170:173], v[24:27]
	v_mfma_f32_16x16x32_bf16 v[16:19], v[194:197], v[178:181], v[16:19]
	v_mfma_f32_16x16x32_bf16 v[8:11], v[206:209], v[178:181], v[8:11]
	v_mfma_f32_16x16x32_bf16 v[4:7], v[194:197], v[186:189], v[4:7]
	v_mfma_f32_16x16x32_bf16 v[0:3], v[206:209], v[186:189], v[0:3]
	v_mfma_f32_16x16x32_bf16 v[48:51], v[202:205], v[166:169], v[48:51]
	v_mfma_f32_16x16x32_bf16 v[40:43], v[210:213], v[166:169], v[40:43]
	v_mfma_f32_16x16x32_bf16 v[32:35], v[202:205], v[174:177], v[32:35]
	v_mfma_f32_16x16x32_bf16 v[24:27], v[210:213], v[174:177], v[24:27]
	v_mfma_f32_16x16x32_bf16 v[16:19], v[202:205], v[182:185], v[16:19]
	v_mfma_f32_16x16x32_bf16 v[8:11], v[210:213], v[182:185], v[8:11]
	v_mfma_f32_16x16x32_bf16 v[4:7], v[202:205], v[190:193], v[4:7]
	v_mfma_f32_16x16x32_bf16 v[0:3], v[210:213], v[190:193], v[0:3]
	s_setprio 0
	s_add_i32 s58, s58, 2
	s_add_u32 s22, s22, 0x100
	s_addc_u32 s23, s23, 0
	s_add_u32 s56, s56, 0x100
	s_addc_u32 s57, s57, 0
	s_cmp_gt_u32 s58, 13
	s_barrier
.LBB0_713:
	ds_read_b128 v[146:149], v143
	ds_read_b128 v[150:153], v143 offset:1024
	ds_read_b128 v[154:157], v143 offset:2048
	ds_read_b128 v[158:161], v143 offset:3072
	s_add_u32 s24, s22, 0xfffc0080
	s_addc_u32 s25, s23, -1
	s_cmp_eq_u32 s58, 12
	s_cselect_b32 s27, s15, s25
	s_cselect_b32 s26, s54, s24
	s_cselect_b32 s25, s13, s57
	s_cselect_b32 s24, s55, s56
	s_add_i32 m0, s21, 0xc000
	ds_read_b128 v[162:165], v144
	ds_read_b128 v[166:169], v144 offset:1024
	ds_read_b128 v[170:173], v144 offset:2048
	ds_read_b128 v[174:177], v144 offset:3072
	ds_read_b128 v[178:181], v144 offset:4096
	ds_read_b128 v[182:185], v144 offset:5120
	ds_read_b128 v[186:189], v144 offset:6144
	ds_read_b128 v[190:193], v144 offset:7168
	global_load_lds_dwordx4 v136, s[22:23]
	s_add_i32 m0, s21, 0xe000
	s_nop 0
	global_load_lds_dwordx4 v138, s[22:23]
	s_waitcnt vmcnt(10)
	s_barrier
	s_waitcnt lgkmcnt(0)
	s_setprio 1
	s_waitcnt lgkmcnt(0)
	v_mfma_f32_16x16x32_bf16 v[124:127], v[146:149], v[162:165], v[124:127]
	v_mfma_f32_16x16x32_bf16 v[120:123], v[154:157], v[162:165], v[120:123]
	v_mfma_f32_16x16x32_bf16 v[116:119], v[146:149], v[170:173], v[116:119]
	v_mfma_f32_16x16x32_bf16 v[108:111], v[154:157], v[170:173], v[108:111]
	v_mfma_f32_16x16x32_bf16 v[100:103], v[146:149], v[178:181], v[100:103]
	v_mfma_f32_16x16x32_bf16 v[92:95], v[154:157], v[178:181], v[92:95]
	v_mfma_f32_16x16x32_bf16 v[84:87], v[146:149], v[186:189], v[84:87]
	v_mfma_f32_16x16x32_bf16 v[76:79], v[154:157], v[186:189], v[76:79]
	v_mfma_f32_16x16x32_bf16 v[124:127], v[150:153], v[166:169], v[124:127]
	v_mfma_f32_16x16x32_bf16 v[120:123], v[158:161], v[166:169], v[120:123]
	v_mfma_f32_16x16x32_bf16 v[116:119], v[150:153], v[174:177], v[116:119]
	v_mfma_f32_16x16x32_bf16 v[108:111], v[158:161], v[174:177], v[108:111]
	v_mfma_f32_16x16x32_bf16 v[100:103], v[150:153], v[182:185], v[100:103]
	v_mfma_f32_16x16x32_bf16 v[92:95], v[158:161], v[182:185], v[92:95]
	v_mfma_f32_16x16x32_bf16 v[84:87], v[150:153], v[190:193], v[84:87]
	v_mfma_f32_16x16x32_bf16 v[76:79], v[158:161], v[190:193], v[76:79]
	s_setprio 0
	s_barrier
	s_add_i32 s59, s46, s34
	s_mov_b32 m0, s59
	ds_read_b128 v[194:197], v145
	ds_read_b128 v[202:205], v145 offset:1024
	ds_read_b128 v[206:209], v145 offset:2048
	ds_read_b128 v[210:213], v145 offset:3072
	global_load_lds_dwordx4 v130, s[24:25]
	s_add_i32 m0, s59, 0x2000
	s_nop 0
	global_load_lds_dwordx4 v134, s[24:25]
	s_waitcnt vmcnt(10)
	s_barrier
; #define PG8_STAGE(bufoff, gbase, voff) do { _Pragma("unroll") for (int _i = 0; _i < 2; ++_i) \
;         __builtin_amdgcn_global_load_lds((const unsigned*)((const char*)(gbase) + (voff)[_i]), (LAS unsigned*)(lds + (bufoff) + ldsw + _i * 8192), 16, 0, 0); } while (0)
; #define PG8_LDA(dst, b, h) do { _Pragma("unroll") for (int m = 0; m < 4; ++m) _Pragma("unroll") for (int k = 0; k < 2; ++k) dst[m][k] = *(const LAS bf16x8*)(lds + PG8_SA(b, h) + aoff + m * 2048 + k * 1024); } while (0)
; #define PG8_LDB(dst, b, h) do { _Pragma("unroll") for (int n = 0; n < 2; ++n) _Pragma("unroll") for (int k = 0; k < 2; ++k) dst[n][k] = *(const LAS bf16x8*)(lds + PG8_SB(b, h) + boff + n * 2048 + k * 1024); } while (0)
; #define PG8_MMA(ai, bj, At, Bt) do { __builtin_amdgcn_s_setprio(1); _Pragma("unroll") for (int m = 0; m < 4; ++m) _Pragma("unroll") for (int n = 0; n < 2; ++n) _Pragma("unroll") for (int k = 0; k < 2; ++k) \
;         acc[ai][bj][m][n] = __builtin_amdgcn_mfma_f32_16x16x32_bf16(Bt[n][k], At[m][k], acc[ai][bj][m][n], 0, 0, 0); __builtin_amdgcn_s_setprio(0); } while (0)
; #define PG8_WAIT_V(n) asm volatile("s_waitcnt vmcnt(" #n ")" ::: "memory")
; #define PG8_WAIT_L(n) asm volatile("s_waitcnt lgkmcnt(" #n ")" ::: "memory")
; #define PG8_BAR __builtin_amdgcn_s_barrier()
; #define PG8_SCHED __builtin_amdgcn_sched_barrier(0)
; template <class Epi, class Sched>
; __device__ __forceinline__ void gemm_phase(LAS unsigned char* lds, const Gemm g, const Sched& S, const Epi& E) {
;     ...
;             PG8_BAR; PG8_WAIT_L(0); PG8_MMA(1, 0, At, B0); PG8_BAR; PG8_SCHED;
;             PG8_STAGE(PG8_SB(0, 1), b2 + hstep, voffB);
;             PG8_WAIT_V(6); PG8_BAR; PG8_MMA(1, 1, At, B1); PG8_BAR;
;             PG8_LDB(B0, 1, 0); PG8_SCHED; PG8_LDA(At, 1, 0); PG8_STAGE(PG8_SA(0, 1), a2 + hstep, voffA);
;             PG8_WAIT_L(8); PG8_BAR; PG8_WAIT_L(0); PG8_MMA(0, 0, At, B0); PG8_BAR; PG8_SCHED;
	s_waitcnt lgkmcnt(0)
	s_setprio 1
	s_waitcnt lgkmcnt(0)
	v_mfma_f32_16x16x32_bf16 v[112:115], v[194:197], v[162:165], v[112:115]
	v_mfma_f32_16x16x32_bf16 v[104:107], v[206:209], v[162:165], v[104:107]
	v_mfma_f32_16x16x32_bf16 v[96:99], v[194:197], v[170:173], v[96:99]
	v_mfma_f32_16x16x32_bf16 v[88:91], v[206:209], v[170:173], v[88:91]
	v_mfma_f32_16x16x32_bf16 v[80:83], v[194:197], v[178:181], v[80:83]
	v_mfma_f32_16x16x32_bf16 v[72:75], v[206:209], v[178:181], v[72:75]
	v_mfma_f32_16x16x32_bf16 v[68:71], v[194:197], v[186:189], v[68:71]
	v_mfma_f32_16x16x32_bf16 v[64:67], v[206:209], v[186:189], v[64:67]
	v_mfma_f32_16x16x32_bf16 v[112:115], v[202:205], v[166:169], v[112:115]
	v_mfma_f32_16x16x32_bf16 v[104:107], v[210:213], v[166:169], v[104:107]
	v_mfma_f32_16x16x32_bf16 v[96:99], v[202:205], v[174:177], v[96:99]
	v_mfma_f32_16x16x32_bf16 v[88:91], v[210:213], v[174:177], v[88:91]
	v_mfma_f32_16x16x32_bf16 v[80:83], v[202:205], v[182:185], v[80:83]
	v_mfma_f32_16x16x32_bf16 v[72:75], v[210:213], v[182:185], v[72:75]
	v_mfma_f32_16x16x32_bf16 v[68:71], v[202:205], v[190:193], v[68:71]
	v_mfma_f32_16x16x32_bf16 v[64:67], v[210:213], v[190:193], v[64:67]
	s_setprio 0
	s_mov_b32 m0, s21
	v_lshl_add_u64 v[216:217], s[26:27], 0, v[128:129]
	s_barrier
	ds_read_b128 v[162:165], v144 offset:16384
	ds_read_b128 v[166:169], v144 offset:17408
	ds_read_b128 v[170:173], v144 offset:18432
	ds_read_b128 v[174:177], v144 offset:19456
	ds_read_b128 v[178:181], v144 offset:20480
	ds_read_b128 v[182:185], v144 offset:21504
	ds_read_b128 v[186:189], v144 offset:22528
	ds_read_b128 v[190:193], v144 offset:23552
	global_load_lds_dwordx4 v128, s[26:27]
	v_lshl_add_u64 v[218:219], s[26:27], 0, v[132:133]
	s_mov_b32 m0, s35
	s_nop 0
	global_load_lds_dwordx4 v132, s[26:27]
	s_barrier
	s_waitcnt lgkmcnt(0)
	s_setprio 1
	s_waitcnt lgkmcnt(0)
	v_mfma_f32_16x16x32_bf16 v[60:63], v[146:149], v[162:165], v[60:63]
	v_mfma_f32_16x16x32_bf16 v[56:59], v[154:157], v[162:165], v[56:59]
	v_mfma_f32_16x16x32_bf16 v[52:55], v[146:149], v[170:173], v[52:55]
	v_mfma_f32_16x16x32_bf16 v[44:47], v[154:157], v[170:173], v[44:47]
	v_mfma_f32_16x16x32_bf16 v[36:39], v[146:149], v[178:181], v[36:39]
	v_mfma_f32_16x16x32_bf16 v[28:31], v[154:157], v[178:181], v[28:31]
	v_mfma_f32_16x16x32_bf16 v[20:23], v[146:149], v[186:189], v[20:23]
	v_mfma_f32_16x16x32_bf16 v[12:15], v[154:157], v[186:189], v[12:15]
	v_mfma_f32_16x16x32_bf16 v[60:63], v[150:153], v[166:169], v[60:63]
	v_mfma_f32_16x16x32_bf16 v[56:59], v[158:161], v[166:169], v[56:59]
	v_mfma_f32_16x16x32_bf16 v[52:55], v[150:153], v[174:177], v[52:55]
	v_mfma_f32_16x16x32_bf16 v[44:47], v[158:161], v[174:177], v[44:47]
	v_mfma_f32_16x16x32_bf16 v[36:39], v[150:153], v[182:185], v[36:39]
	v_mfma_f32_16x16x32_bf16 v[28:31], v[158:161], v[182:185], v[28:31]
	v_mfma_f32_16x16x32_bf16 v[20:23], v[150:153], v[190:193], v[20:23]
	v_mfma_f32_16x16x32_bf16 v[12:15], v[158:161], v[190:193], v[12:15]
	s_setprio 0
	s_barrier
	s_add_u32 s60, s24, 0x40000
	s_addc_u32 s61, s25, 0
	s_add_i32 s59, s47, s34
	s_mov_b32 m0, s59
	s_nop 0
	global_load_lds_dwordx4 v130, s[60:61]
	s_add_i32 m0, s59, 0x2000
	s_nop 0
	global_load_lds_dwordx4 v134, s[60:61]
	s_add_u32 s26, s26, 0x40000
	s_addc_u32 s27, s27, 0
	s_mov_b32 m0, s36
	s_nop 0
	global_load_lds_dwordx4 v128, s[26:27]
	s_mov_b32 m0, s37
	s_nop 0
	global_load_lds_dwordx4 v132, s[26:27]
	s_waitcnt vmcnt(12)
	s_barrier
	s_setprio 1
	v_mfma_f32_16x16x32_bf16 v[48:51], v[194:197], v[162:165], v[48:51]
	v_mfma_f32_16x16x32_bf16 v[40:43], v[206:209], v[162:165], v[40:43]
	v_mfma_f32_16x16x32_bf16 v[32:35], v[194:197], v[170:173], v[32:35]
	v_mfma_f32_16x16x32_bf16 v[24:27], v[206:209], v[170:173], v[24:27]
	v_mfma_f32_16x16x32_bf16 v[16:19], v[194:197], v[178:181], v[16:19]
	v_mfma_f32_16x16x32_bf16 v[8:11], v[206:209], v[178:181], v[8:11]
	v_mfma_f32_16x16x32_bf16 v[4:7], v[194:197], v[186:189], v[4:7]
	v_mfma_f32_16x16x32_bf16 v[0:3], v[206:209], v[186:189], v[0:3]
	v_mfma_f32_16x16x32_bf16 v[48:51], v[202:205], v[166:169], v[48:51]
	v_mfma_f32_16x16x32_bf16 v[40:43], v[210:213], v[166:169], v[40:43]
	v_mfma_f32_16x16x32_bf16 v[32:35], v[202:205], v[174:177], v[32:35]
	v_mfma_f32_16x16x32_bf16 v[24:27], v[210:213], v[174:177], v[24:27]
	v_mfma_f32_16x16x32_bf16 v[16:19], v[202:205], v[182:185], v[16:19]
	v_mfma_f32_16x16x32_bf16 v[8:11], v[210:213], v[182:185], v[8:11]
	v_mfma_f32_16x16x32_bf16 v[4:7], v[202:205], v[190:193], v[4:7]
	v_mfma_f32_16x16x32_bf16 v[0:3], v[210:213], v[190:193], v[0:3]
	s_setprio 0
	s_add_i32 s59, 0, 0x18000
	v_add_u32_e32 v158, s59, v142
	s_barrier
	ds_read_b128 v[146:149], v158
	ds_read_b128 v[150:153], v158 offset:1024
	ds_read_b128 v[154:157], v158 offset:2048
	ds_read_b128 v[158:161], v158 offset:3072
	ds_read_b128 v[162:165], v144 offset:32768
	ds_read_b128 v[166:169], v144 offset:33792
	ds_read_b128 v[170:173], v144 offset:34816
	ds_read_b128 v[174:177], v144 offset:35840
	ds_read_b128 v[178:181], v144 offset:36864
	ds_read_b128 v[182:185], v144 offset:37888
	ds_read_b128 v[186:189], v144 offset:38912
	ds_read_b128 v[190:193], v144 offset:39936
	s_waitcnt vmcnt(10)
	s_barrier
; #define PG8_STAGE(bufoff, gbase, voff) do { _Pragma("unroll") for (int _i = 0; _i < 2; ++_i) \
;         __builtin_amdgcn_global_load_lds((const unsigned*)((const char*)(gbase) + (voff)[_i]), (LAS unsigned*)(lds + (bufoff) + ldsw + _i * 8192), 16, 0, 0); } while (0)
; #define PG8_LDA(dst, b, h) do { _Pragma("unroll") for (int m = 0; m < 4; ++m) _Pragma("unroll") for (int k = 0; k < 2; ++k) dst[m][k] = *(const LAS bf16x8*)(lds + PG8_SA(b, h) + aoff + m * 2048 + k * 1024); } while (0)
; #define PG8_LDB(dst, b, h) do { _Pragma("unroll") for (int n = 0; n < 2; ++n) _Pragma("unroll") for (int k = 0; k < 2; ++k) dst[n][k] = *(const LAS bf16x8*)(lds + PG8_SB(b, h) + boff + n * 2048 + k * 1024); } while (0)
; #define PG8_MMA(ai, bj, At, Bt) do { __builtin_amdgcn_s_setprio(1); _Pragma("unroll") for (int m = 0; m < 4; ++m) _Pragma("unroll") for (int n = 0; n < 2; ++n) _Pragma("unroll") for (int k = 0; k < 2; ++k) \
;         acc[ai][bj][m][n] = __builtin_amdgcn_mfma_f32_16x16x32_bf16(Bt[n][k], At[m][k], acc[ai][bj][m][n], 0, 0, 0); __builtin_amdgcn_s_setprio(0); } while (0)
; #define PG8_WAIT_V(n) asm volatile("s_waitcnt vmcnt(" #n ")" ::: "memory")
; #define PG8_WAIT_L(n) asm volatile("s_waitcnt lgkmcnt(" #n ")" ::: "memory")
; #define PG8_BAR __builtin_amdgcn_s_barrier()
; #define PG8_SCHED __builtin_amdgcn_sched_barrier(0)
; template <class Epi, class Sched>
; __device__ __forceinline__ void gemm_phase(LAS unsigned char* lds, const Gemm g, const Sched& S, const Epi& E) {
;     ...
;             PG8_WAIT_L(8); PG8_BAR; PG8_WAIT_L(0); PG8_MMA(0, 0, At, B0); PG8_BAR; PG8_SCHED;
;             PG8_LDB(B1, 1, 1); PG8_STAGE(PG8_SB(1, 0), b3, voffB);
;             PG8_BAR; PG8_WAIT_L(0); PG8_MMA(0, 1, At, B1); PG8_BAR;
;             PG8_LDA(At, 1, 1); PG8_STAGE(PG8_SA(1, 0), a3, voffA);
;             PG8_BAR; PG8_WAIT_L(0); PG8_MMA(1, 0, At, B0); PG8_BAR; PG8_SCHED;
;             PG8_STAGE(PG8_SB(1, 1), b3 + hstep, voffB);
;             PG8_WAIT_V(6); PG8_BAR; PG8_MMA(1, 1, At, B1); PG8_BAR;
	s_waitcnt lgkmcnt(0)
	s_setprio 1
	s_waitcnt lgkmcnt(0)
	v_mfma_f32_16x16x32_bf16 v[124:127], v[146:149], v[162:165], v[124:127]
	v_mfma_f32_16x16x32_bf16 v[120:123], v[154:157], v[162:165], v[120:123]
	v_mfma_f32_16x16x32_bf16 v[116:119], v[146:149], v[170:173], v[116:119]
	v_mfma_f32_16x16x32_bf16 v[108:111], v[154:157], v[170:173], v[108:111]
	v_mfma_f32_16x16x32_bf16 v[100:103], v[146:149], v[178:181], v[100:103]
	v_mfma_f32_16x16x32_bf16 v[92:95], v[154:157], v[178:181], v[92:95]
	v_mfma_f32_16x16x32_bf16 v[84:87], v[146:149], v[186:189], v[84:87]
	v_mfma_f32_16x16x32_bf16 v[76:79], v[154:157], v[186:189], v[76:79]
	v_mfma_f32_16x16x32_bf16 v[124:127], v[150:153], v[166:169], v[124:127]
	v_mfma_f32_16x16x32_bf16 v[120:123], v[158:161], v[166:169], v[120:123]
	v_mfma_f32_16x16x32_bf16 v[116:119], v[150:153], v[174:177], v[116:119]
	v_mfma_f32_16x16x32_bf16 v[108:111], v[158:161], v[174:177], v[108:111]
	v_mfma_f32_16x16x32_bf16 v[100:103], v[150:153], v[182:185], v[100:103]
	v_mfma_f32_16x16x32_bf16 v[92:95], v[158:161], v[182:185], v[92:95]
	v_mfma_f32_16x16x32_bf16 v[84:87], v[150:153], v[190:193], v[84:87]
	v_mfma_f32_16x16x32_bf16 v[76:79], v[158:161], v[190:193], v[76:79]
	s_setprio 0
	s_barrier
	s_add_i32 s26, 0, 0x1c000
	s_add_i32 s27, s59, s34
	v_add_u32_e32 v210, s26, v142
	s_add_u32 s0, s24, 0x80
	s_addc_u32 s1, s25, 0
	s_mov_b32 m0, s27
	ds_read_b128 v[194:197], v210
	ds_read_b128 v[202:205], v210 offset:1024
	ds_read_b128 v[206:209], v210 offset:2048
	ds_read_b128 v[210:213], v210 offset:3072
	global_load_lds_dwordx4 v130, s[0:1]
	s_add_i32 m0, s27, 0x2000
	s_nop 0
	global_load_lds_dwordx4 v134, s[0:1]
	s_waitcnt vmcnt(10)
	s_barrier
	s_waitcnt lgkmcnt(0)
	s_setprio 1
	s_waitcnt lgkmcnt(0)
	v_mfma_f32_16x16x32_bf16 v[112:115], v[194:197], v[162:165], v[112:115]
	v_mfma_f32_16x16x32_bf16 v[104:107], v[206:209], v[162:165], v[104:107]
	v_mfma_f32_16x16x32_bf16 v[96:99], v[194:197], v[170:173], v[96:99]
	v_mfma_f32_16x16x32_bf16 v[88:91], v[206:209], v[170:173], v[88:91]
	v_mfma_f32_16x16x32_bf16 v[80:83], v[194:197], v[178:181], v[80:83]
	v_mfma_f32_16x16x32_bf16 v[72:75], v[206:209], v[178:181], v[72:75]
	v_mfma_f32_16x16x32_bf16 v[68:71], v[194:197], v[186:189], v[68:71]
	v_mfma_f32_16x16x32_bf16 v[64:67], v[206:209], v[186:189], v[64:67]
	v_mfma_f32_16x16x32_bf16 v[112:115], v[202:205], v[166:169], v[112:115]
	v_mfma_f32_16x16x32_bf16 v[104:107], v[210:213], v[166:169], v[104:107]
	v_mfma_f32_16x16x32_bf16 v[96:99], v[202:205], v[174:177], v[96:99]
	v_mfma_f32_16x16x32_bf16 v[88:91], v[210:213], v[174:177], v[88:91]
	v_mfma_f32_16x16x32_bf16 v[80:83], v[202:205], v[182:185], v[80:83]
	v_mfma_f32_16x16x32_bf16 v[72:75], v[210:213], v[182:185], v[72:75]
	v_mfma_f32_16x16x32_bf16 v[68:71], v[202:205], v[190:193], v[68:71]
	v_mfma_f32_16x16x32_bf16 v[64:67], v[210:213], v[190:193], v[64:67]
	s_setprio 0
	s_mov_b32 m0, s43
	s_mov_b64 s[0:1], 0x80
	v_lshl_add_u64 v[198:199], v[216:217], 0, s[0:1]
	s_barrier
	ds_read_b128 v[162:165], v144 offset:49152
	ds_read_b128 v[166:169], v144 offset:50176
	ds_read_b128 v[170:173], v144 offset:51200
	ds_read_b128 v[174:177], v144 offset:52224
	ds_read_b128 v[178:181], v144 offset:53248
	ds_read_b128 v[182:185], v144 offset:54272
	ds_read_b128 v[186:189], v144 offset:55296
	ds_read_b128 v[190:193], v144 offset:56320
	global_load_lds_dwordx4 v[198:199], off
	v_lshl_add_u64 v[198:199], v[218:219], 0, s[0:1]
	s_mov_b32 m0, s44
	s_nop 0
	global_load_lds_dwordx4 v[198:199], off
	s_barrier
	s_waitcnt lgkmcnt(0)
	s_setprio 1
	s_waitcnt lgkmcnt(0)
	v_mfma_f32_16x16x32_bf16 v[60:63], v[146:149], v[162:165], v[60:63]
	v_mfma_f32_16x16x32_bf16 v[56:59], v[154:157], v[162:165], v[56:59]
	v_mfma_f32_16x16x32_bf16 v[52:55], v[146:149], v[170:173], v[52:55]
	v_mfma_f32_16x16x32_bf16 v[44:47], v[154:157], v[170:173], v[44:47]
	v_mfma_f32_16x16x32_bf16 v[36:39], v[146:149], v[178:181], v[36:39]
	v_mfma_f32_16x16x32_bf16 v[28:31], v[154:157], v[178:181], v[28:31]
	v_mfma_f32_16x16x32_bf16 v[20:23], v[146:149], v[186:189], v[20:23]
	v_mfma_f32_16x16x32_bf16 v[12:15], v[154:157], v[186:189], v[12:15]
	v_mfma_f32_16x16x32_bf16 v[60:63], v[150:153], v[166:169], v[60:63]
	v_mfma_f32_16x16x32_bf16 v[56:59], v[158:161], v[166:169], v[56:59]
	v_mfma_f32_16x16x32_bf16 v[52:55], v[150:153], v[174:177], v[52:55]
	v_mfma_f32_16x16x32_bf16 v[44:47], v[158:161], v[174:177], v[44:47]
	v_mfma_f32_16x16x32_bf16 v[36:39], v[150:153], v[182:185], v[36:39]
	v_mfma_f32_16x16x32_bf16 v[28:31], v[158:161], v[182:185], v[28:31]
	v_mfma_f32_16x16x32_bf16 v[20:23], v[150:153], v[190:193], v[20:23]
	v_mfma_f32_16x16x32_bf16 v[12:15], v[158:161], v[190:193], v[12:15]
	s_setprio 0
	s_barrier
	s_add_u32 s24, s24, 0x40080
	s_addc_u32 s25, s25, 0
	s_add_i32 s26, s26, s34
	s_mov_b32 m0, s26
	s_nop 0
	global_load_lds_dwordx4 v130, s[24:25]
	s_add_i32 m0, s26, 0x2000
	s_nop 0
	global_load_lds_dwordx4 v134, s[24:25]
	s_waitcnt vmcnt(10)
	s_barrier
; __device__ __forceinline__ unsigned cvt_pk_bf16(float lo, float hi) { unsigned r; asm volatile("v_cvt_pk_bf16_f32 %0, %1, %2" : "=v"(r) : "v"(lo), "v"(hi)); return r; }
; #define PG8_MMA(ai, bj, At, Bt) do { __builtin_amdgcn_s_setprio(1); _Pragma("unroll") for (int m = 0; m < 4; ++m) _Pragma("unroll") for (int n = 0; n < 2; ++n) _Pragma("unroll") for (int k = 0; k < 2; ++k) \
;         acc[ai][bj][m][n] = __builtin_amdgcn_mfma_f32_16x16x32_bf16(Bt[n][k], At[m][k], acc[ai][bj][m][n], 0, 0, 0); __builtin_amdgcn_s_setprio(0); } while (0)
; #define PG8_WAIT_V(n) asm volatile("s_waitcnt vmcnt(" #n ")" ::: "memory")
; #define PG8_BAR __builtin_amdgcn_s_barrier()
; template <class Epi, class Sched>
; __device__ __forceinline__ void gemm_phase(LAS unsigned char* lds, const Gemm g, const Sched& S, const Epi& E) {
;     ...
;             PG8_WAIT_V(6); PG8_BAR; PG8_MMA(1, 1, At, B1); PG8_BAR;
;     ...
;         if (!has_next) break;
; #pragma unroll
;         for (int a = 0; a < 2; ++a)
; #pragma unroll
;             for (int b = 0; b < 2; ++b)
; #pragma unroll
;                 for (int m = 0; m < 4; ++m)
; #pragma unroll
;                     for (int n = 0; n < 2; ++n) acc[a][b][m][n] = (f32x4){0.f, 0.f, 0.f, 0.f};
;         cur = nxt; cA = nA; cB = nB; ++ui;
;     }
;     PG8_WAIT_V(0);
;     if (wr == 0) PG8_BAR;
;     PG8_BAR;
;     __device__ __forceinline__ void operator()(const AccT& acc, const Unit& u, int wr, int wc, int fr, int fq) const {
;     ...
;         const int rbase = u.pm * 256 + wr * 64 + fr;
;         const int tb = u.pn * 256 + wc * 32 + 8 * fq;
; #pragma unroll
;         for (int ai = 0; ai < 2; ++ai)
; #pragma unroll
;             for (int m = 0; m < 4; ++m) {
;                 const int r = rbase + ai * 128 + m * 16;
; #pragma unroll
;                 for (int bj = 0; bj < 2; ++bj) {
;                     const int t0 = tb + bj * 128;
;                     const f32x4 v0 = acc[ai][bj][m][0], v1 = acc[ai][bj][m][1];
;                     u32x4 w; w.x = cvt_pk_bf16(v0[0], v0[1]); w.y = cvt_pk_bf16(v0[2], v0[3]); w.z = cvt_pk_bf16(v1[0], v1[1]); w.w = cvt_pk_bf16(v1[2], v1[3]);
;                     *(u32x4*)(VT + (size_t)r * NT + t0) = w;
;                 }
	s_setprio 1
	v_mfma_f32_16x16x32_bf16 v[48:51], v[194:197], v[162:165], v[48:51]
	v_mfma_f32_16x16x32_bf16 v[40:43], v[206:209], v[162:165], v[40:43]
	v_mfma_f32_16x16x32_bf16 v[32:35], v[194:197], v[170:173], v[32:35]
	v_mfma_f32_16x16x32_bf16 v[24:27], v[206:209], v[170:173], v[24:27]
	v_mfma_f32_16x16x32_bf16 v[16:19], v[194:197], v[178:181], v[16:19]
	v_mfma_f32_16x16x32_bf16 v[8:11], v[206:209], v[178:181], v[8:11]
	v_mfma_f32_16x16x32_bf16 v[4:7], v[194:197], v[186:189], v[4:7]
	v_mfma_f32_16x16x32_bf16 v[0:3], v[206:209], v[186:189], v[0:3]
	v_mfma_f32_16x16x32_bf16 v[48:51], v[202:205], v[166:169], v[48:51]
	v_mfma_f32_16x16x32_bf16 v[40:43], v[210:213], v[166:169], v[40:43]
	v_mfma_f32_16x16x32_bf16 v[32:35], v[202:205], v[174:177], v[32:35]
	v_mfma_f32_16x16x32_bf16 v[24:27], v[210:213], v[174:177], v[24:27]
	v_mfma_f32_16x16x32_bf16 v[16:19], v[202:205], v[182:185], v[16:19]
	v_mfma_f32_16x16x32_bf16 v[8:11], v[210:213], v[182:185], v[8:11]
	v_mfma_f32_16x16x32_bf16 v[4:7], v[202:205], v[190:193], v[4:7]
	v_mfma_f32_16x16x32_bf16 v[0:3], v[210:213], v[190:193], v[0:3]
	s_setprio 0
	s_add_i32 s58, s58, 2
	s_add_u32 s22, s22, 0x100
	s_addc_u32 s23, s23, 0
	s_add_u32 s56, s56, 0x100
	s_addc_u32 s57, s57, 0
	s_cmp_gt_u32 s58, 13
	s_barrier
	s_cbranch_scc0 .LBB0_713
	v_mov_b32_e32 v146, v140
	v_mov_b32_e32 v147, v141
	s_lshl_b32 s13, s20, 8
	s_add_i32 s13, s13, s41
	v_add_u32_e32 v146, s13, v146
	s_lshl_b32 s13, s53, 8
	s_or_b32 s13, s13, s42
	v_lshl_add_u32 v148, v147, 3, s13
	v_ashrrev_i32_e32 v147, 31, v146
	v_cvt_pk_bf16_f32 v124, v124, v125
	v_cvt_pk_bf16_f32 v125, v126, v127
	v_cvt_pk_bf16_f32 v126, v120, v121
	v_lshlrev_b64 v[120:121], 14, v[146:147]
	v_lshl_add_u64 v[120:121], s[62:63], 0, v[120:121]
	v_ashrrev_i32_e32 v149, 31, v148
	v_lshl_add_u64 v[120:121], v[148:149], 1, v[120:121]
	s_mov_b32 s13, 0x40000
	v_cvt_pk_bf16_f32 v127, v122, v123
	global_store_dwordx4 v[120:121], v[124:127], off
	v_cvt_pk_bf16_f32 v112, v112, v113
	v_cvt_pk_bf16_f32 v113, v114, v115
	v_cvt_pk_bf16_f32 v114, v104, v105
	v_cvt_pk_bf16_f32 v115, v106, v107
	global_store_dwordx4 v[120:121], v[112:115], off offset:256
	v_cvt_pk_bf16_f32 v104, v116, v117
	v_cvt_pk_bf16_f32 v105, v118, v119
	v_cvt_pk_bf16_f32 v106, v108, v109
	v_cvt_pk_bf16_f32 v107, v110, v111
	s_mov_b64 s[22:23], 0x40000
	v_add_co_u32_e32 v110, vcc, s13, v120
	v_lshl_add_u64 v[108:109], v[120:121], 0, s[22:23]
	s_nop 0
	v_addc_co_u32_e32 v111, vcc, 0, v121, vcc
	s_mov_b32 s13, 0x80000
	global_store_dwordx4 v[110:111], v[104:107], off
	v_cvt_pk_bf16_f32 v96, v96, v97
	v_cvt_pk_bf16_f32 v97, v98, v99
	v_cvt_pk_bf16_f32 v98, v88, v89
	v_cvt_pk_bf16_f32 v99, v90, v91
	global_store_dwordx4 v[108:109], v[96:99], off offset:256
	v_cvt_pk_bf16_f32 v88, v100, v101
	v_cvt_pk_bf16_f32 v89, v102, v103
	v_cvt_pk_bf16_f32 v90, v92, v93
	v_cvt_pk_bf16_f32 v91, v94, v95
	s_mov_b64 s[22:23], 0x80000
	v_add_co_u32_e32 v94, vcc, s13, v120
	v_lshl_add_u64 v[92:93], v[120:121], 0, s[22:23]
	s_nop 0
	v_addc_co_u32_e32 v95, vcc, 0, v121, vcc
	global_store_dwordx4 v[94:95], v[88:91], off
	v_cvt_pk_bf16_f32 v80, v80, v81
	v_cvt_pk_bf16_f32 v81, v82, v83
	v_cvt_pk_bf16_f32 v82, v72, v73
	v_cvt_pk_bf16_f32 v83, v74, v75
	global_store_dwordx4 v[92:93], v[80:83], off offset:256
	v_cvt_pk_bf16_f32 v72, v84, v85
	v_cvt_pk_bf16_f32 v73, v86, v87
	v_cvt_pk_bf16_f32 v74, v76, v77
	v_cvt_pk_bf16_f32 v75, v78, v79
	s_mov_b64 s[22:23], 0xc0000
	v_add_co_u32_e32 v78, vcc, s48, v120
	v_lshl_add_u64 v[76:77], v[120:121], 0, s[22:23]
	s_nop 0
	v_addc_co_u32_e32 v79, vcc, 0, v121, vcc
	global_store_dwordx4 v[78:79], v[72:75], off
	v_cvt_pk_bf16_f32 v68, v68, v69
	v_cvt_pk_bf16_f32 v69, v70, v71
	v_cvt_pk_bf16_f32 v70, v64, v65
	v_cvt_pk_bf16_f32 v71, v66, v67
	global_store_dwordx4 v[76:77], v[68:71], off offset:256
	v_cvt_pk_bf16_f32 v60, v60, v61
	v_cvt_pk_bf16_f32 v61, v62, v63
	v_cvt_pk_bf16_f32 v62, v56, v57
	v_cvt_pk_bf16_f32 v63, v58, v59
	v_add_co_u32_e32 v58, vcc, s49, v120
	v_lshl_add_u64 v[56:57], v[120:121], 0, s[2:3]
	s_nop 0
	v_addc_co_u32_e32 v59, vcc, 0, v121, vcc
	global_store_dwordx4 v[58:59], v[60:63], off
	v_cvt_pk_bf16_f32 v48, v48, v49
	v_cvt_pk_bf16_f32 v49, v50, v51
	v_cvt_pk_bf16_f32 v50, v40, v41
	v_cvt_pk_bf16_f32 v51, v42, v43
	global_store_dwordx4 v[56:57], v[48:51], off offset:256
	v_cvt_pk_bf16_f32 v40, v52, v53
	v_cvt_pk_bf16_f32 v41, v54, v55
	v_cvt_pk_bf16_f32 v42, v44, v45
	v_cvt_pk_bf16_f32 v43, v46, v47
	v_add_co_u32_e32 v46, vcc, s50, v120
	v_lshl_add_u64 v[44:45], v[120:121], 0, s[4:5]
	s_nop 0
	v_addc_co_u32_e32 v47, vcc, 0, v121, vcc
	global_store_dwordx4 v[46:47], v[40:43], off
	v_cvt_pk_bf16_f32 v32, v32, v33
	v_cvt_pk_bf16_f32 v33, v34, v35
	v_cvt_pk_bf16_f32 v34, v24, v25
	v_cvt_pk_bf16_f32 v35, v26, v27
	global_store_dwordx4 v[44:45], v[32:35], off offset:256
	v_cvt_pk_bf16_f32 v24, v36, v37
	v_cvt_pk_bf16_f32 v25, v38, v39
	v_cvt_pk_bf16_f32 v26, v28, v29
	v_cvt_pk_bf16_f32 v27, v30, v31
	v_add_co_u32_e32 v30, vcc, s51, v120
	v_lshl_add_u64 v[28:29], v[120:121], 0, s[6:7]
	s_nop 0
	v_addc_co_u32_e32 v31, vcc, 0, v121, vcc
	global_store_dwordx4 v[30:31], v[24:27], off
	v_cvt_pk_bf16_f32 v16, v16, v17
	v_cvt_pk_bf16_f32 v17, v18, v19
	v_cvt_pk_bf16_f32 v18, v8, v9
	v_cvt_pk_bf16_f32 v19, v10, v11
	global_store_dwordx4 v[28:29], v[16:19], off offset:256
	v_cvt_pk_bf16_f32 v8, v20, v21
	v_cvt_pk_bf16_f32 v9, v22, v23
	v_cvt_pk_bf16_f32 v10, v12, v13
	v_cvt_pk_bf16_f32 v11, v14, v15
	v_add_co_u32_e32 v14, vcc, s52, v120
	v_lshl_add_u64 v[12:13], v[120:121], 0, s[8:9]
	s_nop 0
	v_addc_co_u32_e32 v15, vcc, 0, v121, vcc
	s_and_b64 vcc, exec, s[10:11]
	s_mov_b32 s53, s12
	s_mov_b32 s20, s14
	s_mov_b64 s[24:25], s[18:19]
	s_mov_b64 s[22:23], s[16:17]
	global_store_dwordx4 v[14:15], v[8:11], off
	v_cvt_pk_bf16_f32 v4, v4, v5
	v_cvt_pk_bf16_f32 v5, v6, v7
	v_cvt_pk_bf16_f32 v6, v0, v1
	v_cvt_pk_bf16_f32 v7, v2, v3
	global_store_dwordx4 v[12:13], v[4:7], off offset:256
	s_cbranch_vccz .LBB0_706
	s_waitcnt vmcnt(0)
	s_cmpk_gt_u32 s31, 0xff
	s_cbranch_scc1 .LBB0_717
	s_barrier

; #define PG8_STAGE(bufoff, gbase, voff) do { _Pragma("unroll") for (int _i = 0; _i < 2; ++_i) \
;         __builtin_amdgcn_global_load_lds((const unsigned*)((const char*)(gbase) + (voff)[_i]), (LAS unsigned*)(lds + (bufoff) + ldsw + _i * 8192), 16, 0, 0); } while (0)
; #define PG8_LDA(dst, b, h) do { _Pragma("unroll") for (int m = 0; m < 4; ++m) _Pragma("unroll") for (int k = 0; k < 2; ++k) dst[m][k] = *(const LAS bf16x8*)(lds + PG8_SA(b, h) + aoff + m * 2048 + k * 1024); } while (0)
; #define PG8_LDB(dst, b, h) do { _Pragma("unroll") for (int n = 0; n < 2; ++n) _Pragma("unroll") for (int k = 0; k < 2; ++k) dst[n][k] = *(const LAS bf16x8*)(lds + PG8_SB(b, h) + boff + n * 2048 + k * 1024); } while (0)
; #define PG8_WAIT_V(n) asm volatile("s_waitcnt vmcnt(" #n ")" ::: "memory")
; #define PG8_BAR __builtin_amdgcn_s_barrier()
; template <class Epi, class Sched>
; __device__ __forceinline__ void gemm_phase(LAS unsigned char* lds, const Gemm g, const Sched& S, const Epi& E) {
;     ...
;         const bool has_next = S.next(ui + 1, nxt);
;         const char* nA = has_next ? (const char*)g.A + (size_t)nxt.pm * tstep : cA; const char* nB = has_next ? (const char*)g.Bt + (size_t)nxt.pn * tstep : cB;
;         for (int t = 0; t < nt; t += 2) {
;             const bool last = (t == nt - 2);
;             const char* a1 = cA + (size_t)(t + 1) * kstep;
;             const char* a2 = last ? nA : cA + (size_t)(t + 2) * kstep; const char* b2 = last ? nB : cB + (size_t)(t + 2) * kstep;
;             const char* a3 = a2 + kstep; const char* b3 = b2 + kstep;
;             PG8_LDB(B0, 0, 0); PG8_SCHED; PG8_LDA(At, 0, 0); PG8_STAGE(PG8_SA(1, 1), a1 + hstep, voffA);
;             PG8_WAIT_L(8); PG8_BAR; PG8_WAIT_L(0); PG8_MMA(0, 0, At, B0); PG8_BAR; PG8_SCHED;
;             PG8_LDB(B1, 0, 1); PG8_STAGE(PG8_SB(0, 0), b2, voffB);
;             PG8_BAR; PG8_WAIT_L(0); PG8_MMA(0, 1, At, B1); PG8_BAR;
;             PG8_LDA(At, 0, 1); PG8_STAGE(PG8_SA(0, 0), a2, voffA);
;             PG8_BAR; PG8_WAIT_L(0); PG8_MMA(1, 0, At, B0); PG8_BAR; PG8_SCHED;
;             PG8_STAGE(PG8_SB(0, 1), b2 + hstep, voffB);
;             PG8_WAIT_V(6); PG8_BAR; PG8_MMA(1, 1, At, B1); PG8_BAR;
;             PG8_LDB(B0, 1, 0); PG8_SCHED; PG8_LDA(At, 1, 0); PG8_STAGE(PG8_SA(0, 1), a2 + hstep, voffA);
;             PG8_WAIT_L(8); PG8_BAR; PG8_WAIT_L(0); PG8_MMA(0, 0, At, B0); PG8_BAR; PG8_SCHED;
.LBB0_825:
	s_ashr_i32 s7, s6, 31
	v_cmp_lt_i64_e32 vcc, s[8:9], v[156:157]
	s_lshl_b64 s[8:9], s[6:7], 20
	s_add_u32 s8, s22, s8
	s_addc_u32 s9, s23, s9
	s_and_b64 s[10:11], vcc, exec
	s_cselect_b32 s7, s9, s15
	s_cselect_b32 s39, s8, s14
	s_ashr_i32 s5, s4, 31
	s_lshl_b64 s[10:11], s[4:5], 20
	s_add_u32 s10, s50, s10
	s_addc_u32 s11, s51, s11
	s_and_b64 s[18:19], vcc, exec
	s_cselect_b32 s5, s11, s17
	s_cselect_b32 s40, s10, s16
	s_add_u32 s14, s14, 0x80080
	s_addc_u32 s15, s15, 0
	s_add_u32 s41, s16, 0x100
	s_addc_u32 s42, s17, 0
	s_mov_b32 s43, -2
	ds_read_b128 v[128:131], v168
	ds_read_b128 v[132:135], v168 offset:1024
	ds_read_b128 v[136:139], v168 offset:2048
	ds_read_b128 v[140:143], v168 offset:3072
	s_add_u32 s16, s14, 0xfff80080
	s_addc_u32 s17, s15, -1
	s_cmp_eq_u32 s43, 28
	s_cselect_b32 s19, s7, s17
	s_cselect_b32 s18, s39, s16
	s_cselect_b32 s17, s5, s42
	s_cselect_b32 s16, s40, s41
	s_add_i32 m0, s13, 0xc000
	ds_read_b128 v[162:165], v169
	ds_read_b128 v[172:175], v169 offset:1024
	ds_read_b128 v[176:179], v169 offset:2048
	ds_read_b128 v[180:183], v169 offset:3072
	ds_read_b128 v[184:187], v169 offset:4096
	ds_read_b128 v[188:191], v169 offset:5120
	ds_read_b128 v[192:195], v169 offset:6144
	ds_read_b128 v[196:199], v169 offset:7168
	global_load_lds_dwordx4 v152, s[14:15]
	s_add_i32 m0, s13, 0xe000
	s_nop 0
	global_load_lds_dwordx4 v154, s[14:15]
	s_waitcnt vmcnt(10)
	s_barrier
	s_waitcnt lgkmcnt(0)
	s_setprio 1
	s_waitcnt lgkmcnt(0)
	v_mfma_f32_16x16x32_bf16 v[124:127], v[128:131], v[162:165], 0
	v_mfma_f32_16x16x32_bf16 v[120:123], v[136:139], v[162:165], 0
	v_mfma_f32_16x16x32_bf16 v[116:119], v[128:131], v[176:179], 0
	v_mfma_f32_16x16x32_bf16 v[112:115], v[136:139], v[176:179], 0
	v_mfma_f32_16x16x32_bf16 v[108:111], v[128:131], v[184:187], 0
	v_mfma_f32_16x16x32_bf16 v[100:103], v[136:139], v[184:187], 0
	v_mfma_f32_16x16x32_bf16 v[76:79], v[128:131], v[192:195], 0
	v_mfma_f32_16x16x32_bf16 v[72:75], v[136:139], v[192:195], 0
	v_mfma_f32_16x16x32_bf16 v[124:127], v[132:135], v[172:175], v[124:127]
	v_mfma_f32_16x16x32_bf16 v[120:123], v[140:143], v[172:175], v[120:123]
	v_mfma_f32_16x16x32_bf16 v[116:119], v[132:135], v[180:183], v[116:119]
	v_mfma_f32_16x16x32_bf16 v[112:115], v[140:143], v[180:183], v[112:115]
	v_mfma_f32_16x16x32_bf16 v[108:111], v[132:135], v[188:191], v[108:111]
	v_mfma_f32_16x16x32_bf16 v[100:103], v[140:143], v[188:191], v[100:103]
	v_mfma_f32_16x16x32_bf16 v[76:79], v[132:135], v[196:199], v[76:79]
	v_mfma_f32_16x16x32_bf16 v[72:75], v[140:143], v[196:199], v[72:75]
	s_setprio 0
	s_barrier
	s_add_i32 s44, s35, s24
	s_mov_b32 m0, s44
	ds_read_b128 v[202:205], v170
	ds_read_b128 v[206:209], v170 offset:1024
	ds_read_b128 v[210:213], v170 offset:2048
	ds_read_b128 v[214:217], v170 offset:3072
	global_load_lds_dwordx4 v146, s[16:17]
	s_add_i32 m0, s44, 0x2000
	s_nop 0
	global_load_lds_dwordx4 v150, s[16:17]
	s_waitcnt vmcnt(10)
	s_barrier
	s_waitcnt lgkmcnt(0)
	s_setprio 1
	s_waitcnt lgkmcnt(0)
	v_mfma_f32_16x16x32_bf16 v[104:107], v[202:205], v[162:165], 0
	v_mfma_f32_16x16x32_bf16 v[96:99], v[210:213], v[162:165], 0
	v_mfma_f32_16x16x32_bf16 v[92:95], v[202:205], v[176:179], 0
	v_mfma_f32_16x16x32_bf16 v[88:91], v[210:213], v[176:179], 0
	v_mfma_f32_16x16x32_bf16 v[84:87], v[202:205], v[184:187], 0
	v_mfma_f32_16x16x32_bf16 v[80:83], v[210:213], v[184:187], 0
	v_mfma_f32_16x16x32_bf16 v[68:71], v[202:205], v[192:195], 0
	v_mfma_f32_16x16x32_bf16 v[64:67], v[210:213], v[192:195], 0
	v_mfma_f32_16x16x32_bf16 v[104:107], v[206:209], v[172:175], v[104:107]
	v_mfma_f32_16x16x32_bf16 v[96:99], v[214:217], v[172:175], v[96:99]
	v_mfma_f32_16x16x32_bf16 v[92:95], v[206:209], v[180:183], v[92:95]
	v_mfma_f32_16x16x32_bf16 v[88:91], v[214:217], v[180:183], v[88:91]
	v_mfma_f32_16x16x32_bf16 v[84:87], v[206:209], v[188:191], v[84:87]
	v_mfma_f32_16x16x32_bf16 v[80:83], v[214:217], v[188:191], v[80:83]
	v_mfma_f32_16x16x32_bf16 v[68:71], v[206:209], v[196:199], v[68:71]
	v_mfma_f32_16x16x32_bf16 v[64:67], v[214:217], v[196:199], v[64:67]
	s_setprio 0
	s_mov_b32 m0, s13
	v_lshl_add_u64 v[222:223], s[18:19], 0, v[144:145]
	s_barrier
	ds_read_b128 v[162:165], v169 offset:16384
	ds_read_b128 v[172:175], v169 offset:17408
	ds_read_b128 v[176:179], v169 offset:18432
	ds_read_b128 v[180:183], v169 offset:19456
	ds_read_b128 v[184:187], v169 offset:20480
	ds_read_b128 v[188:191], v169 offset:21504
	ds_read_b128 v[192:195], v169 offset:22528
	ds_read_b128 v[196:199], v169 offset:23552
	global_load_lds_dwordx4 v144, s[18:19]
	v_lshl_add_u64 v[224:225], s[18:19], 0, v[148:149]
	s_mov_b32 m0, s25
	s_nop 0
	global_load_lds_dwordx4 v148, s[18:19]
	s_barrier
	s_waitcnt lgkmcnt(0)
	s_setprio 1
	s_waitcnt lgkmcnt(0)
	v_mfma_f32_16x16x32_bf16 v[60:63], v[128:131], v[162:165], 0
	v_mfma_f32_16x16x32_bf16 v[56:59], v[136:139], v[162:165], 0
	v_mfma_f32_16x16x32_bf16 v[48:51], v[128:131], v[176:179], 0
	v_mfma_f32_16x16x32_bf16 v[40:43], v[136:139], v[176:179], 0
	v_mfma_f32_16x16x32_bf16 v[32:35], v[128:131], v[184:187], 0
	v_mfma_f32_16x16x32_bf16 v[24:27], v[136:139], v[184:187], 0
	v_mfma_f32_16x16x32_bf16 v[16:19], v[128:131], v[192:195], 0
	v_mfma_f32_16x16x32_bf16 v[8:11], v[136:139], v[192:195], 0
	v_mfma_f32_16x16x32_bf16 v[60:63], v[132:135], v[172:175], v[60:63]
	v_mfma_f32_16x16x32_bf16 v[56:59], v[140:143], v[172:175], v[56:59]
	v_mfma_f32_16x16x32_bf16 v[48:51], v[132:135], v[180:183], v[48:51]
	v_mfma_f32_16x16x32_bf16 v[40:43], v[140:143], v[180:183], v[40:43]
	v_mfma_f32_16x16x32_bf16 v[32:35], v[132:135], v[188:191], v[32:35]
	v_mfma_f32_16x16x32_bf16 v[24:27], v[140:143], v[188:191], v[24:27]
	v_mfma_f32_16x16x32_bf16 v[16:19], v[132:135], v[196:199], v[16:19]
	v_mfma_f32_16x16x32_bf16 v[8:11], v[140:143], v[196:199], v[8:11]
	s_setprio 0
	s_barrier
; #define PG8_STAGE(bufoff, gbase, voff) do { _Pragma("unroll") for (int _i = 0; _i < 2; ++_i) \
;         __builtin_amdgcn_global_load_lds((const unsigned*)((const char*)(gbase) + (voff)[_i]), (LAS unsigned*)(lds + (bufoff) + ldsw + _i * 8192), 16, 0, 0); } while (0)
; #define PG8_LDA(dst, b, h) do { _Pragma("unroll") for (int m = 0; m < 4; ++m) _Pragma("unroll") for (int k = 0; k < 2; ++k) dst[m][k] = *(const LAS bf16x8*)(lds + PG8_SA(b, h) + aoff + m * 2048 + k * 1024); } while (0)
; #define PG8_LDB(dst, b, h) do { _Pragma("unroll") for (int n = 0; n < 2; ++n) _Pragma("unroll") for (int k = 0; k < 2; ++k) dst[n][k] = *(const LAS bf16x8*)(lds + PG8_SB(b, h) + boff + n * 2048 + k * 1024); } while (0)
; #define PG8_MMA(ai, bj, At, Bt) do { __builtin_amdgcn_s_setprio(1); _Pragma("unroll") for (int m = 0; m < 4; ++m) _Pragma("unroll") for (int n = 0; n < 2; ++n) _Pragma("unroll") for (int k = 0; k < 2; ++k) \
;         acc[ai][bj][m][n] = __builtin_amdgcn_mfma_f32_16x16x32_bf16(Bt[n][k], At[m][k], acc[ai][bj][m][n], 0, 0, 0); __builtin_amdgcn_s_setprio(0); } while (0)
; #define PG8_WAIT_V(n) asm volatile("s_waitcnt vmcnt(" #n ")" ::: "memory")
; #define PG8_WAIT_L(n) asm volatile("s_waitcnt lgkmcnt(" #n ")" ::: "memory")
; #define PG8_BAR __builtin_amdgcn_s_barrier()
; #define PG8_SCHED __builtin_amdgcn_sched_barrier(0)
; template <class Epi, class Sched>
; __device__ __forceinline__ void gemm_phase(LAS unsigned char* lds, const Gemm g, const Sched& S, const Epi& E) {
;     ...
;             PG8_STAGE(PG8_SB(0, 1), b2 + hstep, voffB);
;             PG8_WAIT_V(6); PG8_BAR; PG8_MMA(1, 1, At, B1); PG8_BAR;
;             PG8_LDB(B0, 1, 0); PG8_SCHED; PG8_LDA(At, 1, 0); PG8_STAGE(PG8_SA(0, 1), a2 + hstep, voffA);
;             PG8_WAIT_L(8); PG8_BAR; PG8_WAIT_L(0); PG8_MMA(0, 0, At, B0); PG8_BAR; PG8_SCHED;
;             PG8_LDB(B1, 1, 1); PG8_STAGE(PG8_SB(1, 0), b3, voffB);
;             PG8_BAR; PG8_WAIT_L(0); PG8_MMA(0, 1, At, B1); PG8_BAR;
;             PG8_LDA(At, 1, 1); PG8_STAGE(PG8_SA(1, 0), a3, voffA);
	s_add_u32 s44, s16, 0x80000
	s_addc_u32 s45, s17, 0
	s_add_i32 s46, s36, s24
	s_mov_b32 m0, s46
	s_nop 0
	global_load_lds_dwordx4 v146, s[44:45]
	s_add_i32 m0, s46, 0x2000
	s_nop 0
	global_load_lds_dwordx4 v150, s[44:45]
	s_add_u32 s18, s18, 0x80000
	s_addc_u32 s19, s19, 0
	s_mov_b32 m0, s26
	s_nop 0
	global_load_lds_dwordx4 v144, s[18:19]
	s_mov_b32 m0, s27
	s_nop 0
	global_load_lds_dwordx4 v148, s[18:19]
	s_waitcnt vmcnt(12)
	s_barrier
	s_setprio 1
	v_mfma_f32_16x16x32_bf16 v[52:55], v[202:205], v[162:165], 0
	v_mfma_f32_16x16x32_bf16 v[44:47], v[210:213], v[162:165], 0
	v_mfma_f32_16x16x32_bf16 v[36:39], v[202:205], v[176:179], 0
	v_mfma_f32_16x16x32_bf16 v[28:31], v[210:213], v[176:179], 0
	v_mfma_f32_16x16x32_bf16 v[20:23], v[202:205], v[184:187], 0
	v_mfma_f32_16x16x32_bf16 v[12:15], v[210:213], v[184:187], 0
	v_mfma_f32_16x16x32_bf16 v[4:7], v[202:205], v[192:195], 0
	v_mfma_f32_16x16x32_bf16 v[0:3], v[210:213], v[192:195], 0
	v_mfma_f32_16x16x32_bf16 v[52:55], v[206:209], v[172:175], v[52:55]
	v_mfma_f32_16x16x32_bf16 v[44:47], v[214:217], v[172:175], v[44:47]
	v_mfma_f32_16x16x32_bf16 v[36:39], v[206:209], v[180:183], v[36:39]
	v_mfma_f32_16x16x32_bf16 v[28:31], v[214:217], v[180:183], v[28:31]
	v_mfma_f32_16x16x32_bf16 v[20:23], v[206:209], v[188:191], v[20:23]
	v_mfma_f32_16x16x32_bf16 v[12:15], v[214:217], v[188:191], v[12:15]
	v_mfma_f32_16x16x32_bf16 v[4:7], v[206:209], v[196:199], v[4:7]
	v_mfma_f32_16x16x32_bf16 v[0:3], v[214:217], v[196:199], v[0:3]
	s_setprio 0
	s_add_i32 s44, 0, 0x18000
	v_add_u32_e32 v140, s44, v167
	s_barrier
	ds_read_b128 v[128:131], v140
	ds_read_b128 v[132:135], v140 offset:1024
	ds_read_b128 v[136:139], v140 offset:2048
	ds_read_b128 v[140:143], v140 offset:3072
	ds_read_b128 v[162:165], v169 offset:32768
	ds_read_b128 v[172:175], v169 offset:33792
	ds_read_b128 v[176:179], v169 offset:34816
	ds_read_b128 v[180:183], v169 offset:35840
	ds_read_b128 v[184:187], v169 offset:36864
	ds_read_b128 v[188:191], v169 offset:37888
	ds_read_b128 v[192:195], v169 offset:38912
	ds_read_b128 v[196:199], v169 offset:39936
	s_waitcnt vmcnt(10)
	s_barrier
	s_waitcnt lgkmcnt(0)
	s_setprio 1
	s_waitcnt lgkmcnt(0)
	v_mfma_f32_16x16x32_bf16 v[124:127], v[128:131], v[162:165], v[124:127]
	v_mfma_f32_16x16x32_bf16 v[120:123], v[136:139], v[162:165], v[120:123]
	v_mfma_f32_16x16x32_bf16 v[116:119], v[128:131], v[176:179], v[116:119]
	v_mfma_f32_16x16x32_bf16 v[112:115], v[136:139], v[176:179], v[112:115]
	v_mfma_f32_16x16x32_bf16 v[108:111], v[128:131], v[184:187], v[108:111]
	v_mfma_f32_16x16x32_bf16 v[100:103], v[136:139], v[184:187], v[100:103]
	v_mfma_f32_16x16x32_bf16 v[76:79], v[128:131], v[192:195], v[76:79]
	v_mfma_f32_16x16x32_bf16 v[72:75], v[136:139], v[192:195], v[72:75]
	v_mfma_f32_16x16x32_bf16 v[124:127], v[132:135], v[172:175], v[124:127]
	v_mfma_f32_16x16x32_bf16 v[120:123], v[140:143], v[172:175], v[120:123]
	v_mfma_f32_16x16x32_bf16 v[116:119], v[132:135], v[180:183], v[116:119]
	v_mfma_f32_16x16x32_bf16 v[112:115], v[140:143], v[180:183], v[112:115]
	v_mfma_f32_16x16x32_bf16 v[108:111], v[132:135], v[188:191], v[108:111]
	v_mfma_f32_16x16x32_bf16 v[100:103], v[140:143], v[188:191], v[100:103]
	v_mfma_f32_16x16x32_bf16 v[76:79], v[132:135], v[196:199], v[76:79]
	v_mfma_f32_16x16x32_bf16 v[72:75], v[140:143], v[196:199], v[72:75]
	s_setprio 0
	s_barrier
	s_add_i32 s18, 0, 0x1c000
	s_add_i32 s19, s44, s24
	v_add_u32_e32 v160, s18, v167
	s_add_u32 s0, s16, 0x80
	s_addc_u32 s1, s17, 0
	s_mov_b32 m0, s19
	ds_read_b128 v[202:205], v160
	ds_read_b128 v[206:209], v160 offset:1024
	ds_read_b128 v[210:213], v160 offset:2048
	ds_read_b128 v[214:217], v160 offset:3072
	global_load_lds_dwordx4 v146, s[0:1]
	s_add_i32 m0, s19, 0x2000
	s_nop 0
	global_load_lds_dwordx4 v150, s[0:1]
	s_waitcnt vmcnt(10)
	s_barrier
	s_waitcnt lgkmcnt(0)
	s_setprio 1
	s_waitcnt lgkmcnt(0)
	v_mfma_f32_16x16x32_bf16 v[104:107], v[202:205], v[162:165], v[104:107]
	v_mfma_f32_16x16x32_bf16 v[96:99], v[210:213], v[162:165], v[96:99]
	v_mfma_f32_16x16x32_bf16 v[92:95], v[202:205], v[176:179], v[92:95]
	v_mfma_f32_16x16x32_bf16 v[88:91], v[210:213], v[176:179], v[88:91]
	v_mfma_f32_16x16x32_bf16 v[84:87], v[202:205], v[184:187], v[84:87]
	v_mfma_f32_16x16x32_bf16 v[80:83], v[210:213], v[184:187], v[80:83]
	v_mfma_f32_16x16x32_bf16 v[68:71], v[202:205], v[192:195], v[68:71]
	v_mfma_f32_16x16x32_bf16 v[64:67], v[210:213], v[192:195], v[64:67]
	v_mfma_f32_16x16x32_bf16 v[104:107], v[206:209], v[172:175], v[104:107]
	v_mfma_f32_16x16x32_bf16 v[96:99], v[214:217], v[172:175], v[96:99]
	v_mfma_f32_16x16x32_bf16 v[92:95], v[206:209], v[180:183], v[92:95]
	v_mfma_f32_16x16x32_bf16 v[88:91], v[214:217], v[180:183], v[88:91]
	v_mfma_f32_16x16x32_bf16 v[84:87], v[206:209], v[188:191], v[84:87]
	v_mfma_f32_16x16x32_bf16 v[80:83], v[214:217], v[188:191], v[80:83]
	v_mfma_f32_16x16x32_bf16 v[68:71], v[206:209], v[196:199], v[68:71]
	v_mfma_f32_16x16x32_bf16 v[64:67], v[214:217], v[196:199], v[64:67]
	s_setprio 0
	s_mov_b32 m0, s31
	s_mov_b64 s[0:1], 0x80
	v_lshl_add_u64 v[218:219], v[222:223], 0, s[0:1]
	s_barrier
	ds_read_b128 v[162:165], v169 offset:49152
	ds_read_b128 v[172:175], v169 offset:50176
	ds_read_b128 v[176:179], v169 offset:51200
	ds_read_b128 v[180:183], v169 offset:52224
	ds_read_b128 v[184:187], v169 offset:53248
	ds_read_b128 v[188:191], v169 offset:54272
	ds_read_b128 v[192:195], v169 offset:55296
	ds_read_b128 v[196:199], v169 offset:56320
	global_load_lds_dwordx4 v[218:219], off
	v_lshl_add_u64 v[218:219], v[224:225], 0, s[0:1]
	s_mov_b32 m0, s33
	s_nop 0
	global_load_lds_dwordx4 v[218:219], off
	s_barrier
; #define PG8_STAGE(bufoff, gbase, voff) do { _Pragma("unroll") for (int _i = 0; _i < 2; ++_i) \
;         __builtin_amdgcn_global_load_lds((const unsigned*)((const char*)(gbase) + (voff)[_i]), (LAS unsigned*)(lds + (bufoff) + ldsw + _i * 8192), 16, 0, 0); } while (0)
; #define PG8_LDA(dst, b, h) do { _Pragma("unroll") for (int m = 0; m < 4; ++m) _Pragma("unroll") for (int k = 0; k < 2; ++k) dst[m][k] = *(const LAS bf16x8*)(lds + PG8_SA(b, h) + aoff + m * 2048 + k * 1024); } while (0)
; #define PG8_LDB(dst, b, h) do { _Pragma("unroll") for (int n = 0; n < 2; ++n) _Pragma("unroll") for (int k = 0; k < 2; ++k) dst[n][k] = *(const LAS bf16x8*)(lds + PG8_SB(b, h) + boff + n * 2048 + k * 1024); } while (0)
; #define PG8_MMA(ai, bj, At, Bt) do { __builtin_amdgcn_s_setprio(1); _Pragma("unroll") for (int m = 0; m < 4; ++m) _Pragma("unroll") for (int n = 0; n < 2; ++n) _Pragma("unroll") for (int k = 0; k < 2; ++k) \
;         acc[ai][bj][m][n] = __builtin_amdgcn_mfma_f32_16x16x32_bf16(Bt[n][k], At[m][k], acc[ai][bj][m][n], 0, 0, 0); __builtin_amdgcn_s_setprio(0); } while (0)
; #define PG8_WAIT_V(n) asm volatile("s_waitcnt vmcnt(" #n ")" ::: "memory")
; #define PG8_WAIT_L(n) asm volatile("s_waitcnt lgkmcnt(" #n ")" ::: "memory")
; #define PG8_BAR __builtin_amdgcn_s_barrier()
; #define PG8_SCHED __builtin_amdgcn_sched_barrier(0)
; template <class Epi, class Sched>
; __device__ __forceinline__ void gemm_phase(LAS unsigned char* lds, const Gemm g, const Sched& S, const Epi& E) {
;     ...
;             PG8_LDB(B0, 0, 0); PG8_SCHED; PG8_LDA(At, 0, 0); PG8_STAGE(PG8_SA(1, 1), a1 + hstep, voffA);
;             PG8_WAIT_L(8); PG8_BAR; PG8_WAIT_L(0); PG8_MMA(0, 0, At, B0); PG8_BAR; PG8_SCHED;
;             PG8_LDB(B1, 0, 1); PG8_STAGE(PG8_SB(0, 0), b2, voffB);
;             PG8_BAR; PG8_WAIT_L(0); PG8_MMA(0, 1, At, B1); PG8_BAR;
;             PG8_LDA(At, 0, 1); PG8_STAGE(PG8_SA(0, 0), a2, voffA);
;             PG8_BAR; PG8_WAIT_L(0); PG8_MMA(1, 0, At, B0); PG8_BAR; PG8_SCHED;
;     ...
;             PG8_BAR; PG8_WAIT_L(0); PG8_MMA(1, 0, At, B0); PG8_BAR; PG8_SCHED;
;             PG8_STAGE(PG8_SB(1, 1), b3 + hstep, voffB);
;             PG8_WAIT_V(6); PG8_BAR; PG8_MMA(1, 1, At, B1); PG8_BAR;
	s_waitcnt lgkmcnt(0)
	s_setprio 1
	s_waitcnt lgkmcnt(0)
	v_mfma_f32_16x16x32_bf16 v[60:63], v[128:131], v[162:165], v[60:63]
	v_mfma_f32_16x16x32_bf16 v[56:59], v[136:139], v[162:165], v[56:59]
	v_mfma_f32_16x16x32_bf16 v[48:51], v[128:131], v[176:179], v[48:51]
	v_mfma_f32_16x16x32_bf16 v[40:43], v[136:139], v[176:179], v[40:43]
	v_mfma_f32_16x16x32_bf16 v[32:35], v[128:131], v[184:187], v[32:35]
	v_mfma_f32_16x16x32_bf16 v[24:27], v[136:139], v[184:187], v[24:27]
	v_mfma_f32_16x16x32_bf16 v[16:19], v[128:131], v[192:195], v[16:19]
	v_mfma_f32_16x16x32_bf16 v[8:11], v[136:139], v[192:195], v[8:11]
	v_mfma_f32_16x16x32_bf16 v[60:63], v[132:135], v[172:175], v[60:63]
	v_mfma_f32_16x16x32_bf16 v[56:59], v[140:143], v[172:175], v[56:59]
	v_mfma_f32_16x16x32_bf16 v[48:51], v[132:135], v[180:183], v[48:51]
	v_mfma_f32_16x16x32_bf16 v[40:43], v[140:143], v[180:183], v[40:43]
	v_mfma_f32_16x16x32_bf16 v[32:35], v[132:135], v[188:191], v[32:35]
	v_mfma_f32_16x16x32_bf16 v[24:27], v[140:143], v[188:191], v[24:27]
	v_mfma_f32_16x16x32_bf16 v[16:19], v[132:135], v[196:199], v[16:19]
	v_mfma_f32_16x16x32_bf16 v[8:11], v[140:143], v[196:199], v[8:11]
	s_setprio 0
	s_barrier
	s_add_u32 s16, s16, 0x80080
	s_addc_u32 s17, s17, 0
	s_add_i32 s18, s18, s24
	s_mov_b32 m0, s18
	s_nop 0
	global_load_lds_dwordx4 v146, s[16:17]
	s_add_i32 m0, s18, 0x2000
	s_nop 0
	global_load_lds_dwordx4 v150, s[16:17]
	s_waitcnt vmcnt(10)
	s_barrier
	s_setprio 1
	v_mfma_f32_16x16x32_bf16 v[52:55], v[202:205], v[162:165], v[52:55]
	v_mfma_f32_16x16x32_bf16 v[44:47], v[210:213], v[162:165], v[44:47]
	v_mfma_f32_16x16x32_bf16 v[36:39], v[202:205], v[176:179], v[36:39]
	v_mfma_f32_16x16x32_bf16 v[28:31], v[210:213], v[176:179], v[28:31]
	v_mfma_f32_16x16x32_bf16 v[20:23], v[202:205], v[184:187], v[20:23]
	v_mfma_f32_16x16x32_bf16 v[12:15], v[210:213], v[184:187], v[12:15]
	v_mfma_f32_16x16x32_bf16 v[4:7], v[202:205], v[192:195], v[4:7]
	v_mfma_f32_16x16x32_bf16 v[0:3], v[210:213], v[192:195], v[0:3]
	v_mfma_f32_16x16x32_bf16 v[52:55], v[206:209], v[172:175], v[52:55]
	v_mfma_f32_16x16x32_bf16 v[44:47], v[214:217], v[172:175], v[44:47]
	v_mfma_f32_16x16x32_bf16 v[36:39], v[206:209], v[180:183], v[36:39]
	v_mfma_f32_16x16x32_bf16 v[28:31], v[214:217], v[180:183], v[28:31]
	v_mfma_f32_16x16x32_bf16 v[20:23], v[206:209], v[188:191], v[20:23]
	v_mfma_f32_16x16x32_bf16 v[12:15], v[214:217], v[188:191], v[12:15]
	v_mfma_f32_16x16x32_bf16 v[4:7], v[206:209], v[196:199], v[4:7]
	v_mfma_f32_16x16x32_bf16 v[0:3], v[214:217], v[196:199], v[0:3]
	s_setprio 0
	s_add_i32 s43, s43, 2
	s_add_u32 s14, s14, 0x100
	s_addc_u32 s15, s15, 0
	s_add_u32 s41, s41, 0x100
	s_addc_u32 s42, s42, 0
	s_cmp_gt_u32 s43, 29
	s_barrier
.LBB0_826:
	ds_read_b128 v[128:131], v168
	ds_read_b128 v[132:135], v168 offset:1024
	ds_read_b128 v[136:139], v168 offset:2048
	ds_read_b128 v[140:143], v168 offset:3072
	s_add_u32 s16, s14, 0xfff80080
	s_addc_u32 s17, s15, -1
	s_cmp_eq_u32 s43, 28
	s_cselect_b32 s19, s7, s17
	s_cselect_b32 s18, s39, s16
	s_cselect_b32 s17, s5, s42
	s_cselect_b32 s16, s40, s41
	s_add_i32 m0, s13, 0xc000
	ds_read_b128 v[162:165], v169
	ds_read_b128 v[172:175], v169 offset:1024
	ds_read_b128 v[176:179], v169 offset:2048
	ds_read_b128 v[180:183], v169 offset:3072
	ds_read_b128 v[184:187], v169 offset:4096
	ds_read_b128 v[188:191], v169 offset:5120
	ds_read_b128 v[192:195], v169 offset:6144
	ds_read_b128 v[196:199], v169 offset:7168
	global_load_lds_dwordx4 v152, s[14:15]
	s_add_i32 m0, s13, 0xe000
	s_nop 0
	global_load_lds_dwordx4 v154, s[14:15]
	s_waitcnt vmcnt(10)
	s_barrier
	s_waitcnt lgkmcnt(0)
	s_setprio 1
	s_waitcnt lgkmcnt(0)
	v_mfma_f32_16x16x32_bf16 v[124:127], v[128:131], v[162:165], v[124:127]
	v_mfma_f32_16x16x32_bf16 v[120:123], v[136:139], v[162:165], v[120:123]
	v_mfma_f32_16x16x32_bf16 v[116:119], v[128:131], v[176:179], v[116:119]
	v_mfma_f32_16x16x32_bf16 v[112:115], v[136:139], v[176:179], v[112:115]
	v_mfma_f32_16x16x32_bf16 v[108:111], v[128:131], v[184:187], v[108:111]
	v_mfma_f32_16x16x32_bf16 v[100:103], v[136:139], v[184:187], v[100:103]
	v_mfma_f32_16x16x32_bf16 v[76:79], v[128:131], v[192:195], v[76:79]
	v_mfma_f32_16x16x32_bf16 v[72:75], v[136:139], v[192:195], v[72:75]
	v_mfma_f32_16x16x32_bf16 v[124:127], v[132:135], v[172:175], v[124:127]
	v_mfma_f32_16x16x32_bf16 v[120:123], v[140:143], v[172:175], v[120:123]
	v_mfma_f32_16x16x32_bf16 v[116:119], v[132:135], v[180:183], v[116:119]
	v_mfma_f32_16x16x32_bf16 v[112:115], v[140:143], v[180:183], v[112:115]
	v_mfma_f32_16x16x32_bf16 v[108:111], v[132:135], v[188:191], v[108:111]
	v_mfma_f32_16x16x32_bf16 v[100:103], v[140:143], v[188:191], v[100:103]
	v_mfma_f32_16x16x32_bf16 v[76:79], v[132:135], v[196:199], v[76:79]
	v_mfma_f32_16x16x32_bf16 v[72:75], v[140:143], v[196:199], v[72:75]
	s_setprio 0
	s_barrier
	s_add_i32 s44, s35, s24
	s_mov_b32 m0, s44
	ds_read_b128 v[202:205], v170
	ds_read_b128 v[206:209], v170 offset:1024
	ds_read_b128 v[210:213], v170 offset:2048
	ds_read_b128 v[214:217], v170 offset:3072
	global_load_lds_dwordx4 v146, s[16:17]
	s_add_i32 m0, s44, 0x2000
	s_nop 0
	global_load_lds_dwordx4 v150, s[16:17]
	s_waitcnt vmcnt(10)
	s_barrier
; #define PG8_STAGE(bufoff, gbase, voff) do { _Pragma("unroll") for (int _i = 0; _i < 2; ++_i) \
;         __builtin_amdgcn_global_load_lds((const unsigned*)((const char*)(gbase) + (voff)[_i]), (LAS unsigned*)(lds + (bufoff) + ldsw + _i * 8192), 16, 0, 0); } while (0)
; #define PG8_LDA(dst, b, h) do { _Pragma("unroll") for (int m = 0; m < 4; ++m) _Pragma("unroll") for (int k = 0; k < 2; ++k) dst[m][k] = *(const LAS bf16x8*)(lds + PG8_SA(b, h) + aoff + m * 2048 + k * 1024); } while (0)
; #define PG8_LDB(dst, b, h) do { _Pragma("unroll") for (int n = 0; n < 2; ++n) _Pragma("unroll") for (int k = 0; k < 2; ++k) dst[n][k] = *(const LAS bf16x8*)(lds + PG8_SB(b, h) + boff + n * 2048 + k * 1024); } while (0)
; #define PG8_MMA(ai, bj, At, Bt) do { __builtin_amdgcn_s_setprio(1); _Pragma("unroll") for (int m = 0; m < 4; ++m) _Pragma("unroll") for (int n = 0; n < 2; ++n) _Pragma("unroll") for (int k = 0; k < 2; ++k) \
;         acc[ai][bj][m][n] = __builtin_amdgcn_mfma_f32_16x16x32_bf16(Bt[n][k], At[m][k], acc[ai][bj][m][n], 0, 0, 0); __builtin_amdgcn_s_setprio(0); } while (0)
; #define PG8_WAIT_V(n) asm volatile("s_waitcnt vmcnt(" #n ")" ::: "memory")
; #define PG8_WAIT_L(n) asm volatile("s_waitcnt lgkmcnt(" #n ")" ::: "memory")
; #define PG8_BAR __builtin_amdgcn_s_barrier()
; #define PG8_SCHED __builtin_amdgcn_sched_barrier(0)
; template <class Epi, class Sched>
; __device__ __forceinline__ void gemm_phase(LAS unsigned char* lds, const Gemm g, const Sched& S, const Epi& E) {
;     ...
;             PG8_BAR; PG8_WAIT_L(0); PG8_MMA(1, 0, At, B0); PG8_BAR; PG8_SCHED;
;             PG8_STAGE(PG8_SB(0, 1), b2 + hstep, voffB);
;             PG8_WAIT_V(6); PG8_BAR; PG8_MMA(1, 1, At, B1); PG8_BAR;
;             PG8_LDB(B0, 1, 0); PG8_SCHED; PG8_LDA(At, 1, 0); PG8_STAGE(PG8_SA(0, 1), a2 + hstep, voffA);
;             PG8_WAIT_L(8); PG8_BAR; PG8_WAIT_L(0); PG8_MMA(0, 0, At, B0); PG8_BAR; PG8_SCHED;
	s_waitcnt lgkmcnt(0)
	s_setprio 1
	s_waitcnt lgkmcnt(0)
	v_mfma_f32_16x16x32_bf16 v[104:107], v[202:205], v[162:165], v[104:107]
	v_mfma_f32_16x16x32_bf16 v[96:99], v[210:213], v[162:165], v[96:99]
	v_mfma_f32_16x16x32_bf16 v[92:95], v[202:205], v[176:179], v[92:95]
	v_mfma_f32_16x16x32_bf16 v[88:91], v[210:213], v[176:179], v[88:91]
	v_mfma_f32_16x16x32_bf16 v[84:87], v[202:205], v[184:187], v[84:87]
	v_mfma_f32_16x16x32_bf16 v[80:83], v[210:213], v[184:187], v[80:83]
	v_mfma_f32_16x16x32_bf16 v[68:71], v[202:205], v[192:195], v[68:71]
	v_mfma_f32_16x16x32_bf16 v[64:67], v[210:213], v[192:195], v[64:67]
	v_mfma_f32_16x16x32_bf16 v[104:107], v[206:209], v[172:175], v[104:107]
	v_mfma_f32_16x16x32_bf16 v[96:99], v[214:217], v[172:175], v[96:99]
	v_mfma_f32_16x16x32_bf16 v[92:95], v[206:209], v[180:183], v[92:95]
	v_mfma_f32_16x16x32_bf16 v[88:91], v[214:217], v[180:183], v[88:91]
	v_mfma_f32_16x16x32_bf16 v[84:87], v[206:209], v[188:191], v[84:87]
	v_mfma_f32_16x16x32_bf16 v[80:83], v[214:217], v[188:191], v[80:83]
	v_mfma_f32_16x16x32_bf16 v[68:71], v[206:209], v[196:199], v[68:71]
	v_mfma_f32_16x16x32_bf16 v[64:67], v[214:217], v[196:199], v[64:67]
	s_setprio 0
	s_mov_b32 m0, s13
	v_lshl_add_u64 v[222:223], s[18:19], 0, v[144:145]
	s_barrier
	ds_read_b128 v[162:165], v169 offset:16384
	ds_read_b128 v[172:175], v169 offset:17408
	ds_read_b128 v[176:179], v169 offset:18432
	ds_read_b128 v[180:183], v169 offset:19456
	ds_read_b128 v[184:187], v169 offset:20480
	ds_read_b128 v[188:191], v169 offset:21504
	ds_read_b128 v[192:195], v169 offset:22528
	ds_read_b128 v[196:199], v169 offset:23552
	global_load_lds_dwordx4 v144, s[18:19]
	v_lshl_add_u64 v[224:225], s[18:19], 0, v[148:149]
	s_mov_b32 m0, s25
	s_nop 0
	global_load_lds_dwordx4 v148, s[18:19]
	s_barrier
	s_waitcnt lgkmcnt(0)
	s_setprio 1
	s_waitcnt lgkmcnt(0)
	v_mfma_f32_16x16x32_bf16 v[60:63], v[128:131], v[162:165], v[60:63]
	v_mfma_f32_16x16x32_bf16 v[56:59], v[136:139], v[162:165], v[56:59]
	v_mfma_f32_16x16x32_bf16 v[48:51], v[128:131], v[176:179], v[48:51]
	v_mfma_f32_16x16x32_bf16 v[40:43], v[136:139], v[176:179], v[40:43]
	v_mfma_f32_16x16x32_bf16 v[32:35], v[128:131], v[184:187], v[32:35]
	v_mfma_f32_16x16x32_bf16 v[24:27], v[136:139], v[184:187], v[24:27]
	v_mfma_f32_16x16x32_bf16 v[16:19], v[128:131], v[192:195], v[16:19]
	v_mfma_f32_16x16x32_bf16 v[8:11], v[136:139], v[192:195], v[8:11]
	v_mfma_f32_16x16x32_bf16 v[60:63], v[132:135], v[172:175], v[60:63]
	v_mfma_f32_16x16x32_bf16 v[56:59], v[140:143], v[172:175], v[56:59]
	v_mfma_f32_16x16x32_bf16 v[48:51], v[132:135], v[180:183], v[48:51]
	v_mfma_f32_16x16x32_bf16 v[40:43], v[140:143], v[180:183], v[40:43]
	v_mfma_f32_16x16x32_bf16 v[32:35], v[132:135], v[188:191], v[32:35]
	v_mfma_f32_16x16x32_bf16 v[24:27], v[140:143], v[188:191], v[24:27]
	v_mfma_f32_16x16x32_bf16 v[16:19], v[132:135], v[196:199], v[16:19]
	v_mfma_f32_16x16x32_bf16 v[8:11], v[140:143], v[196:199], v[8:11]
	s_setprio 0
	s_barrier
	s_add_u32 s44, s16, 0x80000
	s_addc_u32 s45, s17, 0
	s_add_i32 s46, s36, s24
	s_mov_b32 m0, s46
	s_nop 0
	global_load_lds_dwordx4 v146, s[44:45]
	s_add_i32 m0, s46, 0x2000
	s_nop 0
	global_load_lds_dwordx4 v150, s[44:45]
	s_add_u32 s18, s18, 0x80000
	s_addc_u32 s19, s19, 0
	s_mov_b32 m0, s26
	s_nop 0
	global_load_lds_dwordx4 v144, s[18:19]
	s_mov_b32 m0, s27
	s_nop 0
	global_load_lds_dwordx4 v148, s[18:19]
	s_waitcnt vmcnt(12)
	s_barrier
	s_setprio 1
	v_mfma_f32_16x16x32_bf16 v[52:55], v[202:205], v[162:165], v[52:55]
	v_mfma_f32_16x16x32_bf16 v[44:47], v[210:213], v[162:165], v[44:47]
	v_mfma_f32_16x16x32_bf16 v[36:39], v[202:205], v[176:179], v[36:39]
	v_mfma_f32_16x16x32_bf16 v[28:31], v[210:213], v[176:179], v[28:31]
	v_mfma_f32_16x16x32_bf16 v[20:23], v[202:205], v[184:187], v[20:23]
	v_mfma_f32_16x16x32_bf16 v[12:15], v[210:213], v[184:187], v[12:15]
	v_mfma_f32_16x16x32_bf16 v[4:7], v[202:205], v[192:195], v[4:7]
	v_mfma_f32_16x16x32_bf16 v[0:3], v[210:213], v[192:195], v[0:3]
	v_mfma_f32_16x16x32_bf16 v[52:55], v[206:209], v[172:175], v[52:55]
	v_mfma_f32_16x16x32_bf16 v[44:47], v[214:217], v[172:175], v[44:47]
	v_mfma_f32_16x16x32_bf16 v[36:39], v[206:209], v[180:183], v[36:39]
	v_mfma_f32_16x16x32_bf16 v[28:31], v[214:217], v[180:183], v[28:31]
	v_mfma_f32_16x16x32_bf16 v[20:23], v[206:209], v[188:191], v[20:23]
	v_mfma_f32_16x16x32_bf16 v[12:15], v[214:217], v[188:191], v[12:15]
	v_mfma_f32_16x16x32_bf16 v[4:7], v[206:209], v[196:199], v[4:7]
	v_mfma_f32_16x16x32_bf16 v[0:3], v[214:217], v[196:199], v[0:3]
	s_setprio 0
	s_add_i32 s44, 0, 0x18000
	v_add_u32_e32 v140, s44, v167
	s_barrier
	ds_read_b128 v[128:131], v140
	ds_read_b128 v[132:135], v140 offset:1024
	ds_read_b128 v[136:139], v140 offset:2048
	ds_read_b128 v[140:143], v140 offset:3072
	ds_read_b128 v[162:165], v169 offset:32768
	ds_read_b128 v[172:175], v169 offset:33792
	ds_read_b128 v[176:179], v169 offset:34816
	ds_read_b128 v[180:183], v169 offset:35840
	ds_read_b128 v[184:187], v169 offset:36864
	ds_read_b128 v[188:191], v169 offset:37888
	ds_read_b128 v[192:195], v169 offset:38912
	ds_read_b128 v[196:199], v169 offset:39936
	s_waitcnt vmcnt(10)
	s_barrier
; #define PG8_STAGE(bufoff, gbase, voff) do { _Pragma("unroll") for (int _i = 0; _i < 2; ++_i) \
;         __builtin_amdgcn_global_load_lds((const unsigned*)((const char*)(gbase) + (voff)[_i]), (LAS unsigned*)(lds + (bufoff) + ldsw + _i * 8192), 16, 0, 0); } while (0)
; #define PG8_LDA(dst, b, h) do { _Pragma("unroll") for (int m = 0; m < 4; ++m) _Pragma("unroll") for (int k = 0; k < 2; ++k) dst[m][k] = *(const LAS bf16x8*)(lds + PG8_SA(b, h) + aoff + m * 2048 + k * 1024); } while (0)
; #define PG8_LDB(dst, b, h) do { _Pragma("unroll") for (int n = 0; n < 2; ++n) _Pragma("unroll") for (int k = 0; k < 2; ++k) dst[n][k] = *(const LAS bf16x8*)(lds + PG8_SB(b, h) + boff + n * 2048 + k * 1024); } while (0)
; #define PG8_MMA(ai, bj, At, Bt) do { __builtin_amdgcn_s_setprio(1); _Pragma("unroll") for (int m = 0; m < 4; ++m) _Pragma("unroll") for (int n = 0; n < 2; ++n) _Pragma("unroll") for (int k = 0; k < 2; ++k) \
;         acc[ai][bj][m][n] = __builtin_amdgcn_mfma_f32_16x16x32_bf16(Bt[n][k], At[m][k], acc[ai][bj][m][n], 0, 0, 0); __builtin_amdgcn_s_setprio(0); } while (0)
; #define PG8_WAIT_V(n) asm volatile("s_waitcnt vmcnt(" #n ")" ::: "memory")
; #define PG8_WAIT_L(n) asm volatile("s_waitcnt lgkmcnt(" #n ")" ::: "memory")
; #define PG8_BAR __builtin_amdgcn_s_barrier()
; #define PG8_SCHED __builtin_amdgcn_sched_barrier(0)
; template <class Epi, class Sched>
; __device__ __forceinline__ void gemm_phase(LAS unsigned char* lds, const Gemm g, const Sched& S, const Epi& E) {
;     ...
;             PG8_WAIT_L(8); PG8_BAR; PG8_WAIT_L(0); PG8_MMA(0, 0, At, B0); PG8_BAR; PG8_SCHED;
;             PG8_LDB(B1, 1, 1); PG8_STAGE(PG8_SB(1, 0), b3, voffB);
;             PG8_BAR; PG8_WAIT_L(0); PG8_MMA(0, 1, At, B1); PG8_BAR;
;             PG8_LDA(At, 1, 1); PG8_STAGE(PG8_SA(1, 0), a3, voffA);
;             PG8_BAR; PG8_WAIT_L(0); PG8_MMA(1, 0, At, B0); PG8_BAR; PG8_SCHED;
;             PG8_STAGE(PG8_SB(1, 1), b3 + hstep, voffB);
;             PG8_WAIT_V(6); PG8_BAR; PG8_MMA(1, 1, At, B1); PG8_BAR;
	s_waitcnt lgkmcnt(0)
	s_setprio 1
	s_waitcnt lgkmcnt(0)
	v_mfma_f32_16x16x32_bf16 v[124:127], v[128:131], v[162:165], v[124:127]
	v_mfma_f32_16x16x32_bf16 v[120:123], v[136:139], v[162:165], v[120:123]
	v_mfma_f32_16x16x32_bf16 v[116:119], v[128:131], v[176:179], v[116:119]
	v_mfma_f32_16x16x32_bf16 v[112:115], v[136:139], v[176:179], v[112:115]
	v_mfma_f32_16x16x32_bf16 v[108:111], v[128:131], v[184:187], v[108:111]
	v_mfma_f32_16x16x32_bf16 v[100:103], v[136:139], v[184:187], v[100:103]
	v_mfma_f32_16x16x32_bf16 v[76:79], v[128:131], v[192:195], v[76:79]
	v_mfma_f32_16x16x32_bf16 v[72:75], v[136:139], v[192:195], v[72:75]
	v_mfma_f32_16x16x32_bf16 v[124:127], v[132:135], v[172:175], v[124:127]
	v_mfma_f32_16x16x32_bf16 v[120:123], v[140:143], v[172:175], v[120:123]
	v_mfma_f32_16x16x32_bf16 v[116:119], v[132:135], v[180:183], v[116:119]
	v_mfma_f32_16x16x32_bf16 v[112:115], v[140:143], v[180:183], v[112:115]
	v_mfma_f32_16x16x32_bf16 v[108:111], v[132:135], v[188:191], v[108:111]
	v_mfma_f32_16x16x32_bf16 v[100:103], v[140:143], v[188:191], v[100:103]
	v_mfma_f32_16x16x32_bf16 v[76:79], v[132:135], v[196:199], v[76:79]
	v_mfma_f32_16x16x32_bf16 v[72:75], v[140:143], v[196:199], v[72:75]
	s_setprio 0
	s_barrier
	s_add_i32 s18, 0, 0x1c000
	s_add_i32 s19, s44, s24
	v_add_u32_e32 v160, s18, v167
	s_add_u32 s0, s16, 0x80
	s_addc_u32 s1, s17, 0
	s_mov_b32 m0, s19
	ds_read_b128 v[202:205], v160
	ds_read_b128 v[206:209], v160 offset:1024
	ds_read_b128 v[210:213], v160 offset:2048
	ds_read_b128 v[214:217], v160 offset:3072
	global_load_lds_dwordx4 v146, s[0:1]
	s_add_i32 m0, s19, 0x2000
	s_nop 0
	global_load_lds_dwordx4 v150, s[0:1]
	s_waitcnt vmcnt(10)
	s_barrier
	s_waitcnt lgkmcnt(0)
	s_setprio 1
	s_waitcnt lgkmcnt(0)
	v_mfma_f32_16x16x32_bf16 v[104:107], v[202:205], v[162:165], v[104:107]
	v_mfma_f32_16x16x32_bf16 v[96:99], v[210:213], v[162:165], v[96:99]
	v_mfma_f32_16x16x32_bf16 v[92:95], v[202:205], v[176:179], v[92:95]
	v_mfma_f32_16x16x32_bf16 v[88:91], v[210:213], v[176:179], v[88:91]
	v_mfma_f32_16x16x32_bf16 v[84:87], v[202:205], v[184:187], v[84:87]
	v_mfma_f32_16x16x32_bf16 v[80:83], v[210:213], v[184:187], v[80:83]
	v_mfma_f32_16x16x32_bf16 v[68:71], v[202:205], v[192:195], v[68:71]
	v_mfma_f32_16x16x32_bf16 v[64:67], v[210:213], v[192:195], v[64:67]
	v_mfma_f32_16x16x32_bf16 v[104:107], v[206:209], v[172:175], v[104:107]
	v_mfma_f32_16x16x32_bf16 v[96:99], v[214:217], v[172:175], v[96:99]
	v_mfma_f32_16x16x32_bf16 v[92:95], v[206:209], v[180:183], v[92:95]
	v_mfma_f32_16x16x32_bf16 v[88:91], v[214:217], v[180:183], v[88:91]
	v_mfma_f32_16x16x32_bf16 v[84:87], v[206:209], v[188:191], v[84:87]
	v_mfma_f32_16x16x32_bf16 v[80:83], v[214:217], v[188:191], v[80:83]
	v_mfma_f32_16x16x32_bf16 v[68:71], v[206:209], v[196:199], v[68:71]
	v_mfma_f32_16x16x32_bf16 v[64:67], v[214:217], v[196:199], v[64:67]
	s_setprio 0
	s_mov_b32 m0, s31
	s_mov_b64 s[0:1], 0x80
	v_lshl_add_u64 v[218:219], v[222:223], 0, s[0:1]
	s_barrier
	ds_read_b128 v[162:165], v169 offset:49152
	ds_read_b128 v[172:175], v169 offset:50176
	ds_read_b128 v[176:179], v169 offset:51200
	ds_read_b128 v[180:183], v169 offset:52224
	ds_read_b128 v[184:187], v169 offset:53248
	ds_read_b128 v[188:191], v169 offset:54272
	ds_read_b128 v[192:195], v169 offset:55296
	ds_read_b128 v[196:199], v169 offset:56320
	global_load_lds_dwordx4 v[218:219], off
	v_lshl_add_u64 v[218:219], v[224:225], 0, s[0:1]
	s_mov_b32 m0, s33
	s_nop 0
	global_load_lds_dwordx4 v[218:219], off
	s_barrier
	s_waitcnt lgkmcnt(0)
	s_setprio 1
	s_waitcnt lgkmcnt(0)
	v_mfma_f32_16x16x32_bf16 v[60:63], v[128:131], v[162:165], v[60:63]
	v_mfma_f32_16x16x32_bf16 v[56:59], v[136:139], v[162:165], v[56:59]
	v_mfma_f32_16x16x32_bf16 v[48:51], v[128:131], v[176:179], v[48:51]
	v_mfma_f32_16x16x32_bf16 v[40:43], v[136:139], v[176:179], v[40:43]
	v_mfma_f32_16x16x32_bf16 v[32:35], v[128:131], v[184:187], v[32:35]
	v_mfma_f32_16x16x32_bf16 v[24:27], v[136:139], v[184:187], v[24:27]
	v_mfma_f32_16x16x32_bf16 v[16:19], v[128:131], v[192:195], v[16:19]
	v_mfma_f32_16x16x32_bf16 v[8:11], v[136:139], v[192:195], v[8:11]
	v_mfma_f32_16x16x32_bf16 v[60:63], v[132:135], v[172:175], v[60:63]
	v_mfma_f32_16x16x32_bf16 v[56:59], v[140:143], v[172:175], v[56:59]
	v_mfma_f32_16x16x32_bf16 v[48:51], v[132:135], v[180:183], v[48:51]
	v_mfma_f32_16x16x32_bf16 v[40:43], v[140:143], v[180:183], v[40:43]
	v_mfma_f32_16x16x32_bf16 v[32:35], v[132:135], v[188:191], v[32:35]
	v_mfma_f32_16x16x32_bf16 v[24:27], v[140:143], v[188:191], v[24:27]
	v_mfma_f32_16x16x32_bf16 v[16:19], v[132:135], v[196:199], v[16:19]
	v_mfma_f32_16x16x32_bf16 v[8:11], v[140:143], v[196:199], v[8:11]
	s_setprio 0
	s_barrier
	s_add_u32 s16, s16, 0x80080
	s_addc_u32 s17, s17, 0
	s_add_i32 s18, s18, s24
	s_mov_b32 m0, s18
	s_nop 0
	global_load_lds_dwordx4 v146, s[16:17]
	s_add_i32 m0, s18, 0x2000
	s_nop 0
	global_load_lds_dwordx4 v150, s[16:17]
	s_waitcnt vmcnt(10)
	s_barrier
	s_setprio 1
	v_mfma_f32_16x16x32_bf16 v[52:55], v[202:205], v[162:165], v[52:55]
	v_mfma_f32_16x16x32_bf16 v[44:47], v[210:213], v[162:165], v[44:47]
	v_mfma_f32_16x16x32_bf16 v[36:39], v[202:205], v[176:179], v[36:39]
	v_mfma_f32_16x16x32_bf16 v[28:31], v[210:213], v[176:179], v[28:31]
	v_mfma_f32_16x16x32_bf16 v[20:23], v[202:205], v[184:187], v[20:23]
	v_mfma_f32_16x16x32_bf16 v[12:15], v[210:213], v[184:187], v[12:15]
	v_mfma_f32_16x16x32_bf16 v[4:7], v[202:205], v[192:195], v[4:7]
	v_mfma_f32_16x16x32_bf16 v[0:3], v[210:213], v[192:195], v[0:3]
	v_mfma_f32_16x16x32_bf16 v[52:55], v[206:209], v[172:175], v[52:55]
	v_mfma_f32_16x16x32_bf16 v[44:47], v[214:217], v[172:175], v[44:47]
	v_mfma_f32_16x16x32_bf16 v[36:39], v[206:209], v[180:183], v[36:39]
	v_mfma_f32_16x16x32_bf16 v[28:31], v[214:217], v[180:183], v[28:31]
	v_mfma_f32_16x16x32_bf16 v[20:23], v[206:209], v[188:191], v[20:23]
	v_mfma_f32_16x16x32_bf16 v[12:15], v[214:217], v[188:191], v[12:15]
	v_mfma_f32_16x16x32_bf16 v[4:7], v[206:209], v[196:199], v[4:7]
	v_mfma_f32_16x16x32_bf16 v[0:3], v[214:217], v[196:199], v[0:3]
	s_setprio 0
	s_add_i32 s43, s43, 2
	s_add_u32 s14, s14, 0x100
	s_addc_u32 s15, s15, 0
	s_add_u32 s41, s41, 0x100
	s_addc_u32 s42, s42, 0
	s_cmp_gt_u32 s43, 29
	s_barrier
; __device__ __forceinline__ unsigned cvt_pk_bf16(float lo, float hi) { unsigned r; asm volatile("v_cvt_pk_bf16_f32 %0, %1, %2" : "=v"(r) : "v"(lo), "v"(hi)); return r; }
;     __device__ __forceinline__ void operator()(const AccT& acc, const Unit& u, int wr, int wc, int fr, int fq) const {
;     ...
;         const int row0 = u.pm * 256 + wr * 64 + fr; const int b = u.pn >> 1, ch0 = (u.pn & 1) * 256 + wc * 32 + 8 * fq;
;         const float sg = (fr & 1) ? -1.0f : 1.0f;
;         f32x4 yh[2][2];
; #pragma unroll
;         for (int bj = 0; bj < 2; ++bj)
; #pragma unroll
;             for (int n = 0; n < 2; ++n) yh[bj][n] = *(const f32x4*)(YCH + b * 512 + ch0 + bj * 128 + 4 * n) * sg;
; #pragma unroll
;         for (int ai = 0; ai < 2; ++ai)
; #pragma unroll
;             for (int m = 0; m < 4; ++m) {
;                 const int k = row0 + ai * 128 + m * 16;
; #pragma unroll
;                 for (int bj = 0; bj < 2; ++bj) {
;                     const f32x4 v0 = acc[ai][bj][m][0] + yh[bj][0], v1 = acc[ai][bj][m][1] + yh[bj][1];
;                     u32x4 w; w.x = cvt_pk_bf16(v0[0], v0[1]); w.y = cvt_pk_bf16(v0[2], v0[3]); w.z = cvt_pk_bf16(v1[0], v1[1]); w.w = cvt_pk_bf16(v1[2], v1[3]);
;                     *(u32x4*)(CAT + (size_t)(b * 2048 + k) * CATW + 1024 + ch0 + bj * 128) = w;
;                 }
	s_cbranch_scc0 .LBB0_826
	s_ashr_i32 s5, s38, 1
	s_lshl_b32 s7, s38, 8
	s_lshl_b32 s14, s5, 9
	s_and_b32 s7, s7, 0x100
	s_ashr_i32 s15, s14, 31
	v_mov_b32_e32 v171, v161
	v_mov_b32_e32 v128, v166
	s_or_b32 s7, s7, s30
	s_lshl_b64 s[14:15], s[14:15], 2
	s_add_u32 s14, s48, s14
	v_lshl_add_u32 v164, v128, 3, s7
	s_addc_u32 s15, s49, s15
	v_ashrrev_i32_e32 v165, 31, v164
	v_lshl_add_u64 v[128:129], v[164:165], 2, s[14:15]
	global_load_dwordx4 v[140:143], v[128:129], off
	global_load_dwordx4 v[136:139], v[128:129], off offset:16
	global_load_dwordx4 v[132:135], v[128:129], off offset:512
	s_nop 0
	global_load_dwordx4 v[128:131], v[128:129], off offset:528
	s_lshl_b32 s7, s12, 8
	s_lshl_b32 s5, s5, 11
	s_add_i32 s7, s7, s29
	v_and_b32_e32 v160, 1, v171
	s_add_i32 s7, s7, s5
	v_mov_b64_e32 v[162:163], s[96:97]
	v_cmp_eq_u32_e32 vcc, 0, v160
	v_add_u32_e32 v171, s7, v171
	v_lshlrev_b64 v[164:165], 1, v[164:165]
	v_cndmask_b32_e64 v160, -1.0, 1.0, vcc
	v_mad_i64_i32 v[172:173], s[14:15], v171, s37, v[162:163]
	v_add_u32_e32 v174, 16, v171
	v_lshl_add_u64 v[172:173], v[172:173], 0, v[164:165]
	v_mad_i64_i32 v[174:175], s[14:15], v174, s37, v[162:163]
	v_add_u32_e32 v176, 32, v171
	v_lshl_add_u64 v[174:175], v[174:175], 0, v[164:165]
	v_mad_i64_i32 v[176:177], s[14:15], v176, s37, v[162:163]
	v_lshl_add_u64 v[176:177], v[176:177], 0, v[164:165]
	v_add_u32_e32 v182, 48, v171
	s_and_b64 vcc, exec, s[2:3]
	s_mov_b32 s38, s4
	s_mov_b32 s12, s6
	s_mov_b64 s[16:17], s[10:11]
	s_waitcnt vmcnt(0)
	v_pk_fma_f32 v[126:127], v[142:143], v[160:161], v[126:127] op_sel_hi:[1,0,1]
	v_pk_fma_f32 v[124:125], v[140:141], v[160:161], v[124:125] op_sel_hi:[1,0,1]
	v_pk_fma_f32 v[122:123], v[138:139], v[160:161], v[122:123] op_sel_hi:[1,0,1]
	v_pk_fma_f32 v[180:181], v[128:129], v[160:161], v[80:81] op_sel_hi:[1,0,1]
	v_cvt_pk_bf16_f32 v80, v124, v125
	v_cvt_pk_bf16_f32 v81, v126, v127
	v_pk_fma_f32 v[120:121], v[136:137], v[160:161], v[120:121] op_sel_hi:[1,0,1]
	v_pk_fma_f32 v[106:107], v[134:135], v[160:161], v[106:107] op_sel_hi:[1,0,1]
	v_pk_fma_f32 v[104:105], v[132:133], v[160:161], v[104:105] op_sel_hi:[1,0,1]
	v_pk_fma_f32 v[178:179], v[130:131], v[160:161], v[82:83] op_sel_hi:[1,0,1]
	v_cvt_pk_bf16_f32 v82, v120, v121
	v_cvt_pk_bf16_f32 v83, v122, v123
	global_store_dwordx4 v[172:173], v[80:83], off offset:2048
	v_pk_fma_f32 v[98:99], v[130:131], v[160:161], v[98:99] op_sel_hi:[1,0,1]
	v_pk_fma_f32 v[96:97], v[128:129], v[160:161], v[96:97] op_sel_hi:[1,0,1]
	v_cvt_pk_bf16_f32 v80, v104, v105
	v_cvt_pk_bf16_f32 v81, v106, v107
	v_pk_fma_f32 v[118:119], v[142:143], v[160:161], v[118:119] op_sel_hi:[1,0,1]
	v_pk_fma_f32 v[116:117], v[140:141], v[160:161], v[116:117] op_sel_hi:[1,0,1]
	v_cvt_pk_bf16_f32 v82, v96, v97
	v_cvt_pk_bf16_f32 v83, v98, v99
	global_store_dwordx4 v[172:173], v[80:83], off offset:2304
	v_pk_fma_f32 v[114:115], v[138:139], v[160:161], v[114:115] op_sel_hi:[1,0,1]
	v_pk_fma_f32 v[112:113], v[136:137], v[160:161], v[112:113] op_sel_hi:[1,0,1]
	v_cvt_pk_bf16_f32 v80, v116, v117
	v_cvt_pk_bf16_f32 v81, v118, v119
	v_pk_fma_f32 v[94:95], v[134:135], v[160:161], v[94:95] op_sel_hi:[1,0,1]
	v_pk_fma_f32 v[92:93], v[132:133], v[160:161], v[92:93] op_sel_hi:[1,0,1]
	v_cvt_pk_bf16_f32 v82, v112, v113
	v_cvt_pk_bf16_f32 v83, v114, v115
	global_store_dwordx4 v[174:175], v[80:83], off offset:2048
	v_pk_fma_f32 v[90:91], v[130:131], v[160:161], v[90:91] op_sel_hi:[1,0,1]
	v_pk_fma_f32 v[88:89], v[128:129], v[160:161], v[88:89] op_sel_hi:[1,0,1]
	v_cvt_pk_bf16_f32 v80, v92, v93
	v_cvt_pk_bf16_f32 v81, v94, v95
	v_pk_fma_f32 v[110:111], v[142:143], v[160:161], v[110:111] op_sel_hi:[1,0,1]
	v_pk_fma_f32 v[108:109], v[140:141], v[160:161], v[108:109] op_sel_hi:[1,0,1]
	v_cvt_pk_bf16_f32 v82, v88, v89
	v_cvt_pk_bf16_f32 v83, v90, v91
	global_store_dwordx4 v[174:175], v[80:83], off offset:2304
	v_pk_fma_f32 v[102:103], v[138:139], v[160:161], v[102:103] op_sel_hi:[1,0,1]
	v_pk_fma_f32 v[100:101], v[136:137], v[160:161], v[100:101] op_sel_hi:[1,0,1]
	v_cvt_pk_bf16_f32 v80, v108, v109
	v_cvt_pk_bf16_f32 v81, v110, v111
	v_pk_fma_f32 v[86:87], v[134:135], v[160:161], v[86:87] op_sel_hi:[1,0,1]
	v_pk_fma_f32 v[84:85], v[132:133], v[160:161], v[84:85] op_sel_hi:[1,0,1]
	v_cvt_pk_bf16_f32 v82, v100, v101
	v_cvt_pk_bf16_f32 v83, v102, v103
	global_store_dwordx4 v[176:177], v[80:83], off offset:2048
	v_pk_fma_f32 v[76:77], v[140:141], v[160:161], v[76:77] op_sel_hi:[1,0,1]
	v_pk_fma_f32 v[78:79], v[142:143], v[160:161], v[78:79] op_sel_hi:[1,0,1]
	v_cvt_pk_bf16_f32 v80, v84, v85
	v_cvt_pk_bf16_f32 v81, v86, v87
	v_cvt_pk_bf16_f32 v82, v180, v181
	v_cvt_pk_bf16_f32 v83, v178, v179
	global_store_dwordx4 v[176:177], v[80:83], off offset:2304
	v_pk_fma_f32 v[70:71], v[134:135], v[160:161], v[70:71] op_sel_hi:[1,0,1]
	v_pk_fma_f32 v[68:69], v[132:133], v[160:161], v[68:69] op_sel_hi:[1,0,1]
	v_pk_fma_f32 v[80:81], v[138:139], v[160:161], v[74:75] op_sel_hi:[1,0,1]
	v_pk_fma_f32 v[74:75], v[136:137], v[160:161], v[72:73] op_sel_hi:[1,0,1]
	v_cvt_pk_bf16_f32 v72, v76, v77
	v_mad_i64_i32 v[76:77], s[14:15], v182, s37, v[162:163]
	v_cvt_pk_bf16_f32 v73, v78, v79
; __device__ __forceinline__ unsigned cvt_pk_bf16(float lo, float hi) { unsigned r; asm volatile("v_cvt_pk_bf16_f32 %0, %1, %2" : "=v"(r) : "v"(lo), "v"(hi)); return r; }
; #define PG8_WAIT_V(n) asm volatile("s_waitcnt vmcnt(" #n ")" ::: "memory")
; #define PG8_BAR __builtin_amdgcn_s_barrier()
; template <class Epi, class Sched>
; __device__ __forceinline__ void gemm_phase(LAS unsigned char* lds, const Gemm g, const Sched& S, const Epi& E) {
;     ...
;         if (!has_next) break;
; #pragma unroll
;         for (int a = 0; a < 2; ++a)
; #pragma unroll
;             for (int b = 0; b < 2; ++b)
; #pragma unroll
;                 for (int m = 0; m < 4; ++m)
; #pragma unroll
;                     for (int n = 0; n < 2; ++n) acc[a][b][m][n] = (f32x4){0.f, 0.f, 0.f, 0.f};
;         cur = nxt; cA = nA; cB = nB; ++ui;
;     }
;     PG8_WAIT_V(0);
;     if (wr == 0) PG8_BAR;
;     PG8_BAR;
;     __device__ __forceinline__ void operator()(const AccT& acc, const Unit& u, int wr, int wc, int fr, int fq) const {
;     ...
; #pragma unroll
;         for (int ai = 0; ai < 2; ++ai)
; #pragma unroll
;             for (int m = 0; m < 4; ++m) {
;                 const int k = row0 + ai * 128 + m * 16;
; #pragma unroll
;                 for (int bj = 0; bj < 2; ++bj) {
;                     const f32x4 v0 = acc[ai][bj][m][0] + yh[bj][0], v1 = acc[ai][bj][m][1] + yh[bj][1];
;                     u32x4 w; w.x = cvt_pk_bf16(v0[0], v0[1]); w.y = cvt_pk_bf16(v0[2], v0[3]); w.z = cvt_pk_bf16(v1[0], v1[1]); w.w = cvt_pk_bf16(v1[2], v1[3]);
;                     *(u32x4*)(CAT + (size_t)(b * 2048 + k) * CATW + 1024 + ch0 + bj * 128) = w;
;                 }
	v_lshl_add_u64 v[76:77], v[76:77], 0, v[164:165]
	v_cvt_pk_bf16_f32 v74, v74, v75
	v_cvt_pk_bf16_f32 v75, v80, v81
	global_store_dwordx4 v[76:77], v[72:75], off offset:2048
	v_pk_fma_f32 v[60:61], v[140:141], v[160:161], v[60:61] op_sel_hi:[1,0,1]
	v_pk_fma_f32 v[62:63], v[142:143], v[160:161], v[62:63] op_sel_hi:[1,0,1]
	v_pk_fma_f32 v[72:73], v[130:131], v[160:161], v[66:67] op_sel_hi:[1,0,1]
	v_pk_fma_f32 v[66:67], v[128:129], v[160:161], v[64:65] op_sel_hi:[1,0,1]
	v_cvt_pk_bf16_f32 v64, v68, v69
	v_cvt_pk_bf16_f32 v65, v70, v71
	v_pk_fma_f32 v[54:55], v[134:135], v[160:161], v[54:55] op_sel_hi:[1,0,1]
	v_cvt_pk_bf16_f32 v66, v66, v67
	v_cvt_pk_bf16_f32 v67, v72, v73
	global_store_dwordx4 v[76:77], v[64:67], off offset:2304
	v_pk_fma_f32 v[52:53], v[132:133], v[160:161], v[52:53] op_sel_hi:[1,0,1]
	v_pk_fma_f32 v[38:39], v[134:135], v[160:161], v[38:39] op_sel_hi:[1,0,1]
	v_add_u32_e32 v66, 0x80, v171
	v_pk_fma_f32 v[64:65], v[138:139], v[160:161], v[58:59] op_sel_hi:[1,0,1]
	v_pk_fma_f32 v[58:59], v[136:137], v[160:161], v[56:57] op_sel_hi:[1,0,1]
	v_cvt_pk_bf16_f32 v56, v60, v61
	v_mad_i64_i32 v[60:61], s[14:15], v66, s37, v[162:163]
	v_cvt_pk_bf16_f32 v57, v62, v63
	v_lshl_add_u64 v[60:61], v[60:61], 0, v[164:165]
	v_cvt_pk_bf16_f32 v58, v58, v59
	v_cvt_pk_bf16_f32 v59, v64, v65
	global_store_dwordx4 v[60:61], v[56:59], off offset:2048
	v_pk_fma_f32 v[36:37], v[132:133], v[160:161], v[36:37] op_sel_hi:[1,0,1]
	v_pk_fma_f32 v[22:23], v[134:135], v[160:161], v[22:23] op_sel_hi:[1,0,1]
	v_pk_fma_f32 v[56:57], v[130:131], v[160:161], v[46:47] op_sel_hi:[1,0,1]
	v_pk_fma_f32 v[46:47], v[128:129], v[160:161], v[44:45] op_sel_hi:[1,0,1]
	v_cvt_pk_bf16_f32 v44, v52, v53
	v_cvt_pk_bf16_f32 v45, v54, v55
	v_add_u32_e32 v52, 0x90, v171
	v_cvt_pk_bf16_f32 v46, v46, v47
	v_cvt_pk_bf16_f32 v47, v56, v57
	global_store_dwordx4 v[60:61], v[44:47], off offset:2304
	v_pk_fma_f32 v[20:21], v[132:133], v[160:161], v[20:21] op_sel_hi:[1,0,1]
	v_pk_fma_f32 v[6:7], v[134:135], v[160:161], v[6:7] op_sel_hi:[1,0,1]
	v_pk_fma_f32 v[44:45], v[142:143], v[160:161], v[50:51] op_sel_hi:[1,0,1]
	v_pk_fma_f32 v[46:47], v[140:141], v[160:161], v[48:49] op_sel_hi:[1,0,1]
	v_pk_fma_f32 v[48:49], v[138:139], v[160:161], v[42:43] op_sel_hi:[1,0,1]
	v_pk_fma_f32 v[42:43], v[136:137], v[160:161], v[40:41] op_sel_hi:[1,0,1]
	v_cvt_pk_bf16_f32 v40, v46, v47
	v_cvt_pk_bf16_f32 v41, v44, v45
	v_mad_i64_i32 v[44:45], s[14:15], v52, s37, v[162:163]
	v_lshl_add_u64 v[44:45], v[44:45], 0, v[164:165]
	v_cvt_pk_bf16_f32 v42, v42, v43
	v_cvt_pk_bf16_f32 v43, v48, v49
	global_store_dwordx4 v[44:45], v[40:43], off offset:2048
	v_pk_fma_f32 v[4:5], v[132:133], v[160:161], v[4:5] op_sel_hi:[1,0,1]
	s_nop 0
	v_pk_fma_f32 v[40:41], v[130:131], v[160:161], v[30:31] op_sel_hi:[1,0,1]
	v_pk_fma_f32 v[30:31], v[128:129], v[160:161], v[28:29] op_sel_hi:[1,0,1]
	v_cvt_pk_bf16_f32 v28, v36, v37
	v_cvt_pk_bf16_f32 v29, v38, v39
	v_add_u32_e32 v36, 0xa0, v171
	v_cvt_pk_bf16_f32 v30, v30, v31
	v_cvt_pk_bf16_f32 v31, v40, v41
	global_store_dwordx4 v[44:45], v[28:31], off offset:2304
	s_nop 1
	v_pk_fma_f32 v[28:29], v[142:143], v[160:161], v[34:35] op_sel_hi:[1,0,1]
	v_pk_fma_f32 v[30:31], v[140:141], v[160:161], v[32:33] op_sel_hi:[1,0,1]
	v_pk_fma_f32 v[32:33], v[138:139], v[160:161], v[26:27] op_sel_hi:[1,0,1]
	v_pk_fma_f32 v[26:27], v[136:137], v[160:161], v[24:25] op_sel_hi:[1,0,1]
	v_cvt_pk_bf16_f32 v24, v30, v31
	v_cvt_pk_bf16_f32 v25, v28, v29
	v_mad_i64_i32 v[28:29], s[14:15], v36, s37, v[162:163]
	v_lshl_add_u64 v[28:29], v[28:29], 0, v[164:165]
	v_cvt_pk_bf16_f32 v26, v26, v27
	v_cvt_pk_bf16_f32 v27, v32, v33
	global_store_dwordx4 v[28:29], v[24:27], off offset:2048
	s_nop 1
	v_pk_fma_f32 v[24:25], v[130:131], v[160:161], v[14:15] op_sel_hi:[1,0,1]
	v_pk_fma_f32 v[14:15], v[128:129], v[160:161], v[12:13] op_sel_hi:[1,0,1]
	v_cvt_pk_bf16_f32 v12, v20, v21
	v_cvt_pk_bf16_f32 v13, v22, v23
	v_add_u32_e32 v20, 0xb0, v171
	v_cvt_pk_bf16_f32 v14, v14, v15
	v_cvt_pk_bf16_f32 v15, v24, v25
	global_store_dwordx4 v[28:29], v[12:15], off offset:2304
	s_nop 1
	v_pk_fma_f32 v[12:13], v[142:143], v[160:161], v[18:19] op_sel_hi:[1,0,1]
	v_pk_fma_f32 v[14:15], v[140:141], v[160:161], v[16:17] op_sel_hi:[1,0,1]
	v_pk_fma_f32 v[16:17], v[138:139], v[160:161], v[10:11] op_sel_hi:[1,0,1]
	v_pk_fma_f32 v[10:11], v[136:137], v[160:161], v[8:9] op_sel_hi:[1,0,1]
	v_cvt_pk_bf16_f32 v8, v14, v15
	v_cvt_pk_bf16_f32 v9, v12, v13
	v_mad_i64_i32 v[12:13], s[14:15], v20, s37, v[162:163]
	v_lshl_add_u64 v[12:13], v[12:13], 0, v[164:165]
	v_cvt_pk_bf16_f32 v10, v10, v11
	v_cvt_pk_bf16_f32 v11, v16, v17
	global_store_dwordx4 v[12:13], v[8:11], off offset:2048
	s_mov_b64 s[14:15], s[8:9]
	s_nop 0
	v_pk_fma_f32 v[8:9], v[130:131], v[160:161], v[2:3] op_sel_hi:[1,0,1]
	v_pk_fma_f32 v[2:3], v[128:129], v[160:161], v[0:1] op_sel_hi:[1,0,1]
	v_cvt_pk_bf16_f32 v0, v4, v5
	v_cvt_pk_bf16_f32 v1, v6, v7
	s_nop 0
	v_cvt_pk_bf16_f32 v2, v2, v3
	v_cvt_pk_bf16_f32 v3, v8, v9
	global_store_dwordx4 v[12:13], v[0:3], off offset:2304
	s_cbranch_vccz .LBB0_819
	s_waitcnt vmcnt(0)
	s_cmpk_gt_u32 s20, 0xff
	s_cbranch_scc1 .LBB0_830
	s_barrier

; #define PG8_STAGE(bufoff, gbase, voff) do { _Pragma("unroll") for (int _i = 0; _i < 2; ++_i) \
;         __builtin_amdgcn_global_load_lds((const unsigned*)((const char*)(gbase) + (voff)[_i]), (LAS unsigned*)(lds + (bufoff) + ldsw + _i * 8192), 16, 0, 0); } while (0)
; #define PG8_LDA(dst, b, h) do { _Pragma("unroll") for (int m = 0; m < 4; ++m) _Pragma("unroll") for (int k = 0; k < 2; ++k) dst[m][k] = *(const LAS bf16x8*)(lds + PG8_SA(b, h) + aoff + m * 2048 + k * 1024); } while (0)
; #define PG8_LDB(dst, b, h) do { _Pragma("unroll") for (int n = 0; n < 2; ++n) _Pragma("unroll") for (int k = 0; k < 2; ++k) dst[n][k] = *(const LAS bf16x8*)(lds + PG8_SB(b, h) + boff + n * 2048 + k * 1024); } while (0)
; #define PG8_WAIT_V(n) asm volatile("s_waitcnt vmcnt(" #n ")" ::: "memory")
; #define PG8_BAR __builtin_amdgcn_s_barrier()
; template <class Epi, class Sched>
; __device__ __forceinline__ void gemm_phase(LAS unsigned char* lds, const Gemm g, const Sched& S, const Epi& E) {
;     ...
;         const bool has_next = S.next(ui + 1, nxt);
;         const char* nA = has_next ? (const char*)g.A + (size_t)nxt.pm * tstep : cA; const char* nB = has_next ? (const char*)g.Bt + (size_t)nxt.pn * tstep : cB;
;         for (int t = 0; t < nt; t += 2) {
;             const bool last = (t == nt - 2);
;             const char* a1 = cA + (size_t)(t + 1) * kstep;
;             const char* a2 = last ? nA : cA + (size_t)(t + 2) * kstep; const char* b2 = last ? nB : cB + (size_t)(t + 2) * kstep;
;             const char* a3 = a2 + kstep; const char* b3 = b2 + kstep;
;             PG8_LDB(B0, 0, 0); PG8_SCHED; PG8_LDA(At, 0, 0); PG8_STAGE(PG8_SA(1, 1), a1 + hstep, voffA);
;             PG8_WAIT_L(8); PG8_BAR; PG8_WAIT_L(0); PG8_MMA(0, 0, At, B0); PG8_BAR; PG8_SCHED;
;             PG8_LDB(B1, 0, 1); PG8_STAGE(PG8_SB(0, 0), b2, voffB);
;             PG8_BAR; PG8_WAIT_L(0); PG8_MMA(0, 1, At, B1); PG8_BAR;
;             PG8_LDA(At, 0, 1); PG8_STAGE(PG8_SA(0, 0), a2, voffA);
;             PG8_BAR; PG8_WAIT_L(0); PG8_MMA(1, 0, At, B0); PG8_BAR; PG8_SCHED;
;             PG8_STAGE(PG8_SB(0, 1), b2 + hstep, voffB);
;             PG8_WAIT_V(6); PG8_BAR; PG8_MMA(1, 1, At, B1); PG8_BAR;
;             PG8_LDB(B0, 1, 0); PG8_SCHED; PG8_LDA(At, 1, 0); PG8_STAGE(PG8_SA(0, 1), a2 + hstep, voffA);
;             PG8_WAIT_L(8); PG8_BAR; PG8_WAIT_L(0); PG8_MMA(0, 0, At, B0); PG8_BAR; PG8_SCHED;
.LBB0_901:
	s_add_u32 s56, s26, 0x100
	s_addc_u32 s57, s27, 0
	s_mov_b32 s58, -2
	s_waitcnt vmcnt(0)
	ds_read_b128 v[128:131], v237
	ds_read_b128 v[132:135], v237 offset:1024
	ds_read_b128 v[136:139], v237 offset:2048
	ds_read_b128 v[140:143], v237 offset:3072
	s_add_u32 s26, s24, 0x100
	s_addc_u32 s27, s25, 0
	s_cmp_eq_u32 s58, 20
	s_cselect_b32 s31, s5, s27
	s_cselect_b32 s30, s4, s26
	s_cselect_b32 s29, s7, s57
	s_cselect_b32 s28, s6, s56
	v_lshl_add_u64 v[176:177], s[24:25], 0, v[210:211]
	s_add_i32 m0, s38, 0xc000
	ds_read_b128 v[144:147], v238
	ds_read_b128 v[148:151], v238 offset:1024
	ds_read_b128 v[152:155], v238 offset:2048
	ds_read_b128 v[156:159], v238 offset:3072
	ds_read_b128 v[160:163], v238 offset:4096
	ds_read_b128 v[164:167], v238 offset:5120
	ds_read_b128 v[168:171], v238 offset:6144
	ds_read_b128 v[172:175], v238 offset:7168
	global_load_lds_dwordx4 v[176:177], off
	v_lshl_add_u64 v[176:177], s[24:25], 0, v[212:213]
	s_add_i32 m0, s38, 0xe000
	s_nop 0
	global_load_lds_dwordx4 v[176:177], off
	s_waitcnt vmcnt(10)
	s_barrier
	s_waitcnt lgkmcnt(0)
	s_setprio 1
	s_waitcnt lgkmcnt(0)
	v_mfma_f32_16x16x32_bf16 v[124:127], v[128:131], v[144:147], 0
	v_mfma_f32_16x16x32_bf16 v[120:123], v[136:139], v[144:147], 0
	v_mfma_f32_16x16x32_bf16 v[108:111], v[128:131], v[152:155], 0
	v_mfma_f32_16x16x32_bf16 v[104:107], v[136:139], v[152:155], 0
	v_mfma_f32_16x16x32_bf16 v[92:95], v[128:131], v[160:163], 0
	v_mfma_f32_16x16x32_bf16 v[88:91], v[136:139], v[160:163], 0
	v_mfma_f32_16x16x32_bf16 v[76:79], v[128:131], v[168:171], 0
	v_mfma_f32_16x16x32_bf16 v[72:75], v[136:139], v[168:171], 0
	v_mfma_f32_16x16x32_bf16 v[124:127], v[132:135], v[148:151], v[124:127]
	v_mfma_f32_16x16x32_bf16 v[120:123], v[140:143], v[148:151], v[120:123]
	v_mfma_f32_16x16x32_bf16 v[108:111], v[132:135], v[156:159], v[108:111]
	v_mfma_f32_16x16x32_bf16 v[104:107], v[140:143], v[156:159], v[104:107]
	v_mfma_f32_16x16x32_bf16 v[92:95], v[132:135], v[164:167], v[92:95]
	v_mfma_f32_16x16x32_bf16 v[88:91], v[140:143], v[164:167], v[88:91]
	v_mfma_f32_16x16x32_bf16 v[76:79], v[132:135], v[172:175], v[76:79]
	v_mfma_f32_16x16x32_bf16 v[72:75], v[140:143], v[172:175], v[72:75]
	s_setprio 0
	s_barrier
	s_add_i32 s24, s50, s37
	s_mov_b32 m0, s24
	ds_read_b128 v[176:179], v239
	ds_read_b128 v[180:183], v239 offset:1024
	ds_read_b128 v[184:187], v239 offset:2048
	ds_read_b128 v[188:191], v239 offset:3072
	global_load_lds_dwordx4 v204, s[28:29]
	s_add_i32 m0, s24, 0x2000
	s_nop 0
	global_load_lds_dwordx4 v208, s[28:29]
	s_waitcnt vmcnt(10)
	s_barrier
	s_waitcnt lgkmcnt(0)
	s_setprio 1
	s_waitcnt lgkmcnt(0)
	v_mfma_f32_16x16x32_bf16 v[116:119], v[176:179], v[144:147], 0
	v_mfma_f32_16x16x32_bf16 v[112:115], v[184:187], v[144:147], 0
	v_mfma_f32_16x16x32_bf16 v[100:103], v[176:179], v[152:155], 0
	v_mfma_f32_16x16x32_bf16 v[96:99], v[184:187], v[152:155], 0
	v_mfma_f32_16x16x32_bf16 v[84:87], v[176:179], v[160:163], 0
	v_mfma_f32_16x16x32_bf16 v[80:83], v[184:187], v[160:163], 0
	v_mfma_f32_16x16x32_bf16 v[68:71], v[176:179], v[168:171], 0
	v_mfma_f32_16x16x32_bf16 v[64:67], v[184:187], v[168:171], 0
	v_mfma_f32_16x16x32_bf16 v[116:119], v[180:183], v[148:151], v[116:119]
	v_mfma_f32_16x16x32_bf16 v[112:115], v[188:191], v[148:151], v[112:115]
	v_mfma_f32_16x16x32_bf16 v[100:103], v[180:183], v[156:159], v[100:103]
	v_mfma_f32_16x16x32_bf16 v[96:99], v[188:191], v[156:159], v[96:99]
	v_mfma_f32_16x16x32_bf16 v[84:87], v[180:183], v[164:167], v[84:87]
	v_mfma_f32_16x16x32_bf16 v[80:83], v[188:191], v[164:167], v[80:83]
	v_mfma_f32_16x16x32_bf16 v[68:71], v[180:183], v[172:175], v[68:71]
	v_mfma_f32_16x16x32_bf16 v[64:67], v[188:191], v[172:175], v[64:67]
	s_setprio 0
	s_mov_b32 m0, s38
	v_lshl_add_u64 v[196:197], s[30:31], 0, v[202:203]
	s_barrier
	ds_read_b128 v[144:147], v238 offset:16384
	ds_read_b128 v[148:151], v238 offset:17408
	ds_read_b128 v[152:155], v238 offset:18432
	ds_read_b128 v[156:159], v238 offset:19456
	ds_read_b128 v[160:163], v238 offset:20480
	ds_read_b128 v[164:167], v238 offset:21504
	ds_read_b128 v[168:171], v238 offset:22528
	ds_read_b128 v[172:175], v238 offset:23552
	global_load_lds_dwordx4 v202, s[30:31]
	v_lshl_add_u64 v[198:199], s[30:31], 0, v[206:207]
	s_mov_b32 m0, s39
	s_nop 0
	global_load_lds_dwordx4 v206, s[30:31]
	s_barrier
	s_waitcnt lgkmcnt(0)
	s_setprio 1
	s_waitcnt lgkmcnt(0)
	v_mfma_f32_16x16x32_bf16 v[60:63], v[128:131], v[144:147], 0
	v_mfma_f32_16x16x32_bf16 v[56:59], v[136:139], v[144:147], 0
	v_mfma_f32_16x16x32_bf16 v[44:47], v[128:131], v[152:155], 0
	v_mfma_f32_16x16x32_bf16 v[40:43], v[136:139], v[152:155], 0
	v_mfma_f32_16x16x32_bf16 v[28:31], v[128:131], v[160:163], 0
	v_mfma_f32_16x16x32_bf16 v[24:27], v[136:139], v[160:163], 0
	v_mfma_f32_16x16x32_bf16 v[12:15], v[128:131], v[168:171], 0
	v_mfma_f32_16x16x32_bf16 v[8:11], v[136:139], v[168:171], 0
	v_mfma_f32_16x16x32_bf16 v[60:63], v[132:135], v[148:151], v[60:63]
	v_mfma_f32_16x16x32_bf16 v[56:59], v[140:143], v[148:151], v[56:59]
	v_mfma_f32_16x16x32_bf16 v[44:47], v[132:135], v[156:159], v[44:47]
	v_mfma_f32_16x16x32_bf16 v[40:43], v[140:143], v[156:159], v[40:43]
	v_mfma_f32_16x16x32_bf16 v[28:31], v[132:135], v[164:167], v[28:31]
	v_mfma_f32_16x16x32_bf16 v[24:27], v[140:143], v[164:167], v[24:27]
	v_mfma_f32_16x16x32_bf16 v[12:15], v[132:135], v[172:175], v[12:15]
	v_mfma_f32_16x16x32_bf16 v[8:11], v[140:143], v[172:175], v[8:11]
	s_setprio 0
	s_barrier
; #define PG8_STAGE(bufoff, gbase, voff) do { _Pragma("unroll") for (int _i = 0; _i < 2; ++_i) \
;         __builtin_amdgcn_global_load_lds((const unsigned*)((const char*)(gbase) + (voff)[_i]), (LAS unsigned*)(lds + (bufoff) + ldsw + _i * 8192), 16, 0, 0); } while (0)
; #define PG8_LDA(dst, b, h) do { _Pragma("unroll") for (int m = 0; m < 4; ++m) _Pragma("unroll") for (int k = 0; k < 2; ++k) dst[m][k] = *(const LAS bf16x8*)(lds + PG8_SA(b, h) + aoff + m * 2048 + k * 1024); } while (0)
; #define PG8_LDB(dst, b, h) do { _Pragma("unroll") for (int n = 0; n < 2; ++n) _Pragma("unroll") for (int k = 0; k < 2; ++k) dst[n][k] = *(const LAS bf16x8*)(lds + PG8_SB(b, h) + boff + n * 2048 + k * 1024); } while (0)
; #define PG8_MMA(ai, bj, At, Bt) do { __builtin_amdgcn_s_setprio(1); _Pragma("unroll") for (int m = 0; m < 4; ++m) _Pragma("unroll") for (int n = 0; n < 2; ++n) _Pragma("unroll") for (int k = 0; k < 2; ++k) \
;         acc[ai][bj][m][n] = __builtin_amdgcn_mfma_f32_16x16x32_bf16(Bt[n][k], At[m][k], acc[ai][bj][m][n], 0, 0, 0); __builtin_amdgcn_s_setprio(0); } while (0)
; #define PG8_WAIT_V(n) asm volatile("s_waitcnt vmcnt(" #n ")" ::: "memory")
; #define PG8_WAIT_L(n) asm volatile("s_waitcnt lgkmcnt(" #n ")" ::: "memory")
; #define PG8_BAR __builtin_amdgcn_s_barrier()
; #define PG8_SCHED __builtin_amdgcn_sched_barrier(0)
; template <class Epi, class Sched>
; __device__ __forceinline__ void gemm_phase(LAS unsigned char* lds, const Gemm g, const Sched& S, const Epi& E) {
;     ...
;             PG8_STAGE(PG8_SB(0, 1), b2 + hstep, voffB);
;             PG8_WAIT_V(6); PG8_BAR; PG8_MMA(1, 1, At, B1); PG8_BAR;
;             PG8_LDB(B0, 1, 0); PG8_SCHED; PG8_LDA(At, 1, 0); PG8_STAGE(PG8_SA(0, 1), a2 + hstep, voffA);
;             PG8_WAIT_L(8); PG8_BAR; PG8_WAIT_L(0); PG8_MMA(0, 0, At, B0); PG8_BAR; PG8_SCHED;
;             PG8_LDB(B1, 1, 1); PG8_STAGE(PG8_SB(1, 0), b3, voffB);
;             PG8_BAR; PG8_WAIT_L(0); PG8_MMA(0, 1, At, B1); PG8_BAR;
;             PG8_LDA(At, 1, 1); PG8_STAGE(PG8_SA(1, 0), a3, voffA);
	s_add_u32 s24, s28, 0x60000
	s_addc_u32 s25, s29, 0
	s_add_i32 s59, s51, s37
	s_mov_b32 m0, s59
	s_nop 0
	global_load_lds_dwordx4 v204, s[24:25]
	s_add_i32 m0, s59, 0x2000
	s_nop 0
	global_load_lds_dwordx4 v208, s[24:25]
	s_add_u32 s24, s30, 0x60000
	s_addc_u32 s25, s31, 0
	s_mov_b32 m0, s40
	s_nop 0
	global_load_lds_dwordx4 v202, s[24:25]
	s_mov_b32 m0, s41
	s_nop 0
	global_load_lds_dwordx4 v206, s[24:25]
	s_waitcnt vmcnt(12)
	s_barrier
	s_setprio 1
	v_mfma_f32_16x16x32_bf16 v[52:55], v[176:179], v[144:147], 0
	v_mfma_f32_16x16x32_bf16 v[48:51], v[184:187], v[144:147], 0
	v_mfma_f32_16x16x32_bf16 v[36:39], v[176:179], v[152:155], 0
	v_mfma_f32_16x16x32_bf16 v[32:35], v[184:187], v[152:155], 0
	v_mfma_f32_16x16x32_bf16 v[20:23], v[176:179], v[160:163], 0
	v_mfma_f32_16x16x32_bf16 v[16:19], v[184:187], v[160:163], 0
	v_mfma_f32_16x16x32_bf16 v[4:7], v[176:179], v[168:171], 0
	v_mfma_f32_16x16x32_bf16 v[0:3], v[184:187], v[168:171], 0
	v_mfma_f32_16x16x32_bf16 v[52:55], v[180:183], v[148:151], v[52:55]
	v_mfma_f32_16x16x32_bf16 v[48:51], v[188:191], v[148:151], v[48:51]
	v_mfma_f32_16x16x32_bf16 v[36:39], v[180:183], v[156:159], v[36:39]
	v_mfma_f32_16x16x32_bf16 v[32:35], v[188:191], v[156:159], v[32:35]
	v_mfma_f32_16x16x32_bf16 v[20:23], v[180:183], v[164:167], v[20:23]
	v_mfma_f32_16x16x32_bf16 v[16:19], v[188:191], v[164:167], v[16:19]
	v_mfma_f32_16x16x32_bf16 v[4:7], v[180:183], v[172:175], v[4:7]
	v_mfma_f32_16x16x32_bf16 v[0:3], v[188:191], v[172:175], v[0:3]
	s_setprio 0
	s_add_i32 s59, 0, 0x18000
	v_add_u32_e32 v140, s59, v236
	s_barrier
	ds_read_b128 v[128:131], v140
	ds_read_b128 v[132:135], v140 offset:1024
	ds_read_b128 v[136:139], v140 offset:2048
	ds_read_b128 v[140:143], v140 offset:3072
	ds_read_b128 v[144:147], v238 offset:32768
	ds_read_b128 v[148:151], v238 offset:33792
	ds_read_b128 v[152:155], v238 offset:34816
	ds_read_b128 v[156:159], v238 offset:35840
	ds_read_b128 v[160:163], v238 offset:36864
	ds_read_b128 v[164:167], v238 offset:37888
	ds_read_b128 v[168:171], v238 offset:38912
	ds_read_b128 v[172:175], v238 offset:39936
	s_waitcnt vmcnt(10)
	s_barrier
	s_waitcnt lgkmcnt(0)
	s_setprio 1
	s_waitcnt lgkmcnt(0)
	v_mfma_f32_16x16x32_bf16 v[124:127], v[128:131], v[144:147], v[124:127]
	v_mfma_f32_16x16x32_bf16 v[120:123], v[136:139], v[144:147], v[120:123]
	v_mfma_f32_16x16x32_bf16 v[108:111], v[128:131], v[152:155], v[108:111]
	v_mfma_f32_16x16x32_bf16 v[104:107], v[136:139], v[152:155], v[104:107]
	v_mfma_f32_16x16x32_bf16 v[92:95], v[128:131], v[160:163], v[92:95]
	v_mfma_f32_16x16x32_bf16 v[88:91], v[136:139], v[160:163], v[88:91]
	v_mfma_f32_16x16x32_bf16 v[76:79], v[128:131], v[168:171], v[76:79]
	v_mfma_f32_16x16x32_bf16 v[72:75], v[136:139], v[168:171], v[72:75]
	v_mfma_f32_16x16x32_bf16 v[124:127], v[132:135], v[148:151], v[124:127]
	v_mfma_f32_16x16x32_bf16 v[120:123], v[140:143], v[148:151], v[120:123]
	v_mfma_f32_16x16x32_bf16 v[108:111], v[132:135], v[156:159], v[108:111]
	v_mfma_f32_16x16x32_bf16 v[104:107], v[140:143], v[156:159], v[104:107]
	v_mfma_f32_16x16x32_bf16 v[92:95], v[132:135], v[164:167], v[92:95]
	v_mfma_f32_16x16x32_bf16 v[88:91], v[140:143], v[164:167], v[88:91]
	v_mfma_f32_16x16x32_bf16 v[76:79], v[132:135], v[172:175], v[76:79]
	v_mfma_f32_16x16x32_bf16 v[72:75], v[140:143], v[172:175], v[72:75]
	s_setprio 0
	s_barrier
	s_add_i32 s30, 0, 0x1c000
	s_add_i32 s24, s59, s37
	v_add_u32_e32 v188, s30, v236
	s_add_u32 s0, s28, 0x80
	s_addc_u32 s1, s29, 0
	s_mov_b32 m0, s24
	ds_read_b128 v[176:179], v188
	ds_read_b128 v[180:183], v188 offset:1024
	ds_read_b128 v[184:187], v188 offset:2048
	ds_read_b128 v[188:191], v188 offset:3072
	global_load_lds_dwordx4 v204, s[0:1]
	s_add_i32 m0, s24, 0x2000
	s_nop 0
	global_load_lds_dwordx4 v208, s[0:1]
	s_waitcnt vmcnt(10)
	s_barrier
	s_waitcnt lgkmcnt(0)
	s_setprio 1
	s_waitcnt lgkmcnt(0)
	v_mfma_f32_16x16x32_bf16 v[116:119], v[176:179], v[144:147], v[116:119]
	v_mfma_f32_16x16x32_bf16 v[112:115], v[184:187], v[144:147], v[112:115]
	v_mfma_f32_16x16x32_bf16 v[100:103], v[176:179], v[152:155], v[100:103]
	v_mfma_f32_16x16x32_bf16 v[96:99], v[184:187], v[152:155], v[96:99]
	v_mfma_f32_16x16x32_bf16 v[84:87], v[176:179], v[160:163], v[84:87]
	v_mfma_f32_16x16x32_bf16 v[80:83], v[184:187], v[160:163], v[80:83]
	v_mfma_f32_16x16x32_bf16 v[68:71], v[176:179], v[168:171], v[68:71]
	v_mfma_f32_16x16x32_bf16 v[64:67], v[184:187], v[168:171], v[64:67]
	v_mfma_f32_16x16x32_bf16 v[116:119], v[180:183], v[148:151], v[116:119]
	v_mfma_f32_16x16x32_bf16 v[112:115], v[188:191], v[148:151], v[112:115]
	v_mfma_f32_16x16x32_bf16 v[100:103], v[180:183], v[156:159], v[100:103]
	v_mfma_f32_16x16x32_bf16 v[96:99], v[188:191], v[156:159], v[96:99]
	v_mfma_f32_16x16x32_bf16 v[84:87], v[180:183], v[164:167], v[84:87]
	v_mfma_f32_16x16x32_bf16 v[80:83], v[188:191], v[164:167], v[80:83]
	v_mfma_f32_16x16x32_bf16 v[68:71], v[180:183], v[172:175], v[68:71]
	v_mfma_f32_16x16x32_bf16 v[64:67], v[188:191], v[172:175], v[64:67]
	s_setprio 0
	s_mov_b32 m0, s47
	s_mov_b64 s[0:1], 0x80
	v_lshl_add_u64 v[192:193], v[196:197], 0, s[0:1]
	s_barrier
	ds_read_b128 v[144:147], v238 offset:49152
	ds_read_b128 v[148:151], v238 offset:50176
	ds_read_b128 v[152:155], v238 offset:51200
	ds_read_b128 v[156:159], v238 offset:52224
	ds_read_b128 v[160:163], v238 offset:53248
	ds_read_b128 v[164:167], v238 offset:54272
	ds_read_b128 v[168:171], v238 offset:55296
	ds_read_b128 v[172:175], v238 offset:56320
	global_load_lds_dwordx4 v[192:193], off
	v_lshl_add_u64 v[192:193], v[198:199], 0, s[0:1]
	s_mov_b32 m0, s48
	s_nop 0
	global_load_lds_dwordx4 v[192:193], off
	s_barrier
; #define PG8_STAGE(bufoff, gbase, voff) do { _Pragma("unroll") for (int _i = 0; _i < 2; ++_i) \
;         __builtin_amdgcn_global_load_lds((const unsigned*)((const char*)(gbase) + (voff)[_i]), (LAS unsigned*)(lds + (bufoff) + ldsw + _i * 8192), 16, 0, 0); } while (0)
; #define PG8_LDA(dst, b, h) do { _Pragma("unroll") for (int m = 0; m < 4; ++m) _Pragma("unroll") for (int k = 0; k < 2; ++k) dst[m][k] = *(const LAS bf16x8*)(lds + PG8_SA(b, h) + aoff + m * 2048 + k * 1024); } while (0)
; #define PG8_LDB(dst, b, h) do { _Pragma("unroll") for (int n = 0; n < 2; ++n) _Pragma("unroll") for (int k = 0; k < 2; ++k) dst[n][k] = *(const LAS bf16x8*)(lds + PG8_SB(b, h) + boff + n * 2048 + k * 1024); } while (0)
; #define PG8_MMA(ai, bj, At, Bt) do { __builtin_amdgcn_s_setprio(1); _Pragma("unroll") for (int m = 0; m < 4; ++m) _Pragma("unroll") for (int n = 0; n < 2; ++n) _Pragma("unroll") for (int k = 0; k < 2; ++k) \
;         acc[ai][bj][m][n] = __builtin_amdgcn_mfma_f32_16x16x32_bf16(Bt[n][k], At[m][k], acc[ai][bj][m][n], 0, 0, 0); __builtin_amdgcn_s_setprio(0); } while (0)
; #define PG8_WAIT_V(n) asm volatile("s_waitcnt vmcnt(" #n ")" ::: "memory")
; #define PG8_WAIT_L(n) asm volatile("s_waitcnt lgkmcnt(" #n ")" ::: "memory")
; #define PG8_BAR __builtin_amdgcn_s_barrier()
; #define PG8_SCHED __builtin_amdgcn_sched_barrier(0)
; template <class Epi, class Sched>
; __device__ __forceinline__ void gemm_phase(LAS unsigned char* lds, const Gemm g, const Sched& S, const Epi& E) {
;     ...
;             PG8_LDB(B0, 0, 0); PG8_SCHED; PG8_LDA(At, 0, 0); PG8_STAGE(PG8_SA(1, 1), a1 + hstep, voffA);
;             PG8_WAIT_L(8); PG8_BAR; PG8_WAIT_L(0); PG8_MMA(0, 0, At, B0); PG8_BAR; PG8_SCHED;
;             PG8_LDB(B1, 0, 1); PG8_STAGE(PG8_SB(0, 0), b2, voffB);
;             PG8_BAR; PG8_WAIT_L(0); PG8_MMA(0, 1, At, B1); PG8_BAR;
;             PG8_LDA(At, 0, 1); PG8_STAGE(PG8_SA(0, 0), a2, voffA);
;             PG8_BAR; PG8_WAIT_L(0); PG8_MMA(1, 0, At, B0); PG8_BAR; PG8_SCHED;
;     ...
;             PG8_BAR; PG8_WAIT_L(0); PG8_MMA(1, 0, At, B0); PG8_BAR; PG8_SCHED;
;             PG8_STAGE(PG8_SB(1, 1), b3 + hstep, voffB);
;             PG8_WAIT_V(6); PG8_BAR; PG8_MMA(1, 1, At, B1); PG8_BAR;
	s_waitcnt lgkmcnt(0)
	s_setprio 1
	s_waitcnt lgkmcnt(0)
	v_mfma_f32_16x16x32_bf16 v[60:63], v[128:131], v[144:147], v[60:63]
	v_mfma_f32_16x16x32_bf16 v[56:59], v[136:139], v[144:147], v[56:59]
	v_mfma_f32_16x16x32_bf16 v[44:47], v[128:131], v[152:155], v[44:47]
	v_mfma_f32_16x16x32_bf16 v[40:43], v[136:139], v[152:155], v[40:43]
	v_mfma_f32_16x16x32_bf16 v[28:31], v[128:131], v[160:163], v[28:31]
	v_mfma_f32_16x16x32_bf16 v[24:27], v[136:139], v[160:163], v[24:27]
	v_mfma_f32_16x16x32_bf16 v[12:15], v[128:131], v[168:171], v[12:15]
	v_mfma_f32_16x16x32_bf16 v[8:11], v[136:139], v[168:171], v[8:11]
	v_mfma_f32_16x16x32_bf16 v[60:63], v[132:135], v[148:151], v[60:63]
	v_mfma_f32_16x16x32_bf16 v[56:59], v[140:143], v[148:151], v[56:59]
	v_mfma_f32_16x16x32_bf16 v[44:47], v[132:135], v[156:159], v[44:47]
	v_mfma_f32_16x16x32_bf16 v[40:43], v[140:143], v[156:159], v[40:43]
	v_mfma_f32_16x16x32_bf16 v[28:31], v[132:135], v[164:167], v[28:31]
	v_mfma_f32_16x16x32_bf16 v[24:27], v[140:143], v[164:167], v[24:27]
	v_mfma_f32_16x16x32_bf16 v[12:15], v[132:135], v[172:175], v[12:15]
	v_mfma_f32_16x16x32_bf16 v[8:11], v[140:143], v[172:175], v[8:11]
	s_setprio 0
	s_barrier
	s_add_u32 s24, s28, 0x60080
	s_addc_u32 s25, s29, 0
	s_add_i32 s28, s30, s37
	s_mov_b32 m0, s28
	s_nop 0
	global_load_lds_dwordx4 v204, s[24:25]
	s_add_i32 m0, s28, 0x2000
	s_nop 0
	global_load_lds_dwordx4 v208, s[24:25]
	s_waitcnt vmcnt(10)
	s_barrier
	s_setprio 1
	v_mfma_f32_16x16x32_bf16 v[52:55], v[176:179], v[144:147], v[52:55]
	v_mfma_f32_16x16x32_bf16 v[48:51], v[184:187], v[144:147], v[48:51]
	v_mfma_f32_16x16x32_bf16 v[36:39], v[176:179], v[152:155], v[36:39]
	v_mfma_f32_16x16x32_bf16 v[32:35], v[184:187], v[152:155], v[32:35]
	v_mfma_f32_16x16x32_bf16 v[20:23], v[176:179], v[160:163], v[20:23]
	v_mfma_f32_16x16x32_bf16 v[16:19], v[184:187], v[160:163], v[16:19]
	v_mfma_f32_16x16x32_bf16 v[4:7], v[176:179], v[168:171], v[4:7]
	v_mfma_f32_16x16x32_bf16 v[0:3], v[184:187], v[168:171], v[0:3]
	v_mfma_f32_16x16x32_bf16 v[52:55], v[180:183], v[148:151], v[52:55]
	v_mfma_f32_16x16x32_bf16 v[48:51], v[188:191], v[148:151], v[48:51]
	v_mfma_f32_16x16x32_bf16 v[36:39], v[180:183], v[156:159], v[36:39]
	v_mfma_f32_16x16x32_bf16 v[32:35], v[188:191], v[156:159], v[32:35]
	v_mfma_f32_16x16x32_bf16 v[20:23], v[180:183], v[164:167], v[20:23]
	v_mfma_f32_16x16x32_bf16 v[16:19], v[188:191], v[164:167], v[16:19]
	v_mfma_f32_16x16x32_bf16 v[4:7], v[180:183], v[172:175], v[4:7]
	v_mfma_f32_16x16x32_bf16 v[0:3], v[188:191], v[172:175], v[0:3]
	s_setprio 0
	s_add_i32 s58, s58, 2
	s_add_u32 s56, s56, 0x100
	s_addc_u32 s57, s57, 0
	s_cmp_gt_u32 s58, 21
	s_mov_b64 s[24:25], s[26:27]
	s_barrier
.LBB0_902:
	ds_read_b128 v[128:131], v237
	ds_read_b128 v[132:135], v237 offset:1024
	ds_read_b128 v[136:139], v237 offset:2048
	ds_read_b128 v[140:143], v237 offset:3072
	s_add_u32 s26, s24, 0x100
	s_addc_u32 s27, s25, 0
	s_cmp_eq_u32 s58, 20
	s_cselect_b32 s31, s5, s27
	s_cselect_b32 s30, s4, s26
	s_cselect_b32 s29, s7, s57
	s_cselect_b32 s28, s6, s56
	v_lshl_add_u64 v[176:177], s[24:25], 0, v[210:211]
	s_add_i32 m0, s38, 0xc000
	ds_read_b128 v[144:147], v238
	ds_read_b128 v[148:151], v238 offset:1024
	ds_read_b128 v[152:155], v238 offset:2048
	ds_read_b128 v[156:159], v238 offset:3072
	ds_read_b128 v[160:163], v238 offset:4096
	ds_read_b128 v[164:167], v238 offset:5120
	ds_read_b128 v[168:171], v238 offset:6144
	ds_read_b128 v[172:175], v238 offset:7168
	global_load_lds_dwordx4 v[176:177], off
	v_lshl_add_u64 v[176:177], s[24:25], 0, v[212:213]
	s_add_i32 m0, s38, 0xe000
	s_nop 0
	global_load_lds_dwordx4 v[176:177], off
	s_waitcnt vmcnt(10)
	s_barrier
	s_waitcnt lgkmcnt(0)
	s_setprio 1
	s_waitcnt lgkmcnt(0)
	v_mfma_f32_16x16x32_bf16 v[124:127], v[128:131], v[144:147], v[124:127]
	v_mfma_f32_16x16x32_bf16 v[120:123], v[136:139], v[144:147], v[120:123]
	v_mfma_f32_16x16x32_bf16 v[108:111], v[128:131], v[152:155], v[108:111]
	v_mfma_f32_16x16x32_bf16 v[104:107], v[136:139], v[152:155], v[104:107]
	v_mfma_f32_16x16x32_bf16 v[92:95], v[128:131], v[160:163], v[92:95]
	v_mfma_f32_16x16x32_bf16 v[88:91], v[136:139], v[160:163], v[88:91]
	v_mfma_f32_16x16x32_bf16 v[76:79], v[128:131], v[168:171], v[76:79]
	v_mfma_f32_16x16x32_bf16 v[72:75], v[136:139], v[168:171], v[72:75]
	v_mfma_f32_16x16x32_bf16 v[124:127], v[132:135], v[148:151], v[124:127]
	v_mfma_f32_16x16x32_bf16 v[120:123], v[140:143], v[148:151], v[120:123]
	v_mfma_f32_16x16x32_bf16 v[108:111], v[132:135], v[156:159], v[108:111]
	v_mfma_f32_16x16x32_bf16 v[104:107], v[140:143], v[156:159], v[104:107]
	v_mfma_f32_16x16x32_bf16 v[92:95], v[132:135], v[164:167], v[92:95]
	v_mfma_f32_16x16x32_bf16 v[88:91], v[140:143], v[164:167], v[88:91]
	v_mfma_f32_16x16x32_bf16 v[76:79], v[132:135], v[172:175], v[76:79]
	v_mfma_f32_16x16x32_bf16 v[72:75], v[140:143], v[172:175], v[72:75]
	s_setprio 0
	s_barrier
	s_add_i32 s24, s50, s37
	s_mov_b32 m0, s24
	ds_read_b128 v[176:179], v239
	ds_read_b128 v[180:183], v239 offset:1024
	ds_read_b128 v[184:187], v239 offset:2048
	ds_read_b128 v[188:191], v239 offset:3072
	global_load_lds_dwordx4 v204, s[28:29]
	s_add_i32 m0, s24, 0x2000
	s_nop 0
	global_load_lds_dwordx4 v208, s[28:29]
	s_waitcnt vmcnt(10)
	s_barrier
; #define PG8_STAGE(bufoff, gbase, voff) do { _Pragma("unroll") for (int _i = 0; _i < 2; ++_i) \
;         __builtin_amdgcn_global_load_lds((const unsigned*)((const char*)(gbase) + (voff)[_i]), (LAS unsigned*)(lds + (bufoff) + ldsw + _i * 8192), 16, 0, 0); } while (0)
; #define PG8_LDA(dst, b, h) do { _Pragma("unroll") for (int m = 0; m < 4; ++m) _Pragma("unroll") for (int k = 0; k < 2; ++k) dst[m][k] = *(const LAS bf16x8*)(lds + PG8_SA(b, h) + aoff + m * 2048 + k * 1024); } while (0)
; #define PG8_LDB(dst, b, h) do { _Pragma("unroll") for (int n = 0; n < 2; ++n) _Pragma("unroll") for (int k = 0; k < 2; ++k) dst[n][k] = *(const LAS bf16x8*)(lds + PG8_SB(b, h) + boff + n * 2048 + k * 1024); } while (0)
; #define PG8_WAIT_V(n) asm volatile("s_waitcnt vmcnt(" #n ")" ::: "memory")
; #define PG8_WAIT_L(n) asm volatile("s_waitcnt lgkmcnt(" #n ")" ::: "memory")
; #define PG8_BAR __builtin_amdgcn_s_barrier()
; #define PG8_SCHED __builtin_amdgcn_sched_barrier(0)
; template <class Epi, class Sched>
; __device__ __forceinline__ void gemm_phase(LAS unsigned char* lds, const Gemm g, const Sched& S, const Epi& E) {
;     ...
;             PG8_LDB(B0, 0, 0); PG8_SCHED; PG8_LDA(At, 0, 0); PG8_STAGE(PG8_SA(1, 1), a1 + hstep, voffA);
;             PG8_WAIT_L(8); PG8_BAR; PG8_WAIT_L(0); PG8_MMA(0, 0, At, B0); PG8_BAR; PG8_SCHED;
;             PG8_LDB(B1, 0, 1); PG8_STAGE(PG8_SB(0, 0), b2, voffB);
;             PG8_BAR; PG8_WAIT_L(0); PG8_MMA(0, 1, At, B1); PG8_BAR;
;             PG8_LDA(At, 0, 1); PG8_STAGE(PG8_SA(0, 0), a2, voffA);
;             PG8_BAR; PG8_WAIT_L(0); PG8_MMA(1, 0, At, B0); PG8_BAR; PG8_SCHED;
;             PG8_STAGE(PG8_SB(0, 1), b2 + hstep, voffB);
;             PG8_WAIT_V(6); PG8_BAR; PG8_MMA(1, 1, At, B1); PG8_BAR;
;             PG8_LDB(B0, 1, 0); PG8_SCHED; PG8_LDA(At, 1, 0); PG8_STAGE(PG8_SA(0, 1), a2 + hstep, voffA);
;             PG8_WAIT_L(8); PG8_BAR; PG8_WAIT_L(0); PG8_MMA(0, 0, At, B0); PG8_BAR; PG8_SCHED;
;             PG8_LDB(B1, 1, 1); PG8_STAGE(PG8_SB(1, 0), b3, voffB);
;             PG8_BAR; PG8_WAIT_L(0); PG8_MMA(0, 1, At, B1); PG8_BAR;
;             PG8_LDA(At, 1, 1); PG8_STAGE(PG8_SA(1, 0), a3, voffA);
;             PG8_BAR; PG8_WAIT_L(0); PG8_MMA(1, 0, At, B0); PG8_BAR; PG8_SCHED;
;             PG8_STAGE(PG8_SB(1, 1), b3 + hstep, voffB);
;             PG8_WAIT_V(6); PG8_BAR; PG8_MMA(1, 1, At, B1); PG8_BAR;
	s_waitcnt lgkmcnt(0)
	s_setprio 1
	s_waitcnt lgkmcnt(0)
	v_mfma_f32_16x16x32_bf16 v[116:119], v[176:179], v[144:147], v[116:119]
	v_mfma_f32_16x16x32_bf16 v[112:115], v[184:187], v[144:147], v[112:115]
	v_mfma_f32_16x16x32_bf16 v[100:103], v[176:179], v[152:155], v[100:103]
	v_mfma_f32_16x16x32_bf16 v[96:99], v[184:187], v[152:155], v[96:99]
	v_mfma_f32_16x16x32_bf16 v[84:87], v[176:179], v[160:163], v[84:87]
	v_mfma_f32_16x16x32_bf16 v[80:83], v[184:187], v[160:163], v[80:83]
	v_mfma_f32_16x16x32_bf16 v[68:71], v[176:179], v[168:171], v[68:71]
	v_mfma_f32_16x16x32_bf16 v[64:67], v[184:187], v[168:171], v[64:67]
	v_mfma_f32_16x16x32_bf16 v[116:119], v[180:183], v[148:151], v[116:119]
	v_mfma_f32_16x16x32_bf16 v[112:115], v[188:191], v[148:151], v[112:115]
	v_mfma_f32_16x16x32_bf16 v[100:103], v[180:183], v[156:159], v[100:103]
	v_mfma_f32_16x16x32_bf16 v[96:99], v[188:191], v[156:159], v[96:99]
	v_mfma_f32_16x16x32_bf16 v[84:87], v[180:183], v[164:167], v[84:87]
	v_mfma_f32_16x16x32_bf16 v[80:83], v[188:191], v[164:167], v[80:83]
	v_mfma_f32_16x16x32_bf16 v[68:71], v[180:183], v[172:175], v[68:71]
	v_mfma_f32_16x16x32_bf16 v[64:67], v[188:191], v[172:175], v[64:67]
	s_setprio 0
	s_mov_b32 m0, s38
	v_lshl_add_u64 v[196:197], s[30:31], 0, v[202:203]
	s_barrier
	ds_read_b128 v[144:147], v238 offset:16384
	ds_read_b128 v[148:151], v238 offset:17408
	ds_read_b128 v[152:155], v238 offset:18432
	ds_read_b128 v[156:159], v238 offset:19456
	ds_read_b128 v[160:163], v238 offset:20480
	ds_read_b128 v[164:167], v238 offset:21504
	ds_read_b128 v[168:171], v238 offset:22528
	ds_read_b128 v[172:175], v238 offset:23552
	global_load_lds_dwordx4 v202, s[30:31]
	v_lshl_add_u64 v[198:199], s[30:31], 0, v[206:207]
	s_mov_b32 m0, s39
	s_nop 0
	global_load_lds_dwordx4 v206, s[30:31]
	s_barrier
	s_waitcnt lgkmcnt(0)
	s_setprio 1
	s_waitcnt lgkmcnt(0)
	v_mfma_f32_16x16x32_bf16 v[60:63], v[128:131], v[144:147], v[60:63]
	v_mfma_f32_16x16x32_bf16 v[56:59], v[136:139], v[144:147], v[56:59]
	v_mfma_f32_16x16x32_bf16 v[44:47], v[128:131], v[152:155], v[44:47]
	v_mfma_f32_16x16x32_bf16 v[40:43], v[136:139], v[152:155], v[40:43]
	v_mfma_f32_16x16x32_bf16 v[28:31], v[128:131], v[160:163], v[28:31]
	v_mfma_f32_16x16x32_bf16 v[24:27], v[136:139], v[160:163], v[24:27]
	v_mfma_f32_16x16x32_bf16 v[12:15], v[128:131], v[168:171], v[12:15]
	v_mfma_f32_16x16x32_bf16 v[8:11], v[136:139], v[168:171], v[8:11]
	v_mfma_f32_16x16x32_bf16 v[60:63], v[132:135], v[148:151], v[60:63]
	v_mfma_f32_16x16x32_bf16 v[56:59], v[140:143], v[148:151], v[56:59]
	v_mfma_f32_16x16x32_bf16 v[44:47], v[132:135], v[156:159], v[44:47]
	v_mfma_f32_16x16x32_bf16 v[40:43], v[140:143], v[156:159], v[40:43]
	v_mfma_f32_16x16x32_bf16 v[28:31], v[132:135], v[164:167], v[28:31]
	v_mfma_f32_16x16x32_bf16 v[24:27], v[140:143], v[164:167], v[24:27]
	v_mfma_f32_16x16x32_bf16 v[12:15], v[132:135], v[172:175], v[12:15]
	v_mfma_f32_16x16x32_bf16 v[8:11], v[140:143], v[172:175], v[8:11]
	s_setprio 0
	s_barrier
	s_add_u32 s24, s28, 0x60000
	s_addc_u32 s25, s29, 0
	s_add_i32 s59, s51, s37
	s_mov_b32 m0, s59
	s_nop 0
	global_load_lds_dwordx4 v204, s[24:25]
	s_add_i32 m0, s59, 0x2000
	s_nop 0
	global_load_lds_dwordx4 v208, s[24:25]
	s_add_u32 s24, s30, 0x60000
	s_addc_u32 s25, s31, 0
	s_mov_b32 m0, s40
	s_nop 0
	global_load_lds_dwordx4 v202, s[24:25]
	s_mov_b32 m0, s41
	s_nop 0
	global_load_lds_dwordx4 v206, s[24:25]
	s_waitcnt vmcnt(12)
	s_barrier
	s_setprio 1
	v_mfma_f32_16x16x32_bf16 v[52:55], v[176:179], v[144:147], v[52:55]
	v_mfma_f32_16x16x32_bf16 v[48:51], v[184:187], v[144:147], v[48:51]
	v_mfma_f32_16x16x32_bf16 v[36:39], v[176:179], v[152:155], v[36:39]
	v_mfma_f32_16x16x32_bf16 v[32:35], v[184:187], v[152:155], v[32:35]
	v_mfma_f32_16x16x32_bf16 v[20:23], v[176:179], v[160:163], v[20:23]
	v_mfma_f32_16x16x32_bf16 v[16:19], v[184:187], v[160:163], v[16:19]
	v_mfma_f32_16x16x32_bf16 v[4:7], v[176:179], v[168:171], v[4:7]
	v_mfma_f32_16x16x32_bf16 v[0:3], v[184:187], v[168:171], v[0:3]
	v_mfma_f32_16x16x32_bf16 v[52:55], v[180:183], v[148:151], v[52:55]
	v_mfma_f32_16x16x32_bf16 v[48:51], v[188:191], v[148:151], v[48:51]
	v_mfma_f32_16x16x32_bf16 v[36:39], v[180:183], v[156:159], v[36:39]
	v_mfma_f32_16x16x32_bf16 v[32:35], v[188:191], v[156:159], v[32:35]
	v_mfma_f32_16x16x32_bf16 v[20:23], v[180:183], v[164:167], v[20:23]
	v_mfma_f32_16x16x32_bf16 v[16:19], v[188:191], v[164:167], v[16:19]
	v_mfma_f32_16x16x32_bf16 v[4:7], v[180:183], v[172:175], v[4:7]
	v_mfma_f32_16x16x32_bf16 v[0:3], v[188:191], v[172:175], v[0:3]
	s_setprio 0
	s_add_i32 s59, 0, 0x18000
	v_add_u32_e32 v140, s59, v236
	s_barrier
	ds_read_b128 v[128:131], v140
	ds_read_b128 v[132:135], v140 offset:1024
	ds_read_b128 v[136:139], v140 offset:2048
	ds_read_b128 v[140:143], v140 offset:3072
	ds_read_b128 v[144:147], v238 offset:32768
	ds_read_b128 v[148:151], v238 offset:33792
	ds_read_b128 v[152:155], v238 offset:34816
	ds_read_b128 v[156:159], v238 offset:35840
	ds_read_b128 v[160:163], v238 offset:36864
	ds_read_b128 v[164:167], v238 offset:37888
	ds_read_b128 v[168:171], v238 offset:38912
	ds_read_b128 v[172:175], v238 offset:39936
	s_waitcnt vmcnt(10)
	s_barrier
; #define PG8_STAGE(bufoff, gbase, voff) do { _Pragma("unroll") for (int _i = 0; _i < 2; ++_i) \
;         __builtin_amdgcn_global_load_lds((const unsigned*)((const char*)(gbase) + (voff)[_i]), (LAS unsigned*)(lds + (bufoff) + ldsw + _i * 8192), 16, 0, 0); } while (0)
; #define PG8_LDA(dst, b, h) do { _Pragma("unroll") for (int m = 0; m < 4; ++m) _Pragma("unroll") for (int k = 0; k < 2; ++k) dst[m][k] = *(const LAS bf16x8*)(lds + PG8_SA(b, h) + aoff + m * 2048 + k * 1024); } while (0)
; #define PG8_LDB(dst, b, h) do { _Pragma("unroll") for (int n = 0; n < 2; ++n) _Pragma("unroll") for (int k = 0; k < 2; ++k) dst[n][k] = *(const LAS bf16x8*)(lds + PG8_SB(b, h) + boff + n * 2048 + k * 1024); } while (0)
; #define PG8_MMA(ai, bj, At, Bt) do { __builtin_amdgcn_s_setprio(1); _Pragma("unroll") for (int m = 0; m < 4; ++m) _Pragma("unroll") for (int n = 0; n < 2; ++n) _Pragma("unroll") for (int k = 0; k < 2; ++k) \
;         acc[ai][bj][m][n] = __builtin_amdgcn_mfma_f32_16x16x32_bf16(Bt[n][k], At[m][k], acc[ai][bj][m][n], 0, 0, 0); __builtin_amdgcn_s_setprio(0); } while (0)
; #define PG8_WAIT_V(n) asm volatile("s_waitcnt vmcnt(" #n ")" ::: "memory")
; #define PG8_WAIT_L(n) asm volatile("s_waitcnt lgkmcnt(" #n ")" ::: "memory")
; #define PG8_BAR __builtin_amdgcn_s_barrier()
; #define PG8_SCHED __builtin_amdgcn_sched_barrier(0)
; template <class Epi, class Sched>
; __device__ __forceinline__ void gemm_phase(LAS unsigned char* lds, const Gemm g, const Sched& S, const Epi& E) {
;     ...
;             PG8_LDA(At, 0, 1); PG8_STAGE(PG8_SA(0, 0), a2, voffA);
;             PG8_BAR; PG8_WAIT_L(0); PG8_MMA(1, 0, At, B0); PG8_BAR; PG8_SCHED;
;             PG8_STAGE(PG8_SB(0, 1), b2 + hstep, voffB);
;             PG8_WAIT_V(6); PG8_BAR; PG8_MMA(1, 1, At, B1); PG8_BAR;
;             PG8_LDB(B0, 1, 0); PG8_SCHED; PG8_LDA(At, 1, 0); PG8_STAGE(PG8_SA(0, 1), a2 + hstep, voffA);
;             PG8_WAIT_L(8); PG8_BAR; PG8_WAIT_L(0); PG8_MMA(0, 0, At, B0); PG8_BAR; PG8_SCHED;
;             PG8_LDB(B1, 1, 1); PG8_STAGE(PG8_SB(1, 0), b3, voffB);
;             PG8_BAR; PG8_WAIT_L(0); PG8_MMA(0, 1, At, B1); PG8_BAR;
;             PG8_LDA(At, 1, 1); PG8_STAGE(PG8_SA(1, 0), a3, voffA);
;             PG8_BAR; PG8_WAIT_L(0); PG8_MMA(1, 0, At, B0); PG8_BAR; PG8_SCHED;
;             PG8_STAGE(PG8_SB(1, 1), b3 + hstep, voffB);
;             PG8_WAIT_V(6); PG8_BAR; PG8_MMA(1, 1, At, B1); PG8_BAR;
	s_waitcnt lgkmcnt(0)
	s_setprio 1
	s_waitcnt lgkmcnt(0)
	v_mfma_f32_16x16x32_bf16 v[124:127], v[128:131], v[144:147], v[124:127]
	v_mfma_f32_16x16x32_bf16 v[120:123], v[136:139], v[144:147], v[120:123]
	v_mfma_f32_16x16x32_bf16 v[108:111], v[128:131], v[152:155], v[108:111]
	v_mfma_f32_16x16x32_bf16 v[104:107], v[136:139], v[152:155], v[104:107]
	v_mfma_f32_16x16x32_bf16 v[92:95], v[128:131], v[160:163], v[92:95]
	v_mfma_f32_16x16x32_bf16 v[88:91], v[136:139], v[160:163], v[88:91]
	v_mfma_f32_16x16x32_bf16 v[76:79], v[128:131], v[168:171], v[76:79]
	v_mfma_f32_16x16x32_bf16 v[72:75], v[136:139], v[168:171], v[72:75]
	v_mfma_f32_16x16x32_bf16 v[124:127], v[132:135], v[148:151], v[124:127]
	v_mfma_f32_16x16x32_bf16 v[120:123], v[140:143], v[148:151], v[120:123]
	v_mfma_f32_16x16x32_bf16 v[108:111], v[132:135], v[156:159], v[108:111]
	v_mfma_f32_16x16x32_bf16 v[104:107], v[140:143], v[156:159], v[104:107]
	v_mfma_f32_16x16x32_bf16 v[92:95], v[132:135], v[164:167], v[92:95]
	v_mfma_f32_16x16x32_bf16 v[88:91], v[140:143], v[164:167], v[88:91]
	v_mfma_f32_16x16x32_bf16 v[76:79], v[132:135], v[172:175], v[76:79]
	v_mfma_f32_16x16x32_bf16 v[72:75], v[140:143], v[172:175], v[72:75]
	s_setprio 0
	s_barrier
	s_add_i32 s30, 0, 0x1c000
	s_add_i32 s24, s59, s37
	v_add_u32_e32 v188, s30, v236
	s_add_u32 s0, s28, 0x80
	s_addc_u32 s1, s29, 0
	s_mov_b32 m0, s24
	ds_read_b128 v[176:179], v188
	ds_read_b128 v[180:183], v188 offset:1024
	ds_read_b128 v[184:187], v188 offset:2048
	ds_read_b128 v[188:191], v188 offset:3072
	global_load_lds_dwordx4 v204, s[0:1]
	s_add_i32 m0, s24, 0x2000
	s_nop 0
	global_load_lds_dwordx4 v208, s[0:1]
	s_waitcnt vmcnt(10)
	s_barrier
	s_waitcnt lgkmcnt(0)
	s_setprio 1
	s_waitcnt lgkmcnt(0)
	v_mfma_f32_16x16x32_bf16 v[116:119], v[176:179], v[144:147], v[116:119]
	v_mfma_f32_16x16x32_bf16 v[112:115], v[184:187], v[144:147], v[112:115]
	v_mfma_f32_16x16x32_bf16 v[100:103], v[176:179], v[152:155], v[100:103]
	v_mfma_f32_16x16x32_bf16 v[96:99], v[184:187], v[152:155], v[96:99]
	v_mfma_f32_16x16x32_bf16 v[84:87], v[176:179], v[160:163], v[84:87]
	v_mfma_f32_16x16x32_bf16 v[80:83], v[184:187], v[160:163], v[80:83]
	v_mfma_f32_16x16x32_bf16 v[68:71], v[176:179], v[168:171], v[68:71]
	v_mfma_f32_16x16x32_bf16 v[64:67], v[184:187], v[168:171], v[64:67]
	v_mfma_f32_16x16x32_bf16 v[116:119], v[180:183], v[148:151], v[116:119]
	v_mfma_f32_16x16x32_bf16 v[112:115], v[188:191], v[148:151], v[112:115]
	v_mfma_f32_16x16x32_bf16 v[100:103], v[180:183], v[156:159], v[100:103]
	v_mfma_f32_16x16x32_bf16 v[96:99], v[188:191], v[156:159], v[96:99]
	v_mfma_f32_16x16x32_bf16 v[84:87], v[180:183], v[164:167], v[84:87]
	v_mfma_f32_16x16x32_bf16 v[80:83], v[188:191], v[164:167], v[80:83]
	v_mfma_f32_16x16x32_bf16 v[68:71], v[180:183], v[172:175], v[68:71]
	v_mfma_f32_16x16x32_bf16 v[64:67], v[188:191], v[172:175], v[64:67]
	s_setprio 0
	s_mov_b32 m0, s47
	s_mov_b64 s[0:1], 0x80
	v_lshl_add_u64 v[192:193], v[196:197], 0, s[0:1]
	s_barrier
	ds_read_b128 v[144:147], v238 offset:49152
	ds_read_b128 v[148:151], v238 offset:50176
	ds_read_b128 v[152:155], v238 offset:51200
	ds_read_b128 v[156:159], v238 offset:52224
	ds_read_b128 v[160:163], v238 offset:53248
	ds_read_b128 v[164:167], v238 offset:54272
	ds_read_b128 v[168:171], v238 offset:55296
	ds_read_b128 v[172:175], v238 offset:56320
	global_load_lds_dwordx4 v[192:193], off
	v_lshl_add_u64 v[192:193], v[198:199], 0, s[0:1]
	s_mov_b32 m0, s48
	s_nop 0
	global_load_lds_dwordx4 v[192:193], off
	s_barrier
	s_waitcnt lgkmcnt(0)
	s_setprio 1
	s_waitcnt lgkmcnt(0)
	v_mfma_f32_16x16x32_bf16 v[60:63], v[128:131], v[144:147], v[60:63]
	v_mfma_f32_16x16x32_bf16 v[56:59], v[136:139], v[144:147], v[56:59]
	v_mfma_f32_16x16x32_bf16 v[44:47], v[128:131], v[152:155], v[44:47]
	v_mfma_f32_16x16x32_bf16 v[40:43], v[136:139], v[152:155], v[40:43]
	v_mfma_f32_16x16x32_bf16 v[28:31], v[128:131], v[160:163], v[28:31]
	v_mfma_f32_16x16x32_bf16 v[24:27], v[136:139], v[160:163], v[24:27]
	v_mfma_f32_16x16x32_bf16 v[12:15], v[128:131], v[168:171], v[12:15]
	v_mfma_f32_16x16x32_bf16 v[8:11], v[136:139], v[168:171], v[8:11]
	v_mfma_f32_16x16x32_bf16 v[60:63], v[132:135], v[148:151], v[60:63]
	v_mfma_f32_16x16x32_bf16 v[56:59], v[140:143], v[148:151], v[56:59]
	v_mfma_f32_16x16x32_bf16 v[44:47], v[132:135], v[156:159], v[44:47]
	v_mfma_f32_16x16x32_bf16 v[40:43], v[140:143], v[156:159], v[40:43]
	v_mfma_f32_16x16x32_bf16 v[28:31], v[132:135], v[164:167], v[28:31]
	v_mfma_f32_16x16x32_bf16 v[24:27], v[140:143], v[164:167], v[24:27]
	v_mfma_f32_16x16x32_bf16 v[12:15], v[132:135], v[172:175], v[12:15]
	v_mfma_f32_16x16x32_bf16 v[8:11], v[140:143], v[172:175], v[8:11]
	s_setprio 0
	s_barrier
	s_add_u32 s24, s28, 0x60080
	s_addc_u32 s25, s29, 0
	s_add_i32 s28, s30, s37
	s_mov_b32 m0, s28
	s_nop 0
	global_load_lds_dwordx4 v204, s[24:25]
	s_add_i32 m0, s28, 0x2000
	s_nop 0
	global_load_lds_dwordx4 v208, s[24:25]
	s_waitcnt vmcnt(10)
	s_barrier
	s_setprio 1
	v_mfma_f32_16x16x32_bf16 v[52:55], v[176:179], v[144:147], v[52:55]
	v_mfma_f32_16x16x32_bf16 v[48:51], v[184:187], v[144:147], v[48:51]
	v_mfma_f32_16x16x32_bf16 v[36:39], v[176:179], v[152:155], v[36:39]
	v_mfma_f32_16x16x32_bf16 v[32:35], v[184:187], v[152:155], v[32:35]
	v_mfma_f32_16x16x32_bf16 v[20:23], v[176:179], v[160:163], v[20:23]
	v_mfma_f32_16x16x32_bf16 v[16:19], v[184:187], v[160:163], v[16:19]
	v_mfma_f32_16x16x32_bf16 v[4:7], v[176:179], v[168:171], v[4:7]
	v_mfma_f32_16x16x32_bf16 v[0:3], v[184:187], v[168:171], v[0:3]
	v_mfma_f32_16x16x32_bf16 v[52:55], v[180:183], v[148:151], v[52:55]
	v_mfma_f32_16x16x32_bf16 v[48:51], v[188:191], v[148:151], v[48:51]
	v_mfma_f32_16x16x32_bf16 v[36:39], v[180:183], v[156:159], v[36:39]
	v_mfma_f32_16x16x32_bf16 v[32:35], v[188:191], v[156:159], v[32:35]
	v_mfma_f32_16x16x32_bf16 v[20:23], v[180:183], v[164:167], v[20:23]
	v_mfma_f32_16x16x32_bf16 v[16:19], v[188:191], v[164:167], v[16:19]
	v_mfma_f32_16x16x32_bf16 v[4:7], v[180:183], v[172:175], v[4:7]
	v_mfma_f32_16x16x32_bf16 v[0:3], v[188:191], v[172:175], v[0:3]
	s_setprio 0
	s_add_i32 s58, s58, 2
	s_add_u32 s56, s56, 0x100
	s_addc_u32 s57, s57, 0
	s_cmp_gt_u32 s58, 21
	s_mov_b64 s[24:25], s[26:27]
	s_barrier
; __device__ __forceinline__ unsigned cvt_pk_bf16(float lo, float hi) { unsigned r; asm volatile("v_cvt_pk_bf16_f32 %0, %1, %2" : "=v"(r) : "v"(lo), "v"(hi)); return r; }
; __device__ __forceinline__ float bf_lo(unsigned u) { return __uint_as_float(u << 16); }
; __device__ __forceinline__ float bf_hi(unsigned u) { return __uint_as_float(u & 0xffff0000u); }
;     __device__ __forceinline__ void operator()(const AccT& acc, const Unit& u, int wr, int wc, int fr, int fq) const {
;     ...
;         const int rowt = u.pm * 256; const int b = rowt >> 11;
;         const bf16_t* res = res_b + (size_t)rowt * DM; bf16_t* out = hb + (size_t)rowt * DM;
;         const int col0 = u.pn * 256 + wc * 32 + 8 * fq;
;         f32x4 gv[2][2];
; #pragma unroll
;         for (int bj = 0; bj < 2; ++bj)
; #pragma unroll
;             for (int n = 0; n < 2; ++n) gv[bj][n] = *(const f32x4*)(gate + (size_t)b * NMOD + col0 + bj * 128 + n * 4) * gs;
;         u32x4 r[2][4][2];
; #pragma unroll
;         for (int ai = 0; ai < 2; ++ai)
; #pragma unroll
;             for (int m = 0; m < 4; ++m)
; #pragma unroll
;                 for (int bj = 0; bj < 2; ++bj) r[ai][m][bj] = *(const u32x4*)(res + (size_t)(wr * 64 + fr + ai * 128 + m * 16) * DM + col0 + bj * 128);
; #pragma unroll
;         for (int ai = 0; ai < 2; ++ai)
; #pragma unroll
;             for (int m = 0; m < 4; ++m)
; #pragma unroll
;                 for (int bj = 0; bj < 2; ++bj) {
;                     const u32x4 q = r[ai][m][bj];
;                     const f32x4 r0 = {bf_lo(q.x), bf_hi(q.x), bf_lo(q.y), bf_hi(q.y)}, r1 = {bf_lo(q.z), bf_hi(q.z), bf_lo(q.w), bf_hi(q.w)};
;                     const f32x4 h0 = r0 + gv[bj][0] * acc[ai][bj][m][0], h1 = r1 + gv[bj][1] * acc[ai][bj][m][1];
;                     u32x4 w; w.x = cvt_pk_bf16(h0[0], h0[1]); w.y = cvt_pk_bf16(h0[2], h0[3]); w.z = cvt_pk_bf16(h1[0], h1[1]); w.w = cvt_pk_bf16(h1[2], h1[3]);
;                     *(u32x4*)(out + (size_t)(wr * 64 + fr + ai * 128 + m * 16) * DM + col0 + bj * 128) = w;
;                 }
	s_cbranch_scc0 .LBB0_902
	s_lshl_b32 s27, s55, 8
	v_mov_b32_e32 v146, v235
	v_mov_b32_e32 v128, v234
	s_lshl_b32 s24, s54, 8
	s_ashr_i32 s26, s54, 3
	s_or_b32 s27, s27, s46
	s_ashr_i32 s25, s24, 31
	v_lshl_add_u32 v144, v128, 3, s27
	s_mul_hi_i32 s27, s26, 0x9000
	s_mul_i32 s26, s26, 0x9000
	s_add_u32 s26, s43, s26
	s_addc_u32 s27, s44, s27
	v_ashrrev_i32_e32 v145, 31, v144
	s_lshl_b64 s[24:25], s[24:25], 11
	v_lshl_add_u64 v[132:133], v[144:145], 2, s[26:27]
	s_add_u32 s26, s62, s24
	v_add_u32_e32 v146, s45, v146
	s_addc_u32 s27, s63, s25
	v_lshlrev_b64 v[222:223], 1, v[144:145]
	v_ashrrev_i32_e32 v147, 31, v146
	v_lshl_add_u64 v[144:145], s[26:27], 0, v[222:223]
	v_lshlrev_b64 v[248:249], 11, v[146:147]
	v_lshl_add_u64 v[146:147], v[144:145], 0, v[248:249]
	global_load_dwordx4 v[136:139], v[132:133], off offset:16
	global_load_dwordx4 v[140:143], v[132:133], off
	global_load_dwordx4 v[128:131], v[132:133], off offset:528
	s_nop 0
	global_load_dwordx4 v[132:135], v[132:133], off offset:512
	s_nop 0
	global_load_dwordx4 v[240:243], v[146:147], off
	global_load_dwordx4 v[244:247], v[146:147], off offset:256
	v_lshl_add_u64 v[232:233], v[248:249], 0, s[10:11]
	v_lshl_add_u64 v[146:147], v[144:145], 0, v[232:233]
	global_load_dwordx4 v[196:199], v[146:147], off
	global_load_dwordx4 v[192:195], v[146:147], off offset:256
	v_lshl_add_u64 v[230:231], v[248:249], 0, s[12:13]
	v_lshl_add_u64 v[146:147], v[144:145], 0, v[230:231]
	global_load_dwordx4 v[188:191], v[146:147], off
	global_load_dwordx4 v[184:187], v[146:147], off offset:256
	v_lshl_add_u64 v[228:229], v[248:249], 0, s[14:15]
	v_lshl_add_u64 v[146:147], v[144:145], 0, v[228:229]
	global_load_dwordx4 v[180:183], v[146:147], off
	global_load_dwordx4 v[176:179], v[146:147], off offset:256
	v_lshl_add_u64 v[226:227], v[248:249], 0, s[16:17]
	v_lshl_add_u64 v[146:147], v[144:145], 0, v[226:227]
	global_load_dwordx4 v[172:175], v[146:147], off
	global_load_dwordx4 v[168:171], v[146:147], off offset:256
	v_lshl_add_u64 v[224:225], v[248:249], 0, s[18:19]
	v_lshl_add_u64 v[146:147], v[144:145], 0, v[224:225]
	global_load_dwordx4 v[164:167], v[146:147], off
	global_load_dwordx4 v[160:163], v[146:147], off offset:256
	v_lshl_add_u64 v[220:221], v[248:249], 0, s[20:21]
	v_lshl_add_u64 v[146:147], v[144:145], 0, v[220:221]
	global_load_dwordx4 v[156:159], v[146:147], off
	global_load_dwordx4 v[152:155], v[146:147], off offset:256
	v_lshl_add_u64 v[218:219], v[248:249], 0, s[22:23]
	v_lshl_add_u64 v[144:145], v[144:145], 0, v[218:219]
	global_load_dwordx4 v[148:151], v[144:145], off
	s_nop 0
	global_load_dwordx4 v[144:147], v[144:145], off offset:256
	s_add_u32 s24, s80, s24
	s_addc_u32 s25, s81, s25
	v_lshl_add_u64 v[222:223], s[24:25], 0, v[222:223]
	v_lshl_add_u64 v[248:249], v[222:223], 0, v[248:249]
	s_and_b64 vcc, exec, s[2:3]
	s_mov_b32 s55, s52
	s_mov_b32 s54, s53
	s_mov_b64 s[26:27], s[6:7]
	s_mov_b64 s[24:25], s[4:5]
	s_waitcnt vmcnt(0)
	v_lshlrev_b32_e32 v250, 16, v240
	v_and_b32_e32 v251, 0xffff0000, v240
	v_lshlrev_b32_e32 v240, 16, v241
	v_and_b32_e32 v241, 0xffff0000, v241
	v_lshlrev_b32_e32 v252, 16, v242
	v_and_b32_e32 v253, 0xffff0000, v242
	v_lshlrev_b32_e32 v242, 16, v243
	v_and_b32_e32 v243, 0xffff0000, v243
	v_pk_fma_f32 v[126:127], v[126:127], v[142:143], v[240:241]
	v_pk_fma_f32 v[124:125], v[124:125], v[140:141], v[250:251]
	v_pk_fma_f32 v[240:241], v[122:123], v[138:139], v[242:243]
	v_pk_fma_f32 v[122:123], v[120:121], v[136:137], v[252:253]
	v_cvt_pk_bf16_f32 v120, v124, v125
	v_cvt_pk_bf16_f32 v121, v126, v127
	v_lshlrev_b32_e32 v124, 16, v246
	v_cvt_pk_bf16_f32 v122, v122, v123
	v_cvt_pk_bf16_f32 v123, v240, v241
	global_store_dwordx4 v[248:249], v[120:123], off
	v_and_b32_e32 v125, 0xffff0000, v246
	v_lshlrev_b32_e32 v126, 16, v247
	v_lshlrev_b32_e32 v120, 16, v244
	v_and_b32_e32 v121, 0xffff0000, v244
	v_and_b32_e32 v127, 0xffff0000, v247
	v_lshlrev_b32_e32 v122, 16, v245
	v_and_b32_e32 v123, 0xffff0000, v245
	v_pk_fma_f32 v[116:117], v[116:117], v[132:133], v[120:121]
	v_pk_fma_f32 v[120:121], v[114:115], v[130:131], v[126:127]
	v_pk_fma_f32 v[114:115], v[112:113], v[128:129], v[124:125]
	v_pk_fma_f32 v[118:119], v[118:119], v[134:135], v[122:123]
	v_cvt_pk_bf16_f32 v112, v116, v117
	v_lshlrev_b32_e32 v116, 16, v197
	v_cvt_pk_bf16_f32 v113, v118, v119
	v_cvt_pk_bf16_f32 v114, v114, v115
	v_cvt_pk_bf16_f32 v115, v120, v121
	global_store_dwordx4 v[248:249], v[112:115], off offset:256
	v_and_b32_e32 v117, 0xffff0000, v197
	v_lshlrev_b32_e32 v118, 16, v198
	v_lshlrev_b32_e32 v114, 16, v196
	v_and_b32_e32 v115, 0xffff0000, v196
	v_and_b32_e32 v119, 0xffff0000, v198
	v_lshlrev_b32_e32 v120, 16, v199
	v_and_b32_e32 v121, 0xffff0000, v199
	v_lshl_add_u64 v[112:113], v[222:223], 0, v[232:233]
	v_pk_fma_f32 v[110:111], v[110:111], v[142:143], v[116:117]
	v_pk_fma_f32 v[108:109], v[108:109], v[140:141], v[114:115]
	v_pk_fma_f32 v[114:115], v[106:107], v[138:139], v[120:121]
	v_pk_fma_f32 v[106:107], v[104:105], v[136:137], v[118:119]
	v_cvt_pk_bf16_f32 v104, v108, v109
	v_cvt_pk_bf16_f32 v105, v110, v111
	v_lshlrev_b32_e32 v108, 16, v194
	v_cvt_pk_bf16_f32 v106, v106, v107
	v_cvt_pk_bf16_f32 v107, v114, v115
	global_store_dwordx4 v[112:113], v[104:107], off
	v_and_b32_e32 v109, 0xffff0000, v194
	v_lshlrev_b32_e32 v110, 16, v195
	v_lshlrev_b32_e32 v104, 16, v192
	v_and_b32_e32 v105, 0xffff0000, v192
	v_and_b32_e32 v111, 0xffff0000, v195
	v_lshlrev_b32_e32 v106, 16, v193
	v_and_b32_e32 v107, 0xffff0000, v193
	v_pk_fma_f32 v[100:101], v[100:101], v[132:133], v[104:105]
	v_pk_fma_f32 v[104:105], v[98:99], v[130:131], v[110:111]
	v_pk_fma_f32 v[98:99], v[96:97], v[128:129], v[108:109]
; __device__ __forceinline__ unsigned cvt_pk_bf16(float lo, float hi) { unsigned r; asm volatile("v_cvt_pk_bf16_f32 %0, %1, %2" : "=v"(r) : "v"(lo), "v"(hi)); return r; }
; __device__ __forceinline__ float bf_lo(unsigned u) { return __uint_as_float(u << 16); }
; __device__ __forceinline__ float bf_hi(unsigned u) { return __uint_as_float(u & 0xffff0000u); }
;     __device__ __forceinline__ void operator()(const AccT& acc, const Unit& u, int wr, int wc, int fr, int fq) const {
;     ...
;         for (int ai = 0; ai < 2; ++ai)
; #pragma unroll
;             for (int m = 0; m < 4; ++m)
; #pragma unroll
;                 for (int bj = 0; bj < 2; ++bj) {
;                     const u32x4 q = r[ai][m][bj];
;                     const f32x4 r0 = {bf_lo(q.x), bf_hi(q.x), bf_lo(q.y), bf_hi(q.y)}, r1 = {bf_lo(q.z), bf_hi(q.z), bf_lo(q.w), bf_hi(q.w)};
;                     const f32x4 h0 = r0 + gv[bj][0] * acc[ai][bj][m][0], h1 = r1 + gv[bj][1] * acc[ai][bj][m][1];
;                     u32x4 w; w.x = cvt_pk_bf16(h0[0], h0[1]); w.y = cvt_pk_bf16(h0[2], h0[3]); w.z = cvt_pk_bf16(h1[0], h1[1]); w.w = cvt_pk_bf16(h1[2], h1[3]);
;                     *(u32x4*)(out + (size_t)(wr * 64 + fr + ai * 128 + m * 16) * DM + col0 + bj * 128) = w;
;                 }
	v_pk_fma_f32 v[102:103], v[102:103], v[134:135], v[106:107]
	v_cvt_pk_bf16_f32 v96, v100, v101
	v_lshlrev_b32_e32 v100, 16, v189
	v_cvt_pk_bf16_f32 v97, v102, v103
	v_cvt_pk_bf16_f32 v98, v98, v99
	v_cvt_pk_bf16_f32 v99, v104, v105
	global_store_dwordx4 v[112:113], v[96:99], off offset:256
	v_and_b32_e32 v101, 0xffff0000, v189
	v_lshlrev_b32_e32 v102, 16, v190
	v_lshlrev_b32_e32 v98, 16, v188
	v_and_b32_e32 v99, 0xffff0000, v188
	v_and_b32_e32 v103, 0xffff0000, v190
	v_lshlrev_b32_e32 v104, 16, v191
	v_and_b32_e32 v105, 0xffff0000, v191
	v_lshl_add_u64 v[96:97], v[222:223], 0, v[230:231]
	v_pk_fma_f32 v[94:95], v[94:95], v[142:143], v[100:101]
	v_pk_fma_f32 v[92:93], v[92:93], v[140:141], v[98:99]
	v_pk_fma_f32 v[98:99], v[90:91], v[138:139], v[104:105]
	v_pk_fma_f32 v[90:91], v[88:89], v[136:137], v[102:103]
	v_cvt_pk_bf16_f32 v88, v92, v93
	v_cvt_pk_bf16_f32 v89, v94, v95
	v_lshlrev_b32_e32 v92, 16, v186
	v_cvt_pk_bf16_f32 v90, v90, v91
	v_cvt_pk_bf16_f32 v91, v98, v99
	global_store_dwordx4 v[96:97], v[88:91], off
	v_and_b32_e32 v93, 0xffff0000, v186
	v_lshlrev_b32_e32 v94, 16, v187
	v_lshlrev_b32_e32 v88, 16, v184
	v_and_b32_e32 v89, 0xffff0000, v184
	v_and_b32_e32 v95, 0xffff0000, v187
	v_lshlrev_b32_e32 v90, 16, v185
	v_and_b32_e32 v91, 0xffff0000, v185
	v_pk_fma_f32 v[84:85], v[84:85], v[132:133], v[88:89]
	v_pk_fma_f32 v[88:89], v[82:83], v[130:131], v[94:95]
	v_pk_fma_f32 v[82:83], v[80:81], v[128:129], v[92:93]
	v_pk_fma_f32 v[86:87], v[86:87], v[134:135], v[90:91]
	v_cvt_pk_bf16_f32 v80, v84, v85
	v_lshlrev_b32_e32 v84, 16, v181
	v_cvt_pk_bf16_f32 v81, v86, v87
	v_cvt_pk_bf16_f32 v82, v82, v83
	v_cvt_pk_bf16_f32 v83, v88, v89
	global_store_dwordx4 v[96:97], v[80:83], off offset:256
	v_and_b32_e32 v85, 0xffff0000, v181
	v_lshlrev_b32_e32 v86, 16, v182
	v_lshlrev_b32_e32 v82, 16, v180
	v_and_b32_e32 v83, 0xffff0000, v180
	v_and_b32_e32 v87, 0xffff0000, v182
	v_lshlrev_b32_e32 v88, 16, v183
	v_and_b32_e32 v89, 0xffff0000, v183
	v_lshl_add_u64 v[80:81], v[222:223], 0, v[228:229]
	v_pk_fma_f32 v[78:79], v[78:79], v[142:143], v[84:85]
	v_pk_fma_f32 v[76:77], v[76:77], v[140:141], v[82:83]
	v_pk_fma_f32 v[82:83], v[74:75], v[138:139], v[88:89]
	v_pk_fma_f32 v[74:75], v[72:73], v[136:137], v[86:87]
	v_cvt_pk_bf16_f32 v72, v76, v77
	v_cvt_pk_bf16_f32 v73, v78, v79
	v_lshlrev_b32_e32 v76, 16, v178
	v_cvt_pk_bf16_f32 v74, v74, v75
	v_cvt_pk_bf16_f32 v75, v82, v83
	global_store_dwordx4 v[80:81], v[72:75], off
	v_and_b32_e32 v77, 0xffff0000, v178
	v_lshlrev_b32_e32 v78, 16, v179
	v_lshlrev_b32_e32 v72, 16, v176
	v_and_b32_e32 v73, 0xffff0000, v176
	v_and_b32_e32 v79, 0xffff0000, v179
	v_lshlrev_b32_e32 v74, 16, v177
	v_and_b32_e32 v75, 0xffff0000, v177
	v_pk_fma_f32 v[68:69], v[68:69], v[132:133], v[72:73]
	v_pk_fma_f32 v[72:73], v[66:67], v[130:131], v[78:79]
	v_pk_fma_f32 v[66:67], v[64:65], v[128:129], v[76:77]
	v_pk_fma_f32 v[70:71], v[70:71], v[134:135], v[74:75]
	v_cvt_pk_bf16_f32 v64, v68, v69
	v_lshlrev_b32_e32 v68, 16, v173
	v_cvt_pk_bf16_f32 v65, v70, v71
	v_cvt_pk_bf16_f32 v66, v66, v67
	v_cvt_pk_bf16_f32 v67, v72, v73
	global_store_dwordx4 v[80:81], v[64:67], off offset:256
	v_and_b32_e32 v69, 0xffff0000, v173
	v_lshlrev_b32_e32 v70, 16, v174
	v_lshlrev_b32_e32 v66, 16, v172
	v_and_b32_e32 v67, 0xffff0000, v172
	v_and_b32_e32 v71, 0xffff0000, v174
	v_lshlrev_b32_e32 v72, 16, v175
	v_and_b32_e32 v73, 0xffff0000, v175
	v_lshl_add_u64 v[64:65], v[222:223], 0, v[226:227]
	v_pk_fma_f32 v[62:63], v[62:63], v[142:143], v[68:69]
	v_pk_fma_f32 v[60:61], v[60:61], v[140:141], v[66:67]
	v_pk_fma_f32 v[66:67], v[58:59], v[138:139], v[72:73]
	v_pk_fma_f32 v[58:59], v[56:57], v[136:137], v[70:71]
	v_cvt_pk_bf16_f32 v56, v60, v61
	v_cvt_pk_bf16_f32 v57, v62, v63
	v_lshlrev_b32_e32 v60, 16, v170
	v_cvt_pk_bf16_f32 v58, v58, v59
	v_cvt_pk_bf16_f32 v59, v66, v67
	global_store_dwordx4 v[64:65], v[56:59], off
	v_and_b32_e32 v61, 0xffff0000, v170
	v_lshlrev_b32_e32 v62, 16, v171
	v_lshlrev_b32_e32 v56, 16, v168
	v_and_b32_e32 v57, 0xffff0000, v168
	v_and_b32_e32 v63, 0xffff0000, v171
	v_lshlrev_b32_e32 v58, 16, v169
	v_and_b32_e32 v59, 0xffff0000, v169
	v_pk_fma_f32 v[52:53], v[52:53], v[132:133], v[56:57]
	v_pk_fma_f32 v[56:57], v[50:51], v[130:131], v[62:63]
	v_pk_fma_f32 v[50:51], v[48:49], v[128:129], v[60:61]
	v_pk_fma_f32 v[54:55], v[54:55], v[134:135], v[58:59]
	v_cvt_pk_bf16_f32 v48, v52, v53
	v_lshlrev_b32_e32 v52, 16, v165
	v_cvt_pk_bf16_f32 v49, v54, v55
; __device__ __forceinline__ unsigned cvt_pk_bf16(float lo, float hi) { unsigned r; asm volatile("v_cvt_pk_bf16_f32 %0, %1, %2" : "=v"(r) : "v"(lo), "v"(hi)); return r; }
; __device__ __forceinline__ float bf_lo(unsigned u) { return __uint_as_float(u << 16); }
; __device__ __forceinline__ float bf_hi(unsigned u) { return __uint_as_float(u & 0xffff0000u); }
; #define PG8_WAIT_V(n) asm volatile("s_waitcnt vmcnt(" #n ")" ::: "memory")
; #define PG8_BAR __builtin_amdgcn_s_barrier()
; template <class Epi, class Sched>
; __device__ __forceinline__ void gemm_phase(LAS unsigned char* lds, const Gemm g, const Sched& S, const Epi& E) {
;     ...
;         if (!has_next) break;
; #pragma unroll
;         for (int a = 0; a < 2; ++a)
; #pragma unroll
;             for (int b = 0; b < 2; ++b)
; #pragma unroll
;                 for (int m = 0; m < 4; ++m)
; #pragma unroll
;                     for (int n = 0; n < 2; ++n) acc[a][b][m][n] = (f32x4){0.f, 0.f, 0.f, 0.f};
;         cur = nxt; cA = nA; cB = nB; ++ui;
;     }
;     PG8_WAIT_V(0);
;     if (wr == 0) PG8_BAR;
;     PG8_BAR;
;     __device__ __forceinline__ void operator()(const AccT& acc, const Unit& u, int wr, int wc, int fr, int fq) const {
;     ...
;         for (int ai = 0; ai < 2; ++ai)
; #pragma unroll
;             for (int m = 0; m < 4; ++m)
; #pragma unroll
;                 for (int bj = 0; bj < 2; ++bj) {
;                     const u32x4 q = r[ai][m][bj];
;                     const f32x4 r0 = {bf_lo(q.x), bf_hi(q.x), bf_lo(q.y), bf_hi(q.y)}, r1 = {bf_lo(q.z), bf_hi(q.z), bf_lo(q.w), bf_hi(q.w)};
;                     const f32x4 h0 = r0 + gv[bj][0] * acc[ai][bj][m][0], h1 = r1 + gv[bj][1] * acc[ai][bj][m][1];
;                     u32x4 w; w.x = cvt_pk_bf16(h0[0], h0[1]); w.y = cvt_pk_bf16(h0[2], h0[3]); w.z = cvt_pk_bf16(h1[0], h1[1]); w.w = cvt_pk_bf16(h1[2], h1[3]);
;                     *(u32x4*)(out + (size_t)(wr * 64 + fr + ai * 128 + m * 16) * DM + col0 + bj * 128) = w;
;                 }
	v_cvt_pk_bf16_f32 v50, v50, v51
	v_cvt_pk_bf16_f32 v51, v56, v57
	global_store_dwordx4 v[64:65], v[48:51], off offset:256
	v_and_b32_e32 v53, 0xffff0000, v165
	v_lshlrev_b32_e32 v54, 16, v166
	v_lshlrev_b32_e32 v50, 16, v164
	v_and_b32_e32 v51, 0xffff0000, v164
	v_and_b32_e32 v55, 0xffff0000, v166
	v_lshlrev_b32_e32 v56, 16, v167
	v_and_b32_e32 v57, 0xffff0000, v167
	v_lshl_add_u64 v[48:49], v[222:223], 0, v[224:225]
	v_pk_fma_f32 v[46:47], v[46:47], v[142:143], v[52:53]
	v_pk_fma_f32 v[44:45], v[44:45], v[140:141], v[50:51]
	v_pk_fma_f32 v[50:51], v[42:43], v[138:139], v[56:57]
	v_pk_fma_f32 v[42:43], v[40:41], v[136:137], v[54:55]
	v_cvt_pk_bf16_f32 v40, v44, v45
	v_cvt_pk_bf16_f32 v41, v46, v47
	v_lshlrev_b32_e32 v44, 16, v162
	v_cvt_pk_bf16_f32 v42, v42, v43
	v_cvt_pk_bf16_f32 v43, v50, v51
	global_store_dwordx4 v[48:49], v[40:43], off
	v_and_b32_e32 v45, 0xffff0000, v162
	v_lshlrev_b32_e32 v46, 16, v163
	v_lshlrev_b32_e32 v40, 16, v160
	v_and_b32_e32 v41, 0xffff0000, v160
	v_and_b32_e32 v47, 0xffff0000, v163
	v_lshlrev_b32_e32 v42, 16, v161
	v_and_b32_e32 v43, 0xffff0000, v161
	v_pk_fma_f32 v[36:37], v[36:37], v[132:133], v[40:41]
	v_pk_fma_f32 v[40:41], v[34:35], v[130:131], v[46:47]
	v_pk_fma_f32 v[34:35], v[32:33], v[128:129], v[44:45]
	v_pk_fma_f32 v[38:39], v[38:39], v[134:135], v[42:43]
	v_cvt_pk_bf16_f32 v32, v36, v37
	v_lshlrev_b32_e32 v36, 16, v157
	v_cvt_pk_bf16_f32 v33, v38, v39
	v_cvt_pk_bf16_f32 v34, v34, v35
	v_cvt_pk_bf16_f32 v35, v40, v41
	global_store_dwordx4 v[48:49], v[32:35], off offset:256
	v_and_b32_e32 v37, 0xffff0000, v157
	v_lshlrev_b32_e32 v38, 16, v158
	v_lshlrev_b32_e32 v34, 16, v156
	v_and_b32_e32 v35, 0xffff0000, v156
	v_and_b32_e32 v39, 0xffff0000, v158
	v_lshlrev_b32_e32 v40, 16, v159
	v_and_b32_e32 v41, 0xffff0000, v159
	v_lshl_add_u64 v[32:33], v[222:223], 0, v[220:221]
	v_pk_fma_f32 v[30:31], v[30:31], v[142:143], v[36:37]
	v_pk_fma_f32 v[28:29], v[28:29], v[140:141], v[34:35]
	v_pk_fma_f32 v[34:35], v[26:27], v[138:139], v[40:41]
	v_pk_fma_f32 v[26:27], v[24:25], v[136:137], v[38:39]
	v_cvt_pk_bf16_f32 v24, v28, v29
	v_cvt_pk_bf16_f32 v25, v30, v31
	v_lshlrev_b32_e32 v28, 16, v154
	v_cvt_pk_bf16_f32 v26, v26, v27
	v_cvt_pk_bf16_f32 v27, v34, v35
	global_store_dwordx4 v[32:33], v[24:27], off
	v_and_b32_e32 v29, 0xffff0000, v154
	v_lshlrev_b32_e32 v30, 16, v155
	v_lshlrev_b32_e32 v24, 16, v152
	v_and_b32_e32 v25, 0xffff0000, v152
	v_and_b32_e32 v31, 0xffff0000, v155
	v_lshlrev_b32_e32 v26, 16, v153
	v_and_b32_e32 v27, 0xffff0000, v153
	v_pk_fma_f32 v[20:21], v[20:21], v[132:133], v[24:25]
	v_pk_fma_f32 v[24:25], v[18:19], v[130:131], v[30:31]
	v_pk_fma_f32 v[18:19], v[16:17], v[128:129], v[28:29]
	v_pk_fma_f32 v[22:23], v[22:23], v[134:135], v[26:27]
	v_cvt_pk_bf16_f32 v16, v20, v21
	v_lshlrev_b32_e32 v20, 16, v149
	v_cvt_pk_bf16_f32 v17, v22, v23
	v_cvt_pk_bf16_f32 v18, v18, v19
	v_cvt_pk_bf16_f32 v19, v24, v25
	global_store_dwordx4 v[32:33], v[16:19], off offset:256
	v_and_b32_e32 v21, 0xffff0000, v149
	v_lshlrev_b32_e32 v22, 16, v150
	v_lshlrev_b32_e32 v18, 16, v148
	v_and_b32_e32 v19, 0xffff0000, v148
	v_and_b32_e32 v23, 0xffff0000, v150
	v_lshlrev_b32_e32 v24, 16, v151
	v_and_b32_e32 v25, 0xffff0000, v151
	v_lshl_add_u64 v[16:17], v[222:223], 0, v[218:219]
	v_pk_fma_f32 v[14:15], v[14:15], v[142:143], v[20:21]
	v_pk_fma_f32 v[12:13], v[12:13], v[140:141], v[18:19]
	v_pk_fma_f32 v[18:19], v[10:11], v[138:139], v[24:25]
	v_pk_fma_f32 v[10:11], v[8:9], v[136:137], v[22:23]
	v_cvt_pk_bf16_f32 v8, v12, v13
	v_cvt_pk_bf16_f32 v9, v14, v15
	v_lshlrev_b32_e32 v12, 16, v146
	v_cvt_pk_bf16_f32 v10, v10, v11
	v_cvt_pk_bf16_f32 v11, v18, v19
	global_store_dwordx4 v[16:17], v[8:11], off
	v_and_b32_e32 v13, 0xffff0000, v146
	v_lshlrev_b32_e32 v14, 16, v147
	v_lshlrev_b32_e32 v8, 16, v144
	v_and_b32_e32 v9, 0xffff0000, v144
	v_and_b32_e32 v15, 0xffff0000, v147
	v_lshlrev_b32_e32 v10, 16, v145
	v_and_b32_e32 v11, 0xffff0000, v145
	v_pk_fma_f32 v[4:5], v[4:5], v[132:133], v[8:9]
	v_pk_fma_f32 v[8:9], v[2:3], v[130:131], v[14:15]
	v_pk_fma_f32 v[2:3], v[0:1], v[128:129], v[12:13]
	v_pk_fma_f32 v[6:7], v[6:7], v[134:135], v[10:11]
	v_cvt_pk_bf16_f32 v0, v4, v5
	s_nop 0
	v_cvt_pk_bf16_f32 v1, v6, v7
	v_cvt_pk_bf16_f32 v2, v2, v3
	v_cvt_pk_bf16_f32 v3, v8, v9
	global_store_dwordx4 v[16:17], v[0:3], off offset:256
	s_cbranch_vccz .LBB0_891
	s_waitcnt vmcnt(0)
	s_cmpk_gt_u32 s33, 0xff
	s_cbranch_scc1 .LBB0_906
	s_barrier

; #define PG8_STAGE(bufoff, gbase, voff) do { _Pragma("unroll") for (int _i = 0; _i < 2; ++_i) \
;         __builtin_amdgcn_global_load_lds((const unsigned*)((const char*)(gbase) + (voff)[_i]), (LAS unsigned*)(lds + (bufoff) + ldsw + _i * 8192), 16, 0, 0); } while (0)
; #define PG8_LDA(dst, b, h) do { _Pragma("unroll") for (int m = 0; m < 4; ++m) _Pragma("unroll") for (int k = 0; k < 2; ++k) dst[m][k] = *(const LAS bf16x8*)(lds + PG8_SA(b, h) + aoff + m * 2048 + k * 1024); } while (0)
; #define PG8_LDB(dst, b, h) do { _Pragma("unroll") for (int n = 0; n < 2; ++n) _Pragma("unroll") for (int k = 0; k < 2; ++k) dst[n][k] = *(const LAS bf16x8*)(lds + PG8_SB(b, h) + boff + n * 2048 + k * 1024); } while (0)
; #define PG8_MMA(ai, bj, At, Bt) do { __builtin_amdgcn_s_setprio(1); _Pragma("unroll") for (int m = 0; m < 4; ++m) _Pragma("unroll") for (int n = 0; n < 2; ++n) _Pragma("unroll") for (int k = 0; k < 2; ++k) \
;         acc[ai][bj][m][n] = __builtin_amdgcn_mfma_f32_16x16x32_bf16(Bt[n][k], At[m][k], acc[ai][bj][m][n], 0, 0, 0); __builtin_amdgcn_s_setprio(0); } while (0)
; #define PG8_WAIT_L(n) asm volatile("s_waitcnt lgkmcnt(" #n ")" ::: "memory")
; template <class Epi, class Sched>
; __device__ __forceinline__ void gemm_phase(LAS unsigned char* lds, const Gemm g, const Sched& S, const Epi& E) {
;     ...
;     for (;;) {
;         const bool has_next = S.next(ui + 1, nxt);
;         const char* nA = has_next ? (const char*)g.A + (size_t)nxt.pm * tstep : cA; const char* nB = has_next ? (const char*)g.Bt + (size_t)nxt.pn * tstep : cB;
;         for (int t = 0; t < nt; t += 2) {
;             const bool last = (t == nt - 2);
;             const char* a1 = cA + (size_t)(t + 1) * kstep;
;             const char* a2 = last ? nA : cA + (size_t)(t + 2) * kstep; const char* b2 = last ? nB : cB + (size_t)(t + 2) * kstep;
;             const char* a3 = a2 + kstep; const char* b3 = b2 + kstep;
;             PG8_LDB(B0, 0, 0); PG8_SCHED; PG8_LDA(At, 0, 0); PG8_STAGE(PG8_SA(1, 1), a1 + hstep, voffA);
;             PG8_WAIT_L(8); PG8_BAR; PG8_WAIT_L(0); PG8_MMA(0, 0, At, B0); PG8_BAR; PG8_SCHED;
;             PG8_LDB(B1, 0, 1); PG8_STAGE(PG8_SB(0, 0), b2, voffB);
;             PG8_BAR; PG8_WAIT_L(0); PG8_MMA(0, 1, At, B1); PG8_BAR;
;             PG8_LDA(At, 0, 1); PG8_STAGE(PG8_SA(0, 0), a2, voffA);
;             PG8_BAR; PG8_WAIT_L(0); PG8_MMA(1, 0, At, B0); PG8_BAR; PG8_SCHED;
.LBB0_1020:
	s_ashr_i32 s7, s6, 31
	v_cmp_lt_i64_e32 vcc, s[10:11], v[140:141]
	s_lshl_b64 s[10:11], s[6:7], 19
	s_add_u32 s10, s96, s10
	s_addc_u32 s11, s97, s11
	s_and_b64 s[12:13], vcc, exec
	s_cselect_b32 s7, s11, s17
	s_cselect_b32 s42, s10, s16
	s_ashr_i32 s5, s4, 31
	s_lshl_b64 s[12:13], s[4:5], 19
	s_add_u32 s12, s23, s12
	s_addc_u32 s13, s24, s13
	s_and_b64 s[20:21], vcc, exec
	s_cselect_b32 s5, s13, s19
	s_cselect_b32 s43, s12, s18
	s_add_u32 s16, s16, 0x40080
	s_addc_u32 s17, s17, 0
	s_add_u32 s44, s18, 0x100
	s_addc_u32 s45, s19, 0
	s_mov_b32 s46, -2
	ds_read_b128 v[150:153], v147
	ds_read_b128 v[154:157], v147 offset:1024
	ds_read_b128 v[158:161], v147 offset:2048
	ds_read_b128 v[162:165], v147 offset:3072
	s_add_u32 s18, s16, 0xfffc0080
	s_addc_u32 s19, s17, -1
	s_cmp_eq_u32 s46, 12
	s_cselect_b32 s21, s7, s19
	s_cselect_b32 s20, s42, s18
	s_cselect_b32 s19, s5, s45
	s_cselect_b32 s18, s43, s44
	s_add_i32 m0, s15, 0xc000
	ds_read_b128 v[166:169], v148
	ds_read_b128 v[170:173], v148 offset:1024
	ds_read_b128 v[174:177], v148 offset:2048
	ds_read_b128 v[178:181], v148 offset:3072
	ds_read_b128 v[182:185], v148 offset:4096
	ds_read_b128 v[186:189], v148 offset:5120
	ds_read_b128 v[190:193], v148 offset:6144
	ds_read_b128 v[194:197], v148 offset:7168
	global_load_lds_dwordx4 v136, s[16:17]
	s_add_i32 m0, s15, 0xe000
	s_nop 0
	global_load_lds_dwordx4 v138, s[16:17]
	s_waitcnt vmcnt(10)
	s_barrier
	s_waitcnt lgkmcnt(0)
	s_setprio 1
	s_waitcnt lgkmcnt(0)
	v_mfma_f32_16x16x32_bf16 v[124:127], v[150:153], v[166:169], 0
	v_mfma_f32_16x16x32_bf16 v[116:119], v[158:161], v[166:169], 0
	v_mfma_f32_16x16x32_bf16 v[108:111], v[150:153], v[174:177], 0
	v_mfma_f32_16x16x32_bf16 v[100:103], v[158:161], v[174:177], 0
	v_mfma_f32_16x16x32_bf16 v[92:95], v[150:153], v[182:185], 0
	v_mfma_f32_16x16x32_bf16 v[84:87], v[158:161], v[182:185], 0
	v_mfma_f32_16x16x32_bf16 v[76:79], v[150:153], v[190:193], 0
	v_mfma_f32_16x16x32_bf16 v[68:71], v[158:161], v[190:193], 0
	v_mfma_f32_16x16x32_bf16 v[124:127], v[154:157], v[170:173], v[124:127]
	v_mfma_f32_16x16x32_bf16 v[116:119], v[162:165], v[170:173], v[116:119]
	v_mfma_f32_16x16x32_bf16 v[108:111], v[154:157], v[178:181], v[108:111]
	v_mfma_f32_16x16x32_bf16 v[100:103], v[162:165], v[178:181], v[100:103]
	v_mfma_f32_16x16x32_bf16 v[92:95], v[154:157], v[186:189], v[92:95]
	v_mfma_f32_16x16x32_bf16 v[84:87], v[162:165], v[186:189], v[84:87]
	v_mfma_f32_16x16x32_bf16 v[76:79], v[154:157], v[194:197], v[76:79]
	v_mfma_f32_16x16x32_bf16 v[68:71], v[162:165], v[194:197], v[68:71]
	s_setprio 0
	s_barrier
	s_add_i32 s47, s38, s25
	s_mov_b32 m0, s47
	ds_read_b128 v[202:205], v149
	ds_read_b128 v[206:209], v149 offset:1024
	ds_read_b128 v[210:213], v149 offset:2048
	ds_read_b128 v[214:217], v149 offset:3072
	global_load_lds_dwordx4 v132, s[18:19]
	s_add_i32 m0, s47, 0x2000
	s_nop 0
	global_load_lds_dwordx4 v128, s[18:19]
	s_waitcnt vmcnt(10)
	s_barrier
	s_waitcnt lgkmcnt(0)
	s_setprio 1
	s_waitcnt lgkmcnt(0)
	v_mfma_f32_16x16x32_bf16 v[120:123], v[202:205], v[166:169], 0
	v_mfma_f32_16x16x32_bf16 v[112:115], v[210:213], v[166:169], 0
	v_mfma_f32_16x16x32_bf16 v[104:107], v[202:205], v[174:177], 0
	v_mfma_f32_16x16x32_bf16 v[96:99], v[210:213], v[174:177], 0
	v_mfma_f32_16x16x32_bf16 v[88:91], v[202:205], v[182:185], 0
	v_mfma_f32_16x16x32_bf16 v[80:83], v[210:213], v[182:185], 0
	v_mfma_f32_16x16x32_bf16 v[72:75], v[202:205], v[190:193], 0
	v_mfma_f32_16x16x32_bf16 v[64:67], v[210:213], v[190:193], 0
	v_mfma_f32_16x16x32_bf16 v[120:123], v[206:209], v[170:173], v[120:123]
	v_mfma_f32_16x16x32_bf16 v[112:115], v[214:217], v[170:173], v[112:115]
	v_mfma_f32_16x16x32_bf16 v[104:107], v[206:209], v[178:181], v[104:107]
	v_mfma_f32_16x16x32_bf16 v[96:99], v[214:217], v[178:181], v[96:99]
	v_mfma_f32_16x16x32_bf16 v[88:91], v[206:209], v[186:189], v[88:91]
	v_mfma_f32_16x16x32_bf16 v[80:83], v[214:217], v[186:189], v[80:83]
	v_mfma_f32_16x16x32_bf16 v[72:75], v[206:209], v[194:197], v[72:75]
	v_mfma_f32_16x16x32_bf16 v[64:67], v[214:217], v[194:197], v[64:67]
	s_setprio 0
	s_mov_b32 m0, s15
	v_lshl_add_u64 v[220:221], s[20:21], 0, v[134:135]
	s_barrier
	ds_read_b128 v[166:169], v148 offset:16384
	ds_read_b128 v[170:173], v148 offset:17408
	ds_read_b128 v[174:177], v148 offset:18432
	ds_read_b128 v[178:181], v148 offset:19456
	ds_read_b128 v[182:185], v148 offset:20480
	ds_read_b128 v[186:189], v148 offset:21504
	ds_read_b128 v[190:193], v148 offset:22528
	ds_read_b128 v[194:197], v148 offset:23552
	global_load_lds_dwordx4 v134, s[20:21]
	v_lshl_add_u64 v[222:223], s[20:21], 0, v[130:131]
	s_mov_b32 m0, s28
	s_nop 0
	global_load_lds_dwordx4 v130, s[20:21]
	s_barrier
	s_waitcnt lgkmcnt(0)
	s_setprio 1
	s_waitcnt lgkmcnt(0)
	v_mfma_f32_16x16x32_bf16 v[60:63], v[150:153], v[166:169], 0
	v_mfma_f32_16x16x32_bf16 v[56:59], v[158:161], v[166:169], 0
	v_mfma_f32_16x16x32_bf16 v[44:47], v[150:153], v[174:177], 0
	v_mfma_f32_16x16x32_bf16 v[40:43], v[158:161], v[174:177], 0
	v_mfma_f32_16x16x32_bf16 v[28:31], v[150:153], v[182:185], 0
	v_mfma_f32_16x16x32_bf16 v[24:27], v[158:161], v[182:185], 0
	v_mfma_f32_16x16x32_bf16 v[12:15], v[150:153], v[190:193], 0
	v_mfma_f32_16x16x32_bf16 v[8:11], v[158:161], v[190:193], 0
	v_mfma_f32_16x16x32_bf16 v[60:63], v[154:157], v[170:173], v[60:63]
	v_mfma_f32_16x16x32_bf16 v[56:59], v[162:165], v[170:173], v[56:59]
	v_mfma_f32_16x16x32_bf16 v[44:47], v[154:157], v[178:181], v[44:47]
	v_mfma_f32_16x16x32_bf16 v[40:43], v[162:165], v[178:181], v[40:43]
	v_mfma_f32_16x16x32_bf16 v[28:31], v[154:157], v[186:189], v[28:31]
	v_mfma_f32_16x16x32_bf16 v[24:27], v[162:165], v[186:189], v[24:27]
	v_mfma_f32_16x16x32_bf16 v[12:15], v[154:157], v[194:197], v[12:15]
	v_mfma_f32_16x16x32_bf16 v[8:11], v[162:165], v[194:197], v[8:11]
	s_setprio 0
	s_barrier
; #define PG8_STAGE(bufoff, gbase, voff) do { _Pragma("unroll") for (int _i = 0; _i < 2; ++_i) \
;         __builtin_amdgcn_global_load_lds((const unsigned*)((const char*)(gbase) + (voff)[_i]), (LAS unsigned*)(lds + (bufoff) + ldsw + _i * 8192), 16, 0, 0); } while (0)
; #define PG8_LDA(dst, b, h) do { _Pragma("unroll") for (int m = 0; m < 4; ++m) _Pragma("unroll") for (int k = 0; k < 2; ++k) dst[m][k] = *(const LAS bf16x8*)(lds + PG8_SA(b, h) + aoff + m * 2048 + k * 1024); } while (0)
; #define PG8_LDB(dst, b, h) do { _Pragma("unroll") for (int n = 0; n < 2; ++n) _Pragma("unroll") for (int k = 0; k < 2; ++k) dst[n][k] = *(const LAS bf16x8*)(lds + PG8_SB(b, h) + boff + n * 2048 + k * 1024); } while (0)
; #define PG8_MMA(ai, bj, At, Bt) do { __builtin_amdgcn_s_setprio(1); _Pragma("unroll") for (int m = 0; m < 4; ++m) _Pragma("unroll") for (int n = 0; n < 2; ++n) _Pragma("unroll") for (int k = 0; k < 2; ++k) \
;         acc[ai][bj][m][n] = __builtin_amdgcn_mfma_f32_16x16x32_bf16(Bt[n][k], At[m][k], acc[ai][bj][m][n], 0, 0, 0); __builtin_amdgcn_s_setprio(0); } while (0)
; #define PG8_WAIT_V(n) asm volatile("s_waitcnt vmcnt(" #n ")" ::: "memory")
; #define PG8_WAIT_L(n) asm volatile("s_waitcnt lgkmcnt(" #n ")" ::: "memory")
; #define PG8_BAR __builtin_amdgcn_s_barrier()
; #define PG8_SCHED __builtin_amdgcn_sched_barrier(0)
; template <class Epi, class Sched>
; __device__ __forceinline__ void gemm_phase(LAS unsigned char* lds, const Gemm g, const Sched& S, const Epi& E) {
;     ...
;             PG8_LDA(At, 0, 1); PG8_STAGE(PG8_SA(0, 0), a2, voffA);
;             PG8_BAR; PG8_WAIT_L(0); PG8_MMA(1, 0, At, B0); PG8_BAR; PG8_SCHED;
;             PG8_STAGE(PG8_SB(0, 1), b2 + hstep, voffB);
;             PG8_WAIT_V(6); PG8_BAR; PG8_MMA(1, 1, At, B1); PG8_BAR;
;             PG8_LDB(B0, 1, 0); PG8_SCHED; PG8_LDA(At, 1, 0); PG8_STAGE(PG8_SA(0, 1), a2 + hstep, voffA);
;             PG8_WAIT_L(8); PG8_BAR; PG8_WAIT_L(0); PG8_MMA(0, 0, At, B0); PG8_BAR; PG8_SCHED;
;             PG8_LDB(B1, 1, 1); PG8_STAGE(PG8_SB(1, 0), b3, voffB);
;             PG8_BAR; PG8_WAIT_L(0); PG8_MMA(0, 1, At, B1); PG8_BAR;
;             PG8_LDA(At, 1, 1); PG8_STAGE(PG8_SA(1, 0), a3, voffA);
;             PG8_BAR; PG8_WAIT_L(0); PG8_MMA(1, 0, At, B0); PG8_BAR; PG8_SCHED;
	s_add_u32 s48, s18, 0x40000
	s_addc_u32 s49, s19, 0
	s_add_i32 s47, s39, s25
	s_mov_b32 m0, s47
	s_nop 0
	global_load_lds_dwordx4 v132, s[48:49]
	s_add_i32 m0, s47, 0x2000
	s_nop 0
	global_load_lds_dwordx4 v128, s[48:49]
	s_add_u32 s20, s20, 0x40000
	s_addc_u32 s21, s21, 0
	s_mov_b32 m0, s29
	s_nop 0
	global_load_lds_dwordx4 v134, s[20:21]
	s_mov_b32 m0, s30
	s_nop 0
	global_load_lds_dwordx4 v130, s[20:21]
	s_waitcnt vmcnt(12)
	s_barrier
	s_setprio 1
	v_mfma_f32_16x16x32_bf16 v[52:55], v[202:205], v[166:169], 0
	v_mfma_f32_16x16x32_bf16 v[48:51], v[210:213], v[166:169], 0
	v_mfma_f32_16x16x32_bf16 v[36:39], v[202:205], v[174:177], 0
	v_mfma_f32_16x16x32_bf16 v[32:35], v[210:213], v[174:177], 0
	v_mfma_f32_16x16x32_bf16 v[20:23], v[202:205], v[182:185], 0
	v_mfma_f32_16x16x32_bf16 v[16:19], v[210:213], v[182:185], 0
	v_mfma_f32_16x16x32_bf16 v[4:7], v[202:205], v[190:193], 0
	v_mfma_f32_16x16x32_bf16 v[0:3], v[210:213], v[190:193], 0
	v_mfma_f32_16x16x32_bf16 v[52:55], v[206:209], v[170:173], v[52:55]
	v_mfma_f32_16x16x32_bf16 v[48:51], v[214:217], v[170:173], v[48:51]
	v_mfma_f32_16x16x32_bf16 v[36:39], v[206:209], v[178:181], v[36:39]
	v_mfma_f32_16x16x32_bf16 v[32:35], v[214:217], v[178:181], v[32:35]
	v_mfma_f32_16x16x32_bf16 v[20:23], v[206:209], v[186:189], v[20:23]
	v_mfma_f32_16x16x32_bf16 v[16:19], v[214:217], v[186:189], v[16:19]
	v_mfma_f32_16x16x32_bf16 v[4:7], v[206:209], v[194:197], v[4:7]
	v_mfma_f32_16x16x32_bf16 v[0:3], v[214:217], v[194:197], v[0:3]
	s_setprio 0
	s_add_i32 s47, 0, 0x18000
	v_add_u32_e32 v162, s47, v146
	s_barrier
	ds_read_b128 v[150:153], v162
	ds_read_b128 v[154:157], v162 offset:1024
	ds_read_b128 v[158:161], v162 offset:2048
	ds_read_b128 v[162:165], v162 offset:3072
	ds_read_b128 v[166:169], v148 offset:32768
	ds_read_b128 v[170:173], v148 offset:33792
	ds_read_b128 v[174:177], v148 offset:34816
	ds_read_b128 v[178:181], v148 offset:35840
	ds_read_b128 v[182:185], v148 offset:36864
	ds_read_b128 v[186:189], v148 offset:37888
	ds_read_b128 v[190:193], v148 offset:38912
	ds_read_b128 v[194:197], v148 offset:39936
	s_waitcnt vmcnt(10)
	s_barrier
	s_waitcnt lgkmcnt(0)
	s_setprio 1
	s_waitcnt lgkmcnt(0)
	v_mfma_f32_16x16x32_bf16 v[124:127], v[150:153], v[166:169], v[124:127]
	v_mfma_f32_16x16x32_bf16 v[116:119], v[158:161], v[166:169], v[116:119]
	v_mfma_f32_16x16x32_bf16 v[108:111], v[150:153], v[174:177], v[108:111]
	v_mfma_f32_16x16x32_bf16 v[100:103], v[158:161], v[174:177], v[100:103]
	v_mfma_f32_16x16x32_bf16 v[92:95], v[150:153], v[182:185], v[92:95]
	v_mfma_f32_16x16x32_bf16 v[84:87], v[158:161], v[182:185], v[84:87]
	v_mfma_f32_16x16x32_bf16 v[76:79], v[150:153], v[190:193], v[76:79]
	v_mfma_f32_16x16x32_bf16 v[68:71], v[158:161], v[190:193], v[68:71]
	v_mfma_f32_16x16x32_bf16 v[124:127], v[154:157], v[170:173], v[124:127]
	v_mfma_f32_16x16x32_bf16 v[116:119], v[162:165], v[170:173], v[116:119]
	v_mfma_f32_16x16x32_bf16 v[108:111], v[154:157], v[178:181], v[108:111]
	v_mfma_f32_16x16x32_bf16 v[100:103], v[162:165], v[178:181], v[100:103]
	v_mfma_f32_16x16x32_bf16 v[92:95], v[154:157], v[186:189], v[92:95]
	v_mfma_f32_16x16x32_bf16 v[84:87], v[162:165], v[186:189], v[84:87]
	v_mfma_f32_16x16x32_bf16 v[76:79], v[154:157], v[194:197], v[76:79]
	v_mfma_f32_16x16x32_bf16 v[68:71], v[162:165], v[194:197], v[68:71]
	s_setprio 0
	s_barrier
	s_add_i32 s20, 0, 0x1c000
	s_add_i32 s21, s47, s25
	v_add_u32_e32 v214, s20, v146
	s_add_u32 s0, s18, 0x80
	s_addc_u32 s1, s19, 0
	s_mov_b32 m0, s21
	ds_read_b128 v[202:205], v214
	ds_read_b128 v[206:209], v214 offset:1024
	ds_read_b128 v[210:213], v214 offset:2048
	ds_read_b128 v[214:217], v214 offset:3072
	global_load_lds_dwordx4 v132, s[0:1]
	s_add_i32 m0, s21, 0x2000
	s_nop 0
	global_load_lds_dwordx4 v128, s[0:1]
	s_waitcnt vmcnt(10)
	s_barrier
	s_waitcnt lgkmcnt(0)
	s_setprio 1
	s_waitcnt lgkmcnt(0)
	v_mfma_f32_16x16x32_bf16 v[120:123], v[202:205], v[166:169], v[120:123]
	v_mfma_f32_16x16x32_bf16 v[112:115], v[210:213], v[166:169], v[112:115]
	v_mfma_f32_16x16x32_bf16 v[104:107], v[202:205], v[174:177], v[104:107]
	v_mfma_f32_16x16x32_bf16 v[96:99], v[210:213], v[174:177], v[96:99]
	v_mfma_f32_16x16x32_bf16 v[88:91], v[202:205], v[182:185], v[88:91]
	v_mfma_f32_16x16x32_bf16 v[80:83], v[210:213], v[182:185], v[80:83]
	v_mfma_f32_16x16x32_bf16 v[72:75], v[202:205], v[190:193], v[72:75]
	v_mfma_f32_16x16x32_bf16 v[64:67], v[210:213], v[190:193], v[64:67]
	v_mfma_f32_16x16x32_bf16 v[120:123], v[206:209], v[170:173], v[120:123]
	v_mfma_f32_16x16x32_bf16 v[112:115], v[214:217], v[170:173], v[112:115]
	v_mfma_f32_16x16x32_bf16 v[104:107], v[206:209], v[178:181], v[104:107]
	v_mfma_f32_16x16x32_bf16 v[96:99], v[214:217], v[178:181], v[96:99]
	v_mfma_f32_16x16x32_bf16 v[88:91], v[206:209], v[186:189], v[88:91]
	v_mfma_f32_16x16x32_bf16 v[80:83], v[214:217], v[186:189], v[80:83]
	v_mfma_f32_16x16x32_bf16 v[72:75], v[206:209], v[194:197], v[72:75]
	v_mfma_f32_16x16x32_bf16 v[64:67], v[214:217], v[194:197], v[64:67]
	s_setprio 0
	s_mov_b32 m0, s35
	s_mov_b64 s[0:1], 0x80
	v_lshl_add_u64 v[198:199], v[220:221], 0, s[0:1]
	s_barrier
	ds_read_b128 v[166:169], v148 offset:49152
	ds_read_b128 v[170:173], v148 offset:50176
	ds_read_b128 v[174:177], v148 offset:51200
	ds_read_b128 v[178:181], v148 offset:52224
	ds_read_b128 v[182:185], v148 offset:53248
	ds_read_b128 v[186:189], v148 offset:54272
	ds_read_b128 v[190:193], v148 offset:55296
	ds_read_b128 v[194:197], v148 offset:56320
	global_load_lds_dwordx4 v[198:199], off
	v_lshl_add_u64 v[198:199], v[222:223], 0, s[0:1]
	s_mov_b32 m0, s36
	s_nop 0
	global_load_lds_dwordx4 v[198:199], off
	s_barrier
; #define PG8_STAGE(bufoff, gbase, voff) do { _Pragma("unroll") for (int _i = 0; _i < 2; ++_i) \
;         __builtin_amdgcn_global_load_lds((const unsigned*)((const char*)(gbase) + (voff)[_i]), (LAS unsigned*)(lds + (bufoff) + ldsw + _i * 8192), 16, 0, 0); } while (0)
; #define PG8_LDA(dst, b, h) do { _Pragma("unroll") for (int m = 0; m < 4; ++m) _Pragma("unroll") for (int k = 0; k < 2; ++k) dst[m][k] = *(const LAS bf16x8*)(lds + PG8_SA(b, h) + aoff + m * 2048 + k * 1024); } while (0)
; #define PG8_LDB(dst, b, h) do { _Pragma("unroll") for (int n = 0; n < 2; ++n) _Pragma("unroll") for (int k = 0; k < 2; ++k) dst[n][k] = *(const LAS bf16x8*)(lds + PG8_SB(b, h) + boff + n * 2048 + k * 1024); } while (0)
; #define PG8_MMA(ai, bj, At, Bt) do { __builtin_amdgcn_s_setprio(1); _Pragma("unroll") for (int m = 0; m < 4; ++m) _Pragma("unroll") for (int n = 0; n < 2; ++n) _Pragma("unroll") for (int k = 0; k < 2; ++k) \
;         acc[ai][bj][m][n] = __builtin_amdgcn_mfma_f32_16x16x32_bf16(Bt[n][k], At[m][k], acc[ai][bj][m][n], 0, 0, 0); __builtin_amdgcn_s_setprio(0); } while (0)
; #define PG8_WAIT_V(n) asm volatile("s_waitcnt vmcnt(" #n ")" ::: "memory")
; #define PG8_WAIT_L(n) asm volatile("s_waitcnt lgkmcnt(" #n ")" ::: "memory")
; #define PG8_BAR __builtin_amdgcn_s_barrier()
; #define PG8_SCHED __builtin_amdgcn_sched_barrier(0)
; template <class Epi, class Sched>
; __device__ __forceinline__ void gemm_phase(LAS unsigned char* lds, const Gemm g, const Sched& S, const Epi& E) {
;     ...
;             PG8_LDB(B0, 0, 0); PG8_SCHED; PG8_LDA(At, 0, 0); PG8_STAGE(PG8_SA(1, 1), a1 + hstep, voffA);
;             PG8_WAIT_L(8); PG8_BAR; PG8_WAIT_L(0); PG8_MMA(0, 0, At, B0); PG8_BAR; PG8_SCHED;
;             PG8_LDB(B1, 0, 1); PG8_STAGE(PG8_SB(0, 0), b2, voffB);
;             PG8_BAR; PG8_WAIT_L(0); PG8_MMA(0, 1, At, B1); PG8_BAR;
;     ...
;             PG8_LDA(At, 1, 1); PG8_STAGE(PG8_SA(1, 0), a3, voffA);
;             PG8_BAR; PG8_WAIT_L(0); PG8_MMA(1, 0, At, B0); PG8_BAR; PG8_SCHED;
;             PG8_STAGE(PG8_SB(1, 1), b3 + hstep, voffB);
;             PG8_WAIT_V(6); PG8_BAR; PG8_MMA(1, 1, At, B1); PG8_BAR;
	s_waitcnt lgkmcnt(0)
	s_setprio 1
	s_waitcnt lgkmcnt(0)
	v_mfma_f32_16x16x32_bf16 v[60:63], v[150:153], v[166:169], v[60:63]
	v_mfma_f32_16x16x32_bf16 v[56:59], v[158:161], v[166:169], v[56:59]
	v_mfma_f32_16x16x32_bf16 v[44:47], v[150:153], v[174:177], v[44:47]
	v_mfma_f32_16x16x32_bf16 v[40:43], v[158:161], v[174:177], v[40:43]
	v_mfma_f32_16x16x32_bf16 v[28:31], v[150:153], v[182:185], v[28:31]
	v_mfma_f32_16x16x32_bf16 v[24:27], v[158:161], v[182:185], v[24:27]
	v_mfma_f32_16x16x32_bf16 v[12:15], v[150:153], v[190:193], v[12:15]
	v_mfma_f32_16x16x32_bf16 v[8:11], v[158:161], v[190:193], v[8:11]
	v_mfma_f32_16x16x32_bf16 v[60:63], v[154:157], v[170:173], v[60:63]
	v_mfma_f32_16x16x32_bf16 v[56:59], v[162:165], v[170:173], v[56:59]
	v_mfma_f32_16x16x32_bf16 v[44:47], v[154:157], v[178:181], v[44:47]
	v_mfma_f32_16x16x32_bf16 v[40:43], v[162:165], v[178:181], v[40:43]
	v_mfma_f32_16x16x32_bf16 v[28:31], v[154:157], v[186:189], v[28:31]
	v_mfma_f32_16x16x32_bf16 v[24:27], v[162:165], v[186:189], v[24:27]
	v_mfma_f32_16x16x32_bf16 v[12:15], v[154:157], v[194:197], v[12:15]
	v_mfma_f32_16x16x32_bf16 v[8:11], v[162:165], v[194:197], v[8:11]
	s_setprio 0
	s_barrier
	s_add_u32 s18, s18, 0x40080
	s_addc_u32 s19, s19, 0
	s_add_i32 s20, s20, s25
	s_mov_b32 m0, s20
	s_nop 0
	global_load_lds_dwordx4 v132, s[18:19]
	s_add_i32 m0, s20, 0x2000
	s_nop 0
	global_load_lds_dwordx4 v128, s[18:19]
	s_waitcnt vmcnt(10)
	s_barrier
	s_setprio 1
	v_mfma_f32_16x16x32_bf16 v[52:55], v[202:205], v[166:169], v[52:55]
	v_mfma_f32_16x16x32_bf16 v[48:51], v[210:213], v[166:169], v[48:51]
	v_mfma_f32_16x16x32_bf16 v[36:39], v[202:205], v[174:177], v[36:39]
	v_mfma_f32_16x16x32_bf16 v[32:35], v[210:213], v[174:177], v[32:35]
	v_mfma_f32_16x16x32_bf16 v[20:23], v[202:205], v[182:185], v[20:23]
	v_mfma_f32_16x16x32_bf16 v[16:19], v[210:213], v[182:185], v[16:19]
	v_mfma_f32_16x16x32_bf16 v[4:7], v[202:205], v[190:193], v[4:7]
	v_mfma_f32_16x16x32_bf16 v[0:3], v[210:213], v[190:193], v[0:3]
	v_mfma_f32_16x16x32_bf16 v[52:55], v[206:209], v[170:173], v[52:55]
	v_mfma_f32_16x16x32_bf16 v[48:51], v[214:217], v[170:173], v[48:51]
	v_mfma_f32_16x16x32_bf16 v[36:39], v[206:209], v[178:181], v[36:39]
	v_mfma_f32_16x16x32_bf16 v[32:35], v[214:217], v[178:181], v[32:35]
	v_mfma_f32_16x16x32_bf16 v[20:23], v[206:209], v[186:189], v[20:23]
	v_mfma_f32_16x16x32_bf16 v[16:19], v[214:217], v[186:189], v[16:19]
	v_mfma_f32_16x16x32_bf16 v[4:7], v[206:209], v[194:197], v[4:7]
	v_mfma_f32_16x16x32_bf16 v[0:3], v[214:217], v[194:197], v[0:3]
	s_setprio 0
	s_add_i32 s46, s46, 2
	s_add_u32 s16, s16, 0x100
	s_addc_u32 s17, s17, 0
	s_add_u32 s44, s44, 0x100
	s_addc_u32 s45, s45, 0
	s_cmp_gt_u32 s46, 13
	s_barrier
.LBB0_1021:
	ds_read_b128 v[150:153], v147
	ds_read_b128 v[154:157], v147 offset:1024
	ds_read_b128 v[158:161], v147 offset:2048
	ds_read_b128 v[162:165], v147 offset:3072
	s_add_u32 s18, s16, 0xfffc0080
	s_addc_u32 s19, s17, -1
	s_cmp_eq_u32 s46, 12
	s_cselect_b32 s21, s7, s19
	s_cselect_b32 s20, s42, s18
	s_cselect_b32 s19, s5, s45
	s_cselect_b32 s18, s43, s44
	s_add_i32 m0, s15, 0xc000
	ds_read_b128 v[166:169], v148
	ds_read_b128 v[170:173], v148 offset:1024
	ds_read_b128 v[174:177], v148 offset:2048
	ds_read_b128 v[178:181], v148 offset:3072
	ds_read_b128 v[182:185], v148 offset:4096
	ds_read_b128 v[186:189], v148 offset:5120
	ds_read_b128 v[190:193], v148 offset:6144
	ds_read_b128 v[194:197], v148 offset:7168
	global_load_lds_dwordx4 v136, s[16:17]
	s_add_i32 m0, s15, 0xe000
	s_nop 0
	global_load_lds_dwordx4 v138, s[16:17]
	s_waitcnt vmcnt(10)
	s_barrier
	s_waitcnt lgkmcnt(0)
	s_setprio 1
	s_waitcnt lgkmcnt(0)
	v_mfma_f32_16x16x32_bf16 v[124:127], v[150:153], v[166:169], v[124:127]
	v_mfma_f32_16x16x32_bf16 v[116:119], v[158:161], v[166:169], v[116:119]
	v_mfma_f32_16x16x32_bf16 v[108:111], v[150:153], v[174:177], v[108:111]
	v_mfma_f32_16x16x32_bf16 v[100:103], v[158:161], v[174:177], v[100:103]
	v_mfma_f32_16x16x32_bf16 v[92:95], v[150:153], v[182:185], v[92:95]
	v_mfma_f32_16x16x32_bf16 v[84:87], v[158:161], v[182:185], v[84:87]
	v_mfma_f32_16x16x32_bf16 v[76:79], v[150:153], v[190:193], v[76:79]
	v_mfma_f32_16x16x32_bf16 v[68:71], v[158:161], v[190:193], v[68:71]
	v_mfma_f32_16x16x32_bf16 v[124:127], v[154:157], v[170:173], v[124:127]
	v_mfma_f32_16x16x32_bf16 v[116:119], v[162:165], v[170:173], v[116:119]
	v_mfma_f32_16x16x32_bf16 v[108:111], v[154:157], v[178:181], v[108:111]
	v_mfma_f32_16x16x32_bf16 v[100:103], v[162:165], v[178:181], v[100:103]
	v_mfma_f32_16x16x32_bf16 v[92:95], v[154:157], v[186:189], v[92:95]
	v_mfma_f32_16x16x32_bf16 v[84:87], v[162:165], v[186:189], v[84:87]
	v_mfma_f32_16x16x32_bf16 v[76:79], v[154:157], v[194:197], v[76:79]
	v_mfma_f32_16x16x32_bf16 v[68:71], v[162:165], v[194:197], v[68:71]
	s_setprio 0
	s_barrier
	s_add_i32 s47, s38, s25
	s_mov_b32 m0, s47
	ds_read_b128 v[202:205], v149
	ds_read_b128 v[206:209], v149 offset:1024
	ds_read_b128 v[210:213], v149 offset:2048
	ds_read_b128 v[214:217], v149 offset:3072
	global_load_lds_dwordx4 v132, s[18:19]
	s_add_i32 m0, s47, 0x2000
	s_nop 0
	global_load_lds_dwordx4 v128, s[18:19]
	s_waitcnt vmcnt(10)
	s_barrier
; #define PG8_STAGE(bufoff, gbase, voff) do { _Pragma("unroll") for (int _i = 0; _i < 2; ++_i) \
;         __builtin_amdgcn_global_load_lds((const unsigned*)((const char*)(gbase) + (voff)[_i]), (LAS unsigned*)(lds + (bufoff) + ldsw + _i * 8192), 16, 0, 0); } while (0)
; #define PG8_LDA(dst, b, h) do { _Pragma("unroll") for (int m = 0; m < 4; ++m) _Pragma("unroll") for (int k = 0; k < 2; ++k) dst[m][k] = *(const LAS bf16x8*)(lds + PG8_SA(b, h) + aoff + m * 2048 + k * 1024); } while (0)
; #define PG8_LDB(dst, b, h) do { _Pragma("unroll") for (int n = 0; n < 2; ++n) _Pragma("unroll") for (int k = 0; k < 2; ++k) dst[n][k] = *(const LAS bf16x8*)(lds + PG8_SB(b, h) + boff + n * 2048 + k * 1024); } while (0)
; #define PG8_MMA(ai, bj, At, Bt) do { __builtin_amdgcn_s_setprio(1); _Pragma("unroll") for (int m = 0; m < 4; ++m) _Pragma("unroll") for (int n = 0; n < 2; ++n) _Pragma("unroll") for (int k = 0; k < 2; ++k) \
;         acc[ai][bj][m][n] = __builtin_amdgcn_mfma_f32_16x16x32_bf16(Bt[n][k], At[m][k], acc[ai][bj][m][n], 0, 0, 0); __builtin_amdgcn_s_setprio(0); } while (0)
; #define PG8_WAIT_V(n) asm volatile("s_waitcnt vmcnt(" #n ")" ::: "memory")
; #define PG8_WAIT_L(n) asm volatile("s_waitcnt lgkmcnt(" #n ")" ::: "memory")
; #define PG8_BAR __builtin_amdgcn_s_barrier()
; #define PG8_SCHED __builtin_amdgcn_sched_barrier(0)
; template <class Epi, class Sched>
; __device__ __forceinline__ void gemm_phase(LAS unsigned char* lds, const Gemm g, const Sched& S, const Epi& E) {
;     ...
;             PG8_BAR; PG8_WAIT_L(0); PG8_MMA(0, 1, At, B1); PG8_BAR;
;             PG8_LDA(At, 0, 1); PG8_STAGE(PG8_SA(0, 0), a2, voffA);
;             PG8_BAR; PG8_WAIT_L(0); PG8_MMA(1, 0, At, B0); PG8_BAR; PG8_SCHED;
;             PG8_STAGE(PG8_SB(0, 1), b2 + hstep, voffB);
;             PG8_WAIT_V(6); PG8_BAR; PG8_MMA(1, 1, At, B1); PG8_BAR;
;             PG8_LDB(B0, 1, 0); PG8_SCHED; PG8_LDA(At, 1, 0); PG8_STAGE(PG8_SA(0, 1), a2 + hstep, voffA);
;             PG8_WAIT_L(8); PG8_BAR; PG8_WAIT_L(0); PG8_MMA(0, 0, At, B0); PG8_BAR; PG8_SCHED;
;             PG8_LDB(B1, 1, 1); PG8_STAGE(PG8_SB(1, 0), b3, voffB);
;             PG8_BAR; PG8_WAIT_L(0); PG8_MMA(0, 1, At, B1); PG8_BAR;
	s_waitcnt lgkmcnt(0)
	s_setprio 1
	s_waitcnt lgkmcnt(0)
	v_mfma_f32_16x16x32_bf16 v[120:123], v[202:205], v[166:169], v[120:123]
	v_mfma_f32_16x16x32_bf16 v[112:115], v[210:213], v[166:169], v[112:115]
	v_mfma_f32_16x16x32_bf16 v[104:107], v[202:205], v[174:177], v[104:107]
	v_mfma_f32_16x16x32_bf16 v[96:99], v[210:213], v[174:177], v[96:99]
	v_mfma_f32_16x16x32_bf16 v[88:91], v[202:205], v[182:185], v[88:91]
	v_mfma_f32_16x16x32_bf16 v[80:83], v[210:213], v[182:185], v[80:83]
	v_mfma_f32_16x16x32_bf16 v[72:75], v[202:205], v[190:193], v[72:75]
	v_mfma_f32_16x16x32_bf16 v[64:67], v[210:213], v[190:193], v[64:67]
	v_mfma_f32_16x16x32_bf16 v[120:123], v[206:209], v[170:173], v[120:123]
	v_mfma_f32_16x16x32_bf16 v[112:115], v[214:217], v[170:173], v[112:115]
	v_mfma_f32_16x16x32_bf16 v[104:107], v[206:209], v[178:181], v[104:107]
	v_mfma_f32_16x16x32_bf16 v[96:99], v[214:217], v[178:181], v[96:99]
	v_mfma_f32_16x16x32_bf16 v[88:91], v[206:209], v[186:189], v[88:91]
	v_mfma_f32_16x16x32_bf16 v[80:83], v[214:217], v[186:189], v[80:83]
	v_mfma_f32_16x16x32_bf16 v[72:75], v[206:209], v[194:197], v[72:75]
	v_mfma_f32_16x16x32_bf16 v[64:67], v[214:217], v[194:197], v[64:67]
	s_setprio 0
	s_mov_b32 m0, s15
	v_lshl_add_u64 v[220:221], s[20:21], 0, v[134:135]
	s_barrier
	ds_read_b128 v[166:169], v148 offset:16384
	ds_read_b128 v[170:173], v148 offset:17408
	ds_read_b128 v[174:177], v148 offset:18432
	ds_read_b128 v[178:181], v148 offset:19456
	ds_read_b128 v[182:185], v148 offset:20480
	ds_read_b128 v[186:189], v148 offset:21504
	ds_read_b128 v[190:193], v148 offset:22528
	ds_read_b128 v[194:197], v148 offset:23552
	global_load_lds_dwordx4 v134, s[20:21]
	v_lshl_add_u64 v[222:223], s[20:21], 0, v[130:131]
	s_mov_b32 m0, s28
	s_nop 0
	global_load_lds_dwordx4 v130, s[20:21]
	s_barrier
	s_waitcnt lgkmcnt(0)
	s_setprio 1
	s_waitcnt lgkmcnt(0)
	v_mfma_f32_16x16x32_bf16 v[60:63], v[150:153], v[166:169], v[60:63]
	v_mfma_f32_16x16x32_bf16 v[56:59], v[158:161], v[166:169], v[56:59]
	v_mfma_f32_16x16x32_bf16 v[44:47], v[150:153], v[174:177], v[44:47]
	v_mfma_f32_16x16x32_bf16 v[40:43], v[158:161], v[174:177], v[40:43]
	v_mfma_f32_16x16x32_bf16 v[28:31], v[150:153], v[182:185], v[28:31]
	v_mfma_f32_16x16x32_bf16 v[24:27], v[158:161], v[182:185], v[24:27]
	v_mfma_f32_16x16x32_bf16 v[12:15], v[150:153], v[190:193], v[12:15]
	v_mfma_f32_16x16x32_bf16 v[8:11], v[158:161], v[190:193], v[8:11]
	v_mfma_f32_16x16x32_bf16 v[60:63], v[154:157], v[170:173], v[60:63]
	v_mfma_f32_16x16x32_bf16 v[56:59], v[162:165], v[170:173], v[56:59]
	v_mfma_f32_16x16x32_bf16 v[44:47], v[154:157], v[178:181], v[44:47]
	v_mfma_f32_16x16x32_bf16 v[40:43], v[162:165], v[178:181], v[40:43]
	v_mfma_f32_16x16x32_bf16 v[28:31], v[154:157], v[186:189], v[28:31]
	v_mfma_f32_16x16x32_bf16 v[24:27], v[162:165], v[186:189], v[24:27]
	v_mfma_f32_16x16x32_bf16 v[12:15], v[154:157], v[194:197], v[12:15]
	v_mfma_f32_16x16x32_bf16 v[8:11], v[162:165], v[194:197], v[8:11]
	s_setprio 0
	s_barrier
	s_add_u32 s48, s18, 0x40000
	s_addc_u32 s49, s19, 0
	s_add_i32 s47, s39, s25
	s_mov_b32 m0, s47
	s_nop 0
	global_load_lds_dwordx4 v132, s[48:49]
	s_add_i32 m0, s47, 0x2000
	s_nop 0
	global_load_lds_dwordx4 v128, s[48:49]
	s_add_u32 s20, s20, 0x40000
	s_addc_u32 s21, s21, 0
	s_mov_b32 m0, s29
	s_nop 0
	global_load_lds_dwordx4 v134, s[20:21]
	s_mov_b32 m0, s30
	s_nop 0
	global_load_lds_dwordx4 v130, s[20:21]
	s_waitcnt vmcnt(12)
	s_barrier
	s_setprio 1
	v_mfma_f32_16x16x32_bf16 v[52:55], v[202:205], v[166:169], v[52:55]
	v_mfma_f32_16x16x32_bf16 v[48:51], v[210:213], v[166:169], v[48:51]
	v_mfma_f32_16x16x32_bf16 v[36:39], v[202:205], v[174:177], v[36:39]
	v_mfma_f32_16x16x32_bf16 v[32:35], v[210:213], v[174:177], v[32:35]
	v_mfma_f32_16x16x32_bf16 v[20:23], v[202:205], v[182:185], v[20:23]
	v_mfma_f32_16x16x32_bf16 v[16:19], v[210:213], v[182:185], v[16:19]
	v_mfma_f32_16x16x32_bf16 v[4:7], v[202:205], v[190:193], v[4:7]
	v_mfma_f32_16x16x32_bf16 v[0:3], v[210:213], v[190:193], v[0:3]
	v_mfma_f32_16x16x32_bf16 v[52:55], v[206:209], v[170:173], v[52:55]
	v_mfma_f32_16x16x32_bf16 v[48:51], v[214:217], v[170:173], v[48:51]
	v_mfma_f32_16x16x32_bf16 v[36:39], v[206:209], v[178:181], v[36:39]
	v_mfma_f32_16x16x32_bf16 v[32:35], v[214:217], v[178:181], v[32:35]
	v_mfma_f32_16x16x32_bf16 v[20:23], v[206:209], v[186:189], v[20:23]
	v_mfma_f32_16x16x32_bf16 v[16:19], v[214:217], v[186:189], v[16:19]
	v_mfma_f32_16x16x32_bf16 v[4:7], v[206:209], v[194:197], v[4:7]
	v_mfma_f32_16x16x32_bf16 v[0:3], v[214:217], v[194:197], v[0:3]
	s_setprio 0
	s_add_i32 s47, 0, 0x18000
	v_add_u32_e32 v162, s47, v146
	s_barrier
	ds_read_b128 v[150:153], v162
	ds_read_b128 v[154:157], v162 offset:1024
	ds_read_b128 v[158:161], v162 offset:2048
	ds_read_b128 v[162:165], v162 offset:3072
	ds_read_b128 v[166:169], v148 offset:32768
	ds_read_b128 v[170:173], v148 offset:33792
	ds_read_b128 v[174:177], v148 offset:34816
	ds_read_b128 v[178:181], v148 offset:35840
	ds_read_b128 v[182:185], v148 offset:36864
	ds_read_b128 v[186:189], v148 offset:37888
	ds_read_b128 v[190:193], v148 offset:38912
	ds_read_b128 v[194:197], v148 offset:39936
	s_waitcnt vmcnt(10)
	s_barrier
; #define PG8_STAGE(bufoff, gbase, voff) do { _Pragma("unroll") for (int _i = 0; _i < 2; ++_i) \
;         __builtin_amdgcn_global_load_lds((const unsigned*)((const char*)(gbase) + (voff)[_i]), (LAS unsigned*)(lds + (bufoff) + ldsw + _i * 8192), 16, 0, 0); } while (0)
; #define PG8_LDA(dst, b, h) do { _Pragma("unroll") for (int m = 0; m < 4; ++m) _Pragma("unroll") for (int k = 0; k < 2; ++k) dst[m][k] = *(const LAS bf16x8*)(lds + PG8_SA(b, h) + aoff + m * 2048 + k * 1024); } while (0)
; #define PG8_MMA(ai, bj, At, Bt) do { __builtin_amdgcn_s_setprio(1); _Pragma("unroll") for (int m = 0; m < 4; ++m) _Pragma("unroll") for (int n = 0; n < 2; ++n) _Pragma("unroll") for (int k = 0; k < 2; ++k) \
;         acc[ai][bj][m][n] = __builtin_amdgcn_mfma_f32_16x16x32_bf16(Bt[n][k], At[m][k], acc[ai][bj][m][n], 0, 0, 0); __builtin_amdgcn_s_setprio(0); } while (0)
; #define PG8_WAIT_V(n) asm volatile("s_waitcnt vmcnt(" #n ")" ::: "memory")
; #define PG8_WAIT_L(n) asm volatile("s_waitcnt lgkmcnt(" #n ")" ::: "memory")
; #define PG8_BAR __builtin_amdgcn_s_barrier()
; #define PG8_SCHED __builtin_amdgcn_sched_barrier(0)
; template <class Epi, class Sched>
; __device__ __forceinline__ void gemm_phase(LAS unsigned char* lds, const Gemm g, const Sched& S, const Epi& E) {
;     ...
;             PG8_BAR; PG8_WAIT_L(0); PG8_MMA(0, 1, At, B1); PG8_BAR;
;             PG8_LDA(At, 1, 1); PG8_STAGE(PG8_SA(1, 0), a3, voffA);
;             PG8_BAR; PG8_WAIT_L(0); PG8_MMA(1, 0, At, B0); PG8_BAR; PG8_SCHED;
;             PG8_STAGE(PG8_SB(1, 1), b3 + hstep, voffB);
;             PG8_WAIT_V(6); PG8_BAR; PG8_MMA(1, 1, At, B1); PG8_BAR;
	s_waitcnt lgkmcnt(0)
	s_setprio 1
	s_waitcnt lgkmcnt(0)
	v_mfma_f32_16x16x32_bf16 v[124:127], v[150:153], v[166:169], v[124:127]
	v_mfma_f32_16x16x32_bf16 v[116:119], v[158:161], v[166:169], v[116:119]
	v_mfma_f32_16x16x32_bf16 v[108:111], v[150:153], v[174:177], v[108:111]
	v_mfma_f32_16x16x32_bf16 v[100:103], v[158:161], v[174:177], v[100:103]
	v_mfma_f32_16x16x32_bf16 v[92:95], v[150:153], v[182:185], v[92:95]
	v_mfma_f32_16x16x32_bf16 v[84:87], v[158:161], v[182:185], v[84:87]
	v_mfma_f32_16x16x32_bf16 v[76:79], v[150:153], v[190:193], v[76:79]
	v_mfma_f32_16x16x32_bf16 v[68:71], v[158:161], v[190:193], v[68:71]
	v_mfma_f32_16x16x32_bf16 v[124:127], v[154:157], v[170:173], v[124:127]
	v_mfma_f32_16x16x32_bf16 v[116:119], v[162:165], v[170:173], v[116:119]
	v_mfma_f32_16x16x32_bf16 v[108:111], v[154:157], v[178:181], v[108:111]
	v_mfma_f32_16x16x32_bf16 v[100:103], v[162:165], v[178:181], v[100:103]
	v_mfma_f32_16x16x32_bf16 v[92:95], v[154:157], v[186:189], v[92:95]
	v_mfma_f32_16x16x32_bf16 v[84:87], v[162:165], v[186:189], v[84:87]
	v_mfma_f32_16x16x32_bf16 v[76:79], v[154:157], v[194:197], v[76:79]
	v_mfma_f32_16x16x32_bf16 v[68:71], v[162:165], v[194:197], v[68:71]
	s_setprio 0
	s_barrier
	s_add_i32 s20, 0, 0x1c000
	s_add_i32 s21, s47, s25
	v_add_u32_e32 v214, s20, v146
	s_add_u32 s0, s18, 0x80
	s_addc_u32 s1, s19, 0
	s_mov_b32 m0, s21
	ds_read_b128 v[202:205], v214
	ds_read_b128 v[206:209], v214 offset:1024
	ds_read_b128 v[210:213], v214 offset:2048
	ds_read_b128 v[214:217], v214 offset:3072
	global_load_lds_dwordx4 v132, s[0:1]
	s_add_i32 m0, s21, 0x2000
	s_nop 0
	global_load_lds_dwordx4 v128, s[0:1]
	s_waitcnt vmcnt(10)
	s_barrier
	s_waitcnt lgkmcnt(0)
	s_setprio 1
	s_waitcnt lgkmcnt(0)
	v_mfma_f32_16x16x32_bf16 v[120:123], v[202:205], v[166:169], v[120:123]
	v_mfma_f32_16x16x32_bf16 v[112:115], v[210:213], v[166:169], v[112:115]
	v_mfma_f32_16x16x32_bf16 v[104:107], v[202:205], v[174:177], v[104:107]
	v_mfma_f32_16x16x32_bf16 v[96:99], v[210:213], v[174:177], v[96:99]
	v_mfma_f32_16x16x32_bf16 v[88:91], v[202:205], v[182:185], v[88:91]
	v_mfma_f32_16x16x32_bf16 v[80:83], v[210:213], v[182:185], v[80:83]
	v_mfma_f32_16x16x32_bf16 v[72:75], v[202:205], v[190:193], v[72:75]
	v_mfma_f32_16x16x32_bf16 v[64:67], v[210:213], v[190:193], v[64:67]
	v_mfma_f32_16x16x32_bf16 v[120:123], v[206:209], v[170:173], v[120:123]
	v_mfma_f32_16x16x32_bf16 v[112:115], v[214:217], v[170:173], v[112:115]
	v_mfma_f32_16x16x32_bf16 v[104:107], v[206:209], v[178:181], v[104:107]
	v_mfma_f32_16x16x32_bf16 v[96:99], v[214:217], v[178:181], v[96:99]
	v_mfma_f32_16x16x32_bf16 v[88:91], v[206:209], v[186:189], v[88:91]
	v_mfma_f32_16x16x32_bf16 v[80:83], v[214:217], v[186:189], v[80:83]
	v_mfma_f32_16x16x32_bf16 v[72:75], v[206:209], v[194:197], v[72:75]
	v_mfma_f32_16x16x32_bf16 v[64:67], v[214:217], v[194:197], v[64:67]
	s_setprio 0
	s_mov_b32 m0, s35
	s_mov_b64 s[0:1], 0x80
	v_lshl_add_u64 v[198:199], v[220:221], 0, s[0:1]
	s_barrier
	ds_read_b128 v[166:169], v148 offset:49152
	ds_read_b128 v[170:173], v148 offset:50176
	ds_read_b128 v[174:177], v148 offset:51200
	ds_read_b128 v[178:181], v148 offset:52224
	ds_read_b128 v[182:185], v148 offset:53248
	ds_read_b128 v[186:189], v148 offset:54272
	ds_read_b128 v[190:193], v148 offset:55296
	ds_read_b128 v[194:197], v148 offset:56320
	global_load_lds_dwordx4 v[198:199], off
	v_lshl_add_u64 v[198:199], v[222:223], 0, s[0:1]
	s_mov_b32 m0, s36
	s_nop 0
	global_load_lds_dwordx4 v[198:199], off
	s_barrier
	s_waitcnt lgkmcnt(0)
	s_setprio 1
	s_waitcnt lgkmcnt(0)
	v_mfma_f32_16x16x32_bf16 v[60:63], v[150:153], v[166:169], v[60:63]
	v_mfma_f32_16x16x32_bf16 v[56:59], v[158:161], v[166:169], v[56:59]
	v_mfma_f32_16x16x32_bf16 v[44:47], v[150:153], v[174:177], v[44:47]
	v_mfma_f32_16x16x32_bf16 v[40:43], v[158:161], v[174:177], v[40:43]
	v_mfma_f32_16x16x32_bf16 v[28:31], v[150:153], v[182:185], v[28:31]
	v_mfma_f32_16x16x32_bf16 v[24:27], v[158:161], v[182:185], v[24:27]
	v_mfma_f32_16x16x32_bf16 v[12:15], v[150:153], v[190:193], v[12:15]
	v_mfma_f32_16x16x32_bf16 v[8:11], v[158:161], v[190:193], v[8:11]
	v_mfma_f32_16x16x32_bf16 v[60:63], v[154:157], v[170:173], v[60:63]
	v_mfma_f32_16x16x32_bf16 v[56:59], v[162:165], v[170:173], v[56:59]
	v_mfma_f32_16x16x32_bf16 v[44:47], v[154:157], v[178:181], v[44:47]
	v_mfma_f32_16x16x32_bf16 v[40:43], v[162:165], v[178:181], v[40:43]
	v_mfma_f32_16x16x32_bf16 v[28:31], v[154:157], v[186:189], v[28:31]
	v_mfma_f32_16x16x32_bf16 v[24:27], v[162:165], v[186:189], v[24:27]
	v_mfma_f32_16x16x32_bf16 v[12:15], v[154:157], v[194:197], v[12:15]
	v_mfma_f32_16x16x32_bf16 v[8:11], v[162:165], v[194:197], v[8:11]
	s_setprio 0
	s_barrier
	s_add_u32 s18, s18, 0x40080
	s_addc_u32 s19, s19, 0
	s_add_i32 s20, s20, s25
	s_mov_b32 m0, s20
	s_nop 0
	global_load_lds_dwordx4 v132, s[18:19]
	s_add_i32 m0, s20, 0x2000
	s_nop 0
	global_load_lds_dwordx4 v128, s[18:19]
	s_waitcnt vmcnt(10)
	s_barrier
	s_setprio 1
	v_mfma_f32_16x16x32_bf16 v[52:55], v[202:205], v[166:169], v[52:55]
	v_mfma_f32_16x16x32_bf16 v[48:51], v[210:213], v[166:169], v[48:51]
	v_mfma_f32_16x16x32_bf16 v[36:39], v[202:205], v[174:177], v[36:39]
	v_mfma_f32_16x16x32_bf16 v[32:35], v[210:213], v[174:177], v[32:35]
	v_mfma_f32_16x16x32_bf16 v[20:23], v[202:205], v[182:185], v[20:23]
	v_mfma_f32_16x16x32_bf16 v[16:19], v[210:213], v[182:185], v[16:19]
	v_mfma_f32_16x16x32_bf16 v[4:7], v[202:205], v[190:193], v[4:7]
	v_mfma_f32_16x16x32_bf16 v[0:3], v[210:213], v[190:193], v[0:3]
	v_mfma_f32_16x16x32_bf16 v[52:55], v[206:209], v[170:173], v[52:55]
	v_mfma_f32_16x16x32_bf16 v[48:51], v[214:217], v[170:173], v[48:51]
	v_mfma_f32_16x16x32_bf16 v[36:39], v[206:209], v[178:181], v[36:39]
	v_mfma_f32_16x16x32_bf16 v[32:35], v[214:217], v[178:181], v[32:35]
	v_mfma_f32_16x16x32_bf16 v[20:23], v[206:209], v[186:189], v[20:23]
	v_mfma_f32_16x16x32_bf16 v[16:19], v[214:217], v[186:189], v[16:19]
	v_mfma_f32_16x16x32_bf16 v[4:7], v[206:209], v[194:197], v[4:7]
	v_mfma_f32_16x16x32_bf16 v[0:3], v[214:217], v[194:197], v[0:3]
	s_setprio 0
	s_add_i32 s46, s46, 2
	s_add_u32 s16, s16, 0x100
	s_addc_u32 s17, s17, 0
	s_add_u32 s44, s44, 0x100
	s_addc_u32 s45, s45, 0
	s_cmp_gt_u32 s46, 13
	s_cbranch_scc1 .Lconc_last_g11
	s_barrier
	s_branch .LBB0_1021

; #define PG8_STAGE(bufoff, gbase, voff) do { _Pragma("unroll") for (int _i = 0; _i < 2; ++_i) \
;         __builtin_amdgcn_global_load_lds((const unsigned*)((const char*)(gbase) + (voff)[_i]), (LAS unsigned*)(lds + (bufoff) + ldsw + _i * 8192), 16, 0, 0); } while (0)
; #define PG8_LDA(dst, b, h) do { _Pragma("unroll") for (int m = 0; m < 4; ++m) _Pragma("unroll") for (int k = 0; k < 2; ++k) dst[m][k] = *(const LAS bf16x8*)(lds + PG8_SA(b, h) + aoff + m * 2048 + k * 1024); } while (0)
; #define PG8_LDB(dst, b, h) do { _Pragma("unroll") for (int n = 0; n < 2; ++n) _Pragma("unroll") for (int k = 0; k < 2; ++k) dst[n][k] = *(const LAS bf16x8*)(lds + PG8_SB(b, h) + boff + n * 2048 + k * 1024); } while (0)
; #define PG8_WAIT_V(n) asm volatile("s_waitcnt vmcnt(" #n ")" ::: "memory")
; #define PG8_WAIT_L(n) asm volatile("s_waitcnt lgkmcnt(" #n ")" ::: "memory")
; #define PG8_BAR __builtin_amdgcn_s_barrier()
; #define PG8_SCHED __builtin_amdgcn_sched_barrier(0)
; template <class Epi, class Sched>
; __device__ __forceinline__ void gemm_phase(LAS unsigned char* lds, const Gemm g, const Sched& S, const Epi& E) {
;     ...
;     for (;;) {
;         const bool has_next = S.next(ui + 1, nxt);
;         const char* nA = has_next ? (const char*)g.A + (size_t)nxt.pm * tstep : cA; const char* nB = has_next ? (const char*)g.Bt + (size_t)nxt.pn * tstep : cB;
;         for (int t = 0; t < nt; t += 2) {
;             const bool last = (t == nt - 2);
;             const char* a1 = cA + (size_t)(t + 1) * kstep;
;             const char* a2 = last ? nA : cA + (size_t)(t + 2) * kstep; const char* b2 = last ? nB : cB + (size_t)(t + 2) * kstep;
;             const char* a3 = a2 + kstep; const char* b3 = b2 + kstep;
;             PG8_LDB(B0, 0, 0); PG8_SCHED; PG8_LDA(At, 0, 0); PG8_STAGE(PG8_SA(1, 1), a1 + hstep, voffA);
;             PG8_WAIT_L(8); PG8_BAR; PG8_WAIT_L(0); PG8_MMA(0, 0, At, B0); PG8_BAR; PG8_SCHED;
;             PG8_LDB(B1, 0, 1); PG8_STAGE(PG8_SB(0, 0), b2, voffB);
;             PG8_BAR; PG8_WAIT_L(0); PG8_MMA(0, 1, At, B1); PG8_BAR;
;             PG8_LDA(At, 0, 1); PG8_STAGE(PG8_SA(0, 0), a2, voffA);
;             PG8_BAR; PG8_WAIT_L(0); PG8_MMA(1, 0, At, B0); PG8_BAR; PG8_SCHED;
;             PG8_STAGE(PG8_SB(0, 1), b2 + hstep, voffB);
;             PG8_WAIT_V(6); PG8_BAR; PG8_MMA(1, 1, At, B1); PG8_BAR;
.LBB0_1096:
	s_add_u32 s54, s24, 0x100
	s_addc_u32 s55, s25, 0
	s_mov_b32 s56, -2
	ds_read_b128 v[128:131], v241
	ds_read_b128 v[132:135], v241 offset:1024
	ds_read_b128 v[136:139], v241 offset:2048
	ds_read_b128 v[140:143], v241 offset:3072
	s_add_u32 s24, s22, 0x100
	s_addc_u32 s25, s23, 0
	s_cmp_eq_u32 s56, 40
	s_cselect_b32 s29, s5, s25
	s_cselect_b32 s28, s4, s24
	s_cselect_b32 s27, s7, s55
	s_cselect_b32 s26, s6, s54
	v_lshl_add_u64 v[176:177], s[22:23], 0, v[196:197]
	s_add_i32 m0, s35, 0xc000
	ds_read_b128 v[144:147], v242
	ds_read_b128 v[148:151], v242 offset:1024
	ds_read_b128 v[152:155], v242 offset:2048
	ds_read_b128 v[156:159], v242 offset:3072
	ds_read_b128 v[160:163], v242 offset:4096
	ds_read_b128 v[164:167], v242 offset:5120
	ds_read_b128 v[168:171], v242 offset:6144
	ds_read_b128 v[172:175], v242 offset:7168
	global_load_lds_dwordx4 v[176:177], off
	v_lshl_add_u64 v[176:177], s[22:23], 0, v[198:199]
	s_add_i32 m0, s35, 0xe000
	s_nop 0
	global_load_lds_dwordx4 v[176:177], off
	s_waitcnt vmcnt(10)
	s_barrier
	s_waitcnt lgkmcnt(0)
	s_setprio 1
	s_waitcnt lgkmcnt(0)
	v_mfma_f32_16x16x32_bf16 v[124:127], v[128:131], v[144:147], 0
	v_mfma_f32_16x16x32_bf16 v[120:123], v[136:139], v[144:147], 0
	v_mfma_f32_16x16x32_bf16 v[108:111], v[128:131], v[152:155], 0
	v_mfma_f32_16x16x32_bf16 v[104:107], v[136:139], v[152:155], 0
	v_mfma_f32_16x16x32_bf16 v[92:95], v[128:131], v[160:163], 0
	v_mfma_f32_16x16x32_bf16 v[88:91], v[136:139], v[160:163], 0
	v_mfma_f32_16x16x32_bf16 v[76:79], v[128:131], v[168:171], 0
	v_mfma_f32_16x16x32_bf16 v[72:75], v[136:139], v[168:171], 0
	v_mfma_f32_16x16x32_bf16 v[124:127], v[132:135], v[148:151], v[124:127]
	v_mfma_f32_16x16x32_bf16 v[120:123], v[140:143], v[148:151], v[120:123]
	v_mfma_f32_16x16x32_bf16 v[108:111], v[132:135], v[156:159], v[108:111]
	v_mfma_f32_16x16x32_bf16 v[104:107], v[140:143], v[156:159], v[104:107]
	v_mfma_f32_16x16x32_bf16 v[92:95], v[132:135], v[164:167], v[92:95]
	v_mfma_f32_16x16x32_bf16 v[88:91], v[140:143], v[164:167], v[88:91]
	v_mfma_f32_16x16x32_bf16 v[76:79], v[132:135], v[172:175], v[76:79]
	v_mfma_f32_16x16x32_bf16 v[72:75], v[140:143], v[172:175], v[72:75]
	s_setprio 0
	s_barrier
	s_add_i32 s22, s48, s34
	s_mov_b32 m0, s22
	ds_read_b128 v[176:179], v243
	ds_read_b128 v[180:183], v243 offset:1024
	ds_read_b128 v[184:187], v243 offset:2048
	ds_read_b128 v[206:209], v243 offset:3072
	global_load_lds_dwordx4 v190, s[26:27]
	s_add_i32 m0, s22, 0x2000
	s_nop 0
	global_load_lds_dwordx4 v194, s[26:27]
	s_waitcnt vmcnt(10)
	s_barrier
	s_waitcnt lgkmcnt(0)
	s_setprio 1
	s_waitcnt lgkmcnt(0)
	v_mfma_f32_16x16x32_bf16 v[116:119], v[176:179], v[144:147], 0
	v_mfma_f32_16x16x32_bf16 v[112:115], v[184:187], v[144:147], 0
	v_mfma_f32_16x16x32_bf16 v[100:103], v[176:179], v[152:155], 0
	v_mfma_f32_16x16x32_bf16 v[96:99], v[184:187], v[152:155], 0
	v_mfma_f32_16x16x32_bf16 v[84:87], v[176:179], v[160:163], 0
	v_mfma_f32_16x16x32_bf16 v[80:83], v[184:187], v[160:163], 0
	v_mfma_f32_16x16x32_bf16 v[68:71], v[176:179], v[168:171], 0
	v_mfma_f32_16x16x32_bf16 v[64:67], v[184:187], v[168:171], 0
	v_mfma_f32_16x16x32_bf16 v[116:119], v[180:183], v[148:151], v[116:119]
	v_mfma_f32_16x16x32_bf16 v[112:115], v[206:209], v[148:151], v[112:115]
	v_mfma_f32_16x16x32_bf16 v[100:103], v[180:183], v[156:159], v[100:103]
	v_mfma_f32_16x16x32_bf16 v[96:99], v[206:209], v[156:159], v[96:99]
	v_mfma_f32_16x16x32_bf16 v[84:87], v[180:183], v[164:167], v[84:87]
	v_mfma_f32_16x16x32_bf16 v[80:83], v[206:209], v[164:167], v[80:83]
	v_mfma_f32_16x16x32_bf16 v[68:71], v[180:183], v[172:175], v[68:71]
	v_mfma_f32_16x16x32_bf16 v[64:67], v[206:209], v[172:175], v[64:67]
	s_setprio 0
	s_mov_b32 m0, s35
	v_lshl_add_u64 v[214:215], s[28:29], 0, v[188:189]
	s_barrier
	ds_read_b128 v[144:147], v242 offset:16384
	ds_read_b128 v[148:151], v242 offset:17408
	ds_read_b128 v[152:155], v242 offset:18432
	ds_read_b128 v[156:159], v242 offset:19456
	ds_read_b128 v[160:163], v242 offset:20480
	ds_read_b128 v[164:167], v242 offset:21504
	ds_read_b128 v[168:171], v242 offset:22528
	ds_read_b128 v[172:175], v242 offset:23552
	global_load_lds_dwordx4 v188, s[28:29]
	v_lshl_add_u64 v[216:217], s[28:29], 0, v[192:193]
	s_mov_b32 m0, s36
	s_nop 0
	global_load_lds_dwordx4 v192, s[28:29]
	s_barrier
	s_waitcnt lgkmcnt(0)
	s_setprio 1
	s_waitcnt lgkmcnt(0)
	v_mfma_f32_16x16x32_bf16 v[60:63], v[128:131], v[144:147], 0
	v_mfma_f32_16x16x32_bf16 v[56:59], v[136:139], v[144:147], 0
	v_mfma_f32_16x16x32_bf16 v[44:47], v[128:131], v[152:155], 0
	v_mfma_f32_16x16x32_bf16 v[40:43], v[136:139], v[152:155], 0
	v_mfma_f32_16x16x32_bf16 v[28:31], v[128:131], v[160:163], 0
	v_mfma_f32_16x16x32_bf16 v[24:27], v[136:139], v[160:163], 0
	v_mfma_f32_16x16x32_bf16 v[12:15], v[128:131], v[168:171], 0
	v_mfma_f32_16x16x32_bf16 v[8:11], v[136:139], v[168:171], 0
	v_mfma_f32_16x16x32_bf16 v[60:63], v[132:135], v[148:151], v[60:63]
	v_mfma_f32_16x16x32_bf16 v[56:59], v[140:143], v[148:151], v[56:59]
	v_mfma_f32_16x16x32_bf16 v[44:47], v[132:135], v[156:159], v[44:47]
	v_mfma_f32_16x16x32_bf16 v[40:43], v[140:143], v[156:159], v[40:43]
	v_mfma_f32_16x16x32_bf16 v[28:31], v[132:135], v[164:167], v[28:31]
	v_mfma_f32_16x16x32_bf16 v[24:27], v[140:143], v[164:167], v[24:27]
	v_mfma_f32_16x16x32_bf16 v[12:15], v[132:135], v[172:175], v[12:15]
	v_mfma_f32_16x16x32_bf16 v[8:11], v[140:143], v[172:175], v[8:11]
	s_setprio 0
	s_barrier
	s_add_u32 s22, s26, 0xb0000
	s_addc_u32 s23, s27, 0
	s_add_i32 s57, s49, s34
	s_mov_b32 m0, s57
	s_nop 0
	global_load_lds_dwordx4 v190, s[22:23]
	s_add_i32 m0, s57, 0x2000
	s_nop 0
	global_load_lds_dwordx4 v194, s[22:23]
	s_add_u32 s22, s28, 0xb0000
	s_addc_u32 s23, s29, 0
	s_mov_b32 m0, s37
	s_nop 0
	global_load_lds_dwordx4 v188, s[22:23]
	s_mov_b32 m0, s38
	s_nop 0
	global_load_lds_dwordx4 v192, s[22:23]
	s_waitcnt vmcnt(12)
	s_barrier
; #define PG8_STAGE(bufoff, gbase, voff) do { _Pragma("unroll") for (int _i = 0; _i < 2; ++_i) \
;         __builtin_amdgcn_global_load_lds((const unsigned*)((const char*)(gbase) + (voff)[_i]), (LAS unsigned*)(lds + (bufoff) + ldsw + _i * 8192), 16, 0, 0); } while (0)
; #define PG8_LDA(dst, b, h) do { _Pragma("unroll") for (int m = 0; m < 4; ++m) _Pragma("unroll") for (int k = 0; k < 2; ++k) dst[m][k] = *(const LAS bf16x8*)(lds + PG8_SA(b, h) + aoff + m * 2048 + k * 1024); } while (0)
; #define PG8_LDB(dst, b, h) do { _Pragma("unroll") for (int n = 0; n < 2; ++n) _Pragma("unroll") for (int k = 0; k < 2; ++k) dst[n][k] = *(const LAS bf16x8*)(lds + PG8_SB(b, h) + boff + n * 2048 + k * 1024); } while (0)
; #define PG8_MMA(ai, bj, At, Bt) do { __builtin_amdgcn_s_setprio(1); _Pragma("unroll") for (int m = 0; m < 4; ++m) _Pragma("unroll") for (int n = 0; n < 2; ++n) _Pragma("unroll") for (int k = 0; k < 2; ++k) \
;         acc[ai][bj][m][n] = __builtin_amdgcn_mfma_f32_16x16x32_bf16(Bt[n][k], At[m][k], acc[ai][bj][m][n], 0, 0, 0); __builtin_amdgcn_s_setprio(0); } while (0)
; #define PG8_WAIT_V(n) asm volatile("s_waitcnt vmcnt(" #n ")" ::: "memory")
; #define PG8_WAIT_L(n) asm volatile("s_waitcnt lgkmcnt(" #n ")" ::: "memory")
; #define PG8_BAR __builtin_amdgcn_s_barrier()
; #define PG8_SCHED __builtin_amdgcn_sched_barrier(0)
; template <class Epi, class Sched>
; __device__ __forceinline__ void gemm_phase(LAS unsigned char* lds, const Gemm g, const Sched& S, const Epi& E) {
;     ...
;             PG8_WAIT_V(6); PG8_BAR; PG8_MMA(1, 1, At, B1); PG8_BAR;
;             PG8_LDB(B0, 1, 0); PG8_SCHED; PG8_LDA(At, 1, 0); PG8_STAGE(PG8_SA(0, 1), a2 + hstep, voffA);
;             PG8_WAIT_L(8); PG8_BAR; PG8_WAIT_L(0); PG8_MMA(0, 0, At, B0); PG8_BAR; PG8_SCHED;
;             PG8_LDB(B1, 1, 1); PG8_STAGE(PG8_SB(1, 0), b3, voffB);
;             PG8_BAR; PG8_WAIT_L(0); PG8_MMA(0, 1, At, B1); PG8_BAR;
;             PG8_LDA(At, 1, 1); PG8_STAGE(PG8_SA(1, 0), a3, voffA);
;             PG8_BAR; PG8_WAIT_L(0); PG8_MMA(1, 0, At, B0); PG8_BAR; PG8_SCHED;
	s_setprio 1
	v_mfma_f32_16x16x32_bf16 v[52:55], v[176:179], v[144:147], 0
	v_mfma_f32_16x16x32_bf16 v[48:51], v[184:187], v[144:147], 0
	v_mfma_f32_16x16x32_bf16 v[36:39], v[176:179], v[152:155], 0
	v_mfma_f32_16x16x32_bf16 v[32:35], v[184:187], v[152:155], 0
	v_mfma_f32_16x16x32_bf16 v[20:23], v[176:179], v[160:163], 0
	v_mfma_f32_16x16x32_bf16 v[16:19], v[184:187], v[160:163], 0
	v_mfma_f32_16x16x32_bf16 v[4:7], v[176:179], v[168:171], 0
	v_mfma_f32_16x16x32_bf16 v[0:3], v[184:187], v[168:171], 0
	v_mfma_f32_16x16x32_bf16 v[52:55], v[180:183], v[148:151], v[52:55]
	v_mfma_f32_16x16x32_bf16 v[48:51], v[206:209], v[148:151], v[48:51]
	v_mfma_f32_16x16x32_bf16 v[36:39], v[180:183], v[156:159], v[36:39]
	v_mfma_f32_16x16x32_bf16 v[32:35], v[206:209], v[156:159], v[32:35]
	v_mfma_f32_16x16x32_bf16 v[20:23], v[180:183], v[164:167], v[20:23]
	v_mfma_f32_16x16x32_bf16 v[16:19], v[206:209], v[164:167], v[16:19]
	v_mfma_f32_16x16x32_bf16 v[4:7], v[180:183], v[172:175], v[4:7]
	v_mfma_f32_16x16x32_bf16 v[0:3], v[206:209], v[172:175], v[0:3]
	s_setprio 0
	s_add_i32 s57, 0, 0x18000
	v_add_u32_e32 v140, s57, v240
	s_barrier
	ds_read_b128 v[128:131], v140
	ds_read_b128 v[132:135], v140 offset:1024
	ds_read_b128 v[136:139], v140 offset:2048
	ds_read_b128 v[140:143], v140 offset:3072
	ds_read_b128 v[144:147], v242 offset:32768
	ds_read_b128 v[148:151], v242 offset:33792
	ds_read_b128 v[152:155], v242 offset:34816
	ds_read_b128 v[156:159], v242 offset:35840
	ds_read_b128 v[160:163], v242 offset:36864
	ds_read_b128 v[164:167], v242 offset:37888
	ds_read_b128 v[168:171], v242 offset:38912
	ds_read_b128 v[172:175], v242 offset:39936
	s_waitcnt vmcnt(10)
	s_barrier
	s_waitcnt lgkmcnt(0)
	s_setprio 1
	s_waitcnt lgkmcnt(0)
	v_mfma_f32_16x16x32_bf16 v[124:127], v[128:131], v[144:147], v[124:127]
	v_mfma_f32_16x16x32_bf16 v[120:123], v[136:139], v[144:147], v[120:123]
	v_mfma_f32_16x16x32_bf16 v[108:111], v[128:131], v[152:155], v[108:111]
	v_mfma_f32_16x16x32_bf16 v[104:107], v[136:139], v[152:155], v[104:107]
	v_mfma_f32_16x16x32_bf16 v[92:95], v[128:131], v[160:163], v[92:95]
	v_mfma_f32_16x16x32_bf16 v[88:91], v[136:139], v[160:163], v[88:91]
	v_mfma_f32_16x16x32_bf16 v[76:79], v[128:131], v[168:171], v[76:79]
	v_mfma_f32_16x16x32_bf16 v[72:75], v[136:139], v[168:171], v[72:75]
	v_mfma_f32_16x16x32_bf16 v[124:127], v[132:135], v[148:151], v[124:127]
	v_mfma_f32_16x16x32_bf16 v[120:123], v[140:143], v[148:151], v[120:123]
	v_mfma_f32_16x16x32_bf16 v[108:111], v[132:135], v[156:159], v[108:111]
	v_mfma_f32_16x16x32_bf16 v[104:107], v[140:143], v[156:159], v[104:107]
	v_mfma_f32_16x16x32_bf16 v[92:95], v[132:135], v[164:167], v[92:95]
	v_mfma_f32_16x16x32_bf16 v[88:91], v[140:143], v[164:167], v[88:91]
	v_mfma_f32_16x16x32_bf16 v[76:79], v[132:135], v[172:175], v[76:79]
	v_mfma_f32_16x16x32_bf16 v[72:75], v[140:143], v[172:175], v[72:75]
	s_setprio 0
	s_barrier
	s_add_i32 s28, 0, 0x1c000
	s_add_i32 s22, s57, s34
	v_add_u32_e32 v206, s28, v240
	s_add_u32 s0, s26, 0x80
	s_addc_u32 s1, s27, 0
	s_mov_b32 m0, s22
	ds_read_b128 v[176:179], v206
	ds_read_b128 v[180:183], v206 offset:1024
	ds_read_b128 v[184:187], v206 offset:2048
	ds_read_b128 v[206:209], v206 offset:3072
	global_load_lds_dwordx4 v190, s[0:1]
	s_add_i32 m0, s22, 0x2000
	s_nop 0
	global_load_lds_dwordx4 v194, s[0:1]
	s_waitcnt vmcnt(10)
	s_barrier
	s_waitcnt lgkmcnt(0)
	s_setprio 1
	s_waitcnt lgkmcnt(0)
	v_mfma_f32_16x16x32_bf16 v[116:119], v[176:179], v[144:147], v[116:119]
	v_mfma_f32_16x16x32_bf16 v[112:115], v[184:187], v[144:147], v[112:115]
	v_mfma_f32_16x16x32_bf16 v[100:103], v[176:179], v[152:155], v[100:103]
	v_mfma_f32_16x16x32_bf16 v[96:99], v[184:187], v[152:155], v[96:99]
	v_mfma_f32_16x16x32_bf16 v[84:87], v[176:179], v[160:163], v[84:87]
	v_mfma_f32_16x16x32_bf16 v[80:83], v[184:187], v[160:163], v[80:83]
	v_mfma_f32_16x16x32_bf16 v[68:71], v[176:179], v[168:171], v[68:71]
	v_mfma_f32_16x16x32_bf16 v[64:67], v[184:187], v[168:171], v[64:67]
	v_mfma_f32_16x16x32_bf16 v[116:119], v[180:183], v[148:151], v[116:119]
	v_mfma_f32_16x16x32_bf16 v[112:115], v[206:209], v[148:151], v[112:115]
	v_mfma_f32_16x16x32_bf16 v[100:103], v[180:183], v[156:159], v[100:103]
	v_mfma_f32_16x16x32_bf16 v[96:99], v[206:209], v[156:159], v[96:99]
	v_mfma_f32_16x16x32_bf16 v[84:87], v[180:183], v[164:167], v[84:87]
	v_mfma_f32_16x16x32_bf16 v[80:83], v[206:209], v[164:167], v[80:83]
	v_mfma_f32_16x16x32_bf16 v[68:71], v[180:183], v[172:175], v[68:71]
	v_mfma_f32_16x16x32_bf16 v[64:67], v[206:209], v[172:175], v[64:67]
	s_setprio 0
	s_mov_b32 m0, s44
	s_mov_b64 s[0:1], 0x80
	v_lshl_add_u64 v[210:211], v[214:215], 0, s[0:1]
	s_barrier
	ds_read_b128 v[144:147], v242 offset:49152
	ds_read_b128 v[148:151], v242 offset:50176
	ds_read_b128 v[152:155], v242 offset:51200
	ds_read_b128 v[156:159], v242 offset:52224
	ds_read_b128 v[160:163], v242 offset:53248
	ds_read_b128 v[164:167], v242 offset:54272
	ds_read_b128 v[168:171], v242 offset:55296
	ds_read_b128 v[172:175], v242 offset:56320
	global_load_lds_dwordx4 v[210:211], off
	v_lshl_add_u64 v[210:211], v[216:217], 0, s[0:1]
	s_mov_b32 m0, s45
	s_nop 0
	global_load_lds_dwordx4 v[210:211], off
	s_barrier
; #define PG8_STAGE(bufoff, gbase, voff) do { _Pragma("unroll") for (int _i = 0; _i < 2; ++_i) \
;         __builtin_amdgcn_global_load_lds((const unsigned*)((const char*)(gbase) + (voff)[_i]), (LAS unsigned*)(lds + (bufoff) + ldsw + _i * 8192), 16, 0, 0); } while (0)
; #define PG8_LDA(dst, b, h) do { _Pragma("unroll") for (int m = 0; m < 4; ++m) _Pragma("unroll") for (int k = 0; k < 2; ++k) dst[m][k] = *(const LAS bf16x8*)(lds + PG8_SA(b, h) + aoff + m * 2048 + k * 1024); } while (0)
; #define PG8_LDB(dst, b, h) do { _Pragma("unroll") for (int n = 0; n < 2; ++n) _Pragma("unroll") for (int k = 0; k < 2; ++k) dst[n][k] = *(const LAS bf16x8*)(lds + PG8_SB(b, h) + boff + n * 2048 + k * 1024); } while (0)
; #define PG8_MMA(ai, bj, At, Bt) do { __builtin_amdgcn_s_setprio(1); _Pragma("unroll") for (int m = 0; m < 4; ++m) _Pragma("unroll") for (int n = 0; n < 2; ++n) _Pragma("unroll") for (int k = 0; k < 2; ++k) \
;         acc[ai][bj][m][n] = __builtin_amdgcn_mfma_f32_16x16x32_bf16(Bt[n][k], At[m][k], acc[ai][bj][m][n], 0, 0, 0); __builtin_amdgcn_s_setprio(0); } while (0)
; #define PG8_WAIT_V(n) asm volatile("s_waitcnt vmcnt(" #n ")" ::: "memory")
; #define PG8_WAIT_L(n) asm volatile("s_waitcnt lgkmcnt(" #n ")" ::: "memory")
; #define PG8_BAR __builtin_amdgcn_s_barrier()
; #define PG8_SCHED __builtin_amdgcn_sched_barrier(0)
; template <class Epi, class Sched>
; __device__ __forceinline__ void gemm_phase(LAS unsigned char* lds, const Gemm g, const Sched& S, const Epi& E) {
;     ...
;             PG8_LDB(B0, 0, 0); PG8_SCHED; PG8_LDA(At, 0, 0); PG8_STAGE(PG8_SA(1, 1), a1 + hstep, voffA);
;             PG8_WAIT_L(8); PG8_BAR; PG8_WAIT_L(0); PG8_MMA(0, 0, At, B0); PG8_BAR; PG8_SCHED;
;             PG8_LDB(B1, 0, 1); PG8_STAGE(PG8_SB(0, 0), b2, voffB);
;             PG8_BAR; PG8_WAIT_L(0); PG8_MMA(0, 1, At, B1); PG8_BAR;
;             PG8_LDA(At, 0, 1); PG8_STAGE(PG8_SA(0, 0), a2, voffA);
;             PG8_BAR; PG8_WAIT_L(0); PG8_MMA(1, 0, At, B0); PG8_BAR; PG8_SCHED;
;     ...
;             PG8_LDA(At, 1, 1); PG8_STAGE(PG8_SA(1, 0), a3, voffA);
;             PG8_BAR; PG8_WAIT_L(0); PG8_MMA(1, 0, At, B0); PG8_BAR; PG8_SCHED;
;             PG8_STAGE(PG8_SB(1, 1), b3 + hstep, voffB);
;             PG8_WAIT_V(6); PG8_BAR; PG8_MMA(1, 1, At, B1); PG8_BAR;
	s_waitcnt lgkmcnt(0)
	s_setprio 1
	s_waitcnt lgkmcnt(0)
	v_mfma_f32_16x16x32_bf16 v[60:63], v[128:131], v[144:147], v[60:63]
	v_mfma_f32_16x16x32_bf16 v[56:59], v[136:139], v[144:147], v[56:59]
	v_mfma_f32_16x16x32_bf16 v[44:47], v[128:131], v[152:155], v[44:47]
	v_mfma_f32_16x16x32_bf16 v[40:43], v[136:139], v[152:155], v[40:43]
	v_mfma_f32_16x16x32_bf16 v[28:31], v[128:131], v[160:163], v[28:31]
	v_mfma_f32_16x16x32_bf16 v[24:27], v[136:139], v[160:163], v[24:27]
	v_mfma_f32_16x16x32_bf16 v[12:15], v[128:131], v[168:171], v[12:15]
	v_mfma_f32_16x16x32_bf16 v[8:11], v[136:139], v[168:171], v[8:11]
	v_mfma_f32_16x16x32_bf16 v[60:63], v[132:135], v[148:151], v[60:63]
	v_mfma_f32_16x16x32_bf16 v[56:59], v[140:143], v[148:151], v[56:59]
	v_mfma_f32_16x16x32_bf16 v[44:47], v[132:135], v[156:159], v[44:47]
	v_mfma_f32_16x16x32_bf16 v[40:43], v[140:143], v[156:159], v[40:43]
	v_mfma_f32_16x16x32_bf16 v[28:31], v[132:135], v[164:167], v[28:31]
	v_mfma_f32_16x16x32_bf16 v[24:27], v[140:143], v[164:167], v[24:27]
	v_mfma_f32_16x16x32_bf16 v[12:15], v[132:135], v[172:175], v[12:15]
	v_mfma_f32_16x16x32_bf16 v[8:11], v[140:143], v[172:175], v[8:11]
	s_setprio 0
	s_barrier
	s_add_u32 s22, s26, 0xb0080
	s_addc_u32 s23, s27, 0
	s_add_i32 s26, s28, s34
	s_mov_b32 m0, s26
	s_nop 0
	global_load_lds_dwordx4 v190, s[22:23]
	s_add_i32 m0, s26, 0x2000
	s_nop 0
	global_load_lds_dwordx4 v194, s[22:23]
	s_waitcnt vmcnt(10)
	s_barrier
	s_setprio 1
	v_mfma_f32_16x16x32_bf16 v[52:55], v[176:179], v[144:147], v[52:55]
	v_mfma_f32_16x16x32_bf16 v[48:51], v[184:187], v[144:147], v[48:51]
	v_mfma_f32_16x16x32_bf16 v[36:39], v[176:179], v[152:155], v[36:39]
	v_mfma_f32_16x16x32_bf16 v[32:35], v[184:187], v[152:155], v[32:35]
	v_mfma_f32_16x16x32_bf16 v[20:23], v[176:179], v[160:163], v[20:23]
	v_mfma_f32_16x16x32_bf16 v[16:19], v[184:187], v[160:163], v[16:19]
	v_mfma_f32_16x16x32_bf16 v[4:7], v[176:179], v[168:171], v[4:7]
	v_mfma_f32_16x16x32_bf16 v[0:3], v[184:187], v[168:171], v[0:3]
	v_mfma_f32_16x16x32_bf16 v[52:55], v[180:183], v[148:151], v[52:55]
	v_mfma_f32_16x16x32_bf16 v[48:51], v[206:209], v[148:151], v[48:51]
	v_mfma_f32_16x16x32_bf16 v[36:39], v[180:183], v[156:159], v[36:39]
	v_mfma_f32_16x16x32_bf16 v[32:35], v[206:209], v[156:159], v[32:35]
	v_mfma_f32_16x16x32_bf16 v[20:23], v[180:183], v[164:167], v[20:23]
	v_mfma_f32_16x16x32_bf16 v[16:19], v[206:209], v[164:167], v[16:19]
	v_mfma_f32_16x16x32_bf16 v[4:7], v[180:183], v[172:175], v[4:7]
	v_mfma_f32_16x16x32_bf16 v[0:3], v[206:209], v[172:175], v[0:3]
	s_setprio 0
	s_add_i32 s56, s56, 2
	s_add_u32 s54, s54, 0x100
	s_addc_u32 s55, s55, 0
	s_cmp_gt_u32 s56, 41
	s_mov_b64 s[22:23], s[24:25]
	s_barrier
.LBB0_1097:
	ds_read_b128 v[128:131], v241
	ds_read_b128 v[132:135], v241 offset:1024
	ds_read_b128 v[136:139], v241 offset:2048
	ds_read_b128 v[140:143], v241 offset:3072
	s_add_u32 s24, s22, 0x100
	s_addc_u32 s25, s23, 0
	s_cmp_eq_u32 s56, 40
	s_cselect_b32 s29, s5, s25
	s_cselect_b32 s28, s4, s24
	s_cselect_b32 s27, s7, s55
	s_cselect_b32 s26, s6, s54
	v_lshl_add_u64 v[176:177], s[22:23], 0, v[196:197]
	s_add_i32 m0, s35, 0xc000
	ds_read_b128 v[144:147], v242
	ds_read_b128 v[148:151], v242 offset:1024
	ds_read_b128 v[152:155], v242 offset:2048
	ds_read_b128 v[156:159], v242 offset:3072
	ds_read_b128 v[160:163], v242 offset:4096
	ds_read_b128 v[164:167], v242 offset:5120
	ds_read_b128 v[168:171], v242 offset:6144
	ds_read_b128 v[172:175], v242 offset:7168
	global_load_lds_dwordx4 v[176:177], off
	v_lshl_add_u64 v[176:177], s[22:23], 0, v[198:199]
	s_add_i32 m0, s35, 0xe000
	s_nop 0
	global_load_lds_dwordx4 v[176:177], off
	s_waitcnt vmcnt(10)
	s_barrier
	s_waitcnt lgkmcnt(0)
	s_setprio 1
	s_waitcnt lgkmcnt(0)
	v_mfma_f32_16x16x32_bf16 v[124:127], v[128:131], v[144:147], v[124:127]
	v_mfma_f32_16x16x32_bf16 v[120:123], v[136:139], v[144:147], v[120:123]
	v_mfma_f32_16x16x32_bf16 v[108:111], v[128:131], v[152:155], v[108:111]
	v_mfma_f32_16x16x32_bf16 v[104:107], v[136:139], v[152:155], v[104:107]
	v_mfma_f32_16x16x32_bf16 v[92:95], v[128:131], v[160:163], v[92:95]
	v_mfma_f32_16x16x32_bf16 v[88:91], v[136:139], v[160:163], v[88:91]
	v_mfma_f32_16x16x32_bf16 v[76:79], v[128:131], v[168:171], v[76:79]
	v_mfma_f32_16x16x32_bf16 v[72:75], v[136:139], v[168:171], v[72:75]
	v_mfma_f32_16x16x32_bf16 v[124:127], v[132:135], v[148:151], v[124:127]
	v_mfma_f32_16x16x32_bf16 v[120:123], v[140:143], v[148:151], v[120:123]
	v_mfma_f32_16x16x32_bf16 v[108:111], v[132:135], v[156:159], v[108:111]
	v_mfma_f32_16x16x32_bf16 v[104:107], v[140:143], v[156:159], v[104:107]
	v_mfma_f32_16x16x32_bf16 v[92:95], v[132:135], v[164:167], v[92:95]
	v_mfma_f32_16x16x32_bf16 v[88:91], v[140:143], v[164:167], v[88:91]
	v_mfma_f32_16x16x32_bf16 v[76:79], v[132:135], v[172:175], v[76:79]
	v_mfma_f32_16x16x32_bf16 v[72:75], v[140:143], v[172:175], v[72:75]
	s_setprio 0
	s_barrier
	s_add_i32 s22, s48, s34
	s_mov_b32 m0, s22
	ds_read_b128 v[176:179], v243
	ds_read_b128 v[180:183], v243 offset:1024
	ds_read_b128 v[184:187], v243 offset:2048
	ds_read_b128 v[206:209], v243 offset:3072
	global_load_lds_dwordx4 v190, s[26:27]
	s_add_i32 m0, s22, 0x2000
	s_nop 0
	global_load_lds_dwordx4 v194, s[26:27]
	s_waitcnt vmcnt(10)
	s_barrier
; #define PG8_STAGE(bufoff, gbase, voff) do { _Pragma("unroll") for (int _i = 0; _i < 2; ++_i) \
;         __builtin_amdgcn_global_load_lds((const unsigned*)((const char*)(gbase) + (voff)[_i]), (LAS unsigned*)(lds + (bufoff) + ldsw + _i * 8192), 16, 0, 0); } while (0)
; #define PG8_LDA(dst, b, h) do { _Pragma("unroll") for (int m = 0; m < 4; ++m) _Pragma("unroll") for (int k = 0; k < 2; ++k) dst[m][k] = *(const LAS bf16x8*)(lds + PG8_SA(b, h) + aoff + m * 2048 + k * 1024); } while (0)
; #define PG8_LDB(dst, b, h) do { _Pragma("unroll") for (int n = 0; n < 2; ++n) _Pragma("unroll") for (int k = 0; k < 2; ++k) dst[n][k] = *(const LAS bf16x8*)(lds + PG8_SB(b, h) + boff + n * 2048 + k * 1024); } while (0)
; #define PG8_MMA(ai, bj, At, Bt) do { __builtin_amdgcn_s_setprio(1); _Pragma("unroll") for (int m = 0; m < 4; ++m) _Pragma("unroll") for (int n = 0; n < 2; ++n) _Pragma("unroll") for (int k = 0; k < 2; ++k) \
;         acc[ai][bj][m][n] = __builtin_amdgcn_mfma_f32_16x16x32_bf16(Bt[n][k], At[m][k], acc[ai][bj][m][n], 0, 0, 0); __builtin_amdgcn_s_setprio(0); } while (0)
; #define PG8_WAIT_V(n) asm volatile("s_waitcnt vmcnt(" #n ")" ::: "memory")
; #define PG8_WAIT_L(n) asm volatile("s_waitcnt lgkmcnt(" #n ")" ::: "memory")
; #define PG8_BAR __builtin_amdgcn_s_barrier()
; #define PG8_SCHED __builtin_amdgcn_sched_barrier(0)
; template <class Epi, class Sched>
; __device__ __forceinline__ void gemm_phase(LAS unsigned char* lds, const Gemm g, const Sched& S, const Epi& E) {
;     ...
;             PG8_BAR; PG8_WAIT_L(0); PG8_MMA(0, 1, At, B1); PG8_BAR;
;             PG8_LDA(At, 0, 1); PG8_STAGE(PG8_SA(0, 0), a2, voffA);
;             PG8_BAR; PG8_WAIT_L(0); PG8_MMA(1, 0, At, B0); PG8_BAR; PG8_SCHED;
;             PG8_STAGE(PG8_SB(0, 1), b2 + hstep, voffB);
;             PG8_WAIT_V(6); PG8_BAR; PG8_MMA(1, 1, At, B1); PG8_BAR;
;             PG8_LDB(B0, 1, 0); PG8_SCHED; PG8_LDA(At, 1, 0); PG8_STAGE(PG8_SA(0, 1), a2 + hstep, voffA);
;             PG8_WAIT_L(8); PG8_BAR; PG8_WAIT_L(0); PG8_MMA(0, 0, At, B0); PG8_BAR; PG8_SCHED;
	s_waitcnt lgkmcnt(0)
	s_setprio 1
	s_waitcnt lgkmcnt(0)
	v_mfma_f32_16x16x32_bf16 v[116:119], v[176:179], v[144:147], v[116:119]
	v_mfma_f32_16x16x32_bf16 v[112:115], v[184:187], v[144:147], v[112:115]
	v_mfma_f32_16x16x32_bf16 v[100:103], v[176:179], v[152:155], v[100:103]
	v_mfma_f32_16x16x32_bf16 v[96:99], v[184:187], v[152:155], v[96:99]
	v_mfma_f32_16x16x32_bf16 v[84:87], v[176:179], v[160:163], v[84:87]
	v_mfma_f32_16x16x32_bf16 v[80:83], v[184:187], v[160:163], v[80:83]
	v_mfma_f32_16x16x32_bf16 v[68:71], v[176:179], v[168:171], v[68:71]
	v_mfma_f32_16x16x32_bf16 v[64:67], v[184:187], v[168:171], v[64:67]
	v_mfma_f32_16x16x32_bf16 v[116:119], v[180:183], v[148:151], v[116:119]
	v_mfma_f32_16x16x32_bf16 v[112:115], v[206:209], v[148:151], v[112:115]
	v_mfma_f32_16x16x32_bf16 v[100:103], v[180:183], v[156:159], v[100:103]
	v_mfma_f32_16x16x32_bf16 v[96:99], v[206:209], v[156:159], v[96:99]
	v_mfma_f32_16x16x32_bf16 v[84:87], v[180:183], v[164:167], v[84:87]
	v_mfma_f32_16x16x32_bf16 v[80:83], v[206:209], v[164:167], v[80:83]
	v_mfma_f32_16x16x32_bf16 v[68:71], v[180:183], v[172:175], v[68:71]
	v_mfma_f32_16x16x32_bf16 v[64:67], v[206:209], v[172:175], v[64:67]
	s_setprio 0
	s_mov_b32 m0, s35
	v_lshl_add_u64 v[214:215], s[28:29], 0, v[188:189]
	s_barrier
	ds_read_b128 v[144:147], v242 offset:16384
	ds_read_b128 v[148:151], v242 offset:17408
	ds_read_b128 v[152:155], v242 offset:18432
	ds_read_b128 v[156:159], v242 offset:19456
	ds_read_b128 v[160:163], v242 offset:20480
	ds_read_b128 v[164:167], v242 offset:21504
	ds_read_b128 v[168:171], v242 offset:22528
	ds_read_b128 v[172:175], v242 offset:23552
	global_load_lds_dwordx4 v188, s[28:29]
	v_lshl_add_u64 v[216:217], s[28:29], 0, v[192:193]
	s_mov_b32 m0, s36
	s_nop 0
	global_load_lds_dwordx4 v192, s[28:29]
	s_barrier
	s_waitcnt lgkmcnt(0)
	s_setprio 1
	s_waitcnt lgkmcnt(0)
	v_mfma_f32_16x16x32_bf16 v[60:63], v[128:131], v[144:147], v[60:63]
	v_mfma_f32_16x16x32_bf16 v[56:59], v[136:139], v[144:147], v[56:59]
	v_mfma_f32_16x16x32_bf16 v[44:47], v[128:131], v[152:155], v[44:47]
	v_mfma_f32_16x16x32_bf16 v[40:43], v[136:139], v[152:155], v[40:43]
	v_mfma_f32_16x16x32_bf16 v[28:31], v[128:131], v[160:163], v[28:31]
	v_mfma_f32_16x16x32_bf16 v[24:27], v[136:139], v[160:163], v[24:27]
	v_mfma_f32_16x16x32_bf16 v[12:15], v[128:131], v[168:171], v[12:15]
	v_mfma_f32_16x16x32_bf16 v[8:11], v[136:139], v[168:171], v[8:11]
	v_mfma_f32_16x16x32_bf16 v[60:63], v[132:135], v[148:151], v[60:63]
	v_mfma_f32_16x16x32_bf16 v[56:59], v[140:143], v[148:151], v[56:59]
	v_mfma_f32_16x16x32_bf16 v[44:47], v[132:135], v[156:159], v[44:47]
	v_mfma_f32_16x16x32_bf16 v[40:43], v[140:143], v[156:159], v[40:43]
	v_mfma_f32_16x16x32_bf16 v[28:31], v[132:135], v[164:167], v[28:31]
	v_mfma_f32_16x16x32_bf16 v[24:27], v[140:143], v[164:167], v[24:27]
	v_mfma_f32_16x16x32_bf16 v[12:15], v[132:135], v[172:175], v[12:15]
	v_mfma_f32_16x16x32_bf16 v[8:11], v[140:143], v[172:175], v[8:11]
	s_setprio 0
	s_barrier
	s_add_u32 s22, s26, 0xb0000
	s_addc_u32 s23, s27, 0
	s_add_i32 s57, s49, s34
	s_mov_b32 m0, s57
	s_nop 0
	global_load_lds_dwordx4 v190, s[22:23]
	s_add_i32 m0, s57, 0x2000
	s_nop 0
	global_load_lds_dwordx4 v194, s[22:23]
	s_add_u32 s22, s28, 0xb0000
	s_addc_u32 s23, s29, 0
	s_mov_b32 m0, s37
	s_nop 0
	global_load_lds_dwordx4 v188, s[22:23]
	s_mov_b32 m0, s38
	s_nop 0
	global_load_lds_dwordx4 v192, s[22:23]
	s_waitcnt vmcnt(12)
	s_barrier
	s_setprio 1
	v_mfma_f32_16x16x32_bf16 v[52:55], v[176:179], v[144:147], v[52:55]
	v_mfma_f32_16x16x32_bf16 v[48:51], v[184:187], v[144:147], v[48:51]
	v_mfma_f32_16x16x32_bf16 v[36:39], v[176:179], v[152:155], v[36:39]
	v_mfma_f32_16x16x32_bf16 v[32:35], v[184:187], v[152:155], v[32:35]
	v_mfma_f32_16x16x32_bf16 v[20:23], v[176:179], v[160:163], v[20:23]
	v_mfma_f32_16x16x32_bf16 v[16:19], v[184:187], v[160:163], v[16:19]
	v_mfma_f32_16x16x32_bf16 v[4:7], v[176:179], v[168:171], v[4:7]
	v_mfma_f32_16x16x32_bf16 v[0:3], v[184:187], v[168:171], v[0:3]
	v_mfma_f32_16x16x32_bf16 v[52:55], v[180:183], v[148:151], v[52:55]
	v_mfma_f32_16x16x32_bf16 v[48:51], v[206:209], v[148:151], v[48:51]
	v_mfma_f32_16x16x32_bf16 v[36:39], v[180:183], v[156:159], v[36:39]
	v_mfma_f32_16x16x32_bf16 v[32:35], v[206:209], v[156:159], v[32:35]
	v_mfma_f32_16x16x32_bf16 v[20:23], v[180:183], v[164:167], v[20:23]
	v_mfma_f32_16x16x32_bf16 v[16:19], v[206:209], v[164:167], v[16:19]
	v_mfma_f32_16x16x32_bf16 v[4:7], v[180:183], v[172:175], v[4:7]
	v_mfma_f32_16x16x32_bf16 v[0:3], v[206:209], v[172:175], v[0:3]
	s_setprio 0
	s_add_i32 s57, 0, 0x18000
	v_add_u32_e32 v140, s57, v240
	s_barrier
	ds_read_b128 v[128:131], v140
	ds_read_b128 v[132:135], v140 offset:1024
	ds_read_b128 v[136:139], v140 offset:2048
	ds_read_b128 v[140:143], v140 offset:3072
	ds_read_b128 v[144:147], v242 offset:32768
	ds_read_b128 v[148:151], v242 offset:33792
	ds_read_b128 v[152:155], v242 offset:34816
	ds_read_b128 v[156:159], v242 offset:35840
	ds_read_b128 v[160:163], v242 offset:36864
	ds_read_b128 v[164:167], v242 offset:37888
	ds_read_b128 v[168:171], v242 offset:38912
	ds_read_b128 v[172:175], v242 offset:39936
	s_waitcnt vmcnt(10)
	s_barrier
; #define PG8_STAGE(bufoff, gbase, voff) do { _Pragma("unroll") for (int _i = 0; _i < 2; ++_i) \
;         __builtin_amdgcn_global_load_lds((const unsigned*)((const char*)(gbase) + (voff)[_i]), (LAS unsigned*)(lds + (bufoff) + ldsw + _i * 8192), 16, 0, 0); } while (0)
; #define PG8_LDA(dst, b, h) do { _Pragma("unroll") for (int m = 0; m < 4; ++m) _Pragma("unroll") for (int k = 0; k < 2; ++k) dst[m][k] = *(const LAS bf16x8*)(lds + PG8_SA(b, h) + aoff + m * 2048 + k * 1024); } while (0)
; #define PG8_LDB(dst, b, h) do { _Pragma("unroll") for (int n = 0; n < 2; ++n) _Pragma("unroll") for (int k = 0; k < 2; ++k) dst[n][k] = *(const LAS bf16x8*)(lds + PG8_SB(b, h) + boff + n * 2048 + k * 1024); } while (0)
; #define PG8_MMA(ai, bj, At, Bt) do { __builtin_amdgcn_s_setprio(1); _Pragma("unroll") for (int m = 0; m < 4; ++m) _Pragma("unroll") for (int n = 0; n < 2; ++n) _Pragma("unroll") for (int k = 0; k < 2; ++k) \
;         acc[ai][bj][m][n] = __builtin_amdgcn_mfma_f32_16x16x32_bf16(Bt[n][k], At[m][k], acc[ai][bj][m][n], 0, 0, 0); __builtin_amdgcn_s_setprio(0); } while (0)
; #define PG8_WAIT_V(n) asm volatile("s_waitcnt vmcnt(" #n ")" ::: "memory")
; #define PG8_WAIT_L(n) asm volatile("s_waitcnt lgkmcnt(" #n ")" ::: "memory")
; #define PG8_BAR __builtin_amdgcn_s_barrier()
; #define PG8_SCHED __builtin_amdgcn_sched_barrier(0)
; template <class Epi, class Sched>
; __device__ __forceinline__ void gemm_phase(LAS unsigned char* lds, const Gemm g, const Sched& S, const Epi& E) {
;     ...
;             PG8_WAIT_L(8); PG8_BAR; PG8_WAIT_L(0); PG8_MMA(0, 0, At, B0); PG8_BAR; PG8_SCHED;
;             PG8_LDB(B1, 1, 1); PG8_STAGE(PG8_SB(1, 0), b3, voffB);
;             PG8_BAR; PG8_WAIT_L(0); PG8_MMA(0, 1, At, B1); PG8_BAR;
;             PG8_LDA(At, 1, 1); PG8_STAGE(PG8_SA(1, 0), a3, voffA);
;             PG8_BAR; PG8_WAIT_L(0); PG8_MMA(1, 0, At, B0); PG8_BAR; PG8_SCHED;
;             PG8_STAGE(PG8_SB(1, 1), b3 + hstep, voffB);
;             PG8_WAIT_V(6); PG8_BAR; PG8_MMA(1, 1, At, B1); PG8_BAR;
	s_waitcnt lgkmcnt(0)
	s_setprio 1
	s_waitcnt lgkmcnt(0)
	v_mfma_f32_16x16x32_bf16 v[124:127], v[128:131], v[144:147], v[124:127]
	v_mfma_f32_16x16x32_bf16 v[120:123], v[136:139], v[144:147], v[120:123]
	v_mfma_f32_16x16x32_bf16 v[108:111], v[128:131], v[152:155], v[108:111]
	v_mfma_f32_16x16x32_bf16 v[104:107], v[136:139], v[152:155], v[104:107]
	v_mfma_f32_16x16x32_bf16 v[92:95], v[128:131], v[160:163], v[92:95]
	v_mfma_f32_16x16x32_bf16 v[88:91], v[136:139], v[160:163], v[88:91]
	v_mfma_f32_16x16x32_bf16 v[76:79], v[128:131], v[168:171], v[76:79]
	v_mfma_f32_16x16x32_bf16 v[72:75], v[136:139], v[168:171], v[72:75]
	v_mfma_f32_16x16x32_bf16 v[124:127], v[132:135], v[148:151], v[124:127]
	v_mfma_f32_16x16x32_bf16 v[120:123], v[140:143], v[148:151], v[120:123]
	v_mfma_f32_16x16x32_bf16 v[108:111], v[132:135], v[156:159], v[108:111]
	v_mfma_f32_16x16x32_bf16 v[104:107], v[140:143], v[156:159], v[104:107]
	v_mfma_f32_16x16x32_bf16 v[92:95], v[132:135], v[164:167], v[92:95]
	v_mfma_f32_16x16x32_bf16 v[88:91], v[140:143], v[164:167], v[88:91]
	v_mfma_f32_16x16x32_bf16 v[76:79], v[132:135], v[172:175], v[76:79]
	v_mfma_f32_16x16x32_bf16 v[72:75], v[140:143], v[172:175], v[72:75]
	s_setprio 0
	s_barrier
	s_add_i32 s28, 0, 0x1c000
	s_add_i32 s22, s57, s34
	v_add_u32_e32 v206, s28, v240
	s_add_u32 s0, s26, 0x80
	s_addc_u32 s1, s27, 0
	s_mov_b32 m0, s22
	ds_read_b128 v[176:179], v206
	ds_read_b128 v[180:183], v206 offset:1024
	ds_read_b128 v[184:187], v206 offset:2048
	ds_read_b128 v[206:209], v206 offset:3072
	global_load_lds_dwordx4 v190, s[0:1]
	s_add_i32 m0, s22, 0x2000
	s_nop 0
	global_load_lds_dwordx4 v194, s[0:1]
	s_waitcnt vmcnt(10)
	s_barrier
	s_waitcnt lgkmcnt(0)
	s_setprio 1
	s_waitcnt lgkmcnt(0)
	v_mfma_f32_16x16x32_bf16 v[116:119], v[176:179], v[144:147], v[116:119]
	v_mfma_f32_16x16x32_bf16 v[112:115], v[184:187], v[144:147], v[112:115]
	v_mfma_f32_16x16x32_bf16 v[100:103], v[176:179], v[152:155], v[100:103]
	v_mfma_f32_16x16x32_bf16 v[96:99], v[184:187], v[152:155], v[96:99]
	v_mfma_f32_16x16x32_bf16 v[84:87], v[176:179], v[160:163], v[84:87]
	v_mfma_f32_16x16x32_bf16 v[80:83], v[184:187], v[160:163], v[80:83]
	v_mfma_f32_16x16x32_bf16 v[68:71], v[176:179], v[168:171], v[68:71]
	v_mfma_f32_16x16x32_bf16 v[64:67], v[184:187], v[168:171], v[64:67]
	v_mfma_f32_16x16x32_bf16 v[116:119], v[180:183], v[148:151], v[116:119]
	v_mfma_f32_16x16x32_bf16 v[112:115], v[206:209], v[148:151], v[112:115]
	v_mfma_f32_16x16x32_bf16 v[100:103], v[180:183], v[156:159], v[100:103]
	v_mfma_f32_16x16x32_bf16 v[96:99], v[206:209], v[156:159], v[96:99]
	v_mfma_f32_16x16x32_bf16 v[84:87], v[180:183], v[164:167], v[84:87]
	v_mfma_f32_16x16x32_bf16 v[80:83], v[206:209], v[164:167], v[80:83]
	v_mfma_f32_16x16x32_bf16 v[68:71], v[180:183], v[172:175], v[68:71]
	v_mfma_f32_16x16x32_bf16 v[64:67], v[206:209], v[172:175], v[64:67]
	s_setprio 0
	s_mov_b32 m0, s44
	s_mov_b64 s[0:1], 0x80
	v_lshl_add_u64 v[210:211], v[214:215], 0, s[0:1]
	s_barrier
	ds_read_b128 v[144:147], v242 offset:49152
	ds_read_b128 v[148:151], v242 offset:50176
	ds_read_b128 v[152:155], v242 offset:51200
	ds_read_b128 v[156:159], v242 offset:52224
	ds_read_b128 v[160:163], v242 offset:53248
	ds_read_b128 v[164:167], v242 offset:54272
	ds_read_b128 v[168:171], v242 offset:55296
	ds_read_b128 v[172:175], v242 offset:56320
	global_load_lds_dwordx4 v[210:211], off
	v_lshl_add_u64 v[210:211], v[216:217], 0, s[0:1]
	s_mov_b32 m0, s45
	s_nop 0
	global_load_lds_dwordx4 v[210:211], off
	s_barrier
	s_waitcnt lgkmcnt(0)
	s_setprio 1
	s_waitcnt lgkmcnt(0)
	v_mfma_f32_16x16x32_bf16 v[60:63], v[128:131], v[144:147], v[60:63]
	v_mfma_f32_16x16x32_bf16 v[56:59], v[136:139], v[144:147], v[56:59]
	v_mfma_f32_16x16x32_bf16 v[44:47], v[128:131], v[152:155], v[44:47]
	v_mfma_f32_16x16x32_bf16 v[40:43], v[136:139], v[152:155], v[40:43]
	v_mfma_f32_16x16x32_bf16 v[28:31], v[128:131], v[160:163], v[28:31]
	v_mfma_f32_16x16x32_bf16 v[24:27], v[136:139], v[160:163], v[24:27]
	v_mfma_f32_16x16x32_bf16 v[12:15], v[128:131], v[168:171], v[12:15]
	v_mfma_f32_16x16x32_bf16 v[8:11], v[136:139], v[168:171], v[8:11]
	v_mfma_f32_16x16x32_bf16 v[60:63], v[132:135], v[148:151], v[60:63]
	v_mfma_f32_16x16x32_bf16 v[56:59], v[140:143], v[148:151], v[56:59]
	v_mfma_f32_16x16x32_bf16 v[44:47], v[132:135], v[156:159], v[44:47]
	v_mfma_f32_16x16x32_bf16 v[40:43], v[140:143], v[156:159], v[40:43]
	v_mfma_f32_16x16x32_bf16 v[28:31], v[132:135], v[164:167], v[28:31]
	v_mfma_f32_16x16x32_bf16 v[24:27], v[140:143], v[164:167], v[24:27]
	v_mfma_f32_16x16x32_bf16 v[12:15], v[132:135], v[172:175], v[12:15]
	v_mfma_f32_16x16x32_bf16 v[8:11], v[140:143], v[172:175], v[8:11]
	s_setprio 0
	s_barrier
	s_add_u32 s22, s26, 0xb0080
	s_addc_u32 s23, s27, 0
	s_add_i32 s26, s28, s34
	s_mov_b32 m0, s26
	s_nop 0
	global_load_lds_dwordx4 v190, s[22:23]
	s_add_i32 m0, s26, 0x2000
	s_nop 0
	global_load_lds_dwordx4 v194, s[22:23]
	s_waitcnt vmcnt(10)
	s_barrier
	s_setprio 1
	v_mfma_f32_16x16x32_bf16 v[52:55], v[176:179], v[144:147], v[52:55]
	v_mfma_f32_16x16x32_bf16 v[48:51], v[184:187], v[144:147], v[48:51]
	v_mfma_f32_16x16x32_bf16 v[36:39], v[176:179], v[152:155], v[36:39]
	v_mfma_f32_16x16x32_bf16 v[32:35], v[184:187], v[152:155], v[32:35]
	v_mfma_f32_16x16x32_bf16 v[20:23], v[176:179], v[160:163], v[20:23]
	v_mfma_f32_16x16x32_bf16 v[16:19], v[184:187], v[160:163], v[16:19]
	v_mfma_f32_16x16x32_bf16 v[4:7], v[176:179], v[168:171], v[4:7]
	v_mfma_f32_16x16x32_bf16 v[0:3], v[184:187], v[168:171], v[0:3]
	v_mfma_f32_16x16x32_bf16 v[52:55], v[180:183], v[148:151], v[52:55]
	v_mfma_f32_16x16x32_bf16 v[48:51], v[206:209], v[148:151], v[48:51]
	v_mfma_f32_16x16x32_bf16 v[36:39], v[180:183], v[156:159], v[36:39]
	v_mfma_f32_16x16x32_bf16 v[32:35], v[206:209], v[156:159], v[32:35]
	v_mfma_f32_16x16x32_bf16 v[20:23], v[180:183], v[164:167], v[20:23]
	v_mfma_f32_16x16x32_bf16 v[16:19], v[206:209], v[164:167], v[16:19]
	v_mfma_f32_16x16x32_bf16 v[4:7], v[180:183], v[172:175], v[4:7]
	v_mfma_f32_16x16x32_bf16 v[0:3], v[206:209], v[172:175], v[0:3]
	s_setprio 0
	s_add_i32 s56, s56, 2
	s_add_u32 s54, s54, 0x100
	s_addc_u32 s55, s55, 0
	s_cmp_gt_u32 s56, 41
	s_mov_b64 s[22:23], s[24:25]
	s_barrier
; __device__ __forceinline__ unsigned cvt_pk_bf16(float lo, float hi) { unsigned r; asm volatile("v_cvt_pk_bf16_f32 %0, %1, %2" : "=v"(r) : "v"(lo), "v"(hi)); return r; }
; __device__ __forceinline__ float bf_lo(unsigned u) { return __uint_as_float(u << 16); }
; __device__ __forceinline__ float bf_hi(unsigned u) { return __uint_as_float(u & 0xffff0000u); }
; #define PG8_WAIT_V(n) asm volatile("s_waitcnt vmcnt(" #n ")" ::: "memory")
; template <class Epi, class Sched>
; __device__ __forceinline__ void gemm_phase(LAS unsigned char* lds, const Gemm g, const Sched& S, const Epi& E) {
;     ...
;             PG8_WAIT_V(6); PG8_BAR; PG8_MMA(1, 1, At, B1); PG8_BAR;
;         }
;         E(acc, cur, wr, wc, fr, fq);
;     __device__ __forceinline__ void operator()(const AccT& acc, const Unit& u, int wr, int wc, int fr, int fq) const {
;     ...
;         const int rowt = u.pm * 256; const int b = rowt >> 11;
;         const bf16_t* res = res_b + (size_t)rowt * DM; bf16_t* out = hb + (size_t)rowt * DM;
;         const int col0 = u.pn * 256 + wc * 32 + 8 * fq;
;         f32x4 gv[2][2];
; #pragma unroll
;         for (int bj = 0; bj < 2; ++bj)
; #pragma unroll
;             for (int n = 0; n < 2; ++n) gv[bj][n] = *(const f32x4*)(gate + (size_t)b * NMOD + col0 + bj * 128 + n * 4) * gs;
;         u32x4 r[2][4][2];
; #pragma unroll
;         for (int ai = 0; ai < 2; ++ai)
; #pragma unroll
;             for (int m = 0; m < 4; ++m)
; #pragma unroll
;                 for (int bj = 0; bj < 2; ++bj) r[ai][m][bj] = *(const u32x4*)(res + (size_t)(wr * 64 + fr + ai * 128 + m * 16) * DM + col0 + bj * 128);
; #pragma unroll
;         for (int ai = 0; ai < 2; ++ai)
; #pragma unroll
;             for (int m = 0; m < 4; ++m)
; #pragma unroll
;                 for (int bj = 0; bj < 2; ++bj) {
;                     const u32x4 q = r[ai][m][bj];
;                     const f32x4 r0 = {bf_lo(q.x), bf_hi(q.x), bf_lo(q.y), bf_hi(q.y)}, r1 = {bf_lo(q.z), bf_hi(q.z), bf_lo(q.w), bf_hi(q.w)};
;                     const f32x4 h0 = r0 + gv[bj][0] * acc[ai][bj][m][0], h1 = r1 + gv[bj][1] * acc[ai][bj][m][1];
;                     u32x4 w; w.x = cvt_pk_bf16(h0[0], h0[1]); w.y = cvt_pk_bf16(h0[2], h0[3]); w.z = cvt_pk_bf16(h1[0], h1[1]); w.w = cvt_pk_bf16(h1[2], h1[3]);
;                     *(u32x4*)(out + (size_t)(wr * 64 + fr + ai * 128 + m * 16) * DM + col0 + bj * 128) = w;
;                 }
	s_cbranch_scc0 .LBB0_1097
	s_lshl_b32 s25, s52, 8
	v_mov_b32_e32 v140, v239
	v_mov_b32_e32 v128, v238
	s_lshl_b32 s22, s53, 8
	s_ashr_i32 s24, s53, 3
	s_or_b32 s25, s25, s43
	s_ashr_i32 s23, s22, 31
	v_lshl_add_u32 v136, v128, 3, s25
	s_mul_hi_i32 s25, s24, 0x9000
	s_mul_i32 s24, s24, 0x9000
	s_add_u32 s24, s40, s24
	s_addc_u32 s25, s41, s25
	v_ashrrev_i32_e32 v137, 31, v136
	v_lshl_add_u64 v[138:139], v[136:137], 2, s[24:25]
	global_load_dwordx4 v[128:131], v[138:139], off offset:16
	global_load_dwordx4 v[132:135], v[138:139], off
	s_lshl_b64 s[22:23], s[22:23], 11
	s_add_u32 s24, s80, s22
	s_addc_u32 s25, s81, s23
	v_lshlrev_b64 v[226:227], 1, v[136:137]
	s_add_u32 s22, s96, s22
	s_addc_u32 s23, s97, s23
	s_and_b64 vcc, exec, s[2:3]
	s_mov_b32 s52, s50
	s_mov_b32 s53, s51
	s_waitcnt vmcnt(0)
	v_pk_mul_f32 v[216:217], v[130:131], 0.5 op_sel_hi:[1,0]
	v_pk_mul_f32 v[220:221], v[134:135], 0.5 op_sel_hi:[1,0]
	v_pk_mul_f32 v[218:219], v[132:133], 0.5 op_sel_hi:[1,0]
	v_pk_mul_f32 v[214:215], v[128:129], 0.5 op_sel_hi:[1,0]
	global_load_dwordx4 v[128:131], v[138:139], off offset:528
	global_load_dwordx4 v[132:135], v[138:139], off offset:512
	s_waitcnt vmcnt(0)
	v_pk_mul_f32 v[206:207], v[128:129], 0.5 op_sel_hi:[1,0]
	v_add_u32_e32 v128, s42, v140
	v_ashrrev_i32_e32 v129, 31, v128
	v_pk_mul_f32 v[208:209], v[130:131], 0.5 op_sel_hi:[1,0]
	v_lshl_add_u64 v[130:131], s[24:25], 0, v[226:227]
	v_lshlrev_b64 v[248:249], 11, v[128:129]
	v_lshl_add_u64 v[128:129], v[130:131], 0, v[248:249]
	global_load_dwordx4 v[244:247], v[128:129], off
	global_load_dwordx4 v[184:187], v[128:129], off offset:256
	v_lshl_add_u64 v[236:237], v[248:249], 0, s[8:9]
	v_lshl_add_u64 v[128:129], v[130:131], 0, v[236:237]
	global_load_dwordx4 v[180:183], v[128:129], off
	global_load_dwordx4 v[176:179], v[128:129], off offset:256
	v_lshl_add_u64 v[234:235], v[248:249], 0, s[10:11]
	v_lshl_add_u64 v[128:129], v[130:131], 0, v[234:235]
	global_load_dwordx4 v[172:175], v[128:129], off
	global_load_dwordx4 v[168:171], v[128:129], off offset:256
	v_lshl_add_u64 v[232:233], v[248:249], 0, s[12:13]
	v_lshl_add_u64 v[128:129], v[130:131], 0, v[232:233]
	global_load_dwordx4 v[164:167], v[128:129], off
	global_load_dwordx4 v[160:163], v[128:129], off offset:256
	v_lshl_add_u64 v[230:231], v[248:249], 0, s[14:15]
	v_lshl_add_u64 v[128:129], v[130:131], 0, v[230:231]
	global_load_dwordx4 v[156:159], v[128:129], off
	global_load_dwordx4 v[152:155], v[128:129], off offset:256
	v_lshl_add_u64 v[228:229], v[248:249], 0, s[16:17]
	v_lshl_add_u64 v[128:129], v[130:131], 0, v[228:229]
	global_load_dwordx4 v[148:151], v[128:129], off
	global_load_dwordx4 v[144:147], v[128:129], off offset:256
	v_lshl_add_u64 v[224:225], v[248:249], 0, s[18:19]
	v_lshl_add_u64 v[128:129], v[130:131], 0, v[224:225]
	global_load_dwordx4 v[140:143], v[128:129], off
	global_load_dwordx4 v[136:139], v[128:129], off offset:256
	v_lshl_add_u64 v[222:223], v[248:249], 0, s[20:21]
	v_lshl_add_u64 v[128:129], v[130:131], 0, v[222:223]
	v_pk_mul_f32 v[212:213], v[134:135], 0.5 op_sel_hi:[1,0]
	v_pk_mul_f32 v[210:211], v[132:133], 0.5 op_sel_hi:[1,0]
	global_load_dwordx4 v[132:135], v[128:129], off
	s_nop 0
	global_load_dwordx4 v[128:131], v[128:129], off offset:256
	v_lshl_add_u64 v[226:227], s[22:23], 0, v[226:227]
	v_lshl_add_u64 v[248:249], v[226:227], 0, v[248:249]
	s_mov_b64 s[24:25], s[6:7]
	s_mov_b64 s[22:23], s[4:5]
	s_waitcnt vmcnt(0)
	v_lshlrev_b32_e32 v250, 16, v244
	v_and_b32_e32 v251, 0xffff0000, v244
	v_lshlrev_b32_e32 v244, 16, v245
	v_and_b32_e32 v245, 0xffff0000, v245
	v_lshlrev_b32_e32 v252, 16, v246
	v_and_b32_e32 v253, 0xffff0000, v246
	v_lshlrev_b32_e32 v246, 16, v247
	v_and_b32_e32 v247, 0xffff0000, v247
	v_pk_fma_f32 v[126:127], v[126:127], v[220:221], v[244:245]
	v_pk_fma_f32 v[124:125], v[124:125], v[218:219], v[250:251]
	v_pk_fma_f32 v[244:245], v[122:123], v[216:217], v[246:247]
	v_pk_fma_f32 v[122:123], v[120:121], v[214:215], v[252:253]
	v_cvt_pk_bf16_f32 v120, v124, v125
	v_cvt_pk_bf16_f32 v121, v126, v127
	v_lshlrev_b32_e32 v124, 16, v186
	v_cvt_pk_bf16_f32 v122, v122, v123
	v_cvt_pk_bf16_f32 v123, v244, v245
	global_store_dwordx4 v[248:249], v[120:123], off
	v_and_b32_e32 v125, 0xffff0000, v186
	v_lshlrev_b32_e32 v126, 16, v187
	v_lshlrev_b32_e32 v120, 16, v184
	v_and_b32_e32 v121, 0xffff0000, v184
	v_and_b32_e32 v127, 0xffff0000, v187
	v_lshlrev_b32_e32 v122, 16, v185
	v_and_b32_e32 v123, 0xffff0000, v185
	v_pk_fma_f32 v[116:117], v[116:117], v[210:211], v[120:121]
	v_pk_fma_f32 v[120:121], v[114:115], v[208:209], v[126:127]
	v_pk_fma_f32 v[114:115], v[112:113], v[206:207], v[124:125]
	v_pk_fma_f32 v[118:119], v[118:119], v[212:213], v[122:123]
	v_cvt_pk_bf16_f32 v112, v116, v117
	v_lshlrev_b32_e32 v116, 16, v181
	v_cvt_pk_bf16_f32 v113, v118, v119
	v_cvt_pk_bf16_f32 v114, v114, v115
	v_cvt_pk_bf16_f32 v115, v120, v121
	global_store_dwordx4 v[248:249], v[112:115], off offset:256
	v_and_b32_e32 v117, 0xffff0000, v181
	v_lshlrev_b32_e32 v118, 16, v182
	v_lshlrev_b32_e32 v114, 16, v180
	v_and_b32_e32 v115, 0xffff0000, v180
	v_and_b32_e32 v119, 0xffff0000, v182
	v_lshlrev_b32_e32 v120, 16, v183
	v_and_b32_e32 v121, 0xffff0000, v183
	v_lshl_add_u64 v[112:113], v[226:227], 0, v[236:237]
	v_pk_fma_f32 v[110:111], v[110:111], v[220:221], v[116:117]
	v_pk_fma_f32 v[108:109], v[108:109], v[218:219], v[114:115]
	v_pk_fma_f32 v[114:115], v[106:107], v[216:217], v[120:121]
	v_pk_fma_f32 v[106:107], v[104:105], v[214:215], v[118:119]
	v_cvt_pk_bf16_f32 v104, v108, v109
	v_cvt_pk_bf16_f32 v105, v110, v111
	v_lshlrev_b32_e32 v108, 16, v178
	v_cvt_pk_bf16_f32 v106, v106, v107
	v_cvt_pk_bf16_f32 v107, v114, v115
; __device__ __forceinline__ unsigned cvt_pk_bf16(float lo, float hi) { unsigned r; asm volatile("v_cvt_pk_bf16_f32 %0, %1, %2" : "=v"(r) : "v"(lo), "v"(hi)); return r; }
; __device__ __forceinline__ float bf_lo(unsigned u) { return __uint_as_float(u << 16); }
; __device__ __forceinline__ float bf_hi(unsigned u) { return __uint_as_float(u & 0xffff0000u); }
;     __device__ __forceinline__ void operator()(const AccT& acc, const Unit& u, int wr, int wc, int fr, int fq) const {
;     ...
;         for (int ai = 0; ai < 2; ++ai)
; #pragma unroll
;             for (int m = 0; m < 4; ++m)
; #pragma unroll
;                 for (int bj = 0; bj < 2; ++bj) {
;                     const u32x4 q = r[ai][m][bj];
;                     const f32x4 r0 = {bf_lo(q.x), bf_hi(q.x), bf_lo(q.y), bf_hi(q.y)}, r1 = {bf_lo(q.z), bf_hi(q.z), bf_lo(q.w), bf_hi(q.w)};
;                     const f32x4 h0 = r0 + gv[bj][0] * acc[ai][bj][m][0], h1 = r1 + gv[bj][1] * acc[ai][bj][m][1];
;                     u32x4 w; w.x = cvt_pk_bf16(h0[0], h0[1]); w.y = cvt_pk_bf16(h0[2], h0[3]); w.z = cvt_pk_bf16(h1[0], h1[1]); w.w = cvt_pk_bf16(h1[2], h1[3]);
;                     *(u32x4*)(out + (size_t)(wr * 64 + fr + ai * 128 + m * 16) * DM + col0 + bj * 128) = w;
;                 }
	global_store_dwordx4 v[112:113], v[104:107], off
	v_and_b32_e32 v109, 0xffff0000, v178
	v_lshlrev_b32_e32 v110, 16, v179
	v_lshlrev_b32_e32 v104, 16, v176
	v_and_b32_e32 v105, 0xffff0000, v176
	v_and_b32_e32 v111, 0xffff0000, v179
	v_lshlrev_b32_e32 v106, 16, v177
	v_and_b32_e32 v107, 0xffff0000, v177
	v_pk_fma_f32 v[100:101], v[100:101], v[210:211], v[104:105]
	v_pk_fma_f32 v[104:105], v[98:99], v[208:209], v[110:111]
	v_pk_fma_f32 v[98:99], v[96:97], v[206:207], v[108:109]
	v_pk_fma_f32 v[102:103], v[102:103], v[212:213], v[106:107]
	v_cvt_pk_bf16_f32 v96, v100, v101
	v_lshlrev_b32_e32 v100, 16, v173
	v_cvt_pk_bf16_f32 v97, v102, v103
	v_cvt_pk_bf16_f32 v98, v98, v99
	v_cvt_pk_bf16_f32 v99, v104, v105
	global_store_dwordx4 v[112:113], v[96:99], off offset:256
	v_and_b32_e32 v101, 0xffff0000, v173
	v_lshlrev_b32_e32 v102, 16, v174
	v_lshlrev_b32_e32 v98, 16, v172
	v_and_b32_e32 v99, 0xffff0000, v172
	v_and_b32_e32 v103, 0xffff0000, v174
	v_lshlrev_b32_e32 v104, 16, v175
	v_and_b32_e32 v105, 0xffff0000, v175
	v_lshl_add_u64 v[96:97], v[226:227], 0, v[234:235]
	v_pk_fma_f32 v[94:95], v[94:95], v[220:221], v[100:101]
	v_pk_fma_f32 v[92:93], v[92:93], v[218:219], v[98:99]
	v_pk_fma_f32 v[98:99], v[90:91], v[216:217], v[104:105]
	v_pk_fma_f32 v[90:91], v[88:89], v[214:215], v[102:103]
	v_cvt_pk_bf16_f32 v88, v92, v93
	v_cvt_pk_bf16_f32 v89, v94, v95
	v_lshlrev_b32_e32 v92, 16, v170
	v_cvt_pk_bf16_f32 v90, v90, v91
	v_cvt_pk_bf16_f32 v91, v98, v99
	global_store_dwordx4 v[96:97], v[88:91], off
	v_and_b32_e32 v93, 0xffff0000, v170
	v_lshlrev_b32_e32 v94, 16, v171
	v_lshlrev_b32_e32 v88, 16, v168
	v_and_b32_e32 v89, 0xffff0000, v168
	v_and_b32_e32 v95, 0xffff0000, v171
	v_lshlrev_b32_e32 v90, 16, v169
	v_and_b32_e32 v91, 0xffff0000, v169
	v_pk_fma_f32 v[84:85], v[84:85], v[210:211], v[88:89]
	v_pk_fma_f32 v[88:89], v[82:83], v[208:209], v[94:95]
	v_pk_fma_f32 v[82:83], v[80:81], v[206:207], v[92:93]
	v_pk_fma_f32 v[86:87], v[86:87], v[212:213], v[90:91]
	v_cvt_pk_bf16_f32 v80, v84, v85
	v_lshlrev_b32_e32 v84, 16, v165
	v_cvt_pk_bf16_f32 v81, v86, v87
	v_cvt_pk_bf16_f32 v82, v82, v83
	v_cvt_pk_bf16_f32 v83, v88, v89
	global_store_dwordx4 v[96:97], v[80:83], off offset:256
	v_and_b32_e32 v85, 0xffff0000, v165
	v_lshlrev_b32_e32 v86, 16, v166
	v_lshlrev_b32_e32 v82, 16, v164
	v_and_b32_e32 v83, 0xffff0000, v164
	v_and_b32_e32 v87, 0xffff0000, v166
	v_lshlrev_b32_e32 v88, 16, v167
	v_and_b32_e32 v89, 0xffff0000, v167
	v_lshl_add_u64 v[80:81], v[226:227], 0, v[232:233]
	v_pk_fma_f32 v[78:79], v[78:79], v[220:221], v[84:85]
	v_pk_fma_f32 v[76:77], v[76:77], v[218:219], v[82:83]
	v_pk_fma_f32 v[82:83], v[74:75], v[216:217], v[88:89]
	v_pk_fma_f32 v[74:75], v[72:73], v[214:215], v[86:87]
	v_cvt_pk_bf16_f32 v72, v76, v77
	v_cvt_pk_bf16_f32 v73, v78, v79
	v_lshlrev_b32_e32 v76, 16, v162
	v_cvt_pk_bf16_f32 v74, v74, v75
	v_cvt_pk_bf16_f32 v75, v82, v83
	global_store_dwordx4 v[80:81], v[72:75], off
	v_and_b32_e32 v77, 0xffff0000, v162
	v_lshlrev_b32_e32 v78, 16, v163
	v_lshlrev_b32_e32 v72, 16, v160
	v_and_b32_e32 v73, 0xffff0000, v160
	v_and_b32_e32 v79, 0xffff0000, v163
	v_lshlrev_b32_e32 v74, 16, v161
	v_and_b32_e32 v75, 0xffff0000, v161
	v_pk_fma_f32 v[68:69], v[68:69], v[210:211], v[72:73]
	v_pk_fma_f32 v[72:73], v[66:67], v[208:209], v[78:79]
	v_pk_fma_f32 v[66:67], v[64:65], v[206:207], v[76:77]
	v_pk_fma_f32 v[70:71], v[70:71], v[212:213], v[74:75]
	v_cvt_pk_bf16_f32 v64, v68, v69
	v_lshlrev_b32_e32 v68, 16, v157
	v_cvt_pk_bf16_f32 v65, v70, v71
	v_cvt_pk_bf16_f32 v66, v66, v67
	v_cvt_pk_bf16_f32 v67, v72, v73
	global_store_dwordx4 v[80:81], v[64:67], off offset:256
	v_and_b32_e32 v69, 0xffff0000, v157
	v_lshlrev_b32_e32 v70, 16, v158
	v_lshlrev_b32_e32 v66, 16, v156
	v_and_b32_e32 v67, 0xffff0000, v156
	v_and_b32_e32 v71, 0xffff0000, v158
	v_lshlrev_b32_e32 v72, 16, v159
	v_and_b32_e32 v73, 0xffff0000, v159
	v_lshl_add_u64 v[64:65], v[226:227], 0, v[230:231]
	v_pk_fma_f32 v[62:63], v[62:63], v[220:221], v[68:69]
	v_pk_fma_f32 v[60:61], v[60:61], v[218:219], v[66:67]
	v_pk_fma_f32 v[66:67], v[58:59], v[216:217], v[72:73]
	v_pk_fma_f32 v[58:59], v[56:57], v[214:215], v[70:71]
	v_cvt_pk_bf16_f32 v56, v60, v61
	v_cvt_pk_bf16_f32 v57, v62, v63
	v_lshlrev_b32_e32 v60, 16, v154
	v_cvt_pk_bf16_f32 v58, v58, v59
	v_cvt_pk_bf16_f32 v59, v66, v67
	global_store_dwordx4 v[64:65], v[56:59], off
	v_and_b32_e32 v61, 0xffff0000, v154
	v_lshlrev_b32_e32 v62, 16, v155
	v_lshlrev_b32_e32 v56, 16, v152
	v_and_b32_e32 v57, 0xffff0000, v152
	v_and_b32_e32 v63, 0xffff0000, v155
	v_lshlrev_b32_e32 v58, 16, v153
	v_and_b32_e32 v59, 0xffff0000, v153
	v_pk_fma_f32 v[52:53], v[52:53], v[210:211], v[56:57]
; __device__ __forceinline__ unsigned cvt_pk_bf16(float lo, float hi) { unsigned r; asm volatile("v_cvt_pk_bf16_f32 %0, %1, %2" : "=v"(r) : "v"(lo), "v"(hi)); return r; }
; __device__ __forceinline__ float bf_lo(unsigned u) { return __uint_as_float(u << 16); }
; __device__ __forceinline__ float bf_hi(unsigned u) { return __uint_as_float(u & 0xffff0000u); }
; #define PG8_WAIT_V(n) asm volatile("s_waitcnt vmcnt(" #n ")" ::: "memory")
; #define PG8_BAR __builtin_amdgcn_s_barrier()
; template <class Epi, class Sched>
; __device__ __forceinline__ void gemm_phase(LAS unsigned char* lds, const Gemm g, const Sched& S, const Epi& E) {
;     ...
;         if (!has_next) break;
; #pragma unroll
;         for (int a = 0; a < 2; ++a)
; #pragma unroll
;             for (int b = 0; b < 2; ++b)
; #pragma unroll
;                 for (int m = 0; m < 4; ++m)
; #pragma unroll
;                     for (int n = 0; n < 2; ++n) acc[a][b][m][n] = (f32x4){0.f, 0.f, 0.f, 0.f};
;         cur = nxt; cA = nA; cB = nB; ++ui;
;     }
;     PG8_WAIT_V(0);
;     if (wr == 0) PG8_BAR;
;     PG8_BAR;
;     __device__ __forceinline__ void operator()(const AccT& acc, const Unit& u, int wr, int wc, int fr, int fq) const {
;     ...
;         for (int ai = 0; ai < 2; ++ai)
; #pragma unroll
;             for (int m = 0; m < 4; ++m)
; #pragma unroll
;                 for (int bj = 0; bj < 2; ++bj) {
;                     const u32x4 q = r[ai][m][bj];
;                     const f32x4 r0 = {bf_lo(q.x), bf_hi(q.x), bf_lo(q.y), bf_hi(q.y)}, r1 = {bf_lo(q.z), bf_hi(q.z), bf_lo(q.w), bf_hi(q.w)};
;                     const f32x4 h0 = r0 + gv[bj][0] * acc[ai][bj][m][0], h1 = r1 + gv[bj][1] * acc[ai][bj][m][1];
;                     u32x4 w; w.x = cvt_pk_bf16(h0[0], h0[1]); w.y = cvt_pk_bf16(h0[2], h0[3]); w.z = cvt_pk_bf16(h1[0], h1[1]); w.w = cvt_pk_bf16(h1[2], h1[3]);
;                     *(u32x4*)(out + (size_t)(wr * 64 + fr + ai * 128 + m * 16) * DM + col0 + bj * 128) = w;
;                 }
	v_pk_fma_f32 v[56:57], v[50:51], v[208:209], v[62:63]
	v_pk_fma_f32 v[50:51], v[48:49], v[206:207], v[60:61]
	v_pk_fma_f32 v[54:55], v[54:55], v[212:213], v[58:59]
	v_cvt_pk_bf16_f32 v48, v52, v53
	v_lshlrev_b32_e32 v52, 16, v149
	v_cvt_pk_bf16_f32 v49, v54, v55
	v_cvt_pk_bf16_f32 v50, v50, v51
	v_cvt_pk_bf16_f32 v51, v56, v57
	global_store_dwordx4 v[64:65], v[48:51], off offset:256
	v_and_b32_e32 v53, 0xffff0000, v149
	v_lshlrev_b32_e32 v54, 16, v150
	v_lshlrev_b32_e32 v50, 16, v148
	v_and_b32_e32 v51, 0xffff0000, v148
	v_and_b32_e32 v55, 0xffff0000, v150
	v_lshlrev_b32_e32 v56, 16, v151
	v_and_b32_e32 v57, 0xffff0000, v151
	v_lshl_add_u64 v[48:49], v[226:227], 0, v[228:229]
	v_pk_fma_f32 v[46:47], v[46:47], v[220:221], v[52:53]
	v_pk_fma_f32 v[44:45], v[44:45], v[218:219], v[50:51]
	v_pk_fma_f32 v[50:51], v[42:43], v[216:217], v[56:57]
	v_pk_fma_f32 v[42:43], v[40:41], v[214:215], v[54:55]
	v_cvt_pk_bf16_f32 v40, v44, v45
	v_cvt_pk_bf16_f32 v41, v46, v47
	v_lshlrev_b32_e32 v44, 16, v146
	v_cvt_pk_bf16_f32 v42, v42, v43
	v_cvt_pk_bf16_f32 v43, v50, v51
	global_store_dwordx4 v[48:49], v[40:43], off
	v_and_b32_e32 v45, 0xffff0000, v146
	v_lshlrev_b32_e32 v46, 16, v147
	v_lshlrev_b32_e32 v40, 16, v144
	v_and_b32_e32 v41, 0xffff0000, v144
	v_and_b32_e32 v47, 0xffff0000, v147
	v_lshlrev_b32_e32 v42, 16, v145
	v_and_b32_e32 v43, 0xffff0000, v145
	v_pk_fma_f32 v[36:37], v[36:37], v[210:211], v[40:41]
	v_pk_fma_f32 v[40:41], v[34:35], v[208:209], v[46:47]
	v_pk_fma_f32 v[34:35], v[32:33], v[206:207], v[44:45]
	v_pk_fma_f32 v[38:39], v[38:39], v[212:213], v[42:43]
	v_cvt_pk_bf16_f32 v32, v36, v37
	v_lshlrev_b32_e32 v36, 16, v141
	v_cvt_pk_bf16_f32 v33, v38, v39
	v_cvt_pk_bf16_f32 v34, v34, v35
	v_cvt_pk_bf16_f32 v35, v40, v41
	global_store_dwordx4 v[48:49], v[32:35], off offset:256
	v_and_b32_e32 v37, 0xffff0000, v141
	v_lshlrev_b32_e32 v38, 16, v142
	v_lshlrev_b32_e32 v34, 16, v140
	v_and_b32_e32 v35, 0xffff0000, v140
	v_and_b32_e32 v39, 0xffff0000, v142
	v_lshlrev_b32_e32 v40, 16, v143
	v_and_b32_e32 v41, 0xffff0000, v143
	v_lshl_add_u64 v[32:33], v[226:227], 0, v[224:225]
	v_pk_fma_f32 v[30:31], v[30:31], v[220:221], v[36:37]
	v_pk_fma_f32 v[28:29], v[28:29], v[218:219], v[34:35]
	v_pk_fma_f32 v[34:35], v[26:27], v[216:217], v[40:41]
	v_pk_fma_f32 v[26:27], v[24:25], v[214:215], v[38:39]
	v_cvt_pk_bf16_f32 v24, v28, v29
	v_cvt_pk_bf16_f32 v25, v30, v31
	v_lshlrev_b32_e32 v28, 16, v138
	v_cvt_pk_bf16_f32 v26, v26, v27
	v_cvt_pk_bf16_f32 v27, v34, v35
	global_store_dwordx4 v[32:33], v[24:27], off
	v_and_b32_e32 v29, 0xffff0000, v138
	v_lshlrev_b32_e32 v30, 16, v139
	v_lshlrev_b32_e32 v24, 16, v136
	v_and_b32_e32 v25, 0xffff0000, v136
	v_and_b32_e32 v31, 0xffff0000, v139
	v_lshlrev_b32_e32 v26, 16, v137
	v_and_b32_e32 v27, 0xffff0000, v137
	v_pk_fma_f32 v[20:21], v[20:21], v[210:211], v[24:25]
	v_pk_fma_f32 v[24:25], v[18:19], v[208:209], v[30:31]
	v_pk_fma_f32 v[18:19], v[16:17], v[206:207], v[28:29]
	v_pk_fma_f32 v[22:23], v[22:23], v[212:213], v[26:27]
	v_cvt_pk_bf16_f32 v16, v20, v21
	v_lshlrev_b32_e32 v20, 16, v133
	v_cvt_pk_bf16_f32 v17, v22, v23
	v_cvt_pk_bf16_f32 v18, v18, v19
	v_cvt_pk_bf16_f32 v19, v24, v25
	global_store_dwordx4 v[32:33], v[16:19], off offset:256
	v_and_b32_e32 v21, 0xffff0000, v133
	v_lshlrev_b32_e32 v22, 16, v134
	v_lshlrev_b32_e32 v18, 16, v132
	v_and_b32_e32 v19, 0xffff0000, v132
	v_and_b32_e32 v23, 0xffff0000, v134
	v_lshlrev_b32_e32 v24, 16, v135
	v_and_b32_e32 v25, 0xffff0000, v135
	v_lshl_add_u64 v[16:17], v[226:227], 0, v[222:223]
	v_pk_fma_f32 v[14:15], v[14:15], v[220:221], v[20:21]
	v_pk_fma_f32 v[12:13], v[12:13], v[218:219], v[18:19]
	v_pk_fma_f32 v[18:19], v[10:11], v[216:217], v[24:25]
	v_pk_fma_f32 v[10:11], v[8:9], v[214:215], v[22:23]
	v_cvt_pk_bf16_f32 v8, v12, v13
	v_cvt_pk_bf16_f32 v9, v14, v15
	v_lshlrev_b32_e32 v12, 16, v130
	v_cvt_pk_bf16_f32 v10, v10, v11
	v_cvt_pk_bf16_f32 v11, v18, v19
	global_store_dwordx4 v[16:17], v[8:11], off
	v_and_b32_e32 v13, 0xffff0000, v130
	v_lshlrev_b32_e32 v14, 16, v131
	v_lshlrev_b32_e32 v8, 16, v128
	v_and_b32_e32 v9, 0xffff0000, v128
	v_and_b32_e32 v15, 0xffff0000, v131
	v_lshlrev_b32_e32 v10, 16, v129
	v_and_b32_e32 v11, 0xffff0000, v129
	v_pk_fma_f32 v[4:5], v[4:5], v[210:211], v[8:9]
	v_pk_fma_f32 v[8:9], v[2:3], v[208:209], v[14:15]
	v_pk_fma_f32 v[2:3], v[0:1], v[206:207], v[12:13]
	v_pk_fma_f32 v[6:7], v[6:7], v[212:213], v[10:11]
	v_cvt_pk_bf16_f32 v0, v4, v5
	s_nop 0
	v_cvt_pk_bf16_f32 v1, v6, v7
	v_cvt_pk_bf16_f32 v2, v2, v3
	v_cvt_pk_bf16_f32 v3, v8, v9
	global_store_dwordx4 v[16:17], v[0:3], off offset:256
	s_cbranch_vccz .LBB0_1086
	s_waitcnt vmcnt(0)
	s_cmpk_gt_u32 s30, 0xff
	s_cbranch_scc1 .LBB0_1101
	s_barrier
